# row scales of every selection fetched once by the list build into LDS arrays (the wave's dead slice of the selection table): no scale gathers inside the u-table sweep
# speedup vs baseline: 1.0112x; 1.0005x over previous
; __device__ __forceinline__ unsigned f2key(float f) { const unsigned u = __float_as_uint(f); return (u & 0x80000000u) ? ~u : (u | 0x80000000u); }
; __device__ __forceinline__ void peer_tile(const Args& A, LAS unsigned char* lds, int tile) {
;     ...
;         const int tg = w & 3, hg = w >> 2, tl = 16 * tg + l15;
;         const size_t m = (size_t)tile * 64 + tl;
;         unsigned LA[4][2][16];
; #pragma unroll
;         for (int hh = 0; hh < 4; ++hh) {
;             const int h = 4 * hg + hh;
; #pragma unroll
;             for (int p = 0; p < 2; ++p) {
;                 const int hp = 2 * h + p;
;                 unsigned k0[16], k1[16];
;                 { const bf16_t* sp = QRY + m * 2048 + hp * 128 + 32 * g;
;                   const u32x4 s0 = *(const u32x4*)sp, s1 = *(const u32x4*)(sp + 8), s2 = *(const u32x4*)(sp + 16), s3 = *(const u32x4*)(sp + 24);
;                   const unsigned sw[16] = {s0.x, s0.y, s0.z, s0.w, s1.x, s1.y, s1.z, s1.w, s2.x, s2.y, s2.z, s2.w, s3.x, s3.y, s3.z, s3.w};
; #pragma unroll
;                   for (int i = 0; i < 16; ++i) {
;                       const float lo = (float)__builtin_bit_cast(_Float16, (unsigned short)(sw[i] & 0xffffu)), hi = (float)__builtin_bit_cast(_Float16, (unsigned short)(sw[i] >> 16));
;                       const unsigned klo = (f2key(lo) & ~127u) | (unsigned)(127 - (32 * g + 2 * i)), khi = (f2key(hi) & ~127u) | (unsigned)(127 - (32 * g + 2 * i + 1));
;                       if (i < 8) { k0[2 * i] = klo; k0[2 * i + 1] = khi; } else { k1[2 * (i - 8)] = klo; k1[2 * (i - 8) + 1] = khi; } } }
.LBB0_699:
	v_mov_b32_e32 v19, v214
	s_ashr_i32 s3, s2, 31
	v_ashrrev_i32_e32 v7, 6, v19
	v_and_b32_e32 v0, 15, v19
	v_lshlrev_b32_e32 v1, 4, v7
	v_and_or_b32 v13, v1, 48, v0
	s_lshl_b64 s[28:29], s[2:3], 6
	v_or_b32_e32 v0, s28, v13
	v_mov_b32_e32 v1, s29
	v_bfe_u32 v221, v19, 4, 2
	v_ashrrev_i32_e32 v11, 8, v19
	v_lshlrev_b64 v[0:1], 12, v[0:1]
	v_lshlrev_b32_e32 v2, 10, v11
	v_lshl_add_u64 v[0:1], s[54:55], 0, v[0:1]
	v_lshlrev_b32_e32 v112, 6, v221
	v_lshl_add_u64 v[0:1], v[0:1], 0, v[112:113]
	v_ashrrev_i32_e32 v3, 31, v2
	v_lshl_add_u64 v[4:5], v[2:3], 1, v[0:1]
	global_load_dwordx4 v[20:23], v[4:5], off
	global_load_dwordx4 v[24:27], v[4:5], off offset:16
	global_load_dwordx4 v[0:3], v[4:5], off offset:48
	global_load_dwordx4 v[28:31], v[4:5], off offset:32
	v_lshlrev_b32_e32 v15, 5, v221
	v_or_b32_e32 v8, 8, v15
	v_or_b32_e32 v14, 2, v15
	v_or_b32_e32 v12, 4, v15
	v_or_b32_e32 v10, 6, v15
	v_and_b32_e32 v9, 63, v19
	v_cmp_gt_u32_e64 s[0:1], 16, v9
	v_cmp_gt_u32_e64 s[4:5], 32, v9
	v_mul_lo_u32 v6, v19, s17
	s_mov_b32 s3, 8
	s_waitcnt vmcnt(3)
	v_cvt_f32_f16_sdwa v17, v20 dst_sel:DWORD dst_unused:UNUSED_PAD src0_sel:WORD_1
	v_cvt_f32_f16_e32 v16, v20
	v_cvt_f32_f16_sdwa v20, v21 dst_sel:DWORD dst_unused:UNUSED_PAD src0_sel:WORD_1
	v_cvt_f32_f16_e32 v18, v21
	v_cvt_f32_f16_e32 v21, v22
	v_cvt_f32_f16_sdwa v22, v22 dst_sel:DWORD dst_unused:UNUSED_PAD src0_sel:WORD_1
	v_not_b32_e32 v34, v17
	v_or_b32_e32 v35, 0x80000000, v17
	v_cmp_gt_i32_e32 vcc, 0, v17
	v_not_b32_e32 v36, v16
	v_or_b32_e32 v37, 0x80000000, v16
	v_cndmask_b32_e32 v17, v35, v34, vcc
	v_cmp_gt_i32_e32 vcc, 0, v16
	v_cvt_f32_f16_e32 v32, v23
	v_cvt_f32_f16_sdwa v23, v23 dst_sel:DWORD dst_unused:UNUSED_PAD src0_sel:WORD_1
	v_not_b32_e32 v38, v20
	v_or_b32_e32 v39, 0x80000000, v20
	v_cndmask_b32_e32 v16, v37, v36, vcc
	v_cmp_gt_i32_e32 vcc, 0, v20
	v_not_b32_e32 v40, v18
	v_or_b32_e32 v41, 0x80000000, v18
	v_cndmask_b32_e32 v20, v39, v38, vcc
	v_cmp_gt_i32_e32 vcc, 0, v18
	s_waitcnt vmcnt(2)
	v_cvt_f32_f16_e32 v33, v24
	v_cvt_f32_f16_sdwa v24, v24 dst_sel:DWORD dst_unused:UNUSED_PAD src0_sel:WORD_1
	v_not_b32_e32 v42, v22
	v_or_b32_e32 v43, 0x80000000, v22
	v_cndmask_b32_e32 v18, v41, v40, vcc
	v_cmp_gt_i32_e32 vcc, 0, v22
	v_not_b32_e32 v44, v21
	v_or_b32_e32 v45, 0x80000000, v21
	v_cndmask_b32_e32 v22, v43, v42, vcc
	v_cmp_gt_i32_e32 vcc, 0, v21
	v_not_b32_e32 v46, v23
	v_or_b32_e32 v47, 0x80000000, v23
	v_cndmask_b32_e32 v21, v45, v44, vcc
	v_cmp_gt_i32_e32 vcc, 0, v23
	v_not_b32_e32 v48, v32
	v_or_b32_e32 v49, 0x80000000, v32
	v_cndmask_b32_e32 v23, v47, v46, vcc
	v_cmp_gt_i32_e32 vcc, 0, v32
	v_and_b32_e32 v16, 0xffffff80, v16
	v_not_b32_e32 v50, v24
	v_or_b32_e32 v51, 0x80000000, v24
	v_cndmask_b32_e32 v32, v49, v48, vcc
	v_sub_u32_e32 v16, v16, v15
	v_cmp_gt_i32_e32 vcc, 0, v24
	v_add_u32_e32 v35, 0x7f, v16
	v_and_b32_e32 v17, 0xffffff80, v17
	v_cndmask_b32_e32 v16, v51, v50, vcc
	v_and_b32_e32 v16, 0xffffff80, v16
	v_sub_u32_e32 v17, v17, v15
	v_sub_u32_e32 v16, v16, v8
	v_add_u32_e32 v34, 0x7e, v17
	v_add_u32_e32 v41, 0x7e, v16
	v_not_b32_e32 v16, v33
	v_or_b32_e32 v17, 0x80000000, v33
	v_cmp_gt_i32_e32 vcc, 0, v33
	v_and_b32_e32 v20, 0xffffff80, v20
	v_and_b32_e32 v18, 0xffffff80, v18
	v_cndmask_b32_e32 v16, v17, v16, vcc
	v_cvt_f32_f16_sdwa v17, v25 dst_sel:DWORD dst_unused:UNUSED_PAD src0_sel:WORD_1
	v_and_b32_e32 v21, 0xffffff80, v21
	v_sub_u32_e32 v20, v20, v14
	v_sub_u32_e32 v18, v18, v14
	v_sub_u32_e32 v21, v21, v12
	v_add_u32_e32 v36, 0x7e, v20
	v_add_u32_e32 v37, 0x7f, v18
	v_add_u32_e32 v39, 0x7f, v21
	v_and_b32_e32 v16, 0xffffff80, v16
	v_cvt_f32_f16_e32 v18, v25
	v_not_b32_e32 v20, v17
	v_or_b32_e32 v21, 0x80000000, v17
	v_cmp_gt_i32_e32 vcc, 0, v17
	v_sub_u32_e32 v16, v16, v8
	v_add_u32_e32 v33, 0x7f, v16
	v_cndmask_b32_e32 v17, v21, v20, vcc
	v_or_b32_e32 v16, 10, v15
	v_and_b32_e32 v17, 0xffffff80, v17
	v_sub_u32_e32 v17, v17, v16
	v_add_u32_e32 v42, 0x7e, v17
	v_not_b32_e32 v17, v18
	v_or_b32_e32 v20, 0x80000000, v18
	v_cmp_gt_i32_e32 vcc, 0, v18
	v_cvt_f32_f16_sdwa v18, v26 dst_sel:DWORD dst_unused:UNUSED_PAD src0_sel:WORD_1
	v_and_b32_e32 v22, 0xffffff80, v22
	v_sub_u32_e32 v22, v22, v12
	v_cndmask_b32_e32 v17, v20, v17, vcc
	v_add_u32_e32 v38, 0x7e, v22
	v_and_b32_e32 v17, 0xffffff80, v17
	v_cvt_f32_f16_e32 v20, v26
	v_not_b32_e32 v21, v18
	v_or_b32_e32 v22, 0x80000000, v18
	v_cmp_gt_i32_e32 vcc, 0, v18
	v_sub_u32_e32 v17, v17, v16
	v_add_u32_e32 v43, 0x7f, v17
	v_cndmask_b32_e32 v18, v22, v21, vcc
	v_or_b32_e32 v17, 12, v15
	v_and_b32_e32 v18, 0xffffff80, v18
	v_sub_u32_e32 v18, v18, v17
	v_add_u32_e32 v44, 0x7e, v18
	v_not_b32_e32 v18, v20
	v_or_b32_e32 v21, 0x80000000, v20
	v_cmp_gt_i32_e32 vcc, 0, v20
	v_cvt_f32_f16_sdwa v20, v27 dst_sel:DWORD dst_unused:UNUSED_PAD src0_sel:WORD_1
	v_and_b32_e32 v23, 0xffffff80, v23
	v_sub_u32_e32 v23, v23, v10
	v_cndmask_b32_e32 v18, v21, v18, vcc
	v_add_u32_e32 v40, 0x7e, v23
	v_and_b32_e32 v18, 0xffffff80, v18
	v_cvt_f32_f16_e32 v21, v27
	v_not_b32_e32 v22, v20
	v_or_b32_e32 v23, 0x80000000, v20
	v_cmp_gt_i32_e32 vcc, 0, v20
	v_sub_u32_e32 v18, v18, v17
	v_add_u32_e32 v45, 0x7f, v18
	v_cndmask_b32_e32 v20, v23, v22, vcc
	v_or_b32_e32 v18, 14, v15
	v_and_b32_e32 v20, 0xffffff80, v20
	v_sub_u32_e32 v20, v20, v18
	v_add_u32_e32 v27, 0x7e, v20
	v_not_b32_e32 v20, v21
	v_or_b32_e32 v22, 0x80000000, v21
	v_cmp_gt_i32_e32 vcc, 0, v21
	s_waitcnt vmcnt(0)
; __device__ __forceinline__ unsigned f2key(float f) { const unsigned u = __float_as_uint(f); return (u & 0x80000000u) ? ~u : (u | 0x80000000u); }
; #define CE_DESC(a, b) do { const unsigned _mx = (a) > (b) ? (a) : (b), _mn = (a) > (b) ? (b) : (a); (a) = _mx; (b) = _mn; } while (0)
; __device__ __forceinline__ void sort16_desc(unsigned (&k)[16]) {
; #pragma unroll
;     for (int size = 2; size <= 16; size <<= 1)
; #pragma unroll
;         for (int stride = size >> 1; stride > 0; stride >>= 1)
; #pragma unroll
;             for (int i = 0; i < 16; ++i) { const int j = i ^ stride;
;                 if (j > i) { if ((i & size) == 0) CE_DESC(k[i], k[j]); else CE_DESC(k[j], k[i]); } }
; }
; __device__ __forceinline__ void peer_tile(const Args& A, LAS unsigned char* lds, int tile) {
;     ...
;                 { const bf16_t* sp = QRY + m * 2048 + hp * 128 + 32 * g;
;                   const u32x4 s0 = *(const u32x4*)sp, s1 = *(const u32x4*)(sp + 8), s2 = *(const u32x4*)(sp + 16), s3 = *(const u32x4*)(sp + 24);
;                   const unsigned sw[16] = {s0.x, s0.y, s0.z, s0.w, s1.x, s1.y, s1.z, s1.w, s2.x, s2.y, s2.z, s2.w, s3.x, s3.y, s3.z, s3.w};
; #pragma unroll
;                   for (int i = 0; i < 16; ++i) {
;                       const float lo = (float)__builtin_bit_cast(_Float16, (unsigned short)(sw[i] & 0xffffu)), hi = (float)__builtin_bit_cast(_Float16, (unsigned short)(sw[i] >> 16));
;                       const unsigned klo = (f2key(lo) & ~127u) | (unsigned)(127 - (32 * g + 2 * i)), khi = (f2key(hi) & ~127u) | (unsigned)(127 - (32 * g + 2 * i + 1));
;                       if (i < 8) { k0[2 * i] = klo; k0[2 * i + 1] = khi; } else { k1[2 * (i - 8)] = klo; k1[2 * (i - 8) + 1] = khi; } } }
;                 sort16_desc(k0); sort16_desc(k1); merge16(k0, k1);
	v_cvt_f32_f16_sdwa v21, v28 dst_sel:DWORD dst_unused:UNUSED_PAD src0_sel:WORD_1
	v_and_b32_e32 v32, 0xffffff80, v32
	v_cndmask_b32_e32 v20, v22, v20, vcc
	v_and_b32_e32 v20, 0xffffff80, v20
	v_cvt_f32_f16_e32 v22, v28
	v_not_b32_e32 v23, v21
	v_or_b32_e32 v24, 0x80000000, v21
	v_cmp_gt_i32_e32 vcc, 0, v21
	v_sub_u32_e32 v20, v20, v18
	v_add_u32_e32 v46, 0x7f, v20
	v_cndmask_b32_e32 v21, v24, v23, vcc
	v_or_b32_e32 v20, 16, v15
	v_and_b32_e32 v21, 0xffffff80, v21
	v_sub_u32_e32 v21, v21, v20
	v_add_u32_e32 v47, 0x7e, v21
	v_not_b32_e32 v21, v22
	v_or_b32_e32 v23, 0x80000000, v22
	v_cmp_gt_i32_e32 vcc, 0, v22
	v_cvt_f32_f16_sdwa v22, v29 dst_sel:DWORD dst_unused:UNUSED_PAD src0_sel:WORD_1
	v_sub_u32_e32 v32, v32, v10
	v_cndmask_b32_e32 v21, v23, v21, vcc
	v_and_b32_e32 v21, 0xffffff80, v21
	v_cvt_f32_f16_e32 v23, v29
	v_not_b32_e32 v24, v22
	v_or_b32_e32 v25, 0x80000000, v22
	v_cmp_gt_i32_e32 vcc, 0, v22
	v_sub_u32_e32 v21, v21, v20
	v_add_u32_e32 v48, 0x7f, v21
	v_cndmask_b32_e32 v22, v25, v24, vcc
	v_or_b32_e32 v21, 18, v15
	v_and_b32_e32 v22, 0xffffff80, v22
	v_sub_u32_e32 v22, v22, v21
	v_add_u32_e32 v29, 0x7e, v22
	v_not_b32_e32 v22, v23
	v_or_b32_e32 v24, 0x80000000, v23
	v_cmp_gt_i32_e32 vcc, 0, v23
	v_cvt_f32_f16_sdwa v23, v30 dst_sel:DWORD dst_unused:UNUSED_PAD src0_sel:WORD_1
	v_add_u32_e32 v32, 0x7f, v32
	v_cndmask_b32_e32 v22, v24, v22, vcc
	v_and_b32_e32 v22, 0xffffff80, v22
	v_cvt_f32_f16_e32 v24, v30
	v_not_b32_e32 v25, v23
	v_or_b32_e32 v26, 0x80000000, v23
	v_cmp_gt_i32_e32 vcc, 0, v23
	v_sub_u32_e32 v22, v22, v21
	v_add_u32_e32 v49, 0x7f, v22
	v_cndmask_b32_e32 v23, v26, v25, vcc
	v_or_b32_e32 v22, 20, v15
	v_and_b32_e32 v23, 0xffffff80, v23
	v_sub_u32_e32 v23, v23, v22
	v_add_u32_e32 v30, 0x7e, v23
	v_not_b32_e32 v23, v24
	v_or_b32_e32 v25, 0x80000000, v24
	v_cmp_gt_i32_e32 vcc, 0, v24
	v_cvt_f32_f16_sdwa v24, v31 dst_sel:DWORD dst_unused:UNUSED_PAD src0_sel:WORD_1
	v_max_u32_e32 v64, v48, v47
	v_cndmask_b32_e32 v23, v25, v23, vcc
	v_and_b32_e32 v23, 0xffffff80, v23
	v_cvt_f32_f16_e32 v25, v31
	v_not_b32_e32 v26, v24
	v_or_b32_e32 v28, 0x80000000, v24
	v_cmp_gt_i32_e32 vcc, 0, v24
	v_sub_u32_e32 v23, v23, v22
	v_add_u32_e32 v50, 0x7f, v23
	v_cndmask_b32_e32 v24, v28, v26, vcc
	v_or_b32_e32 v23, 22, v15
	v_and_b32_e32 v24, 0xffffff80, v24
	v_sub_u32_e32 v24, v24, v23
	v_add_u32_e32 v31, 0x7e, v24
	v_not_b32_e32 v24, v25
	v_or_b32_e32 v26, 0x80000000, v25
	v_cmp_gt_i32_e32 vcc, 0, v25
	v_cvt_f32_f16_sdwa v25, v0 dst_sel:DWORD dst_unused:UNUSED_PAD src0_sel:WORD_1
	v_cvt_f32_f16_e32 v0, v0
	v_cndmask_b32_e32 v24, v26, v24, vcc
	v_and_b32_e32 v24, 0xffffff80, v24
	v_not_b32_e32 v26, v25
	v_or_b32_e32 v28, 0x80000000, v25
	v_cmp_gt_i32_e32 vcc, 0, v25
	v_sub_u32_e32 v24, v24, v23
	v_add_u32_e32 v51, 0x7f, v24
	v_cndmask_b32_e32 v25, v28, v26, vcc
	v_or_b32_e32 v24, 24, v15
	v_and_b32_e32 v25, 0xffffff80, v25
	v_sub_u32_e32 v25, v25, v24
	v_add_u32_e32 v52, 0x7e, v25
	v_not_b32_e32 v25, v0
	v_or_b32_e32 v26, 0x80000000, v0
	v_cmp_gt_i32_e32 vcc, 0, v0
	v_min_u32_e32 v47, v48, v47
	v_max_u32_e32 v48, v29, v49
	v_cndmask_b32_e32 v0, v26, v25, vcc
	v_cvt_f32_f16_sdwa v26, v1 dst_sel:DWORD dst_unused:UNUSED_PAD src0_sel:WORD_1
	v_cvt_f32_f16_e32 v1, v1
	v_or_b32_e32 v25, 26, v15
	v_and_b32_e32 v0, 0xffffff80, v0
	v_not_b32_e32 v28, v26
	v_or_b32_e32 v53, 0x80000000, v26
	v_cmp_gt_i32_e32 vcc, 0, v26
	v_sub_u32_e32 v0, v0, v24
	v_add_u32_e32 v0, 0x7f, v0
	v_cndmask_b32_e32 v26, v53, v28, vcc
	v_and_b32_e32 v26, 0xffffff80, v26
	v_sub_u32_e32 v26, v26, v25
	v_add_u32_e32 v53, 0x7e, v26
	v_not_b32_e32 v26, v1
	v_or_b32_e32 v28, 0x80000000, v1
	v_cmp_gt_i32_e32 vcc, 0, v1
	v_min_u32_e32 v29, v29, v49
	v_max_u32_e32 v49, v50, v30
	v_cndmask_b32_e32 v1, v28, v26, vcc
	v_cvt_f32_f16_sdwa v28, v2 dst_sel:DWORD dst_unused:UNUSED_PAD src0_sel:WORD_1
	v_cvt_f32_f16_e32 v2, v2
	v_or_b32_e32 v26, 28, v15
	v_and_b32_e32 v1, 0xffffff80, v1
	v_not_b32_e32 v54, v28
	v_or_b32_e32 v55, 0x80000000, v28
	v_cmp_gt_i32_e32 vcc, 0, v28
	v_sub_u32_e32 v1, v1, v25
	v_add_u32_e32 v1, 0x7f, v1
	v_cndmask_b32_e32 v28, v55, v54, vcc
	v_and_b32_e32 v28, 0xffffff80, v28
	v_sub_u32_e32 v28, v28, v26
	v_add_u32_e32 v54, 0x7e, v28
	v_not_b32_e32 v28, v2
	v_or_b32_e32 v55, 0x80000000, v2
	v_cmp_gt_i32_e32 vcc, 0, v2
	v_min_u32_e32 v30, v50, v30
	v_max_u32_e32 v50, v31, v51
	v_cndmask_b32_e32 v2, v55, v28, vcc
	v_cvt_f32_f16_e32 v55, v3
	v_cvt_f32_f16_sdwa v3, v3 dst_sel:DWORD dst_unused:UNUSED_PAD src0_sel:WORD_1
	v_and_b32_e32 v2, 0xffffff80, v2
	v_or_b32_e32 v28, 30, v15
	v_not_b32_e32 v56, v55
	v_or_b32_e32 v57, 0x80000000, v55
	v_cmp_gt_i32_e32 vcc, 0, v55
	v_sub_u32_e32 v2, v2, v26
	v_add_u32_e32 v2, 0x7f, v2
	v_cndmask_b32_e32 v55, v57, v56, vcc
	v_not_b32_e32 v56, v3
	v_or_b32_e32 v57, 0x80000000, v3
	v_cmp_gt_i32_e32 vcc, 0, v3
	v_and_b32_e32 v55, 0xffffff80, v55
	v_sub_u32_e32 v55, v55, v28
	v_cndmask_b32_e32 v3, v57, v56, vcc
	v_and_b32_e32 v3, 0xffffff80, v3
	v_sub_u32_e32 v3, v3, v28
	v_add_u32_e32 v55, 0x7f, v55
	v_add_u32_e32 v3, 0x7e, v3
	v_max_u32_e32 v56, v35, v34
	v_min_u32_e32 v34, v35, v34
	v_max_u32_e32 v35, v36, v37
	v_min_u32_e32 v36, v36, v37
	v_max_u32_e32 v37, v39, v38
	v_min_u32_e32 v38, v39, v38
	v_max_u32_e32 v39, v40, v32
	v_min_u32_e32 v32, v40, v32
	v_max_u32_e32 v40, v33, v41
	v_min_u32_e32 v33, v33, v41
	v_max_u32_e32 v41, v42, v43
	v_min_u32_e32 v42, v42, v43
	v_max_u32_e32 v43, v45, v44
	v_min_u32_e32 v44, v45, v44
	v_max_u32_e32 v45, v27, v46
	v_min_u32_e32 v27, v27, v46
	v_min_u32_e32 v31, v31, v51
	v_max_u32_e32 v51, v0, v52
	v_min_u32_e32 v0, v0, v52
	v_max_u32_e32 v52, v53, v1
	v_min_u32_e32 v1, v53, v1
	v_max_u32_e32 v53, v2, v54
; #define CE_DESC(a, b) do { const unsigned _mx = (a) > (b) ? (a) : (b), _mn = (a) > (b) ? (b) : (a); (a) = _mx; (b) = _mn; } while (0)
; __device__ __forceinline__ void sort16_desc(unsigned (&k)[16]) {
; #pragma unroll
;     for (int size = 2; size <= 16; size <<= 1)
; #pragma unroll
;         for (int stride = size >> 1; stride > 0; stride >>= 1)
; #pragma unroll
;             for (int i = 0; i < 16; ++i) { const int j = i ^ stride;
;                 if (j > i) { if ((i & size) == 0) CE_DESC(k[i], k[j]); else CE_DESC(k[j], k[i]); } }
; }
	v_min_u32_e32 v2, v2, v54
	v_max_u32_e32 v54, v3, v55
	v_min_u32_e32 v3, v3, v55
	v_max_u32_e32 v46, v56, v36
	v_min_u32_e32 v36, v56, v36
	v_max_u32_e32 v56, v34, v35
	v_min_u32_e32 v34, v34, v35
	v_max_u32_e32 v35, v32, v37
	v_min_u32_e32 v32, v32, v37
	v_max_u32_e32 v37, v39, v38
	v_min_u32_e32 v38, v39, v38
	v_max_u32_e32 v39, v40, v42
	v_min_u32_e32 v40, v40, v42
	v_max_u32_e32 v42, v33, v41
	v_min_u32_e32 v33, v33, v41
	v_max_u32_e32 v41, v27, v43
	v_min_u32_e32 v27, v27, v43
	v_max_u32_e32 v43, v45, v44
	v_min_u32_e32 v44, v45, v44
	v_max_u32_e32 v55, v64, v29
	v_min_u32_e32 v29, v64, v29
	v_max_u32_e32 v64, v47, v48
	v_min_u32_e32 v47, v47, v48
	v_max_u32_e32 v48, v31, v49
	v_min_u32_e32 v31, v31, v49
	v_max_u32_e32 v49, v50, v30
	v_min_u32_e32 v30, v50, v30
	v_max_u32_e32 v50, v51, v1
	v_min_u32_e32 v1, v51, v1
	v_max_u32_e32 v51, v0, v52
	v_min_u32_e32 v0, v0, v52
	v_max_u32_e32 v52, v3, v53
	v_min_u32_e32 v3, v3, v53
	v_max_u32_e32 v53, v54, v2
	v_min_u32_e32 v2, v54, v2
	v_max_u32_e32 v45, v46, v56
	v_min_u32_e32 v46, v46, v56
	v_max_u32_e32 v56, v36, v34
	v_min_u32_e32 v34, v36, v34
	v_max_u32_e32 v36, v38, v32
	v_min_u32_e32 v32, v38, v32
	v_max_u32_e32 v38, v37, v35
	v_min_u32_e32 v35, v37, v35
	v_max_u32_e32 v37, v39, v42
	v_min_u32_e32 v39, v39, v42
	v_max_u32_e32 v42, v40, v33
	v_min_u32_e32 v33, v40, v33
	v_max_u32_e32 v40, v44, v27
	v_min_u32_e32 v27, v44, v27
	v_max_u32_e32 v44, v43, v41
	v_min_u32_e32 v41, v43, v41
	v_max_u32_e32 v54, v55, v64
	v_min_u32_e32 v55, v55, v64
	v_max_u32_e32 v64, v29, v47
	v_min_u32_e32 v29, v29, v47
	v_max_u32_e32 v47, v30, v31
	v_min_u32_e32 v30, v30, v31
	v_max_u32_e32 v31, v49, v48
	v_min_u32_e32 v48, v49, v48
	v_max_u32_e32 v49, v50, v51
	v_min_u32_e32 v50, v50, v51
	v_max_u32_e32 v51, v1, v0
	v_min_u32_e32 v0, v1, v0
	v_max_u32_e32 v1, v2, v3
	v_min_u32_e32 v2, v2, v3
	v_max_u32_e32 v3, v53, v52
	v_min_u32_e32 v52, v53, v52
	v_max_u32_e32 v43, v45, v32
	v_min_u32_e32 v32, v45, v32
	v_max_u32_e32 v45, v46, v36
	v_min_u32_e32 v36, v46, v36
	v_max_u32_e32 v46, v56, v35
	v_min_u32_e32 v35, v56, v35
	v_max_u32_e32 v56, v34, v38
	v_min_u32_e32 v34, v34, v38
	v_max_u32_e32 v38, v27, v37
	v_min_u32_e32 v27, v27, v37
	v_max_u32_e32 v37, v40, v39
	v_min_u32_e32 v39, v40, v39
	v_max_u32_e32 v40, v41, v42
	v_min_u32_e32 v41, v41, v42
	v_max_u32_e32 v42, v44, v33
	v_min_u32_e32 v33, v44, v33
	v_max_u32_e32 v53, v54, v30
	v_min_u32_e32 v30, v54, v30
	v_max_u32_e32 v54, v55, v47
	v_min_u32_e32 v47, v55, v47
	v_max_u32_e32 v55, v64, v48
	v_min_u32_e32 v48, v64, v48
	v_max_u32_e32 v64, v29, v31
	v_min_u32_e32 v29, v29, v31
	v_max_u32_e32 v31, v2, v49
	v_min_u32_e32 v2, v2, v49
	v_max_u32_e32 v49, v1, v50
	v_min_u32_e32 v1, v1, v50
	v_max_u32_e32 v50, v52, v51
	v_min_u32_e32 v51, v52, v51
	v_max_u32_e32 v52, v3, v0
	v_min_u32_e32 v0, v3, v0
	v_max_u32_e32 v44, v43, v46
	v_min_u32_e32 v43, v43, v46
	v_max_u32_e32 v46, v45, v56
	v_min_u32_e32 v45, v45, v56
	v_max_u32_e32 v56, v32, v35
	v_min_u32_e32 v32, v32, v35
	v_max_u32_e32 v35, v36, v34
	v_min_u32_e32 v34, v36, v34
	v_max_u32_e32 v36, v41, v27
	v_min_u32_e32 v27, v41, v27
	v_max_u32_e32 v41, v33, v39
	v_min_u32_e32 v33, v33, v39
	v_max_u32_e32 v39, v40, v38
	v_min_u32_e32 v38, v40, v38
	v_max_u32_e32 v40, v42, v37
	v_min_u32_e32 v37, v42, v37
	v_max_u32_e32 v3, v53, v55
	v_min_u32_e32 v53, v53, v55
	v_max_u32_e32 v55, v54, v64
	v_min_u32_e32 v54, v54, v64
	v_max_u32_e32 v64, v30, v48
	v_min_u32_e32 v30, v30, v48
	v_max_u32_e32 v48, v47, v29
	v_min_u32_e32 v29, v47, v29
	v_max_u32_e32 v47, v51, v2
	v_min_u32_e32 v2, v51, v2
	v_max_u32_e32 v51, v0, v1
	v_min_u32_e32 v0, v0, v1
	v_max_u32_e32 v1, v50, v31
	v_min_u32_e32 v31, v50, v31
	v_max_u32_e32 v50, v52, v49
	v_min_u32_e32 v49, v52, v49
	v_max_u32_e32 v42, v44, v46
	v_min_u32_e32 v44, v44, v46
	v_max_u32_e32 v46, v43, v45
	v_min_u32_e32 v43, v43, v45
	v_max_u32_e32 v45, v56, v35
	v_min_u32_e32 v35, v56, v35
	v_max_u32_e32 v56, v32, v34
	v_min_u32_e32 v32, v32, v34
	v_max_u32_e32 v34, v33, v27
	v_min_u32_e32 v27, v33, v27
	v_max_u32_e32 v33, v41, v36
	v_min_u32_e32 v36, v41, v36
	v_max_u32_e32 v41, v37, v38
	v_min_u32_e32 v37, v37, v38
	v_max_u32_e32 v38, v40, v39
	v_min_u32_e32 v39, v40, v39
	v_max_u32_e32 v52, v3, v55
	v_min_u32_e32 v3, v3, v55
	v_max_u32_e32 v55, v53, v54
	v_min_u32_e32 v53, v53, v54
	v_max_u32_e32 v54, v64, v48
	v_min_u32_e32 v48, v64, v48
	v_max_u32_e32 v64, v30, v29
	v_min_u32_e32 v29, v30, v29
	v_max_u32_e32 v30, v0, v2
	v_min_u32_e32 v0, v0, v2
	v_max_u32_e32 v2, v51, v47
	v_min_u32_e32 v47, v51, v47
	v_max_u32_e32 v51, v49, v31
	v_min_u32_e32 v31, v49, v31
	v_max_u32_e32 v49, v50, v1
	v_min_u32_e32 v1, v50, v1
	v_max_u32_e32 v40, v42, v27
	v_min_u32_e32 v27, v42, v27
	v_max_u32_e32 v42, v44, v34
	v_min_u32_e32 v34, v44, v34
	v_max_u32_e32 v44, v46, v36
	v_min_u32_e32 v36, v46, v36
	v_max_u32_e32 v46, v43, v33
	v_min_u32_e32 v33, v43, v33
	v_max_u32_e32 v43, v45, v37
	v_min_u32_e32 v37, v45, v37
	v_max_u32_e32 v45, v35, v41
	v_min_u32_e32 v35, v35, v41
	v_max_u32_e32 v41, v56, v39
	v_min_u32_e32 v39, v56, v39
	v_max_u32_e32 v56, v32, v38
	v_min_u32_e32 v32, v32, v38
	v_max_u32_e32 v50, v52, v0
	v_min_u32_e32 v0, v52, v0
	v_max_u32_e32 v52, v3, v30
	v_min_u32_e32 v3, v3, v30
	v_max_u32_e32 v30, v55, v47
	v_min_u32_e32 v47, v55, v47
	v_max_u32_e32 v55, v53, v2
	v_min_u32_e32 v2, v53, v2
	v_max_u32_e32 v53, v54, v31
	v_min_u32_e32 v31, v54, v31
	v_max_u32_e32 v54, v48, v51
	v_min_u32_e32 v48, v48, v51
	v_max_u32_e32 v51, v64, v1
	v_min_u32_e32 v1, v64, v1
	v_max_u32_e32 v64, v29, v49
	v_min_u32_e32 v29, v29, v49
	v_max_u32_e32 v38, v40, v43
	v_min_u32_e32 v40, v40, v43
; #define CE_DESC(a, b) do { const unsigned _mx = (a) > (b) ? (a) : (b), _mn = (a) > (b) ? (b) : (a); (a) = _mx; (b) = _mn; } while (0)
; __device__ __forceinline__ void merge16(unsigned (&a)[16], const unsigned (&b)[16]) {
; #pragma unroll
;     for (int i = 0; i < 16; ++i) a[i] = a[i] > b[15 - i] ? a[i] : b[15 - i];
; #pragma unroll
;     for (int stride = 8; stride > 0; stride >>= 1)
; #pragma unroll
;         for (int i = 0; i < 16; ++i) { const int j = i ^ stride; if (j > i) CE_DESC(a[i], a[j]); }
; }
; __device__ __forceinline__ void peer_tile(const Args& A, LAS unsigned char* lds, int tile) {
;     ...
;                 sort16_desc(k0); sort16_desc(k1); merge16(k0, k1);
; #pragma unroll
;                 for (int msk = 16; msk <= 32; msk <<= 1) {
; #pragma unroll
;                     for (int i = 0; i < 16; ++i) k1[i] = (unsigned)__shfl_xor((int)k0[i], msk);
;                     merge16(k0, k1); }
	v_max_u32_e32 v43, v42, v45
	v_min_u32_e32 v42, v42, v45
	v_max_u32_e32 v45, v44, v41
	v_min_u32_e32 v41, v44, v41
	v_max_u32_e32 v44, v46, v56
	v_min_u32_e32 v46, v46, v56
	v_max_u32_e32 v56, v27, v37
	v_min_u32_e32 v27, v27, v37
	v_max_u32_e32 v37, v34, v35
	v_min_u32_e32 v34, v34, v35
	v_max_u32_e32 v35, v36, v39
	v_min_u32_e32 v36, v36, v39
	v_max_u32_e32 v39, v33, v32
	v_min_u32_e32 v32, v33, v32
	v_max_u32_e32 v49, v50, v53
	v_min_u32_e32 v50, v50, v53
	v_max_u32_e32 v53, v52, v54
	v_min_u32_e32 v52, v52, v54
	v_max_u32_e32 v54, v30, v51
	v_min_u32_e32 v30, v30, v51
	v_max_u32_e32 v51, v55, v64
	v_min_u32_e32 v55, v55, v64
	v_max_u32_e32 v64, v0, v31
	v_min_u32_e32 v0, v0, v31
	v_max_u32_e32 v31, v3, v48
	v_min_u32_e32 v3, v3, v48
	v_max_u32_e32 v48, v47, v1
	v_min_u32_e32 v1, v47, v1
	v_max_u32_e32 v47, v2, v29
	v_min_u32_e32 v2, v2, v29
	v_max_u32_e32 v33, v38, v45
	v_min_u32_e32 v38, v38, v45
	v_max_u32_e32 v45, v43, v44
	v_min_u32_e32 v43, v43, v44
	v_max_u32_e32 v44, v40, v41
	v_min_u32_e32 v40, v40, v41
	v_max_u32_e32 v41, v42, v46
	v_min_u32_e32 v42, v42, v46
	v_max_u32_e32 v46, v56, v35
	v_min_u32_e32 v35, v56, v35
	v_max_u32_e32 v56, v37, v39
	v_min_u32_e32 v37, v37, v39
	v_max_u32_e32 v39, v27, v36
	v_min_u32_e32 v27, v27, v36
	v_max_u32_e32 v36, v34, v32
	v_min_u32_e32 v32, v34, v32
	v_max_u32_e32 v29, v49, v54
	v_min_u32_e32 v49, v49, v54
	v_max_u32_e32 v54, v53, v51
	v_min_u32_e32 v51, v53, v51
	v_max_u32_e32 v53, v50, v30
	v_min_u32_e32 v30, v50, v30
	v_max_u32_e32 v50, v52, v55
	v_min_u32_e32 v52, v52, v55
	v_max_u32_e32 v55, v64, v48
	v_min_u32_e32 v48, v64, v48
	v_max_u32_e32 v64, v31, v47
	v_min_u32_e32 v31, v31, v47
	v_max_u32_e32 v47, v0, v1
	v_min_u32_e32 v0, v0, v1
	v_max_u32_e32 v1, v3, v2
	v_min_u32_e32 v2, v3, v2
	v_min_u32_e32 v34, v33, v45
	v_min_u32_e32 v57, v38, v43
	v_min_u32_e32 v58, v44, v41
	v_min_u32_e32 v59, v40, v42
	v_min_u32_e32 v60, v46, v56
	v_min_u32_e32 v61, v35, v37
	v_min_u32_e32 v62, v39, v36
	v_min_u32_e32 v63, v27, v32
	v_min_u32_e32 v3, v29, v54
	v_min_u32_e32 v65, v49, v51
	v_min_u32_e32 v66, v53, v50
	v_min_u32_e32 v67, v30, v52
	v_min_u32_e32 v68, v55, v64
	v_min_u32_e32 v69, v48, v31
	v_min_u32_e32 v70, v47, v1
	v_min_u32_e32 v71, v0, v2
	v_max3_u32 v33, v33, v45, v71
	v_max3_u32 v0, v34, v0, v2
	v_max3_u32 v2, v38, v43, v70
	v_max3_u32 v1, v57, v47, v1
	v_max3_u32 v34, v44, v41, v69
	v_max3_u32 v31, v58, v48, v31
	v_max3_u32 v38, v40, v42, v68
	v_max3_u32 v40, v59, v55, v64
	v_max3_u32 v41, v46, v56, v67
	v_max3_u32 v30, v60, v30, v52
	v_max3_u32 v35, v35, v37, v66
	v_max3_u32 v37, v61, v53, v50
	v_max3_u32 v36, v39, v36, v65
	v_max3_u32 v39, v62, v49, v51
	v_max3_u32 v3, v27, v32, v3
	v_max3_u32 v27, v63, v29, v54
	v_max_u32_e32 v29, v33, v41
	v_min_u32_e32 v32, v33, v41
	v_max_u32_e32 v33, v0, v30
	v_min_u32_e32 v0, v0, v30
	v_max_u32_e32 v30, v2, v35
	v_min_u32_e32 v2, v2, v35
	v_max_u32_e32 v35, v1, v37
	v_min_u32_e32 v1, v1, v37
	v_max_u32_e32 v37, v34, v36
	v_min_u32_e32 v34, v34, v36
	v_max_u32_e32 v36, v31, v39
	v_min_u32_e32 v31, v31, v39
	v_max_u32_e32 v39, v38, v3
	v_min_u32_e32 v3, v38, v3
	v_max_u32_e32 v38, v40, v27
	v_min_u32_e32 v27, v40, v27
	v_max_u32_e32 v40, v29, v37
	v_min_u32_e32 v29, v29, v37
	v_max_u32_e32 v37, v33, v36
	v_min_u32_e32 v33, v33, v36
	v_max_u32_e32 v36, v30, v39
	v_min_u32_e32 v30, v30, v39
	v_max_u32_e32 v39, v35, v38
	v_min_u32_e32 v35, v35, v38
	v_max_u32_e32 v38, v32, v34
	v_min_u32_e32 v32, v32, v34
	v_max_u32_e32 v34, v0, v31
	v_min_u32_e32 v0, v0, v31
	v_max_u32_e32 v31, v2, v3
	v_min_u32_e32 v2, v2, v3
	v_max_u32_e32 v3, v1, v27
	v_min_u32_e32 v1, v1, v27
	v_max_u32_e32 v27, v40, v36
	v_min_u32_e32 v36, v40, v36
	v_max_u32_e32 v40, v37, v39
	v_min_u32_e32 v37, v37, v39
	v_max_u32_e32 v39, v29, v30
	v_min_u32_e32 v29, v29, v30
	v_max_u32_e32 v30, v33, v35
	v_min_u32_e32 v33, v33, v35
	v_max_u32_e32 v35, v38, v31
	v_min_u32_e32 v31, v38, v31
	v_max_u32_e32 v38, v34, v3
	v_min_u32_e32 v3, v34, v3
	v_max_u32_e32 v34, v32, v2
	v_min_u32_e32 v2, v32, v2
	v_max_u32_e32 v32, v0, v1
	v_min_u32_e32 v0, v0, v1
	v_cmp_lt_i32_e32 vcc, v217, v216
	v_max_u32_e32 v41, v36, v37
	v_min_u32_e32 v36, v36, v37
	v_max_u32_e32 v37, v39, v30
	v_min_u32_e32 v30, v39, v30
	v_max_u32_e32 v39, v29, v33
	v_min_u32_e32 v29, v29, v33
	v_max_u32_e32 v33, v35, v38
	v_min_u32_e32 v35, v35, v38
	v_max_u32_e32 v38, v31, v3
	v_min_u32_e32 v3, v31, v3
	v_max_u32_e32 v31, v34, v32
	v_min_u32_e32 v32, v34, v32
	v_max_u32_e32 v34, v2, v0
	v_min_u32_e32 v0, v2, v0
	v_cndmask_b32_e32 v2, v215, v217, vcc
	v_max_u32_e32 v1, v27, v40
	v_min_u32_e32 v40, v27, v40
	v_lshlrev_b32_e32 v27, 2, v2
	ds_bpermute_b32 v2, v27, v1
	ds_bpermute_b32 v42, v27, v40
	ds_bpermute_b32 v43, v27, v41
	ds_bpermute_b32 v44, v27, v36
	ds_bpermute_b32 v45, v27, v37
	ds_bpermute_b32 v46, v27, v30
	ds_bpermute_b32 v47, v27, v39
	ds_bpermute_b32 v48, v27, v29
	ds_bpermute_b32 v49, v27, v33
	ds_bpermute_b32 v50, v27, v35
	ds_bpermute_b32 v51, v27, v38
	ds_bpermute_b32 v52, v27, v0
	ds_bpermute_b32 v53, v27, v34
	ds_bpermute_b32 v54, v27, v32
	ds_bpermute_b32 v55, v27, v31
	ds_bpermute_b32 v56, v27, v3
	s_waitcnt lgkmcnt(4)
	v_max_u32_e32 v1, v1, v52
	s_waitcnt lgkmcnt(3)
	v_max_u32_e32 v40, v40, v53
	s_waitcnt lgkmcnt(2)
	v_max_u32_e32 v41, v41, v54
	s_waitcnt lgkmcnt(1)
	v_max_u32_e32 v36, v36, v55
	s_waitcnt lgkmcnt(0)
; #define CE_DESC(a, b) do { const unsigned _mx = (a) > (b) ? (a) : (b), _mn = (a) > (b) ? (b) : (a); (a) = _mx; (b) = _mn; } while (0)
; __device__ __forceinline__ void merge16(unsigned (&a)[16], const unsigned (&b)[16]) {
; #pragma unroll
;     for (int i = 0; i < 16; ++i) a[i] = a[i] > b[15 - i] ? a[i] : b[15 - i];
; #pragma unroll
;     for (int stride = 8; stride > 0; stride >>= 1)
; #pragma unroll
;         for (int i = 0; i < 16; ++i) { const int j = i ^ stride; if (j > i) CE_DESC(a[i], a[j]); }
; }
; __device__ __forceinline__ void peer_tile(const Args& A, LAS unsigned char* lds, int tile) {
;     ...
;                 for (int msk = 16; msk <= 32; msk <<= 1) {
; #pragma unroll
;                     for (int i = 0; i < 16; ++i) k1[i] = (unsigned)__shfl_xor((int)k0[i], msk);
;                     merge16(k0, k1); }
	v_max_u32_e32 v37, v37, v56
	v_max_u32_e32 v30, v30, v51
	v_max_u32_e32 v39, v39, v50
	v_max_u32_e32 v29, v29, v49
	v_max_u32_e32 v33, v33, v48
	v_max_u32_e32 v35, v35, v47
	v_max_u32_e32 v38, v38, v46
	v_max_u32_e32 v3, v3, v45
	v_max_u32_e32 v31, v31, v44
	v_max_u32_e32 v32, v32, v43
	v_max_u32_e32 v34, v34, v42
	v_max_u32_e32 v0, v0, v2
	v_max_u32_e32 v2, v1, v33
	v_min_u32_e32 v1, v1, v33
	v_max_u32_e32 v33, v40, v35
	v_min_u32_e32 v35, v40, v35
	v_max_u32_e32 v40, v41, v38
	v_min_u32_e32 v38, v41, v38
	v_max_u32_e32 v41, v36, v3
	v_min_u32_e32 v3, v36, v3
	v_max_u32_e32 v36, v37, v31
	v_min_u32_e32 v31, v37, v31
	v_max_u32_e32 v37, v30, v32
	v_min_u32_e32 v30, v30, v32
	v_max_u32_e32 v32, v39, v34
	v_min_u32_e32 v34, v39, v34
	v_max_u32_e32 v39, v29, v0
	v_min_u32_e32 v0, v29, v0
	v_max_u32_e32 v29, v2, v36
	v_min_u32_e32 v2, v2, v36
	v_max_u32_e32 v36, v33, v37
	v_min_u32_e32 v33, v33, v37
	v_max_u32_e32 v37, v40, v32
	v_min_u32_e32 v32, v40, v32
	v_max_u32_e32 v40, v41, v39
	v_min_u32_e32 v39, v41, v39
	v_max_u32_e32 v41, v1, v31
	v_min_u32_e32 v1, v1, v31
	v_max_u32_e32 v31, v35, v30
	v_min_u32_e32 v30, v35, v30
	v_max_u32_e32 v35, v38, v34
	v_min_u32_e32 v34, v38, v34
	v_max_u32_e32 v38, v3, v0
	v_min_u32_e32 v0, v3, v0
	v_max_u32_e32 v3, v29, v37
	v_min_u32_e32 v29, v29, v37
	v_max_u32_e32 v37, v36, v40
	v_min_u32_e32 v36, v36, v40
	v_max_u32_e32 v40, v2, v32
	v_min_u32_e32 v2, v2, v32
	v_max_u32_e32 v32, v33, v39
	v_min_u32_e32 v33, v33, v39
	v_max_u32_e32 v39, v41, v35
	v_min_u32_e32 v35, v41, v35
	v_max_u32_e32 v41, v31, v38
	v_min_u32_e32 v31, v31, v38
	v_max_u32_e32 v38, v1, v34
	v_min_u32_e32 v1, v1, v34
	v_max_u32_e32 v34, v30, v0
	v_min_u32_e32 v0, v30, v0
	v_cmp_lt_i32_e32 vcc, v218, v216
	v_max_u32_e32 v42, v40, v32
	v_min_u32_e32 v32, v40, v32
	v_max_u32_e32 v40, v2, v33
	v_min_u32_e32 v2, v2, v33
	v_max_u32_e32 v33, v39, v41
	v_min_u32_e32 v39, v39, v41
	v_max_u32_e32 v41, v35, v31
	v_min_u32_e32 v31, v35, v31
	v_max_u32_e32 v35, v38, v34
	v_min_u32_e32 v34, v38, v34
	v_max_u32_e32 v38, v1, v0
	v_min_u32_e32 v0, v1, v0
	v_cndmask_b32_e32 v1, v215, v218, vcc
	v_max_u32_e32 v30, v3, v37
	v_min_u32_e32 v3, v3, v37
	v_max_u32_e32 v37, v29, v36
	v_min_u32_e32 v36, v29, v36
	v_lshlrev_b32_e32 v29, 2, v1
	ds_bpermute_b32 v46, v29, v0
	ds_bpermute_b32 v1, v29, v30
	ds_bpermute_b32 v43, v29, v3
	ds_bpermute_b32 v44, v29, v37
	ds_bpermute_b32 v45, v29, v36
	s_waitcnt lgkmcnt(4)
	v_max_u32_e32 v30, v30, v46
	global_load_dwordx4 v[46:49], v[4:5], off offset:272
	global_load_dwordx4 v[50:53], v[4:5], off offset:256
	ds_bpermute_b32 v54, v29, v42
	ds_bpermute_b32 v55, v29, v32
	ds_bpermute_b32 v56, v29, v40
	ds_bpermute_b32 v57, v29, v2
	ds_bpermute_b32 v58, v29, v33
	ds_bpermute_b32 v59, v29, v39
	ds_bpermute_b32 v60, v29, v41
	ds_bpermute_b32 v61, v29, v31
	ds_bpermute_b32 v62, v29, v35
	ds_bpermute_b32 v63, v29, v38
	ds_bpermute_b32 v64, v29, v34
	s_waitcnt lgkmcnt(4)
	v_max_u32_e32 v32, v32, v60
	s_waitcnt lgkmcnt(3)
	v_max_u32_e32 v42, v42, v61
	s_waitcnt lgkmcnt(2)
	v_max_u32_e32 v36, v36, v62
	s_waitcnt lgkmcnt(1)
	v_max_u32_e32 v3, v3, v63
	s_waitcnt lgkmcnt(0)
	v_max_u32_e32 v37, v37, v64
	v_max_u32_e32 v40, v40, v59
	v_max_u32_e32 v2, v2, v58
	v_max_u32_e32 v33, v33, v57
	v_max_u32_e32 v39, v39, v56
	v_max_u32_e32 v41, v41, v55
	v_max_u32_e32 v31, v31, v54
	v_max_u32_e32 v35, v35, v45
	v_max_u32_e32 v34, v34, v44
	v_max_u32_e32 v38, v38, v43
	v_max_u32_e32 v0, v0, v1
	v_max_u32_e32 v1, v30, v33
	v_min_u32_e32 v30, v30, v33
	v_max_u32_e32 v33, v3, v39
	v_min_u32_e32 v3, v3, v39
	v_max_u32_e32 v39, v37, v41
	v_min_u32_e32 v37, v37, v41
	v_max_u32_e32 v41, v36, v31
	v_min_u32_e32 v31, v36, v31
	v_max_u32_e32 v36, v42, v35
	v_min_u32_e32 v35, v42, v35
	v_max_u32_e32 v42, v32, v34
	v_min_u32_e32 v32, v32, v34
	v_max_u32_e32 v34, v40, v38
	v_min_u32_e32 v38, v40, v38
	v_max_u32_e32 v40, v2, v0
	v_min_u32_e32 v0, v2, v0
	v_max_u32_e32 v2, v1, v36
	v_min_u32_e32 v1, v1, v36
	v_max_u32_e32 v36, v33, v42
	v_min_u32_e32 v33, v33, v42
	v_max_u32_e32 v42, v39, v34
	v_min_u32_e32 v34, v39, v34
	v_max_u32_e32 v39, v41, v40
	v_min_u32_e32 v40, v41, v40
	v_max_u32_e32 v41, v30, v35
	v_min_u32_e32 v30, v30, v35
	v_max_u32_e32 v35, v3, v32
	v_min_u32_e32 v3, v3, v32
	v_max_u32_e32 v32, v37, v38
	v_min_u32_e32 v37, v37, v38
	v_max_u32_e32 v38, v31, v0
	v_min_u32_e32 v0, v31, v0
	v_max_u32_e32 v31, v2, v42
	v_min_u32_e32 v2, v2, v42
	v_max_u32_e32 v42, v36, v39
	v_min_u32_e32 v36, v36, v39
	v_max_u32_e32 v39, v1, v34
	v_min_u32_e32 v1, v1, v34
	v_max_u32_e32 v34, v33, v40
	v_min_u32_e32 v33, v33, v40
	v_max_u32_e32 v54, v41, v32
	v_min_u32_e32 v32, v41, v32
	v_max_u32_e32 v55, v35, v38
	v_min_u32_e32 v56, v35, v38
	v_max_u32_e32 v57, v30, v37
	v_min_u32_e32 v30, v30, v37
	v_max_u32_e32 v58, v3, v0
	v_min_u32_e32 v0, v3, v0
	v_max_u32_e32 v45, v31, v42
	v_min_u32_e32 v44, v31, v42
	v_max_u32_e32 v43, v2, v36
	v_min_u32_e32 v42, v2, v36
	v_max_u32_e32 v41, v39, v34
	v_min_u32_e32 v40, v39, v34
	v_max_u32_e32 v39, v1, v33
	v_min_u32_e32 v38, v1, v33
	v_max_u32_e32 v37, v54, v55
	v_min_u32_e32 v36, v54, v55
	v_max_u32_e32 v35, v32, v56
	v_min_u32_e32 v34, v32, v56
	v_max_u32_e32 v33, v57, v58
	v_min_u32_e32 v32, v57, v58
	v_max_u32_e32 v31, v30, v0
	v_min_u32_e32 v30, v30, v0
	global_load_dwordx4 v[0:3], v[4:5], off offset:304
	global_load_dwordx4 v[54:57], v[4:5], off offset:288
	s_waitcnt vmcnt(2)
; __device__ __forceinline__ unsigned f2key(float f) { const unsigned u = __float_as_uint(f); return (u & 0x80000000u) ? ~u : (u | 0x80000000u); }
; __device__ __forceinline__ void peer_tile(const Args& A, LAS unsigned char* lds, int tile) {
;     ...
;                 { const bf16_t* sp = QRY + m * 2048 + hp * 128 + 32 * g;
;                   const u32x4 s0 = *(const u32x4*)sp, s1 = *(const u32x4*)(sp + 8), s2 = *(const u32x4*)(sp + 16), s3 = *(const u32x4*)(sp + 24);
;                   const unsigned sw[16] = {s0.x, s0.y, s0.z, s0.w, s1.x, s1.y, s1.z, s1.w, s2.x, s2.y, s2.z, s2.w, s3.x, s3.y, s3.z, s3.w};
; #pragma unroll
;                   for (int i = 0; i < 16; ++i) {
;                       const float lo = (float)__builtin_bit_cast(_Float16, (unsigned short)(sw[i] & 0xffffu)), hi = (float)__builtin_bit_cast(_Float16, (unsigned short)(sw[i] >> 16));
;                       const unsigned klo = (f2key(lo) & ~127u) | (unsigned)(127 - (32 * g + 2 * i)), khi = (f2key(hi) & ~127u) | (unsigned)(127 - (32 * g + 2 * i + 1));
;                       if (i < 8) { k0[2 * i] = klo; k0[2 * i + 1] = khi; } else { k1[2 * (i - 8)] = klo; k1[2 * (i - 8) + 1] = khi; } } }
	v_cvt_f32_f16_sdwa v58, v50 dst_sel:DWORD dst_unused:UNUSED_PAD src0_sel:WORD_1
	v_cvt_f32_f16_e32 v50, v50
	v_not_b32_e32 v59, v58
	v_or_b32_e32 v60, 0x80000000, v58
	v_cmp_gt_i32_e32 vcc, 0, v58
	s_nop 1
	v_cndmask_b32_e32 v58, v60, v59, vcc
	v_not_b32_e32 v59, v50
	v_or_b32_e32 v60, 0x80000000, v50
	v_cmp_gt_i32_e32 vcc, 0, v50
	v_and_b32_e32 v58, 0xffffff80, v58
	v_sub_u32_e32 v58, v58, v15
	v_cndmask_b32_e32 v50, v60, v59, vcc
	v_cvt_f32_f16_sdwa v59, v51 dst_sel:DWORD dst_unused:UNUSED_PAD src0_sel:WORD_1
	v_cvt_f32_f16_e32 v51, v51
	v_and_b32_e32 v50, 0xffffff80, v50
	v_sub_u32_e32 v50, v50, v15
	v_not_b32_e32 v60, v59
	v_or_b32_e32 v61, 0x80000000, v59
	v_cmp_gt_i32_e32 vcc, 0, v59
	v_add_u32_e32 v58, 0x7e, v58
	v_add_u32_e32 v50, 0x7f, v50
	v_cndmask_b32_e32 v59, v61, v60, vcc
	v_not_b32_e32 v60, v51
	v_or_b32_e32 v61, 0x80000000, v51
	v_cmp_gt_i32_e32 vcc, 0, v51
	v_and_b32_e32 v59, 0xffffff80, v59
	v_sub_u32_e32 v59, v59, v14
	v_cndmask_b32_e32 v51, v61, v60, vcc
	v_cvt_f32_f16_sdwa v60, v52 dst_sel:DWORD dst_unused:UNUSED_PAD src0_sel:WORD_1
	v_cvt_f32_f16_e32 v52, v52
	v_and_b32_e32 v51, 0xffffff80, v51
	v_sub_u32_e32 v51, v51, v14
	v_not_b32_e32 v61, v60
	v_or_b32_e32 v62, 0x80000000, v60
	v_cmp_gt_i32_e32 vcc, 0, v60
	v_add_u32_e32 v59, 0x7e, v59
	v_add_u32_e32 v51, 0x7f, v51
	v_cndmask_b32_e32 v60, v62, v61, vcc
	v_not_b32_e32 v61, v52
	v_or_b32_e32 v62, 0x80000000, v52
	v_cmp_gt_i32_e32 vcc, 0, v52
	v_and_b32_e32 v60, 0xffffff80, v60
	v_sub_u32_e32 v60, v60, v12
	v_cndmask_b32_e32 v52, v62, v61, vcc
	v_cvt_f32_f16_sdwa v61, v53 dst_sel:DWORD dst_unused:UNUSED_PAD src0_sel:WORD_1
	v_cvt_f32_f16_e32 v53, v53
	v_and_b32_e32 v52, 0xffffff80, v52
	v_sub_u32_e32 v52, v52, v12
	v_not_b32_e32 v62, v61
	v_or_b32_e32 v63, 0x80000000, v61
	v_cmp_gt_i32_e32 vcc, 0, v61
	v_add_u32_e32 v60, 0x7e, v60
	v_add_u32_e32 v52, 0x7f, v52
	v_cndmask_b32_e32 v61, v63, v62, vcc
	v_not_b32_e32 v62, v53
	v_or_b32_e32 v63, 0x80000000, v53
	v_cmp_gt_i32_e32 vcc, 0, v53
	v_and_b32_e32 v61, 0xffffff80, v61
	v_sub_u32_e32 v61, v61, v10
	v_cndmask_b32_e32 v53, v63, v62, vcc
	v_cvt_f32_f16_sdwa v62, v46 dst_sel:DWORD dst_unused:UNUSED_PAD src0_sel:WORD_1
	v_cvt_f32_f16_e32 v46, v46
	v_and_b32_e32 v53, 0xffffff80, v53
	v_sub_u32_e32 v53, v53, v10
	v_not_b32_e32 v63, v62
	v_or_b32_e32 v64, 0x80000000, v62
	v_cmp_gt_i32_e32 vcc, 0, v62
	v_add_u32_e32 v61, 0x7e, v61
	v_add_u32_e32 v53, 0x7f, v53
	v_cndmask_b32_e32 v62, v64, v63, vcc
	v_not_b32_e32 v63, v46
	v_or_b32_e32 v64, 0x80000000, v46
	v_cmp_gt_i32_e32 vcc, 0, v46
	v_and_b32_e32 v62, 0xffffff80, v62
	v_sub_u32_e32 v62, v62, v8
	v_cndmask_b32_e32 v46, v64, v63, vcc
	v_cvt_f32_f16_sdwa v63, v47 dst_sel:DWORD dst_unused:UNUSED_PAD src0_sel:WORD_1
	v_cvt_f32_f16_e32 v47, v47
	v_and_b32_e32 v46, 0xffffff80, v46
	v_sub_u32_e32 v46, v46, v8
	v_not_b32_e32 v64, v63
	v_or_b32_e32 v65, 0x80000000, v63
	v_cmp_gt_i32_e32 vcc, 0, v63
	v_add_u32_e32 v62, 0x7e, v62
	v_add_u32_e32 v46, 0x7f, v46
	v_cndmask_b32_e32 v63, v65, v64, vcc
	v_not_b32_e32 v64, v47
	v_or_b32_e32 v65, 0x80000000, v47
	v_cmp_gt_i32_e32 vcc, 0, v47
	v_and_b32_e32 v63, 0xffffff80, v63
	v_sub_u32_e32 v63, v63, v16
	v_cndmask_b32_e32 v47, v65, v64, vcc
	v_cvt_f32_f16_sdwa v64, v48 dst_sel:DWORD dst_unused:UNUSED_PAD src0_sel:WORD_1
	v_cvt_f32_f16_e32 v48, v48
	v_and_b32_e32 v47, 0xffffff80, v47
	v_sub_u32_e32 v47, v47, v16
	v_not_b32_e32 v65, v64
	v_or_b32_e32 v66, 0x80000000, v64
	v_cmp_gt_i32_e32 vcc, 0, v64
	v_add_u32_e32 v63, 0x7e, v63
	v_add_u32_e32 v47, 0x7f, v47
	v_cndmask_b32_e32 v64, v66, v65, vcc
	v_not_b32_e32 v65, v48
	v_or_b32_e32 v66, 0x80000000, v48
	v_cmp_gt_i32_e32 vcc, 0, v48
	v_and_b32_e32 v64, 0xffffff80, v64
	v_sub_u32_e32 v64, v64, v17
	v_cndmask_b32_e32 v48, v66, v65, vcc
	v_cvt_f32_f16_sdwa v65, v49 dst_sel:DWORD dst_unused:UNUSED_PAD src0_sel:WORD_1
	v_cvt_f32_f16_e32 v49, v49
	v_and_b32_e32 v48, 0xffffff80, v48
	v_sub_u32_e32 v48, v48, v17
	v_not_b32_e32 v66, v65
	v_or_b32_e32 v67, 0x80000000, v65
	v_cmp_gt_i32_e32 vcc, 0, v65
	v_add_u32_e32 v64, 0x7e, v64
	v_add_u32_e32 v48, 0x7f, v48
	v_cndmask_b32_e32 v65, v67, v66, vcc
	v_not_b32_e32 v66, v49
	v_or_b32_e32 v67, 0x80000000, v49
	v_cmp_gt_i32_e32 vcc, 0, v49
	v_and_b32_e32 v65, 0xffffff80, v65
	v_sub_u32_e32 v65, v65, v18
	v_cndmask_b32_e32 v49, v67, v66, vcc
	s_waitcnt vmcnt(0)
; __device__ __forceinline__ unsigned f2key(float f) { const unsigned u = __float_as_uint(f); return (u & 0x80000000u) ? ~u : (u | 0x80000000u); }
; #define CE_DESC(a, b) do { const unsigned _mx = (a) > (b) ? (a) : (b), _mn = (a) > (b) ? (b) : (a); (a) = _mx; (b) = _mn; } while (0)
; __device__ __forceinline__ void sort16_desc(unsigned (&k)[16]) {
; #pragma unroll
;     for (int size = 2; size <= 16; size <<= 1)
; #pragma unroll
;         for (int stride = size >> 1; stride > 0; stride >>= 1)
; #pragma unroll
;             for (int i = 0; i < 16; ++i) { const int j = i ^ stride;
;                 if (j > i) { if ((i & size) == 0) CE_DESC(k[i], k[j]); else CE_DESC(k[j], k[i]); } }
; }
; __device__ __forceinline__ void peer_tile(const Args& A, LAS unsigned char* lds, int tile) {
;     ...
;                 { const bf16_t* sp = QRY + m * 2048 + hp * 128 + 32 * g;
;                   const u32x4 s0 = *(const u32x4*)sp, s1 = *(const u32x4*)(sp + 8), s2 = *(const u32x4*)(sp + 16), s3 = *(const u32x4*)(sp + 24);
;                   const unsigned sw[16] = {s0.x, s0.y, s0.z, s0.w, s1.x, s1.y, s1.z, s1.w, s2.x, s2.y, s2.z, s2.w, s3.x, s3.y, s3.z, s3.w};
; #pragma unroll
;                   for (int i = 0; i < 16; ++i) {
;                       const float lo = (float)__builtin_bit_cast(_Float16, (unsigned short)(sw[i] & 0xffffu)), hi = (float)__builtin_bit_cast(_Float16, (unsigned short)(sw[i] >> 16));
;                       const unsigned klo = (f2key(lo) & ~127u) | (unsigned)(127 - (32 * g + 2 * i)), khi = (f2key(hi) & ~127u) | (unsigned)(127 - (32 * g + 2 * i + 1));
;                       if (i < 8) { k0[2 * i] = klo; k0[2 * i + 1] = khi; } else { k1[2 * (i - 8)] = klo; k1[2 * (i - 8) + 1] = khi; } } }
;                 sort16_desc(k0); sort16_desc(k1); merge16(k0, k1);
	v_cvt_f32_f16_sdwa v66, v54 dst_sel:DWORD dst_unused:UNUSED_PAD src0_sel:WORD_1
	v_cvt_f32_f16_e32 v54, v54
	v_and_b32_e32 v49, 0xffffff80, v49
	v_sub_u32_e32 v49, v49, v18
	v_not_b32_e32 v67, v66
	v_or_b32_e32 v68, 0x80000000, v66
	v_cmp_gt_i32_e32 vcc, 0, v66
	v_add_u32_e32 v65, 0x7e, v65
	v_add_u32_e32 v49, 0x7f, v49
	v_cndmask_b32_e32 v66, v68, v67, vcc
	v_not_b32_e32 v67, v54
	v_or_b32_e32 v68, 0x80000000, v54
	v_cmp_gt_i32_e32 vcc, 0, v54
	v_and_b32_e32 v66, 0xffffff80, v66
	v_sub_u32_e32 v66, v66, v20
	v_cndmask_b32_e32 v54, v68, v67, vcc
	v_cvt_f32_f16_sdwa v67, v55 dst_sel:DWORD dst_unused:UNUSED_PAD src0_sel:WORD_1
	v_cvt_f32_f16_e32 v55, v55
	v_and_b32_e32 v54, 0xffffff80, v54
	v_sub_u32_e32 v54, v54, v20
	v_not_b32_e32 v68, v67
	v_or_b32_e32 v69, 0x80000000, v67
	v_cmp_gt_i32_e32 vcc, 0, v67
	v_add_u32_e32 v66, 0x7e, v66
	v_add_u32_e32 v54, 0x7f, v54
	v_cndmask_b32_e32 v67, v69, v68, vcc
	v_not_b32_e32 v68, v55
	v_or_b32_e32 v69, 0x80000000, v55
	v_cmp_gt_i32_e32 vcc, 0, v55
	v_and_b32_e32 v67, 0xffffff80, v67
	v_sub_u32_e32 v67, v67, v21
	v_cndmask_b32_e32 v55, v69, v68, vcc
	v_cvt_f32_f16_sdwa v68, v56 dst_sel:DWORD dst_unused:UNUSED_PAD src0_sel:WORD_1
	v_cvt_f32_f16_e32 v56, v56
	v_and_b32_e32 v55, 0xffffff80, v55
	v_sub_u32_e32 v55, v55, v21
	v_not_b32_e32 v69, v68
	v_or_b32_e32 v70, 0x80000000, v68
	v_cmp_gt_i32_e32 vcc, 0, v68
	v_add_u32_e32 v67, 0x7e, v67
	v_add_u32_e32 v55, 0x7f, v55
	v_cndmask_b32_e32 v68, v70, v69, vcc
	v_not_b32_e32 v69, v56
	v_or_b32_e32 v70, 0x80000000, v56
	v_cmp_gt_i32_e32 vcc, 0, v56
	v_and_b32_e32 v68, 0xffffff80, v68
	v_sub_u32_e32 v68, v68, v22
	v_cndmask_b32_e32 v56, v70, v69, vcc
	v_cvt_f32_f16_sdwa v69, v57 dst_sel:DWORD dst_unused:UNUSED_PAD src0_sel:WORD_1
	v_cvt_f32_f16_e32 v57, v57
	v_and_b32_e32 v56, 0xffffff80, v56
	v_sub_u32_e32 v56, v56, v22
	v_not_b32_e32 v70, v69
	v_or_b32_e32 v71, 0x80000000, v69
	v_cmp_gt_i32_e32 vcc, 0, v69
	v_add_u32_e32 v68, 0x7e, v68
	v_add_u32_e32 v56, 0x7f, v56
	v_cndmask_b32_e32 v69, v71, v70, vcc
	v_not_b32_e32 v70, v57
	v_or_b32_e32 v71, 0x80000000, v57
	v_cmp_gt_i32_e32 vcc, 0, v57
	v_and_b32_e32 v69, 0xffffff80, v69
	v_sub_u32_e32 v69, v69, v23
	v_cndmask_b32_e32 v57, v71, v70, vcc
	v_cvt_f32_f16_sdwa v70, v0 dst_sel:DWORD dst_unused:UNUSED_PAD src0_sel:WORD_1
	v_cvt_f32_f16_e32 v0, v0
	v_and_b32_e32 v57, 0xffffff80, v57
	v_sub_u32_e32 v57, v57, v23
	v_not_b32_e32 v71, v70
	v_or_b32_e32 v72, 0x80000000, v70
	v_cmp_gt_i32_e32 vcc, 0, v70
	v_add_u32_e32 v69, 0x7e, v69
	v_add_u32_e32 v57, 0x7f, v57
	v_cndmask_b32_e32 v70, v72, v71, vcc
	v_not_b32_e32 v71, v0
	v_or_b32_e32 v72, 0x80000000, v0
	v_cmp_gt_i32_e32 vcc, 0, v0
	v_and_b32_e32 v70, 0xffffff80, v70
	v_sub_u32_e32 v70, v70, v24
	v_cndmask_b32_e32 v0, v72, v71, vcc
	v_cvt_f32_f16_sdwa v71, v1 dst_sel:DWORD dst_unused:UNUSED_PAD src0_sel:WORD_1
	v_cvt_f32_f16_e32 v1, v1
	v_and_b32_e32 v0, 0xffffff80, v0
	v_sub_u32_e32 v0, v0, v24
	v_not_b32_e32 v72, v71
	v_or_b32_e32 v73, 0x80000000, v71
	v_cmp_gt_i32_e32 vcc, 0, v71
	v_add_u32_e32 v70, 0x7e, v70
	v_add_u32_e32 v0, 0x7f, v0
	v_cndmask_b32_e32 v71, v73, v72, vcc
	v_not_b32_e32 v72, v1
	v_or_b32_e32 v73, 0x80000000, v1
	v_cmp_gt_i32_e32 vcc, 0, v1
	v_and_b32_e32 v71, 0xffffff80, v71
	v_sub_u32_e32 v71, v71, v25
	v_cndmask_b32_e32 v1, v73, v72, vcc
	v_cvt_f32_f16_sdwa v72, v2 dst_sel:DWORD dst_unused:UNUSED_PAD src0_sel:WORD_1
	v_cvt_f32_f16_e32 v2, v2
	v_and_b32_e32 v1, 0xffffff80, v1
	v_sub_u32_e32 v1, v1, v25
	v_not_b32_e32 v73, v72
	v_or_b32_e32 v74, 0x80000000, v72
	v_cmp_gt_i32_e32 vcc, 0, v72
	v_add_u32_e32 v71, 0x7e, v71
	v_add_u32_e32 v1, 0x7f, v1
	v_cndmask_b32_e32 v72, v74, v73, vcc
	v_not_b32_e32 v73, v2
	v_or_b32_e32 v74, 0x80000000, v2
	v_cmp_gt_i32_e32 vcc, 0, v2
	v_and_b32_e32 v72, 0xffffff80, v72
	v_sub_u32_e32 v72, v72, v26
	v_cndmask_b32_e32 v2, v74, v73, vcc
	v_cvt_f32_f16_sdwa v73, v3 dst_sel:DWORD dst_unused:UNUSED_PAD src0_sel:WORD_1
	v_cvt_f32_f16_e32 v3, v3
	v_and_b32_e32 v2, 0xffffff80, v2
	v_sub_u32_e32 v2, v2, v26
	v_not_b32_e32 v74, v73
	v_or_b32_e32 v75, 0x80000000, v73
	v_cmp_gt_i32_e32 vcc, 0, v73
	v_add_u32_e32 v72, 0x7e, v72
	v_add_u32_e32 v2, 0x7f, v2
	v_cndmask_b32_e32 v73, v75, v74, vcc
	v_not_b32_e32 v74, v3
	v_or_b32_e32 v75, 0x80000000, v3
	v_cmp_gt_i32_e32 vcc, 0, v3
	v_and_b32_e32 v73, 0xffffff80, v73
	v_sub_u32_e32 v73, v73, v28
	v_cndmask_b32_e32 v3, v75, v74, vcc
	v_and_b32_e32 v3, 0xffffff80, v3
	v_sub_u32_e32 v3, v3, v28
	v_add_u32_e32 v73, 0x7e, v73
	v_add_u32_e32 v3, 0x7f, v3
	v_max_u32_e32 v74, v50, v58
	v_min_u32_e32 v50, v50, v58
	v_max_u32_e32 v58, v59, v51
	v_min_u32_e32 v51, v59, v51
	v_max_u32_e32 v59, v52, v60
	v_min_u32_e32 v52, v52, v60
	v_max_u32_e32 v60, v61, v53
	v_min_u32_e32 v53, v61, v53
	v_max_u32_e32 v61, v46, v62
	v_min_u32_e32 v46, v46, v62
	v_max_u32_e32 v62, v63, v47
	v_min_u32_e32 v47, v63, v47
	v_max_u32_e32 v63, v48, v64
	v_min_u32_e32 v48, v48, v64
	v_max_u32_e32 v64, v65, v49
	v_min_u32_e32 v49, v65, v49
	v_max_u32_e32 v82, v54, v66
	v_min_u32_e32 v54, v54, v66
	v_max_u32_e32 v66, v67, v55
	v_min_u32_e32 v55, v67, v55
	v_max_u32_e32 v67, v56, v68
	v_min_u32_e32 v56, v56, v68
	v_max_u32_e32 v68, v69, v57
	v_min_u32_e32 v57, v69, v57
	v_max_u32_e32 v69, v0, v70
	v_min_u32_e32 v0, v0, v70
	v_max_u32_e32 v70, v71, v1
	v_min_u32_e32 v1, v71, v1
	v_max_u32_e32 v71, v2, v72
	v_min_u32_e32 v2, v2, v72
	v_max_u32_e32 v72, v73, v3
	v_min_u32_e32 v3, v73, v3
	v_max_u32_e32 v65, v74, v51
	v_min_u32_e32 v51, v74, v51
	v_max_u32_e32 v74, v50, v58
	v_min_u32_e32 v50, v50, v58
	v_max_u32_e32 v58, v53, v59
	v_min_u32_e32 v53, v53, v59
	v_max_u32_e32 v59, v60, v52
	v_min_u32_e32 v52, v60, v52
; #define CE_DESC(a, b) do { const unsigned _mx = (a) > (b) ? (a) : (b), _mn = (a) > (b) ? (b) : (a); (a) = _mx; (b) = _mn; } while (0)
; __device__ __forceinline__ void sort16_desc(unsigned (&k)[16]) {
; #pragma unroll
;     for (int size = 2; size <= 16; size <<= 1)
; #pragma unroll
;         for (int stride = size >> 1; stride > 0; stride >>= 1)
; #pragma unroll
;             for (int i = 0; i < 16; ++i) { const int j = i ^ stride;
;                 if (j > i) { if ((i & size) == 0) CE_DESC(k[i], k[j]); else CE_DESC(k[j], k[i]); } }
; }
	v_max_u32_e32 v60, v61, v47
	v_min_u32_e32 v47, v61, v47
	v_max_u32_e32 v61, v46, v62
	v_min_u32_e32 v46, v46, v62
	v_max_u32_e32 v62, v49, v63
	v_min_u32_e32 v49, v49, v63
	v_max_u32_e32 v63, v64, v48
	v_min_u32_e32 v48, v64, v48
	v_max_u32_e32 v73, v82, v55
	v_min_u32_e32 v55, v82, v55
	v_max_u32_e32 v82, v54, v66
	v_min_u32_e32 v54, v54, v66
	v_max_u32_e32 v66, v57, v67
	v_min_u32_e32 v57, v57, v67
	v_max_u32_e32 v67, v68, v56
	v_min_u32_e32 v56, v68, v56
	v_max_u32_e32 v68, v69, v1
	v_min_u32_e32 v1, v69, v1
	v_max_u32_e32 v69, v0, v70
	v_min_u32_e32 v0, v0, v70
	v_max_u32_e32 v70, v3, v71
	v_min_u32_e32 v3, v3, v71
	v_max_u32_e32 v71, v72, v2
	v_min_u32_e32 v2, v72, v2
	v_max_u32_e32 v64, v65, v74
	v_min_u32_e32 v65, v65, v74
	v_max_u32_e32 v74, v51, v50
	v_min_u32_e32 v50, v51, v50
	v_max_u32_e32 v51, v52, v53
	v_min_u32_e32 v52, v52, v53
	v_max_u32_e32 v53, v59, v58
	v_min_u32_e32 v58, v59, v58
	v_max_u32_e32 v59, v60, v61
	v_min_u32_e32 v60, v60, v61
	v_max_u32_e32 v61, v47, v46
	v_min_u32_e32 v46, v47, v46
	v_max_u32_e32 v47, v48, v49
	v_min_u32_e32 v48, v48, v49
	v_max_u32_e32 v49, v63, v62
	v_min_u32_e32 v62, v63, v62
	v_max_u32_e32 v72, v73, v82
	v_min_u32_e32 v73, v73, v82
	v_max_u32_e32 v82, v55, v54
	v_min_u32_e32 v54, v55, v54
	v_max_u32_e32 v55, v56, v57
	v_min_u32_e32 v56, v56, v57
	v_max_u32_e32 v57, v67, v66
	v_min_u32_e32 v66, v67, v66
	v_max_u32_e32 v67, v68, v69
	v_min_u32_e32 v68, v68, v69
	v_max_u32_e32 v69, v1, v0
	v_min_u32_e32 v0, v1, v0
	v_max_u32_e32 v1, v2, v3
	v_min_u32_e32 v2, v2, v3
	v_max_u32_e32 v3, v71, v70
	v_min_u32_e32 v70, v71, v70
	v_max_u32_e32 v63, v64, v52
	v_min_u32_e32 v52, v64, v52
	v_max_u32_e32 v64, v65, v51
	v_min_u32_e32 v51, v65, v51
	v_max_u32_e32 v65, v74, v58
	v_min_u32_e32 v58, v74, v58
	v_max_u32_e32 v74, v50, v53
	v_min_u32_e32 v50, v50, v53
	v_max_u32_e32 v53, v48, v59
	v_min_u32_e32 v48, v48, v59
	v_max_u32_e32 v59, v47, v60
	v_min_u32_e32 v47, v47, v60
	v_max_u32_e32 v60, v62, v61
	v_min_u32_e32 v61, v62, v61
	v_max_u32_e32 v62, v49, v46
	v_min_u32_e32 v46, v49, v46
	v_max_u32_e32 v71, v72, v56
	v_min_u32_e32 v56, v72, v56
	v_max_u32_e32 v72, v73, v55
	v_min_u32_e32 v55, v73, v55
	v_max_u32_e32 v73, v82, v66
	v_min_u32_e32 v66, v82, v66
	v_max_u32_e32 v82, v54, v57
	v_min_u32_e32 v54, v54, v57
	v_max_u32_e32 v57, v2, v67
	v_min_u32_e32 v2, v2, v67
	v_max_u32_e32 v67, v1, v68
	v_min_u32_e32 v1, v1, v68
	v_max_u32_e32 v68, v70, v69
	v_min_u32_e32 v69, v70, v69
	v_max_u32_e32 v70, v3, v0
	v_min_u32_e32 v0, v3, v0
	v_max_u32_e32 v49, v63, v65
	v_min_u32_e32 v63, v63, v65
	v_max_u32_e32 v65, v64, v74
	v_min_u32_e32 v64, v64, v74
	v_max_u32_e32 v74, v52, v58
	v_min_u32_e32 v52, v52, v58
	v_max_u32_e32 v58, v51, v50
	v_min_u32_e32 v50, v51, v50
	v_max_u32_e32 v51, v61, v48
	v_min_u32_e32 v48, v61, v48
	v_max_u32_e32 v61, v46, v47
	v_min_u32_e32 v46, v46, v47
	v_max_u32_e32 v47, v60, v53
	v_min_u32_e32 v53, v60, v53
	v_max_u32_e32 v60, v62, v59
	v_min_u32_e32 v59, v62, v59
	v_max_u32_e32 v3, v71, v73
	v_min_u32_e32 v71, v71, v73
	v_max_u32_e32 v73, v72, v82
	v_min_u32_e32 v72, v72, v82
	v_max_u32_e32 v82, v56, v66
	v_min_u32_e32 v56, v56, v66
	v_max_u32_e32 v66, v55, v54
	v_min_u32_e32 v54, v55, v54
	v_max_u32_e32 v55, v69, v2
	v_min_u32_e32 v2, v69, v2
	v_max_u32_e32 v69, v0, v1
	v_min_u32_e32 v0, v0, v1
	v_max_u32_e32 v1, v68, v57
	v_min_u32_e32 v57, v68, v57
	v_max_u32_e32 v68, v70, v67
	v_min_u32_e32 v67, v70, v67
	v_max_u32_e32 v62, v49, v65
	v_min_u32_e32 v49, v49, v65
	v_max_u32_e32 v65, v63, v64
	v_min_u32_e32 v63, v63, v64
	v_max_u32_e32 v64, v74, v58
	v_min_u32_e32 v58, v74, v58
	v_max_u32_e32 v74, v52, v50
	v_min_u32_e32 v50, v52, v50
	v_max_u32_e32 v52, v46, v48
	v_min_u32_e32 v46, v46, v48
	v_max_u32_e32 v48, v61, v51
	v_min_u32_e32 v51, v61, v51
	v_max_u32_e32 v61, v59, v53
	v_min_u32_e32 v53, v59, v53
	v_max_u32_e32 v59, v60, v47
	v_min_u32_e32 v47, v60, v47
	v_max_u32_e32 v70, v3, v73
	v_min_u32_e32 v3, v3, v73
	v_max_u32_e32 v73, v71, v72
	v_min_u32_e32 v71, v71, v72
	v_max_u32_e32 v72, v82, v66
	v_min_u32_e32 v66, v82, v66
	v_max_u32_e32 v82, v56, v54
	v_min_u32_e32 v54, v56, v54
	v_max_u32_e32 v56, v0, v2
	v_min_u32_e32 v0, v0, v2
	v_max_u32_e32 v2, v69, v55
	v_min_u32_e32 v55, v69, v55
	v_max_u32_e32 v69, v67, v57
	v_min_u32_e32 v57, v67, v57
	v_max_u32_e32 v67, v68, v1
	v_min_u32_e32 v1, v68, v1
	v_max_u32_e32 v60, v62, v46
	v_min_u32_e32 v46, v62, v46
	v_max_u32_e32 v62, v49, v52
	v_min_u32_e32 v49, v49, v52
	v_max_u32_e32 v52, v65, v51
	v_min_u32_e32 v51, v65, v51
	v_max_u32_e32 v65, v63, v48
	v_min_u32_e32 v48, v63, v48
	v_max_u32_e32 v63, v64, v53
	v_min_u32_e32 v53, v64, v53
	v_max_u32_e32 v64, v58, v61
	v_min_u32_e32 v58, v58, v61
	v_max_u32_e32 v61, v74, v47
	v_min_u32_e32 v47, v74, v47
	v_max_u32_e32 v74, v50, v59
	v_min_u32_e32 v50, v50, v59
	v_max_u32_e32 v68, v70, v0
	v_min_u32_e32 v0, v70, v0
	v_max_u32_e32 v70, v3, v56
	v_min_u32_e32 v3, v3, v56
	v_max_u32_e32 v56, v73, v55
	v_min_u32_e32 v55, v73, v55
	v_max_u32_e32 v73, v71, v2
	v_min_u32_e32 v2, v71, v2
	v_max_u32_e32 v71, v72, v57
	v_min_u32_e32 v57, v72, v57
	v_max_u32_e32 v72, v66, v69
	v_min_u32_e32 v66, v66, v69
	v_max_u32_e32 v69, v82, v1
	v_min_u32_e32 v1, v82, v1
	v_max_u32_e32 v82, v54, v67
	v_min_u32_e32 v54, v54, v67
	v_max_u32_e32 v59, v60, v63
	v_min_u32_e32 v60, v60, v63
	v_max_u32_e32 v63, v62, v64
	v_min_u32_e32 v62, v62, v64
	v_max_u32_e32 v64, v52, v61
	v_min_u32_e32 v52, v52, v61
	v_max_u32_e32 v61, v65, v74
	v_min_u32_e32 v65, v65, v74
	v_max_u32_e32 v74, v46, v53
	v_min_u32_e32 v46, v46, v53
	v_max_u32_e32 v53, v49, v58
	v_min_u32_e32 v49, v49, v58
	v_max_u32_e32 v58, v51, v47
; #define CE_DESC(a, b) do { const unsigned _mx = (a) > (b) ? (a) : (b), _mn = (a) > (b) ? (b) : (a); (a) = _mx; (b) = _mn; } while (0)
; __device__ __forceinline__ void sort16_desc(unsigned (&k)[16]) {
; #pragma unroll
;     for (int size = 2; size <= 16; size <<= 1)
; #pragma unroll
;         for (int stride = size >> 1; stride > 0; stride >>= 1)
; #pragma unroll
;             for (int i = 0; i < 16; ++i) { const int j = i ^ stride;
;                 if (j > i) { if ((i & size) == 0) CE_DESC(k[i], k[j]); else CE_DESC(k[j], k[i]); } }
; }
; __device__ __forceinline__ void merge16(unsigned (&a)[16], const unsigned (&b)[16]) {
; #pragma unroll
;     for (int i = 0; i < 16; ++i) a[i] = a[i] > b[15 - i] ? a[i] : b[15 - i];
; #pragma unroll
;     for (int stride = 8; stride > 0; stride >>= 1)
; #pragma unroll
;         for (int i = 0; i < 16; ++i) { const int j = i ^ stride; if (j > i) CE_DESC(a[i], a[j]); }
; }
; __device__ __forceinline__ void peer_tile(const Args& A, LAS unsigned char* lds, int tile) {
;     ...
;                 sort16_desc(k0); sort16_desc(k1); merge16(k0, k1);
; #pragma unroll
;                 for (int msk = 16; msk <= 32; msk <<= 1) {
; #pragma unroll
;                     for (int i = 0; i < 16; ++i) k1[i] = (unsigned)__shfl_xor((int)k0[i], msk);
;                     merge16(k0, k1); }
	v_min_u32_e32 v47, v51, v47
	v_max_u32_e32 v51, v48, v50
	v_min_u32_e32 v48, v48, v50
	v_max_u32_e32 v67, v68, v71
	v_min_u32_e32 v68, v68, v71
	v_max_u32_e32 v71, v70, v72
	v_min_u32_e32 v70, v70, v72
	v_max_u32_e32 v72, v56, v69
	v_min_u32_e32 v56, v56, v69
	v_max_u32_e32 v69, v73, v82
	v_min_u32_e32 v73, v73, v82
	v_max_u32_e32 v82, v0, v57
	v_min_u32_e32 v0, v0, v57
	v_max_u32_e32 v57, v3, v66
	v_min_u32_e32 v3, v3, v66
	v_max_u32_e32 v66, v55, v1
	v_min_u32_e32 v1, v55, v1
	v_max_u32_e32 v55, v2, v54
	v_min_u32_e32 v2, v2, v54
	v_max_u32_e32 v50, v59, v64
	v_min_u32_e32 v59, v59, v64
	v_max_u32_e32 v64, v63, v61
	v_min_u32_e32 v61, v63, v61
	v_max_u32_e32 v63, v60, v52
	v_min_u32_e32 v52, v60, v52
	v_max_u32_e32 v60, v62, v65
	v_min_u32_e32 v62, v62, v65
	v_max_u32_e32 v65, v74, v58
	v_min_u32_e32 v58, v74, v58
	v_max_u32_e32 v74, v53, v51
	v_min_u32_e32 v51, v53, v51
	v_max_u32_e32 v53, v46, v47
	v_min_u32_e32 v46, v46, v47
	v_max_u32_e32 v47, v49, v48
	v_min_u32_e32 v48, v49, v48
	v_max_u32_e32 v54, v67, v72
	v_min_u32_e32 v67, v67, v72
	v_max_u32_e32 v72, v71, v69
	v_min_u32_e32 v69, v71, v69
	v_max_u32_e32 v71, v68, v56
	v_min_u32_e32 v56, v68, v56
	v_max_u32_e32 v68, v70, v73
	v_min_u32_e32 v70, v70, v73
	v_max_u32_e32 v73, v82, v66
	v_min_u32_e32 v66, v82, v66
	v_max_u32_e32 v82, v57, v55
	v_min_u32_e32 v55, v57, v55
	v_max_u32_e32 v57, v0, v1
	v_min_u32_e32 v0, v0, v1
	v_max_u32_e32 v1, v3, v2
	v_min_u32_e32 v2, v3, v2
	v_min_u32_e32 v49, v50, v64
	v_min_u32_e32 v75, v59, v61
	v_min_u32_e32 v76, v63, v60
	v_min_u32_e32 v77, v52, v62
	v_min_u32_e32 v78, v65, v74
	v_min_u32_e32 v79, v58, v51
	v_min_u32_e32 v80, v53, v47
	v_min_u32_e32 v81, v46, v48
	v_min_u32_e32 v3, v54, v72
	v_min_u32_e32 v83, v67, v69
	v_min_u32_e32 v84, v71, v68
	v_min_u32_e32 v85, v56, v70
	v_min_u32_e32 v86, v73, v82
	v_min_u32_e32 v87, v66, v55
	v_min_u32_e32 v88, v57, v1
	v_min_u32_e32 v89, v0, v2
	v_max3_u32 v50, v50, v64, v89
	v_max3_u32 v0, v49, v0, v2
	v_max3_u32 v2, v59, v61, v88
	v_max3_u32 v1, v75, v57, v1
	v_max3_u32 v49, v63, v60, v87
	v_max3_u32 v55, v76, v66, v55
	v_max3_u32 v52, v52, v62, v86
	v_max3_u32 v57, v77, v73, v82
	v_max3_u32 v59, v65, v74, v85
	v_max3_u32 v56, v78, v56, v70
	v_max3_u32 v51, v58, v51, v84
	v_max3_u32 v58, v79, v71, v68
	v_max3_u32 v47, v53, v47, v83
	v_max3_u32 v53, v80, v67, v69
	v_max3_u32 v3, v46, v48, v3
	v_max3_u32 v46, v81, v54, v72
	v_max_u32_e32 v48, v50, v59
	v_min_u32_e32 v50, v50, v59
	v_max_u32_e32 v54, v0, v56
	v_min_u32_e32 v0, v0, v56
	v_max_u32_e32 v56, v2, v51
	v_min_u32_e32 v2, v2, v51
	v_max_u32_e32 v51, v1, v58
	v_min_u32_e32 v1, v1, v58
	v_max_u32_e32 v58, v49, v47
	v_min_u32_e32 v47, v49, v47
	v_max_u32_e32 v49, v55, v53
	v_min_u32_e32 v53, v55, v53
	v_max_u32_e32 v55, v52, v3
	v_min_u32_e32 v3, v52, v3
	v_max_u32_e32 v52, v57, v46
	v_min_u32_e32 v46, v57, v46
	v_max_u32_e32 v57, v48, v58
	v_min_u32_e32 v48, v48, v58
	v_max_u32_e32 v58, v54, v49
	v_min_u32_e32 v49, v54, v49
	v_max_u32_e32 v54, v56, v55
	v_min_u32_e32 v55, v56, v55
	v_max_u32_e32 v56, v51, v52
	v_min_u32_e32 v51, v51, v52
	v_max_u32_e32 v52, v50, v47
	v_min_u32_e32 v47, v50, v47
	v_max_u32_e32 v50, v0, v53
	v_min_u32_e32 v0, v0, v53
	v_max_u32_e32 v53, v2, v3
	v_min_u32_e32 v2, v2, v3
	v_max_u32_e32 v3, v1, v46
	v_min_u32_e32 v1, v1, v46
	v_max_u32_e32 v46, v57, v54
	v_min_u32_e32 v54, v57, v54
	v_max_u32_e32 v57, v58, v56
	v_min_u32_e32 v56, v58, v56
	v_max_u32_e32 v58, v48, v55
	v_min_u32_e32 v48, v48, v55
	v_max_u32_e32 v55, v49, v51
	v_min_u32_e32 v49, v49, v51
	v_max_u32_e32 v51, v52, v53
	v_min_u32_e32 v52, v52, v53
	v_max_u32_e32 v53, v50, v3
	v_min_u32_e32 v3, v50, v3
	v_max_u32_e32 v50, v47, v2
	v_min_u32_e32 v2, v47, v2
	v_max_u32_e32 v47, v0, v1
	v_min_u32_e32 v0, v0, v1
	v_max_u32_e32 v1, v46, v57
	v_min_u32_e32 v46, v46, v57
	v_max_u32_e32 v57, v54, v56
	v_min_u32_e32 v54, v54, v56
	v_max_u32_e32 v56, v58, v55
	v_min_u32_e32 v55, v58, v55
	v_max_u32_e32 v58, v48, v49
	v_min_u32_e32 v48, v48, v49
	v_max_u32_e32 v49, v51, v53
	v_min_u32_e32 v51, v51, v53
	v_max_u32_e32 v53, v52, v3
	v_min_u32_e32 v3, v52, v3
	v_max_u32_e32 v52, v50, v47
	v_min_u32_e32 v47, v50, v47
	v_max_u32_e32 v50, v2, v0
	v_min_u32_e32 v0, v2, v0
	ds_bpermute_b32 v2, v27, v1
	ds_bpermute_b32 v59, v27, v46
	ds_bpermute_b32 v60, v27, v57
	ds_bpermute_b32 v61, v27, v54
	ds_bpermute_b32 v62, v27, v56
	ds_bpermute_b32 v63, v27, v55
	ds_bpermute_b32 v64, v27, v58
	ds_bpermute_b32 v65, v27, v48
	ds_bpermute_b32 v66, v27, v49
	ds_bpermute_b32 v67, v27, v51
	ds_bpermute_b32 v68, v27, v53
	ds_bpermute_b32 v69, v27, v0
	ds_bpermute_b32 v70, v27, v50
	ds_bpermute_b32 v71, v27, v47
	ds_bpermute_b32 v72, v27, v52
	ds_bpermute_b32 v73, v27, v3
	s_waitcnt lgkmcnt(4)
	v_max_u32_e32 v1, v1, v69
	s_waitcnt lgkmcnt(3)
	v_max_u32_e32 v46, v46, v70
	s_waitcnt lgkmcnt(2)
	v_max_u32_e32 v57, v57, v71
	s_waitcnt lgkmcnt(1)
	v_max_u32_e32 v54, v54, v72
	s_waitcnt lgkmcnt(0)
; #define CE_DESC(a, b) do { const unsigned _mx = (a) > (b) ? (a) : (b), _mn = (a) > (b) ? (b) : (a); (a) = _mx; (b) = _mn; } while (0)
; __device__ __forceinline__ void merge16(unsigned (&a)[16], const unsigned (&b)[16]) {
; #pragma unroll
;     for (int i = 0; i < 16; ++i) a[i] = a[i] > b[15 - i] ? a[i] : b[15 - i];
; #pragma unroll
;     for (int stride = 8; stride > 0; stride >>= 1)
; #pragma unroll
;         for (int i = 0; i < 16; ++i) { const int j = i ^ stride; if (j > i) CE_DESC(a[i], a[j]); }
; }
; __device__ __forceinline__ void peer_tile(const Args& A, LAS unsigned char* lds, int tile) {
;     ...
;                 { const bf16_t* sp = QRY + m * 2048 + hp * 128 + 32 * g;
;                   const u32x4 s0 = *(const u32x4*)sp, s1 = *(const u32x4*)(sp + 8), s2 = *(const u32x4*)(sp + 16), s3 = *(const u32x4*)(sp + 24);
;                   const unsigned sw[16] = {s0.x, s0.y, s0.z, s0.w, s1.x, s1.y, s1.z, s1.w, s2.x, s2.y, s2.z, s2.w, s3.x, s3.y, s3.z, s3.w};
;     ...
;                 sort16_desc(k0); sort16_desc(k1); merge16(k0, k1);
; #pragma unroll
;                 for (int msk = 16; msk <= 32; msk <<= 1) {
; #pragma unroll
;                     for (int i = 0; i < 16; ++i) k1[i] = (unsigned)__shfl_xor((int)k0[i], msk);
;                     merge16(k0, k1); }
	v_max_u32_e32 v56, v56, v73
	v_max_u32_e32 v55, v55, v68
	v_max_u32_e32 v58, v58, v67
	v_max_u32_e32 v48, v48, v66
	v_max_u32_e32 v49, v49, v65
	v_max_u32_e32 v51, v51, v64
	v_max_u32_e32 v53, v53, v63
	v_max_u32_e32 v3, v3, v62
	v_max_u32_e32 v52, v52, v61
	v_max_u32_e32 v47, v47, v60
	v_max_u32_e32 v50, v50, v59
	v_max_u32_e32 v0, v0, v2
	v_max_u32_e32 v2, v1, v49
	v_min_u32_e32 v1, v1, v49
	v_max_u32_e32 v49, v46, v51
	v_min_u32_e32 v46, v46, v51
	v_max_u32_e32 v51, v57, v53
	v_min_u32_e32 v53, v57, v53
	v_max_u32_e32 v57, v54, v3
	v_min_u32_e32 v3, v54, v3
	v_max_u32_e32 v54, v56, v52
	v_min_u32_e32 v52, v56, v52
	v_max_u32_e32 v56, v55, v47
	v_min_u32_e32 v47, v55, v47
	v_max_u32_e32 v55, v58, v50
	v_min_u32_e32 v50, v58, v50
	v_max_u32_e32 v58, v48, v0
	v_min_u32_e32 v0, v48, v0
	v_max_u32_e32 v48, v2, v54
	v_min_u32_e32 v2, v2, v54
	v_max_u32_e32 v54, v49, v56
	v_min_u32_e32 v49, v49, v56
	v_max_u32_e32 v56, v51, v55
	v_min_u32_e32 v51, v51, v55
	v_max_u32_e32 v55, v57, v58
	v_min_u32_e32 v57, v57, v58
	v_max_u32_e32 v58, v1, v52
	v_min_u32_e32 v1, v1, v52
	v_max_u32_e32 v52, v46, v47
	v_min_u32_e32 v46, v46, v47
	v_max_u32_e32 v47, v53, v50
	v_min_u32_e32 v50, v53, v50
	v_max_u32_e32 v53, v3, v0
	v_min_u32_e32 v0, v3, v0
	v_max_u32_e32 v3, v48, v56
	v_min_u32_e32 v48, v48, v56
	v_max_u32_e32 v56, v54, v55
	v_min_u32_e32 v54, v54, v55
	v_max_u32_e32 v55, v2, v51
	v_min_u32_e32 v2, v2, v51
	v_max_u32_e32 v51, v49, v57
	v_min_u32_e32 v49, v49, v57
	v_max_u32_e32 v57, v58, v47
	v_min_u32_e32 v47, v58, v47
	v_max_u32_e32 v58, v52, v53
	v_min_u32_e32 v52, v52, v53
	v_max_u32_e32 v53, v1, v50
	v_min_u32_e32 v1, v1, v50
	v_max_u32_e32 v50, v46, v0
	v_min_u32_e32 v0, v46, v0
	v_max_u32_e32 v46, v3, v56
	v_min_u32_e32 v3, v3, v56
	v_max_u32_e32 v56, v48, v54
	v_min_u32_e32 v48, v48, v54
	v_max_u32_e32 v54, v55, v51
	v_min_u32_e32 v51, v55, v51
	v_max_u32_e32 v55, v2, v49
	v_min_u32_e32 v2, v2, v49
	v_max_u32_e32 v49, v57, v58
	v_min_u32_e32 v57, v57, v58
	v_max_u32_e32 v58, v47, v52
	v_min_u32_e32 v47, v47, v52
	v_max_u32_e32 v52, v53, v50
	v_min_u32_e32 v50, v53, v50
	v_max_u32_e32 v53, v1, v0
	v_min_u32_e32 v0, v1, v0
	ds_bpermute_b32 v62, v29, v0
	ds_bpermute_b32 v1, v29, v46
	ds_bpermute_b32 v59, v29, v3
	ds_bpermute_b32 v60, v29, v56
	ds_bpermute_b32 v61, v29, v48
	s_waitcnt lgkmcnt(4)
	v_max_u32_e32 v46, v46, v62
	global_load_dwordx4 v[62:65], v[4:5], off offset:528
	global_load_dwordx4 v[66:69], v[4:5], off offset:512
	ds_bpermute_b32 v70, v29, v54
	ds_bpermute_b32 v71, v29, v51
	ds_bpermute_b32 v72, v29, v55
	ds_bpermute_b32 v73, v29, v2
	ds_bpermute_b32 v74, v29, v49
	ds_bpermute_b32 v75, v29, v57
	ds_bpermute_b32 v76, v29, v58
	ds_bpermute_b32 v77, v29, v47
	ds_bpermute_b32 v78, v29, v52
	ds_bpermute_b32 v79, v29, v53
	ds_bpermute_b32 v80, v29, v50
	s_waitcnt lgkmcnt(4)
	v_max_u32_e32 v51, v51, v76
	s_waitcnt lgkmcnt(3)
	v_max_u32_e32 v54, v54, v77
	s_waitcnt lgkmcnt(2)
	v_max_u32_e32 v48, v48, v78
	s_waitcnt lgkmcnt(1)
	v_max_u32_e32 v3, v3, v79
	s_waitcnt lgkmcnt(0)
	v_max_u32_e32 v56, v56, v80
	v_max_u32_e32 v55, v55, v75
	v_max_u32_e32 v2, v2, v74
	v_max_u32_e32 v49, v49, v73
	v_max_u32_e32 v57, v57, v72
	v_max_u32_e32 v58, v58, v71
	v_max_u32_e32 v47, v47, v70
	v_max_u32_e32 v52, v52, v61
	v_max_u32_e32 v50, v50, v60
	v_max_u32_e32 v53, v53, v59
	v_max_u32_e32 v0, v0, v1
	v_max_u32_e32 v1, v46, v49
	v_min_u32_e32 v46, v46, v49
	v_max_u32_e32 v49, v3, v57
	v_min_u32_e32 v3, v3, v57
	v_max_u32_e32 v57, v56, v58
	v_min_u32_e32 v56, v56, v58
	v_max_u32_e32 v58, v48, v47
	v_min_u32_e32 v47, v48, v47
	v_max_u32_e32 v48, v54, v52
	v_min_u32_e32 v52, v54, v52
	v_max_u32_e32 v54, v51, v50
	v_min_u32_e32 v50, v51, v50
	v_max_u32_e32 v51, v55, v53
	v_min_u32_e32 v53, v55, v53
	v_max_u32_e32 v55, v2, v0
	v_min_u32_e32 v0, v2, v0
	v_max_u32_e32 v2, v1, v48
	v_min_u32_e32 v1, v1, v48
	v_max_u32_e32 v48, v49, v54
	v_min_u32_e32 v49, v49, v54
	v_max_u32_e32 v54, v57, v51
	v_min_u32_e32 v51, v57, v51
	v_max_u32_e32 v57, v58, v55
	v_min_u32_e32 v55, v58, v55
	v_max_u32_e32 v58, v46, v52
	v_min_u32_e32 v46, v46, v52
	v_max_u32_e32 v52, v3, v50
	v_min_u32_e32 v3, v3, v50
	v_max_u32_e32 v50, v56, v53
	v_min_u32_e32 v53, v56, v53
	v_max_u32_e32 v56, v47, v0
	v_min_u32_e32 v0, v47, v0
	v_max_u32_e32 v47, v2, v54
	v_min_u32_e32 v2, v2, v54
	v_max_u32_e32 v54, v48, v57
	v_min_u32_e32 v48, v48, v57
	v_max_u32_e32 v70, v1, v51
	v_min_u32_e32 v1, v1, v51
	v_max_u32_e32 v51, v49, v55
	v_min_u32_e32 v49, v49, v55
	v_max_u32_e32 v71, v58, v50
	v_min_u32_e32 v50, v58, v50
	v_max_u32_e32 v72, v52, v56
	v_min_u32_e32 v73, v52, v56
	v_max_u32_e32 v74, v46, v53
	v_min_u32_e32 v46, v46, v53
	v_max_u32_e32 v75, v3, v0
	v_min_u32_e32 v0, v3, v0
	v_max_u32_e32 v61, v47, v54
	v_min_u32_e32 v60, v47, v54
	v_max_u32_e32 v59, v2, v48
	v_min_u32_e32 v58, v2, v48
	v_max_u32_e32 v57, v70, v51
	v_min_u32_e32 v56, v70, v51
	v_max_u32_e32 v55, v1, v49
	v_min_u32_e32 v54, v1, v49
	v_max_u32_e32 v53, v71, v72
	v_min_u32_e32 v52, v71, v72
	v_max_u32_e32 v51, v50, v73
	v_min_u32_e32 v50, v50, v73
	v_max_u32_e32 v47, v46, v0
	v_min_u32_e32 v46, v46, v0
	global_load_dwordx4 v[0:3], v[4:5], off offset:560
	global_load_dwordx4 v[70:73], v[4:5], off offset:544
	v_max_u32_e32 v49, v74, v75
	v_min_u32_e32 v48, v74, v75
	s_waitcnt vmcnt(2)
; __device__ __forceinline__ unsigned f2key(float f) { const unsigned u = __float_as_uint(f); return (u & 0x80000000u) ? ~u : (u | 0x80000000u); }
; __device__ __forceinline__ void peer_tile(const Args& A, LAS unsigned char* lds, int tile) {
;     ...
;                   for (int i = 0; i < 16; ++i) {
;                       const float lo = (float)__builtin_bit_cast(_Float16, (unsigned short)(sw[i] & 0xffffu)), hi = (float)__builtin_bit_cast(_Float16, (unsigned short)(sw[i] >> 16));
;                       const unsigned klo = (f2key(lo) & ~127u) | (unsigned)(127 - (32 * g + 2 * i)), khi = (f2key(hi) & ~127u) | (unsigned)(127 - (32 * g + 2 * i + 1));
;                       if (i < 8) { k0[2 * i] = klo; k0[2 * i + 1] = khi; } else { k1[2 * (i - 8)] = klo; k1[2 * (i - 8) + 1] = khi; } } }
	v_cvt_f32_f16_sdwa v74, v66 dst_sel:DWORD dst_unused:UNUSED_PAD src0_sel:WORD_1
	v_cvt_f32_f16_e32 v66, v66
	v_not_b32_e32 v75, v74
	v_or_b32_e32 v76, 0x80000000, v74
	v_cmp_gt_i32_e32 vcc, 0, v74
	s_nop 1
	v_cndmask_b32_e32 v74, v76, v75, vcc
	v_not_b32_e32 v75, v66
	v_or_b32_e32 v76, 0x80000000, v66
	v_cmp_gt_i32_e32 vcc, 0, v66
	v_and_b32_e32 v74, 0xffffff80, v74
	v_sub_u32_e32 v74, v74, v15
	v_cndmask_b32_e32 v66, v76, v75, vcc
	v_cvt_f32_f16_sdwa v75, v67 dst_sel:DWORD dst_unused:UNUSED_PAD src0_sel:WORD_1
	v_cvt_f32_f16_e32 v67, v67
	v_and_b32_e32 v66, 0xffffff80, v66
	v_sub_u32_e32 v66, v66, v15
	v_not_b32_e32 v76, v75
	v_or_b32_e32 v77, 0x80000000, v75
	v_cmp_gt_i32_e32 vcc, 0, v75
	v_add_u32_e32 v74, 0x7e, v74
	v_add_u32_e32 v66, 0x7f, v66
	v_cndmask_b32_e32 v75, v77, v76, vcc
	v_not_b32_e32 v76, v67
	v_or_b32_e32 v77, 0x80000000, v67
	v_cmp_gt_i32_e32 vcc, 0, v67
	v_and_b32_e32 v75, 0xffffff80, v75
	v_sub_u32_e32 v75, v75, v14
	v_cndmask_b32_e32 v67, v77, v76, vcc
	v_cvt_f32_f16_sdwa v76, v68 dst_sel:DWORD dst_unused:UNUSED_PAD src0_sel:WORD_1
	v_cvt_f32_f16_e32 v68, v68
	v_and_b32_e32 v67, 0xffffff80, v67
	v_sub_u32_e32 v67, v67, v14
	v_not_b32_e32 v77, v76
	v_or_b32_e32 v78, 0x80000000, v76
	v_cmp_gt_i32_e32 vcc, 0, v76
	v_add_u32_e32 v75, 0x7e, v75
	v_add_u32_e32 v67, 0x7f, v67
	v_cndmask_b32_e32 v76, v78, v77, vcc
	v_not_b32_e32 v77, v68
	v_or_b32_e32 v78, 0x80000000, v68
	v_cmp_gt_i32_e32 vcc, 0, v68
	v_and_b32_e32 v76, 0xffffff80, v76
	v_sub_u32_e32 v76, v76, v12
	v_cndmask_b32_e32 v68, v78, v77, vcc
	v_cvt_f32_f16_sdwa v77, v69 dst_sel:DWORD dst_unused:UNUSED_PAD src0_sel:WORD_1
	v_cvt_f32_f16_e32 v69, v69
	v_and_b32_e32 v68, 0xffffff80, v68
	v_sub_u32_e32 v68, v68, v12
	v_not_b32_e32 v78, v77
	v_or_b32_e32 v79, 0x80000000, v77
	v_cmp_gt_i32_e32 vcc, 0, v77
	v_add_u32_e32 v76, 0x7e, v76
	v_add_u32_e32 v68, 0x7f, v68
	v_cndmask_b32_e32 v77, v79, v78, vcc
	v_not_b32_e32 v78, v69
	v_or_b32_e32 v79, 0x80000000, v69
	v_cmp_gt_i32_e32 vcc, 0, v69
	v_and_b32_e32 v77, 0xffffff80, v77
	v_sub_u32_e32 v77, v77, v10
	v_cndmask_b32_e32 v69, v79, v78, vcc
	v_cvt_f32_f16_sdwa v78, v62 dst_sel:DWORD dst_unused:UNUSED_PAD src0_sel:WORD_1
	v_cvt_f32_f16_e32 v62, v62
	v_and_b32_e32 v69, 0xffffff80, v69
	v_sub_u32_e32 v69, v69, v10
	v_not_b32_e32 v79, v78
	v_or_b32_e32 v80, 0x80000000, v78
	v_cmp_gt_i32_e32 vcc, 0, v78
	v_add_u32_e32 v77, 0x7e, v77
	v_add_u32_e32 v69, 0x7f, v69
	v_cndmask_b32_e32 v78, v80, v79, vcc
	v_not_b32_e32 v79, v62
	v_or_b32_e32 v80, 0x80000000, v62
	v_cmp_gt_i32_e32 vcc, 0, v62
	v_and_b32_e32 v78, 0xffffff80, v78
	v_sub_u32_e32 v78, v78, v8
	v_cndmask_b32_e32 v62, v80, v79, vcc
	v_cvt_f32_f16_sdwa v79, v63 dst_sel:DWORD dst_unused:UNUSED_PAD src0_sel:WORD_1
	v_cvt_f32_f16_e32 v63, v63
	v_and_b32_e32 v62, 0xffffff80, v62
	v_sub_u32_e32 v62, v62, v8
	v_not_b32_e32 v80, v79
	v_or_b32_e32 v81, 0x80000000, v79
	v_cmp_gt_i32_e32 vcc, 0, v79
	v_add_u32_e32 v78, 0x7e, v78
	v_add_u32_e32 v62, 0x7f, v62
	v_cndmask_b32_e32 v79, v81, v80, vcc
	v_not_b32_e32 v80, v63
	v_or_b32_e32 v81, 0x80000000, v63
	v_cmp_gt_i32_e32 vcc, 0, v63
	v_and_b32_e32 v79, 0xffffff80, v79
	v_sub_u32_e32 v79, v79, v16
	v_cndmask_b32_e32 v63, v81, v80, vcc
	v_cvt_f32_f16_sdwa v80, v64 dst_sel:DWORD dst_unused:UNUSED_PAD src0_sel:WORD_1
	v_cvt_f32_f16_e32 v64, v64
	v_and_b32_e32 v63, 0xffffff80, v63
	v_sub_u32_e32 v63, v63, v16
	v_not_b32_e32 v81, v80
	v_or_b32_e32 v82, 0x80000000, v80
	v_cmp_gt_i32_e32 vcc, 0, v80
	v_add_u32_e32 v79, 0x7e, v79
	v_add_u32_e32 v63, 0x7f, v63
	v_cndmask_b32_e32 v80, v82, v81, vcc
	v_not_b32_e32 v81, v64
	v_or_b32_e32 v82, 0x80000000, v64
	v_cmp_gt_i32_e32 vcc, 0, v64
	v_and_b32_e32 v80, 0xffffff80, v80
	v_sub_u32_e32 v80, v80, v17
	v_cndmask_b32_e32 v64, v82, v81, vcc
	v_cvt_f32_f16_sdwa v81, v65 dst_sel:DWORD dst_unused:UNUSED_PAD src0_sel:WORD_1
	v_cvt_f32_f16_e32 v65, v65
	v_and_b32_e32 v64, 0xffffff80, v64
	v_sub_u32_e32 v64, v64, v17
	v_not_b32_e32 v82, v81
	v_or_b32_e32 v83, 0x80000000, v81
	v_cmp_gt_i32_e32 vcc, 0, v81
	v_add_u32_e32 v80, 0x7e, v80
	v_add_u32_e32 v64, 0x7f, v64
	v_cndmask_b32_e32 v81, v83, v82, vcc
	v_not_b32_e32 v82, v65
	v_or_b32_e32 v83, 0x80000000, v65
	v_cmp_gt_i32_e32 vcc, 0, v65
	v_and_b32_e32 v81, 0xffffff80, v81
	v_sub_u32_e32 v81, v81, v18
	v_cndmask_b32_e32 v65, v83, v82, vcc
	s_waitcnt vmcnt(0)
; __device__ __forceinline__ unsigned f2key(float f) { const unsigned u = __float_as_uint(f); return (u & 0x80000000u) ? ~u : (u | 0x80000000u); }
; #define CE_DESC(a, b) do { const unsigned _mx = (a) > (b) ? (a) : (b), _mn = (a) > (b) ? (b) : (a); (a) = _mx; (b) = _mn; } while (0)
; __device__ __forceinline__ void sort16_desc(unsigned (&k)[16]) {
; #pragma unroll
;     for (int size = 2; size <= 16; size <<= 1)
; #pragma unroll
;         for (int stride = size >> 1; stride > 0; stride >>= 1)
; #pragma unroll
;             for (int i = 0; i < 16; ++i) { const int j = i ^ stride;
;                 if (j > i) { if ((i & size) == 0) CE_DESC(k[i], k[j]); else CE_DESC(k[j], k[i]); } }
; }
; __device__ __forceinline__ void peer_tile(const Args& A, LAS unsigned char* lds, int tile) {
;     ...
;                   for (int i = 0; i < 16; ++i) {
;                       const float lo = (float)__builtin_bit_cast(_Float16, (unsigned short)(sw[i] & 0xffffu)), hi = (float)__builtin_bit_cast(_Float16, (unsigned short)(sw[i] >> 16));
;                       const unsigned klo = (f2key(lo) & ~127u) | (unsigned)(127 - (32 * g + 2 * i)), khi = (f2key(hi) & ~127u) | (unsigned)(127 - (32 * g + 2 * i + 1));
;                       if (i < 8) { k0[2 * i] = klo; k0[2 * i + 1] = khi; } else { k1[2 * (i - 8)] = klo; k1[2 * (i - 8) + 1] = khi; } } }
	v_cvt_f32_f16_sdwa v82, v70 dst_sel:DWORD dst_unused:UNUSED_PAD src0_sel:WORD_1
	v_cvt_f32_f16_e32 v70, v70
	v_and_b32_e32 v65, 0xffffff80, v65
	v_sub_u32_e32 v65, v65, v18
	v_not_b32_e32 v83, v82
	v_or_b32_e32 v84, 0x80000000, v82
	v_cmp_gt_i32_e32 vcc, 0, v82
	v_add_u32_e32 v81, 0x7e, v81
	v_add_u32_e32 v65, 0x7f, v65
	v_cndmask_b32_e32 v82, v84, v83, vcc
	v_not_b32_e32 v83, v70
	v_or_b32_e32 v84, 0x80000000, v70
	v_cmp_gt_i32_e32 vcc, 0, v70
	v_and_b32_e32 v82, 0xffffff80, v82
	v_sub_u32_e32 v82, v82, v20
	v_cndmask_b32_e32 v70, v84, v83, vcc
	v_cvt_f32_f16_sdwa v83, v71 dst_sel:DWORD dst_unused:UNUSED_PAD src0_sel:WORD_1
	v_cvt_f32_f16_e32 v71, v71
	v_and_b32_e32 v70, 0xffffff80, v70
	v_sub_u32_e32 v70, v70, v20
	v_not_b32_e32 v84, v83
	v_or_b32_e32 v85, 0x80000000, v83
	v_cmp_gt_i32_e32 vcc, 0, v83
	v_add_u32_e32 v82, 0x7e, v82
	v_add_u32_e32 v70, 0x7f, v70
	v_cndmask_b32_e32 v83, v85, v84, vcc
	v_not_b32_e32 v84, v71
	v_or_b32_e32 v85, 0x80000000, v71
	v_cmp_gt_i32_e32 vcc, 0, v71
	v_and_b32_e32 v83, 0xffffff80, v83
	v_sub_u32_e32 v83, v83, v21
	v_cndmask_b32_e32 v71, v85, v84, vcc
	v_cvt_f32_f16_sdwa v84, v72 dst_sel:DWORD dst_unused:UNUSED_PAD src0_sel:WORD_1
	v_cvt_f32_f16_e32 v72, v72
	v_and_b32_e32 v71, 0xffffff80, v71
	v_sub_u32_e32 v71, v71, v21
	v_not_b32_e32 v85, v84
	v_or_b32_e32 v86, 0x80000000, v84
	v_cmp_gt_i32_e32 vcc, 0, v84
	v_add_u32_e32 v83, 0x7e, v83
	v_add_u32_e32 v71, 0x7f, v71
	v_cndmask_b32_e32 v84, v86, v85, vcc
	v_not_b32_e32 v85, v72
	v_or_b32_e32 v86, 0x80000000, v72
	v_cmp_gt_i32_e32 vcc, 0, v72
	v_and_b32_e32 v84, 0xffffff80, v84
	v_sub_u32_e32 v84, v84, v22
	v_cndmask_b32_e32 v72, v86, v85, vcc
	v_cvt_f32_f16_sdwa v85, v73 dst_sel:DWORD dst_unused:UNUSED_PAD src0_sel:WORD_1
	v_cvt_f32_f16_e32 v73, v73
	v_and_b32_e32 v72, 0xffffff80, v72
	v_sub_u32_e32 v72, v72, v22
	v_not_b32_e32 v86, v85
	v_or_b32_e32 v87, 0x80000000, v85
	v_cmp_gt_i32_e32 vcc, 0, v85
	v_add_u32_e32 v84, 0x7e, v84
	v_add_u32_e32 v72, 0x7f, v72
	v_cndmask_b32_e32 v85, v87, v86, vcc
	v_not_b32_e32 v86, v73
	v_or_b32_e32 v87, 0x80000000, v73
	v_cmp_gt_i32_e32 vcc, 0, v73
	v_and_b32_e32 v85, 0xffffff80, v85
	v_sub_u32_e32 v85, v85, v23
	v_cndmask_b32_e32 v73, v87, v86, vcc
	v_cvt_f32_f16_sdwa v86, v0 dst_sel:DWORD dst_unused:UNUSED_PAD src0_sel:WORD_1
	v_cvt_f32_f16_e32 v0, v0
	v_and_b32_e32 v73, 0xffffff80, v73
	v_sub_u32_e32 v73, v73, v23
	v_not_b32_e32 v87, v86
	v_or_b32_e32 v88, 0x80000000, v86
	v_cmp_gt_i32_e32 vcc, 0, v86
	v_add_u32_e32 v85, 0x7e, v85
	v_add_u32_e32 v73, 0x7f, v73
	v_cndmask_b32_e32 v86, v88, v87, vcc
	v_not_b32_e32 v87, v0
	v_or_b32_e32 v88, 0x80000000, v0
	v_cmp_gt_i32_e32 vcc, 0, v0
	v_and_b32_e32 v86, 0xffffff80, v86
	v_sub_u32_e32 v86, v86, v24
	v_cndmask_b32_e32 v0, v88, v87, vcc
	v_cvt_f32_f16_sdwa v87, v1 dst_sel:DWORD dst_unused:UNUSED_PAD src0_sel:WORD_1
	v_cvt_f32_f16_e32 v1, v1
	v_and_b32_e32 v0, 0xffffff80, v0
	v_sub_u32_e32 v0, v0, v24
	v_not_b32_e32 v88, v87
	v_or_b32_e32 v89, 0x80000000, v87
	v_cmp_gt_i32_e32 vcc, 0, v87
	v_add_u32_e32 v86, 0x7e, v86
	v_add_u32_e32 v0, 0x7f, v0
	v_cndmask_b32_e32 v87, v89, v88, vcc
	v_not_b32_e32 v88, v1
	v_or_b32_e32 v89, 0x80000000, v1
	v_cmp_gt_i32_e32 vcc, 0, v1
	v_and_b32_e32 v87, 0xffffff80, v87
	v_sub_u32_e32 v87, v87, v25
	v_cndmask_b32_e32 v1, v89, v88, vcc
	v_cvt_f32_f16_sdwa v88, v2 dst_sel:DWORD dst_unused:UNUSED_PAD src0_sel:WORD_1
	v_cvt_f32_f16_e32 v2, v2
	v_and_b32_e32 v1, 0xffffff80, v1
	v_sub_u32_e32 v1, v1, v25
	v_not_b32_e32 v89, v88
	v_or_b32_e32 v90, 0x80000000, v88
	v_cmp_gt_i32_e32 vcc, 0, v88
	v_add_u32_e32 v87, 0x7e, v87
	v_add_u32_e32 v1, 0x7f, v1
	v_cndmask_b32_e32 v88, v90, v89, vcc
	v_not_b32_e32 v89, v2
	v_or_b32_e32 v90, 0x80000000, v2
	v_cmp_gt_i32_e32 vcc, 0, v2
	v_and_b32_e32 v88, 0xffffff80, v88
	v_sub_u32_e32 v88, v88, v26
	v_cndmask_b32_e32 v2, v90, v89, vcc
	v_cvt_f32_f16_sdwa v89, v3 dst_sel:DWORD dst_unused:UNUSED_PAD src0_sel:WORD_1
	v_cvt_f32_f16_e32 v3, v3
	v_and_b32_e32 v2, 0xffffff80, v2
	v_sub_u32_e32 v2, v2, v26
	v_not_b32_e32 v90, v89
	v_or_b32_e32 v91, 0x80000000, v89
	v_cmp_gt_i32_e32 vcc, 0, v89
	v_add_u32_e32 v88, 0x7e, v88
	v_add_u32_e32 v2, 0x7f, v2
	v_cndmask_b32_e32 v89, v91, v90, vcc
	v_not_b32_e32 v90, v3
	v_or_b32_e32 v91, 0x80000000, v3
	v_cmp_gt_i32_e32 vcc, 0, v3
	v_and_b32_e32 v89, 0xffffff80, v89
	v_sub_u32_e32 v89, v89, v28
	v_cndmask_b32_e32 v3, v91, v90, vcc
	v_and_b32_e32 v3, 0xffffff80, v3
	v_sub_u32_e32 v3, v3, v28
	v_add_u32_e32 v89, 0x7e, v89
	v_add_u32_e32 v3, 0x7f, v3
	v_max_u32_e32 v90, v66, v74
	v_min_u32_e32 v66, v66, v74
	v_max_u32_e32 v74, v75, v67
	v_min_u32_e32 v67, v75, v67
	v_max_u32_e32 v75, v68, v76
	v_min_u32_e32 v68, v68, v76
	v_max_u32_e32 v76, v77, v69
	v_min_u32_e32 v69, v77, v69
	v_max_u32_e32 v77, v62, v78
	v_min_u32_e32 v62, v62, v78
	v_max_u32_e32 v78, v79, v63
	v_min_u32_e32 v63, v79, v63
	v_max_u32_e32 v79, v64, v80
	v_min_u32_e32 v64, v64, v80
	v_max_u32_e32 v80, v81, v65
	v_min_u32_e32 v65, v81, v65
	v_max_u32_e32 v98, v70, v82
	v_min_u32_e32 v70, v70, v82
	v_max_u32_e32 v82, v83, v71
	v_min_u32_e32 v71, v83, v71
	v_max_u32_e32 v83, v72, v84
	v_min_u32_e32 v72, v72, v84
	v_max_u32_e32 v84, v85, v73
	v_min_u32_e32 v73, v85, v73
	v_max_u32_e32 v85, v0, v86
	v_min_u32_e32 v0, v0, v86
	v_max_u32_e32 v86, v87, v1
	v_min_u32_e32 v1, v87, v1
	v_max_u32_e32 v87, v2, v88
	v_min_u32_e32 v2, v2, v88
	v_max_u32_e32 v88, v89, v3
	v_min_u32_e32 v3, v89, v3
	v_max_u32_e32 v81, v90, v67
	v_min_u32_e32 v67, v90, v67
	v_max_u32_e32 v90, v66, v74
	v_min_u32_e32 v66, v66, v74
	v_max_u32_e32 v74, v69, v75
	v_min_u32_e32 v69, v69, v75
	v_max_u32_e32 v75, v76, v68
	v_min_u32_e32 v68, v76, v68
; #define CE_DESC(a, b) do { const unsigned _mx = (a) > (b) ? (a) : (b), _mn = (a) > (b) ? (b) : (a); (a) = _mx; (b) = _mn; } while (0)
; __device__ __forceinline__ void sort16_desc(unsigned (&k)[16]) {
; #pragma unroll
;     for (int size = 2; size <= 16; size <<= 1)
; #pragma unroll
;         for (int stride = size >> 1; stride > 0; stride >>= 1)
; #pragma unroll
;             for (int i = 0; i < 16; ++i) { const int j = i ^ stride;
;                 if (j > i) { if ((i & size) == 0) CE_DESC(k[i], k[j]); else CE_DESC(k[j], k[i]); } }
; }
	v_max_u32_e32 v76, v77, v63
	v_min_u32_e32 v63, v77, v63
	v_max_u32_e32 v77, v62, v78
	v_min_u32_e32 v62, v62, v78
	v_max_u32_e32 v78, v65, v79
	v_min_u32_e32 v65, v65, v79
	v_max_u32_e32 v79, v80, v64
	v_min_u32_e32 v64, v80, v64
	v_max_u32_e32 v89, v98, v71
	v_min_u32_e32 v71, v98, v71
	v_max_u32_e32 v98, v70, v82
	v_min_u32_e32 v70, v70, v82
	v_max_u32_e32 v82, v73, v83
	v_min_u32_e32 v73, v73, v83
	v_max_u32_e32 v83, v84, v72
	v_min_u32_e32 v72, v84, v72
	v_max_u32_e32 v84, v85, v1
	v_min_u32_e32 v1, v85, v1
	v_max_u32_e32 v85, v0, v86
	v_min_u32_e32 v0, v0, v86
	v_max_u32_e32 v86, v3, v87
	v_min_u32_e32 v3, v3, v87
	v_max_u32_e32 v87, v88, v2
	v_min_u32_e32 v2, v88, v2
	v_max_u32_e32 v80, v81, v90
	v_min_u32_e32 v81, v81, v90
	v_max_u32_e32 v90, v67, v66
	v_min_u32_e32 v66, v67, v66
	v_max_u32_e32 v67, v68, v69
	v_min_u32_e32 v68, v68, v69
	v_max_u32_e32 v69, v75, v74
	v_min_u32_e32 v74, v75, v74
	v_max_u32_e32 v75, v76, v77
	v_min_u32_e32 v76, v76, v77
	v_max_u32_e32 v77, v63, v62
	v_min_u32_e32 v62, v63, v62
	v_max_u32_e32 v63, v64, v65
	v_min_u32_e32 v64, v64, v65
	v_max_u32_e32 v65, v79, v78
	v_min_u32_e32 v78, v79, v78
	v_max_u32_e32 v88, v89, v98
	v_min_u32_e32 v89, v89, v98
	v_max_u32_e32 v98, v71, v70
	v_min_u32_e32 v70, v71, v70
	v_max_u32_e32 v71, v72, v73
	v_min_u32_e32 v72, v72, v73
	v_max_u32_e32 v73, v83, v82
	v_min_u32_e32 v82, v83, v82
	v_max_u32_e32 v83, v84, v85
	v_min_u32_e32 v84, v84, v85
	v_max_u32_e32 v85, v1, v0
	v_min_u32_e32 v0, v1, v0
	v_max_u32_e32 v1, v2, v3
	v_min_u32_e32 v2, v2, v3
	v_max_u32_e32 v3, v87, v86
	v_min_u32_e32 v86, v87, v86
	v_max_u32_e32 v79, v80, v68
	v_min_u32_e32 v68, v80, v68
	v_max_u32_e32 v80, v81, v67
	v_min_u32_e32 v67, v81, v67
	v_max_u32_e32 v81, v90, v74
	v_min_u32_e32 v74, v90, v74
	v_max_u32_e32 v90, v66, v69
	v_min_u32_e32 v66, v66, v69
	v_max_u32_e32 v69, v64, v75
	v_min_u32_e32 v64, v64, v75
	v_max_u32_e32 v75, v63, v76
	v_min_u32_e32 v63, v63, v76
	v_max_u32_e32 v76, v78, v77
	v_min_u32_e32 v77, v78, v77
	v_max_u32_e32 v78, v65, v62
	v_min_u32_e32 v62, v65, v62
	v_max_u32_e32 v87, v88, v72
	v_min_u32_e32 v72, v88, v72
	v_max_u32_e32 v88, v89, v71
	v_min_u32_e32 v71, v89, v71
	v_max_u32_e32 v89, v98, v82
	v_min_u32_e32 v82, v98, v82
	v_max_u32_e32 v98, v70, v73
	v_min_u32_e32 v70, v70, v73
	v_max_u32_e32 v73, v2, v83
	v_min_u32_e32 v2, v2, v83
	v_max_u32_e32 v83, v1, v84
	v_min_u32_e32 v1, v1, v84
	v_max_u32_e32 v84, v86, v85
	v_min_u32_e32 v85, v86, v85
	v_max_u32_e32 v86, v3, v0
	v_min_u32_e32 v0, v3, v0
	v_max_u32_e32 v65, v79, v81
	v_min_u32_e32 v79, v79, v81
	v_max_u32_e32 v81, v80, v90
	v_min_u32_e32 v80, v80, v90
	v_max_u32_e32 v90, v68, v74
	v_min_u32_e32 v68, v68, v74
	v_max_u32_e32 v74, v67, v66
	v_min_u32_e32 v66, v67, v66
	v_max_u32_e32 v67, v77, v64
	v_min_u32_e32 v64, v77, v64
	v_max_u32_e32 v77, v62, v63
	v_min_u32_e32 v62, v62, v63
	v_max_u32_e32 v63, v76, v69
	v_min_u32_e32 v69, v76, v69
	v_max_u32_e32 v76, v78, v75
	v_min_u32_e32 v75, v78, v75
	v_max_u32_e32 v3, v87, v89
	v_min_u32_e32 v87, v87, v89
	v_max_u32_e32 v89, v88, v98
	v_min_u32_e32 v88, v88, v98
	v_max_u32_e32 v98, v72, v82
	v_min_u32_e32 v72, v72, v82
	v_max_u32_e32 v82, v71, v70
	v_min_u32_e32 v70, v71, v70
	v_max_u32_e32 v71, v85, v2
	v_min_u32_e32 v2, v85, v2
	v_max_u32_e32 v85, v0, v1
	v_min_u32_e32 v0, v0, v1
	v_max_u32_e32 v1, v84, v73
	v_min_u32_e32 v73, v84, v73
	v_max_u32_e32 v84, v86, v83
	v_min_u32_e32 v83, v86, v83
	v_max_u32_e32 v78, v65, v81
	v_min_u32_e32 v65, v65, v81
	v_max_u32_e32 v81, v79, v80
	v_min_u32_e32 v79, v79, v80
	v_max_u32_e32 v80, v90, v74
	v_min_u32_e32 v74, v90, v74
	v_max_u32_e32 v90, v68, v66
	v_min_u32_e32 v66, v68, v66
	v_max_u32_e32 v68, v62, v64
	v_min_u32_e32 v62, v62, v64
	v_max_u32_e32 v64, v77, v67
	v_min_u32_e32 v67, v77, v67
	v_max_u32_e32 v77, v75, v69
	v_min_u32_e32 v69, v75, v69
	v_max_u32_e32 v75, v76, v63
	v_min_u32_e32 v63, v76, v63
	v_max_u32_e32 v86, v3, v89
	v_min_u32_e32 v3, v3, v89
	v_max_u32_e32 v89, v87, v88
	v_min_u32_e32 v87, v87, v88
	v_max_u32_e32 v88, v98, v82
	v_min_u32_e32 v82, v98, v82
	v_max_u32_e32 v98, v72, v70
	v_min_u32_e32 v70, v72, v70
	v_max_u32_e32 v72, v0, v2
	v_min_u32_e32 v0, v0, v2
	v_max_u32_e32 v2, v85, v71
	v_min_u32_e32 v71, v85, v71
	v_max_u32_e32 v85, v83, v73
	v_min_u32_e32 v73, v83, v73
	v_max_u32_e32 v83, v84, v1
	v_min_u32_e32 v1, v84, v1
	v_max_u32_e32 v76, v78, v62
	v_min_u32_e32 v62, v78, v62
	v_max_u32_e32 v78, v65, v68
	v_min_u32_e32 v65, v65, v68
	v_max_u32_e32 v68, v81, v67
	v_min_u32_e32 v67, v81, v67
	v_max_u32_e32 v81, v79, v64
	v_min_u32_e32 v64, v79, v64
	v_max_u32_e32 v79, v80, v69
	v_min_u32_e32 v69, v80, v69
	v_max_u32_e32 v80, v74, v77
	v_min_u32_e32 v74, v74, v77
	v_max_u32_e32 v77, v90, v63
	v_min_u32_e32 v63, v90, v63
	v_max_u32_e32 v90, v66, v75
	v_min_u32_e32 v66, v66, v75
	v_max_u32_e32 v84, v86, v0
	v_min_u32_e32 v0, v86, v0
	v_max_u32_e32 v86, v3, v72
	v_min_u32_e32 v3, v3, v72
	v_max_u32_e32 v72, v89, v71
	v_min_u32_e32 v71, v89, v71
	v_max_u32_e32 v89, v87, v2
	v_min_u32_e32 v2, v87, v2
	v_max_u32_e32 v87, v88, v73
	v_min_u32_e32 v73, v88, v73
	v_max_u32_e32 v88, v82, v85
	v_min_u32_e32 v82, v82, v85
	v_max_u32_e32 v85, v98, v1
	v_min_u32_e32 v1, v98, v1
	v_max_u32_e32 v98, v70, v83
	v_min_u32_e32 v70, v70, v83
	v_max_u32_e32 v75, v76, v79
	v_min_u32_e32 v76, v76, v79
	v_max_u32_e32 v79, v78, v80
	v_min_u32_e32 v78, v78, v80
	v_max_u32_e32 v80, v68, v77
	v_min_u32_e32 v68, v68, v77
	v_max_u32_e32 v77, v81, v90
	v_min_u32_e32 v81, v81, v90
	v_max_u32_e32 v90, v62, v69
	v_min_u32_e32 v62, v62, v69
	v_max_u32_e32 v69, v65, v74
	v_min_u32_e32 v65, v65, v74
	v_max_u32_e32 v74, v67, v63
; #define CE_DESC(a, b) do { const unsigned _mx = (a) > (b) ? (a) : (b), _mn = (a) > (b) ? (b) : (a); (a) = _mx; (b) = _mn; } while (0)
; __device__ __forceinline__ void sort16_desc(unsigned (&k)[16]) {
; #pragma unroll
;     for (int size = 2; size <= 16; size <<= 1)
; #pragma unroll
;         for (int stride = size >> 1; stride > 0; stride >>= 1)
; #pragma unroll
;             for (int i = 0; i < 16; ++i) { const int j = i ^ stride;
;                 if (j > i) { if ((i & size) == 0) CE_DESC(k[i], k[j]); else CE_DESC(k[j], k[i]); } }
; }
; __device__ __forceinline__ void merge16(unsigned (&a)[16], const unsigned (&b)[16]) {
; #pragma unroll
;     for (int i = 0; i < 16; ++i) a[i] = a[i] > b[15 - i] ? a[i] : b[15 - i];
; #pragma unroll
;     for (int stride = 8; stride > 0; stride >>= 1)
; #pragma unroll
;         for (int i = 0; i < 16; ++i) { const int j = i ^ stride; if (j > i) CE_DESC(a[i], a[j]); }
; }
; __device__ __forceinline__ void peer_tile(const Args& A, LAS unsigned char* lds, int tile) {
;     ...
;                 sort16_desc(k0); sort16_desc(k1); merge16(k0, k1);
; #pragma unroll
;                 for (int msk = 16; msk <= 32; msk <<= 1) {
; #pragma unroll
;                     for (int i = 0; i < 16; ++i) k1[i] = (unsigned)__shfl_xor((int)k0[i], msk);
;                     merge16(k0, k1); }
	v_min_u32_e32 v63, v67, v63
	v_max_u32_e32 v67, v64, v66
	v_min_u32_e32 v64, v64, v66
	v_max_u32_e32 v83, v84, v87
	v_min_u32_e32 v84, v84, v87
	v_max_u32_e32 v87, v86, v88
	v_min_u32_e32 v86, v86, v88
	v_max_u32_e32 v88, v72, v85
	v_min_u32_e32 v72, v72, v85
	v_max_u32_e32 v85, v89, v98
	v_min_u32_e32 v89, v89, v98
	v_max_u32_e32 v98, v0, v73
	v_min_u32_e32 v0, v0, v73
	v_max_u32_e32 v73, v3, v82
	v_min_u32_e32 v3, v3, v82
	v_max_u32_e32 v82, v71, v1
	v_min_u32_e32 v1, v71, v1
	v_max_u32_e32 v71, v2, v70
	v_min_u32_e32 v2, v2, v70
	v_max_u32_e32 v66, v75, v80
	v_min_u32_e32 v75, v75, v80
	v_max_u32_e32 v80, v79, v77
	v_min_u32_e32 v77, v79, v77
	v_max_u32_e32 v79, v76, v68
	v_min_u32_e32 v68, v76, v68
	v_max_u32_e32 v76, v78, v81
	v_min_u32_e32 v78, v78, v81
	v_max_u32_e32 v81, v90, v74
	v_min_u32_e32 v74, v90, v74
	v_max_u32_e32 v90, v69, v67
	v_min_u32_e32 v67, v69, v67
	v_max_u32_e32 v69, v62, v63
	v_min_u32_e32 v62, v62, v63
	v_max_u32_e32 v63, v65, v64
	v_min_u32_e32 v64, v65, v64
	v_max_u32_e32 v70, v83, v88
	v_min_u32_e32 v83, v83, v88
	v_max_u32_e32 v88, v87, v85
	v_min_u32_e32 v85, v87, v85
	v_max_u32_e32 v87, v84, v72
	v_min_u32_e32 v72, v84, v72
	v_max_u32_e32 v84, v86, v89
	v_min_u32_e32 v86, v86, v89
	v_max_u32_e32 v89, v98, v82
	v_min_u32_e32 v82, v98, v82
	v_max_u32_e32 v98, v73, v71
	v_min_u32_e32 v71, v73, v71
	v_max_u32_e32 v73, v0, v1
	v_min_u32_e32 v0, v0, v1
	v_max_u32_e32 v1, v3, v2
	v_min_u32_e32 v2, v3, v2
	v_min_u32_e32 v65, v66, v80
	v_min_u32_e32 v91, v75, v77
	v_min_u32_e32 v92, v79, v76
	v_min_u32_e32 v93, v68, v78
	v_min_u32_e32 v94, v81, v90
	v_min_u32_e32 v95, v74, v67
	v_min_u32_e32 v96, v69, v63
	v_min_u32_e32 v97, v62, v64
	v_min_u32_e32 v3, v70, v88
	v_min_u32_e32 v99, v83, v85
	v_min_u32_e32 v100, v87, v84
	v_min_u32_e32 v101, v72, v86
	v_min_u32_e32 v102, v89, v98
	v_min_u32_e32 v103, v82, v71
	v_min_u32_e32 v104, v73, v1
	v_min_u32_e32 v105, v0, v2
	v_max3_u32 v66, v66, v80, v105
	v_max3_u32 v0, v65, v0, v2
	v_max3_u32 v2, v75, v77, v104
	v_max3_u32 v1, v91, v73, v1
	v_max3_u32 v65, v79, v76, v103
	v_max3_u32 v71, v92, v82, v71
	v_max3_u32 v68, v68, v78, v102
	v_max3_u32 v73, v93, v89, v98
	v_max3_u32 v75, v81, v90, v101
	v_max3_u32 v72, v94, v72, v86
	v_max3_u32 v67, v74, v67, v100
	v_max3_u32 v74, v95, v87, v84
	v_max3_u32 v63, v69, v63, v99
	v_max3_u32 v69, v96, v83, v85
	v_max3_u32 v3, v62, v64, v3
	v_max3_u32 v62, v97, v70, v88
	v_max_u32_e32 v64, v66, v75
	v_min_u32_e32 v66, v66, v75
	v_max_u32_e32 v70, v0, v72
	v_min_u32_e32 v0, v0, v72
	v_max_u32_e32 v72, v2, v67
	v_min_u32_e32 v2, v2, v67
	v_max_u32_e32 v67, v1, v74
	v_min_u32_e32 v1, v1, v74
	v_max_u32_e32 v74, v65, v63
	v_min_u32_e32 v63, v65, v63
	v_max_u32_e32 v65, v71, v69
	v_min_u32_e32 v69, v71, v69
	v_max_u32_e32 v71, v68, v3
	v_min_u32_e32 v3, v68, v3
	v_max_u32_e32 v68, v73, v62
	v_min_u32_e32 v62, v73, v62
	v_max_u32_e32 v73, v64, v74
	v_min_u32_e32 v64, v64, v74
	v_max_u32_e32 v74, v70, v65
	v_min_u32_e32 v65, v70, v65
	v_max_u32_e32 v70, v72, v71
	v_min_u32_e32 v71, v72, v71
	v_max_u32_e32 v72, v67, v68
	v_min_u32_e32 v67, v67, v68
	v_max_u32_e32 v68, v66, v63
	v_min_u32_e32 v63, v66, v63
	v_max_u32_e32 v66, v0, v69
	v_min_u32_e32 v0, v0, v69
	v_max_u32_e32 v69, v2, v3
	v_min_u32_e32 v2, v2, v3
	v_max_u32_e32 v3, v1, v62
	v_min_u32_e32 v1, v1, v62
	v_max_u32_e32 v62, v73, v70
	v_min_u32_e32 v70, v73, v70
	v_max_u32_e32 v73, v74, v72
	v_min_u32_e32 v72, v74, v72
	v_max_u32_e32 v74, v64, v71
	v_min_u32_e32 v64, v64, v71
	v_max_u32_e32 v71, v65, v67
	v_min_u32_e32 v65, v65, v67
	v_max_u32_e32 v67, v68, v69
	v_min_u32_e32 v68, v68, v69
	v_max_u32_e32 v69, v66, v3
	v_min_u32_e32 v3, v66, v3
	v_max_u32_e32 v66, v63, v2
	v_min_u32_e32 v2, v63, v2
	v_max_u32_e32 v63, v0, v1
	v_min_u32_e32 v0, v0, v1
	v_max_u32_e32 v1, v62, v73
	v_min_u32_e32 v62, v62, v73
	v_max_u32_e32 v73, v70, v72
	v_min_u32_e32 v70, v70, v72
	v_max_u32_e32 v72, v74, v71
	v_min_u32_e32 v71, v74, v71
	v_max_u32_e32 v74, v64, v65
	v_min_u32_e32 v64, v64, v65
	v_max_u32_e32 v65, v67, v69
	v_min_u32_e32 v67, v67, v69
	v_max_u32_e32 v69, v68, v3
	v_min_u32_e32 v3, v68, v3
	v_max_u32_e32 v68, v66, v63
	v_min_u32_e32 v63, v66, v63
	v_max_u32_e32 v66, v2, v0
	v_min_u32_e32 v0, v2, v0
	ds_bpermute_b32 v2, v27, v1
	ds_bpermute_b32 v75, v27, v62
	ds_bpermute_b32 v76, v27, v73
	ds_bpermute_b32 v77, v27, v70
	ds_bpermute_b32 v78, v27, v72
	ds_bpermute_b32 v79, v27, v71
	ds_bpermute_b32 v80, v27, v74
	ds_bpermute_b32 v81, v27, v64
	ds_bpermute_b32 v82, v27, v65
	ds_bpermute_b32 v83, v27, v67
	ds_bpermute_b32 v84, v27, v69
	ds_bpermute_b32 v85, v27, v0
	ds_bpermute_b32 v86, v27, v66
	ds_bpermute_b32 v87, v27, v63
	ds_bpermute_b32 v88, v27, v68
	ds_bpermute_b32 v89, v27, v3
	s_waitcnt lgkmcnt(4)
	v_max_u32_e32 v1, v1, v85
	s_waitcnt lgkmcnt(3)
	v_max_u32_e32 v62, v62, v86
	s_waitcnt lgkmcnt(2)
	v_max_u32_e32 v73, v73, v87
	s_waitcnt lgkmcnt(1)
	v_max_u32_e32 v70, v70, v88
	s_waitcnt lgkmcnt(0)
; #define CE_DESC(a, b) do { const unsigned _mx = (a) > (b) ? (a) : (b), _mn = (a) > (b) ? (b) : (a); (a) = _mx; (b) = _mn; } while (0)
; __device__ __forceinline__ void merge16(unsigned (&a)[16], const unsigned (&b)[16]) {
; #pragma unroll
;     for (int i = 0; i < 16; ++i) a[i] = a[i] > b[15 - i] ? a[i] : b[15 - i];
; #pragma unroll
;     for (int stride = 8; stride > 0; stride >>= 1)
; #pragma unroll
;         for (int i = 0; i < 16; ++i) { const int j = i ^ stride; if (j > i) CE_DESC(a[i], a[j]); }
; }
; __device__ __forceinline__ void peer_tile(const Args& A, LAS unsigned char* lds, int tile) {
;     ...
;                 { const bf16_t* sp = QRY + m * 2048 + hp * 128 + 32 * g;
;                   const u32x4 s0 = *(const u32x4*)sp, s1 = *(const u32x4*)(sp + 8), s2 = *(const u32x4*)(sp + 16), s3 = *(const u32x4*)(sp + 24);
;                   const unsigned sw[16] = {s0.x, s0.y, s0.z, s0.w, s1.x, s1.y, s1.z, s1.w, s2.x, s2.y, s2.z, s2.w, s3.x, s3.y, s3.z, s3.w};
;     ...
;                 sort16_desc(k0); sort16_desc(k1); merge16(k0, k1);
; #pragma unroll
;                 for (int msk = 16; msk <= 32; msk <<= 1) {
; #pragma unroll
;                     for (int i = 0; i < 16; ++i) k1[i] = (unsigned)__shfl_xor((int)k0[i], msk);
;                     merge16(k0, k1); }
	v_max_u32_e32 v72, v72, v89
	v_max_u32_e32 v71, v71, v84
	v_max_u32_e32 v74, v74, v83
	v_max_u32_e32 v64, v64, v82
	v_max_u32_e32 v65, v65, v81
	v_max_u32_e32 v67, v67, v80
	v_max_u32_e32 v69, v69, v79
	v_max_u32_e32 v3, v3, v78
	v_max_u32_e32 v68, v68, v77
	v_max_u32_e32 v63, v63, v76
	v_max_u32_e32 v66, v66, v75
	v_max_u32_e32 v0, v0, v2
	v_max_u32_e32 v2, v1, v65
	v_min_u32_e32 v1, v1, v65
	v_max_u32_e32 v65, v62, v67
	v_min_u32_e32 v62, v62, v67
	v_max_u32_e32 v67, v73, v69
	v_min_u32_e32 v69, v73, v69
	v_max_u32_e32 v73, v70, v3
	v_min_u32_e32 v3, v70, v3
	v_max_u32_e32 v70, v72, v68
	v_min_u32_e32 v68, v72, v68
	v_max_u32_e32 v72, v71, v63
	v_min_u32_e32 v63, v71, v63
	v_max_u32_e32 v71, v74, v66
	v_min_u32_e32 v66, v74, v66
	v_max_u32_e32 v74, v64, v0
	v_min_u32_e32 v0, v64, v0
	v_max_u32_e32 v64, v2, v70
	v_min_u32_e32 v2, v2, v70
	v_max_u32_e32 v70, v65, v72
	v_min_u32_e32 v65, v65, v72
	v_max_u32_e32 v72, v67, v71
	v_min_u32_e32 v67, v67, v71
	v_max_u32_e32 v71, v73, v74
	v_min_u32_e32 v73, v73, v74
	v_max_u32_e32 v74, v1, v68
	v_min_u32_e32 v1, v1, v68
	v_max_u32_e32 v68, v62, v63
	v_min_u32_e32 v62, v62, v63
	v_max_u32_e32 v63, v69, v66
	v_min_u32_e32 v66, v69, v66
	v_max_u32_e32 v69, v3, v0
	v_min_u32_e32 v0, v3, v0
	v_max_u32_e32 v3, v64, v72
	v_min_u32_e32 v64, v64, v72
	v_max_u32_e32 v72, v70, v71
	v_min_u32_e32 v70, v70, v71
	v_max_u32_e32 v71, v2, v67
	v_min_u32_e32 v2, v2, v67
	v_max_u32_e32 v67, v65, v73
	v_min_u32_e32 v65, v65, v73
	v_max_u32_e32 v73, v74, v63
	v_min_u32_e32 v63, v74, v63
	v_max_u32_e32 v74, v68, v69
	v_min_u32_e32 v68, v68, v69
	v_max_u32_e32 v69, v1, v66
	v_min_u32_e32 v1, v1, v66
	v_max_u32_e32 v66, v62, v0
	v_min_u32_e32 v0, v62, v0
	v_max_u32_e32 v62, v3, v72
	v_min_u32_e32 v3, v3, v72
	v_max_u32_e32 v72, v64, v70
	v_min_u32_e32 v64, v64, v70
	v_max_u32_e32 v70, v71, v67
	v_min_u32_e32 v67, v71, v67
	v_max_u32_e32 v71, v2, v65
	v_min_u32_e32 v2, v2, v65
	v_max_u32_e32 v65, v73, v74
	v_min_u32_e32 v73, v73, v74
	v_max_u32_e32 v74, v63, v68
	v_min_u32_e32 v63, v63, v68
	v_max_u32_e32 v68, v69, v66
	v_min_u32_e32 v66, v69, v66
	v_max_u32_e32 v69, v1, v0
	v_min_u32_e32 v0, v1, v0
	ds_bpermute_b32 v78, v29, v0
	ds_bpermute_b32 v1, v29, v62
	ds_bpermute_b32 v75, v29, v3
	ds_bpermute_b32 v76, v29, v72
	ds_bpermute_b32 v77, v29, v64
	s_waitcnt lgkmcnt(4)
	v_max_u32_e32 v62, v62, v78
	global_load_dwordx4 v[78:81], v[4:5], off offset:784
	global_load_dwordx4 v[82:85], v[4:5], off offset:768
	ds_bpermute_b32 v86, v29, v70
	ds_bpermute_b32 v87, v29, v67
	ds_bpermute_b32 v88, v29, v71
	ds_bpermute_b32 v89, v29, v2
	ds_bpermute_b32 v90, v29, v65
	ds_bpermute_b32 v91, v29, v73
	ds_bpermute_b32 v92, v29, v74
	ds_bpermute_b32 v93, v29, v63
	ds_bpermute_b32 v94, v29, v68
	ds_bpermute_b32 v95, v29, v69
	ds_bpermute_b32 v96, v29, v66
	s_waitcnt lgkmcnt(4)
	v_max_u32_e32 v67, v67, v92
	s_waitcnt lgkmcnt(3)
	v_max_u32_e32 v70, v70, v93
	s_waitcnt lgkmcnt(2)
	v_max_u32_e32 v64, v64, v94
	s_waitcnt lgkmcnt(1)
	v_max_u32_e32 v3, v3, v95
	s_waitcnt lgkmcnt(0)
	v_max_u32_e32 v72, v72, v96
	v_max_u32_e32 v71, v71, v91
	v_max_u32_e32 v2, v2, v90
	v_max_u32_e32 v65, v65, v89
	v_max_u32_e32 v73, v73, v88
	v_max_u32_e32 v74, v74, v87
	v_max_u32_e32 v63, v63, v86
	v_max_u32_e32 v68, v68, v77
	v_max_u32_e32 v66, v66, v76
	v_max_u32_e32 v69, v69, v75
	v_max_u32_e32 v0, v0, v1
	v_max_u32_e32 v1, v62, v65
	v_min_u32_e32 v62, v62, v65
	v_max_u32_e32 v65, v3, v73
	v_min_u32_e32 v3, v3, v73
	v_max_u32_e32 v73, v72, v74
	v_min_u32_e32 v72, v72, v74
	v_max_u32_e32 v74, v64, v63
	v_min_u32_e32 v63, v64, v63
	v_max_u32_e32 v64, v70, v68
	v_min_u32_e32 v68, v70, v68
	v_max_u32_e32 v70, v67, v66
	v_min_u32_e32 v66, v67, v66
	v_max_u32_e32 v67, v71, v69
	v_min_u32_e32 v69, v71, v69
	v_max_u32_e32 v71, v2, v0
	v_min_u32_e32 v0, v2, v0
	v_max_u32_e32 v2, v1, v64
	v_min_u32_e32 v1, v1, v64
	v_max_u32_e32 v64, v65, v70
	v_min_u32_e32 v65, v65, v70
	v_max_u32_e32 v70, v73, v67
	v_min_u32_e32 v67, v73, v67
	v_max_u32_e32 v73, v74, v71
	v_min_u32_e32 v71, v74, v71
	v_max_u32_e32 v74, v62, v68
	v_min_u32_e32 v62, v62, v68
	v_max_u32_e32 v68, v3, v66
	v_min_u32_e32 v3, v3, v66
	v_max_u32_e32 v66, v72, v69
	v_min_u32_e32 v69, v72, v69
	v_max_u32_e32 v72, v63, v0
	v_min_u32_e32 v0, v63, v0
	v_max_u32_e32 v63, v2, v70
	v_min_u32_e32 v2, v2, v70
	v_max_u32_e32 v70, v64, v73
	v_min_u32_e32 v64, v64, v73
	v_max_u32_e32 v86, v1, v67
	v_min_u32_e32 v1, v1, v67
	v_max_u32_e32 v67, v65, v71
	v_min_u32_e32 v65, v65, v71
	v_max_u32_e32 v87, v74, v66
	v_min_u32_e32 v66, v74, v66
	v_max_u32_e32 v88, v68, v72
	v_min_u32_e32 v89, v68, v72
	v_max_u32_e32 v90, v62, v69
	v_min_u32_e32 v62, v62, v69
	v_max_u32_e32 v91, v3, v0
	v_min_u32_e32 v0, v3, v0
	v_max_u32_e32 v77, v63, v70
	v_min_u32_e32 v76, v63, v70
	v_max_u32_e32 v75, v2, v64
	v_min_u32_e32 v74, v2, v64
	v_max_u32_e32 v73, v86, v67
	v_min_u32_e32 v72, v86, v67
	v_max_u32_e32 v71, v1, v65
	v_min_u32_e32 v70, v1, v65
	v_max_u32_e32 v69, v87, v88
	v_min_u32_e32 v68, v87, v88
	v_max_u32_e32 v67, v66, v89
	v_min_u32_e32 v66, v66, v89
	v_max_u32_e32 v63, v62, v0
	v_min_u32_e32 v62, v62, v0
	global_load_dwordx4 v[0:3], v[4:5], off offset:816
	global_load_dwordx4 v[86:89], v[4:5], off offset:800
	v_max_u32_e32 v65, v90, v91
	v_min_u32_e32 v64, v90, v91
	s_waitcnt vmcnt(2)
; __device__ __forceinline__ unsigned f2key(float f) { const unsigned u = __float_as_uint(f); return (u & 0x80000000u) ? ~u : (u | 0x80000000u); }
; __device__ __forceinline__ void peer_tile(const Args& A, LAS unsigned char* lds, int tile) {
;     ...
;                   for (int i = 0; i < 16; ++i) {
;                       const float lo = (float)__builtin_bit_cast(_Float16, (unsigned short)(sw[i] & 0xffffu)), hi = (float)__builtin_bit_cast(_Float16, (unsigned short)(sw[i] >> 16));
;                       const unsigned klo = (f2key(lo) & ~127u) | (unsigned)(127 - (32 * g + 2 * i)), khi = (f2key(hi) & ~127u) | (unsigned)(127 - (32 * g + 2 * i + 1));
;                       if (i < 8) { k0[2 * i] = klo; k0[2 * i + 1] = khi; } else { k1[2 * (i - 8)] = klo; k1[2 * (i - 8) + 1] = khi; } } }
;     ...
;                 for (int i = 0; i < 16; ++i) L2[p][i] = (g & 2) ? ((g & 1) ? LA[3][p][i] : LA[2][p][i]) : ((g & 1) ? LA[1][p][i] : LA[0][p][i]);
	v_cvt_f32_f16_sdwa v90, v82 dst_sel:DWORD dst_unused:UNUSED_PAD src0_sel:WORD_1
	v_cvt_f32_f16_e32 v82, v82
	v_cndmask_b32_e64 v38, v70, v38, s[0:1]
	v_cndmask_b32_e64 v37, v69, v37, s[0:1]
	v_not_b32_e32 v91, v90
	v_or_b32_e32 v92, 0x80000000, v90
	v_cmp_gt_i32_e32 vcc, 0, v90
	v_cndmask_b32_e64 v36, v68, v36, s[0:1]
	v_cndmask_b32_e64 v35, v67, v35, s[0:1]
	v_cndmask_b32_e32 v90, v92, v91, vcc
	v_not_b32_e32 v91, v82
	v_or_b32_e32 v92, 0x80000000, v82
	v_cmp_gt_i32_e32 vcc, 0, v82
	v_and_b32_e32 v90, 0xffffff80, v90
	v_sub_u32_e32 v90, v90, v15
	v_cndmask_b32_e32 v82, v92, v91, vcc
	v_cvt_f32_f16_sdwa v91, v83 dst_sel:DWORD dst_unused:UNUSED_PAD src0_sel:WORD_1
	v_cvt_f32_f16_e32 v83, v83
	v_and_b32_e32 v82, 0xffffff80, v82
	v_sub_u32_e32 v82, v82, v15
	v_not_b32_e32 v92, v91
	v_or_b32_e32 v93, 0x80000000, v91
	v_cmp_gt_i32_e32 vcc, 0, v91
	v_add_u32_e32 v90, 0x7e, v90
	v_add_u32_e32 v82, 0x7f, v82
	v_cndmask_b32_e32 v91, v93, v92, vcc
	v_not_b32_e32 v92, v83
	v_or_b32_e32 v93, 0x80000000, v83
	v_cmp_gt_i32_e32 vcc, 0, v83
	v_and_b32_e32 v91, 0xffffff80, v91
	v_sub_u32_e32 v91, v91, v14
	v_cndmask_b32_e32 v83, v93, v92, vcc
	v_cvt_f32_f16_sdwa v92, v84 dst_sel:DWORD dst_unused:UNUSED_PAD src0_sel:WORD_1
	v_cvt_f32_f16_e32 v84, v84
	v_and_b32_e32 v83, 0xffffff80, v83
	v_sub_u32_e32 v83, v83, v14
	v_not_b32_e32 v93, v92
	v_or_b32_e32 v94, 0x80000000, v92
	v_cmp_gt_i32_e32 vcc, 0, v92
	v_add_u32_e32 v91, 0x7e, v91
	v_add_u32_e32 v83, 0x7f, v83
	v_cndmask_b32_e32 v92, v94, v93, vcc
	v_not_b32_e32 v93, v84
	v_or_b32_e32 v94, 0x80000000, v84
	v_cmp_gt_i32_e32 vcc, 0, v84
	v_and_b32_e32 v92, 0xffffff80, v92
	v_sub_u32_e32 v92, v92, v12
	v_cndmask_b32_e32 v84, v94, v93, vcc
	v_cvt_f32_f16_sdwa v93, v85 dst_sel:DWORD dst_unused:UNUSED_PAD src0_sel:WORD_1
	v_cvt_f32_f16_e32 v85, v85
	v_and_b32_e32 v84, 0xffffff80, v84
	v_sub_u32_e32 v84, v84, v12
	v_not_b32_e32 v94, v93
	v_or_b32_e32 v95, 0x80000000, v93
	v_cmp_gt_i32_e32 vcc, 0, v93
	v_add_u32_e32 v92, 0x7e, v92
	v_add_u32_e32 v84, 0x7f, v84
	v_cndmask_b32_e32 v93, v95, v94, vcc
	v_not_b32_e32 v94, v85
	v_or_b32_e32 v95, 0x80000000, v85
	v_cmp_gt_i32_e32 vcc, 0, v85
	v_and_b32_e32 v93, 0xffffff80, v93
	v_sub_u32_e32 v93, v93, v10
	v_cndmask_b32_e32 v85, v95, v94, vcc
	v_cvt_f32_f16_sdwa v94, v78 dst_sel:DWORD dst_unused:UNUSED_PAD src0_sel:WORD_1
	v_cvt_f32_f16_e32 v78, v78
	v_and_b32_e32 v85, 0xffffff80, v85
	v_sub_u32_e32 v85, v85, v10
	v_not_b32_e32 v95, v94
	v_or_b32_e32 v96, 0x80000000, v94
	v_cmp_gt_i32_e32 vcc, 0, v94
	v_add_u32_e32 v93, 0x7e, v93
	v_add_u32_e32 v85, 0x7f, v85
	v_cndmask_b32_e32 v94, v96, v95, vcc
	v_not_b32_e32 v95, v78
	v_or_b32_e32 v96, 0x80000000, v78
	v_cmp_gt_i32_e32 vcc, 0, v78
	v_and_b32_e32 v94, 0xffffff80, v94
	v_sub_u32_e32 v94, v94, v8
	v_cndmask_b32_e32 v78, v96, v95, vcc
	v_cvt_f32_f16_sdwa v95, v79 dst_sel:DWORD dst_unused:UNUSED_PAD src0_sel:WORD_1
	v_cvt_f32_f16_e32 v79, v79
	v_and_b32_e32 v78, 0xffffff80, v78
	v_sub_u32_e32 v78, v78, v8
	v_not_b32_e32 v96, v95
	v_or_b32_e32 v97, 0x80000000, v95
	v_cmp_gt_i32_e32 vcc, 0, v95
	v_add_u32_e32 v94, 0x7e, v94
	v_add_u32_e32 v78, 0x7f, v78
	v_cndmask_b32_e32 v95, v97, v96, vcc
	v_not_b32_e32 v96, v79
	v_or_b32_e32 v97, 0x80000000, v79
	v_cmp_gt_i32_e32 vcc, 0, v79
	v_and_b32_e32 v95, 0xffffff80, v95
	v_sub_u32_e32 v95, v95, v16
	v_cndmask_b32_e32 v79, v97, v96, vcc
	v_cvt_f32_f16_sdwa v96, v80 dst_sel:DWORD dst_unused:UNUSED_PAD src0_sel:WORD_1
	v_cvt_f32_f16_e32 v80, v80
	v_and_b32_e32 v79, 0xffffff80, v79
	v_sub_u32_e32 v79, v79, v16
	v_not_b32_e32 v97, v96
	v_or_b32_e32 v98, 0x80000000, v96
	v_cmp_gt_i32_e32 vcc, 0, v96
	v_add_u32_e32 v95, 0x7e, v95
	v_add_u32_e32 v79, 0x7f, v79
	v_cndmask_b32_e32 v96, v98, v97, vcc
	v_not_b32_e32 v97, v80
	v_or_b32_e32 v98, 0x80000000, v80
	v_cmp_gt_i32_e32 vcc, 0, v80
	v_and_b32_e32 v96, 0xffffff80, v96
	v_sub_u32_e32 v96, v96, v17
	v_cndmask_b32_e32 v80, v98, v97, vcc
	v_cvt_f32_f16_sdwa v97, v81 dst_sel:DWORD dst_unused:UNUSED_PAD src0_sel:WORD_1
	v_cvt_f32_f16_e32 v81, v81
	v_and_b32_e32 v80, 0xffffff80, v80
	v_sub_u32_e32 v80, v80, v17
	v_not_b32_e32 v98, v97
	v_or_b32_e32 v99, 0x80000000, v97
	v_cmp_gt_i32_e32 vcc, 0, v97
	v_add_u32_e32 v96, 0x7e, v96
	v_add_u32_e32 v80, 0x7f, v80
	v_cndmask_b32_e32 v97, v99, v98, vcc
	v_not_b32_e32 v98, v81
	v_or_b32_e32 v99, 0x80000000, v81
	v_cmp_gt_i32_e32 vcc, 0, v81
	v_and_b32_e32 v97, 0xffffff80, v97
	v_sub_u32_e32 v97, v97, v18
	v_cndmask_b32_e32 v81, v99, v98, vcc
	s_waitcnt vmcnt(0)
; __device__ __forceinline__ unsigned f2key(float f) { const unsigned u = __float_as_uint(f); return (u & 0x80000000u) ? ~u : (u | 0x80000000u); }
; #define CE_DESC(a, b) do { const unsigned _mx = (a) > (b) ? (a) : (b), _mn = (a) > (b) ? (b) : (a); (a) = _mx; (b) = _mn; } while (0)
; __device__ __forceinline__ void sort16_desc(unsigned (&k)[16]) {
; #pragma unroll
;     for (int size = 2; size <= 16; size <<= 1)
; #pragma unroll
;         for (int stride = size >> 1; stride > 0; stride >>= 1)
; #pragma unroll
;             for (int i = 0; i < 16; ++i) { const int j = i ^ stride;
;                 if (j > i) { if ((i & size) == 0) CE_DESC(k[i], k[j]); else CE_DESC(k[j], k[i]); } }
; }
; __device__ __forceinline__ void peer_tile(const Args& A, LAS unsigned char* lds, int tile) {
;     ...
;                   for (int i = 0; i < 16; ++i) {
;                       const float lo = (float)__builtin_bit_cast(_Float16, (unsigned short)(sw[i] & 0xffffu)), hi = (float)__builtin_bit_cast(_Float16, (unsigned short)(sw[i] >> 16));
;                       const unsigned klo = (f2key(lo) & ~127u) | (unsigned)(127 - (32 * g + 2 * i)), khi = (f2key(hi) & ~127u) | (unsigned)(127 - (32 * g + 2 * i + 1));
;                       if (i < 8) { k0[2 * i] = klo; k0[2 * i + 1] = khi; } else { k1[2 * (i - 8)] = klo; k1[2 * (i - 8) + 1] = khi; } } }
	v_cvt_f32_f16_sdwa v98, v86 dst_sel:DWORD dst_unused:UNUSED_PAD src0_sel:WORD_1
	v_cvt_f32_f16_e32 v86, v86
	v_and_b32_e32 v81, 0xffffff80, v81
	v_sub_u32_e32 v81, v81, v18
	v_not_b32_e32 v99, v98
	v_or_b32_e32 v100, 0x80000000, v98
	v_cmp_gt_i32_e32 vcc, 0, v98
	v_add_u32_e32 v97, 0x7e, v97
	v_add_u32_e32 v81, 0x7f, v81
	v_cndmask_b32_e32 v98, v100, v99, vcc
	v_not_b32_e32 v99, v86
	v_or_b32_e32 v100, 0x80000000, v86
	v_cmp_gt_i32_e32 vcc, 0, v86
	v_and_b32_e32 v98, 0xffffff80, v98
	v_sub_u32_e32 v98, v98, v20
	v_cndmask_b32_e32 v86, v100, v99, vcc
	v_cvt_f32_f16_sdwa v99, v87 dst_sel:DWORD dst_unused:UNUSED_PAD src0_sel:WORD_1
	v_cvt_f32_f16_e32 v87, v87
	v_and_b32_e32 v86, 0xffffff80, v86
	v_sub_u32_e32 v86, v86, v20
	v_not_b32_e32 v100, v99
	v_or_b32_e32 v101, 0x80000000, v99
	v_cmp_gt_i32_e32 vcc, 0, v99
	v_add_u32_e32 v98, 0x7e, v98
	v_add_u32_e32 v86, 0x7f, v86
	v_cndmask_b32_e32 v99, v101, v100, vcc
	v_not_b32_e32 v100, v87
	v_or_b32_e32 v101, 0x80000000, v87
	v_cmp_gt_i32_e32 vcc, 0, v87
	v_and_b32_e32 v99, 0xffffff80, v99
	v_sub_u32_e32 v99, v99, v21
	v_cndmask_b32_e32 v87, v101, v100, vcc
	v_cvt_f32_f16_sdwa v100, v88 dst_sel:DWORD dst_unused:UNUSED_PAD src0_sel:WORD_1
	v_cvt_f32_f16_e32 v88, v88
	v_and_b32_e32 v87, 0xffffff80, v87
	v_sub_u32_e32 v87, v87, v21
	v_not_b32_e32 v101, v100
	v_or_b32_e32 v102, 0x80000000, v100
	v_cmp_gt_i32_e32 vcc, 0, v100
	v_add_u32_e32 v99, 0x7e, v99
	v_add_u32_e32 v87, 0x7f, v87
	v_cndmask_b32_e32 v100, v102, v101, vcc
	v_not_b32_e32 v101, v88
	v_or_b32_e32 v102, 0x80000000, v88
	v_cmp_gt_i32_e32 vcc, 0, v88
	v_and_b32_e32 v100, 0xffffff80, v100
	v_sub_u32_e32 v100, v100, v22
	v_cndmask_b32_e32 v88, v102, v101, vcc
	v_cvt_f32_f16_sdwa v101, v89 dst_sel:DWORD dst_unused:UNUSED_PAD src0_sel:WORD_1
	v_cvt_f32_f16_e32 v89, v89
	v_and_b32_e32 v88, 0xffffff80, v88
	v_sub_u32_e32 v88, v88, v22
	v_not_b32_e32 v102, v101
	v_or_b32_e32 v103, 0x80000000, v101
	v_cmp_gt_i32_e32 vcc, 0, v101
	v_add_u32_e32 v100, 0x7e, v100
	v_add_u32_e32 v88, 0x7f, v88
	v_cndmask_b32_e32 v101, v103, v102, vcc
	v_not_b32_e32 v102, v89
	v_or_b32_e32 v103, 0x80000000, v89
	v_cmp_gt_i32_e32 vcc, 0, v89
	v_and_b32_e32 v101, 0xffffff80, v101
	v_sub_u32_e32 v101, v101, v23
	v_cndmask_b32_e32 v89, v103, v102, vcc
	v_cvt_f32_f16_sdwa v102, v0 dst_sel:DWORD dst_unused:UNUSED_PAD src0_sel:WORD_1
	v_cvt_f32_f16_e32 v0, v0
	v_and_b32_e32 v89, 0xffffff80, v89
	v_sub_u32_e32 v89, v89, v23
	v_not_b32_e32 v103, v102
	v_or_b32_e32 v104, 0x80000000, v102
	v_cmp_gt_i32_e32 vcc, 0, v102
	v_add_u32_e32 v101, 0x7e, v101
	v_add_u32_e32 v89, 0x7f, v89
	v_cndmask_b32_e32 v102, v104, v103, vcc
	v_not_b32_e32 v103, v0
	v_or_b32_e32 v104, 0x80000000, v0
	v_cmp_gt_i32_e32 vcc, 0, v0
	v_and_b32_e32 v102, 0xffffff80, v102
	v_sub_u32_e32 v102, v102, v24
	v_cndmask_b32_e32 v0, v104, v103, vcc
	v_cvt_f32_f16_sdwa v103, v1 dst_sel:DWORD dst_unused:UNUSED_PAD src0_sel:WORD_1
	v_cvt_f32_f16_e32 v1, v1
	v_and_b32_e32 v0, 0xffffff80, v0
	v_sub_u32_e32 v0, v0, v24
	v_not_b32_e32 v104, v103
	v_or_b32_e32 v105, 0x80000000, v103
	v_cmp_gt_i32_e32 vcc, 0, v103
	v_add_u32_e32 v102, 0x7e, v102
	v_add_u32_e32 v0, 0x7f, v0
	v_cndmask_b32_e32 v103, v105, v104, vcc
	v_not_b32_e32 v104, v1
	v_or_b32_e32 v105, 0x80000000, v1
	v_cmp_gt_i32_e32 vcc, 0, v1
	v_and_b32_e32 v103, 0xffffff80, v103
	v_sub_u32_e32 v103, v103, v25
	v_cndmask_b32_e32 v1, v105, v104, vcc
	v_cvt_f32_f16_sdwa v104, v2 dst_sel:DWORD dst_unused:UNUSED_PAD src0_sel:WORD_1
	v_cvt_f32_f16_e32 v2, v2
	v_and_b32_e32 v1, 0xffffff80, v1
	v_sub_u32_e32 v1, v1, v25
	v_not_b32_e32 v105, v104
	v_or_b32_e32 v106, 0x80000000, v104
	v_cmp_gt_i32_e32 vcc, 0, v104
	v_add_u32_e32 v103, 0x7e, v103
	v_add_u32_e32 v1, 0x7f, v1
	v_cndmask_b32_e32 v104, v106, v105, vcc
	v_not_b32_e32 v105, v2
	v_or_b32_e32 v106, 0x80000000, v2
	v_cmp_gt_i32_e32 vcc, 0, v2
	v_and_b32_e32 v104, 0xffffff80, v104
	v_sub_u32_e32 v104, v104, v26
	v_cndmask_b32_e32 v2, v106, v105, vcc
	v_cvt_f32_f16_sdwa v105, v3 dst_sel:DWORD dst_unused:UNUSED_PAD src0_sel:WORD_1
	v_cvt_f32_f16_e32 v3, v3
	v_and_b32_e32 v2, 0xffffff80, v2
	v_sub_u32_e32 v2, v2, v26
	v_not_b32_e32 v106, v105
	v_or_b32_e32 v107, 0x80000000, v105
	v_cmp_gt_i32_e32 vcc, 0, v105
	v_add_u32_e32 v104, 0x7e, v104
	v_add_u32_e32 v2, 0x7f, v2
	v_cndmask_b32_e32 v105, v107, v106, vcc
	v_not_b32_e32 v106, v3
	v_or_b32_e32 v107, 0x80000000, v3
	v_cmp_gt_i32_e32 vcc, 0, v3
	v_and_b32_e32 v105, 0xffffff80, v105
	v_sub_u32_e32 v105, v105, v28
	v_cndmask_b32_e32 v3, v107, v106, vcc
	v_and_b32_e32 v3, 0xffffff80, v3
	v_sub_u32_e32 v3, v3, v28
	v_add_u32_e32 v105, 0x7e, v105
	v_add_u32_e32 v3, 0x7f, v3
	v_max_u32_e32 v106, v82, v90
	v_min_u32_e32 v82, v82, v90
	v_max_u32_e32 v90, v91, v83
	v_min_u32_e32 v83, v91, v83
	v_max_u32_e32 v91, v84, v92
	v_min_u32_e32 v84, v84, v92
	v_max_u32_e32 v92, v93, v85
	v_min_u32_e32 v85, v93, v85
	v_max_u32_e32 v93, v78, v94
	v_min_u32_e32 v78, v78, v94
	v_max_u32_e32 v94, v95, v79
	v_min_u32_e32 v79, v95, v79
	v_max_u32_e32 v95, v80, v96
	v_min_u32_e32 v80, v80, v96
	v_max_u32_e32 v96, v97, v81
	v_min_u32_e32 v81, v97, v81
	v_max_u32_e32 v115, v86, v98
	v_min_u32_e32 v86, v86, v98
	v_max_u32_e32 v98, v99, v87
	v_min_u32_e32 v87, v99, v87
	v_max_u32_e32 v99, v88, v100
	v_min_u32_e32 v88, v88, v100
	v_max_u32_e32 v100, v101, v89
	v_min_u32_e32 v89, v101, v89
	v_max_u32_e32 v101, v0, v102
	v_min_u32_e32 v0, v0, v102
	v_max_u32_e32 v102, v103, v1
	v_min_u32_e32 v1, v103, v1
	v_max_u32_e32 v103, v2, v104
	v_min_u32_e32 v2, v2, v104
	v_max_u32_e32 v104, v105, v3
	v_min_u32_e32 v3, v105, v3
	v_max_u32_e32 v97, v106, v83
	v_min_u32_e32 v83, v106, v83
	v_max_u32_e32 v106, v82, v90
; #define CE_DESC(a, b) do { const unsigned _mx = (a) > (b) ? (a) : (b), _mn = (a) > (b) ? (b) : (a); (a) = _mx; (b) = _mn; } while (0)
; __device__ __forceinline__ void sort16_desc(unsigned (&k)[16]) {
; #pragma unroll
;     for (int size = 2; size <= 16; size <<= 1)
; #pragma unroll
;         for (int stride = size >> 1; stride > 0; stride >>= 1)
; #pragma unroll
;             for (int i = 0; i < 16; ++i) { const int j = i ^ stride;
;                 if (j > i) { if ((i & size) == 0) CE_DESC(k[i], k[j]); else CE_DESC(k[j], k[i]); } }
; }
	v_min_u32_e32 v82, v82, v90
	v_max_u32_e32 v90, v85, v91
	v_min_u32_e32 v85, v85, v91
	v_max_u32_e32 v91, v92, v84
	v_min_u32_e32 v84, v92, v84
	v_max_u32_e32 v92, v93, v79
	v_min_u32_e32 v79, v93, v79
	v_max_u32_e32 v93, v78, v94
	v_min_u32_e32 v78, v78, v94
	v_max_u32_e32 v94, v81, v95
	v_min_u32_e32 v81, v81, v95
	v_max_u32_e32 v95, v96, v80
	v_min_u32_e32 v80, v96, v80
	v_max_u32_e32 v105, v115, v87
	v_min_u32_e32 v87, v115, v87
	v_max_u32_e32 v115, v86, v98
	v_min_u32_e32 v86, v86, v98
	v_max_u32_e32 v98, v89, v99
	v_min_u32_e32 v89, v89, v99
	v_max_u32_e32 v99, v100, v88
	v_min_u32_e32 v88, v100, v88
	v_max_u32_e32 v100, v101, v1
	v_min_u32_e32 v1, v101, v1
	v_max_u32_e32 v101, v0, v102
	v_min_u32_e32 v0, v0, v102
	v_max_u32_e32 v102, v3, v103
	v_min_u32_e32 v3, v3, v103
	v_max_u32_e32 v103, v104, v2
	v_min_u32_e32 v2, v104, v2
	v_max_u32_e32 v96, v97, v106
	v_min_u32_e32 v97, v97, v106
	v_max_u32_e32 v106, v83, v82
	v_min_u32_e32 v82, v83, v82
	v_max_u32_e32 v83, v84, v85
	v_min_u32_e32 v84, v84, v85
	v_max_u32_e32 v85, v91, v90
	v_min_u32_e32 v90, v91, v90
	v_max_u32_e32 v91, v92, v93
	v_min_u32_e32 v92, v92, v93
	v_max_u32_e32 v93, v79, v78
	v_min_u32_e32 v78, v79, v78
	v_max_u32_e32 v79, v80, v81
	v_min_u32_e32 v80, v80, v81
	v_max_u32_e32 v81, v95, v94
	v_min_u32_e32 v94, v95, v94
	v_max_u32_e32 v104, v105, v115
	v_min_u32_e32 v105, v105, v115
	v_max_u32_e32 v115, v87, v86
	v_min_u32_e32 v86, v87, v86
	v_max_u32_e32 v87, v88, v89
	v_min_u32_e32 v88, v88, v89
	v_max_u32_e32 v89, v99, v98
	v_min_u32_e32 v98, v99, v98
	v_max_u32_e32 v99, v100, v101
	v_min_u32_e32 v100, v100, v101
	v_max_u32_e32 v101, v1, v0
	v_min_u32_e32 v0, v1, v0
	v_max_u32_e32 v1, v2, v3
	v_min_u32_e32 v2, v2, v3
	v_max_u32_e32 v3, v103, v102
	v_min_u32_e32 v102, v103, v102
	v_max_u32_e32 v95, v96, v84
	v_min_u32_e32 v84, v96, v84
	v_max_u32_e32 v96, v97, v83
	v_min_u32_e32 v83, v97, v83
	v_max_u32_e32 v97, v106, v90
	v_min_u32_e32 v90, v106, v90
	v_max_u32_e32 v106, v82, v85
	v_min_u32_e32 v82, v82, v85
	v_max_u32_e32 v85, v80, v91
	v_min_u32_e32 v80, v80, v91
	v_max_u32_e32 v91, v79, v92
	v_min_u32_e32 v79, v79, v92
	v_max_u32_e32 v92, v94, v93
	v_min_u32_e32 v93, v94, v93
	v_max_u32_e32 v94, v81, v78
	v_min_u32_e32 v78, v81, v78
	v_max_u32_e32 v103, v104, v88
	v_min_u32_e32 v88, v104, v88
	v_max_u32_e32 v104, v105, v87
	v_min_u32_e32 v87, v105, v87
	v_max_u32_e32 v105, v115, v98
	v_min_u32_e32 v98, v115, v98
	v_max_u32_e32 v115, v86, v89
	v_min_u32_e32 v86, v86, v89
	v_max_u32_e32 v89, v2, v99
	v_min_u32_e32 v2, v2, v99
	v_max_u32_e32 v99, v1, v100
	v_min_u32_e32 v1, v1, v100
	v_max_u32_e32 v100, v102, v101
	v_min_u32_e32 v101, v102, v101
	v_max_u32_e32 v102, v3, v0
	v_min_u32_e32 v0, v3, v0
	v_max_u32_e32 v81, v95, v97
	v_min_u32_e32 v95, v95, v97
	v_max_u32_e32 v97, v96, v106
	v_min_u32_e32 v96, v96, v106
	v_max_u32_e32 v106, v84, v90
	v_min_u32_e32 v84, v84, v90
	v_max_u32_e32 v90, v83, v82
	v_min_u32_e32 v82, v83, v82
	v_max_u32_e32 v83, v93, v80
	v_min_u32_e32 v80, v93, v80
	v_max_u32_e32 v93, v78, v79
	v_min_u32_e32 v78, v78, v79
	v_max_u32_e32 v79, v92, v85
	v_min_u32_e32 v85, v92, v85
	v_max_u32_e32 v92, v94, v91
	v_min_u32_e32 v91, v94, v91
	v_max_u32_e32 v3, v103, v105
	v_min_u32_e32 v103, v103, v105
	v_max_u32_e32 v105, v104, v115
	v_min_u32_e32 v104, v104, v115
	v_max_u32_e32 v115, v88, v98
	v_min_u32_e32 v88, v88, v98
	v_max_u32_e32 v98, v87, v86
	v_min_u32_e32 v86, v87, v86
	v_max_u32_e32 v87, v101, v2
	v_min_u32_e32 v2, v101, v2
	v_max_u32_e32 v101, v0, v1
	v_min_u32_e32 v0, v0, v1
	v_max_u32_e32 v1, v100, v89
	v_min_u32_e32 v89, v100, v89
	v_max_u32_e32 v100, v102, v99
	v_min_u32_e32 v99, v102, v99
	v_max_u32_e32 v94, v81, v97
	v_min_u32_e32 v81, v81, v97
	v_max_u32_e32 v97, v95, v96
	v_min_u32_e32 v95, v95, v96
	v_max_u32_e32 v96, v106, v90
	v_min_u32_e32 v90, v106, v90
	v_max_u32_e32 v106, v84, v82
	v_min_u32_e32 v82, v84, v82
	v_max_u32_e32 v84, v78, v80
	v_min_u32_e32 v78, v78, v80
	v_max_u32_e32 v80, v93, v83
	v_min_u32_e32 v83, v93, v83
	v_max_u32_e32 v93, v91, v85
	v_min_u32_e32 v85, v91, v85
	v_max_u32_e32 v91, v92, v79
	v_min_u32_e32 v79, v92, v79
	v_max_u32_e32 v102, v3, v105
	v_min_u32_e32 v3, v3, v105
	v_max_u32_e32 v105, v103, v104
	v_min_u32_e32 v103, v103, v104
	v_max_u32_e32 v104, v115, v98
	v_min_u32_e32 v98, v115, v98
	v_max_u32_e32 v115, v88, v86
	v_min_u32_e32 v86, v88, v86
	v_max_u32_e32 v88, v0, v2
	v_min_u32_e32 v0, v0, v2
	v_max_u32_e32 v2, v101, v87
	v_min_u32_e32 v87, v101, v87
	v_max_u32_e32 v101, v99, v89
	v_min_u32_e32 v89, v99, v89
	v_max_u32_e32 v99, v100, v1
	v_min_u32_e32 v1, v100, v1
	v_max_u32_e32 v92, v94, v78
	v_min_u32_e32 v78, v94, v78
	v_max_u32_e32 v94, v81, v84
	v_min_u32_e32 v81, v81, v84
	v_max_u32_e32 v84, v97, v83
	v_min_u32_e32 v83, v97, v83
	v_max_u32_e32 v97, v95, v80
	v_min_u32_e32 v80, v95, v80
	v_max_u32_e32 v95, v96, v85
	v_min_u32_e32 v85, v96, v85
	v_max_u32_e32 v96, v90, v93
	v_min_u32_e32 v90, v90, v93
	v_max_u32_e32 v93, v106, v79
	v_min_u32_e32 v79, v106, v79
	v_max_u32_e32 v106, v82, v91
	v_min_u32_e32 v82, v82, v91
	v_max_u32_e32 v100, v102, v0
	v_min_u32_e32 v0, v102, v0
	v_max_u32_e32 v102, v3, v88
	v_min_u32_e32 v3, v3, v88
	v_max_u32_e32 v88, v105, v87
	v_min_u32_e32 v87, v105, v87
	v_max_u32_e32 v105, v103, v2
	v_min_u32_e32 v2, v103, v2
	v_max_u32_e32 v103, v104, v89
	v_min_u32_e32 v89, v104, v89
	v_max_u32_e32 v104, v98, v101
	v_min_u32_e32 v98, v98, v101
	v_max_u32_e32 v101, v115, v1
	v_min_u32_e32 v1, v115, v1
	v_max_u32_e32 v115, v86, v99
	v_min_u32_e32 v86, v86, v99
	v_max_u32_e32 v91, v92, v95
	v_min_u32_e32 v92, v92, v95
	v_max_u32_e32 v95, v94, v96
; #define CE_DESC(a, b) do { const unsigned _mx = (a) > (b) ? (a) : (b), _mn = (a) > (b) ? (b) : (a); (a) = _mx; (b) = _mn; } while (0)
; __device__ __forceinline__ void sort16_desc(unsigned (&k)[16]) {
; #pragma unroll
;     for (int size = 2; size <= 16; size <<= 1)
; #pragma unroll
;         for (int stride = size >> 1; stride > 0; stride >>= 1)
; #pragma unroll
;             for (int i = 0; i < 16; ++i) { const int j = i ^ stride;
;                 if (j > i) { if ((i & size) == 0) CE_DESC(k[i], k[j]); else CE_DESC(k[j], k[i]); } }
; }
; __device__ __forceinline__ void merge16(unsigned (&a)[16], const unsigned (&b)[16]) {
; #pragma unroll
;     for (int i = 0; i < 16; ++i) a[i] = a[i] > b[15 - i] ? a[i] : b[15 - i];
; #pragma unroll
;     for (int stride = 8; stride > 0; stride >>= 1)
; #pragma unroll
;         for (int i = 0; i < 16; ++i) { const int j = i ^ stride; if (j > i) CE_DESC(a[i], a[j]); }
; }
; __device__ __forceinline__ void peer_tile(const Args& A, LAS unsigned char* lds, int tile) {
;     ...
;                 sort16_desc(k0); sort16_desc(k1); merge16(k0, k1);
; #pragma unroll
;                 for (int msk = 16; msk <= 32; msk <<= 1) {
; #pragma unroll
;                     for (int i = 0; i < 16; ++i) k1[i] = (unsigned)__shfl_xor((int)k0[i], msk);
;                     merge16(k0, k1); }
	v_min_u32_e32 v94, v94, v96
	v_max_u32_e32 v96, v84, v93
	v_min_u32_e32 v84, v84, v93
	v_max_u32_e32 v93, v97, v106
	v_min_u32_e32 v97, v97, v106
	v_max_u32_e32 v106, v78, v85
	v_min_u32_e32 v78, v78, v85
	v_max_u32_e32 v85, v81, v90
	v_min_u32_e32 v81, v81, v90
	v_max_u32_e32 v90, v83, v79
	v_min_u32_e32 v79, v83, v79
	v_max_u32_e32 v83, v80, v82
	v_min_u32_e32 v80, v80, v82
	v_max_u32_e32 v99, v100, v103
	v_min_u32_e32 v100, v100, v103
	v_max_u32_e32 v103, v102, v104
	v_min_u32_e32 v102, v102, v104
	v_max_u32_e32 v104, v88, v101
	v_min_u32_e32 v88, v88, v101
	v_max_u32_e32 v101, v105, v115
	v_min_u32_e32 v105, v105, v115
	v_max_u32_e32 v115, v0, v89
	v_min_u32_e32 v0, v0, v89
	v_max_u32_e32 v89, v3, v98
	v_min_u32_e32 v3, v3, v98
	v_max_u32_e32 v98, v87, v1
	v_min_u32_e32 v1, v87, v1
	v_max_u32_e32 v87, v2, v86
	v_min_u32_e32 v2, v2, v86
	v_max_u32_e32 v82, v91, v96
	v_min_u32_e32 v91, v91, v96
	v_max_u32_e32 v96, v95, v93
	v_min_u32_e32 v93, v95, v93
	v_max_u32_e32 v95, v92, v84
	v_min_u32_e32 v84, v92, v84
	v_max_u32_e32 v92, v94, v97
	v_min_u32_e32 v94, v94, v97
	v_max_u32_e32 v97, v106, v90
	v_min_u32_e32 v90, v106, v90
	v_max_u32_e32 v106, v85, v83
	v_min_u32_e32 v83, v85, v83
	v_max_u32_e32 v85, v78, v79
	v_min_u32_e32 v78, v78, v79
	v_max_u32_e32 v79, v81, v80
	v_min_u32_e32 v80, v81, v80
	v_max_u32_e32 v86, v99, v104
	v_min_u32_e32 v99, v99, v104
	v_max_u32_e32 v104, v103, v101
	v_min_u32_e32 v101, v103, v101
	v_max_u32_e32 v103, v100, v88
	v_min_u32_e32 v88, v100, v88
	v_max_u32_e32 v100, v102, v105
	v_min_u32_e32 v102, v102, v105
	v_max_u32_e32 v105, v115, v98
	v_min_u32_e32 v98, v115, v98
	v_max_u32_e32 v115, v89, v87
	v_min_u32_e32 v87, v89, v87
	v_max_u32_e32 v89, v0, v1
	v_min_u32_e32 v0, v0, v1
	v_max_u32_e32 v1, v3, v2
	v_min_u32_e32 v2, v3, v2
	v_min_u32_e32 v81, v82, v96
	v_min_u32_e32 v107, v91, v93
	v_min_u32_e32 v108, v95, v92
	v_min_u32_e32 v109, v84, v94
	v_min_u32_e32 v110, v97, v106
	v_min_u32_e32 v111, v90, v83
	v_min_u32_e32 v112, v85, v79
	v_min_u32_e32 v114, v78, v80
	v_min_u32_e32 v3, v86, v104
	v_min_u32_e32 v116, v99, v101
	v_min_u32_e32 v117, v103, v100
	v_min_u32_e32 v118, v88, v102
	v_min_u32_e32 v119, v105, v115
	v_min_u32_e32 v120, v98, v87
	v_min_u32_e32 v121, v89, v1
	v_min_u32_e32 v122, v0, v2
	v_max3_u32 v82, v82, v96, v122
	v_max3_u32 v0, v81, v0, v2
	v_max3_u32 v2, v91, v93, v121
	v_max3_u32 v1, v107, v89, v1
	v_max3_u32 v81, v95, v92, v120
	v_max3_u32 v87, v108, v98, v87
	v_max3_u32 v84, v84, v94, v119
	v_max3_u32 v89, v109, v105, v115
	v_max3_u32 v91, v97, v106, v118
	v_max3_u32 v88, v110, v88, v102
	v_max3_u32 v83, v90, v83, v117
	v_max3_u32 v90, v111, v103, v100
	v_max3_u32 v79, v85, v79, v116
	v_max3_u32 v85, v112, v99, v101
	v_max3_u32 v3, v78, v80, v3
	v_max3_u32 v78, v114, v86, v104
	v_max_u32_e32 v80, v82, v91
	v_min_u32_e32 v82, v82, v91
	v_max_u32_e32 v86, v0, v88
	v_min_u32_e32 v0, v0, v88
	v_max_u32_e32 v88, v2, v83
	v_min_u32_e32 v2, v2, v83
	v_max_u32_e32 v83, v1, v90
	v_min_u32_e32 v1, v1, v90
	v_max_u32_e32 v90, v81, v79
	v_min_u32_e32 v79, v81, v79
	v_max_u32_e32 v81, v87, v85
	v_min_u32_e32 v85, v87, v85
	v_max_u32_e32 v87, v84, v3
	v_min_u32_e32 v3, v84, v3
	v_max_u32_e32 v84, v89, v78
	v_min_u32_e32 v78, v89, v78
	v_max_u32_e32 v89, v80, v90
	v_min_u32_e32 v80, v80, v90
	v_max_u32_e32 v90, v86, v81
	v_min_u32_e32 v81, v86, v81
	v_max_u32_e32 v86, v88, v87
	v_min_u32_e32 v87, v88, v87
	v_max_u32_e32 v88, v83, v84
	v_min_u32_e32 v83, v83, v84
	v_max_u32_e32 v84, v82, v79
	v_min_u32_e32 v79, v82, v79
	v_max_u32_e32 v82, v0, v85
	v_min_u32_e32 v0, v0, v85
	v_max_u32_e32 v85, v2, v3
	v_min_u32_e32 v2, v2, v3
	v_max_u32_e32 v3, v1, v78
	v_min_u32_e32 v1, v1, v78
	v_max_u32_e32 v78, v89, v86
	v_min_u32_e32 v86, v89, v86
	v_max_u32_e32 v89, v90, v88
	v_min_u32_e32 v88, v90, v88
	v_max_u32_e32 v90, v80, v87
	v_min_u32_e32 v80, v80, v87
	v_max_u32_e32 v87, v81, v83
	v_min_u32_e32 v81, v81, v83
	v_max_u32_e32 v83, v84, v85
	v_min_u32_e32 v84, v84, v85
	v_max_u32_e32 v85, v82, v3
	v_min_u32_e32 v3, v82, v3
	v_max_u32_e32 v82, v79, v2
	v_min_u32_e32 v2, v79, v2
	v_max_u32_e32 v79, v0, v1
	v_min_u32_e32 v0, v0, v1
	v_max_u32_e32 v1, v78, v89
	v_min_u32_e32 v78, v78, v89
	v_max_u32_e32 v89, v86, v88
	v_min_u32_e32 v86, v86, v88
	v_max_u32_e32 v88, v90, v87
	v_min_u32_e32 v87, v90, v87
	v_max_u32_e32 v90, v80, v81
	v_min_u32_e32 v80, v80, v81
	v_max_u32_e32 v81, v83, v85
	v_min_u32_e32 v83, v83, v85
	v_max_u32_e32 v85, v84, v3
	v_min_u32_e32 v3, v84, v3
	v_max_u32_e32 v84, v82, v79
	v_min_u32_e32 v79, v82, v79
	v_max_u32_e32 v82, v2, v0
	v_min_u32_e32 v0, v2, v0
	ds_bpermute_b32 v2, v27, v1
	ds_bpermute_b32 v91, v27, v78
	ds_bpermute_b32 v92, v27, v89
	ds_bpermute_b32 v93, v27, v86
	ds_bpermute_b32 v94, v27, v88
	ds_bpermute_b32 v95, v27, v87
	ds_bpermute_b32 v96, v27, v90
	ds_bpermute_b32 v97, v27, v80
	ds_bpermute_b32 v98, v27, v81
	ds_bpermute_b32 v99, v27, v83
	ds_bpermute_b32 v100, v27, v85
	ds_bpermute_b32 v101, v27, v0
	ds_bpermute_b32 v102, v27, v82
	ds_bpermute_b32 v103, v27, v79
	ds_bpermute_b32 v104, v27, v84
	ds_bpermute_b32 v105, v27, v3
	s_waitcnt lgkmcnt(4)
	v_max_u32_e32 v1, v1, v101
	s_waitcnt lgkmcnt(3)
	v_max_u32_e32 v78, v78, v102
	s_waitcnt lgkmcnt(2)
	v_max_u32_e32 v89, v89, v103
	s_waitcnt lgkmcnt(1)
	v_max_u32_e32 v86, v86, v104
	s_waitcnt lgkmcnt(0)
; #define CE_DESC(a, b) do { const unsigned _mx = (a) > (b) ? (a) : (b), _mn = (a) > (b) ? (b) : (a); (a) = _mx; (b) = _mn; } while (0)
; __device__ __forceinline__ void merge16(unsigned (&a)[16], const unsigned (&b)[16]) {
; #pragma unroll
;     for (int i = 0; i < 16; ++i) a[i] = a[i] > b[15 - i] ? a[i] : b[15 - i];
; #pragma unroll
;     for (int stride = 8; stride > 0; stride >>= 1)
; #pragma unroll
;         for (int i = 0; i < 16; ++i) { const int j = i ^ stride; if (j > i) CE_DESC(a[i], a[j]); }
; }
; __device__ __forceinline__ void peer_tile(const Args& A, LAS unsigned char* lds, int tile) {
;     ...
;                 { const bf16_t* sp = QRY + m * 2048 + hp * 128 + 32 * g;
;                   const u32x4 s0 = *(const u32x4*)sp, s1 = *(const u32x4*)(sp + 8), s2 = *(const u32x4*)(sp + 16), s3 = *(const u32x4*)(sp + 24);
;                   const unsigned sw[16] = {s0.x, s0.y, s0.z, s0.w, s1.x, s1.y, s1.z, s1.w, s2.x, s2.y, s2.z, s2.w, s3.x, s3.y, s3.z, s3.w};
;     ...
;                 sort16_desc(k0); sort16_desc(k1); merge16(k0, k1);
; #pragma unroll
;                 for (int msk = 16; msk <= 32; msk <<= 1) {
; #pragma unroll
;                     for (int i = 0; i < 16; ++i) k1[i] = (unsigned)__shfl_xor((int)k0[i], msk);
;                     merge16(k0, k1); }
	v_max_u32_e32 v88, v88, v105
	v_max_u32_e32 v87, v87, v100
	v_max_u32_e32 v90, v90, v99
	v_max_u32_e32 v80, v80, v98
	v_max_u32_e32 v81, v81, v97
	v_max_u32_e32 v83, v83, v96
	v_max_u32_e32 v85, v85, v95
	v_max_u32_e32 v3, v3, v94
	v_max_u32_e32 v84, v84, v93
	v_max_u32_e32 v79, v79, v92
	v_max_u32_e32 v82, v82, v91
	v_max_u32_e32 v0, v0, v2
	v_max_u32_e32 v2, v1, v81
	v_min_u32_e32 v1, v1, v81
	v_max_u32_e32 v81, v78, v83
	v_min_u32_e32 v78, v78, v83
	v_max_u32_e32 v83, v89, v85
	v_min_u32_e32 v85, v89, v85
	v_max_u32_e32 v89, v86, v3
	v_min_u32_e32 v3, v86, v3
	v_max_u32_e32 v86, v88, v84
	v_min_u32_e32 v84, v88, v84
	v_max_u32_e32 v88, v87, v79
	v_min_u32_e32 v79, v87, v79
	v_max_u32_e32 v87, v90, v82
	v_min_u32_e32 v82, v90, v82
	v_max_u32_e32 v90, v80, v0
	v_min_u32_e32 v0, v80, v0
	v_max_u32_e32 v80, v2, v86
	v_min_u32_e32 v2, v2, v86
	v_max_u32_e32 v86, v81, v88
	v_min_u32_e32 v81, v81, v88
	v_max_u32_e32 v88, v83, v87
	v_min_u32_e32 v83, v83, v87
	v_max_u32_e32 v87, v89, v90
	v_min_u32_e32 v89, v89, v90
	v_max_u32_e32 v90, v1, v84
	v_min_u32_e32 v1, v1, v84
	v_max_u32_e32 v84, v78, v79
	v_min_u32_e32 v78, v78, v79
	v_max_u32_e32 v79, v85, v82
	v_min_u32_e32 v82, v85, v82
	v_max_u32_e32 v85, v3, v0
	v_min_u32_e32 v0, v3, v0
	v_max_u32_e32 v3, v80, v88
	v_min_u32_e32 v80, v80, v88
	v_max_u32_e32 v88, v86, v87
	v_min_u32_e32 v86, v86, v87
	v_max_u32_e32 v87, v2, v83
	v_min_u32_e32 v2, v2, v83
	v_max_u32_e32 v83, v81, v89
	v_min_u32_e32 v81, v81, v89
	v_max_u32_e32 v89, v90, v79
	v_min_u32_e32 v79, v90, v79
	v_max_u32_e32 v90, v84, v85
	v_min_u32_e32 v84, v84, v85
	v_max_u32_e32 v85, v1, v82
	v_min_u32_e32 v1, v1, v82
	v_max_u32_e32 v82, v78, v0
	v_min_u32_e32 v0, v78, v0
	v_max_u32_e32 v78, v3, v88
	v_min_u32_e32 v3, v3, v88
	v_max_u32_e32 v88, v80, v86
	v_min_u32_e32 v80, v80, v86
	v_max_u32_e32 v86, v87, v83
	v_min_u32_e32 v83, v87, v83
	v_max_u32_e32 v87, v2, v81
	v_min_u32_e32 v2, v2, v81
	v_max_u32_e32 v81, v89, v90
	v_min_u32_e32 v89, v89, v90
	v_max_u32_e32 v90, v79, v84
	v_min_u32_e32 v79, v79, v84
	v_max_u32_e32 v84, v85, v82
	v_min_u32_e32 v82, v85, v82
	v_max_u32_e32 v85, v1, v0
	v_min_u32_e32 v0, v1, v0
	ds_bpermute_b32 v94, v29, v0
	ds_bpermute_b32 v1, v29, v78
	ds_bpermute_b32 v91, v29, v3
	ds_bpermute_b32 v92, v29, v88
	ds_bpermute_b32 v93, v29, v80
	s_waitcnt lgkmcnt(4)
	v_max_u32_e32 v78, v78, v94
	global_load_dwordx4 v[94:97], v[4:5], off offset:1040
	global_load_dwordx4 v[98:101], v[4:5], off offset:1024
	ds_bpermute_b32 v102, v29, v86
	ds_bpermute_b32 v103, v29, v83
	ds_bpermute_b32 v104, v29, v87
	ds_bpermute_b32 v105, v29, v2
	ds_bpermute_b32 v106, v29, v81
	ds_bpermute_b32 v107, v29, v89
	ds_bpermute_b32 v108, v29, v90
	ds_bpermute_b32 v109, v29, v79
	ds_bpermute_b32 v110, v29, v84
	ds_bpermute_b32 v111, v29, v85
	ds_bpermute_b32 v112, v29, v82
	s_waitcnt lgkmcnt(4)
	v_max_u32_e32 v83, v83, v108
	s_waitcnt lgkmcnt(3)
	v_max_u32_e32 v86, v86, v109
	s_waitcnt lgkmcnt(2)
	v_max_u32_e32 v80, v80, v110
	s_waitcnt lgkmcnt(1)
	v_max_u32_e32 v3, v3, v111
	s_waitcnt lgkmcnt(0)
	v_max_u32_e32 v88, v88, v112
	v_max_u32_e32 v87, v87, v107
	v_max_u32_e32 v2, v2, v106
	v_max_u32_e32 v81, v81, v105
	v_max_u32_e32 v89, v89, v104
	v_max_u32_e32 v90, v90, v103
	v_max_u32_e32 v79, v79, v102
	v_max_u32_e32 v84, v84, v93
	v_max_u32_e32 v82, v82, v92
	v_max_u32_e32 v85, v85, v91
	v_max_u32_e32 v0, v0, v1
	v_max_u32_e32 v1, v78, v81
	v_min_u32_e32 v78, v78, v81
	v_max_u32_e32 v81, v3, v89
	v_min_u32_e32 v3, v3, v89
	v_max_u32_e32 v89, v88, v90
	v_min_u32_e32 v88, v88, v90
	v_max_u32_e32 v90, v80, v79
	v_min_u32_e32 v79, v80, v79
	v_max_u32_e32 v80, v86, v84
	v_min_u32_e32 v84, v86, v84
	v_max_u32_e32 v86, v83, v82
	v_min_u32_e32 v82, v83, v82
	v_max_u32_e32 v83, v87, v85
	v_min_u32_e32 v85, v87, v85
	v_max_u32_e32 v87, v2, v0
	v_min_u32_e32 v0, v2, v0
	v_max_u32_e32 v2, v1, v80
	v_min_u32_e32 v1, v1, v80
	v_max_u32_e32 v80, v81, v86
	v_min_u32_e32 v81, v81, v86
	v_max_u32_e32 v86, v89, v83
	v_min_u32_e32 v83, v89, v83
	v_max_u32_e32 v89, v90, v87
	v_min_u32_e32 v87, v90, v87
	v_max_u32_e32 v90, v78, v84
	v_min_u32_e32 v78, v78, v84
	v_max_u32_e32 v84, v3, v82
	v_min_u32_e32 v3, v3, v82
	v_max_u32_e32 v82, v88, v85
	v_min_u32_e32 v85, v88, v85
	v_max_u32_e32 v88, v79, v0
	v_min_u32_e32 v0, v79, v0
	v_max_u32_e32 v79, v2, v86
	v_min_u32_e32 v2, v2, v86
	v_max_u32_e32 v86, v80, v89
	v_min_u32_e32 v80, v80, v89
	v_max_u32_e32 v102, v1, v83
	v_min_u32_e32 v1, v1, v83
	v_max_u32_e32 v83, v81, v87
	v_min_u32_e32 v81, v81, v87
	v_max_u32_e32 v103, v90, v82
	v_min_u32_e32 v82, v90, v82
	v_max_u32_e32 v104, v84, v88
	v_min_u32_e32 v105, v84, v88
	v_max_u32_e32 v106, v78, v85
	v_min_u32_e32 v78, v78, v85
	v_max_u32_e32 v107, v3, v0
	v_min_u32_e32 v0, v3, v0
	v_max_u32_e32 v93, v79, v86
	v_min_u32_e32 v92, v79, v86
	v_max_u32_e32 v91, v2, v80
	v_min_u32_e32 v90, v2, v80
	v_max_u32_e32 v89, v102, v83
	v_min_u32_e32 v88, v102, v83
	v_max_u32_e32 v87, v1, v81
	v_min_u32_e32 v86, v1, v81
	v_max_u32_e32 v85, v103, v104
	v_min_u32_e32 v84, v103, v104
	v_max_u32_e32 v83, v82, v105
	v_min_u32_e32 v82, v82, v105
	v_max_u32_e32 v79, v78, v0
	v_min_u32_e32 v78, v78, v0
	global_load_dwordx4 v[0:3], v[4:5], off offset:1072
	global_load_dwordx4 v[102:105], v[4:5], off offset:1056
	v_max_u32_e32 v81, v106, v107
	v_min_u32_e32 v80, v106, v107
	s_waitcnt vmcnt(2)
; __device__ __forceinline__ unsigned f2key(float f) { const unsigned u = __float_as_uint(f); return (u & 0x80000000u) ? ~u : (u | 0x80000000u); }
; __device__ __forceinline__ void peer_tile(const Args& A, LAS unsigned char* lds, int tile) {
;     ...
;                   for (int i = 0; i < 16; ++i) {
;                       const float lo = (float)__builtin_bit_cast(_Float16, (unsigned short)(sw[i] & 0xffffu)), hi = (float)__builtin_bit_cast(_Float16, (unsigned short)(sw[i] >> 16));
;                       const unsigned klo = (f2key(lo) & ~127u) | (unsigned)(127 - (32 * g + 2 * i)), khi = (f2key(hi) & ~127u) | (unsigned)(127 - (32 * g + 2 * i + 1));
;                       if (i < 8) { k0[2 * i] = klo; k0[2 * i + 1] = khi; } else { k1[2 * (i - 8)] = klo; k1[2 * (i - 8) + 1] = khi; } } }
;     ...
;                 for (int i = 0; i < 16; ++i) L2[p][i] = (g & 2) ? ((g & 1) ? LA[3][p][i] : LA[2][p][i]) : ((g & 1) ? LA[1][p][i] : LA[0][p][i]);
	v_cvt_f32_f16_sdwa v106, v98 dst_sel:DWORD dst_unused:UNUSED_PAD src0_sel:WORD_1
	v_cvt_f32_f16_e32 v98, v98
	v_cndmask_b32_e64 v34, v66, v34, s[0:1]
	v_cndmask_b32_e64 v33, v65, v33, s[0:1]
	v_not_b32_e32 v107, v106
	v_or_b32_e32 v108, 0x80000000, v106
	v_cmp_gt_i32_e32 vcc, 0, v106
	v_cndmask_b32_e64 v32, v64, v32, s[0:1]
	v_cndmask_b32_e64 v31, v63, v31, s[0:1]
	v_cndmask_b32_e32 v106, v108, v107, vcc
	v_not_b32_e32 v107, v98
	v_or_b32_e32 v108, 0x80000000, v98
	v_cmp_gt_i32_e32 vcc, 0, v98
	v_and_b32_e32 v106, 0xffffff80, v106
	v_sub_u32_e32 v106, v106, v15
	v_cndmask_b32_e32 v98, v108, v107, vcc
	v_cvt_f32_f16_sdwa v107, v99 dst_sel:DWORD dst_unused:UNUSED_PAD src0_sel:WORD_1
	v_cvt_f32_f16_e32 v99, v99
	v_and_b32_e32 v98, 0xffffff80, v98
	v_sub_u32_e32 v98, v98, v15
	v_not_b32_e32 v108, v107
	v_or_b32_e32 v109, 0x80000000, v107
	v_cmp_gt_i32_e32 vcc, 0, v107
	v_add_u32_e32 v106, 0x7e, v106
	v_add_u32_e32 v98, 0x7f, v98
	v_cndmask_b32_e32 v107, v109, v108, vcc
	v_not_b32_e32 v108, v99
	v_or_b32_e32 v109, 0x80000000, v99
	v_cmp_gt_i32_e32 vcc, 0, v99
	v_and_b32_e32 v107, 0xffffff80, v107
	v_sub_u32_e32 v107, v107, v14
	v_cndmask_b32_e32 v99, v109, v108, vcc
	v_cvt_f32_f16_sdwa v108, v100 dst_sel:DWORD dst_unused:UNUSED_PAD src0_sel:WORD_1
	v_cvt_f32_f16_e32 v100, v100
	v_and_b32_e32 v99, 0xffffff80, v99
	v_sub_u32_e32 v99, v99, v14
	v_not_b32_e32 v109, v108
	v_or_b32_e32 v110, 0x80000000, v108
	v_cmp_gt_i32_e32 vcc, 0, v108
	v_add_u32_e32 v107, 0x7e, v107
	v_add_u32_e32 v99, 0x7f, v99
	v_cndmask_b32_e32 v108, v110, v109, vcc
	v_not_b32_e32 v109, v100
	v_or_b32_e32 v110, 0x80000000, v100
	v_cmp_gt_i32_e32 vcc, 0, v100
	v_and_b32_e32 v108, 0xffffff80, v108
	v_sub_u32_e32 v108, v108, v12
	v_cndmask_b32_e32 v100, v110, v109, vcc
	v_cvt_f32_f16_sdwa v109, v101 dst_sel:DWORD dst_unused:UNUSED_PAD src0_sel:WORD_1
	v_cvt_f32_f16_e32 v101, v101
	v_and_b32_e32 v100, 0xffffff80, v100
	v_sub_u32_e32 v100, v100, v12
	v_not_b32_e32 v110, v109
	v_or_b32_e32 v111, 0x80000000, v109
	v_cmp_gt_i32_e32 vcc, 0, v109
	v_add_u32_e32 v108, 0x7e, v108
	v_add_u32_e32 v100, 0x7f, v100
	v_cndmask_b32_e32 v109, v111, v110, vcc
	v_not_b32_e32 v110, v101
	v_or_b32_e32 v111, 0x80000000, v101
	v_cmp_gt_i32_e32 vcc, 0, v101
	v_and_b32_e32 v109, 0xffffff80, v109
	v_sub_u32_e32 v109, v109, v10
	v_cndmask_b32_e32 v101, v111, v110, vcc
	v_cvt_f32_f16_sdwa v110, v94 dst_sel:DWORD dst_unused:UNUSED_PAD src0_sel:WORD_1
	v_cvt_f32_f16_e32 v94, v94
	v_and_b32_e32 v101, 0xffffff80, v101
	v_sub_u32_e32 v101, v101, v10
	v_not_b32_e32 v111, v110
	v_or_b32_e32 v112, 0x80000000, v110
	v_cmp_gt_i32_e32 vcc, 0, v110
	v_add_u32_e32 v109, 0x7e, v109
	v_add_u32_e32 v101, 0x7f, v101
	v_cndmask_b32_e32 v110, v112, v111, vcc
	v_not_b32_e32 v111, v94
	v_or_b32_e32 v112, 0x80000000, v94
	v_cmp_gt_i32_e32 vcc, 0, v94
	v_and_b32_e32 v110, 0xffffff80, v110
	v_sub_u32_e32 v110, v110, v8
	v_cndmask_b32_e32 v94, v112, v111, vcc
	v_cvt_f32_f16_sdwa v111, v95 dst_sel:DWORD dst_unused:UNUSED_PAD src0_sel:WORD_1
	v_cvt_f32_f16_e32 v95, v95
	v_and_b32_e32 v94, 0xffffff80, v94
	v_sub_u32_e32 v94, v94, v8
	v_not_b32_e32 v112, v111
	v_or_b32_e32 v114, 0x80000000, v111
	v_cmp_gt_i32_e32 vcc, 0, v111
	v_add_u32_e32 v110, 0x7e, v110
	v_add_u32_e32 v94, 0x7f, v94
	v_cndmask_b32_e32 v111, v114, v112, vcc
	v_not_b32_e32 v112, v95
	v_or_b32_e32 v114, 0x80000000, v95
	v_cmp_gt_i32_e32 vcc, 0, v95
	v_and_b32_e32 v111, 0xffffff80, v111
	v_sub_u32_e32 v111, v111, v16
	v_cndmask_b32_e32 v95, v114, v112, vcc
	v_cvt_f32_f16_sdwa v112, v96 dst_sel:DWORD dst_unused:UNUSED_PAD src0_sel:WORD_1
	v_cvt_f32_f16_e32 v96, v96
	v_and_b32_e32 v95, 0xffffff80, v95
	v_sub_u32_e32 v95, v95, v16
	v_not_b32_e32 v114, v112
	v_or_b32_e32 v115, 0x80000000, v112
	v_cmp_gt_i32_e32 vcc, 0, v112
	v_add_u32_e32 v111, 0x7e, v111
	v_add_u32_e32 v95, 0x7f, v95
	v_cndmask_b32_e32 v112, v115, v114, vcc
	v_not_b32_e32 v114, v96
	v_or_b32_e32 v115, 0x80000000, v96
	v_cmp_gt_i32_e32 vcc, 0, v96
	v_and_b32_e32 v112, 0xffffff80, v112
	v_sub_u32_e32 v112, v112, v17
	v_cndmask_b32_e32 v96, v115, v114, vcc
	v_cvt_f32_f16_sdwa v114, v97 dst_sel:DWORD dst_unused:UNUSED_PAD src0_sel:WORD_1
	v_cvt_f32_f16_e32 v97, v97
	v_and_b32_e32 v96, 0xffffff80, v96
	v_sub_u32_e32 v96, v96, v17
	v_not_b32_e32 v115, v114
	v_or_b32_e32 v116, 0x80000000, v114
	v_cmp_gt_i32_e32 vcc, 0, v114
	v_add_u32_e32 v112, 0x7e, v112
	v_add_u32_e32 v96, 0x7f, v96
	v_cndmask_b32_e32 v114, v116, v115, vcc
	v_not_b32_e32 v115, v97
	v_or_b32_e32 v116, 0x80000000, v97
	v_cmp_gt_i32_e32 vcc, 0, v97
	v_and_b32_e32 v114, 0xffffff80, v114
	v_sub_u32_e32 v114, v114, v18
	v_cndmask_b32_e32 v97, v116, v115, vcc
	s_waitcnt vmcnt(0)
; __device__ __forceinline__ unsigned f2key(float f) { const unsigned u = __float_as_uint(f); return (u & 0x80000000u) ? ~u : (u | 0x80000000u); }
; #define CE_DESC(a, b) do { const unsigned _mx = (a) > (b) ? (a) : (b), _mn = (a) > (b) ? (b) : (a); (a) = _mx; (b) = _mn; } while (0)
; __device__ __forceinline__ void sort16_desc(unsigned (&k)[16]) {
; #pragma unroll
;     for (int size = 2; size <= 16; size <<= 1)
; #pragma unroll
;         for (int stride = size >> 1; stride > 0; stride >>= 1)
; #pragma unroll
;             for (int i = 0; i < 16; ++i) { const int j = i ^ stride;
;                 if (j > i) { if ((i & size) == 0) CE_DESC(k[i], k[j]); else CE_DESC(k[j], k[i]); } }
; }
; __device__ __forceinline__ void peer_tile(const Args& A, LAS unsigned char* lds, int tile) {
;     ...
;                   for (int i = 0; i < 16; ++i) {
;                       const float lo = (float)__builtin_bit_cast(_Float16, (unsigned short)(sw[i] & 0xffffu)), hi = (float)__builtin_bit_cast(_Float16, (unsigned short)(sw[i] >> 16));
;                       const unsigned klo = (f2key(lo) & ~127u) | (unsigned)(127 - (32 * g + 2 * i)), khi = (f2key(hi) & ~127u) | (unsigned)(127 - (32 * g + 2 * i + 1));
;                       if (i < 8) { k0[2 * i] = klo; k0[2 * i + 1] = khi; } else { k1[2 * (i - 8)] = klo; k1[2 * (i - 8) + 1] = khi; } } }
	v_cvt_f32_f16_sdwa v115, v102 dst_sel:DWORD dst_unused:UNUSED_PAD src0_sel:WORD_1
	v_cvt_f32_f16_e32 v102, v102
	v_and_b32_e32 v97, 0xffffff80, v97
	v_sub_u32_e32 v97, v97, v18
	v_not_b32_e32 v116, v115
	v_or_b32_e32 v117, 0x80000000, v115
	v_cmp_gt_i32_e32 vcc, 0, v115
	v_add_u32_e32 v114, 0x7e, v114
	v_add_u32_e32 v97, 0x7f, v97
	v_cndmask_b32_e32 v115, v117, v116, vcc
	v_not_b32_e32 v116, v102
	v_or_b32_e32 v117, 0x80000000, v102
	v_cmp_gt_i32_e32 vcc, 0, v102
	v_and_b32_e32 v115, 0xffffff80, v115
	v_sub_u32_e32 v115, v115, v20
	v_cndmask_b32_e32 v102, v117, v116, vcc
	v_cvt_f32_f16_sdwa v116, v103 dst_sel:DWORD dst_unused:UNUSED_PAD src0_sel:WORD_1
	v_cvt_f32_f16_e32 v103, v103
	v_and_b32_e32 v102, 0xffffff80, v102
	v_sub_u32_e32 v102, v102, v20
	v_not_b32_e32 v117, v116
	v_or_b32_e32 v118, 0x80000000, v116
	v_cmp_gt_i32_e32 vcc, 0, v116
	v_add_u32_e32 v115, 0x7e, v115
	v_add_u32_e32 v102, 0x7f, v102
	v_cndmask_b32_e32 v116, v118, v117, vcc
	v_not_b32_e32 v117, v103
	v_or_b32_e32 v118, 0x80000000, v103
	v_cmp_gt_i32_e32 vcc, 0, v103
	v_and_b32_e32 v116, 0xffffff80, v116
	v_sub_u32_e32 v116, v116, v21
	v_cndmask_b32_e32 v103, v118, v117, vcc
	v_cvt_f32_f16_sdwa v117, v104 dst_sel:DWORD dst_unused:UNUSED_PAD src0_sel:WORD_1
	v_cvt_f32_f16_e32 v104, v104
	v_and_b32_e32 v103, 0xffffff80, v103
	v_sub_u32_e32 v103, v103, v21
	v_not_b32_e32 v118, v117
	v_or_b32_e32 v119, 0x80000000, v117
	v_cmp_gt_i32_e32 vcc, 0, v117
	v_add_u32_e32 v116, 0x7e, v116
	v_add_u32_e32 v103, 0x7f, v103
	v_cndmask_b32_e32 v117, v119, v118, vcc
	v_not_b32_e32 v118, v104
	v_or_b32_e32 v119, 0x80000000, v104
	v_cmp_gt_i32_e32 vcc, 0, v104
	v_and_b32_e32 v117, 0xffffff80, v117
	v_sub_u32_e32 v117, v117, v22
	v_cndmask_b32_e32 v104, v119, v118, vcc
	v_cvt_f32_f16_sdwa v118, v105 dst_sel:DWORD dst_unused:UNUSED_PAD src0_sel:WORD_1
	v_cvt_f32_f16_e32 v105, v105
	v_and_b32_e32 v104, 0xffffff80, v104
	v_sub_u32_e32 v104, v104, v22
	v_not_b32_e32 v119, v118
	v_or_b32_e32 v120, 0x80000000, v118
	v_cmp_gt_i32_e32 vcc, 0, v118
	v_add_u32_e32 v117, 0x7e, v117
	v_add_u32_e32 v104, 0x7f, v104
	v_cndmask_b32_e32 v118, v120, v119, vcc
	v_not_b32_e32 v119, v105
	v_or_b32_e32 v120, 0x80000000, v105
	v_cmp_gt_i32_e32 vcc, 0, v105
	v_and_b32_e32 v118, 0xffffff80, v118
	v_sub_u32_e32 v118, v118, v23
	v_cndmask_b32_e32 v105, v120, v119, vcc
	v_cvt_f32_f16_sdwa v119, v0 dst_sel:DWORD dst_unused:UNUSED_PAD src0_sel:WORD_1
	v_cvt_f32_f16_e32 v0, v0
	v_and_b32_e32 v105, 0xffffff80, v105
	v_sub_u32_e32 v105, v105, v23
	v_not_b32_e32 v120, v119
	v_or_b32_e32 v121, 0x80000000, v119
	v_cmp_gt_i32_e32 vcc, 0, v119
	v_add_u32_e32 v118, 0x7e, v118
	v_add_u32_e32 v105, 0x7f, v105
	v_cndmask_b32_e32 v119, v121, v120, vcc
	v_not_b32_e32 v120, v0
	v_or_b32_e32 v121, 0x80000000, v0
	v_cmp_gt_i32_e32 vcc, 0, v0
	v_and_b32_e32 v119, 0xffffff80, v119
	v_sub_u32_e32 v119, v119, v24
	v_cndmask_b32_e32 v0, v121, v120, vcc
	v_cvt_f32_f16_sdwa v120, v1 dst_sel:DWORD dst_unused:UNUSED_PAD src0_sel:WORD_1
	v_cvt_f32_f16_e32 v1, v1
	v_and_b32_e32 v0, 0xffffff80, v0
	v_sub_u32_e32 v0, v0, v24
	v_not_b32_e32 v121, v120
	v_or_b32_e32 v122, 0x80000000, v120
	v_cmp_gt_i32_e32 vcc, 0, v120
	v_add_u32_e32 v119, 0x7e, v119
	v_add_u32_e32 v0, 0x7f, v0
	v_cndmask_b32_e32 v120, v122, v121, vcc
	v_not_b32_e32 v121, v1
	v_or_b32_e32 v122, 0x80000000, v1
	v_cmp_gt_i32_e32 vcc, 0, v1
	v_and_b32_e32 v120, 0xffffff80, v120
	v_sub_u32_e32 v120, v120, v25
	v_cndmask_b32_e32 v1, v122, v121, vcc
	v_cvt_f32_f16_sdwa v121, v2 dst_sel:DWORD dst_unused:UNUSED_PAD src0_sel:WORD_1
	v_cvt_f32_f16_e32 v2, v2
	v_and_b32_e32 v1, 0xffffff80, v1
	v_sub_u32_e32 v1, v1, v25
	v_not_b32_e32 v122, v121
	v_or_b32_e32 v123, 0x80000000, v121
	v_cmp_gt_i32_e32 vcc, 0, v121
	v_add_u32_e32 v120, 0x7e, v120
	v_add_u32_e32 v1, 0x7f, v1
	v_cndmask_b32_e32 v121, v123, v122, vcc
	v_not_b32_e32 v122, v2
	v_or_b32_e32 v123, 0x80000000, v2
	v_cmp_gt_i32_e32 vcc, 0, v2
	v_and_b32_e32 v121, 0xffffff80, v121
	v_sub_u32_e32 v121, v121, v26
	v_cndmask_b32_e32 v2, v123, v122, vcc
	v_cvt_f32_f16_sdwa v122, v3 dst_sel:DWORD dst_unused:UNUSED_PAD src0_sel:WORD_1
	v_cvt_f32_f16_e32 v3, v3
	v_and_b32_e32 v2, 0xffffff80, v2
	v_sub_u32_e32 v2, v2, v26
	v_not_b32_e32 v123, v122
	v_or_b32_e32 v124, 0x80000000, v122
	v_cmp_gt_i32_e32 vcc, 0, v122
	v_add_u32_e32 v121, 0x7e, v121
	v_add_u32_e32 v2, 0x7f, v2
	v_cndmask_b32_e32 v122, v124, v123, vcc
	v_not_b32_e32 v123, v3
	v_or_b32_e32 v124, 0x80000000, v3
	v_cmp_gt_i32_e32 vcc, 0, v3
	v_and_b32_e32 v122, 0xffffff80, v122
	v_sub_u32_e32 v122, v122, v28
	v_cndmask_b32_e32 v3, v124, v123, vcc
	v_and_b32_e32 v3, 0xffffff80, v3
	v_sub_u32_e32 v3, v3, v28
	v_add_u32_e32 v122, 0x7e, v122
	v_add_u32_e32 v3, 0x7f, v3
	v_max_u32_e32 v123, v98, v106
	v_min_u32_e32 v98, v98, v106
	v_max_u32_e32 v106, v107, v99
	v_min_u32_e32 v99, v107, v99
	v_max_u32_e32 v107, v100, v108
	v_min_u32_e32 v100, v100, v108
	v_max_u32_e32 v108, v109, v101
	v_min_u32_e32 v101, v109, v101
	v_max_u32_e32 v109, v94, v110
	v_min_u32_e32 v94, v94, v110
	v_max_u32_e32 v110, v111, v95
	v_min_u32_e32 v95, v111, v95
	v_max_u32_e32 v111, v96, v112
	v_min_u32_e32 v96, v96, v112
	v_max_u32_e32 v112, v114, v97
	v_min_u32_e32 v97, v114, v97
	v_max_u32_e32 v131, v102, v115
	v_min_u32_e32 v102, v102, v115
	v_max_u32_e32 v115, v116, v103
	v_min_u32_e32 v103, v116, v103
	v_max_u32_e32 v116, v104, v117
	v_min_u32_e32 v104, v104, v117
	v_max_u32_e32 v117, v118, v105
	v_min_u32_e32 v105, v118, v105
	v_max_u32_e32 v118, v0, v119
	v_min_u32_e32 v0, v0, v119
	v_max_u32_e32 v119, v120, v1
	v_min_u32_e32 v1, v120, v1
	v_max_u32_e32 v120, v2, v121
	v_min_u32_e32 v2, v2, v121
; #define CE_DESC(a, b) do { const unsigned _mx = (a) > (b) ? (a) : (b), _mn = (a) > (b) ? (b) : (a); (a) = _mx; (b) = _mn; } while (0)
; __device__ __forceinline__ void sort16_desc(unsigned (&k)[16]) {
; #pragma unroll
;     for (int size = 2; size <= 16; size <<= 1)
; #pragma unroll
;         for (int stride = size >> 1; stride > 0; stride >>= 1)
; #pragma unroll
;             for (int i = 0; i < 16; ++i) { const int j = i ^ stride;
;                 if (j > i) { if ((i & size) == 0) CE_DESC(k[i], k[j]); else CE_DESC(k[j], k[i]); } }
; }
	v_max_u32_e32 v121, v122, v3
	v_min_u32_e32 v3, v122, v3
	v_max_u32_e32 v114, v123, v99
	v_min_u32_e32 v99, v123, v99
	v_max_u32_e32 v123, v98, v106
	v_min_u32_e32 v98, v98, v106
	v_max_u32_e32 v106, v101, v107
	v_min_u32_e32 v101, v101, v107
	v_max_u32_e32 v107, v108, v100
	v_min_u32_e32 v100, v108, v100
	v_max_u32_e32 v108, v109, v95
	v_min_u32_e32 v95, v109, v95
	v_max_u32_e32 v109, v94, v110
	v_min_u32_e32 v94, v94, v110
	v_max_u32_e32 v110, v97, v111
	v_min_u32_e32 v97, v97, v111
	v_max_u32_e32 v111, v112, v96
	v_min_u32_e32 v96, v112, v96
	v_max_u32_e32 v122, v131, v103
	v_min_u32_e32 v103, v131, v103
	v_max_u32_e32 v131, v102, v115
	v_min_u32_e32 v102, v102, v115
	v_max_u32_e32 v115, v105, v116
	v_min_u32_e32 v105, v105, v116
	v_max_u32_e32 v116, v117, v104
	v_min_u32_e32 v104, v117, v104
	v_max_u32_e32 v117, v118, v1
	v_min_u32_e32 v1, v118, v1
	v_max_u32_e32 v118, v0, v119
	v_min_u32_e32 v0, v0, v119
	v_max_u32_e32 v119, v3, v120
	v_min_u32_e32 v3, v3, v120
	v_max_u32_e32 v120, v121, v2
	v_min_u32_e32 v2, v121, v2
	v_max_u32_e32 v112, v114, v123
	v_min_u32_e32 v114, v114, v123
	v_max_u32_e32 v123, v99, v98
	v_min_u32_e32 v98, v99, v98
	v_max_u32_e32 v99, v100, v101
	v_min_u32_e32 v100, v100, v101
	v_max_u32_e32 v101, v107, v106
	v_min_u32_e32 v106, v107, v106
	v_max_u32_e32 v107, v108, v109
	v_min_u32_e32 v108, v108, v109
	v_max_u32_e32 v109, v95, v94
	v_min_u32_e32 v94, v95, v94
	v_max_u32_e32 v95, v96, v97
	v_min_u32_e32 v96, v96, v97
	v_max_u32_e32 v97, v111, v110
	v_min_u32_e32 v110, v111, v110
	v_max_u32_e32 v121, v122, v131
	v_min_u32_e32 v122, v122, v131
	v_max_u32_e32 v131, v103, v102
	v_min_u32_e32 v102, v103, v102
	v_max_u32_e32 v103, v104, v105
	v_min_u32_e32 v104, v104, v105
	v_max_u32_e32 v105, v116, v115
	v_min_u32_e32 v115, v116, v115
	v_max_u32_e32 v116, v117, v118
	v_min_u32_e32 v117, v117, v118
	v_max_u32_e32 v118, v1, v0
	v_min_u32_e32 v0, v1, v0
	v_max_u32_e32 v1, v2, v3
	v_min_u32_e32 v2, v2, v3
	v_max_u32_e32 v3, v120, v119
	v_min_u32_e32 v119, v120, v119
	v_max_u32_e32 v111, v112, v100
	v_min_u32_e32 v100, v112, v100
	v_max_u32_e32 v112, v114, v99
	v_min_u32_e32 v99, v114, v99
	v_max_u32_e32 v114, v123, v106
	v_min_u32_e32 v106, v123, v106
	v_max_u32_e32 v123, v98, v101
	v_min_u32_e32 v98, v98, v101
	v_max_u32_e32 v101, v96, v107
	v_min_u32_e32 v96, v96, v107
	v_max_u32_e32 v107, v95, v108
	v_min_u32_e32 v95, v95, v108
	v_max_u32_e32 v108, v110, v109
	v_min_u32_e32 v109, v110, v109
	v_max_u32_e32 v110, v97, v94
	v_min_u32_e32 v94, v97, v94
	v_max_u32_e32 v120, v121, v104
	v_min_u32_e32 v104, v121, v104
	v_max_u32_e32 v121, v122, v103
	v_min_u32_e32 v103, v122, v103
	v_max_u32_e32 v122, v131, v115
	v_min_u32_e32 v115, v131, v115
	v_max_u32_e32 v131, v102, v105
	v_min_u32_e32 v102, v102, v105
	v_max_u32_e32 v105, v2, v116
	v_min_u32_e32 v2, v2, v116
	v_max_u32_e32 v116, v1, v117
	v_min_u32_e32 v1, v1, v117
	v_max_u32_e32 v117, v119, v118
	v_min_u32_e32 v118, v119, v118
	v_max_u32_e32 v119, v3, v0
	v_min_u32_e32 v0, v3, v0
	v_max_u32_e32 v97, v111, v114
	v_min_u32_e32 v111, v111, v114
	v_max_u32_e32 v114, v112, v123
	v_min_u32_e32 v112, v112, v123
	v_max_u32_e32 v123, v100, v106
	v_min_u32_e32 v100, v100, v106
	v_max_u32_e32 v106, v99, v98
	v_min_u32_e32 v98, v99, v98
	v_max_u32_e32 v99, v109, v96
	v_min_u32_e32 v96, v109, v96
	v_max_u32_e32 v109, v94, v95
	v_min_u32_e32 v94, v94, v95
	v_max_u32_e32 v95, v108, v101
	v_min_u32_e32 v101, v108, v101
	v_max_u32_e32 v108, v110, v107
	v_min_u32_e32 v107, v110, v107
	v_max_u32_e32 v3, v120, v122
	v_min_u32_e32 v120, v120, v122
	v_max_u32_e32 v122, v121, v131
	v_min_u32_e32 v121, v121, v131
	v_max_u32_e32 v131, v104, v115
	v_min_u32_e32 v104, v104, v115
	v_max_u32_e32 v115, v103, v102
	v_min_u32_e32 v102, v103, v102
	v_max_u32_e32 v103, v118, v2
	v_min_u32_e32 v2, v118, v2
	v_max_u32_e32 v118, v0, v1
	v_min_u32_e32 v0, v0, v1
	v_max_u32_e32 v1, v117, v105
	v_min_u32_e32 v105, v117, v105
	v_max_u32_e32 v117, v119, v116
	v_min_u32_e32 v116, v119, v116
	v_max_u32_e32 v110, v97, v114
	v_min_u32_e32 v97, v97, v114
	v_max_u32_e32 v114, v111, v112
	v_min_u32_e32 v111, v111, v112
	v_max_u32_e32 v112, v123, v106
	v_min_u32_e32 v106, v123, v106
	v_max_u32_e32 v123, v100, v98
	v_min_u32_e32 v98, v100, v98
	v_max_u32_e32 v100, v94, v96
	v_min_u32_e32 v94, v94, v96
	v_max_u32_e32 v96, v109, v99
	v_min_u32_e32 v99, v109, v99
	v_max_u32_e32 v109, v107, v101
	v_min_u32_e32 v101, v107, v101
	v_max_u32_e32 v107, v108, v95
	v_min_u32_e32 v95, v108, v95
	v_max_u32_e32 v119, v3, v122
	v_min_u32_e32 v3, v3, v122
	v_max_u32_e32 v122, v120, v121
	v_min_u32_e32 v120, v120, v121
	v_max_u32_e32 v121, v131, v115
	v_min_u32_e32 v115, v131, v115
	v_max_u32_e32 v131, v104, v102
	v_min_u32_e32 v102, v104, v102
	v_max_u32_e32 v104, v0, v2
	v_min_u32_e32 v0, v0, v2
	v_max_u32_e32 v2, v118, v103
	v_min_u32_e32 v103, v118, v103
	v_max_u32_e32 v118, v116, v105
	v_min_u32_e32 v105, v116, v105
	v_max_u32_e32 v116, v117, v1
	v_min_u32_e32 v1, v117, v1
	v_max_u32_e32 v108, v110, v94
	v_min_u32_e32 v94, v110, v94
	v_max_u32_e32 v110, v97, v100
	v_min_u32_e32 v97, v97, v100
	v_max_u32_e32 v100, v114, v99
	v_min_u32_e32 v99, v114, v99
	v_max_u32_e32 v114, v111, v96
	v_min_u32_e32 v96, v111, v96
	v_max_u32_e32 v111, v112, v101
	v_min_u32_e32 v101, v112, v101
	v_max_u32_e32 v112, v106, v109
	v_min_u32_e32 v106, v106, v109
	v_max_u32_e32 v109, v123, v95
	v_min_u32_e32 v95, v123, v95
	v_max_u32_e32 v123, v98, v107
	v_min_u32_e32 v98, v98, v107
	v_max_u32_e32 v117, v119, v0
	v_min_u32_e32 v0, v119, v0
	v_max_u32_e32 v119, v3, v104
	v_min_u32_e32 v3, v3, v104
	v_max_u32_e32 v104, v122, v103
	v_min_u32_e32 v103, v122, v103
; #define CE_DESC(a, b) do { const unsigned _mx = (a) > (b) ? (a) : (b), _mn = (a) > (b) ? (b) : (a); (a) = _mx; (b) = _mn; } while (0)
; __device__ __forceinline__ void sort16_desc(unsigned (&k)[16]) {
; #pragma unroll
;     for (int size = 2; size <= 16; size <<= 1)
; #pragma unroll
;         for (int stride = size >> 1; stride > 0; stride >>= 1)
; #pragma unroll
;             for (int i = 0; i < 16; ++i) { const int j = i ^ stride;
;                 if (j > i) { if ((i & size) == 0) CE_DESC(k[i], k[j]); else CE_DESC(k[j], k[i]); } }
; }
; __device__ __forceinline__ void merge16(unsigned (&a)[16], const unsigned (&b)[16]) {
; #pragma unroll
;     for (int i = 0; i < 16; ++i) a[i] = a[i] > b[15 - i] ? a[i] : b[15 - i];
; #pragma unroll
;     for (int stride = 8; stride > 0; stride >>= 1)
; #pragma unroll
;         for (int i = 0; i < 16; ++i) { const int j = i ^ stride; if (j > i) CE_DESC(a[i], a[j]); }
; }
; __device__ __forceinline__ void peer_tile(const Args& A, LAS unsigned char* lds, int tile) {
;     ...
;                 sort16_desc(k0); sort16_desc(k1); merge16(k0, k1);
; #pragma unroll
;                 for (int msk = 16; msk <= 32; msk <<= 1) {
; #pragma unroll
;                     for (int i = 0; i < 16; ++i) k1[i] = (unsigned)__shfl_xor((int)k0[i], msk);
;                     merge16(k0, k1); }
	v_max_u32_e32 v122, v120, v2
	v_min_u32_e32 v2, v120, v2
	v_max_u32_e32 v120, v121, v105
	v_min_u32_e32 v105, v121, v105
	v_max_u32_e32 v121, v115, v118
	v_min_u32_e32 v115, v115, v118
	v_max_u32_e32 v118, v131, v1
	v_min_u32_e32 v1, v131, v1
	v_max_u32_e32 v131, v102, v116
	v_min_u32_e32 v102, v102, v116
	v_max_u32_e32 v107, v108, v111
	v_min_u32_e32 v108, v108, v111
	v_max_u32_e32 v111, v110, v112
	v_min_u32_e32 v110, v110, v112
	v_max_u32_e32 v112, v100, v109
	v_min_u32_e32 v100, v100, v109
	v_max_u32_e32 v109, v114, v123
	v_min_u32_e32 v114, v114, v123
	v_max_u32_e32 v123, v94, v101
	v_min_u32_e32 v94, v94, v101
	v_max_u32_e32 v101, v97, v106
	v_min_u32_e32 v97, v97, v106
	v_max_u32_e32 v106, v99, v95
	v_min_u32_e32 v95, v99, v95
	v_max_u32_e32 v99, v96, v98
	v_min_u32_e32 v96, v96, v98
	v_max_u32_e32 v116, v117, v120
	v_min_u32_e32 v117, v117, v120
	v_max_u32_e32 v120, v119, v121
	v_min_u32_e32 v119, v119, v121
	v_max_u32_e32 v121, v104, v118
	v_min_u32_e32 v104, v104, v118
	v_max_u32_e32 v118, v122, v131
	v_min_u32_e32 v122, v122, v131
	v_max_u32_e32 v131, v0, v105
	v_min_u32_e32 v0, v0, v105
	v_max_u32_e32 v105, v3, v115
	v_min_u32_e32 v3, v3, v115
	v_max_u32_e32 v115, v103, v1
	v_min_u32_e32 v1, v103, v1
	v_max_u32_e32 v103, v2, v102
	v_min_u32_e32 v2, v2, v102
	v_max_u32_e32 v98, v107, v112
	v_min_u32_e32 v107, v107, v112
	v_max_u32_e32 v112, v111, v109
	v_min_u32_e32 v109, v111, v109
	v_max_u32_e32 v111, v108, v100
	v_min_u32_e32 v100, v108, v100
	v_max_u32_e32 v108, v110, v114
	v_min_u32_e32 v110, v110, v114
	v_max_u32_e32 v114, v123, v106
	v_min_u32_e32 v106, v123, v106
	v_max_u32_e32 v123, v101, v99
	v_min_u32_e32 v99, v101, v99
	v_max_u32_e32 v101, v94, v95
	v_min_u32_e32 v94, v94, v95
	v_max_u32_e32 v95, v97, v96
	v_min_u32_e32 v96, v97, v96
	v_max_u32_e32 v102, v116, v121
	v_min_u32_e32 v116, v116, v121
	v_max_u32_e32 v121, v120, v118
	v_min_u32_e32 v118, v120, v118
	v_max_u32_e32 v120, v117, v104
	v_min_u32_e32 v104, v117, v104
	v_max_u32_e32 v117, v119, v122
	v_min_u32_e32 v119, v119, v122
	v_max_u32_e32 v122, v131, v115
	v_min_u32_e32 v115, v131, v115
	v_max_u32_e32 v131, v105, v103
	v_min_u32_e32 v103, v105, v103
	v_max_u32_e32 v105, v0, v1
	v_min_u32_e32 v0, v0, v1
	v_max_u32_e32 v1, v3, v2
	v_min_u32_e32 v2, v3, v2
	v_min_u32_e32 v97, v98, v112
	v_min_u32_e32 v124, v107, v109
	v_min_u32_e32 v125, v111, v108
	v_min_u32_e32 v126, v100, v110
	v_min_u32_e32 v127, v114, v123
	v_min_u32_e32 v128, v106, v99
	v_min_u32_e32 v129, v101, v95
	v_min_u32_e32 v130, v94, v96
	v_min_u32_e32 v3, v102, v121
	v_min_u32_e32 v132, v116, v118
	v_min_u32_e32 v133, v120, v117
	v_min_u32_e32 v134, v104, v119
	v_min_u32_e32 v135, v122, v131
	v_min_u32_e32 v136, v115, v103
	v_min_u32_e32 v137, v105, v1
	v_min_u32_e32 v138, v0, v2
	v_max3_u32 v98, v98, v112, v138
	v_max3_u32 v0, v97, v0, v2
	v_max3_u32 v2, v107, v109, v137
	v_max3_u32 v1, v124, v105, v1
	v_max3_u32 v97, v111, v108, v136
	v_max3_u32 v103, v125, v115, v103
	v_max3_u32 v100, v100, v110, v135
	v_max3_u32 v105, v126, v122, v131
	v_max3_u32 v107, v114, v123, v134
	v_max3_u32 v104, v127, v104, v119
	v_max3_u32 v99, v106, v99, v133
	v_max3_u32 v106, v128, v120, v117
	v_max3_u32 v95, v101, v95, v132
	v_max3_u32 v101, v129, v116, v118
	v_max3_u32 v3, v94, v96, v3
	v_max3_u32 v94, v130, v102, v121
	v_max_u32_e32 v96, v98, v107
	v_min_u32_e32 v98, v98, v107
	v_max_u32_e32 v102, v0, v104
	v_min_u32_e32 v0, v0, v104
	v_max_u32_e32 v104, v2, v99
	v_min_u32_e32 v2, v2, v99
	v_max_u32_e32 v99, v1, v106
	v_min_u32_e32 v1, v1, v106
	v_max_u32_e32 v106, v97, v95
	v_min_u32_e32 v95, v97, v95
	v_max_u32_e32 v97, v103, v101
	v_min_u32_e32 v101, v103, v101
	v_max_u32_e32 v103, v100, v3
	v_min_u32_e32 v3, v100, v3
	v_max_u32_e32 v100, v105, v94
	v_min_u32_e32 v94, v105, v94
	v_max_u32_e32 v105, v96, v106
	v_min_u32_e32 v96, v96, v106
	v_max_u32_e32 v106, v102, v97
	v_min_u32_e32 v97, v102, v97
	v_max_u32_e32 v102, v104, v103
	v_min_u32_e32 v103, v104, v103
	v_max_u32_e32 v104, v99, v100
	v_min_u32_e32 v99, v99, v100
	v_max_u32_e32 v100, v98, v95
	v_min_u32_e32 v95, v98, v95
	v_max_u32_e32 v98, v0, v101
	v_min_u32_e32 v0, v0, v101
	v_max_u32_e32 v101, v2, v3
	v_min_u32_e32 v2, v2, v3
	v_max_u32_e32 v3, v1, v94
	v_min_u32_e32 v1, v1, v94
	v_max_u32_e32 v94, v105, v102
	v_min_u32_e32 v102, v105, v102
	v_max_u32_e32 v105, v106, v104
	v_min_u32_e32 v104, v106, v104
	v_max_u32_e32 v106, v96, v103
	v_min_u32_e32 v96, v96, v103
	v_max_u32_e32 v103, v97, v99
	v_min_u32_e32 v97, v97, v99
	v_max_u32_e32 v99, v100, v101
	v_min_u32_e32 v100, v100, v101
	v_max_u32_e32 v101, v98, v3
	v_min_u32_e32 v3, v98, v3
	v_max_u32_e32 v98, v95, v2
	v_min_u32_e32 v2, v95, v2
	v_max_u32_e32 v95, v0, v1
	v_min_u32_e32 v0, v0, v1
	v_max_u32_e32 v1, v94, v105
	v_min_u32_e32 v94, v94, v105
	v_max_u32_e32 v105, v102, v104
	v_min_u32_e32 v102, v102, v104
	v_max_u32_e32 v104, v106, v103
	v_min_u32_e32 v103, v106, v103
	v_max_u32_e32 v106, v96, v97
	v_min_u32_e32 v96, v96, v97
	v_max_u32_e32 v97, v99, v101
	v_min_u32_e32 v99, v99, v101
	v_max_u32_e32 v101, v100, v3
	v_min_u32_e32 v3, v100, v3
	v_max_u32_e32 v100, v98, v95
	v_min_u32_e32 v95, v98, v95
	v_max_u32_e32 v98, v2, v0
	v_min_u32_e32 v0, v2, v0
	ds_bpermute_b32 v2, v27, v1
	ds_bpermute_b32 v107, v27, v94
	ds_bpermute_b32 v108, v27, v105
	ds_bpermute_b32 v109, v27, v102
	ds_bpermute_b32 v110, v27, v104
	ds_bpermute_b32 v111, v27, v103
	ds_bpermute_b32 v112, v27, v106
	ds_bpermute_b32 v114, v27, v96
	ds_bpermute_b32 v115, v27, v97
	ds_bpermute_b32 v116, v27, v99
	ds_bpermute_b32 v117, v27, v101
	ds_bpermute_b32 v118, v27, v0
	ds_bpermute_b32 v119, v27, v98
	ds_bpermute_b32 v120, v27, v95
	ds_bpermute_b32 v121, v27, v100
	ds_bpermute_b32 v122, v27, v3
	s_waitcnt lgkmcnt(4)
; #define CE_DESC(a, b) do { const unsigned _mx = (a) > (b) ? (a) : (b), _mn = (a) > (b) ? (b) : (a); (a) = _mx; (b) = _mn; } while (0)
; __device__ __forceinline__ void merge16(unsigned (&a)[16], const unsigned (&b)[16]) {
; #pragma unroll
;     for (int i = 0; i < 16; ++i) a[i] = a[i] > b[15 - i] ? a[i] : b[15 - i];
; #pragma unroll
;     for (int stride = 8; stride > 0; stride >>= 1)
; #pragma unroll
;         for (int i = 0; i < 16; ++i) { const int j = i ^ stride; if (j > i) CE_DESC(a[i], a[j]); }
; }
; __device__ __forceinline__ void peer_tile(const Args& A, LAS unsigned char* lds, int tile) {
;     ...
;                 { const bf16_t* sp = QRY + m * 2048 + hp * 128 + 32 * g;
;                   const u32x4 s0 = *(const u32x4*)sp, s1 = *(const u32x4*)(sp + 8), s2 = *(const u32x4*)(sp + 16), s3 = *(const u32x4*)(sp + 24);
;                   const unsigned sw[16] = {s0.x, s0.y, s0.z, s0.w, s1.x, s1.y, s1.z, s1.w, s2.x, s2.y, s2.z, s2.w, s3.x, s3.y, s3.z, s3.w};
;     ...
;                 sort16_desc(k0); sort16_desc(k1); merge16(k0, k1);
; #pragma unroll
;                 for (int msk = 16; msk <= 32; msk <<= 1) {
; #pragma unroll
;                     for (int i = 0; i < 16; ++i) k1[i] = (unsigned)__shfl_xor((int)k0[i], msk);
;                     merge16(k0, k1); }
	v_max_u32_e32 v1, v1, v118
	s_waitcnt lgkmcnt(3)
	v_max_u32_e32 v94, v94, v119
	s_waitcnt lgkmcnt(2)
	v_max_u32_e32 v105, v105, v120
	s_waitcnt lgkmcnt(1)
	v_max_u32_e32 v102, v102, v121
	s_waitcnt lgkmcnt(0)
	v_max_u32_e32 v104, v104, v122
	v_max_u32_e32 v103, v103, v117
	v_max_u32_e32 v106, v106, v116
	v_max_u32_e32 v96, v96, v115
	v_max_u32_e32 v97, v97, v114
	v_max_u32_e32 v99, v99, v112
	v_max_u32_e32 v101, v101, v111
	v_max_u32_e32 v3, v3, v110
	v_max_u32_e32 v100, v100, v109
	v_max_u32_e32 v95, v95, v108
	v_max_u32_e32 v98, v98, v107
	v_max_u32_e32 v0, v0, v2
	v_max_u32_e32 v2, v1, v97
	v_min_u32_e32 v1, v1, v97
	v_max_u32_e32 v97, v94, v99
	v_min_u32_e32 v94, v94, v99
	v_max_u32_e32 v99, v105, v101
	v_min_u32_e32 v101, v105, v101
	v_max_u32_e32 v105, v102, v3
	v_min_u32_e32 v3, v102, v3
	v_max_u32_e32 v102, v104, v100
	v_min_u32_e32 v100, v104, v100
	v_max_u32_e32 v104, v103, v95
	v_min_u32_e32 v95, v103, v95
	v_max_u32_e32 v103, v106, v98
	v_min_u32_e32 v98, v106, v98
	v_max_u32_e32 v106, v96, v0
	v_min_u32_e32 v0, v96, v0
	v_max_u32_e32 v96, v2, v102
	v_min_u32_e32 v2, v2, v102
	v_max_u32_e32 v102, v97, v104
	v_min_u32_e32 v97, v97, v104
	v_max_u32_e32 v104, v99, v103
	v_min_u32_e32 v99, v99, v103
	v_max_u32_e32 v103, v105, v106
	v_min_u32_e32 v105, v105, v106
	v_max_u32_e32 v106, v1, v100
	v_min_u32_e32 v1, v1, v100
	v_max_u32_e32 v100, v94, v95
	v_min_u32_e32 v94, v94, v95
	v_max_u32_e32 v95, v101, v98
	v_min_u32_e32 v98, v101, v98
	v_max_u32_e32 v101, v3, v0
	v_min_u32_e32 v0, v3, v0
	v_max_u32_e32 v3, v96, v104
	v_min_u32_e32 v96, v96, v104
	v_max_u32_e32 v104, v102, v103
	v_min_u32_e32 v102, v102, v103
	v_max_u32_e32 v103, v2, v99
	v_min_u32_e32 v2, v2, v99
	v_max_u32_e32 v99, v97, v105
	v_min_u32_e32 v97, v97, v105
	v_max_u32_e32 v105, v106, v95
	v_min_u32_e32 v95, v106, v95
	v_max_u32_e32 v106, v100, v101
	v_min_u32_e32 v100, v100, v101
	v_max_u32_e32 v101, v1, v98
	v_min_u32_e32 v1, v1, v98
	v_max_u32_e32 v98, v94, v0
	v_min_u32_e32 v0, v94, v0
	v_max_u32_e32 v94, v3, v104
	v_min_u32_e32 v3, v3, v104
	v_max_u32_e32 v104, v96, v102
	v_min_u32_e32 v96, v96, v102
	v_max_u32_e32 v102, v103, v99
	v_min_u32_e32 v99, v103, v99
	v_max_u32_e32 v103, v2, v97
	v_min_u32_e32 v2, v2, v97
	v_max_u32_e32 v97, v105, v106
	v_min_u32_e32 v105, v105, v106
	v_max_u32_e32 v106, v95, v100
	v_min_u32_e32 v95, v95, v100
	v_max_u32_e32 v100, v101, v98
	v_min_u32_e32 v98, v101, v98
	v_max_u32_e32 v101, v1, v0
	v_min_u32_e32 v0, v1, v0
	ds_bpermute_b32 v114, v29, v0
	ds_bpermute_b32 v1, v29, v94
	ds_bpermute_b32 v107, v29, v3
	ds_bpermute_b32 v108, v29, v104
	ds_bpermute_b32 v109, v29, v96
	s_waitcnt lgkmcnt(4)
	v_max_u32_e32 v94, v94, v114
	global_load_dwordx4 v[114:117], v[4:5], off offset:1296
	global_load_dwordx4 v[118:121], v[4:5], off offset:1280
	ds_bpermute_b32 v110, v29, v102
	ds_bpermute_b32 v111, v29, v99
	ds_bpermute_b32 v112, v29, v103
	ds_bpermute_b32 v122, v29, v2
	ds_bpermute_b32 v123, v29, v97
	ds_bpermute_b32 v124, v29, v105
	ds_bpermute_b32 v125, v29, v106
	ds_bpermute_b32 v126, v29, v95
	ds_bpermute_b32 v127, v29, v100
	ds_bpermute_b32 v128, v29, v101
	ds_bpermute_b32 v129, v29, v98
	s_waitcnt lgkmcnt(4)
	v_max_u32_e32 v99, v99, v125
	s_waitcnt lgkmcnt(3)
	v_max_u32_e32 v102, v102, v126
	s_waitcnt lgkmcnt(2)
	v_max_u32_e32 v96, v96, v127
	s_waitcnt lgkmcnt(1)
	v_max_u32_e32 v3, v3, v128
	s_waitcnt lgkmcnt(0)
	v_max_u32_e32 v104, v104, v129
	v_max_u32_e32 v103, v103, v124
	v_max_u32_e32 v2, v2, v123
	v_max_u32_e32 v97, v97, v122
	v_max_u32_e32 v105, v105, v112
	v_max_u32_e32 v106, v106, v111
	v_max_u32_e32 v95, v95, v110
	v_max_u32_e32 v100, v100, v109
	v_max_u32_e32 v98, v98, v108
	v_max_u32_e32 v101, v101, v107
	v_max_u32_e32 v0, v0, v1
	v_max_u32_e32 v1, v94, v97
	v_min_u32_e32 v94, v94, v97
	v_max_u32_e32 v97, v3, v105
	v_min_u32_e32 v3, v3, v105
	v_max_u32_e32 v105, v104, v106
	v_min_u32_e32 v104, v104, v106
	v_max_u32_e32 v106, v96, v95
	v_min_u32_e32 v95, v96, v95
	v_max_u32_e32 v96, v102, v100
	v_min_u32_e32 v100, v102, v100
	v_max_u32_e32 v102, v99, v98
	v_min_u32_e32 v98, v99, v98
	v_max_u32_e32 v99, v103, v101
	v_min_u32_e32 v101, v103, v101
	v_max_u32_e32 v103, v2, v0
	v_min_u32_e32 v0, v2, v0
	v_max_u32_e32 v2, v1, v96
	v_min_u32_e32 v1, v1, v96
	v_max_u32_e32 v96, v97, v102
	v_min_u32_e32 v97, v97, v102
	v_max_u32_e32 v102, v105, v99
	v_min_u32_e32 v99, v105, v99
	v_max_u32_e32 v105, v106, v103
	v_min_u32_e32 v103, v106, v103
	v_max_u32_e32 v106, v94, v100
	v_min_u32_e32 v94, v94, v100
	v_max_u32_e32 v100, v3, v98
	v_min_u32_e32 v3, v3, v98
	v_max_u32_e32 v98, v104, v101
	v_min_u32_e32 v101, v104, v101
	v_max_u32_e32 v104, v95, v0
	v_min_u32_e32 v0, v95, v0
	v_max_u32_e32 v95, v2, v102
	v_min_u32_e32 v2, v2, v102
	v_max_u32_e32 v102, v96, v105
	v_min_u32_e32 v96, v96, v105
	v_max_u32_e32 v110, v1, v99
	v_min_u32_e32 v1, v1, v99
	v_max_u32_e32 v99, v97, v103
	v_min_u32_e32 v97, v97, v103
	v_max_u32_e32 v111, v106, v98
	v_min_u32_e32 v98, v106, v98
	v_min_u32_e32 v122, v100, v104
	v_max_u32_e32 v123, v94, v101
	v_min_u32_e32 v94, v94, v101
	v_max_u32_e32 v124, v3, v0
	v_min_u32_e32 v0, v3, v0
	v_max_u32_e32 v112, v100, v104
	v_max_u32_e32 v109, v95, v102
	v_min_u32_e32 v108, v95, v102
	v_max_u32_e32 v107, v2, v96
	v_min_u32_e32 v106, v2, v96
	v_max_u32_e32 v105, v110, v99
	v_min_u32_e32 v104, v110, v99
	v_max_u32_e32 v103, v1, v97
	v_min_u32_e32 v102, v1, v97
	v_max_u32_e32 v99, v98, v122
	v_min_u32_e32 v98, v98, v122
	v_max_u32_e32 v97, v123, v124
	v_min_u32_e32 v96, v123, v124
	v_max_u32_e32 v95, v94, v0
	v_min_u32_e32 v94, v94, v0
	global_load_dwordx4 v[0:3], v[4:5], off offset:1328
	global_load_dwordx4 v[122:125], v[4:5], off offset:1312
	s_waitcnt vmcnt(2)
; __device__ __forceinline__ unsigned f2key(float f) { const unsigned u = __float_as_uint(f); return (u & 0x80000000u) ? ~u : (u | 0x80000000u); }
; __device__ __forceinline__ void peer_tile(const Args& A, LAS unsigned char* lds, int tile) {
;     ...
;                   for (int i = 0; i < 16; ++i) {
;                       const float lo = (float)__builtin_bit_cast(_Float16, (unsigned short)(sw[i] & 0xffffu)), hi = (float)__builtin_bit_cast(_Float16, (unsigned short)(sw[i] >> 16));
;                       const unsigned klo = (f2key(lo) & ~127u) | (unsigned)(127 - (32 * g + 2 * i)), khi = (f2key(hi) & ~127u) | (unsigned)(127 - (32 * g + 2 * i + 1));
;                       if (i < 8) { k0[2 * i] = klo; k0[2 * i + 1] = khi; } else { k1[2 * (i - 8)] = klo; k1[2 * (i - 8) + 1] = khi; } } }
;     ...
;                 for (int i = 0; i < 16; ++i) L2[p][i] = (g & 2) ? ((g & 1) ? LA[3][p][i] : LA[2][p][i]) : ((g & 1) ? LA[1][p][i] : LA[0][p][i]);
	v_cvt_f32_f16_sdwa v110, v118 dst_sel:DWORD dst_unused:UNUSED_PAD src0_sel:WORD_1
	v_max_u32_e32 v101, v111, v112
	v_min_u32_e32 v100, v111, v112
	v_cvt_f32_f16_e32 v111, v118
	v_not_b32_e32 v112, v110
	v_or_b32_e32 v118, 0x80000000, v110
	v_cmp_gt_i32_e32 vcc, 0, v110
	v_cndmask_b32_e64 v30, v62, v30, s[0:1]
	s_nop 0
	v_cndmask_b32_e32 v110, v118, v112, vcc
	v_not_b32_e32 v112, v111
	v_or_b32_e32 v118, 0x80000000, v111
	v_cmp_gt_i32_e32 vcc, 0, v111
	v_and_b32_e32 v110, 0xffffff80, v110
	v_sub_u32_e32 v110, v110, v15
	v_cndmask_b32_e32 v111, v118, v112, vcc
	v_cvt_f32_f16_sdwa v112, v119 dst_sel:DWORD dst_unused:UNUSED_PAD src0_sel:WORD_1
	v_cvt_f32_f16_e32 v118, v119
	v_and_b32_e32 v111, 0xffffff80, v111
	v_sub_u32_e32 v111, v111, v15
	v_not_b32_e32 v119, v112
	v_or_b32_e32 v126, 0x80000000, v112
	v_cmp_gt_i32_e32 vcc, 0, v112
	v_add_u32_e32 v110, 0x7e, v110
	v_add_u32_e32 v111, 0x7f, v111
	v_cndmask_b32_e32 v112, v126, v119, vcc
	v_not_b32_e32 v119, v118
	v_or_b32_e32 v126, 0x80000000, v118
	v_cmp_gt_i32_e32 vcc, 0, v118
	v_and_b32_e32 v112, 0xffffff80, v112
	v_sub_u32_e32 v112, v112, v14
	v_cndmask_b32_e32 v118, v126, v119, vcc
	v_cvt_f32_f16_sdwa v119, v120 dst_sel:DWORD dst_unused:UNUSED_PAD src0_sel:WORD_1
	v_cvt_f32_f16_e32 v120, v120
	v_and_b32_e32 v118, 0xffffff80, v118
	v_sub_u32_e32 v118, v118, v14
	v_not_b32_e32 v126, v119
	v_or_b32_e32 v127, 0x80000000, v119
	v_cmp_gt_i32_e32 vcc, 0, v119
	v_add_u32_e32 v112, 0x7e, v112
	v_add_u32_e32 v118, 0x7f, v118
	v_cndmask_b32_e32 v119, v127, v126, vcc
	v_not_b32_e32 v126, v120
	v_or_b32_e32 v127, 0x80000000, v120
	v_cmp_gt_i32_e32 vcc, 0, v120
	v_and_b32_e32 v119, 0xffffff80, v119
	v_sub_u32_e32 v119, v119, v12
	v_cndmask_b32_e32 v120, v127, v126, vcc
	v_cvt_f32_f16_sdwa v126, v121 dst_sel:DWORD dst_unused:UNUSED_PAD src0_sel:WORD_1
	v_cvt_f32_f16_e32 v121, v121
	v_and_b32_e32 v120, 0xffffff80, v120
	v_sub_u32_e32 v120, v120, v12
	v_not_b32_e32 v127, v126
	v_or_b32_e32 v128, 0x80000000, v126
	v_cmp_gt_i32_e32 vcc, 0, v126
	v_add_u32_e32 v119, 0x7e, v119
	v_add_u32_e32 v120, 0x7f, v120
	v_cndmask_b32_e32 v126, v128, v127, vcc
	v_not_b32_e32 v127, v121
	v_or_b32_e32 v128, 0x80000000, v121
	v_cmp_gt_i32_e32 vcc, 0, v121
	v_and_b32_e32 v126, 0xffffff80, v126
	v_sub_u32_e32 v126, v126, v10
	v_cndmask_b32_e32 v121, v128, v127, vcc
	v_cvt_f32_f16_sdwa v127, v114 dst_sel:DWORD dst_unused:UNUSED_PAD src0_sel:WORD_1
	v_cvt_f32_f16_e32 v114, v114
	v_and_b32_e32 v121, 0xffffff80, v121
	v_sub_u32_e32 v121, v121, v10
	v_not_b32_e32 v128, v127
	v_or_b32_e32 v129, 0x80000000, v127
	v_cmp_gt_i32_e32 vcc, 0, v127
	v_add_u32_e32 v126, 0x7e, v126
	v_add_u32_e32 v121, 0x7f, v121
	v_cndmask_b32_e32 v127, v129, v128, vcc
	v_not_b32_e32 v128, v114
	v_or_b32_e32 v129, 0x80000000, v114
	v_cmp_gt_i32_e32 vcc, 0, v114
	v_and_b32_e32 v127, 0xffffff80, v127
	v_sub_u32_e32 v127, v127, v8
	v_cndmask_b32_e32 v114, v129, v128, vcc
	v_cvt_f32_f16_sdwa v128, v115 dst_sel:DWORD dst_unused:UNUSED_PAD src0_sel:WORD_1
	v_cvt_f32_f16_e32 v115, v115
	v_and_b32_e32 v114, 0xffffff80, v114
	v_sub_u32_e32 v114, v114, v8
	v_not_b32_e32 v129, v128
	v_or_b32_e32 v130, 0x80000000, v128
	v_cmp_gt_i32_e32 vcc, 0, v128
	v_add_u32_e32 v127, 0x7e, v127
	v_add_u32_e32 v114, 0x7f, v114
	v_cndmask_b32_e32 v128, v130, v129, vcc
	v_not_b32_e32 v129, v115
	v_or_b32_e32 v130, 0x80000000, v115
	v_cmp_gt_i32_e32 vcc, 0, v115
	v_and_b32_e32 v128, 0xffffff80, v128
	v_sub_u32_e32 v128, v128, v16
	v_cndmask_b32_e32 v115, v130, v129, vcc
	v_cvt_f32_f16_sdwa v129, v116 dst_sel:DWORD dst_unused:UNUSED_PAD src0_sel:WORD_1
	v_cvt_f32_f16_e32 v116, v116
	v_and_b32_e32 v115, 0xffffff80, v115
	v_sub_u32_e32 v115, v115, v16
	v_not_b32_e32 v130, v129
	v_or_b32_e32 v131, 0x80000000, v129
	v_cmp_gt_i32_e32 vcc, 0, v129
	v_add_u32_e32 v128, 0x7e, v128
	v_add_u32_e32 v115, 0x7f, v115
	v_cndmask_b32_e32 v129, v131, v130, vcc
	v_not_b32_e32 v130, v116
	v_or_b32_e32 v131, 0x80000000, v116
	v_cmp_gt_i32_e32 vcc, 0, v116
	v_and_b32_e32 v129, 0xffffff80, v129
	v_sub_u32_e32 v129, v129, v17
	v_cndmask_b32_e32 v116, v131, v130, vcc
	v_cvt_f32_f16_sdwa v130, v117 dst_sel:DWORD dst_unused:UNUSED_PAD src0_sel:WORD_1
	v_cvt_f32_f16_e32 v117, v117
	v_and_b32_e32 v116, 0xffffff80, v116
	v_sub_u32_e32 v116, v116, v17
	v_not_b32_e32 v131, v130
	v_or_b32_e32 v132, 0x80000000, v130
	v_cmp_gt_i32_e32 vcc, 0, v130
	v_add_u32_e32 v129, 0x7e, v129
	v_add_u32_e32 v116, 0x7f, v116
	v_cndmask_b32_e32 v130, v132, v131, vcc
	v_not_b32_e32 v131, v117
	v_or_b32_e32 v132, 0x80000000, v117
	v_cmp_gt_i32_e32 vcc, 0, v117
	v_and_b32_e32 v130, 0xffffff80, v130
	v_sub_u32_e32 v130, v130, v18
	v_cndmask_b32_e32 v117, v132, v131, vcc
	s_waitcnt vmcnt(0)
; __device__ __forceinline__ unsigned f2key(float f) { const unsigned u = __float_as_uint(f); return (u & 0x80000000u) ? ~u : (u | 0x80000000u); }
; #define CE_DESC(a, b) do { const unsigned _mx = (a) > (b) ? (a) : (b), _mn = (a) > (b) ? (b) : (a); (a) = _mx; (b) = _mn; } while (0)
; __device__ __forceinline__ void sort16_desc(unsigned (&k)[16]) {
; #pragma unroll
;     for (int size = 2; size <= 16; size <<= 1)
; #pragma unroll
;         for (int stride = size >> 1; stride > 0; stride >>= 1)
; #pragma unroll
;             for (int i = 0; i < 16; ++i) { const int j = i ^ stride;
;                 if (j > i) { if ((i & size) == 0) CE_DESC(k[i], k[j]); else CE_DESC(k[j], k[i]); } }
; }
; __device__ __forceinline__ void peer_tile(const Args& A, LAS unsigned char* lds, int tile) {
;     ...
;                   for (int i = 0; i < 16; ++i) {
;                       const float lo = (float)__builtin_bit_cast(_Float16, (unsigned short)(sw[i] & 0xffffu)), hi = (float)__builtin_bit_cast(_Float16, (unsigned short)(sw[i] >> 16));
;                       const unsigned klo = (f2key(lo) & ~127u) | (unsigned)(127 - (32 * g + 2 * i)), khi = (f2key(hi) & ~127u) | (unsigned)(127 - (32 * g + 2 * i + 1));
;                       if (i < 8) { k0[2 * i] = klo; k0[2 * i + 1] = khi; } else { k1[2 * (i - 8)] = klo; k1[2 * (i - 8) + 1] = khi; } } }
	v_cvt_f32_f16_sdwa v131, v122 dst_sel:DWORD dst_unused:UNUSED_PAD src0_sel:WORD_1
	v_cvt_f32_f16_e32 v122, v122
	v_and_b32_e32 v117, 0xffffff80, v117
	v_sub_u32_e32 v117, v117, v18
	v_not_b32_e32 v132, v131
	v_or_b32_e32 v133, 0x80000000, v131
	v_cmp_gt_i32_e32 vcc, 0, v131
	v_add_u32_e32 v130, 0x7e, v130
	v_add_u32_e32 v117, 0x7f, v117
	v_cndmask_b32_e32 v131, v133, v132, vcc
	v_not_b32_e32 v132, v122
	v_or_b32_e32 v133, 0x80000000, v122
	v_cmp_gt_i32_e32 vcc, 0, v122
	v_and_b32_e32 v131, 0xffffff80, v131
	v_sub_u32_e32 v131, v131, v20
	v_cndmask_b32_e32 v122, v133, v132, vcc
	v_cvt_f32_f16_sdwa v132, v123 dst_sel:DWORD dst_unused:UNUSED_PAD src0_sel:WORD_1
	v_cvt_f32_f16_e32 v123, v123
	v_and_b32_e32 v122, 0xffffff80, v122
	v_sub_u32_e32 v122, v122, v20
	v_not_b32_e32 v133, v132
	v_or_b32_e32 v134, 0x80000000, v132
	v_cmp_gt_i32_e32 vcc, 0, v132
	v_add_u32_e32 v131, 0x7e, v131
	v_add_u32_e32 v122, 0x7f, v122
	v_cndmask_b32_e32 v132, v134, v133, vcc
	v_not_b32_e32 v133, v123
	v_or_b32_e32 v134, 0x80000000, v123
	v_cmp_gt_i32_e32 vcc, 0, v123
	v_and_b32_e32 v132, 0xffffff80, v132
	v_sub_u32_e32 v132, v132, v21
	v_cndmask_b32_e32 v123, v134, v133, vcc
	v_cvt_f32_f16_sdwa v133, v124 dst_sel:DWORD dst_unused:UNUSED_PAD src0_sel:WORD_1
	v_cvt_f32_f16_e32 v124, v124
	v_and_b32_e32 v123, 0xffffff80, v123
	v_sub_u32_e32 v123, v123, v21
	v_not_b32_e32 v134, v133
	v_or_b32_e32 v135, 0x80000000, v133
	v_cmp_gt_i32_e32 vcc, 0, v133
	v_add_u32_e32 v132, 0x7e, v132
	v_add_u32_e32 v123, 0x7f, v123
	v_cndmask_b32_e32 v133, v135, v134, vcc
	v_not_b32_e32 v134, v124
	v_or_b32_e32 v135, 0x80000000, v124
	v_cmp_gt_i32_e32 vcc, 0, v124
	v_and_b32_e32 v133, 0xffffff80, v133
	v_sub_u32_e32 v133, v133, v22
	v_cndmask_b32_e32 v124, v135, v134, vcc
	v_cvt_f32_f16_sdwa v134, v125 dst_sel:DWORD dst_unused:UNUSED_PAD src0_sel:WORD_1
	v_cvt_f32_f16_e32 v125, v125
	v_and_b32_e32 v124, 0xffffff80, v124
	v_sub_u32_e32 v124, v124, v22
	v_not_b32_e32 v135, v134
	v_or_b32_e32 v136, 0x80000000, v134
	v_cmp_gt_i32_e32 vcc, 0, v134
	v_add_u32_e32 v133, 0x7e, v133
	v_add_u32_e32 v124, 0x7f, v124
	v_cndmask_b32_e32 v134, v136, v135, vcc
	v_not_b32_e32 v135, v125
	v_or_b32_e32 v136, 0x80000000, v125
	v_cmp_gt_i32_e32 vcc, 0, v125
	v_and_b32_e32 v134, 0xffffff80, v134
	v_sub_u32_e32 v134, v134, v23
	v_cndmask_b32_e32 v125, v136, v135, vcc
	v_cvt_f32_f16_sdwa v135, v0 dst_sel:DWORD dst_unused:UNUSED_PAD src0_sel:WORD_1
	v_cvt_f32_f16_e32 v0, v0
	v_and_b32_e32 v125, 0xffffff80, v125
	v_sub_u32_e32 v125, v125, v23
	v_not_b32_e32 v136, v135
	v_or_b32_e32 v137, 0x80000000, v135
	v_cmp_gt_i32_e32 vcc, 0, v135
	v_add_u32_e32 v134, 0x7e, v134
	v_add_u32_e32 v125, 0x7f, v125
	v_cndmask_b32_e32 v135, v137, v136, vcc
	v_not_b32_e32 v136, v0
	v_or_b32_e32 v137, 0x80000000, v0
	v_cmp_gt_i32_e32 vcc, 0, v0
	v_and_b32_e32 v135, 0xffffff80, v135
	v_sub_u32_e32 v135, v135, v24
	v_cndmask_b32_e32 v0, v137, v136, vcc
	v_cvt_f32_f16_sdwa v136, v1 dst_sel:DWORD dst_unused:UNUSED_PAD src0_sel:WORD_1
	v_cvt_f32_f16_e32 v1, v1
	v_and_b32_e32 v0, 0xffffff80, v0
	v_sub_u32_e32 v0, v0, v24
	v_not_b32_e32 v137, v136
	v_or_b32_e32 v138, 0x80000000, v136
	v_cmp_gt_i32_e32 vcc, 0, v136
	v_add_u32_e32 v135, 0x7e, v135
	v_add_u32_e32 v0, 0x7f, v0
	v_cndmask_b32_e32 v136, v138, v137, vcc
	v_not_b32_e32 v137, v1
	v_or_b32_e32 v138, 0x80000000, v1
	v_cmp_gt_i32_e32 vcc, 0, v1
	v_and_b32_e32 v136, 0xffffff80, v136
	v_sub_u32_e32 v136, v136, v25
	v_cndmask_b32_e32 v1, v138, v137, vcc
	v_cvt_f32_f16_sdwa v137, v2 dst_sel:DWORD dst_unused:UNUSED_PAD src0_sel:WORD_1
	v_cvt_f32_f16_e32 v2, v2
	v_and_b32_e32 v1, 0xffffff80, v1
	v_sub_u32_e32 v1, v1, v25
	v_not_b32_e32 v138, v137
	v_or_b32_e32 v139, 0x80000000, v137
	v_cmp_gt_i32_e32 vcc, 0, v137
	v_add_u32_e32 v136, 0x7e, v136
	v_add_u32_e32 v1, 0x7f, v1
	v_cndmask_b32_e32 v137, v139, v138, vcc
	v_not_b32_e32 v138, v2
	v_or_b32_e32 v139, 0x80000000, v2
	v_cmp_gt_i32_e32 vcc, 0, v2
	v_and_b32_e32 v137, 0xffffff80, v137
	v_sub_u32_e32 v137, v137, v26
	v_cndmask_b32_e32 v2, v139, v138, vcc
	v_cvt_f32_f16_sdwa v138, v3 dst_sel:DWORD dst_unused:UNUSED_PAD src0_sel:WORD_1
	v_cvt_f32_f16_e32 v3, v3
	v_and_b32_e32 v2, 0xffffff80, v2
	v_sub_u32_e32 v2, v2, v26
	v_not_b32_e32 v139, v138
	v_or_b32_e32 v140, 0x80000000, v138
	v_cmp_gt_i32_e32 vcc, 0, v138
	v_add_u32_e32 v137, 0x7e, v137
	v_add_u32_e32 v2, 0x7f, v2
	v_cndmask_b32_e32 v138, v140, v139, vcc
	v_not_b32_e32 v139, v3
	v_or_b32_e32 v140, 0x80000000, v3
	v_cmp_gt_i32_e32 vcc, 0, v3
	v_and_b32_e32 v138, 0xffffff80, v138
	v_sub_u32_e32 v138, v138, v28
	v_cndmask_b32_e32 v3, v140, v139, vcc
	v_and_b32_e32 v3, 0xffffff80, v3
	v_sub_u32_e32 v3, v3, v28
	v_add_u32_e32 v138, 0x7e, v138
	v_add_u32_e32 v3, 0x7f, v3
	v_max_u32_e32 v139, v111, v110
	v_min_u32_e32 v110, v111, v110
	v_max_u32_e32 v111, v112, v118
	v_min_u32_e32 v112, v112, v118
	v_max_u32_e32 v118, v120, v119
	v_min_u32_e32 v119, v120, v119
	v_max_u32_e32 v120, v126, v121
	v_min_u32_e32 v121, v126, v121
	v_max_u32_e32 v126, v114, v127
	v_min_u32_e32 v114, v114, v127
	v_max_u32_e32 v127, v128, v115
	v_min_u32_e32 v115, v128, v115
	v_max_u32_e32 v128, v116, v129
	v_min_u32_e32 v116, v116, v129
	v_max_u32_e32 v129, v130, v117
	v_min_u32_e32 v117, v130, v117
	v_max_u32_e32 v147, v122, v131
	v_min_u32_e32 v122, v122, v131
	v_max_u32_e32 v131, v132, v123
	v_min_u32_e32 v123, v132, v123
	v_max_u32_e32 v132, v124, v133
	v_min_u32_e32 v124, v124, v133
	v_max_u32_e32 v133, v134, v125
	v_min_u32_e32 v125, v134, v125
	v_max_u32_e32 v134, v0, v135
	v_min_u32_e32 v0, v0, v135
	v_max_u32_e32 v135, v136, v1
	v_min_u32_e32 v1, v136, v1
	v_max_u32_e32 v136, v2, v137
	v_min_u32_e32 v2, v2, v137
; #define CE_DESC(a, b) do { const unsigned _mx = (a) > (b) ? (a) : (b), _mn = (a) > (b) ? (b) : (a); (a) = _mx; (b) = _mn; } while (0)
; __device__ __forceinline__ void sort16_desc(unsigned (&k)[16]) {
; #pragma unroll
;     for (int size = 2; size <= 16; size <<= 1)
; #pragma unroll
;         for (int stride = size >> 1; stride > 0; stride >>= 1)
; #pragma unroll
;             for (int i = 0; i < 16; ++i) { const int j = i ^ stride;
;                 if (j > i) { if ((i & size) == 0) CE_DESC(k[i], k[j]); else CE_DESC(k[j], k[i]); } }
; }
	v_max_u32_e32 v137, v138, v3
	v_min_u32_e32 v3, v138, v3
	v_max_u32_e32 v130, v139, v112
	v_min_u32_e32 v112, v139, v112
	v_max_u32_e32 v139, v110, v111
	v_min_u32_e32 v110, v110, v111
	v_max_u32_e32 v111, v121, v118
	v_min_u32_e32 v118, v121, v118
	v_max_u32_e32 v121, v120, v119
	v_min_u32_e32 v119, v120, v119
	v_max_u32_e32 v120, v126, v115
	v_min_u32_e32 v115, v126, v115
	v_max_u32_e32 v126, v114, v127
	v_min_u32_e32 v114, v114, v127
	v_max_u32_e32 v127, v117, v128
	v_min_u32_e32 v117, v117, v128
	v_max_u32_e32 v128, v129, v116
	v_min_u32_e32 v116, v129, v116
	v_max_u32_e32 v138, v147, v123
	v_min_u32_e32 v123, v147, v123
	v_max_u32_e32 v147, v122, v131
	v_min_u32_e32 v122, v122, v131
	v_max_u32_e32 v131, v125, v132
	v_min_u32_e32 v125, v125, v132
	v_max_u32_e32 v132, v133, v124
	v_min_u32_e32 v124, v133, v124
	v_max_u32_e32 v133, v134, v1
	v_min_u32_e32 v1, v134, v1
	v_max_u32_e32 v134, v0, v135
	v_min_u32_e32 v0, v0, v135
	v_max_u32_e32 v135, v3, v136
	v_min_u32_e32 v3, v3, v136
	v_max_u32_e32 v136, v137, v2
	v_min_u32_e32 v2, v137, v2
	v_max_u32_e32 v129, v130, v139
	v_min_u32_e32 v130, v130, v139
	v_max_u32_e32 v139, v112, v110
	v_min_u32_e32 v110, v112, v110
	v_max_u32_e32 v112, v119, v118
	v_min_u32_e32 v118, v119, v118
	v_max_u32_e32 v119, v121, v111
	v_min_u32_e32 v111, v121, v111
	v_max_u32_e32 v121, v120, v126
	v_min_u32_e32 v120, v120, v126
	v_max_u32_e32 v126, v115, v114
	v_min_u32_e32 v114, v115, v114
	v_max_u32_e32 v115, v116, v117
	v_min_u32_e32 v116, v116, v117
	v_max_u32_e32 v117, v128, v127
	v_min_u32_e32 v127, v128, v127
	v_max_u32_e32 v137, v138, v147
	v_min_u32_e32 v138, v138, v147
	v_max_u32_e32 v147, v123, v122
	v_min_u32_e32 v122, v123, v122
	v_max_u32_e32 v123, v124, v125
	v_min_u32_e32 v124, v124, v125
	v_max_u32_e32 v125, v132, v131
	v_min_u32_e32 v131, v132, v131
	v_max_u32_e32 v132, v133, v134
	v_min_u32_e32 v133, v133, v134
	v_max_u32_e32 v134, v1, v0
	v_min_u32_e32 v0, v1, v0
	v_max_u32_e32 v1, v2, v3
	v_min_u32_e32 v2, v2, v3
	v_max_u32_e32 v3, v136, v135
	v_min_u32_e32 v135, v136, v135
	v_max_u32_e32 v128, v129, v118
	v_min_u32_e32 v118, v129, v118
	v_max_u32_e32 v129, v130, v112
	v_min_u32_e32 v112, v130, v112
	v_max_u32_e32 v130, v139, v111
	v_min_u32_e32 v111, v139, v111
	v_max_u32_e32 v139, v110, v119
	v_min_u32_e32 v110, v110, v119
	v_max_u32_e32 v119, v116, v121
	v_min_u32_e32 v116, v116, v121
	v_max_u32_e32 v121, v115, v120
	v_min_u32_e32 v115, v115, v120
	v_max_u32_e32 v120, v127, v126
	v_min_u32_e32 v126, v127, v126
	v_max_u32_e32 v127, v117, v114
	v_min_u32_e32 v114, v117, v114
	v_max_u32_e32 v136, v137, v124
	v_min_u32_e32 v124, v137, v124
	v_max_u32_e32 v137, v138, v123
	v_min_u32_e32 v123, v138, v123
	v_max_u32_e32 v138, v147, v131
	v_min_u32_e32 v131, v147, v131
	v_max_u32_e32 v147, v122, v125
	v_min_u32_e32 v122, v122, v125
	v_max_u32_e32 v125, v2, v132
	v_min_u32_e32 v2, v2, v132
	v_max_u32_e32 v132, v1, v133
	v_min_u32_e32 v1, v1, v133
	v_max_u32_e32 v133, v135, v134
	v_min_u32_e32 v134, v135, v134
	v_max_u32_e32 v135, v3, v0
	v_min_u32_e32 v0, v3, v0
	v_max_u32_e32 v117, v128, v130
	v_min_u32_e32 v128, v128, v130
	v_max_u32_e32 v130, v129, v139
	v_min_u32_e32 v129, v129, v139
	v_max_u32_e32 v139, v118, v111
	v_min_u32_e32 v111, v118, v111
	v_max_u32_e32 v118, v112, v110
	v_min_u32_e32 v110, v112, v110
	v_max_u32_e32 v112, v126, v116
	v_min_u32_e32 v116, v126, v116
	v_max_u32_e32 v126, v114, v115
	v_min_u32_e32 v114, v114, v115
	v_max_u32_e32 v115, v120, v119
	v_min_u32_e32 v119, v120, v119
	v_max_u32_e32 v120, v127, v121
	v_min_u32_e32 v121, v127, v121
	v_max_u32_e32 v3, v136, v138
	v_min_u32_e32 v136, v136, v138
	v_max_u32_e32 v138, v137, v147
	v_min_u32_e32 v137, v137, v147
	v_max_u32_e32 v147, v124, v131
	v_min_u32_e32 v124, v124, v131
	v_max_u32_e32 v131, v123, v122
	v_min_u32_e32 v122, v123, v122
	v_max_u32_e32 v123, v134, v2
	v_min_u32_e32 v2, v134, v2
	v_max_u32_e32 v134, v0, v1
	v_min_u32_e32 v0, v0, v1
	v_max_u32_e32 v1, v133, v125
	v_min_u32_e32 v125, v133, v125
	v_max_u32_e32 v133, v135, v132
	v_min_u32_e32 v132, v135, v132
	v_max_u32_e32 v127, v117, v130
	v_min_u32_e32 v117, v117, v130
	v_max_u32_e32 v130, v128, v129
	v_min_u32_e32 v128, v128, v129
	v_max_u32_e32 v129, v139, v118
	v_min_u32_e32 v118, v139, v118
	v_max_u32_e32 v139, v111, v110
	v_min_u32_e32 v110, v111, v110
	v_max_u32_e32 v111, v114, v116
	v_min_u32_e32 v114, v114, v116
	v_max_u32_e32 v116, v126, v112
	v_min_u32_e32 v112, v126, v112
	v_max_u32_e32 v126, v121, v119
	v_min_u32_e32 v119, v121, v119
	v_max_u32_e32 v121, v120, v115
	v_min_u32_e32 v115, v120, v115
	v_max_u32_e32 v135, v3, v138
	v_min_u32_e32 v3, v3, v138
	v_max_u32_e32 v138, v136, v137
	v_min_u32_e32 v136, v136, v137
	v_max_u32_e32 v137, v147, v131
	v_min_u32_e32 v131, v147, v131
	v_max_u32_e32 v147, v124, v122
	v_min_u32_e32 v122, v124, v122
	v_max_u32_e32 v124, v0, v2
	v_min_u32_e32 v0, v0, v2
	v_max_u32_e32 v2, v134, v123
	v_min_u32_e32 v123, v134, v123
	v_max_u32_e32 v134, v132, v125
	v_min_u32_e32 v125, v132, v125
	v_max_u32_e32 v132, v133, v1
	v_min_u32_e32 v1, v133, v1
	v_max_u32_e32 v120, v127, v114
	v_min_u32_e32 v114, v127, v114
	v_max_u32_e32 v127, v117, v111
	v_min_u32_e32 v111, v117, v111
	v_max_u32_e32 v117, v130, v112
	v_min_u32_e32 v112, v130, v112
	v_max_u32_e32 v130, v128, v116
	v_min_u32_e32 v116, v128, v116
	v_max_u32_e32 v128, v129, v119
	v_min_u32_e32 v119, v129, v119
	v_max_u32_e32 v129, v118, v126
	v_min_u32_e32 v118, v118, v126
	v_max_u32_e32 v126, v139, v115
	v_min_u32_e32 v115, v139, v115
	v_max_u32_e32 v139, v110, v121
	v_min_u32_e32 v110, v110, v121
	v_max_u32_e32 v133, v135, v0
	v_min_u32_e32 v0, v135, v0
; #define CE_DESC(a, b) do { const unsigned _mx = (a) > (b) ? (a) : (b), _mn = (a) > (b) ? (b) : (a); (a) = _mx; (b) = _mn; } while (0)
; __device__ __forceinline__ void sort16_desc(unsigned (&k)[16]) {
; #pragma unroll
;     for (int size = 2; size <= 16; size <<= 1)
; #pragma unroll
;         for (int stride = size >> 1; stride > 0; stride >>= 1)
; #pragma unroll
;             for (int i = 0; i < 16; ++i) { const int j = i ^ stride;
;                 if (j > i) { if ((i & size) == 0) CE_DESC(k[i], k[j]); else CE_DESC(k[j], k[i]); } }
; }
; __device__ __forceinline__ void merge16(unsigned (&a)[16], const unsigned (&b)[16]) {
; #pragma unroll
;     for (int i = 0; i < 16; ++i) a[i] = a[i] > b[15 - i] ? a[i] : b[15 - i];
; #pragma unroll
;     for (int stride = 8; stride > 0; stride >>= 1)
; #pragma unroll
;         for (int i = 0; i < 16; ++i) { const int j = i ^ stride; if (j > i) CE_DESC(a[i], a[j]); }
; }
; __device__ __forceinline__ void peer_tile(const Args& A, LAS unsigned char* lds, int tile) {
;     ...
;                 sort16_desc(k0); sort16_desc(k1); merge16(k0, k1);
; #pragma unroll
;                 for (int msk = 16; msk <= 32; msk <<= 1) {
; #pragma unroll
;                     for (int i = 0; i < 16; ++i) k1[i] = (unsigned)__shfl_xor((int)k0[i], msk);
;                     merge16(k0, k1); }
	v_max_u32_e32 v135, v3, v124
	v_min_u32_e32 v3, v3, v124
	v_max_u32_e32 v124, v138, v123
	v_min_u32_e32 v123, v138, v123
	v_max_u32_e32 v138, v136, v2
	v_min_u32_e32 v2, v136, v2
	v_max_u32_e32 v136, v137, v125
	v_min_u32_e32 v125, v137, v125
	v_max_u32_e32 v137, v131, v134
	v_min_u32_e32 v131, v131, v134
	v_max_u32_e32 v134, v147, v1
	v_min_u32_e32 v1, v147, v1
	v_max_u32_e32 v147, v122, v132
	v_min_u32_e32 v122, v122, v132
	v_max_u32_e32 v121, v120, v128
	v_min_u32_e32 v120, v120, v128
	v_max_u32_e32 v128, v127, v129
	v_min_u32_e32 v127, v127, v129
	v_max_u32_e32 v129, v117, v126
	v_min_u32_e32 v117, v117, v126
	v_max_u32_e32 v126, v130, v139
	v_min_u32_e32 v130, v130, v139
	v_max_u32_e32 v139, v114, v119
	v_min_u32_e32 v114, v114, v119
	v_max_u32_e32 v119, v111, v118
	v_min_u32_e32 v111, v111, v118
	v_max_u32_e32 v118, v112, v115
	v_min_u32_e32 v112, v112, v115
	v_max_u32_e32 v115, v116, v110
	v_min_u32_e32 v110, v116, v110
	v_max_u32_e32 v132, v133, v136
	v_min_u32_e32 v133, v133, v136
	v_max_u32_e32 v136, v135, v137
	v_min_u32_e32 v135, v135, v137
	v_max_u32_e32 v137, v124, v134
	v_min_u32_e32 v124, v124, v134
	v_max_u32_e32 v134, v138, v147
	v_min_u32_e32 v138, v138, v147
	v_max_u32_e32 v147, v0, v125
	v_min_u32_e32 v0, v0, v125
	v_max_u32_e32 v125, v3, v131
	v_min_u32_e32 v3, v3, v131
	v_max_u32_e32 v131, v123, v1
	v_min_u32_e32 v1, v123, v1
	v_max_u32_e32 v123, v2, v122
	v_min_u32_e32 v2, v2, v122
	v_max_u32_e32 v116, v121, v129
	v_min_u32_e32 v121, v121, v129
	v_max_u32_e32 v129, v128, v126
	v_min_u32_e32 v126, v128, v126
	v_max_u32_e32 v128, v120, v117
	v_min_u32_e32 v117, v120, v117
	v_max_u32_e32 v120, v127, v130
	v_min_u32_e32 v127, v127, v130
	v_max_u32_e32 v130, v139, v118
	v_min_u32_e32 v118, v139, v118
	v_max_u32_e32 v139, v119, v115
	v_min_u32_e32 v115, v119, v115
	v_max_u32_e32 v119, v114, v112
	v_min_u32_e32 v112, v114, v112
	v_max_u32_e32 v114, v111, v110
	v_min_u32_e32 v110, v111, v110
	v_max_u32_e32 v122, v132, v137
	v_min_u32_e32 v132, v132, v137
	v_max_u32_e32 v137, v136, v134
	v_min_u32_e32 v134, v136, v134
	v_max_u32_e32 v136, v133, v124
	v_min_u32_e32 v124, v133, v124
	v_max_u32_e32 v133, v135, v138
	v_min_u32_e32 v135, v135, v138
	v_max_u32_e32 v138, v147, v131
	v_min_u32_e32 v131, v147, v131
	v_max_u32_e32 v147, v125, v123
	v_min_u32_e32 v123, v125, v123
	v_max_u32_e32 v125, v0, v1
	v_min_u32_e32 v0, v0, v1
	v_max_u32_e32 v1, v3, v2
	v_min_u32_e32 v2, v3, v2
	v_min_u32_e32 v111, v116, v129
	v_min_u32_e32 v140, v121, v126
	v_min_u32_e32 v141, v128, v120
	v_min_u32_e32 v142, v117, v127
	v_min_u32_e32 v143, v130, v139
	v_min_u32_e32 v144, v118, v115
	v_min_u32_e32 v145, v119, v114
	v_min_u32_e32 v146, v112, v110
	v_min_u32_e32 v3, v122, v137
	v_min_u32_e32 v148, v132, v134
	v_min_u32_e32 v149, v136, v133
	v_min_u32_e32 v150, v124, v135
	v_min_u32_e32 v151, v138, v147
	v_min_u32_e32 v152, v131, v123
	v_min_u32_e32 v153, v125, v1
	v_min_u32_e32 v154, v0, v2
	v_max3_u32 v116, v116, v129, v154
	v_max3_u32 v0, v111, v0, v2
	v_max3_u32 v2, v121, v126, v153
	v_max3_u32 v1, v140, v125, v1
	v_max3_u32 v111, v128, v120, v152
	v_max3_u32 v120, v141, v131, v123
	v_max3_u32 v117, v117, v127, v151
	v_max3_u32 v121, v142, v138, v147
	v_max3_u32 v123, v130, v139, v150
	v_max3_u32 v124, v143, v124, v135
	v_max3_u32 v115, v118, v115, v149
	v_max3_u32 v118, v144, v136, v133
	v_max3_u32 v114, v119, v114, v148
	v_max3_u32 v119, v145, v132, v134
	v_max3_u32 v3, v112, v110, v3
	v_max3_u32 v110, v146, v122, v137
	v_max_u32_e32 v112, v116, v123
	v_min_u32_e32 v116, v116, v123
	v_max_u32_e32 v122, v0, v124
	v_min_u32_e32 v0, v0, v124
	v_max_u32_e32 v123, v2, v115
	v_min_u32_e32 v2, v2, v115
	v_max_u32_e32 v115, v1, v118
	v_min_u32_e32 v1, v1, v118
	v_max_u32_e32 v118, v111, v114
	v_min_u32_e32 v111, v111, v114
	v_max_u32_e32 v114, v120, v119
	v_min_u32_e32 v119, v120, v119
	v_max_u32_e32 v120, v117, v3
	v_min_u32_e32 v3, v117, v3
	v_max_u32_e32 v117, v121, v110
	v_min_u32_e32 v110, v121, v110
	v_max_u32_e32 v121, v112, v118
	v_min_u32_e32 v112, v112, v118
	v_max_u32_e32 v118, v122, v114
	v_min_u32_e32 v114, v122, v114
	v_max_u32_e32 v122, v123, v120
	v_min_u32_e32 v120, v123, v120
	v_max_u32_e32 v123, v115, v117
	v_min_u32_e32 v115, v115, v117
	v_max_u32_e32 v117, v116, v111
	v_min_u32_e32 v111, v116, v111
	v_max_u32_e32 v116, v0, v119
	v_min_u32_e32 v0, v0, v119
	v_max_u32_e32 v119, v2, v3
	v_min_u32_e32 v2, v2, v3
	v_max_u32_e32 v3, v1, v110
	v_min_u32_e32 v1, v1, v110
	v_max_u32_e32 v110, v121, v122
	v_min_u32_e32 v121, v121, v122
	v_max_u32_e32 v122, v118, v123
	v_min_u32_e32 v118, v118, v123
	v_max_u32_e32 v123, v112, v120
	v_min_u32_e32 v112, v112, v120
	v_max_u32_e32 v120, v114, v115
	v_min_u32_e32 v114, v114, v115
	v_max_u32_e32 v115, v117, v119
	v_min_u32_e32 v117, v117, v119
	v_max_u32_e32 v119, v116, v3
	v_min_u32_e32 v3, v116, v3
	v_max_u32_e32 v116, v111, v2
	v_min_u32_e32 v2, v111, v2
	v_max_u32_e32 v111, v0, v1
	v_min_u32_e32 v0, v0, v1
	v_max_u32_e32 v1, v110, v122
	v_min_u32_e32 v110, v110, v122
	v_max_u32_e32 v122, v121, v118
	v_min_u32_e32 v118, v121, v118
	v_max_u32_e32 v121, v123, v120
	v_min_u32_e32 v120, v123, v120
	v_max_u32_e32 v123, v112, v114
	v_min_u32_e32 v112, v112, v114
	v_max_u32_e32 v114, v115, v119
	v_min_u32_e32 v115, v115, v119
	v_max_u32_e32 v119, v117, v3
	v_min_u32_e32 v3, v117, v3
	v_max_u32_e32 v117, v116, v111
	v_min_u32_e32 v111, v116, v111
	v_max_u32_e32 v116, v2, v0
	v_min_u32_e32 v0, v2, v0
	ds_bpermute_b32 v2, v27, v1
	ds_bpermute_b32 v124, v27, v110
	ds_bpermute_b32 v125, v27, v122
	ds_bpermute_b32 v126, v27, v118
	ds_bpermute_b32 v127, v27, v121
	ds_bpermute_b32 v128, v27, v120
	ds_bpermute_b32 v129, v27, v123
	ds_bpermute_b32 v130, v27, v112
	ds_bpermute_b32 v131, v27, v114
	ds_bpermute_b32 v132, v27, v115
	ds_bpermute_b32 v133, v27, v119
	ds_bpermute_b32 v134, v27, v0
	ds_bpermute_b32 v135, v27, v116
	ds_bpermute_b32 v136, v27, v111
	ds_bpermute_b32 v137, v27, v117
	ds_bpermute_b32 v138, v27, v3
	s_waitcnt lgkmcnt(4)
; #define CE_DESC(a, b) do { const unsigned _mx = (a) > (b) ? (a) : (b), _mn = (a) > (b) ? (b) : (a); (a) = _mx; (b) = _mn; } while (0)
; __device__ __forceinline__ void merge16(unsigned (&a)[16], const unsigned (&b)[16]) {
; #pragma unroll
;     for (int i = 0; i < 16; ++i) a[i] = a[i] > b[15 - i] ? a[i] : b[15 - i];
; #pragma unroll
;     for (int stride = 8; stride > 0; stride >>= 1)
; #pragma unroll
;         for (int i = 0; i < 16; ++i) { const int j = i ^ stride; if (j > i) CE_DESC(a[i], a[j]); }
; }
; __device__ __forceinline__ void peer_tile(const Args& A, LAS unsigned char* lds, int tile) {
;     ...
;                 { const bf16_t* sp = QRY + m * 2048 + hp * 128 + 32 * g;
;                   const u32x4 s0 = *(const u32x4*)sp, s1 = *(const u32x4*)(sp + 8), s2 = *(const u32x4*)(sp + 16), s3 = *(const u32x4*)(sp + 24);
;                   const unsigned sw[16] = {s0.x, s0.y, s0.z, s0.w, s1.x, s1.y, s1.z, s1.w, s2.x, s2.y, s2.z, s2.w, s3.x, s3.y, s3.z, s3.w};
;     ...
;                 sort16_desc(k0); sort16_desc(k1); merge16(k0, k1);
; #pragma unroll
;                 for (int msk = 16; msk <= 32; msk <<= 1) {
; #pragma unroll
;                     for (int i = 0; i < 16; ++i) k1[i] = (unsigned)__shfl_xor((int)k0[i], msk);
;                     merge16(k0, k1); }
	v_max_u32_e32 v1, v1, v134
	s_waitcnt lgkmcnt(3)
	v_max_u32_e32 v110, v110, v135
	s_waitcnt lgkmcnt(2)
	v_max_u32_e32 v122, v122, v136
	s_waitcnt lgkmcnt(1)
	v_max_u32_e32 v118, v118, v137
	s_waitcnt lgkmcnt(0)
	v_max_u32_e32 v121, v121, v138
	v_max_u32_e32 v120, v120, v133
	v_max_u32_e32 v123, v123, v132
	v_max_u32_e32 v112, v112, v131
	v_max_u32_e32 v114, v114, v130
	v_max_u32_e32 v115, v115, v129
	v_max_u32_e32 v119, v119, v128
	v_max_u32_e32 v3, v3, v127
	v_max_u32_e32 v117, v117, v126
	v_max_u32_e32 v111, v111, v125
	v_max_u32_e32 v116, v116, v124
	v_max_u32_e32 v0, v0, v2
	v_max_u32_e32 v2, v1, v114
	v_min_u32_e32 v1, v1, v114
	v_max_u32_e32 v114, v110, v115
	v_min_u32_e32 v110, v110, v115
	v_max_u32_e32 v115, v122, v119
	v_min_u32_e32 v119, v122, v119
	v_max_u32_e32 v122, v118, v3
	v_min_u32_e32 v3, v118, v3
	v_max_u32_e32 v118, v121, v117
	v_min_u32_e32 v117, v121, v117
	v_max_u32_e32 v121, v120, v111
	v_min_u32_e32 v111, v120, v111
	v_max_u32_e32 v120, v123, v116
	v_min_u32_e32 v116, v123, v116
	v_max_u32_e32 v123, v112, v0
	v_min_u32_e32 v0, v112, v0
	v_max_u32_e32 v112, v2, v118
	v_min_u32_e32 v2, v2, v118
	v_max_u32_e32 v118, v114, v121
	v_min_u32_e32 v114, v114, v121
	v_max_u32_e32 v121, v115, v120
	v_min_u32_e32 v115, v115, v120
	v_max_u32_e32 v120, v122, v123
	v_min_u32_e32 v122, v122, v123
	v_max_u32_e32 v123, v1, v117
	v_min_u32_e32 v1, v1, v117
	v_max_u32_e32 v117, v110, v111
	v_min_u32_e32 v110, v110, v111
	v_max_u32_e32 v111, v119, v116
	v_min_u32_e32 v116, v119, v116
	v_max_u32_e32 v119, v3, v0
	v_min_u32_e32 v0, v3, v0
	v_max_u32_e32 v3, v112, v121
	v_min_u32_e32 v112, v112, v121
	v_max_u32_e32 v121, v118, v120
	v_min_u32_e32 v118, v118, v120
	v_max_u32_e32 v120, v2, v115
	v_min_u32_e32 v2, v2, v115
	v_max_u32_e32 v115, v114, v122
	v_min_u32_e32 v114, v114, v122
	v_max_u32_e32 v122, v123, v111
	v_min_u32_e32 v111, v123, v111
	v_max_u32_e32 v123, v117, v119
	v_min_u32_e32 v117, v117, v119
	v_max_u32_e32 v119, v1, v116
	v_min_u32_e32 v1, v1, v116
	v_max_u32_e32 v116, v110, v0
	v_min_u32_e32 v0, v110, v0
	v_max_u32_e32 v110, v3, v121
	v_min_u32_e32 v3, v3, v121
	v_max_u32_e32 v121, v112, v118
	v_min_u32_e32 v112, v112, v118
	v_max_u32_e32 v118, v120, v115
	v_min_u32_e32 v115, v120, v115
	v_max_u32_e32 v120, v2, v114
	v_min_u32_e32 v2, v2, v114
	v_max_u32_e32 v114, v122, v123
	v_min_u32_e32 v122, v122, v123
	v_max_u32_e32 v123, v111, v117
	v_min_u32_e32 v111, v111, v117
	v_max_u32_e32 v117, v119, v116
	v_min_u32_e32 v116, v119, v116
	v_max_u32_e32 v119, v1, v0
	v_min_u32_e32 v0, v1, v0
	ds_bpermute_b32 v128, v29, v0
	ds_bpermute_b32 v1, v29, v110
	ds_bpermute_b32 v124, v29, v3
	ds_bpermute_b32 v125, v29, v121
	ds_bpermute_b32 v126, v29, v112
	s_waitcnt lgkmcnt(4)
	v_max_u32_e32 v110, v110, v128
	global_load_dwordx4 v[128:131], v[4:5], off offset:1552
	global_load_dwordx4 v[132:135], v[4:5], off offset:1536
	ds_bpermute_b32 v127, v29, v118
	ds_bpermute_b32 v136, v29, v115
	ds_bpermute_b32 v137, v29, v120
	ds_bpermute_b32 v138, v29, v2
	ds_bpermute_b32 v139, v29, v114
	ds_bpermute_b32 v140, v29, v122
	ds_bpermute_b32 v141, v29, v123
	ds_bpermute_b32 v142, v29, v111
	ds_bpermute_b32 v143, v29, v117
	ds_bpermute_b32 v144, v29, v119
	ds_bpermute_b32 v145, v29, v116
	s_waitcnt lgkmcnt(4)
	v_max_u32_e32 v115, v115, v141
	s_waitcnt lgkmcnt(3)
	v_max_u32_e32 v118, v118, v142
	s_waitcnt lgkmcnt(2)
	v_max_u32_e32 v112, v112, v143
	s_waitcnt lgkmcnt(1)
	v_max_u32_e32 v3, v3, v144
	s_waitcnt lgkmcnt(0)
	v_max_u32_e32 v121, v121, v145
	v_max_u32_e32 v120, v120, v140
	v_max_u32_e32 v2, v2, v139
	v_max_u32_e32 v114, v114, v138
	v_max_u32_e32 v122, v122, v137
	v_max_u32_e32 v123, v123, v136
	v_max_u32_e32 v111, v111, v127
	v_max_u32_e32 v117, v117, v126
	v_max_u32_e32 v116, v116, v125
	v_max_u32_e32 v119, v119, v124
	v_max_u32_e32 v0, v0, v1
	v_max_u32_e32 v1, v110, v114
	v_min_u32_e32 v110, v110, v114
	v_max_u32_e32 v114, v3, v122
	v_min_u32_e32 v3, v3, v122
	v_max_u32_e32 v122, v121, v123
	v_min_u32_e32 v121, v121, v123
	v_max_u32_e32 v123, v112, v111
	v_min_u32_e32 v111, v112, v111
	v_max_u32_e32 v112, v118, v117
	v_min_u32_e32 v117, v118, v117
	v_max_u32_e32 v118, v115, v116
	v_min_u32_e32 v115, v115, v116
	v_max_u32_e32 v116, v120, v119
	v_min_u32_e32 v119, v120, v119
	v_max_u32_e32 v120, v2, v0
	v_min_u32_e32 v0, v2, v0
	v_max_u32_e32 v2, v1, v112
	v_min_u32_e32 v1, v1, v112
	v_max_u32_e32 v112, v114, v118
	v_min_u32_e32 v114, v114, v118
	v_max_u32_e32 v118, v122, v116
	v_min_u32_e32 v116, v122, v116
	v_max_u32_e32 v122, v123, v120
	v_min_u32_e32 v120, v123, v120
	v_max_u32_e32 v123, v110, v117
	v_min_u32_e32 v110, v110, v117
	v_max_u32_e32 v117, v3, v115
	v_min_u32_e32 v3, v3, v115
	v_max_u32_e32 v115, v121, v119
	v_min_u32_e32 v119, v121, v119
	v_max_u32_e32 v121, v111, v0
	v_min_u32_e32 v0, v111, v0
	v_max_u32_e32 v111, v2, v118
	v_min_u32_e32 v2, v2, v118
	v_max_u32_e32 v118, v112, v122
	v_min_u32_e32 v112, v112, v122
	v_max_u32_e32 v127, v1, v116
	v_min_u32_e32 v1, v1, v116
	v_max_u32_e32 v116, v114, v120
	v_min_u32_e32 v114, v114, v120
	v_max_u32_e32 v136, v123, v115
	v_min_u32_e32 v115, v123, v115
	v_max_u32_e32 v137, v117, v121
	v_min_u32_e32 v138, v117, v121
	v_max_u32_e32 v139, v110, v119
	v_min_u32_e32 v110, v110, v119
	v_max_u32_e32 v140, v3, v0
	v_min_u32_e32 v0, v3, v0
	v_max_u32_e32 v126, v111, v118
	v_min_u32_e32 v125, v111, v118
	v_max_u32_e32 v124, v2, v112
	v_min_u32_e32 v123, v2, v112
	v_max_u32_e32 v122, v127, v116
	v_min_u32_e32 v121, v127, v116
	v_max_u32_e32 v120, v1, v114
	v_min_u32_e32 v119, v1, v114
	v_max_u32_e32 v118, v136, v137
	v_min_u32_e32 v117, v136, v137
	v_max_u32_e32 v116, v115, v138
	v_min_u32_e32 v115, v115, v138
	v_max_u32_e32 v114, v139, v140
	v_min_u32_e32 v112, v139, v140
	v_max_u32_e32 v111, v110, v0
	v_min_u32_e32 v110, v110, v0
	global_load_dwordx4 v[0:3], v[4:5], off offset:1584
	global_load_dwordx4 v[136:139], v[4:5], off offset:1568
	s_waitcnt vmcnt(2)
; __device__ __forceinline__ unsigned f2key(float f) { const unsigned u = __float_as_uint(f); return (u & 0x80000000u) ? ~u : (u | 0x80000000u); }
; __device__ __forceinline__ void peer_tile(const Args& A, LAS unsigned char* lds, int tile) {
;     ...
;                   for (int i = 0; i < 16; ++i) {
;                       const float lo = (float)__builtin_bit_cast(_Float16, (unsigned short)(sw[i] & 0xffffu)), hi = (float)__builtin_bit_cast(_Float16, (unsigned short)(sw[i] >> 16));
;                       const unsigned klo = (f2key(lo) & ~127u) | (unsigned)(127 - (32 * g + 2 * i)), khi = (f2key(hi) & ~127u) | (unsigned)(127 - (32 * g + 2 * i + 1));
;                       if (i < 8) { k0[2 * i] = klo; k0[2 * i + 1] = khi; } else { k1[2 * (i - 8)] = klo; k1[2 * (i - 8) + 1] = khi; } } }
	v_cvt_f32_f16_sdwa v127, v132 dst_sel:DWORD dst_unused:UNUSED_PAD src0_sel:WORD_1
	v_cvt_f32_f16_e32 v132, v132
	v_not_b32_e32 v140, v127
	v_or_b32_e32 v141, 0x80000000, v127
	v_cmp_gt_i32_e32 vcc, 0, v127
	s_nop 1
	v_cndmask_b32_e32 v127, v141, v140, vcc
	v_not_b32_e32 v140, v132
	v_or_b32_e32 v141, 0x80000000, v132
	v_cmp_gt_i32_e32 vcc, 0, v132
	v_and_b32_e32 v127, 0xffffff80, v127
	v_sub_u32_e32 v127, v127, v15
	v_cndmask_b32_e32 v132, v141, v140, vcc
	v_cvt_f32_f16_sdwa v140, v133 dst_sel:DWORD dst_unused:UNUSED_PAD src0_sel:WORD_1
	v_cvt_f32_f16_e32 v133, v133
	v_and_b32_e32 v132, 0xffffff80, v132
	v_sub_u32_e32 v132, v132, v15
	v_not_b32_e32 v141, v140
	v_or_b32_e32 v142, 0x80000000, v140
	v_cmp_gt_i32_e32 vcc, 0, v140
	v_add_u32_e32 v127, 0x7e, v127
	v_add_u32_e32 v132, 0x7f, v132
	v_cndmask_b32_e32 v140, v142, v141, vcc
	v_not_b32_e32 v141, v133
	v_or_b32_e32 v142, 0x80000000, v133
	v_cmp_gt_i32_e32 vcc, 0, v133
	v_and_b32_e32 v140, 0xffffff80, v140
	v_sub_u32_e32 v140, v140, v14
	v_cndmask_b32_e32 v133, v142, v141, vcc
	v_cvt_f32_f16_sdwa v141, v134 dst_sel:DWORD dst_unused:UNUSED_PAD src0_sel:WORD_1
	v_cvt_f32_f16_e32 v134, v134
	v_and_b32_e32 v133, 0xffffff80, v133
	v_sub_u32_e32 v133, v133, v14
	v_not_b32_e32 v142, v141
	v_or_b32_e32 v143, 0x80000000, v141
	v_cmp_gt_i32_e32 vcc, 0, v141
	v_add_u32_e32 v140, 0x7e, v140
	v_add_u32_e32 v133, 0x7f, v133
	v_cndmask_b32_e32 v141, v143, v142, vcc
	v_not_b32_e32 v142, v134
	v_or_b32_e32 v143, 0x80000000, v134
	v_cmp_gt_i32_e32 vcc, 0, v134
	v_and_b32_e32 v141, 0xffffff80, v141
	v_sub_u32_e32 v141, v141, v12
	v_cndmask_b32_e32 v134, v143, v142, vcc
	v_cvt_f32_f16_sdwa v142, v135 dst_sel:DWORD dst_unused:UNUSED_PAD src0_sel:WORD_1
	v_cvt_f32_f16_e32 v135, v135
	v_and_b32_e32 v134, 0xffffff80, v134
	v_sub_u32_e32 v134, v134, v12
	v_not_b32_e32 v143, v142
	v_or_b32_e32 v144, 0x80000000, v142
	v_cmp_gt_i32_e32 vcc, 0, v142
	v_add_u32_e32 v141, 0x7e, v141
	v_add_u32_e32 v134, 0x7f, v134
	v_cndmask_b32_e32 v142, v144, v143, vcc
	v_not_b32_e32 v143, v135
	v_or_b32_e32 v144, 0x80000000, v135
	v_cmp_gt_i32_e32 vcc, 0, v135
	v_and_b32_e32 v142, 0xffffff80, v142
	v_sub_u32_e32 v142, v142, v10
	v_cndmask_b32_e32 v135, v144, v143, vcc
	v_cvt_f32_f16_sdwa v143, v128 dst_sel:DWORD dst_unused:UNUSED_PAD src0_sel:WORD_1
	v_cvt_f32_f16_e32 v128, v128
	v_and_b32_e32 v135, 0xffffff80, v135
	v_sub_u32_e32 v135, v135, v10
	v_not_b32_e32 v144, v143
	v_or_b32_e32 v145, 0x80000000, v143
	v_cmp_gt_i32_e32 vcc, 0, v143
	v_add_u32_e32 v142, 0x7e, v142
	v_add_u32_e32 v135, 0x7f, v135
	v_cndmask_b32_e32 v143, v145, v144, vcc
	v_not_b32_e32 v144, v128
	v_or_b32_e32 v145, 0x80000000, v128
	v_cmp_gt_i32_e32 vcc, 0, v128
	v_and_b32_e32 v143, 0xffffff80, v143
	v_sub_u32_e32 v143, v143, v8
	v_cndmask_b32_e32 v128, v145, v144, vcc
	v_cvt_f32_f16_sdwa v144, v129 dst_sel:DWORD dst_unused:UNUSED_PAD src0_sel:WORD_1
	v_cvt_f32_f16_e32 v129, v129
	v_and_b32_e32 v128, 0xffffff80, v128
	v_sub_u32_e32 v128, v128, v8
	v_not_b32_e32 v145, v144
	v_or_b32_e32 v146, 0x80000000, v144
	v_cmp_gt_i32_e32 vcc, 0, v144
	v_add_u32_e32 v143, 0x7e, v143
	v_add_u32_e32 v128, 0x7f, v128
	v_cndmask_b32_e32 v144, v146, v145, vcc
	v_not_b32_e32 v145, v129
	v_or_b32_e32 v146, 0x80000000, v129
	v_cmp_gt_i32_e32 vcc, 0, v129
	v_and_b32_e32 v144, 0xffffff80, v144
	v_sub_u32_e32 v144, v144, v16
	v_cndmask_b32_e32 v129, v146, v145, vcc
	v_cvt_f32_f16_sdwa v145, v130 dst_sel:DWORD dst_unused:UNUSED_PAD src0_sel:WORD_1
	v_cvt_f32_f16_e32 v130, v130
	v_and_b32_e32 v129, 0xffffff80, v129
	v_sub_u32_e32 v129, v129, v16
	v_not_b32_e32 v146, v145
	v_or_b32_e32 v147, 0x80000000, v145
	v_cmp_gt_i32_e32 vcc, 0, v145
	v_add_u32_e32 v144, 0x7e, v144
	v_add_u32_e32 v129, 0x7f, v129
	v_cndmask_b32_e32 v145, v147, v146, vcc
	v_not_b32_e32 v146, v130
	v_or_b32_e32 v147, 0x80000000, v130
	v_cmp_gt_i32_e32 vcc, 0, v130
	v_and_b32_e32 v145, 0xffffff80, v145
	v_sub_u32_e32 v145, v145, v17
	v_cndmask_b32_e32 v130, v147, v146, vcc
	v_cvt_f32_f16_sdwa v146, v131 dst_sel:DWORD dst_unused:UNUSED_PAD src0_sel:WORD_1
	v_cvt_f32_f16_e32 v131, v131
	v_and_b32_e32 v130, 0xffffff80, v130
	v_sub_u32_e32 v130, v130, v17
	v_not_b32_e32 v147, v146
	v_or_b32_e32 v148, 0x80000000, v146
	v_cmp_gt_i32_e32 vcc, 0, v146
	v_add_u32_e32 v145, 0x7e, v145
	v_add_u32_e32 v130, 0x7f, v130
	v_cndmask_b32_e32 v146, v148, v147, vcc
	v_not_b32_e32 v147, v131
	v_or_b32_e32 v148, 0x80000000, v131
	v_cmp_gt_i32_e32 vcc, 0, v131
	v_and_b32_e32 v146, 0xffffff80, v146
	v_sub_u32_e32 v146, v146, v18
	v_cndmask_b32_e32 v131, v148, v147, vcc
	s_waitcnt vmcnt(0)
; __device__ __forceinline__ unsigned f2key(float f) { const unsigned u = __float_as_uint(f); return (u & 0x80000000u) ? ~u : (u | 0x80000000u); }
; #define CE_DESC(a, b) do { const unsigned _mx = (a) > (b) ? (a) : (b), _mn = (a) > (b) ? (b) : (a); (a) = _mx; (b) = _mn; } while (0)
; __device__ __forceinline__ void sort16_desc(unsigned (&k)[16]) {
; #pragma unroll
;     for (int size = 2; size <= 16; size <<= 1)
; #pragma unroll
;         for (int stride = size >> 1; stride > 0; stride >>= 1)
; #pragma unroll
;             for (int i = 0; i < 16; ++i) { const int j = i ^ stride;
;                 if (j > i) { if ((i & size) == 0) CE_DESC(k[i], k[j]); else CE_DESC(k[j], k[i]); } }
; }
; __device__ __forceinline__ void peer_tile(const Args& A, LAS unsigned char* lds, int tile) {
;     ...
;                 { const bf16_t* sp = QRY + m * 2048 + hp * 128 + 32 * g;
;                   const u32x4 s0 = *(const u32x4*)sp, s1 = *(const u32x4*)(sp + 8), s2 = *(const u32x4*)(sp + 16), s3 = *(const u32x4*)(sp + 24);
;                   const unsigned sw[16] = {s0.x, s0.y, s0.z, s0.w, s1.x, s1.y, s1.z, s1.w, s2.x, s2.y, s2.z, s2.w, s3.x, s3.y, s3.z, s3.w};
; #pragma unroll
;                   for (int i = 0; i < 16; ++i) {
;                       const float lo = (float)__builtin_bit_cast(_Float16, (unsigned short)(sw[i] & 0xffffu)), hi = (float)__builtin_bit_cast(_Float16, (unsigned short)(sw[i] >> 16));
;                       const unsigned klo = (f2key(lo) & ~127u) | (unsigned)(127 - (32 * g + 2 * i)), khi = (f2key(hi) & ~127u) | (unsigned)(127 - (32 * g + 2 * i + 1));
;                       if (i < 8) { k0[2 * i] = klo; k0[2 * i + 1] = khi; } else { k1[2 * (i - 8)] = klo; k1[2 * (i - 8) + 1] = khi; } } }
	v_cvt_f32_f16_sdwa v147, v136 dst_sel:DWORD dst_unused:UNUSED_PAD src0_sel:WORD_1
	v_cvt_f32_f16_e32 v136, v136
	v_and_b32_e32 v131, 0xffffff80, v131
	v_sub_u32_e32 v131, v131, v18
	v_not_b32_e32 v148, v147
	v_or_b32_e32 v149, 0x80000000, v147
	v_cmp_gt_i32_e32 vcc, 0, v147
	v_add_u32_e32 v146, 0x7e, v146
	v_add_u32_e32 v131, 0x7f, v131
	v_cndmask_b32_e32 v147, v149, v148, vcc
	v_not_b32_e32 v148, v136
	v_or_b32_e32 v149, 0x80000000, v136
	v_cmp_gt_i32_e32 vcc, 0, v136
	v_and_b32_e32 v147, 0xffffff80, v147
	v_sub_u32_e32 v147, v147, v20
	v_cndmask_b32_e32 v136, v149, v148, vcc
	v_cvt_f32_f16_sdwa v148, v137 dst_sel:DWORD dst_unused:UNUSED_PAD src0_sel:WORD_1
	v_cvt_f32_f16_e32 v137, v137
	v_and_b32_e32 v136, 0xffffff80, v136
	v_sub_u32_e32 v136, v136, v20
	v_not_b32_e32 v149, v148
	v_or_b32_e32 v150, 0x80000000, v148
	v_cmp_gt_i32_e32 vcc, 0, v148
	v_add_u32_e32 v147, 0x7e, v147
	v_add_u32_e32 v136, 0x7f, v136
	v_cndmask_b32_e32 v148, v150, v149, vcc
	v_not_b32_e32 v149, v137
	v_or_b32_e32 v150, 0x80000000, v137
	v_cmp_gt_i32_e32 vcc, 0, v137
	v_and_b32_e32 v148, 0xffffff80, v148
	v_sub_u32_e32 v148, v148, v21
	v_cndmask_b32_e32 v137, v150, v149, vcc
	v_cvt_f32_f16_sdwa v149, v138 dst_sel:DWORD dst_unused:UNUSED_PAD src0_sel:WORD_1
	v_cvt_f32_f16_e32 v138, v138
	v_and_b32_e32 v137, 0xffffff80, v137
	v_sub_u32_e32 v137, v137, v21
	v_not_b32_e32 v150, v149
	v_or_b32_e32 v151, 0x80000000, v149
	v_cmp_gt_i32_e32 vcc, 0, v149
	v_add_u32_e32 v148, 0x7e, v148
	v_add_u32_e32 v137, 0x7f, v137
	v_cndmask_b32_e32 v149, v151, v150, vcc
	v_not_b32_e32 v150, v138
	v_or_b32_e32 v151, 0x80000000, v138
	v_cmp_gt_i32_e32 vcc, 0, v138
	v_and_b32_e32 v149, 0xffffff80, v149
	v_sub_u32_e32 v149, v149, v22
	v_cndmask_b32_e32 v138, v151, v150, vcc
	v_cvt_f32_f16_sdwa v150, v139 dst_sel:DWORD dst_unused:UNUSED_PAD src0_sel:WORD_1
	v_cvt_f32_f16_e32 v139, v139
	v_and_b32_e32 v138, 0xffffff80, v138
	v_sub_u32_e32 v138, v138, v22
	v_not_b32_e32 v151, v150
	v_or_b32_e32 v152, 0x80000000, v150
	v_cmp_gt_i32_e32 vcc, 0, v150
	v_add_u32_e32 v149, 0x7e, v149
	v_add_u32_e32 v138, 0x7f, v138
	v_cndmask_b32_e32 v150, v152, v151, vcc
	v_not_b32_e32 v151, v139
	v_or_b32_e32 v152, 0x80000000, v139
	v_cmp_gt_i32_e32 vcc, 0, v139
	v_and_b32_e32 v150, 0xffffff80, v150
	v_sub_u32_e32 v150, v150, v23
	v_cndmask_b32_e32 v139, v152, v151, vcc
	v_cvt_f32_f16_sdwa v151, v0 dst_sel:DWORD dst_unused:UNUSED_PAD src0_sel:WORD_1
	v_cvt_f32_f16_e32 v0, v0
	v_and_b32_e32 v139, 0xffffff80, v139
	v_sub_u32_e32 v139, v139, v23
	v_not_b32_e32 v152, v151
	v_or_b32_e32 v153, 0x80000000, v151
	v_cmp_gt_i32_e32 vcc, 0, v151
	v_add_u32_e32 v150, 0x7e, v150
	v_add_u32_e32 v139, 0x7f, v139
	v_cndmask_b32_e32 v151, v153, v152, vcc
	v_not_b32_e32 v152, v0
	v_or_b32_e32 v153, 0x80000000, v0
	v_cmp_gt_i32_e32 vcc, 0, v0
	v_and_b32_e32 v151, 0xffffff80, v151
	v_sub_u32_e32 v151, v151, v24
	v_cndmask_b32_e32 v0, v153, v152, vcc
	v_cvt_f32_f16_sdwa v152, v1 dst_sel:DWORD dst_unused:UNUSED_PAD src0_sel:WORD_1
	v_cvt_f32_f16_e32 v1, v1
	v_and_b32_e32 v0, 0xffffff80, v0
	v_sub_u32_e32 v0, v0, v24
	v_not_b32_e32 v153, v152
	v_or_b32_e32 v154, 0x80000000, v152
	v_cmp_gt_i32_e32 vcc, 0, v152
	v_add_u32_e32 v151, 0x7e, v151
	v_add_u32_e32 v0, 0x7f, v0
	v_cndmask_b32_e32 v152, v154, v153, vcc
	v_not_b32_e32 v153, v1
	v_or_b32_e32 v154, 0x80000000, v1
	v_cmp_gt_i32_e32 vcc, 0, v1
	v_and_b32_e32 v152, 0xffffff80, v152
	v_sub_u32_e32 v152, v152, v25
	v_cndmask_b32_e32 v1, v154, v153, vcc
	v_cvt_f32_f16_sdwa v153, v2 dst_sel:DWORD dst_unused:UNUSED_PAD src0_sel:WORD_1
	v_cvt_f32_f16_e32 v2, v2
	v_and_b32_e32 v1, 0xffffff80, v1
	v_sub_u32_e32 v1, v1, v25
	v_not_b32_e32 v154, v153
	v_or_b32_e32 v155, 0x80000000, v153
	v_cmp_gt_i32_e32 vcc, 0, v153
	v_add_u32_e32 v152, 0x7e, v152
	v_add_u32_e32 v1, 0x7f, v1
	v_cndmask_b32_e32 v153, v155, v154, vcc
	v_not_b32_e32 v154, v2
	v_or_b32_e32 v155, 0x80000000, v2
	v_cmp_gt_i32_e32 vcc, 0, v2
	v_and_b32_e32 v153, 0xffffff80, v153
	v_sub_u32_e32 v153, v153, v26
	v_cndmask_b32_e32 v2, v155, v154, vcc
	v_cvt_f32_f16_sdwa v154, v3 dst_sel:DWORD dst_unused:UNUSED_PAD src0_sel:WORD_1
	v_cvt_f32_f16_e32 v3, v3
	v_and_b32_e32 v2, 0xffffff80, v2
	v_sub_u32_e32 v2, v2, v26
	v_not_b32_e32 v155, v154
	v_or_b32_e32 v156, 0x80000000, v154
	v_cmp_gt_i32_e32 vcc, 0, v154
	v_add_u32_e32 v153, 0x7e, v153
	v_add_u32_e32 v2, 0x7f, v2
	v_cndmask_b32_e32 v154, v156, v155, vcc
	v_not_b32_e32 v155, v3
	v_or_b32_e32 v156, 0x80000000, v3
	v_cmp_gt_i32_e32 vcc, 0, v3
	v_and_b32_e32 v154, 0xffffff80, v154
	v_sub_u32_e32 v154, v154, v28
	v_cndmask_b32_e32 v3, v156, v155, vcc
	v_and_b32_e32 v3, 0xffffff80, v3
	v_sub_u32_e32 v3, v3, v28
	v_add_u32_e32 v154, 0x7e, v154
	v_add_u32_e32 v3, 0x7f, v3
	v_max_u32_e32 v155, v132, v127
	v_min_u32_e32 v127, v132, v127
	v_max_u32_e32 v132, v140, v133
	v_min_u32_e32 v133, v140, v133
	v_max_u32_e32 v140, v134, v141
	v_min_u32_e32 v134, v134, v141
	v_max_u32_e32 v141, v142, v135
	v_min_u32_e32 v135, v142, v135
	v_max_u32_e32 v142, v128, v143
	v_min_u32_e32 v128, v128, v143
	v_max_u32_e32 v143, v144, v129
	v_min_u32_e32 v129, v144, v129
	v_max_u32_e32 v144, v130, v145
	v_min_u32_e32 v130, v130, v145
	v_max_u32_e32 v145, v146, v131
	v_min_u32_e32 v131, v146, v131
	v_max_u32_e32 v163, v136, v147
	v_min_u32_e32 v136, v136, v147
	v_max_u32_e32 v147, v148, v137
	v_min_u32_e32 v137, v148, v137
	v_max_u32_e32 v148, v138, v149
	v_min_u32_e32 v138, v138, v149
	v_max_u32_e32 v149, v150, v139
	v_min_u32_e32 v139, v150, v139
	v_max_u32_e32 v150, v0, v151
	v_min_u32_e32 v0, v0, v151
	v_max_u32_e32 v151, v152, v1
	v_min_u32_e32 v1, v152, v1
	v_max_u32_e32 v152, v2, v153
	v_min_u32_e32 v2, v2, v153
; #define CE_DESC(a, b) do { const unsigned _mx = (a) > (b) ? (a) : (b), _mn = (a) > (b) ? (b) : (a); (a) = _mx; (b) = _mn; } while (0)
; __device__ __forceinline__ void sort16_desc(unsigned (&k)[16]) {
; #pragma unroll
;     for (int size = 2; size <= 16; size <<= 1)
; #pragma unroll
;         for (int stride = size >> 1; stride > 0; stride >>= 1)
; #pragma unroll
;             for (int i = 0; i < 16; ++i) { const int j = i ^ stride;
;                 if (j > i) { if ((i & size) == 0) CE_DESC(k[i], k[j]); else CE_DESC(k[j], k[i]); } }
; }
	v_max_u32_e32 v153, v154, v3
	v_min_u32_e32 v3, v154, v3
	v_max_u32_e32 v146, v155, v133
	v_min_u32_e32 v133, v155, v133
	v_max_u32_e32 v155, v127, v132
	v_min_u32_e32 v127, v127, v132
	v_max_u32_e32 v132, v135, v140
	v_min_u32_e32 v135, v135, v140
	v_max_u32_e32 v140, v141, v134
	v_min_u32_e32 v134, v141, v134
	v_max_u32_e32 v141, v142, v129
	v_min_u32_e32 v129, v142, v129
	v_max_u32_e32 v142, v128, v143
	v_min_u32_e32 v128, v128, v143
	v_max_u32_e32 v143, v131, v144
	v_min_u32_e32 v131, v131, v144
	v_max_u32_e32 v144, v145, v130
	v_min_u32_e32 v130, v145, v130
	v_max_u32_e32 v154, v163, v137
	v_min_u32_e32 v137, v163, v137
	v_max_u32_e32 v163, v136, v147
	v_min_u32_e32 v136, v136, v147
	v_max_u32_e32 v147, v139, v148
	v_min_u32_e32 v139, v139, v148
	v_max_u32_e32 v148, v149, v138
	v_min_u32_e32 v138, v149, v138
	v_max_u32_e32 v149, v150, v1
	v_min_u32_e32 v1, v150, v1
	v_max_u32_e32 v150, v0, v151
	v_min_u32_e32 v0, v0, v151
	v_max_u32_e32 v151, v3, v152
	v_min_u32_e32 v3, v3, v152
	v_max_u32_e32 v152, v153, v2
	v_min_u32_e32 v2, v153, v2
	v_max_u32_e32 v145, v146, v155
	v_min_u32_e32 v146, v146, v155
	v_max_u32_e32 v155, v133, v127
	v_min_u32_e32 v127, v133, v127
	v_max_u32_e32 v133, v134, v135
	v_min_u32_e32 v134, v134, v135
	v_max_u32_e32 v135, v140, v132
	v_min_u32_e32 v132, v140, v132
	v_max_u32_e32 v140, v141, v142
	v_min_u32_e32 v141, v141, v142
	v_max_u32_e32 v142, v129, v128
	v_min_u32_e32 v128, v129, v128
	v_max_u32_e32 v129, v130, v131
	v_min_u32_e32 v130, v130, v131
	v_max_u32_e32 v131, v144, v143
	v_min_u32_e32 v143, v144, v143
	v_max_u32_e32 v153, v154, v163
	v_min_u32_e32 v154, v154, v163
	v_max_u32_e32 v163, v137, v136
	v_min_u32_e32 v136, v137, v136
	v_max_u32_e32 v137, v138, v139
	v_min_u32_e32 v138, v138, v139
	v_max_u32_e32 v139, v148, v147
	v_min_u32_e32 v147, v148, v147
	v_max_u32_e32 v148, v149, v150
	v_min_u32_e32 v149, v149, v150
	v_max_u32_e32 v150, v1, v0
	v_min_u32_e32 v0, v1, v0
	v_max_u32_e32 v1, v2, v3
	v_min_u32_e32 v2, v2, v3
	v_max_u32_e32 v3, v152, v151
	v_min_u32_e32 v151, v152, v151
	v_max_u32_e32 v144, v145, v134
	v_min_u32_e32 v134, v145, v134
	v_max_u32_e32 v145, v146, v133
	v_min_u32_e32 v133, v146, v133
	v_max_u32_e32 v146, v155, v132
	v_min_u32_e32 v132, v155, v132
	v_max_u32_e32 v155, v127, v135
	v_min_u32_e32 v127, v127, v135
	v_max_u32_e32 v135, v130, v140
	v_min_u32_e32 v130, v130, v140
	v_max_u32_e32 v140, v129, v141
	v_min_u32_e32 v129, v129, v141
	v_max_u32_e32 v141, v143, v142
	v_min_u32_e32 v142, v143, v142
	v_max_u32_e32 v143, v131, v128
	v_min_u32_e32 v128, v131, v128
	v_max_u32_e32 v152, v153, v138
	v_min_u32_e32 v138, v153, v138
	v_max_u32_e32 v153, v154, v137
	v_min_u32_e32 v137, v154, v137
	v_max_u32_e32 v154, v163, v147
	v_min_u32_e32 v147, v163, v147
	v_max_u32_e32 v163, v136, v139
	v_min_u32_e32 v136, v136, v139
	v_max_u32_e32 v139, v2, v148
	v_min_u32_e32 v2, v2, v148
	v_max_u32_e32 v148, v1, v149
	v_min_u32_e32 v1, v1, v149
	v_max_u32_e32 v149, v151, v150
	v_min_u32_e32 v150, v151, v150
	v_max_u32_e32 v151, v3, v0
	v_min_u32_e32 v0, v3, v0
	v_max_u32_e32 v131, v144, v146
	v_min_u32_e32 v144, v144, v146
	v_max_u32_e32 v146, v145, v155
	v_min_u32_e32 v145, v145, v155
	v_max_u32_e32 v155, v134, v132
	v_min_u32_e32 v132, v134, v132
	v_max_u32_e32 v134, v133, v127
	v_min_u32_e32 v127, v133, v127
	v_max_u32_e32 v133, v142, v130
	v_min_u32_e32 v130, v142, v130
	v_max_u32_e32 v142, v128, v129
	v_min_u32_e32 v128, v128, v129
	v_max_u32_e32 v129, v141, v135
	v_min_u32_e32 v135, v141, v135
	v_max_u32_e32 v141, v143, v140
	v_min_u32_e32 v140, v143, v140
	v_max_u32_e32 v3, v152, v154
	v_min_u32_e32 v152, v152, v154
	v_max_u32_e32 v154, v153, v163
	v_min_u32_e32 v153, v153, v163
	v_max_u32_e32 v163, v138, v147
	v_min_u32_e32 v138, v138, v147
	v_max_u32_e32 v147, v137, v136
	v_min_u32_e32 v136, v137, v136
	v_max_u32_e32 v137, v150, v2
	v_min_u32_e32 v2, v150, v2
	v_max_u32_e32 v150, v0, v1
	v_min_u32_e32 v0, v0, v1
	v_max_u32_e32 v1, v149, v139
	v_min_u32_e32 v139, v149, v139
	v_max_u32_e32 v149, v151, v148
	v_min_u32_e32 v148, v151, v148
	v_max_u32_e32 v143, v131, v146
	v_min_u32_e32 v131, v131, v146
	v_max_u32_e32 v146, v144, v145
	v_min_u32_e32 v144, v144, v145
	v_max_u32_e32 v145, v155, v134
	v_min_u32_e32 v134, v155, v134
	v_max_u32_e32 v155, v132, v127
	v_min_u32_e32 v127, v132, v127
	v_max_u32_e32 v132, v128, v130
	v_min_u32_e32 v128, v128, v130
	v_max_u32_e32 v130, v142, v133
	v_min_u32_e32 v133, v142, v133
	v_max_u32_e32 v142, v140, v135
	v_min_u32_e32 v135, v140, v135
	v_max_u32_e32 v140, v141, v129
	v_min_u32_e32 v129, v141, v129
	v_max_u32_e32 v151, v3, v154
	v_min_u32_e32 v3, v3, v154
	v_max_u32_e32 v154, v152, v153
	v_min_u32_e32 v152, v152, v153
	v_max_u32_e32 v153, v163, v147
	v_min_u32_e32 v147, v163, v147
	v_max_u32_e32 v163, v138, v136
	v_min_u32_e32 v136, v138, v136
	v_max_u32_e32 v138, v0, v2
	v_min_u32_e32 v0, v0, v2
	v_max_u32_e32 v2, v150, v137
	v_min_u32_e32 v137, v150, v137
	v_max_u32_e32 v150, v148, v139
	v_min_u32_e32 v139, v148, v139
	v_max_u32_e32 v148, v149, v1
	v_min_u32_e32 v1, v149, v1
	v_max_u32_e32 v141, v143, v128
	v_min_u32_e32 v128, v143, v128
	v_max_u32_e32 v143, v131, v132
	v_min_u32_e32 v131, v131, v132
	v_max_u32_e32 v132, v146, v133
	v_min_u32_e32 v133, v146, v133
	v_max_u32_e32 v146, v144, v130
	v_min_u32_e32 v130, v144, v130
	v_max_u32_e32 v144, v145, v135
	v_min_u32_e32 v135, v145, v135
	v_max_u32_e32 v145, v134, v142
	v_min_u32_e32 v134, v134, v142
	v_max_u32_e32 v142, v155, v129
	v_min_u32_e32 v129, v155, v129
	v_max_u32_e32 v155, v127, v140
	v_min_u32_e32 v127, v127, v140
	v_max_u32_e32 v149, v151, v0
	v_min_u32_e32 v0, v151, v0
; #define CE_DESC(a, b) do { const unsigned _mx = (a) > (b) ? (a) : (b), _mn = (a) > (b) ? (b) : (a); (a) = _mx; (b) = _mn; } while (0)
; __device__ __forceinline__ void sort16_desc(unsigned (&k)[16]) {
; #pragma unroll
;     for (int size = 2; size <= 16; size <<= 1)
; #pragma unroll
;         for (int stride = size >> 1; stride > 0; stride >>= 1)
; #pragma unroll
;             for (int i = 0; i < 16; ++i) { const int j = i ^ stride;
;                 if (j > i) { if ((i & size) == 0) CE_DESC(k[i], k[j]); else CE_DESC(k[j], k[i]); } }
; }
; __device__ __forceinline__ void merge16(unsigned (&a)[16], const unsigned (&b)[16]) {
; #pragma unroll
;     for (int i = 0; i < 16; ++i) a[i] = a[i] > b[15 - i] ? a[i] : b[15 - i];
; #pragma unroll
;     for (int stride = 8; stride > 0; stride >>= 1)
; #pragma unroll
;         for (int i = 0; i < 16; ++i) { const int j = i ^ stride; if (j > i) CE_DESC(a[i], a[j]); }
; }
; __device__ __forceinline__ void peer_tile(const Args& A, LAS unsigned char* lds, int tile) {
;     ...
;                 for (int msk = 16; msk <= 32; msk <<= 1) {
; #pragma unroll
;                     for (int i = 0; i < 16; ++i) k1[i] = (unsigned)__shfl_xor((int)k0[i], msk);
;                     merge16(k0, k1); }
	v_max_u32_e32 v151, v3, v138
	v_min_u32_e32 v3, v3, v138
	v_max_u32_e32 v138, v154, v137
	v_min_u32_e32 v137, v154, v137
	v_max_u32_e32 v154, v152, v2
	v_min_u32_e32 v2, v152, v2
	v_max_u32_e32 v152, v153, v139
	v_min_u32_e32 v139, v153, v139
	v_max_u32_e32 v153, v147, v150
	v_min_u32_e32 v147, v147, v150
	v_max_u32_e32 v150, v163, v1
	v_min_u32_e32 v1, v163, v1
	v_max_u32_e32 v163, v136, v148
	v_min_u32_e32 v136, v136, v148
	v_max_u32_e32 v140, v141, v144
	v_min_u32_e32 v141, v141, v144
	v_max_u32_e32 v144, v143, v145
	v_min_u32_e32 v143, v143, v145
	v_max_u32_e32 v145, v132, v142
	v_min_u32_e32 v132, v132, v142
	v_max_u32_e32 v142, v146, v155
	v_min_u32_e32 v146, v146, v155
	v_max_u32_e32 v155, v128, v135
	v_min_u32_e32 v128, v128, v135
	v_max_u32_e32 v135, v131, v134
	v_min_u32_e32 v131, v131, v134
	v_max_u32_e32 v134, v133, v129
	v_min_u32_e32 v129, v133, v129
	v_max_u32_e32 v133, v130, v127
	v_min_u32_e32 v127, v130, v127
	v_max_u32_e32 v148, v149, v152
	v_min_u32_e32 v149, v149, v152
	v_max_u32_e32 v152, v151, v153
	v_min_u32_e32 v151, v151, v153
	v_max_u32_e32 v153, v138, v150
	v_min_u32_e32 v138, v138, v150
	v_max_u32_e32 v150, v154, v163
	v_min_u32_e32 v154, v154, v163
	v_max_u32_e32 v163, v0, v139
	v_min_u32_e32 v0, v0, v139
	v_max_u32_e32 v139, v3, v147
	v_min_u32_e32 v3, v3, v147
	v_max_u32_e32 v147, v137, v1
	v_min_u32_e32 v1, v137, v1
	v_max_u32_e32 v137, v2, v136
	v_min_u32_e32 v2, v2, v136
	v_max_u32_e32 v130, v140, v145
	v_min_u32_e32 v140, v140, v145
	v_max_u32_e32 v145, v144, v142
	v_min_u32_e32 v142, v144, v142
	v_max_u32_e32 v144, v141, v132
	v_min_u32_e32 v132, v141, v132
	v_max_u32_e32 v141, v143, v146
	v_min_u32_e32 v143, v143, v146
	v_max_u32_e32 v146, v155, v134
	v_min_u32_e32 v134, v155, v134
	v_max_u32_e32 v155, v135, v133
	v_min_u32_e32 v133, v135, v133
	v_max_u32_e32 v135, v128, v129
	v_min_u32_e32 v128, v128, v129
	v_max_u32_e32 v129, v131, v127
	v_min_u32_e32 v127, v131, v127
	v_max_u32_e32 v136, v148, v153
	v_min_u32_e32 v148, v148, v153
	v_max_u32_e32 v153, v152, v150
	v_min_u32_e32 v150, v152, v150
	v_max_u32_e32 v152, v149, v138
	v_min_u32_e32 v138, v149, v138
	v_max_u32_e32 v149, v151, v154
	v_min_u32_e32 v151, v151, v154
	v_max_u32_e32 v154, v163, v147
	v_min_u32_e32 v147, v163, v147
	v_max_u32_e32 v163, v139, v137
	v_min_u32_e32 v137, v139, v137
	v_max_u32_e32 v139, v0, v1
	v_min_u32_e32 v0, v0, v1
	v_max_u32_e32 v1, v3, v2
	v_min_u32_e32 v2, v3, v2
	v_min_u32_e32 v131, v130, v145
	v_min_u32_e32 v156, v140, v142
	v_min_u32_e32 v157, v144, v141
	v_min_u32_e32 v158, v132, v143
	v_min_u32_e32 v159, v146, v155
	v_min_u32_e32 v160, v134, v133
	v_min_u32_e32 v161, v135, v129
	v_min_u32_e32 v162, v128, v127
	v_min_u32_e32 v3, v136, v153
	v_min_u32_e32 v164, v148, v150
	v_min_u32_e32 v165, v152, v149
	v_min_u32_e32 v166, v138, v151
	v_min_u32_e32 v167, v154, v163
	v_min_u32_e32 v168, v147, v137
	v_min_u32_e32 v169, v139, v1
	v_min_u32_e32 v170, v0, v2
	v_max3_u32 v130, v130, v145, v170
	v_max3_u32 v0, v131, v0, v2
	v_max3_u32 v2, v140, v142, v169
	v_max3_u32 v1, v156, v139, v1
	v_max3_u32 v131, v144, v141, v168
	v_max3_u32 v137, v157, v147, v137
	v_max3_u32 v132, v132, v143, v167
	v_max3_u32 v139, v158, v154, v163
	v_max3_u32 v140, v146, v155, v166
	v_max3_u32 v138, v159, v138, v151
	v_max3_u32 v133, v134, v133, v165
	v_max3_u32 v134, v160, v152, v149
	v_max3_u32 v129, v135, v129, v164
	v_max3_u32 v135, v161, v148, v150
	v_max3_u32 v3, v128, v127, v3
	v_max3_u32 v127, v162, v136, v153
	v_max_u32_e32 v128, v130, v140
	v_min_u32_e32 v130, v130, v140
	v_max_u32_e32 v136, v0, v138
	v_min_u32_e32 v0, v0, v138
	v_max_u32_e32 v138, v2, v133
	v_min_u32_e32 v2, v2, v133
	v_max_u32_e32 v133, v1, v134
	v_min_u32_e32 v1, v1, v134
	v_max_u32_e32 v134, v131, v129
	v_min_u32_e32 v129, v131, v129
	v_max_u32_e32 v131, v137, v135
	v_min_u32_e32 v135, v137, v135
	v_max_u32_e32 v137, v132, v3
	v_min_u32_e32 v3, v132, v3
	v_max_u32_e32 v132, v139, v127
	v_min_u32_e32 v127, v139, v127
	v_max_u32_e32 v139, v128, v134
	v_min_u32_e32 v128, v128, v134
	v_max_u32_e32 v134, v136, v131
	v_min_u32_e32 v131, v136, v131
	v_max_u32_e32 v136, v138, v137
	v_min_u32_e32 v137, v138, v137
	v_max_u32_e32 v138, v133, v132
	v_min_u32_e32 v132, v133, v132
	v_max_u32_e32 v133, v130, v129
	v_min_u32_e32 v129, v130, v129
	v_max_u32_e32 v130, v0, v135
	v_min_u32_e32 v0, v0, v135
	v_max_u32_e32 v135, v2, v3
	v_min_u32_e32 v2, v2, v3
	v_max_u32_e32 v3, v1, v127
	v_min_u32_e32 v1, v1, v127
	v_max_u32_e32 v127, v139, v136
	v_min_u32_e32 v136, v139, v136
	v_max_u32_e32 v139, v134, v138
	v_min_u32_e32 v134, v134, v138
	v_max_u32_e32 v138, v128, v137
	v_min_u32_e32 v128, v128, v137
	v_max_u32_e32 v137, v131, v132
	v_min_u32_e32 v131, v131, v132
	v_max_u32_e32 v132, v133, v135
	v_min_u32_e32 v133, v133, v135
	v_max_u32_e32 v135, v130, v3
	v_min_u32_e32 v3, v130, v3
	v_max_u32_e32 v130, v129, v2
	v_min_u32_e32 v2, v129, v2
	v_max_u32_e32 v129, v0, v1
	v_min_u32_e32 v0, v0, v1
	v_max_u32_e32 v1, v127, v139
	v_min_u32_e32 v127, v127, v139
	v_max_u32_e32 v139, v136, v134
	v_min_u32_e32 v134, v136, v134
	v_max_u32_e32 v136, v138, v137
	v_min_u32_e32 v137, v138, v137
	v_max_u32_e32 v138, v128, v131
	v_min_u32_e32 v128, v128, v131
	v_max_u32_e32 v131, v132, v135
	v_min_u32_e32 v132, v132, v135
	v_max_u32_e32 v135, v133, v3
	v_min_u32_e32 v3, v133, v3
	v_max_u32_e32 v133, v130, v129
	v_min_u32_e32 v129, v130, v129
	v_max_u32_e32 v130, v2, v0
	v_min_u32_e32 v0, v2, v0
	ds_bpermute_b32 v2, v27, v1
	ds_bpermute_b32 v140, v27, v127
	ds_bpermute_b32 v141, v27, v139
	ds_bpermute_b32 v142, v27, v134
	ds_bpermute_b32 v143, v27, v136
	ds_bpermute_b32 v144, v27, v137
	ds_bpermute_b32 v145, v27, v138
	ds_bpermute_b32 v146, v27, v128
	ds_bpermute_b32 v147, v27, v131
	ds_bpermute_b32 v148, v27, v132
	ds_bpermute_b32 v149, v27, v135
	ds_bpermute_b32 v150, v27, v0
	ds_bpermute_b32 v151, v27, v130
	ds_bpermute_b32 v152, v27, v129
	ds_bpermute_b32 v153, v27, v133
	ds_bpermute_b32 v154, v27, v3
	s_waitcnt lgkmcnt(4)
; #define CE_DESC(a, b) do { const unsigned _mx = (a) > (b) ? (a) : (b), _mn = (a) > (b) ? (b) : (a); (a) = _mx; (b) = _mn; } while (0)
; __device__ __forceinline__ void merge16(unsigned (&a)[16], const unsigned (&b)[16]) {
; #pragma unroll
;     for (int i = 0; i < 16; ++i) a[i] = a[i] > b[15 - i] ? a[i] : b[15 - i];
; #pragma unroll
;     for (int stride = 8; stride > 0; stride >>= 1)
; #pragma unroll
;         for (int i = 0; i < 16; ++i) { const int j = i ^ stride; if (j > i) CE_DESC(a[i], a[j]); }
; }
; __device__ __forceinline__ void peer_tile(const Args& A, LAS unsigned char* lds, int tile) {
;     ...
;                 { const bf16_t* sp = QRY + m * 2048 + hp * 128 + 32 * g;
;                   const u32x4 s0 = *(const u32x4*)sp, s1 = *(const u32x4*)(sp + 8), s2 = *(const u32x4*)(sp + 16), s3 = *(const u32x4*)(sp + 24);
;     ...
;                 for (int msk = 16; msk <= 32; msk <<= 1) {
; #pragma unroll
;                     for (int i = 0; i < 16; ++i) k1[i] = (unsigned)__shfl_xor((int)k0[i], msk);
;                     merge16(k0, k1); }
	v_max_u32_e32 v1, v1, v150
	s_waitcnt lgkmcnt(3)
	v_max_u32_e32 v127, v127, v151
	s_waitcnt lgkmcnt(2)
	v_max_u32_e32 v139, v139, v152
	s_waitcnt lgkmcnt(1)
	v_max_u32_e32 v134, v134, v153
	s_waitcnt lgkmcnt(0)
	v_max_u32_e32 v136, v136, v154
	v_max_u32_e32 v137, v137, v149
	v_max_u32_e32 v138, v138, v148
	v_max_u32_e32 v128, v128, v147
	v_max_u32_e32 v131, v131, v146
	v_max_u32_e32 v132, v132, v145
	v_max_u32_e32 v135, v135, v144
	v_max_u32_e32 v3, v3, v143
	v_max_u32_e32 v133, v133, v142
	v_max_u32_e32 v129, v129, v141
	v_max_u32_e32 v130, v130, v140
	v_max_u32_e32 v0, v0, v2
	v_max_u32_e32 v2, v1, v131
	v_min_u32_e32 v1, v1, v131
	v_max_u32_e32 v131, v127, v132
	v_min_u32_e32 v127, v127, v132
	v_max_u32_e32 v132, v139, v135
	v_min_u32_e32 v135, v139, v135
	v_max_u32_e32 v139, v134, v3
	v_min_u32_e32 v3, v134, v3
	v_max_u32_e32 v134, v136, v133
	v_min_u32_e32 v133, v136, v133
	v_max_u32_e32 v136, v137, v129
	v_min_u32_e32 v129, v137, v129
	v_max_u32_e32 v137, v138, v130
	v_min_u32_e32 v130, v138, v130
	v_max_u32_e32 v138, v128, v0
	v_min_u32_e32 v0, v128, v0
	v_max_u32_e32 v128, v2, v134
	v_min_u32_e32 v2, v2, v134
	v_max_u32_e32 v134, v131, v136
	v_min_u32_e32 v131, v131, v136
	v_max_u32_e32 v136, v132, v137
	v_min_u32_e32 v132, v132, v137
	v_max_u32_e32 v137, v139, v138
	v_min_u32_e32 v138, v139, v138
	v_max_u32_e32 v139, v1, v133
	v_min_u32_e32 v1, v1, v133
	v_max_u32_e32 v133, v127, v129
	v_min_u32_e32 v127, v127, v129
	v_max_u32_e32 v129, v135, v130
	v_min_u32_e32 v130, v135, v130
	v_max_u32_e32 v135, v3, v0
	v_min_u32_e32 v0, v3, v0
	v_max_u32_e32 v3, v128, v136
	v_min_u32_e32 v128, v128, v136
	v_max_u32_e32 v136, v134, v137
	v_min_u32_e32 v134, v134, v137
	v_max_u32_e32 v137, v2, v132
	v_min_u32_e32 v2, v2, v132
	v_max_u32_e32 v132, v131, v138
	v_min_u32_e32 v131, v131, v138
	v_max_u32_e32 v138, v139, v129
	v_min_u32_e32 v129, v139, v129
	v_max_u32_e32 v139, v133, v135
	v_min_u32_e32 v133, v133, v135
	v_max_u32_e32 v135, v1, v130
	v_min_u32_e32 v1, v1, v130
	v_max_u32_e32 v130, v127, v0
	v_min_u32_e32 v0, v127, v0
	v_max_u32_e32 v127, v3, v136
	v_min_u32_e32 v3, v3, v136
	v_max_u32_e32 v136, v128, v134
	v_min_u32_e32 v128, v128, v134
	v_max_u32_e32 v134, v137, v132
	v_min_u32_e32 v132, v137, v132
	v_max_u32_e32 v137, v2, v131
	v_min_u32_e32 v2, v2, v131
	v_max_u32_e32 v131, v138, v139
	v_min_u32_e32 v138, v138, v139
	v_max_u32_e32 v139, v129, v133
	v_min_u32_e32 v129, v129, v133
	v_max_u32_e32 v133, v135, v130
	v_min_u32_e32 v130, v135, v130
	v_max_u32_e32 v135, v1, v0
	v_min_u32_e32 v0, v1, v0
	ds_bpermute_b32 v144, v29, v0
	ds_bpermute_b32 v1, v29, v127
	ds_bpermute_b32 v140, v29, v3
	ds_bpermute_b32 v141, v29, v136
	ds_bpermute_b32 v142, v29, v128
	s_waitcnt lgkmcnt(4)
	v_max_u32_e32 v127, v127, v144
	global_load_dwordx4 v[144:147], v[4:5], off offset:1808
	global_load_dwordx4 v[148:151], v[4:5], off offset:1792
	ds_bpermute_b32 v143, v29, v134
	ds_bpermute_b32 v152, v29, v132
	ds_bpermute_b32 v153, v29, v137
	ds_bpermute_b32 v154, v29, v2
	ds_bpermute_b32 v155, v29, v131
	ds_bpermute_b32 v156, v29, v138
	ds_bpermute_b32 v157, v29, v139
	ds_bpermute_b32 v158, v29, v129
	ds_bpermute_b32 v159, v29, v133
	ds_bpermute_b32 v160, v29, v135
	ds_bpermute_b32 v161, v29, v130
	s_waitcnt lgkmcnt(4)
	v_max_u32_e32 v132, v132, v157
	s_waitcnt lgkmcnt(3)
	v_max_u32_e32 v134, v134, v158
	s_waitcnt lgkmcnt(2)
	v_max_u32_e32 v128, v128, v159
	s_waitcnt lgkmcnt(1)
	v_max_u32_e32 v3, v3, v160
	s_waitcnt lgkmcnt(0)
	v_max_u32_e32 v136, v136, v161
	v_max_u32_e32 v137, v137, v156
	v_max_u32_e32 v2, v2, v155
	v_max_u32_e32 v131, v131, v154
	v_max_u32_e32 v138, v138, v153
	v_max_u32_e32 v139, v139, v152
	v_max_u32_e32 v129, v129, v143
	v_max_u32_e32 v133, v133, v142
	v_max_u32_e32 v130, v130, v141
	v_max_u32_e32 v135, v135, v140
	v_max_u32_e32 v0, v0, v1
	v_max_u32_e32 v1, v127, v131
	v_min_u32_e32 v127, v127, v131
	v_max_u32_e32 v131, v3, v138
	v_min_u32_e32 v3, v3, v138
	v_max_u32_e32 v138, v136, v139
	v_min_u32_e32 v136, v136, v139
	v_max_u32_e32 v139, v128, v129
	v_min_u32_e32 v128, v128, v129
	v_max_u32_e32 v129, v134, v133
	v_min_u32_e32 v133, v134, v133
	v_max_u32_e32 v134, v132, v130
	v_min_u32_e32 v130, v132, v130
	v_max_u32_e32 v132, v137, v135
	v_min_u32_e32 v135, v137, v135
	v_max_u32_e32 v137, v2, v0
	v_min_u32_e32 v0, v2, v0
	v_max_u32_e32 v2, v1, v129
	v_min_u32_e32 v1, v1, v129
	v_max_u32_e32 v129, v131, v134
	v_min_u32_e32 v131, v131, v134
	v_max_u32_e32 v134, v138, v132
	v_min_u32_e32 v132, v138, v132
	v_max_u32_e32 v138, v139, v137
	v_min_u32_e32 v137, v139, v137
	v_max_u32_e32 v139, v127, v133
	v_min_u32_e32 v127, v127, v133
	v_max_u32_e32 v133, v3, v130
	v_min_u32_e32 v3, v3, v130
	v_max_u32_e32 v130, v136, v135
	v_min_u32_e32 v135, v136, v135
	v_max_u32_e32 v136, v128, v0
	v_min_u32_e32 v0, v128, v0
	v_max_u32_e32 v128, v2, v134
	v_min_u32_e32 v2, v2, v134
	v_max_u32_e32 v134, v129, v138
	v_min_u32_e32 v129, v129, v138
	v_max_u32_e32 v143, v1, v132
	v_min_u32_e32 v1, v1, v132
	v_max_u32_e32 v132, v131, v137
	v_min_u32_e32 v131, v131, v137
	v_max_u32_e32 v152, v139, v130
	v_min_u32_e32 v130, v139, v130
	v_max_u32_e32 v153, v133, v136
	v_min_u32_e32 v154, v133, v136
	v_max_u32_e32 v155, v127, v135
	v_min_u32_e32 v127, v127, v135
	v_max_u32_e32 v156, v3, v0
	v_min_u32_e32 v0, v3, v0
	v_max_u32_e32 v142, v128, v134
	v_min_u32_e32 v141, v128, v134
	v_max_u32_e32 v140, v2, v129
	v_min_u32_e32 v139, v2, v129
	v_max_u32_e32 v138, v143, v132
	v_min_u32_e32 v137, v143, v132
	v_max_u32_e32 v136, v1, v131
	v_min_u32_e32 v135, v1, v131
	v_max_u32_e32 v134, v152, v153
	v_min_u32_e32 v133, v152, v153
	v_max_u32_e32 v132, v130, v154
	v_min_u32_e32 v131, v130, v154
	v_max_u32_e32 v130, v155, v156
	v_min_u32_e32 v129, v155, v156
	v_max_u32_e32 v128, v127, v0
	v_min_u32_e32 v127, v127, v0
	global_load_dwordx4 v[0:3], v[4:5], off offset:1840
	global_load_dwordx4 v[152:155], v[4:5], off offset:1824
	s_waitcnt vmcnt(2)
; __device__ __forceinline__ unsigned f2key(float f) { const unsigned u = __float_as_uint(f); return (u & 0x80000000u) ? ~u : (u | 0x80000000u); }
; __device__ __forceinline__ void peer_tile(const Args& A, LAS unsigned char* lds, int tile) {
;     ...
;                 { const bf16_t* sp = QRY + m * 2048 + hp * 128 + 32 * g;
;                   const u32x4 s0 = *(const u32x4*)sp, s1 = *(const u32x4*)(sp + 8), s2 = *(const u32x4*)(sp + 16), s3 = *(const u32x4*)(sp + 24);
;                   const unsigned sw[16] = {s0.x, s0.y, s0.z, s0.w, s1.x, s1.y, s1.z, s1.w, s2.x, s2.y, s2.z, s2.w, s3.x, s3.y, s3.z, s3.w};
; #pragma unroll
;                   for (int i = 0; i < 16; ++i) {
;                       const float lo = (float)__builtin_bit_cast(_Float16, (unsigned short)(sw[i] & 0xffffu)), hi = (float)__builtin_bit_cast(_Float16, (unsigned short)(sw[i] >> 16));
;                       const unsigned klo = (f2key(lo) & ~127u) | (unsigned)(127 - (32 * g + 2 * i)), khi = (f2key(hi) & ~127u) | (unsigned)(127 - (32 * g + 2 * i + 1));
;                       if (i < 8) { k0[2 * i] = klo; k0[2 * i + 1] = khi; } else { k1[2 * (i - 8)] = klo; k1[2 * (i - 8) + 1] = khi; } } }
	v_cvt_f32_f16_sdwa v143, v148 dst_sel:DWORD dst_unused:UNUSED_PAD src0_sel:WORD_1
	v_cvt_f32_f16_e32 v4, v148
	v_not_b32_e32 v5, v143
	v_or_b32_e32 v148, 0x80000000, v143
	v_cmp_gt_i32_e32 vcc, 0, v143
	v_not_b32_e32 v143, v4
	s_nop 0
	v_cndmask_b32_e32 v5, v148, v5, vcc
	v_or_b32_e32 v148, 0x80000000, v4
	v_cmp_gt_i32_e32 vcc, 0, v4
	v_and_b32_e32 v5, 0xffffff80, v5
	v_sub_u32_e32 v5, v5, v15
	v_cndmask_b32_e32 v4, v148, v143, vcc
	v_and_b32_e32 v4, 0xffffff80, v4
	v_cvt_f32_f16_sdwa v143, v149 dst_sel:DWORD dst_unused:UNUSED_PAD src0_sel:WORD_1
	v_sub_u32_e32 v4, v4, v15
	v_cvt_f32_f16_e32 v15, v149
	v_add_u32_e32 v5, 0x7e, v5
	v_not_b32_e32 v148, v143
	v_or_b32_e32 v149, 0x80000000, v143
	v_cmp_gt_i32_e32 vcc, 0, v143
	v_add_u32_e32 v4, 0x7f, v4
	s_nop 0
	v_cndmask_b32_e32 v143, v149, v148, vcc
	v_not_b32_e32 v148, v15
	v_or_b32_e32 v149, 0x80000000, v15
	v_cmp_gt_i32_e32 vcc, 0, v15
	v_and_b32_e32 v143, 0xffffff80, v143
	v_sub_u32_e32 v143, v143, v14
	v_cndmask_b32_e32 v15, v149, v148, vcc
	v_and_b32_e32 v15, 0xffffff80, v15
	v_cvt_f32_f16_sdwa v148, v150 dst_sel:DWORD dst_unused:UNUSED_PAD src0_sel:WORD_1
	v_sub_u32_e32 v14, v15, v14
	v_cvt_f32_f16_e32 v15, v150
	v_add_u32_e32 v143, 0x7e, v143
	v_not_b32_e32 v149, v148
	v_or_b32_e32 v150, 0x80000000, v148
	v_cmp_gt_i32_e32 vcc, 0, v148
	v_add_u32_e32 v14, 0x7f, v14
	s_nop 0
	v_cndmask_b32_e32 v148, v150, v149, vcc
	v_not_b32_e32 v149, v15
	v_or_b32_e32 v150, 0x80000000, v15
	v_cmp_gt_i32_e32 vcc, 0, v15
	v_and_b32_e32 v148, 0xffffff80, v148
	v_sub_u32_e32 v148, v148, v12
	v_cndmask_b32_e32 v15, v150, v149, vcc
	v_and_b32_e32 v15, 0xffffff80, v15
	v_cvt_f32_f16_sdwa v149, v151 dst_sel:DWORD dst_unused:UNUSED_PAD src0_sel:WORD_1
	v_sub_u32_e32 v12, v15, v12
	v_cvt_f32_f16_e32 v15, v151
	v_add_u32_e32 v148, 0x7e, v148
	v_not_b32_e32 v150, v149
	v_or_b32_e32 v151, 0x80000000, v149
	v_cmp_gt_i32_e32 vcc, 0, v149
	v_add_u32_e32 v12, 0x7f, v12
	s_nop 0
	v_cndmask_b32_e32 v149, v151, v150, vcc
	v_not_b32_e32 v150, v15
	v_or_b32_e32 v151, 0x80000000, v15
	v_cmp_gt_i32_e32 vcc, 0, v15
	v_and_b32_e32 v149, 0xffffff80, v149
	v_sub_u32_e32 v149, v149, v10
	v_cndmask_b32_e32 v15, v151, v150, vcc
	v_and_b32_e32 v15, 0xffffff80, v15
	v_cvt_f32_f16_sdwa v150, v144 dst_sel:DWORD dst_unused:UNUSED_PAD src0_sel:WORD_1
	v_sub_u32_e32 v10, v15, v10
	v_cvt_f32_f16_e32 v15, v144
	v_add_u32_e32 v149, 0x7e, v149
	v_not_b32_e32 v144, v150
	v_or_b32_e32 v151, 0x80000000, v150
	v_cmp_gt_i32_e32 vcc, 0, v150
	v_not_b32_e32 v150, v15
	v_add_u32_e32 v10, 0x7f, v10
	v_cndmask_b32_e32 v144, v151, v144, vcc
	v_or_b32_e32 v151, 0x80000000, v15
	v_cmp_gt_i32_e32 vcc, 0, v15
	v_and_b32_e32 v144, 0xffffff80, v144
	v_sub_u32_e32 v144, v144, v8
	v_cndmask_b32_e32 v15, v151, v150, vcc
	v_and_b32_e32 v15, 0xffffff80, v15
	v_cvt_f32_f16_sdwa v150, v145 dst_sel:DWORD dst_unused:UNUSED_PAD src0_sel:WORD_1
	v_sub_u32_e32 v8, v15, v8
	v_cvt_f32_f16_e32 v15, v145
	v_add_u32_e32 v144, 0x7e, v144
	v_not_b32_e32 v145, v150
	v_or_b32_e32 v151, 0x80000000, v150
	v_cmp_gt_i32_e32 vcc, 0, v150
	v_not_b32_e32 v150, v15
	v_add_u32_e32 v8, 0x7f, v8
	v_cndmask_b32_e32 v145, v151, v145, vcc
	v_or_b32_e32 v151, 0x80000000, v15
	v_cmp_gt_i32_e32 vcc, 0, v15
	v_and_b32_e32 v145, 0xffffff80, v145
	v_sub_u32_e32 v145, v145, v16
	v_cndmask_b32_e32 v15, v151, v150, vcc
	v_and_b32_e32 v15, 0xffffff80, v15
	v_cvt_f32_f16_sdwa v150, v146 dst_sel:DWORD dst_unused:UNUSED_PAD src0_sel:WORD_1
	v_sub_u32_e32 v15, v15, v16
	v_cvt_f32_f16_e32 v16, v146
	v_add_u32_e32 v145, 0x7e, v145
	v_not_b32_e32 v146, v150
	v_or_b32_e32 v151, 0x80000000, v150
	v_cmp_gt_i32_e32 vcc, 0, v150
	v_not_b32_e32 v150, v16
	v_add_u32_e32 v15, 0x7f, v15
	v_cndmask_b32_e32 v146, v151, v146, vcc
	v_or_b32_e32 v151, 0x80000000, v16
	v_cmp_gt_i32_e32 vcc, 0, v16
	v_and_b32_e32 v146, 0xffffff80, v146
	v_sub_u32_e32 v146, v146, v17
	v_cndmask_b32_e32 v16, v151, v150, vcc
	v_and_b32_e32 v16, 0xffffff80, v16
	v_cvt_f32_f16_sdwa v150, v147 dst_sel:DWORD dst_unused:UNUSED_PAD src0_sel:WORD_1
	v_sub_u32_e32 v16, v16, v17
	v_cvt_f32_f16_e32 v17, v147
	v_add_u32_e32 v146, 0x7e, v146
	v_not_b32_e32 v147, v150
	v_or_b32_e32 v151, 0x80000000, v150
	v_cmp_gt_i32_e32 vcc, 0, v150
	v_not_b32_e32 v150, v17
	v_add_u32_e32 v16, 0x7f, v16
	v_cndmask_b32_e32 v147, v151, v147, vcc
	v_or_b32_e32 v151, 0x80000000, v17
	v_cmp_gt_i32_e32 vcc, 0, v17
	v_and_b32_e32 v147, 0xffffff80, v147
	v_sub_u32_e32 v147, v147, v18
	v_cndmask_b32_e32 v17, v151, v150, vcc
	v_and_b32_e32 v17, 0xffffff80, v17
	s_waitcnt vmcnt(0)
; __device__ __forceinline__ unsigned f2key(float f) { const unsigned u = __float_as_uint(f); return (u & 0x80000000u) ? ~u : (u | 0x80000000u); }
; #define CE_DESC(a, b) do { const unsigned _mx = (a) > (b) ? (a) : (b), _mn = (a) > (b) ? (b) : (a); (a) = _mx; (b) = _mn; } while (0)
; __device__ __forceinline__ void sort16_desc(unsigned (&k)[16]) {
; #pragma unroll
;     for (int size = 2; size <= 16; size <<= 1)
; #pragma unroll
;         for (int stride = size >> 1; stride > 0; stride >>= 1)
; #pragma unroll
;             for (int i = 0; i < 16; ++i) { const int j = i ^ stride;
;                 if (j > i) { if ((i & size) == 0) CE_DESC(k[i], k[j]); else CE_DESC(k[j], k[i]); } }
; }
; __device__ __forceinline__ void peer_tile(const Args& A, LAS unsigned char* lds, int tile) {
;     ...
;                 { const bf16_t* sp = QRY + m * 2048 + hp * 128 + 32 * g;
;                   const u32x4 s0 = *(const u32x4*)sp, s1 = *(const u32x4*)(sp + 8), s2 = *(const u32x4*)(sp + 16), s3 = *(const u32x4*)(sp + 24);
;                   const unsigned sw[16] = {s0.x, s0.y, s0.z, s0.w, s1.x, s1.y, s1.z, s1.w, s2.x, s2.y, s2.z, s2.w, s3.x, s3.y, s3.z, s3.w};
; #pragma unroll
;                   for (int i = 0; i < 16; ++i) {
;                       const float lo = (float)__builtin_bit_cast(_Float16, (unsigned short)(sw[i] & 0xffffu)), hi = (float)__builtin_bit_cast(_Float16, (unsigned short)(sw[i] >> 16));
;                       const unsigned klo = (f2key(lo) & ~127u) | (unsigned)(127 - (32 * g + 2 * i)), khi = (f2key(hi) & ~127u) | (unsigned)(127 - (32 * g + 2 * i + 1));
;                       if (i < 8) { k0[2 * i] = klo; k0[2 * i + 1] = khi; } else { k1[2 * (i - 8)] = klo; k1[2 * (i - 8) + 1] = khi; } } }
	v_cvt_f32_f16_sdwa v150, v152 dst_sel:DWORD dst_unused:UNUSED_PAD src0_sel:WORD_1
	v_sub_u32_e32 v17, v17, v18
	v_cvt_f32_f16_e32 v18, v152
	v_add_u32_e32 v147, 0x7e, v147
	v_not_b32_e32 v151, v150
	v_or_b32_e32 v152, 0x80000000, v150
	v_cmp_gt_i32_e32 vcc, 0, v150
	v_add_u32_e32 v17, 0x7f, v17
	s_nop 0
	v_cndmask_b32_e32 v150, v152, v151, vcc
	v_not_b32_e32 v151, v18
	v_or_b32_e32 v152, 0x80000000, v18
	v_cmp_gt_i32_e32 vcc, 0, v18
	v_and_b32_e32 v150, 0xffffff80, v150
	v_sub_u32_e32 v150, v150, v20
	v_cndmask_b32_e32 v18, v152, v151, vcc
	v_and_b32_e32 v18, 0xffffff80, v18
	v_cvt_f32_f16_sdwa v151, v153 dst_sel:DWORD dst_unused:UNUSED_PAD src0_sel:WORD_1
	v_sub_u32_e32 v18, v18, v20
	v_cvt_f32_f16_e32 v20, v153
	v_add_u32_e32 v150, 0x7e, v150
	v_not_b32_e32 v152, v151
	v_or_b32_e32 v153, 0x80000000, v151
	v_cmp_gt_i32_e32 vcc, 0, v151
	v_add_u32_e32 v18, 0x7f, v18
	v_max_u32_e32 v161, v18, v150
	v_cndmask_b32_e32 v151, v153, v152, vcc
	v_not_b32_e32 v152, v20
	v_or_b32_e32 v153, 0x80000000, v20
	v_cmp_gt_i32_e32 vcc, 0, v20
	v_and_b32_e32 v151, 0xffffff80, v151
	v_sub_u32_e32 v151, v151, v21
	v_cndmask_b32_e32 v20, v153, v152, vcc
	v_and_b32_e32 v20, 0xffffff80, v20
	v_cvt_f32_f16_sdwa v152, v154 dst_sel:DWORD dst_unused:UNUSED_PAD src0_sel:WORD_1
	v_sub_u32_e32 v20, v20, v21
	v_cvt_f32_f16_e32 v21, v154
	v_add_u32_e32 v151, 0x7e, v151
	v_not_b32_e32 v153, v152
	v_or_b32_e32 v154, 0x80000000, v152
	v_cmp_gt_i32_e32 vcc, 0, v152
	v_add_u32_e32 v20, 0x7f, v20
	v_min_u32_e32 v18, v18, v150
	v_cndmask_b32_e32 v152, v154, v153, vcc
	v_not_b32_e32 v153, v21
	v_or_b32_e32 v154, 0x80000000, v21
	v_cmp_gt_i32_e32 vcc, 0, v21
	v_and_b32_e32 v152, 0xffffff80, v152
	v_sub_u32_e32 v152, v152, v22
	v_cndmask_b32_e32 v21, v154, v153, vcc
	v_and_b32_e32 v21, 0xffffff80, v21
	v_cvt_f32_f16_sdwa v153, v155 dst_sel:DWORD dst_unused:UNUSED_PAD src0_sel:WORD_1
	v_sub_u32_e32 v21, v21, v22
	v_cvt_f32_f16_e32 v22, v155
	v_add_u32_e32 v152, 0x7e, v152
	v_not_b32_e32 v154, v153
	v_or_b32_e32 v155, 0x80000000, v153
	v_cmp_gt_i32_e32 vcc, 0, v153
	v_add_u32_e32 v21, 0x7f, v21
	v_max_u32_e32 v150, v151, v20
	v_cndmask_b32_e32 v153, v155, v154, vcc
	v_not_b32_e32 v154, v22
	v_or_b32_e32 v155, 0x80000000, v22
	v_cmp_gt_i32_e32 vcc, 0, v22
	v_and_b32_e32 v153, 0xffffff80, v153
	v_sub_u32_e32 v153, v153, v23
	v_cndmask_b32_e32 v22, v155, v154, vcc
	v_cvt_f32_f16_sdwa v154, v0 dst_sel:DWORD dst_unused:UNUSED_PAD src0_sel:WORD_1
	v_cvt_f32_f16_e32 v0, v0
	v_and_b32_e32 v22, 0xffffff80, v22
	v_sub_u32_e32 v22, v22, v23
	v_not_b32_e32 v23, v154
	v_or_b32_e32 v155, 0x80000000, v154
	v_cmp_gt_i32_e32 vcc, 0, v154
	v_not_b32_e32 v154, v0
	v_add_u32_e32 v153, 0x7e, v153
	v_cndmask_b32_e32 v23, v155, v23, vcc
	v_or_b32_e32 v155, 0x80000000, v0
	v_cmp_gt_i32_e32 vcc, 0, v0
	v_and_b32_e32 v23, 0xffffff80, v23
	v_sub_u32_e32 v23, v23, v24
	v_cndmask_b32_e32 v0, v155, v154, vcc
	v_cvt_f32_f16_sdwa v154, v1 dst_sel:DWORD dst_unused:UNUSED_PAD src0_sel:WORD_1
	v_cvt_f32_f16_e32 v1, v1
	v_and_b32_e32 v0, 0xffffff80, v0
	v_sub_u32_e32 v0, v0, v24
	v_not_b32_e32 v24, v154
	v_or_b32_e32 v155, 0x80000000, v154
	v_cmp_gt_i32_e32 vcc, 0, v154
	v_not_b32_e32 v154, v1
	v_add_u32_e32 v22, 0x7f, v22
	v_cndmask_b32_e32 v24, v155, v24, vcc
	v_or_b32_e32 v155, 0x80000000, v1
	v_cmp_gt_i32_e32 vcc, 0, v1
	v_and_b32_e32 v24, 0xffffff80, v24
	v_sub_u32_e32 v24, v24, v25
	v_cndmask_b32_e32 v1, v155, v154, vcc
	v_cvt_f32_f16_sdwa v154, v2 dst_sel:DWORD dst_unused:UNUSED_PAD src0_sel:WORD_1
	v_cvt_f32_f16_e32 v2, v2
	v_and_b32_e32 v1, 0xffffff80, v1
	v_sub_u32_e32 v1, v1, v25
	v_not_b32_e32 v25, v154
	v_or_b32_e32 v155, 0x80000000, v154
	v_cmp_gt_i32_e32 vcc, 0, v154
	v_not_b32_e32 v154, v2
	v_add_u32_e32 v23, 0x7e, v23
	v_cndmask_b32_e32 v25, v155, v25, vcc
	v_or_b32_e32 v155, 0x80000000, v2
	v_cmp_gt_i32_e32 vcc, 0, v2
	v_and_b32_e32 v25, 0xffffff80, v25
	v_sub_u32_e32 v25, v25, v26
	v_cndmask_b32_e32 v2, v155, v154, vcc
	v_cvt_f32_f16_sdwa v154, v3 dst_sel:DWORD dst_unused:UNUSED_PAD src0_sel:WORD_1
	v_cvt_f32_f16_e32 v3, v3
	v_and_b32_e32 v2, 0xffffff80, v2
	v_sub_u32_e32 v2, v2, v26
	v_not_b32_e32 v26, v154
	v_or_b32_e32 v155, 0x80000000, v154
	v_cmp_gt_i32_e32 vcc, 0, v154
	v_not_b32_e32 v154, v3
	v_add_u32_e32 v0, 0x7f, v0
	v_cndmask_b32_e32 v26, v155, v26, vcc
	v_or_b32_e32 v155, 0x80000000, v3
	v_cmp_gt_i32_e32 vcc, 0, v3
	v_and_b32_e32 v26, 0xffffff80, v26
	v_sub_u32_e32 v26, v26, v28
	v_cndmask_b32_e32 v3, v155, v154, vcc
	v_and_b32_e32 v3, 0xffffff80, v3
	v_sub_u32_e32 v3, v3, v28
	v_add_u32_e32 v24, 0x7e, v24
	v_add_u32_e32 v1, 0x7f, v1
	v_add_u32_e32 v25, 0x7e, v25
	v_add_u32_e32 v2, 0x7f, v2
	v_add_u32_e32 v26, 0x7e, v26
	v_add_u32_e32 v3, 0x7f, v3
	v_max_u32_e32 v28, v4, v5
	v_min_u32_e32 v4, v4, v5
	v_max_u32_e32 v5, v143, v14
	v_min_u32_e32 v14, v143, v14
	v_max_u32_e32 v143, v12, v148
	v_min_u32_e32 v12, v12, v148
	v_max_u32_e32 v148, v149, v10
	v_min_u32_e32 v10, v149, v10
	v_max_u32_e32 v149, v8, v144
	v_min_u32_e32 v8, v8, v144
	v_max_u32_e32 v144, v145, v15
	v_min_u32_e32 v15, v145, v15
	v_max_u32_e32 v145, v16, v146
	v_min_u32_e32 v16, v16, v146
	v_max_u32_e32 v146, v147, v17
	v_min_u32_e32 v17, v147, v17
	v_min_u32_e32 v20, v151, v20
	v_max_u32_e32 v151, v21, v152
	v_min_u32_e32 v21, v21, v152
	v_max_u32_e32 v152, v153, v22
	v_min_u32_e32 v22, v153, v22
	v_max_u32_e32 v153, v0, v23
	v_min_u32_e32 v0, v0, v23
	v_max_u32_e32 v23, v24, v1
	v_min_u32_e32 v1, v24, v1
	v_max_u32_e32 v24, v2, v25
	v_min_u32_e32 v2, v2, v25
	v_max_u32_e32 v25, v26, v3
	v_min_u32_e32 v3, v26, v3
	v_max_u32_e32 v147, v28, v14
	v_min_u32_e32 v14, v28, v14
	v_max_u32_e32 v28, v4, v5
	v_min_u32_e32 v4, v4, v5
; #define CE_DESC(a, b) do { const unsigned _mx = (a) > (b) ? (a) : (b), _mn = (a) > (b) ? (b) : (a); (a) = _mx; (b) = _mn; } while (0)
; __device__ __forceinline__ void sort16_desc(unsigned (&k)[16]) {
; #pragma unroll
;     for (int size = 2; size <= 16; size <<= 1)
; #pragma unroll
;         for (int stride = size >> 1; stride > 0; stride >>= 1)
; #pragma unroll
;             for (int i = 0; i < 16; ++i) { const int j = i ^ stride;
;                 if (j > i) { if ((i & size) == 0) CE_DESC(k[i], k[j]); else CE_DESC(k[j], k[i]); } }
; }
	v_max_u32_e32 v5, v10, v143
	v_min_u32_e32 v10, v10, v143
	v_max_u32_e32 v143, v148, v12
	v_min_u32_e32 v12, v148, v12
	v_max_u32_e32 v148, v149, v15
	v_min_u32_e32 v15, v149, v15
	v_max_u32_e32 v149, v8, v144
	v_min_u32_e32 v8, v8, v144
	v_max_u32_e32 v144, v17, v145
	v_min_u32_e32 v17, v17, v145
	v_max_u32_e32 v145, v146, v16
	v_min_u32_e32 v16, v146, v16
	v_max_u32_e32 v26, v161, v20
	v_min_u32_e32 v20, v161, v20
	v_max_u32_e32 v161, v18, v150
	v_min_u32_e32 v18, v18, v150
	v_max_u32_e32 v150, v22, v151
	v_min_u32_e32 v22, v22, v151
	v_max_u32_e32 v151, v152, v21
	v_min_u32_e32 v21, v152, v21
	v_max_u32_e32 v152, v153, v1
	v_min_u32_e32 v1, v153, v1
	v_max_u32_e32 v153, v0, v23
	v_min_u32_e32 v0, v0, v23
	v_max_u32_e32 v23, v3, v24
	v_min_u32_e32 v3, v3, v24
	v_max_u32_e32 v24, v25, v2
	v_min_u32_e32 v2, v25, v2
	v_max_u32_e32 v146, v147, v28
	v_min_u32_e32 v28, v147, v28
	v_max_u32_e32 v147, v14, v4
	v_min_u32_e32 v4, v14, v4
	v_max_u32_e32 v14, v12, v10
	v_min_u32_e32 v10, v12, v10
	v_max_u32_e32 v12, v143, v5
	v_min_u32_e32 v5, v143, v5
	v_max_u32_e32 v143, v148, v149
	v_min_u32_e32 v148, v148, v149
	v_max_u32_e32 v149, v15, v8
	v_min_u32_e32 v8, v15, v8
	v_max_u32_e32 v15, v16, v17
	v_min_u32_e32 v16, v16, v17
	v_max_u32_e32 v17, v145, v144
	v_min_u32_e32 v144, v145, v144
	v_max_u32_e32 v25, v26, v161
	v_min_u32_e32 v26, v26, v161
	v_max_u32_e32 v161, v20, v18
	v_min_u32_e32 v18, v20, v18
	v_max_u32_e32 v20, v21, v22
	v_min_u32_e32 v21, v21, v22
	v_max_u32_e32 v22, v151, v150
	v_min_u32_e32 v150, v151, v150
	v_max_u32_e32 v151, v152, v153
	v_min_u32_e32 v152, v152, v153
	v_max_u32_e32 v153, v1, v0
	v_min_u32_e32 v0, v1, v0
	v_max_u32_e32 v1, v2, v3
	v_min_u32_e32 v2, v2, v3
	v_max_u32_e32 v3, v24, v23
	v_min_u32_e32 v23, v24, v23
	v_max_u32_e32 v145, v146, v10
	v_min_u32_e32 v10, v146, v10
	v_max_u32_e32 v146, v28, v14
	v_min_u32_e32 v14, v28, v14
	v_max_u32_e32 v28, v147, v5
	v_min_u32_e32 v5, v147, v5
	v_max_u32_e32 v147, v4, v12
	v_min_u32_e32 v4, v4, v12
	v_max_u32_e32 v12, v16, v143
	v_min_u32_e32 v16, v16, v143
	v_max_u32_e32 v143, v15, v148
	v_min_u32_e32 v15, v15, v148
	v_max_u32_e32 v148, v144, v149
	v_min_u32_e32 v144, v144, v149
	v_max_u32_e32 v149, v17, v8
	v_min_u32_e32 v8, v17, v8
	v_max_u32_e32 v24, v25, v21
	v_min_u32_e32 v21, v25, v21
	v_max_u32_e32 v25, v26, v20
	v_min_u32_e32 v20, v26, v20
	v_max_u32_e32 v26, v161, v150
	v_min_u32_e32 v150, v161, v150
	v_max_u32_e32 v161, v18, v22
	v_min_u32_e32 v18, v18, v22
	v_max_u32_e32 v22, v2, v151
	v_min_u32_e32 v2, v2, v151
	v_max_u32_e32 v151, v1, v152
	v_min_u32_e32 v1, v1, v152
	v_max_u32_e32 v152, v23, v153
	v_min_u32_e32 v23, v23, v153
	v_max_u32_e32 v153, v3, v0
	v_min_u32_e32 v0, v3, v0
	v_max_u32_e32 v17, v145, v28
	v_min_u32_e32 v28, v145, v28
	v_max_u32_e32 v145, v146, v147
	v_min_u32_e32 v146, v146, v147
	v_max_u32_e32 v147, v10, v5
	v_min_u32_e32 v5, v10, v5
	v_max_u32_e32 v10, v14, v4
	v_min_u32_e32 v4, v14, v4
	v_max_u32_e32 v14, v144, v16
	v_min_u32_e32 v16, v144, v16
	v_max_u32_e32 v144, v8, v15
	v_min_u32_e32 v8, v8, v15
	v_max_u32_e32 v15, v148, v12
	v_min_u32_e32 v12, v148, v12
	v_max_u32_e32 v148, v149, v143
	v_min_u32_e32 v143, v149, v143
	v_max_u32_e32 v3, v24, v26
	v_min_u32_e32 v24, v24, v26
	v_max_u32_e32 v26, v25, v161
	v_min_u32_e32 v25, v25, v161
	v_max_u32_e32 v161, v21, v150
	v_min_u32_e32 v21, v21, v150
	v_max_u32_e32 v150, v20, v18
	v_min_u32_e32 v18, v20, v18
	v_max_u32_e32 v20, v23, v2
	v_min_u32_e32 v2, v23, v2
	v_max_u32_e32 v23, v0, v1
	v_min_u32_e32 v0, v0, v1
	v_max_u32_e32 v1, v152, v22
	v_min_u32_e32 v22, v152, v22
	v_max_u32_e32 v152, v153, v151
	v_min_u32_e32 v151, v153, v151
	v_max_u32_e32 v149, v17, v145
	v_min_u32_e32 v17, v17, v145
	v_max_u32_e32 v145, v28, v146
	v_min_u32_e32 v28, v28, v146
	v_max_u32_e32 v146, v147, v10
	v_min_u32_e32 v10, v147, v10
	v_max_u32_e32 v147, v5, v4
	v_min_u32_e32 v4, v5, v4
	v_max_u32_e32 v5, v8, v16
	v_min_u32_e32 v8, v8, v16
	v_max_u32_e32 v16, v144, v14
	v_min_u32_e32 v14, v144, v14
	v_max_u32_e32 v144, v143, v12
	v_min_u32_e32 v12, v143, v12
	v_max_u32_e32 v143, v148, v15
	v_min_u32_e32 v15, v148, v15
	v_max_u32_e32 v153, v3, v26
	v_min_u32_e32 v3, v3, v26
	v_max_u32_e32 v26, v24, v25
	v_min_u32_e32 v24, v24, v25
	v_max_u32_e32 v25, v161, v150
	v_min_u32_e32 v150, v161, v150
	v_max_u32_e32 v161, v21, v18
	v_min_u32_e32 v18, v21, v18
	v_max_u32_e32 v21, v0, v2
	v_min_u32_e32 v0, v0, v2
	v_max_u32_e32 v2, v23, v20
	v_min_u32_e32 v20, v23, v20
	v_max_u32_e32 v23, v151, v22
	v_min_u32_e32 v22, v151, v22
	v_max_u32_e32 v151, v152, v1
	v_min_u32_e32 v1, v152, v1
	v_max_u32_e32 v148, v149, v8
	v_min_u32_e32 v8, v149, v8
	v_max_u32_e32 v149, v17, v5
	v_min_u32_e32 v5, v17, v5
	v_max_u32_e32 v17, v145, v14
	v_min_u32_e32 v14, v145, v14
	v_max_u32_e32 v145, v28, v16
	v_min_u32_e32 v16, v28, v16
	v_max_u32_e32 v28, v146, v12
	v_min_u32_e32 v12, v146, v12
	v_max_u32_e32 v146, v10, v144
	v_min_u32_e32 v10, v10, v144
	v_max_u32_e32 v144, v147, v15
	v_min_u32_e32 v15, v147, v15
	v_max_u32_e32 v147, v4, v143
	v_min_u32_e32 v4, v4, v143
	v_max_u32_e32 v152, v153, v0
	v_min_u32_e32 v0, v153, v0
	v_max_u32_e32 v153, v3, v21
	v_min_u32_e32 v3, v3, v21
	v_max_u32_e32 v21, v26, v20
	v_min_u32_e32 v20, v26, v20
	v_max_u32_e32 v26, v24, v2
	v_min_u32_e32 v2, v24, v2
	v_max_u32_e32 v24, v25, v22
	v_min_u32_e32 v22, v25, v22
	v_max_u32_e32 v25, v150, v23
	v_min_u32_e32 v23, v150, v23
	v_max_u32_e32 v150, v161, v1
	v_min_u32_e32 v1, v161, v1
	v_max_u32_e32 v161, v18, v151
	v_min_u32_e32 v18, v18, v151
	v_max_u32_e32 v143, v148, v28
	v_min_u32_e32 v28, v148, v28
	v_max_u32_e32 v148, v149, v146
	v_min_u32_e32 v146, v149, v146
; #define CE_DESC(a, b) do { const unsigned _mx = (a) > (b) ? (a) : (b), _mn = (a) > (b) ? (b) : (a); (a) = _mx; (b) = _mn; } while (0)
; __device__ __forceinline__ void sort16_desc(unsigned (&k)[16]) {
; #pragma unroll
;     for (int size = 2; size <= 16; size <<= 1)
; #pragma unroll
;         for (int stride = size >> 1; stride > 0; stride >>= 1)
; #pragma unroll
;             for (int i = 0; i < 16; ++i) { const int j = i ^ stride;
;                 if (j > i) { if ((i & size) == 0) CE_DESC(k[i], k[j]); else CE_DESC(k[j], k[i]); } }
; }
; __device__ __forceinline__ void merge16(unsigned (&a)[16], const unsigned (&b)[16]) {
; #pragma unroll
;     for (int i = 0; i < 16; ++i) a[i] = a[i] > b[15 - i] ? a[i] : b[15 - i];
; #pragma unroll
;     for (int stride = 8; stride > 0; stride >>= 1)
; #pragma unroll
;         for (int i = 0; i < 16; ++i) { const int j = i ^ stride; if (j > i) CE_DESC(a[i], a[j]); }
; }
; __device__ __forceinline__ void peer_tile(const Args& A, LAS unsigned char* lds, int tile) {
;     ...
;                 for (int msk = 16; msk <= 32; msk <<= 1) {
; #pragma unroll
;                     for (int i = 0; i < 16; ++i) k1[i] = (unsigned)__shfl_xor((int)k0[i], msk);
;                     merge16(k0, k1); }
	v_max_u32_e32 v149, v17, v144
	v_min_u32_e32 v17, v17, v144
	v_max_u32_e32 v144, v145, v147
	v_min_u32_e32 v145, v145, v147
	v_max_u32_e32 v147, v8, v12
	v_min_u32_e32 v8, v8, v12
	v_max_u32_e32 v12, v5, v10
	v_min_u32_e32 v5, v5, v10
	v_max_u32_e32 v10, v14, v15
	v_min_u32_e32 v14, v14, v15
	v_max_u32_e32 v15, v16, v4
	v_min_u32_e32 v4, v16, v4
	v_max_u32_e32 v151, v152, v24
	v_min_u32_e32 v24, v152, v24
	v_max_u32_e32 v152, v153, v25
	v_min_u32_e32 v25, v153, v25
	v_max_u32_e32 v153, v21, v150
	v_min_u32_e32 v21, v21, v150
	v_max_u32_e32 v150, v26, v161
	v_min_u32_e32 v26, v26, v161
	v_max_u32_e32 v161, v0, v22
	v_min_u32_e32 v0, v0, v22
	v_max_u32_e32 v22, v3, v23
	v_min_u32_e32 v3, v3, v23
	v_max_u32_e32 v23, v20, v1
	v_min_u32_e32 v1, v20, v1
	v_max_u32_e32 v20, v2, v18
	v_min_u32_e32 v2, v2, v18
	v_max_u32_e32 v16, v143, v149
	v_min_u32_e32 v143, v143, v149
	v_max_u32_e32 v149, v148, v144
	v_min_u32_e32 v144, v148, v144
	v_max_u32_e32 v148, v28, v17
	v_min_u32_e32 v17, v28, v17
	v_max_u32_e32 v28, v146, v145
	v_min_u32_e32 v145, v146, v145
	v_max_u32_e32 v146, v147, v10
	v_min_u32_e32 v10, v147, v10
	v_max_u32_e32 v147, v12, v15
	v_min_u32_e32 v12, v12, v15
	v_max_u32_e32 v15, v8, v14
	v_min_u32_e32 v8, v8, v14
	v_max_u32_e32 v14, v5, v4
	v_min_u32_e32 v4, v5, v4
	v_max_u32_e32 v18, v151, v153
	v_min_u32_e32 v151, v151, v153
	v_max_u32_e32 v153, v152, v150
	v_min_u32_e32 v150, v152, v150
	v_max_u32_e32 v152, v24, v21
	v_min_u32_e32 v21, v24, v21
	v_max_u32_e32 v24, v25, v26
	v_min_u32_e32 v25, v25, v26
	v_max_u32_e32 v26, v161, v23
	v_min_u32_e32 v23, v161, v23
	v_max_u32_e32 v161, v22, v20
	v_min_u32_e32 v20, v22, v20
	v_max_u32_e32 v22, v0, v1
	v_min_u32_e32 v0, v0, v1
	v_max_u32_e32 v1, v3, v2
	v_min_u32_e32 v2, v3, v2
	v_min_u32_e32 v5, v16, v149
	v_min_u32_e32 v154, v143, v144
	v_min_u32_e32 v155, v148, v28
	v_min_u32_e32 v156, v17, v145
	v_min_u32_e32 v157, v146, v147
	v_min_u32_e32 v158, v10, v12
	v_min_u32_e32 v159, v15, v14
	v_min_u32_e32 v160, v8, v4
	v_min_u32_e32 v3, v18, v153
	v_min_u32_e32 v162, v151, v150
	v_min_u32_e32 v163, v152, v24
	v_min_u32_e32 v164, v21, v25
	v_min_u32_e32 v165, v26, v161
	v_min_u32_e32 v166, v23, v20
	v_min_u32_e32 v167, v22, v1
	v_min_u32_e32 v168, v0, v2
	v_max3_u32 v16, v16, v149, v168
	v_max3_u32 v0, v5, v0, v2
	v_max3_u32 v2, v143, v144, v167
	v_max3_u32 v1, v154, v22, v1
	v_max3_u32 v5, v148, v28, v166
	v_max3_u32 v20, v155, v23, v20
	v_max3_u32 v17, v17, v145, v165
	v_max3_u32 v22, v156, v26, v161
	v_max3_u32 v23, v146, v147, v164
	v_max3_u32 v21, v157, v21, v25
	v_max3_u32 v10, v10, v12, v163
	v_max3_u32 v12, v158, v152, v24
	v_max3_u32 v14, v15, v14, v162
	v_max3_u32 v15, v159, v151, v150
	v_max3_u32 v3, v8, v4, v3
	v_max3_u32 v4, v160, v18, v153
	v_max_u32_e32 v8, v16, v23
	v_min_u32_e32 v16, v16, v23
	v_max_u32_e32 v18, v0, v21
	v_min_u32_e32 v0, v0, v21
	v_max_u32_e32 v21, v2, v10
	v_min_u32_e32 v2, v2, v10
	v_max_u32_e32 v10, v1, v12
	v_min_u32_e32 v1, v1, v12
	v_max_u32_e32 v12, v5, v14
	v_min_u32_e32 v5, v5, v14
	v_max_u32_e32 v14, v20, v15
	v_min_u32_e32 v15, v20, v15
	v_max_u32_e32 v20, v17, v3
	v_min_u32_e32 v3, v17, v3
	v_max_u32_e32 v17, v22, v4
	v_min_u32_e32 v4, v22, v4
	v_max_u32_e32 v22, v8, v12
	v_min_u32_e32 v8, v8, v12
	v_max_u32_e32 v12, v18, v14
	v_min_u32_e32 v14, v18, v14
	v_max_u32_e32 v18, v21, v20
	v_min_u32_e32 v20, v21, v20
	v_max_u32_e32 v21, v10, v17
	v_min_u32_e32 v10, v10, v17
	v_max_u32_e32 v17, v16, v5
	v_min_u32_e32 v5, v16, v5
	v_max_u32_e32 v16, v0, v15
	v_min_u32_e32 v0, v0, v15
	v_max_u32_e32 v15, v2, v3
	v_min_u32_e32 v2, v2, v3
	v_max_u32_e32 v3, v1, v4
	v_min_u32_e32 v1, v1, v4
	v_max_u32_e32 v4, v22, v18
	v_min_u32_e32 v18, v22, v18
	v_max_u32_e32 v22, v12, v21
	v_min_u32_e32 v12, v12, v21
	v_max_u32_e32 v21, v8, v20
	v_min_u32_e32 v8, v8, v20
	v_max_u32_e32 v20, v14, v10
	v_min_u32_e32 v10, v14, v10
	v_max_u32_e32 v14, v17, v15
	v_min_u32_e32 v15, v17, v15
	v_max_u32_e32 v17, v16, v3
	v_min_u32_e32 v3, v16, v3
	v_max_u32_e32 v16, v5, v2
	v_min_u32_e32 v2, v5, v2
	v_max_u32_e32 v5, v0, v1
	v_min_u32_e32 v0, v0, v1
	v_max_u32_e32 v1, v4, v22
	v_min_u32_e32 v4, v4, v22
	v_max_u32_e32 v22, v18, v12
	v_min_u32_e32 v12, v18, v12
	v_max_u32_e32 v18, v21, v20
	v_min_u32_e32 v20, v21, v20
	v_max_u32_e32 v21, v8, v10
	v_min_u32_e32 v8, v8, v10
	v_max_u32_e32 v10, v14, v17
	v_min_u32_e32 v14, v14, v17
	v_max_u32_e32 v17, v15, v3
	v_min_u32_e32 v3, v15, v3
	v_max_u32_e32 v15, v16, v5
	v_min_u32_e32 v5, v16, v5
	v_max_u32_e32 v16, v2, v0
	v_min_u32_e32 v0, v2, v0
	ds_bpermute_b32 v2, v27, v1
	ds_bpermute_b32 v23, v27, v4
	ds_bpermute_b32 v24, v27, v22
	ds_bpermute_b32 v25, v27, v12
	ds_bpermute_b32 v26, v27, v18
	ds_bpermute_b32 v28, v27, v20
	ds_bpermute_b32 v143, v27, v21
	ds_bpermute_b32 v144, v27, v8
	ds_bpermute_b32 v145, v27, v10
	ds_bpermute_b32 v146, v27, v14
	ds_bpermute_b32 v147, v27, v17
	ds_bpermute_b32 v148, v27, v0
	ds_bpermute_b32 v149, v27, v16
	ds_bpermute_b32 v150, v27, v5
	ds_bpermute_b32 v151, v27, v15
	ds_bpermute_b32 v27, v27, v3
	s_waitcnt lgkmcnt(4)
	v_max_u32_e32 v1, v1, v148
	s_waitcnt lgkmcnt(3)
	v_max_u32_e32 v4, v4, v149
	s_waitcnt lgkmcnt(2)
	v_max_u32_e32 v22, v22, v150
	s_waitcnt lgkmcnt(1)
	v_max_u32_e32 v12, v12, v151
	s_waitcnt lgkmcnt(0)
; #define CE_DESC(a, b) do { const unsigned _mx = (a) > (b) ? (a) : (b), _mn = (a) > (b) ? (b) : (a); (a) = _mx; (b) = _mn; } while (0)
; __device__ __forceinline__ void merge16(unsigned (&a)[16], const unsigned (&b)[16]) {
; #pragma unroll
;     for (int i = 0; i < 16; ++i) a[i] = a[i] > b[15 - i] ? a[i] : b[15 - i];
; #pragma unroll
;     for (int stride = 8; stride > 0; stride >>= 1)
; #pragma unroll
;         for (int i = 0; i < 16; ++i) { const int j = i ^ stride; if (j > i) CE_DESC(a[i], a[j]); }
; }
; __device__ __forceinline__ void peer_tile(const Args& A, LAS unsigned char* lds, int tile) {
;     ...
;                 for (int msk = 16; msk <= 32; msk <<= 1) {
; #pragma unroll
;                     for (int i = 0; i < 16; ++i) k1[i] = (unsigned)__shfl_xor((int)k0[i], msk);
;                     merge16(k0, k1); }
; #pragma unroll
;                 for (int i = 0; i < 16; ++i) LA[hh][p][i] = k0[i];
;             }
;         }
;         {
;             const int h = 4 * hg + g;
;             unsigned L2[2][16];
; #pragma unroll
;             for (int p = 0; p < 2; ++p)
; #pragma unroll
;                 for (int i = 0; i < 16; ++i) L2[p][i] = (g & 2) ? ((g & 1) ? LA[3][p][i] : LA[2][p][i]) : ((g & 1) ? LA[1][p][i] : LA[0][p][i]);
	v_max_u32_e32 v18, v18, v27
	v_max_u32_e32 v20, v20, v147
	v_max_u32_e32 v21, v21, v146
	v_max_u32_e32 v8, v8, v145
	v_max_u32_e32 v10, v10, v144
	v_max_u32_e32 v14, v14, v143
	v_max_u32_e32 v17, v17, v28
	v_max_u32_e32 v3, v3, v26
	v_max_u32_e32 v15, v15, v25
	v_max_u32_e32 v5, v5, v24
	v_max_u32_e32 v16, v16, v23
	v_max_u32_e32 v0, v0, v2
	v_max_u32_e32 v2, v1, v10
	v_min_u32_e32 v1, v1, v10
	v_max_u32_e32 v10, v4, v14
	v_min_u32_e32 v4, v4, v14
	v_max_u32_e32 v14, v22, v17
	v_min_u32_e32 v17, v22, v17
	v_max_u32_e32 v22, v12, v3
	v_min_u32_e32 v3, v12, v3
	v_max_u32_e32 v12, v18, v15
	v_min_u32_e32 v15, v18, v15
	v_max_u32_e32 v18, v20, v5
	v_min_u32_e32 v5, v20, v5
	v_max_u32_e32 v20, v21, v16
	v_min_u32_e32 v16, v21, v16
	v_max_u32_e32 v21, v8, v0
	v_min_u32_e32 v0, v8, v0
	v_max_u32_e32 v8, v2, v12
	v_min_u32_e32 v2, v2, v12
	v_max_u32_e32 v12, v10, v18
	v_min_u32_e32 v10, v10, v18
	v_max_u32_e32 v18, v14, v20
	v_min_u32_e32 v14, v14, v20
	v_max_u32_e32 v20, v22, v21
	v_min_u32_e32 v21, v22, v21
	v_max_u32_e32 v22, v1, v15
	v_min_u32_e32 v1, v1, v15
	v_max_u32_e32 v15, v4, v5
	v_min_u32_e32 v4, v4, v5
	v_max_u32_e32 v5, v17, v16
	v_min_u32_e32 v16, v17, v16
	v_max_u32_e32 v17, v3, v0
	v_min_u32_e32 v0, v3, v0
	v_max_u32_e32 v3, v8, v18
	v_min_u32_e32 v8, v8, v18
	v_max_u32_e32 v18, v12, v20
	v_min_u32_e32 v12, v12, v20
	v_max_u32_e32 v20, v2, v14
	v_min_u32_e32 v2, v2, v14
	v_max_u32_e32 v14, v10, v21
	v_min_u32_e32 v10, v10, v21
	v_max_u32_e32 v21, v22, v5
	v_min_u32_e32 v5, v22, v5
	v_max_u32_e32 v22, v15, v17
	v_min_u32_e32 v15, v15, v17
	v_max_u32_e32 v17, v1, v16
	v_min_u32_e32 v1, v1, v16
	v_max_u32_e32 v16, v4, v0
	v_min_u32_e32 v0, v4, v0
	v_max_u32_e32 v4, v3, v18
	v_min_u32_e32 v3, v3, v18
	v_max_u32_e32 v18, v8, v12
	v_min_u32_e32 v8, v8, v12
	v_max_u32_e32 v12, v20, v14
	v_min_u32_e32 v14, v20, v14
	v_max_u32_e32 v20, v2, v10
	v_min_u32_e32 v2, v2, v10
	v_max_u32_e32 v10, v21, v22
	v_min_u32_e32 v21, v21, v22
	v_max_u32_e32 v22, v5, v15
	v_min_u32_e32 v5, v5, v15
	v_max_u32_e32 v15, v17, v16
	v_min_u32_e32 v16, v17, v16
	v_max_u32_e32 v17, v1, v0
	v_min_u32_e32 v0, v1, v0
	ds_bpermute_b32 v1, v29, v4
	ds_bpermute_b32 v23, v29, v3
	ds_bpermute_b32 v24, v29, v18
	ds_bpermute_b32 v25, v29, v8
	ds_bpermute_b32 v26, v29, v12
	ds_bpermute_b32 v27, v29, v14
	ds_bpermute_b32 v28, v29, v20
	ds_bpermute_b32 v143, v29, v2
	ds_bpermute_b32 v144, v29, v10
	ds_bpermute_b32 v145, v29, v21
	ds_bpermute_b32 v146, v29, v22
	ds_bpermute_b32 v147, v29, v0
	ds_bpermute_b32 v148, v29, v17
	ds_bpermute_b32 v149, v29, v16
	ds_bpermute_b32 v150, v29, v15
	ds_bpermute_b32 v29, v29, v5
	s_waitcnt lgkmcnt(4)
	v_max_u32_e32 v4, v4, v147
	s_waitcnt lgkmcnt(3)
	v_max_u32_e32 v3, v3, v148
	s_waitcnt lgkmcnt(2)
	v_max_u32_e32 v18, v18, v149
	s_waitcnt lgkmcnt(1)
	v_max_u32_e32 v8, v8, v150
	s_waitcnt lgkmcnt(0)
	v_max_u32_e32 v12, v12, v29
	v_max_u32_e32 v14, v14, v146
	v_max_u32_e32 v20, v20, v145
	v_max_u32_e32 v2, v2, v144
	v_max_u32_e32 v10, v10, v143
	v_max_u32_e32 v21, v21, v28
	v_max_u32_e32 v22, v22, v27
	v_max_u32_e32 v5, v5, v26
	v_max_u32_e32 v15, v15, v25
	v_max_u32_e32 v16, v16, v24
	v_max_u32_e32 v17, v17, v23
	v_max_u32_e32 v0, v0, v1
	v_max_u32_e32 v1, v4, v10
	v_min_u32_e32 v4, v4, v10
	v_max_u32_e32 v10, v3, v21
	v_min_u32_e32 v3, v3, v21
	v_max_u32_e32 v21, v18, v22
	v_min_u32_e32 v18, v18, v22
	v_max_u32_e32 v22, v8, v5
	v_min_u32_e32 v5, v8, v5
	v_max_u32_e32 v8, v12, v15
	v_min_u32_e32 v12, v12, v15
	v_max_u32_e32 v15, v14, v16
	v_min_u32_e32 v14, v14, v16
	v_max_u32_e32 v16, v20, v17
	v_min_u32_e32 v17, v20, v17
	v_max_u32_e32 v20, v2, v0
	v_min_u32_e32 v0, v2, v0
	v_max_u32_e32 v2, v1, v8
	v_min_u32_e32 v1, v1, v8
	v_max_u32_e32 v8, v10, v15
	v_min_u32_e32 v10, v10, v15
	v_max_u32_e32 v15, v21, v16
	v_min_u32_e32 v16, v21, v16
	v_max_u32_e32 v21, v22, v20
	v_min_u32_e32 v20, v22, v20
	v_max_u32_e32 v22, v4, v12
	v_min_u32_e32 v4, v4, v12
	v_max_u32_e32 v12, v3, v14
	v_min_u32_e32 v3, v3, v14
	v_max_u32_e32 v14, v18, v17
	v_min_u32_e32 v17, v18, v17
	v_max_u32_e32 v18, v5, v0
	v_min_u32_e32 v0, v5, v0
	v_max_u32_e32 v5, v2, v15
	v_min_u32_e32 v2, v2, v15
	v_max_u32_e32 v15, v8, v21
	v_min_u32_e32 v8, v8, v21
	v_max_u32_e32 v21, v1, v16
	v_min_u32_e32 v1, v1, v16
	v_max_u32_e32 v16, v10, v20
	v_min_u32_e32 v10, v10, v20
	v_max_u32_e32 v20, v22, v14
	v_min_u32_e32 v14, v22, v14
	v_max_u32_e32 v22, v12, v18
	v_min_u32_e32 v12, v12, v18
	v_max_u32_e32 v18, v4, v17
	v_min_u32_e32 v4, v4, v17
	v_max_u32_e32 v17, v3, v0
	v_min_u32_e32 v0, v3, v0
	v_max_u32_e32 v3, v5, v15
	v_min_u32_e32 v5, v5, v15
	v_max_u32_e32 v15, v2, v8
	v_min_u32_e32 v2, v2, v8
	v_max_u32_e32 v8, v21, v16
	v_min_u32_e32 v16, v21, v16
	v_max_u32_e32 v21, v1, v10
	v_min_u32_e32 v1, v1, v10
	v_max_u32_e32 v10, v20, v22
	v_min_u32_e32 v20, v20, v22
	v_max_u32_e32 v22, v14, v12
	v_min_u32_e32 v12, v14, v12
	v_max_u32_e32 v14, v18, v17
	v_min_u32_e32 v17, v18, v17
	v_max_u32_e32 v18, v4, v0
	v_min_u32_e32 v0, v4, v0
	v_and_b32_e32 v4, 16, v19
	v_cmp_eq_u32_e32 vcc, 0, v4
	v_cndmask_b32_e64 v23, v77, v45, s[0:1]
	v_cndmask_b32_e64 v24, v76, v44, s[0:1]
	v_cndmask_b32_e32 v4, v142, v109, vcc
	v_cndmask_b32_e64 v4, v4, v23, s[4:5]
	v_cndmask_b32_e32 v23, v141, v108, vcc
	v_cndmask_b32_e64 v23, v23, v24, s[4:5]
	v_cndmask_b32_e32 v24, v140, v107, vcc
	v_cndmask_b32_e64 v25, v75, v43, s[0:1]
	v_cndmask_b32_e64 v24, v24, v25, s[4:5]
	v_cndmask_b32_e32 v25, v139, v106, vcc
	v_cndmask_b32_e64 v26, v74, v42, s[0:1]
	v_cndmask_b32_e64 v25, v25, v26, s[4:5]
	v_cndmask_b32_e32 v26, v138, v105, vcc
	v_cndmask_b32_e64 v27, v73, v41, s[0:1]
	v_cndmask_b32_e64 v26, v26, v27, s[4:5]
; __device__ __forceinline__ float key2f(unsigned k) { const unsigned u = (k & 0x80000000u) ? (k & 0x7fffffffu) : ~k; return __uint_as_float(u); }
; #define CK(i, j) ((f2key(va[i] + vb[j]) & ~255u) | (unsigned)(255 - (16 * (i) + (j))))
; __device__ __forceinline__ void peer_tile(const Args& A, LAS unsigned char* lds, int tile) {
;     ...
;                 for (int i = 0; i < 16; ++i) L2[p][i] = (g & 2) ? ((g & 1) ? LA[3][p][i] : LA[2][p][i]) : ((g & 1) ? LA[1][p][i] : LA[0][p][i]);
;             float va[16], vb[16];
; #pragma unroll
;             for (int i = 0; i < 16; ++i) { va[i] = key2f(L2[0][i] & ~127u); vb[i] = key2f(L2[1][i] & ~127u); idx[i] = 127u - (L2[0][i] & 127u); idx[16 + i] = 127u - (L2[1][i] & 127u); }
;     ...
;             unsigned Lf[16], Bt[16];
; #pragma unroll
;             for (int j = 0; j < 16; ++j) Lf[j] = CK(0, j);
; #pragma unroll
;             for (int j = 0; j < 8; ++j) Bt[j] = CK(1, j);
; #pragma unroll
;             for (int j = 0; j < 5; ++j) Bt[8 + j] = CK(2, j);
	v_cndmask_b32_e32 v27, v137, v104, vcc
	v_cndmask_b32_e64 v28, v72, v40, s[0:1]
	v_cndmask_b32_e64 v27, v27, v28, s[4:5]
	v_cndmask_b32_e32 v28, v136, v103, vcc
	v_cndmask_b32_e64 v29, v71, v39, s[0:1]
	v_cndmask_b32_e64 v28, v28, v29, s[4:5]
	v_cndmask_b32_e32 v29, v135, v102, vcc
	v_cndmask_b32_e64 v29, v29, v38, s[4:5]
	v_cndmask_b32_e32 v38, v134, v101, vcc
	v_cndmask_b32_e64 v37, v38, v37, s[4:5]
	v_cndmask_b32_e32 v38, v133, v100, vcc
	v_cndmask_b32_e64 v36, v38, v36, s[4:5]
	v_cndmask_b32_e32 v38, v132, v99, vcc
	v_cndmask_b32_e64 v38, v38, v35, s[4:5]
	v_cndmask_b32_e32 v35, v131, v98, vcc
	v_cndmask_b32_e64 v39, v35, v34, s[4:5]
	v_cndmask_b32_e32 v34, v130, v97, vcc
	v_cndmask_b32_e64 v33, v34, v33, s[4:5]
	v_cndmask_b32_e32 v34, v129, v96, vcc
	v_cndmask_b32_e64 v40, v34, v32, s[4:5]
	v_cndmask_b32_e32 v32, v128, v95, vcc
	v_cndmask_b32_e64 v42, v32, v31, s[4:5]
	v_cndmask_b32_e32 v31, v127, v94, vcc
	v_cndmask_b32_e64 v43, v31, v30, s[4:5]
	v_cndmask_b32_e32 v3, v3, v126, vcc
	v_cndmask_b32_e64 v30, v93, v61, s[0:1]
	v_cndmask_b32_e64 v3, v3, v30, s[4:5]
	v_cndmask_b32_e32 v5, v5, v125, vcc
	v_cndmask_b32_e64 v30, v92, v60, s[0:1]
	v_cndmask_b32_e64 v30, v5, v30, s[4:5]
	v_cndmask_b32_e32 v5, v15, v124, vcc
	v_cndmask_b32_e64 v15, v91, v59, s[0:1]
	v_cndmask_b32_e64 v15, v5, v15, s[4:5]
	v_cndmask_b32_e32 v2, v2, v123, vcc
	v_cndmask_b32_e64 v5, v90, v58, s[0:1]
	v_cndmask_b32_e64 v31, v2, v5, s[4:5]
	v_cndmask_b32_e32 v2, v8, v122, vcc
	v_cndmask_b32_e64 v5, v89, v57, s[0:1]
	v_cndmask_b32_e64 v8, v2, v5, s[4:5]
	v_cndmask_b32_e32 v2, v16, v121, vcc
	v_cndmask_b32_e64 v5, v88, v56, s[0:1]
	v_cndmask_b32_e64 v32, v2, v5, s[4:5]
	v_cndmask_b32_e32 v2, v21, v120, vcc
	v_cndmask_b32_e64 v5, v87, v55, s[0:1]
	v_cndmask_b32_e64 v21, v2, v5, s[4:5]
	v_cndmask_b32_e32 v1, v1, v119, vcc
	v_cndmask_b32_e64 v2, v86, v54, s[0:1]
	v_cndmask_b32_e64 v34, v1, v2, s[4:5]
	v_cndmask_b32_e32 v1, v10, v118, vcc
	v_cndmask_b32_e64 v2, v85, v53, s[0:1]
	v_cndmask_b32_e64 v41, v1, v2, s[4:5]
	v_cndmask_b32_e32 v1, v20, v117, vcc
	v_cndmask_b32_e64 v2, v84, v52, s[0:1]
	v_cndmask_b32_e64 v44, v1, v2, s[4:5]
	v_cndmask_b32_e32 v1, v22, v116, vcc
	v_cndmask_b32_e64 v2, v83, v51, s[0:1]
	v_cndmask_b32_e64 v45, v1, v2, s[4:5]
	v_cndmask_b32_e32 v1, v12, v115, vcc
	v_cndmask_b32_e64 v2, v82, v50, s[0:1]
	v_cndmask_b32_e64 v50, v1, v2, s[4:5]
	v_cndmask_b32_e32 v1, v14, v114, vcc
	v_cndmask_b32_e64 v2, v81, v49, s[0:1]
	v_cndmask_b32_e64 v49, v1, v2, s[4:5]
	v_cndmask_b32_e32 v1, v17, v112, vcc
	v_cndmask_b32_e64 v2, v80, v48, s[0:1]
	v_cndmask_b32_e64 v48, v1, v2, s[4:5]
	v_cndmask_b32_e32 v1, v18, v111, vcc
	v_cndmask_b32_e64 v2, v79, v47, s[0:1]
	v_cndmask_b32_e64 v47, v1, v2, s[4:5]
	v_cndmask_b32_e32 v0, v0, v110, vcc
	v_cndmask_b32_e64 v1, v78, v46, s[0:1]
	v_cndmask_b32_e64 v46, v0, v1, s[4:5]
	v_and_b32_e32 v0, 0x7fffff80, v4
	v_bitop3_b32 v1, v4, s19, v4 bitop3:0xcf
	v_cmp_gt_i32_e32 vcc, 0, v4
	v_bitop3_b32 v2, v4, s19, v4 bitop3:0xc
	v_bitop3_b32 v4, v23, s19, v23 bitop3:0xcf
	v_cndmask_b32_e32 v20, v1, v0, vcc
	v_and_b32_e32 v0, 0x7fffff80, v3
	v_bitop3_b32 v1, v3, s19, v3 bitop3:0xcf
	v_cmp_gt_i32_e32 vcc, 0, v3
	v_add_u32_e32 v5, 0, v6
	v_bitop3_b32 v3, v3, s19, v3 bitop3:0xc
	v_cndmask_b32_e32 v1, v1, v0, vcc
	v_and_b32_e32 v0, 0x7fffff80, v23
	v_cmp_gt_i32_e32 vcc, 0, v23
	v_bitop3_b32 v14, v31, s19, v31 bitop3:0xcf
	v_bitop3_b32 v6, v24, s19, v24 bitop3:0xc
	v_cndmask_b32_e32 v18, v4, v0, vcc
	v_and_b32_e32 v0, 0x7fffff80, v30
	v_bitop3_b32 v4, v30, s19, v30 bitop3:0xcf
	v_cmp_gt_i32_e32 vcc, 0, v30
	v_bitop3_b32 v10, v15, s19, v15 bitop3:0xc
	v_bitop3_b32 v16, v32, s19, v32 bitop3:0xcf
	v_cndmask_b32_e32 v0, v4, v0, vcc
	v_bitop3_b32 v4, v23, s19, v23 bitop3:0xc
	ds_write2_b32 v5, v2, v4 offset1:1
	v_bitop3_b32 v2, v30, s19, v30 bitop3:0xc
	ds_write2_b32 v5, v3, v2 offset0:16 offset1:17
	v_and_b32_e32 v2, 0x7fffff80, v24
	v_bitop3_b32 v3, v24, s19, v24 bitop3:0xcf
	v_cmp_gt_i32_e32 vcc, 0, v24
	v_bitop3_b32 v4, v25, s19, v25 bitop3:0xcf
	v_bitop3_b32 v22, v29, s19, v29 bitop3:0xcf
	v_cndmask_b32_e32 v12, v3, v2, vcc
	v_and_b32_e32 v2, 0x7fffff80, v15
	v_bitop3_b32 v3, v15, s19, v15 bitop3:0xcf
	v_cmp_gt_i32_e32 vcc, 0, v15
	v_bitop3_b32 v15, v27, s19, v27 bitop3:0xcf
	v_bitop3_b32 v24, v34, s19, v34 bitop3:0xcf
	v_cndmask_b32_e32 v3, v3, v2, vcc
	v_and_b32_e32 v2, 0x7fffff80, v25
	v_cmp_gt_i32_e32 vcc, 0, v25
	s_nop 1
	v_cndmask_b32_e32 v4, v4, v2, vcc
	v_and_b32_e32 v2, 0x7fffff80, v31
	v_cmp_gt_i32_e32 vcc, 0, v31
	s_nop 1
	v_cndmask_b32_e32 v2, v14, v2, vcc
	v_bitop3_b32 v14, v25, s19, v25 bitop3:0xc
	ds_write2_b32 v5, v6, v14 offset0:2 offset1:3
	v_bitop3_b32 v6, v31, s19, v31 bitop3:0xc
	ds_write2_b32 v5, v10, v6 offset0:18 offset1:19
	v_and_b32_e32 v6, 0x7fffff80, v26
	v_bitop3_b32 v10, v26, s19, v26 bitop3:0xcf
	v_cmp_gt_i32_e32 vcc, 0, v26
	v_bitop3_b32 v25, v36, s19, v36 bitop3:0xcf
	s_nop 0
	v_cndmask_b32_e32 v14, v10, v6, vcc
	v_and_b32_e32 v6, 0x7fffff80, v8
	v_bitop3_b32 v10, v8, s19, v8 bitop3:0xcf
	v_cmp_gt_i32_e32 vcc, 0, v8
	v_bitop3_b32 v8, v8, s19, v8 bitop3:0xc
	s_nop 0
	v_cndmask_b32_e32 v17, v10, v6, vcc
	v_and_b32_e32 v10, 0x7fffff80, v27
	v_cmp_gt_i32_e32 vcc, 0, v27
	v_bitop3_b32 v6, v26, s19, v26 bitop3:0xc
	v_bitop3_b32 v26, v43, s19, v43 bitop3:0xcf
	v_cndmask_b32_e32 v10, v15, v10, vcc
	v_and_b32_e32 v15, 0x7fffff80, v32
	v_cmp_gt_i32_e32 vcc, 0, v32
	s_nop 1
	v_cndmask_b32_e32 v16, v16, v15, vcc
	v_bitop3_b32 v15, v27, s19, v27 bitop3:0xc
	ds_write2_b32 v5, v6, v15 offset0:4 offset1:5
	v_bitop3_b32 v6, v32, s19, v32 bitop3:0xc
	ds_write2_b32 v5, v8, v6 offset0:20 offset1:21
	v_and_b32_e32 v6, 0x7fffff80, v28
; __device__ __forceinline__ float key2f(unsigned k) { const unsigned u = (k & 0x80000000u) ? (k & 0x7fffffffu) : ~k; return __uint_as_float(u); }
; #define CK(i, j) ((f2key(va[i] + vb[j]) & ~255u) | (unsigned)(255 - (16 * (i) + (j))))
; __device__ __forceinline__ void peer_tile(const Args& A, LAS unsigned char* lds, int tile) {
;     ...
;                 for (int i = 0; i < 16; ++i) L2[p][i] = (g & 2) ? ((g & 1) ? LA[3][p][i] : LA[2][p][i]) : ((g & 1) ? LA[1][p][i] : LA[0][p][i]);
;             float va[16], vb[16];
; #pragma unroll
;             for (int i = 0; i < 16; ++i) { va[i] = key2f(L2[0][i] & ~127u); vb[i] = key2f(L2[1][i] & ~127u); idx[i] = 127u - (L2[0][i] & 127u); idx[16 + i] = 127u - (L2[1][i] & 127u); }
;     ...
;             unsigned Lf[16], Bt[16];
; #pragma unroll
;             for (int j = 0; j < 16; ++j) Lf[j] = CK(0, j);
; #pragma unroll
;             for (int j = 0; j < 8; ++j) Bt[j] = CK(1, j);
; #pragma unroll
;             for (int j = 0; j < 5; ++j) Bt[8 + j] = CK(2, j);
	v_bitop3_b32 v8, v28, s19, v28 bitop3:0xcf
	v_cmp_gt_i32_e32 vcc, 0, v28
	v_bitop3_b32 v15, v21, s19, v21 bitop3:0xcf
	s_nop 0
	v_cndmask_b32_e32 v8, v8, v6, vcc
	v_and_b32_e32 v6, 0x7fffff80, v21
	v_cmp_gt_i32_e32 vcc, 0, v21
	v_bitop3_b32 v21, v21, s19, v21 bitop3:0xc
	s_nop 0
	v_cndmask_b32_e32 v23, v15, v6, vcc
	v_and_b32_e32 v6, 0x7fffff80, v29
	v_cmp_gt_i32_e32 vcc, 0, v29
	v_bitop3_b32 v15, v28, s19, v28 bitop3:0xc
	s_nop 0
	v_cndmask_b32_e32 v6, v22, v6, vcc
	v_and_b32_e32 v22, 0x7fffff80, v34
	v_cmp_gt_i32_e32 vcc, 0, v34
	s_nop 1
	v_cndmask_b32_e32 v22, v24, v22, vcc
	v_bitop3_b32 v24, v29, s19, v29 bitop3:0xc
	ds_write2_b32 v5, v15, v24 offset0:6 offset1:7
	v_bitop3_b32 v15, v34, s19, v34 bitop3:0xc
	ds_write2_b32 v5, v21, v15 offset0:22 offset1:23
	v_and_b32_e32 v15, 0x7fffff80, v37
	v_bitop3_b32 v21, v37, s19, v37 bitop3:0xcf
	v_cmp_gt_i32_e32 vcc, 0, v37
	v_and_b32_e32 v24, 0x7fffff80, v36
	s_nop 0
	v_cndmask_b32_e32 v27, v21, v15, vcc
	v_and_b32_e32 v15, 0x7fffff80, v41
	v_bitop3_b32 v21, v41, s19, v41 bitop3:0xcf
	v_cmp_gt_i32_e32 vcc, 0, v41
	s_nop 1
	v_cndmask_b32_e32 v35, v21, v15, vcc
	v_cmp_gt_i32_e32 vcc, 0, v36
	v_bitop3_b32 v15, v37, s19, v37 bitop3:0xc
	v_bitop3_b32 v21, v41, s19, v41 bitop3:0xc
	v_cndmask_b32_e32 v28, v25, v24, vcc
	v_and_b32_e32 v24, 0x7fffff80, v44
	v_bitop3_b32 v25, v44, s19, v44 bitop3:0xcf
	v_cmp_gt_i32_e32 vcc, 0, v44
	s_nop 1
	v_cndmask_b32_e32 v34, v25, v24, vcc
	v_bitop3_b32 v24, v36, s19, v36 bitop3:0xc
	ds_write2_b32 v5, v15, v24 offset0:8 offset1:9
	v_bitop3_b32 v15, v44, s19, v44 bitop3:0xc
	ds_write2_b32 v5, v21, v15 offset0:24 offset1:25
	v_and_b32_e32 v15, 0x7fffff80, v38
	v_bitop3_b32 v21, v38, s19, v38 bitop3:0xcf
	v_cmp_gt_i32_e32 vcc, 0, v38
	v_and_b32_e32 v24, 0x7fffff80, v39
	v_bitop3_b32 v25, v39, s19, v39 bitop3:0xcf
	v_cndmask_b32_e32 v29, v21, v15, vcc
	v_and_b32_e32 v15, 0x7fffff80, v45
	v_bitop3_b32 v21, v45, s19, v45 bitop3:0xcf
	v_cmp_gt_i32_e32 vcc, 0, v45
	s_nop 1
	v_cndmask_b32_e32 v37, v21, v15, vcc
	v_cmp_gt_i32_e32 vcc, 0, v39
	v_bitop3_b32 v15, v38, s19, v38 bitop3:0xc
	v_bitop3_b32 v21, v45, s19, v45 bitop3:0xc
	v_cndmask_b32_e32 v30, v25, v24, vcc
	v_and_b32_e32 v24, 0x7fffff80, v50
	v_bitop3_b32 v25, v50, s19, v50 bitop3:0xcf
	v_cmp_gt_i32_e32 vcc, 0, v50
	s_nop 1
	v_cndmask_b32_e32 v36, v25, v24, vcc
	v_bitop3_b32 v24, v39, s19, v39 bitop3:0xc
	ds_write2_b32 v5, v15, v24 offset0:10 offset1:11
	v_bitop3_b32 v15, v50, s19, v50 bitop3:0xc
	ds_write2_b32 v5, v21, v15 offset0:26 offset1:27
	v_and_b32_e32 v15, 0x7fffff80, v33
	v_bitop3_b32 v21, v33, s19, v33 bitop3:0xcf
	v_cmp_gt_i32_e32 vcc, 0, v33
	v_and_b32_e32 v24, 0x7fffff80, v40
	v_bitop3_b32 v25, v40, s19, v40 bitop3:0xcf
	v_cndmask_b32_e32 v31, v21, v15, vcc
	v_and_b32_e32 v15, 0x7fffff80, v49
	v_bitop3_b32 v21, v49, s19, v49 bitop3:0xcf
	v_cmp_gt_i32_e32 vcc, 0, v49
	s_nop 1
	v_cndmask_b32_e32 v39, v21, v15, vcc
	v_cmp_gt_i32_e32 vcc, 0, v40
	v_bitop3_b32 v15, v33, s19, v33 bitop3:0xc
	v_bitop3_b32 v21, v49, s19, v49 bitop3:0xc
	v_cndmask_b32_e32 v32, v25, v24, vcc
	v_and_b32_e32 v24, 0x7fffff80, v48
	v_bitop3_b32 v25, v48, s19, v48 bitop3:0xcf
	v_cmp_gt_i32_e32 vcc, 0, v48
	v_bitop3_b32 v33, v46, s19, v46 bitop3:0xcf
	s_nop 0
	v_cndmask_b32_e32 v38, v25, v24, vcc
	v_bitop3_b32 v24, v40, s19, v40 bitop3:0xc
	ds_write2_b32 v5, v15, v24 offset0:12 offset1:13
	v_bitop3_b32 v15, v48, s19, v48 bitop3:0xc
	ds_write2_b32 v5, v21, v15 offset0:28 offset1:29
	v_and_b32_e32 v15, 0x7fffff80, v42
	v_bitop3_b32 v21, v42, s19, v42 bitop3:0xcf
	v_cmp_gt_i32_e32 vcc, 0, v42
	v_and_b32_e32 v24, 0x7fffff80, v43
	s_nop 0
	v_cndmask_b32_e32 v25, v21, v15, vcc
	v_and_b32_e32 v15, 0x7fffff80, v47
	v_bitop3_b32 v21, v47, s19, v47 bitop3:0xcf
	v_cmp_gt_i32_e32 vcc, 0, v47
	s_nop 1
	v_cndmask_b32_e32 v41, v21, v15, vcc
	v_cmp_gt_i32_e32 vcc, 0, v43
	v_bitop3_b32 v21, v47, s19, v47 bitop3:0xc
	v_bitop3_b32 v15, v42, s19, v42 bitop3:0xc
	v_cndmask_b32_e32 v26, v26, v24, vcc
	v_and_b32_e32 v24, 0x7fffff80, v46
	v_cmp_gt_i32_e32 vcc, 0, v46
	v_pk_add_f32 v[34:35], v[20:21], v[34:35] op_sel_hi:[0,1]
	s_nop 0
	v_cndmask_b32_e32 v40, v33, v24, vcc
	v_bitop3_b32 v24, v43, s19, v43 bitop3:0xc
	v_pk_add_f32 v[42:43], v[20:21], v[0:1] op_sel_hi:[0,1]
	ds_write2_b32 v5, v15, v24 offset0:14 offset1:15
	v_not_b32_e32 v15, v43
	v_or_b32_e32 v33, 0x80000000, v43
	v_cmp_gt_i32_e32 vcc, 0, v43
	v_or_b32_e32 v43, 0x80000000, v42
	v_bitop3_b32 v24, v46, s19, v46 bitop3:0xc
	v_cndmask_b32_e32 v15, v33, v15, vcc
	v_or_b32_e32 v33, 0xff, v15
	v_not_b32_e32 v15, v42
	v_cmp_gt_i32_e32 vcc, 0, v42
	ds_write2_b32 v5, v21, v24 offset0:30 offset1:31
	s_waitcnt lgkmcnt(0)
; #define CK(i, j) ((f2key(va[i] + vb[j]) & ~255u) | (unsigned)(255 - (16 * (i) + (j))))
; __device__ __forceinline__ void peer_tile(const Args& A, LAS unsigned char* lds, int tile) {
;     ...
;             unsigned Lf[16], Bt[16];
; #pragma unroll
;             for (int j = 0; j < 16; ++j) Lf[j] = CK(0, j);
; #pragma unroll
;             for (int j = 0; j < 8; ++j) Bt[j] = CK(1, j);
; #pragma unroll
;             for (int j = 0; j < 5; ++j) Bt[8 + j] = CK(2, j);
; #pragma unroll
;             for (int j = 0; j < 3; ++j) Bt[13 + j] = CK(4, j);
	s_nop 0
	v_cndmask_b32_e32 v15, v43, v15, vcc
	v_and_b32_e32 v15, 0xffffff00, v15
	v_pk_add_f32 v[42:43], v[20:21], v[2:3] op_sel_hi:[0,1]
	v_or_b32_e32 v44, 0xfe, v15
	v_not_b32_e32 v15, v43
	v_or_b32_e32 v45, 0x80000000, v43
	v_cmp_gt_i32_e32 vcc, 0, v43
	v_or_b32_e32 v43, 0x80000000, v42
	s_nop 0
	v_cndmask_b32_e32 v15, v45, v15, vcc
	v_and_b32_e32 v15, 0xffffff00, v15
	v_or_b32_e32 v45, 0xfd, v15
	v_not_b32_e32 v15, v42
	v_cmp_gt_i32_e32 vcc, 0, v42
	s_nop 1
	v_cndmask_b32_e32 v15, v43, v15, vcc
	v_and_b32_e32 v15, 0xffffff00, v15
	v_pk_add_f32 v[42:43], v[20:21], v[16:17] op_sel_hi:[0,1]
	v_or_b32_e32 v46, 0xfc, v15
	v_not_b32_e32 v15, v43
	v_or_b32_e32 v47, 0x80000000, v43
	v_cmp_gt_i32_e32 vcc, 0, v43
	v_or_b32_e32 v43, 0x80000000, v42
	s_nop 0
	v_cndmask_b32_e32 v15, v47, v15, vcc
	v_and_b32_e32 v15, 0xffffff00, v15
	v_or_b32_e32 v47, 0xfb, v15
	v_not_b32_e32 v15, v42
	v_cmp_gt_i32_e32 vcc, 0, v42
	s_nop 1
	v_cndmask_b32_e32 v15, v43, v15, vcc
	v_and_b32_e32 v15, 0xffffff00, v15
	v_pk_add_f32 v[42:43], v[20:21], v[22:23] op_sel_hi:[0,1]
	v_or_b32_e32 v48, 0xfa, v15
	v_not_b32_e32 v15, v43
	v_or_b32_e32 v49, 0x80000000, v43
	v_cmp_gt_i32_e32 vcc, 0, v43
	v_pk_add_f32 v[22:23], v[18:19], v[22:23] op_sel_hi:[0,1]
	s_nop 0
	v_cndmask_b32_e32 v15, v49, v15, vcc
	v_and_b32_e32 v15, 0xffffff00, v15
	v_or_b32_e32 v43, 0xf9, v15
	v_not_b32_e32 v15, v42
	v_or_b32_e32 v49, 0x80000000, v42
	v_cmp_gt_i32_e32 vcc, 0, v42
	s_nop 1
	v_cndmask_b32_e32 v15, v49, v15, vcc
	v_and_b32_e32 v15, 0xffffff00, v15
	v_or_b32_e32 v42, 0xf8, v15
	v_not_b32_e32 v15, v35
	v_or_b32_e32 v49, 0x80000000, v35
	v_cmp_gt_i32_e32 vcc, 0, v35
	v_or_b32_e32 v35, 0x80000000, v34
	s_nop 0
	v_cndmask_b32_e32 v15, v49, v15, vcc
	v_and_b32_e32 v15, 0xffffff00, v15
	v_or_b32_e32 v49, 0xf7, v15
	v_not_b32_e32 v15, v34
	v_cmp_gt_i32_e32 vcc, 0, v34
	s_nop 1
	v_cndmask_b32_e32 v15, v35, v15, vcc
	v_and_b32_e32 v15, 0xffffff00, v15
	v_pk_add_f32 v[34:35], v[20:21], v[36:37] op_sel_hi:[0,1]
	v_or_b32_e32 v50, 0xf6, v15
	v_not_b32_e32 v15, v35
	v_or_b32_e32 v36, 0x80000000, v35
	v_cmp_gt_i32_e32 vcc, 0, v35
	v_or_b32_e32 v35, 0x80000000, v34
	s_nop 0
	v_cndmask_b32_e32 v15, v36, v15, vcc
	v_and_b32_e32 v15, 0xffffff00, v15
	v_or_b32_e32 v36, 0xf5, v15
	v_not_b32_e32 v15, v34
	v_cmp_gt_i32_e32 vcc, 0, v34
	s_nop 1
	v_cndmask_b32_e32 v15, v35, v15, vcc
	v_and_b32_e32 v15, 0xffffff00, v15
	v_pk_add_f32 v[34:35], v[20:21], v[38:39] op_sel_hi:[0,1]
	v_or_b32_e32 v37, 0xf4, v15
	v_not_b32_e32 v15, v35
	v_or_b32_e32 v38, 0x80000000, v35
	v_cmp_gt_i32_e32 vcc, 0, v35
	v_or_b32_e32 v35, 0x80000000, v34
	s_nop 0
	v_cndmask_b32_e32 v15, v38, v15, vcc
	v_and_b32_e32 v15, 0xffffff00, v15
	v_or_b32_e32 v38, 0xf3, v15
	v_not_b32_e32 v15, v34
	v_cmp_gt_i32_e32 vcc, 0, v34
	s_nop 1
	v_cndmask_b32_e32 v15, v35, v15, vcc
	v_and_b32_e32 v15, 0xffffff00, v15
	v_pk_add_f32 v[34:35], v[20:21], v[40:41] op_sel_hi:[0,1]
	v_or_b32_e32 v39, 0xf2, v15
	v_not_b32_e32 v15, v35
	v_or_b32_e32 v20, 0x80000000, v35
	v_cmp_gt_i32_e32 vcc, 0, v35
	v_or_b32_e32 v35, 0x80000000, v34
	s_nop 0
	v_cndmask_b32_e32 v15, v20, v15, vcc
	v_and_b32_e32 v15, 0xffffff00, v15
	v_or_b32_e32 v20, 0xf1, v15
	v_not_b32_e32 v15, v34
	v_cmp_gt_i32_e32 vcc, 0, v34
	s_nop 1
	v_cndmask_b32_e32 v15, v35, v15, vcc
	v_and_b32_e32 v15, 0xffffff00, v15
	v_pk_add_f32 v[34:35], v[18:19], v[0:1] op_sel_hi:[0,1]
	v_or_b32_e32 v40, 0xf0, v15
	v_not_b32_e32 v15, v35
	v_or_b32_e32 v41, 0x80000000, v35
	v_cmp_gt_i32_e32 vcc, 0, v35
	v_or_b32_e32 v35, 0x80000000, v34
	s_nop 0
	v_cndmask_b32_e32 v15, v41, v15, vcc
	v_and_b32_e32 v15, 0xffffff00, v15
	v_or_b32_e32 v41, 0xef, v15
	v_not_b32_e32 v15, v34
	v_cmp_gt_i32_e32 vcc, 0, v34
	s_nop 1
	v_cndmask_b32_e32 v15, v35, v15, vcc
	v_and_b32_e32 v15, 0xffffff00, v15
	v_pk_add_f32 v[34:35], v[18:19], v[2:3] op_sel_hi:[0,1]
	v_or_b32_e32 v51, 0xee, v15
	v_not_b32_e32 v15, v35
	v_or_b32_e32 v52, 0x80000000, v35
	v_cmp_gt_i32_e32 vcc, 0, v35
	v_or_b32_e32 v35, 0x80000000, v34
	s_nop 0
	v_cndmask_b32_e32 v15, v52, v15, vcc
	v_and_b32_e32 v15, 0xffffff00, v15
	v_or_b32_e32 v52, 0xed, v15
	v_not_b32_e32 v15, v34
	v_cmp_gt_i32_e32 vcc, 0, v34
	s_nop 1
	v_cndmask_b32_e32 v15, v35, v15, vcc
	v_and_b32_e32 v15, 0xffffff00, v15
	v_pk_add_f32 v[34:35], v[18:19], v[16:17] op_sel_hi:[0,1]
	v_or_b32_e32 v53, 0xec, v15
	v_not_b32_e32 v15, v35
	v_or_b32_e32 v16, 0x80000000, v35
	v_cmp_gt_i32_e32 vcc, 0, v35
	s_nop 1
	v_cndmask_b32_e32 v15, v16, v15, vcc
	v_and_b32_e32 v15, 0xffffff00, v15
	v_or_b32_e32 v35, 0xeb, v15
	v_not_b32_e32 v15, v34
	v_or_b32_e32 v16, 0x80000000, v34
	v_cmp_gt_i32_e32 vcc, 0, v34
	s_nop 1
	v_cndmask_b32_e32 v15, v16, v15, vcc
	v_and_b32_e32 v15, 0xffffff00, v15
	v_or_b32_e32 v34, 0xea, v15
	v_not_b32_e32 v15, v23
	v_or_b32_e32 v16, 0x80000000, v23
	v_cmp_gt_i32_e32 vcc, 0, v23
	s_nop 1
	v_cndmask_b32_e32 v15, v16, v15, vcc
	v_and_b32_e32 v15, 0xffffff00, v15
	v_or_b32_e32 v18, 0xe9, v15
	v_not_b32_e32 v15, v22
	v_or_b32_e32 v16, 0x80000000, v22
	v_cmp_gt_i32_e32 vcc, 0, v22
	v_pk_add_f32 v[22:23], v[12:13], v[0:1] op_sel_hi:[0,1]
	s_nop 0
	v_cndmask_b32_e32 v15, v16, v15, vcc
	v_and_b32_e32 v15, 0xffffff00, v15
	v_or_b32_e32 v54, 0xe8, v15
	v_not_b32_e32 v15, v23
	v_or_b32_e32 v16, 0x80000000, v23
	v_cmp_gt_i32_e32 vcc, 0, v23
	s_nop 1
	v_cndmask_b32_e32 v15, v16, v15, vcc
	v_and_b32_e32 v15, 0xffffff00, v15
	v_or_b32_e32 v55, 0xdf, v15
	v_not_b32_e32 v15, v22
	v_or_b32_e32 v16, 0x80000000, v22
	v_cmp_gt_i32_e32 vcc, 0, v22
	v_pk_add_f32 v[22:23], v[12:13], v[2:3] op_sel_hi:[0,1]
	v_lshl_add_u32 v13, v13, 10, s35
	v_cndmask_b32_e32 v15, v16, v15, vcc
	v_and_b32_e32 v15, 0xffffff00, v15
; #define CE_DESC(a, b) do { const unsigned _mx = (a) > (b) ? (a) : (b), _mn = (a) > (b) ? (b) : (a); (a) = _mx; (b) = _mn; } while (0)
; #define CK(i, j) ((f2key(va[i] + vb[j]) & ~255u) | (unsigned)(255 - (16 * (i) + (j))))
; __device__ __forceinline__ void sort16_desc(unsigned (&k)[16]) {
; #pragma unroll
;     for (int size = 2; size <= 16; size <<= 1)
; #pragma unroll
;         for (int stride = size >> 1; stride > 0; stride >>= 1)
; #pragma unroll
;             for (int i = 0; i < 16; ++i) { const int j = i ^ stride;
;                 if (j > i) { if ((i & size) == 0) CE_DESC(k[i], k[j]); else CE_DESC(k[j], k[i]); } }
; }
; __device__ __forceinline__ void peer_tile(const Args& A, LAS unsigned char* lds, int tile) {
;     ...
;             unsigned Lf[16], Bt[16];
; #pragma unroll
;             for (int j = 0; j < 16; ++j) Lf[j] = CK(0, j);
; #pragma unroll
;             for (int j = 0; j < 8; ++j) Bt[j] = CK(1, j);
; #pragma unroll
;             for (int j = 0; j < 5; ++j) Bt[8 + j] = CK(2, j);
; #pragma unroll
;             for (int j = 0; j < 3; ++j) Bt[13 + j] = CK(4, j);
;             sort16_desc(Bt); merge16(Lf, Bt);
	v_or_b32_e32 v56, 0xde, v15
	v_not_b32_e32 v15, v23
	v_or_b32_e32 v16, 0x80000000, v23
	v_cmp_gt_i32_e32 vcc, 0, v23
	s_nop 1
	v_cndmask_b32_e32 v15, v16, v15, vcc
	v_and_b32_e32 v15, 0xffffff00, v15
	v_or_b32_e32 v23, 0xdd, v15
	v_not_b32_e32 v15, v22
	v_or_b32_e32 v16, 0x80000000, v22
	v_cmp_gt_i32_e32 vcc, 0, v22
	s_nop 1
	v_cndmask_b32_e32 v15, v16, v15, vcc
	v_and_b32_e32 v15, 0xffffff00, v15
	v_or_b32_e32 v22, 0xdc, v15
	v_mov_b32_e32 v15, v12
	v_mov_b32_e32 v16, v1
	v_pk_add_f32 v[16:17], v[14:15], v[16:17]
	s_nop 0
	v_not_b32_e32 v12, v17
	v_or_b32_e32 v15, 0x80000000, v17
	v_cmp_gt_i32_e32 vcc, 0, v17
	v_or_b32_e32 v17, 0x80000000, v16
	s_nop 0
	v_cndmask_b32_e32 v12, v15, v12, vcc
	v_not_b32_e32 v15, v16
	v_cmp_gt_i32_e32 vcc, 0, v16
	v_mov_b32_e32 v16, v3
	v_and_b32_e32 v12, 0xffffff00, v12
	v_cndmask_b32_e32 v15, v17, v15, vcc
	v_and_b32_e32 v15, 0xffffff00, v15
	v_mov_b32_e32 v17, v0
	v_or_b32_e32 v57, 0xbf, v15
	v_pk_add_f32 v[14:15], v[14:15], v[16:17] op_sel_hi:[0,1]
	v_not_b32_e32 v16, v15
	v_or_b32_e32 v17, 0x80000000, v15
	v_cmp_gt_i32_e32 vcc, 0, v15
	v_or_b32_e32 v12, 0xdb, v12
	v_pk_add_f32 v[2:3], v[4:5], v[2:3] op_sel_hi:[0,1]
	v_cndmask_b32_e32 v15, v17, v16, vcc
	v_not_b32_e32 v16, v14
	v_or_b32_e32 v17, 0x80000000, v14
	v_cmp_gt_i32_e32 vcc, 0, v14
	v_and_b32_e32 v15, 0xffffff00, v15
	v_or_b32_e32 v15, 0xbe, v15
	v_cndmask_b32_e32 v14, v17, v16, vcc
	v_and_b32_e32 v14, 0xffffff00, v14
	v_or_b32_e32 v14, 0xbd, v14
	v_max_u32_e32 v16, v41, v51
	v_min_u32_e32 v17, v41, v51
	v_max_u32_e32 v41, v53, v52
	v_min_u32_e32 v51, v53, v52
	v_max_u32_e32 v52, v35, v34
	v_min_u32_e32 v34, v35, v34
	v_max_u32_e32 v35, v54, v18
	v_min_u32_e32 v18, v54, v18
	v_max_u32_e32 v53, v55, v56
	v_min_u32_e32 v54, v55, v56
	v_max_u32_e32 v55, v22, v23
	v_min_u32_e32 v22, v22, v23
	v_max_u32_e32 v23, v12, v57
	v_min_u32_e32 v12, v12, v57
	v_max_u32_e32 v56, v14, v15
	v_min_u32_e32 v14, v14, v15
	v_max_u32_e32 v15, v16, v51
	v_min_u32_e32 v16, v16, v51
	v_max_u32_e32 v51, v17, v41
	v_min_u32_e32 v17, v17, v41
	v_max_u32_e32 v41, v18, v52
	v_min_u32_e32 v18, v18, v52
	v_max_u32_e32 v52, v35, v34
	v_min_u32_e32 v34, v35, v34
	v_max_u32_e32 v35, v53, v22
	v_min_u32_e32 v22, v53, v22
	v_max_u32_e32 v53, v54, v55
	v_min_u32_e32 v54, v54, v55
	v_max_u32_e32 v55, v14, v23
	v_min_u32_e32 v14, v14, v23
	v_max_u32_e32 v23, v56, v12
	v_min_u32_e32 v12, v56, v12
	v_max_u32_e32 v56, v15, v51
	v_min_u32_e32 v15, v15, v51
	v_max_u32_e32 v51, v16, v17
	v_min_u32_e32 v16, v16, v17
	v_max_u32_e32 v17, v34, v18
	v_min_u32_e32 v18, v34, v18
	v_max_u32_e32 v34, v52, v41
	v_min_u32_e32 v41, v52, v41
	v_max_u32_e32 v52, v35, v53
	v_min_u32_e32 v35, v35, v53
	v_max_u32_e32 v53, v22, v54
	v_min_u32_e32 v22, v22, v54
	v_max_u32_e32 v54, v12, v14
	v_min_u32_e32 v12, v12, v14
	v_max_u32_e32 v14, v23, v55
	v_min_u32_e32 v23, v23, v55
	v_max_u32_e32 v55, v56, v18
	v_min_u32_e32 v18, v56, v18
	v_max_u32_e32 v56, v15, v17
	v_min_u32_e32 v15, v15, v17
	v_max_u32_e32 v17, v51, v41
	v_min_u32_e32 v41, v51, v41
	v_max_u32_e32 v51, v16, v34
	v_min_u32_e32 v16, v16, v34
	v_max_u32_e32 v34, v12, v52
	v_min_u32_e32 v12, v12, v52
	v_max_u32_e32 v52, v54, v35
	v_min_u32_e32 v35, v54, v35
	v_max_u32_e32 v54, v23, v53
	v_min_u32_e32 v23, v23, v53
	v_max_u32_e32 v53, v14, v22
	v_min_u32_e32 v14, v14, v22
	v_max_u32_e32 v22, v55, v17
	v_min_u32_e32 v17, v55, v17
	v_max_u32_e32 v55, v56, v51
	v_min_u32_e32 v51, v56, v51
	v_max_u32_e32 v56, v18, v41
	v_min_u32_e32 v18, v18, v41
	v_max_u32_e32 v41, v15, v16
	v_min_u32_e32 v15, v15, v16
	v_max_u32_e32 v16, v23, v12
	v_min_u32_e32 v12, v23, v12
	v_max_u32_e32 v23, v14, v35
	v_min_u32_e32 v14, v14, v35
	v_max_u32_e32 v35, v54, v34
	v_min_u32_e32 v34, v54, v34
	v_max_u32_e32 v54, v53, v52
	v_min_u32_e32 v52, v53, v52
	v_max_u32_e32 v53, v22, v55
	v_min_u32_e32 v22, v22, v55
	v_max_u32_e32 v55, v17, v51
	v_min_u32_e32 v17, v17, v51
	v_max_u32_e32 v51, v56, v41
	v_min_u32_e32 v41, v56, v41
	v_max_u32_e32 v56, v18, v15
	v_min_u32_e32 v15, v18, v15
	v_max_u32_e32 v18, v14, v12
	v_min_u32_e32 v12, v14, v12
	v_max_u32_e32 v14, v23, v16
	v_min_u32_e32 v16, v23, v16
	v_max_u32_e32 v23, v52, v34
	v_min_u32_e32 v34, v52, v34
	v_max_u32_e32 v52, v54, v35
	v_min_u32_e32 v35, v54, v35
	v_max_u32_e32 v54, v53, v12
	v_min_u32_e32 v12, v53, v12
	v_max_u32_e32 v53, v22, v18
	v_min_u32_e32 v18, v22, v18
	v_max_u32_e32 v22, v55, v16
	v_min_u32_e32 v16, v55, v16
	v_max_u32_e32 v55, v17, v14
	v_min_u32_e32 v14, v17, v14
	v_max_u32_e32 v17, v51, v34
	v_min_u32_e32 v34, v51, v34
	v_max_u32_e32 v51, v41, v23
	v_min_u32_e32 v23, v41, v23
	v_max_u32_e32 v41, v56, v35
	v_min_u32_e32 v35, v56, v35
	v_max_u32_e32 v56, v15, v52
	v_min_u32_e32 v15, v15, v52
	v_max_u32_e32 v52, v54, v17
	v_min_u32_e32 v17, v54, v17
	v_max_u32_e32 v54, v53, v51
	v_min_u32_e32 v51, v53, v51
	v_max_u32_e32 v53, v22, v41
	v_min_u32_e32 v22, v22, v41
	v_max_u32_e32 v41, v55, v56
	v_min_u32_e32 v55, v55, v56
	v_max_u32_e32 v56, v12, v34
	v_min_u32_e32 v12, v12, v34
	v_max_u32_e32 v34, v18, v23
	v_min_u32_e32 v18, v18, v23
	v_max_u32_e32 v23, v16, v35
	v_min_u32_e32 v16, v16, v35
	v_max_u32_e32 v35, v14, v15
	v_min_u32_e32 v14, v14, v15
	v_max_u32_e32 v15, v52, v53
	v_min_u32_e32 v52, v52, v53
	v_max_u32_e32 v53, v54, v41
	v_min_u32_e32 v41, v54, v41
	v_max_u32_e32 v54, v17, v22
	v_min_u32_e32 v17, v17, v22
	v_max_u32_e32 v22, v51, v55
	v_min_u32_e32 v51, v51, v55
	v_max_u32_e32 v55, v56, v23
	v_min_u32_e32 v23, v56, v23
	v_max_u32_e32 v56, v34, v35
	v_min_u32_e32 v34, v34, v35
	v_max_u32_e32 v35, v12, v16
	v_min_u32_e32 v12, v12, v16
	v_max_u32_e32 v16, v18, v14
	v_min_u32_e32 v14, v18, v14
; #define CE_DESC(a, b) do { const unsigned _mx = (a) > (b) ? (a) : (b), _mn = (a) > (b) ? (b) : (a); (a) = _mx; (b) = _mn; } while (0)
; #define CK(i, j) ((f2key(va[i] + vb[j]) & ~255u) | (unsigned)(255 - (16 * (i) + (j))))
; __device__ __forceinline__ void merge16(unsigned (&a)[16], const unsigned (&b)[16]) {
; #pragma unroll
;     for (int i = 0; i < 16; ++i) a[i] = a[i] > b[15 - i] ? a[i] : b[15 - i];
; #pragma unroll
;     for (int stride = 8; stride > 0; stride >>= 1)
; #pragma unroll
;         for (int i = 0; i < 16; ++i) { const int j = i ^ stride; if (j > i) CE_DESC(a[i], a[j]); }
; }
; __device__ __forceinline__ void peer_tile(const Args& A, LAS unsigned char* lds, int tile) {
;     ...
;             sort16_desc(Bt); merge16(Lf, Bt);
; #pragma unroll
;             for (int j = 0; j < 4; ++j) Bt[j] = CK(3, j);
;             Bt[4] = CK(5, 0); Bt[5] = CK(5, 1); Bt[6] = CK(6, 0); Bt[7] = CK(6, 1); Bt[8] = CK(7, 0); Bt[9] = CK(7, 1);
;             Bt[10] = CK(8, 0); Bt[11] = CK(9, 0); Bt[12] = CK(10, 0); Bt[13] = CK(11, 0); Bt[14] = CK(12, 0); Bt[15] = CK(13, 0);
;             sort16_desc(Bt); merge16(Lf, Bt);
	v_min_u32_e32 v18, v15, v53
	v_min_u32_e32 v57, v52, v41
	v_min_u32_e32 v58, v54, v22
	v_min_u32_e32 v59, v17, v51
	v_min_u32_e32 v60, v55, v56
	v_min_u32_e32 v61, v23, v34
	v_min_u32_e32 v62, v35, v16
	v_min_u32_e32 v63, v12, v14
	v_max_u32_e32 v33, v33, v63
	v_max3_u32 v12, v44, v12, v14
	v_max_u32_e32 v14, v45, v62
	v_max3_u32 v16, v46, v35, v16
	v_max_u32_e32 v35, v47, v61
	v_max3_u32 v23, v48, v23, v34
	v_max_u32_e32 v34, v43, v60
	v_max3_u32 v42, v42, v55, v56
	v_max_u32_e32 v43, v49, v59
	v_max3_u32 v17, v50, v17, v51
	v_max_u32_e32 v36, v36, v58
	v_max3_u32 v22, v37, v54, v22
	v_max_u32_e32 v37, v38, v57
	v_max3_u32 v38, v39, v52, v41
	v_max_u32_e32 v18, v20, v18
	v_max3_u32 v15, v40, v15, v53
	v_max_u32_e32 v20, v33, v43
	v_min_u32_e32 v33, v33, v43
	v_max_u32_e32 v39, v12, v17
	v_min_u32_e32 v12, v12, v17
	v_max_u32_e32 v17, v14, v36
	v_min_u32_e32 v14, v14, v36
	v_max_u32_e32 v36, v16, v22
	v_min_u32_e32 v16, v16, v22
	v_max_u32_e32 v22, v35, v37
	v_min_u32_e32 v35, v35, v37
	v_max_u32_e32 v37, v23, v38
	v_min_u32_e32 v23, v23, v38
	v_max_u32_e32 v38, v34, v18
	v_min_u32_e32 v18, v34, v18
	v_max_u32_e32 v34, v42, v15
	v_min_u32_e32 v15, v42, v15
	v_max_u32_e32 v40, v20, v22
	v_min_u32_e32 v20, v20, v22
	v_max_u32_e32 v22, v39, v37
	v_min_u32_e32 v37, v39, v37
	v_max_u32_e32 v39, v17, v38
	v_min_u32_e32 v17, v17, v38
	v_max_u32_e32 v38, v36, v34
	v_min_u32_e32 v34, v36, v34
	v_max_u32_e32 v36, v33, v35
	v_min_u32_e32 v33, v33, v35
	v_max_u32_e32 v35, v12, v23
	v_min_u32_e32 v12, v12, v23
	v_max_u32_e32 v23, v14, v18
	v_min_u32_e32 v14, v14, v18
	v_max_u32_e32 v18, v16, v15
	v_min_u32_e32 v15, v16, v15
	v_max_u32_e32 v16, v40, v39
	v_min_u32_e32 v39, v40, v39
	v_max_u32_e32 v40, v22, v38
	v_min_u32_e32 v22, v22, v38
	v_max_u32_e32 v38, v20, v17
	v_min_u32_e32 v17, v20, v17
	v_max_u32_e32 v20, v37, v34
	v_min_u32_e32 v34, v37, v34
	v_max_u32_e32 v37, v36, v23
	v_min_u32_e32 v23, v36, v23
	v_max_u32_e32 v36, v35, v18
	v_min_u32_e32 v18, v35, v18
	v_max_u32_e32 v35, v33, v14
	v_min_u32_e32 v33, v33, v14
	v_max_u32_e32 v41, v12, v15
	v_min_u32_e32 v12, v12, v15
	v_pk_add_f32 v[14:15], v[4:5], v[0:1] op_sel_hi:[0,1]
	v_not_b32_e32 v50, v15
	v_or_b32_e32 v51, 0x80000000, v15
	v_cmp_gt_i32_e32 vcc, 0, v15
	v_not_b32_e32 v4, v3
	v_min_u32_e32 v42, v16, v40
	v_cndmask_b32_e32 v15, v51, v50, vcc
	v_not_b32_e32 v50, v14
	v_or_b32_e32 v51, 0x80000000, v14
	v_cmp_gt_i32_e32 vcc, 0, v14
	v_and_b32_e32 v15, 0xffffff00, v15
	v_or_b32_e32 v15, 0xcf, v15
	v_cndmask_b32_e32 v14, v51, v50, vcc
	v_or_b32_e32 v50, 0x80000000, v3
	v_cmp_gt_i32_e32 vcc, 0, v3
	v_and_b32_e32 v14, 0xffffff00, v14
	v_or_b32_e32 v14, 0xce, v14
	v_cndmask_b32_e32 v3, v50, v4, vcc
	v_and_b32_e32 v3, 0xffffff00, v3
	v_or_b32_e32 v4, 0xcd, v3
	v_not_b32_e32 v3, v2
	v_or_b32_e32 v50, 0x80000000, v2
	v_cmp_gt_i32_e32 vcc, 0, v2
	v_min_u32_e32 v43, v39, v22
	v_min_u32_e32 v44, v38, v20
	v_cndmask_b32_e32 v2, v50, v3, vcc
	v_and_b32_e32 v2, 0xffffff00, v2
	v_or_b32_e32 v50, 0xcc, v2
	v_pk_add_f32 v[2:3], v[10:11], v[0:1] op_sel_hi:[0,1]
	v_not_b32_e32 v10, v3
	v_or_b32_e32 v51, 0x80000000, v3
	v_cmp_gt_i32_e32 vcc, 0, v3
	v_min_u32_e32 v45, v17, v34
	v_min_u32_e32 v46, v37, v36
	v_cndmask_b32_e32 v3, v51, v10, vcc
	v_and_b32_e32 v3, 0xffffff00, v3
	v_or_b32_e32 v10, 0xaf, v3
	v_not_b32_e32 v3, v2
	v_or_b32_e32 v51, 0x80000000, v2
	v_cmp_gt_i32_e32 vcc, 0, v2
	v_min_u32_e32 v47, v23, v18
	v_min_u32_e32 v48, v35, v41
	v_cndmask_b32_e32 v2, v51, v3, vcc
	v_and_b32_e32 v2, 0xffffff00, v2
	v_or_b32_e32 v51, 0xae, v2
	v_pk_add_f32 v[2:3], v[8:9], v[0:1] op_sel_hi:[0,1]
	v_not_b32_e32 v8, v3
	v_or_b32_e32 v52, 0x80000000, v3
	v_cmp_gt_i32_e32 vcc, 0, v3
	v_min_u32_e32 v49, v33, v12
	v_lshlrev_b32_e32 v11, 9, v11
	v_cndmask_b32_e32 v3, v52, v8, vcc
	v_and_b32_e32 v3, 0xffffff00, v3
	v_or_b32_e32 v8, 0x9f, v3
	v_not_b32_e32 v3, v2
	v_or_b32_e32 v52, 0x80000000, v2
	v_cmp_gt_i32_e32 vcc, 0, v2
	s_nop 1
	v_cndmask_b32_e32 v2, v52, v3, vcc
	v_and_b32_e32 v2, 0xffffff00, v2
	v_or_b32_e32 v52, 0x9e, v2
	v_pk_add_f32 v[2:3], v[6:7], v[0:1] op_sel_hi:[0,1]
	v_not_b32_e32 v0, v3
	v_or_b32_e32 v6, 0x80000000, v3
	v_cmp_gt_i32_e32 vcc, 0, v3
	v_not_b32_e32 v3, v2
	s_nop 0
	v_cndmask_b32_e32 v0, v6, v0, vcc
	v_or_b32_e32 v6, 0x80000000, v2
	v_cmp_gt_i32_e32 vcc, 0, v2
	v_and_b32_e32 v0, 0xffffff00, v0
	v_or_b32_e32 v0, 0x8f, v0
	v_cndmask_b32_e32 v2, v6, v3, vcc
	v_add_f32_e32 v3, v27, v1
	v_not_b32_e32 v6, v3
	v_or_b32_e32 v27, 0x80000000, v3
	v_cmp_gt_i32_e32 vcc, 0, v3
	v_and_b32_e32 v2, 0xffffff00, v2
	v_or_b32_e32 v2, 0x8e, v2
	v_cndmask_b32_e32 v3, v27, v6, vcc
	v_add_f32_e32 v6, v28, v1
	v_not_b32_e32 v27, v6
	v_or_b32_e32 v28, 0x80000000, v6
	v_cmp_gt_i32_e32 vcc, 0, v6
	v_and_b32_e32 v3, 0xffffff00, v3
	v_or_b32_e32 v3, 0x7f, v3
	v_cndmask_b32_e32 v6, v28, v27, vcc
	v_add_f32_e32 v27, v29, v1
	v_not_b32_e32 v28, v27
	v_or_b32_e32 v29, 0x80000000, v27
	v_cmp_gt_i32_e32 vcc, 0, v27
	v_and_b32_e32 v6, 0xffffff00, v6
	v_or_b32_e32 v6, 0x6f, v6
	v_cndmask_b32_e32 v27, v29, v28, vcc
	v_add_f32_e32 v28, v30, v1
	v_not_b32_e32 v29, v28
	v_or_b32_e32 v30, 0x80000000, v28
	v_cmp_gt_i32_e32 vcc, 0, v28
	v_and_b32_e32 v27, 0xffffff00, v27
	v_or_b32_e32 v27, 0x5f, v27
	v_cndmask_b32_e32 v28, v30, v29, vcc
	v_add_f32_e32 v29, v31, v1
	v_not_b32_e32 v30, v29
	v_or_b32_e32 v31, 0x80000000, v29
	v_cmp_gt_i32_e32 vcc, 0, v29
	v_and_b32_e32 v28, 0xffffff00, v28
	v_or_b32_e32 v28, 0x4f, v28
	v_cndmask_b32_e32 v29, v31, v30, vcc
	v_add_f32_e32 v30, v32, v1
	v_not_b32_e32 v31, v30
	v_or_b32_e32 v32, 0x80000000, v30
	v_cmp_gt_i32_e32 vcc, 0, v30
	v_and_or_b32 v29, v29, s34, 63
	s_nop 0
	v_cndmask_b32_e32 v30, v32, v31, vcc
; #define CE_DESC(a, b) do { const unsigned _mx = (a) > (b) ? (a) : (b), _mn = (a) > (b) ? (b) : (a); (a) = _mx; (b) = _mn; } while (0)
; #define CK(i, j) ((f2key(va[i] + vb[j]) & ~255u) | (unsigned)(255 - (16 * (i) + (j))))
; __device__ __forceinline__ void sort16_desc(unsigned (&k)[16]) {
; #pragma unroll
;     for (int size = 2; size <= 16; size <<= 1)
; #pragma unroll
;         for (int stride = size >> 1; stride > 0; stride >>= 1)
; #pragma unroll
;             for (int i = 0; i < 16; ++i) { const int j = i ^ stride;
;                 if (j > i) { if ((i & size) == 0) CE_DESC(k[i], k[j]); else CE_DESC(k[j], k[i]); } }
; }
; __device__ __forceinline__ void merge16(unsigned (&a)[16], const unsigned (&b)[16]) {
; #pragma unroll
;     for (int i = 0; i < 16; ++i) a[i] = a[i] > b[15 - i] ? a[i] : b[15 - i];
; #pragma unroll
;     for (int stride = 8; stride > 0; stride >>= 1)
; #pragma unroll
;         for (int i = 0; i < 16; ++i) { const int j = i ^ stride; if (j > i) CE_DESC(a[i], a[j]); }
; }
; __device__ __forceinline__ void peer_tile(const Args& A, LAS unsigned char* lds, int tile) {
;     ...
;             sort16_desc(Bt); merge16(Lf, Bt);
; #pragma unroll
;             for (int j = 0; j < 4; ++j) Bt[j] = CK(3, j);
;             Bt[4] = CK(5, 0); Bt[5] = CK(5, 1); Bt[6] = CK(6, 0); Bt[7] = CK(6, 1); Bt[8] = CK(7, 0); Bt[9] = CK(7, 1);
;             Bt[10] = CK(8, 0); Bt[11] = CK(9, 0); Bt[12] = CK(10, 0); Bt[13] = CK(11, 0); Bt[14] = CK(12, 0); Bt[15] = CK(13, 0);
;             sort16_desc(Bt); merge16(Lf, Bt);
	v_and_or_b32 v30, v30, s34, 47
	v_max_u32_e32 v31, v15, v14
	v_min_u32_e32 v14, v15, v14
	v_max_u32_e32 v15, v50, v4
	v_min_u32_e32 v4, v50, v4
	v_max_u32_e32 v32, v10, v51
	v_min_u32_e32 v10, v10, v51
	v_max_u32_e32 v50, v52, v8
	v_min_u32_e32 v8, v52, v8
	v_max_u32_e32 v51, v0, v2
	v_min_u32_e32 v0, v0, v2
	v_max_u32_e32 v2, v6, v3
	v_min_u32_e32 v3, v6, v3
	v_max_u32_e32 v6, v27, v28
	v_min_u32_e32 v27, v27, v28
	v_max_u32_e32 v28, v30, v29
	v_min_u32_e32 v29, v30, v29
	v_max_u32_e32 v30, v31, v4
	v_min_u32_e32 v4, v31, v4
	v_max_u32_e32 v31, v14, v15
	v_min_u32_e32 v14, v14, v15
	v_max_u32_e32 v15, v8, v32
	v_min_u32_e32 v8, v8, v32
	v_max_u32_e32 v32, v50, v10
	v_min_u32_e32 v10, v50, v10
	v_max_u32_e32 v50, v51, v3
	v_min_u32_e32 v3, v51, v3
	v_max_u32_e32 v51, v0, v2
	v_min_u32_e32 v0, v0, v2
	v_max_u32_e32 v2, v29, v6
	v_min_u32_e32 v6, v29, v6
	v_max_u32_e32 v29, v28, v27
	v_min_u32_e32 v27, v28, v27
	v_max_u32_e32 v28, v30, v31
	v_min_u32_e32 v30, v30, v31
	v_max_u32_e32 v31, v4, v14
	v_min_u32_e32 v4, v4, v14
	v_max_u32_e32 v14, v10, v8
	v_min_u32_e32 v8, v10, v8
	v_max_u32_e32 v10, v32, v15
	v_min_u32_e32 v15, v32, v15
	v_max_u32_e32 v32, v50, v51
	v_min_u32_e32 v50, v50, v51
	v_max_u32_e32 v51, v3, v0
	v_min_u32_e32 v0, v3, v0
	v_max_u32_e32 v3, v27, v6
	v_min_u32_e32 v6, v27, v6
	v_max_u32_e32 v27, v29, v2
	v_min_u32_e32 v2, v29, v2
	v_max_u32_e32 v29, v28, v8
	v_min_u32_e32 v8, v28, v8
	v_max_u32_e32 v28, v30, v14
	v_min_u32_e32 v14, v30, v14
	v_max_u32_e32 v30, v31, v15
	v_min_u32_e32 v15, v31, v15
	v_max_u32_e32 v31, v4, v10
	v_min_u32_e32 v4, v4, v10
	v_max_u32_e32 v10, v6, v32
	v_min_u32_e32 v6, v6, v32
	v_max_u32_e32 v32, v3, v50
	v_min_u32_e32 v3, v3, v50
	v_max_u32_e32 v50, v2, v51
	v_min_u32_e32 v2, v2, v51
	v_max_u32_e32 v51, v27, v0
	v_min_u32_e32 v0, v27, v0
	v_max_u32_e32 v27, v29, v30
	v_min_u32_e32 v29, v29, v30
	v_max_u32_e32 v30, v28, v31
	v_min_u32_e32 v28, v28, v31
	v_max_u32_e32 v31, v8, v15
	v_min_u32_e32 v8, v8, v15
	v_max_u32_e32 v15, v14, v4
	v_min_u32_e32 v4, v14, v4
	v_max_u32_e32 v14, v2, v6
	v_min_u32_e32 v2, v2, v6
	v_max_u32_e32 v6, v0, v3
	v_min_u32_e32 v0, v0, v3
	v_max_u32_e32 v3, v50, v10
	v_min_u32_e32 v10, v50, v10
	v_max_u32_e32 v50, v51, v32
	v_min_u32_e32 v32, v51, v32
	v_max_u32_e32 v51, v27, v30
	v_min_u32_e32 v27, v27, v30
	v_max_u32_e32 v30, v29, v28
	v_min_u32_e32 v28, v29, v28
	v_max_u32_e32 v29, v31, v15
	v_min_u32_e32 v15, v31, v15
	v_max_u32_e32 v31, v8, v4
	v_min_u32_e32 v4, v8, v4
	v_max_u32_e32 v8, v0, v2
	v_min_u32_e32 v0, v0, v2
	v_max_u32_e32 v2, v6, v14
	v_min_u32_e32 v6, v6, v14
	v_max_u32_e32 v14, v32, v10
	v_min_u32_e32 v10, v32, v10
	v_max_u32_e32 v32, v50, v3
	v_min_u32_e32 v3, v50, v3
	v_max_u32_e32 v50, v51, v0
	v_min_u32_e32 v0, v51, v0
	v_max_u32_e32 v51, v27, v8
	v_min_u32_e32 v8, v27, v8
	v_max_u32_e32 v27, v30, v6
	v_min_u32_e32 v6, v30, v6
	v_max_u32_e32 v30, v28, v2
	v_min_u32_e32 v2, v28, v2
	v_max_u32_e32 v28, v29, v10
	v_min_u32_e32 v10, v29, v10
	v_max_u32_e32 v29, v15, v14
	v_min_u32_e32 v14, v15, v14
	v_max_u32_e32 v15, v31, v3
	v_min_u32_e32 v3, v31, v3
	v_max_u32_e32 v31, v4, v32
	v_min_u32_e32 v4, v4, v32
	v_max_u32_e32 v32, v50, v28
	v_min_u32_e32 v28, v50, v28
	v_max_u32_e32 v50, v51, v29
	v_min_u32_e32 v29, v51, v29
	v_max_u32_e32 v51, v27, v15
	v_min_u32_e32 v15, v27, v15
	v_max_u32_e32 v27, v30, v31
	v_min_u32_e32 v30, v30, v31
	v_max_u32_e32 v31, v0, v10
	v_min_u32_e32 v0, v0, v10
	v_max_u32_e32 v10, v8, v14
	v_min_u32_e32 v8, v8, v14
	v_max_u32_e32 v14, v6, v3
	v_min_u32_e32 v3, v6, v3
	v_max_u32_e32 v6, v2, v4
	v_min_u32_e32 v2, v2, v4
	v_max_u32_e32 v4, v32, v51
	v_min_u32_e32 v32, v32, v51
	v_max_u32_e32 v51, v50, v27
	v_min_u32_e32 v27, v50, v27
	v_max_u32_e32 v50, v28, v15
	v_min_u32_e32 v15, v28, v15
	v_max_u32_e32 v28, v29, v30
	v_min_u32_e32 v29, v29, v30
	v_max_u32_e32 v30, v31, v14
	v_min_u32_e32 v14, v31, v14
	v_max_u32_e32 v31, v10, v6
	v_min_u32_e32 v6, v10, v6
	v_max_u32_e32 v10, v0, v3
	v_min_u32_e32 v0, v0, v3
	v_max_u32_e32 v3, v8, v2
	v_min_u32_e32 v2, v8, v2
	v_min_u32_e32 v8, v4, v51
	v_min_u32_e32 v52, v32, v27
	v_min_u32_e32 v53, v50, v28
	v_min_u32_e32 v54, v15, v29
	v_min_u32_e32 v55, v30, v31
	v_min_u32_e32 v56, v14, v6
	v_min_u32_e32 v57, v10, v3
	v_min_u32_e32 v58, v0, v2
	v_max3_u32 v16, v16, v40, v58
	v_max3_u32 v0, v42, v0, v2
	v_max3_u32 v2, v39, v22, v57
	v_max3_u32 v3, v43, v10, v3
	v_max3_u32 v10, v38, v20, v56
	v_max3_u32 v6, v44, v14, v6
	v_max3_u32 v14, v17, v34, v55
	v_max3_u32 v17, v45, v30, v31
	v_max3_u32 v20, v37, v36, v54
	v_max3_u32 v15, v46, v15, v29
	v_max3_u32 v18, v23, v18, v53
	v_max3_u32 v22, v47, v50, v28
	v_max3_u32 v23, v35, v41, v52
	v_max3_u32 v27, v48, v32, v27
	v_max3_u32 v8, v33, v12, v8
	v_max3_u32 v4, v49, v4, v51
	v_max_u32_e32 v12, v16, v20
	v_min_u32_e32 v16, v16, v20
	v_max_u32_e32 v20, v0, v15
	v_min_u32_e32 v0, v0, v15
	v_max_u32_e32 v15, v2, v18
	v_min_u32_e32 v2, v2, v18
	v_max_u32_e32 v18, v3, v22
	v_min_u32_e32 v3, v3, v22
	v_max_u32_e32 v22, v10, v23
	v_min_u32_e32 v10, v10, v23
	v_max_u32_e32 v23, v6, v27
	v_min_u32_e32 v6, v6, v27
	v_max_u32_e32 v27, v14, v8
	v_min_u32_e32 v8, v14, v8
	v_max_u32_e32 v14, v17, v4
	v_min_u32_e32 v4, v17, v4
	v_max_u32_e32 v17, v12, v22
	v_min_u32_e32 v12, v12, v22
	v_max_u32_e32 v22, v20, v23
	v_min_u32_e32 v20, v20, v23
	v_max_u32_e32 v23, v15, v27
	v_min_u32_e32 v15, v15, v27
	v_max_u32_e32 v27, v18, v14
	v_min_u32_e32 v14, v18, v14
	v_max_u32_e32 v18, v16, v10
	v_min_u32_e32 v10, v16, v10
	v_max_u32_e32 v16, v0, v6
	v_min_u32_e32 v0, v0, v6
	v_max_u32_e32 v6, v2, v8
	v_min_u32_e32 v2, v2, v8
	v_max_u32_e32 v8, v3, v4
; __device__ __forceinline__ float key2f(unsigned k) { const unsigned u = (k & 0x80000000u) ? (k & 0x7fffffffu) : ~k; return __uint_as_float(u); }
; #define CE_DESC(a, b) do { const unsigned _mx = (a) > (b) ? (a) : (b), _mn = (a) > (b) ? (b) : (a); (a) = _mx; (b) = _mn; } while (0)
; #define CK(i, j) ((f2key(va[i] + vb[j]) & ~255u) | (unsigned)(255 - (16 * (i) + (j))))
; __device__ __forceinline__ void peer_tile(const Args& A, LAS unsigned char* lds, int tile) {
;     ...
;             { unsigned x0 = CK(14, 0), x1 = CK(15, 0);
; #pragma unroll
;               for (int i = 0; i < 16; ++i) CE_DESC(Lf[i], x0);
; #pragma unroll
;               for (int i = 0; i < 16; ++i) CE_DESC(Lf[i], x1); }
;     ...
;             float fv[16], den = 0.f; const float f0 = key2f(Lf[0] & ~255u);
; #pragma unroll
;             for (int k = 0; k < 16; ++k) { fv[k] = __expf(key2f(Lf[k] & ~255u) - f0); den += fv[k]; }
;             const float rden = 1.f / den;
	v_min_u32_e32 v3, v3, v4
	v_max_u32_e32 v4, v17, v23
	v_min_u32_e32 v17, v17, v23
	v_max_u32_e32 v23, v22, v27
	v_min_u32_e32 v22, v22, v27
	v_max_u32_e32 v27, v12, v15
	v_min_u32_e32 v12, v12, v15
	v_max_u32_e32 v15, v20, v14
	v_min_u32_e32 v14, v20, v14
	v_max_u32_e32 v20, v18, v6
	v_min_u32_e32 v6, v18, v6
	v_max_u32_e32 v18, v16, v8
	v_min_u32_e32 v8, v16, v8
	v_max_u32_e32 v16, v10, v2
	v_min_u32_e32 v2, v10, v2
	v_max_u32_e32 v10, v0, v3
	v_min_u32_e32 v0, v0, v3
	v_max_u32_e32 v41, v2, v0
	v_min_u32_e32 v0, v2, v0
	v_add_f32_e32 v2, v25, v1
	v_not_b32_e32 v25, v2
	v_or_b32_e32 v42, 0x80000000, v2
	v_cmp_gt_i32_e32 vcc, 0, v2
	v_add_f32_e32 v1, v26, v1
	v_max_u32_e32 v3, v4, v23
	v_cndmask_b32_e32 v2, v42, v25, vcc
	v_and_or_b32 v2, v2, s34, 31
	v_not_b32_e32 v25, v1
	v_or_b32_e32 v26, 0x80000000, v1
	v_cmp_gt_i32_e32 vcc, 0, v1
	v_min_u32_e32 v28, v4, v23
	v_max_u32_e32 v29, v17, v22
	v_cndmask_b32_e32 v1, v26, v25, vcc
	v_max_u32_e32 v25, v3, v2
	v_min_u32_e32 v3, v3, v2
	v_min_u32_e32 v3, v28, v3
	v_min_u32_e32 v30, v17, v22
	v_med3_u32 v2, v4, v23, v2
	v_min_u32_e32 v23, v29, v3
	v_max_u32_e32 v31, v27, v15
	v_max_u32_e32 v4, v29, v3
	v_med3_u32 v3, v17, v22, v3
	v_min_u32_e32 v17, v30, v23
	v_min_u32_e32 v32, v27, v15
	v_min_u32_e32 v23, v31, v17
	v_max_u32_e32 v33, v12, v14
	v_max_u32_e32 v22, v31, v17
	v_med3_u32 v15, v27, v15, v17
	v_min_u32_e32 v17, v32, v23
	v_min_u32_e32 v34, v12, v14
	v_min_u32_e32 v26, v33, v17
	v_max_u32_e32 v35, v20, v18
	v_med3_u32 v12, v12, v14, v17
	v_min_u32_e32 v14, v34, v26
	v_min_u32_e32 v36, v20, v18
	v_min_u32_e32 v26, v35, v14
	v_max_u32_e32 v37, v6, v8
	v_max_u32_e32 v23, v33, v17
	v_max_u32_e32 v17, v35, v14
	v_med3_u32 v14, v20, v18, v14
	v_min_u32_e32 v18, v36, v26
	v_min_u32_e32 v38, v6, v8
	v_min_u32_e32 v26, v37, v18
	v_max_u32_e32 v39, v16, v10
	v_med3_u32 v6, v6, v8, v18
	v_min_u32_e32 v8, v38, v26
	v_min_u32_e32 v40, v16, v10
	v_min_u32_e32 v26, v39, v8
	v_and_or_b32 v1, v1, s34, 15
	v_max_u32_e32 v20, v37, v18
	v_max_u32_e32 v18, v39, v8
	v_med3_u32 v8, v16, v10, v8
	v_min_u32_e32 v10, v40, v26
	v_max_u32_e32 v26, v25, v1
	v_min_u32_e32 v1, v25, v1
	v_max_u32_e32 v25, v2, v1
	v_min_u32_e32 v1, v2, v1
	v_max_u32_e32 v2, v4, v1
	v_min_u32_e32 v1, v4, v1
	v_max_u32_e32 v4, v3, v1
	v_min_u32_e32 v1, v3, v1
	v_max_u32_e32 v3, v22, v1
	v_min_u32_e32 v1, v22, v1
	v_max_u32_e32 v22, v15, v1
	v_min_u32_e32 v1, v15, v1
	v_max_u32_e32 v15, v23, v1
	v_min_u32_e32 v1, v23, v1
	v_max_u32_e32 v23, v12, v1
	v_min_u32_e32 v1, v12, v1
	v_max_u32_e32 v12, v17, v1
	v_min_u32_e32 v1, v17, v1
	v_max_u32_e32 v17, v14, v1
	v_min_u32_e32 v1, v14, v1
	v_max_u32_e32 v14, v20, v1
	v_min_u32_e32 v1, v20, v1
	v_max_u32_e32 v20, v6, v1
	v_min_u32_e32 v1, v6, v1
	v_max_u32_e32 v6, v18, v1
	v_min_u32_e32 v1, v18, v1
	v_max_u32_e32 v16, v41, v10
	v_max_u32_e32 v18, v8, v1
	v_min_u32_e32 v1, v8, v1
	v_min_u32_e32 v10, v41, v10
	v_max_u32_e32 v8, v16, v1
	v_min_u32_e32 v1, v16, v1
	v_max3_u32 v10, v0, v10, v1
	v_and_b32_e32 v0, 0x7fffff00, v26
	v_bitop3_b32 v1, v26, s33, v26 bitop3:0xcf
	v_cmp_gt_i32_e32 vcc, 0, v26
	v_and_b32_e32 v16, 0x7fffff00, v25
	v_bitop3_b32 v27, v25, s33, v25 bitop3:0xcf
	v_cndmask_b32_e32 v0, v1, v0, vcc
	v_cmp_gt_i32_e32 vcc, 0, v25
	v_sub_f32_e32 v1, v0, v0
	v_bitop3_b32 v28, v2, s33, v2 bitop3:0xcf
	v_cndmask_b32_e32 v16, v27, v16, vcc
	v_and_b32_e32 v27, 0x7fffff00, v2
	v_cmp_gt_i32_e32 vcc, 0, v2
	v_mul_f32_e32 v1, 0x3fb8aa3b, v1
	v_sub_f32_e32 v16, v16, v0
	v_cndmask_b32_e32 v27, v28, v27, vcc
	v_and_b32_e32 v28, 0x7fffff00, v4
	v_bitop3_b32 v29, v4, s33, v4 bitop3:0xcf
	v_cmp_gt_i32_e32 vcc, 0, v4
	v_exp_f32_e32 v1, v1
	v_mul_f32_e32 v16, 0x3fb8aa3b, v16
	v_sub_f32_e32 v27, v27, v0
	v_cndmask_b32_e32 v28, v29, v28, vcc
	v_and_b32_e32 v30, 0x7fffff00, v3
	v_bitop3_b32 v31, v3, s33, v3 bitop3:0xcf
	v_cmp_gt_i32_e32 vcc, 0, v3
	v_exp_f32_e32 v16, v16
	v_mul_f32_e32 v27, 0x3fb8aa3b, v27
	v_sub_f32_e32 v28, v28, v0
	v_cndmask_b32_e32 v30, v31, v30, vcc
	v_and_b32_e32 v31, 0x7fffff00, v22
	v_bitop3_b32 v32, v22, s33, v22 bitop3:0xcf
	v_cmp_gt_i32_e32 vcc, 0, v22
	v_exp_f32_e32 v27, v27
	v_mul_f32_e32 v28, 0x3fb8aa3b, v28
	v_sub_f32_e32 v30, v30, v0
	v_cndmask_b32_e32 v31, v32, v31, vcc
	v_and_b32_e32 v32, 0x7fffff00, v15
	v_bitop3_b32 v33, v15, s33, v15 bitop3:0xcf
	v_cmp_gt_i32_e32 vcc, 0, v15
	v_exp_f32_e32 v28, v28
	v_mul_f32_e32 v30, 0x3fb8aa3b, v30
	v_sub_f32_e32 v31, v31, v0
	v_cndmask_b32_e32 v32, v33, v32, vcc
	v_and_b32_e32 v33, 0x7fffff00, v23
	v_bitop3_b32 v34, v23, s33, v23 bitop3:0xcf
	v_cmp_gt_i32_e32 vcc, 0, v23
	v_add_f32_e32 v29, 0, v1
	v_exp_f32_e32 v30, v30
	v_mul_f32_e32 v31, 0x3fb8aa3b, v31
	v_sub_f32_e32 v32, v32, v0
	v_cndmask_b32_e32 v33, v34, v33, vcc
	v_and_b32_e32 v34, 0x7fffff00, v12
	v_bitop3_b32 v35, v12, s33, v12 bitop3:0xcf
	v_cmp_gt_i32_e32 vcc, 0, v12
	v_add_f32_e32 v29, v29, v16
	v_exp_f32_e32 v31, v31
	v_mul_f32_e32 v32, 0x3fb8aa3b, v32
	v_sub_f32_e32 v33, v33, v0
	v_cndmask_b32_e32 v34, v35, v34, vcc
	v_and_b32_e32 v35, 0x7fffff00, v17
	v_bitop3_b32 v36, v17, s33, v17 bitop3:0xcf
	v_cmp_gt_i32_e32 vcc, 0, v17
	v_add_f32_e32 v29, v29, v27
	v_exp_f32_e32 v32, v32
	v_mul_f32_e32 v33, 0x3fb8aa3b, v33
	v_sub_f32_e32 v34, v34, v0
	v_cndmask_b32_e32 v35, v36, v35, vcc
	v_and_b32_e32 v36, 0x7fffff00, v14
	v_bitop3_b32 v37, v14, s33, v14 bitop3:0xcf
	v_cmp_gt_i32_e32 vcc, 0, v14
	v_add_f32_e32 v29, v29, v28
	v_exp_f32_e32 v33, v33
	v_mul_f32_e32 v34, 0x3fb8aa3b, v34
	v_sub_f32_e32 v35, v35, v0
	v_cndmask_b32_e32 v36, v37, v36, vcc
	v_and_b32_e32 v37, 0x7fffff00, v20
	v_bitop3_b32 v38, v20, s33, v20 bitop3:0xcf
	v_cmp_gt_i32_e32 vcc, 0, v20
	v_add_f32_e32 v29, v29, v30
; #define LDS_WAIT() asm volatile("s_waitcnt lgkmcnt(0)" ::: "memory")
; __device__ __forceinline__ float key2f(unsigned k) { const unsigned u = (k & 0x80000000u) ? (k & 0x7fffffffu) : ~k; return __uint_as_float(u); }
; __device__ __forceinline__ void peer_tile(const Args& A, LAS unsigned char* lds, int tile) {
;     ...
;             float fv[16], den = 0.f; const float f0 = key2f(Lf[0] & ~255u);
; #pragma unroll
;             for (int k = 0; k < 16; ++k) { fv[k] = __expf(key2f(Lf[k] & ~255u) - f0); den += fv[k]; }
;             const float rden = 1.f / den;
;             LDS_WAIT();
; #pragma unroll
;             for (int k = 0; k < 16; ++k) { const unsigned code = 255u - (Lf[k] & 255u); const unsigned e = idx[code >> 4] * 128u + idx[16 + (code & 15u)];
;                 u32x2 sv; sv.x = e; sv.y = __float_as_uint(fv[k] * rden); SEL[(tl * 8 + h) * 16 + k] = sv; }
	v_exp_f32_e32 v34, v34
	v_mul_f32_e32 v35, 0x3fb8aa3b, v35
	v_sub_f32_e32 v36, v36, v0
	v_cndmask_b32_e32 v37, v38, v37, vcc
	v_and_b32_e32 v38, 0x7fffff00, v6
	v_bitop3_b32 v39, v6, s33, v6 bitop3:0xcf
	v_cmp_gt_i32_e32 vcc, 0, v6
	v_add_f32_e32 v29, v29, v31
	v_exp_f32_e32 v35, v35
	v_mul_f32_e32 v36, 0x3fb8aa3b, v36
	v_sub_f32_e32 v37, v37, v0
	v_cndmask_b32_e32 v38, v39, v38, vcc
	v_and_b32_e32 v39, 0x7fffff00, v18
	v_bitop3_b32 v40, v18, s33, v18 bitop3:0xcf
	v_cmp_gt_i32_e32 vcc, 0, v18
	v_add_f32_e32 v29, v29, v32
	v_exp_f32_e32 v36, v36
	v_mul_f32_e32 v37, 0x3fb8aa3b, v37
	v_sub_f32_e32 v38, v38, v0
	v_cndmask_b32_e32 v39, v40, v39, vcc
	v_and_b32_e32 v40, 0x7fffff00, v8
	v_bitop3_b32 v41, v8, s33, v8 bitop3:0xcf
	v_cmp_gt_i32_e32 vcc, 0, v8
	v_add_f32_e32 v29, v29, v33
	v_exp_f32_e32 v37, v37
	v_mul_f32_e32 v38, 0x3fb8aa3b, v38
	v_sub_f32_e32 v39, v39, v0
	v_cndmask_b32_e32 v40, v41, v40, vcc
	v_and_b32_e32 v41, 0x7fffff00, v10
	v_bitop3_b32 v42, v10, s33, v10 bitop3:0xcf
	v_cmp_gt_i32_e32 vcc, 0, v10
	v_add_f32_e32 v29, v29, v34
	v_exp_f32_e32 v38, v38
	v_mul_f32_e32 v39, 0x3fb8aa3b, v39
	v_sub_f32_e32 v40, v40, v0
	v_cndmask_b32_e32 v41, v42, v41, vcc
	v_add_f32_e32 v29, v29, v35
	v_exp_f32_e32 v39, v39
	v_mul_f32_e32 v40, 0x3fb8aa3b, v40
	v_sub_f32_e32 v0, v41, v0
	v_add_f32_e32 v29, v29, v36
	v_exp_f32_e32 v40, v40
	v_mul_f32_e32 v0, 0x3fb8aa3b, v0
	v_add_f32_e32 v29, v29, v37
	v_exp_f32_e32 v41, v0
	v_add_f32_e32 v0, v29, v38
	v_add_f32_e32 v0, v0, v39
	v_add_f32_e32 v0, v0, v40
	v_add_f32_e32 v0, v0, v41
	v_div_scale_f32 v29, s[0:1], v0, v0, 1.0
	v_rcp_f32_e32 v42, v29
	v_not_b32_e32 v21, v26
	v_not_b32_e32 v24, v25
	v_fma_f32 v43, -v29, v42, 1.0
	v_fmac_f32_e32 v42, v43, v42
	v_div_scale_f32 v43, vcc, 1.0, v0, 1.0
	v_mul_f32_e32 v44, v43, v42
	v_fma_f32 v45, -v29, v44, v43
	v_fmac_f32_e32 v44, v45, v42
	v_fma_f32 v29, -v29, v44, v43
	v_div_fmas_f32 v29, v29, v42, v44
	v_div_fixup_f32 v29, v29, v0, 1.0
	v_and_b32_e32 v0, 48, v19
	v_lshrrev_b32_e32 v19, 2, v21
	v_and_b32_e32 v19, 60, v19
	v_bitop3_b32 v21, v26, 15, v26 bitop3:0xc
	v_add_u32_e32 v19, v5, v19
	v_lshl_add_u32 v21, v21, 2, v5
	ds_read_b32 v19, v19
	ds_read_b32 v21, v21 offset:64
	v_lshlrev_b32_e32 v0, 3, v0
	v_add3_u32 v11, v13, v11, v0
	v_mul_f32_e32 v1, v1, v29
	v_not_b32_e32 v13, v2
	s_waitcnt lgkmcnt(0)
	v_lshl_add_u32 v0, v19, 7, v21
	ds_write_b64 v11, v[0:1]
	v_lshrrev_b32_e32 v0, 2, v24
	v_and_b32_e32 v0, 60, v0
	v_bitop3_b32 v1, v25, 15, v25 bitop3:0xc
	v_add_u32_e32 v0, v5, v0
	v_lshl_add_u32 v1, v1, 2, v5
	ds_read_b32 v0, v0
	ds_read_b32 v1, v1 offset:64
	v_cmp_eq_u32_e32 vcc, 0, v9
	s_waitcnt lgkmcnt(0)
	v_lshl_add_u32 v0, v0, 7, v1
	v_mul_f32_e32 v1, v16, v29
	ds_write_b64 v11, v[0:1] offset:8
	v_lshrrev_b32_e32 v0, 2, v13
	v_and_b32_e32 v0, 60, v0
	v_bitop3_b32 v1, v2, 15, v2 bitop3:0xc
	v_add_u32_e32 v0, v5, v0
	v_lshl_add_u32 v1, v1, 2, v5
	ds_read_b32 v0, v0
	ds_read_b32 v1, v1 offset:64
	v_not_b32_e32 v2, v4
	s_waitcnt lgkmcnt(0)
	v_lshl_add_u32 v0, v0, 7, v1
	v_mul_f32_e32 v1, v27, v29
	ds_write_b64 v11, v[0:1] offset:16
	v_lshrrev_b32_e32 v0, 2, v2
	v_and_b32_e32 v0, 60, v0
	v_bitop3_b32 v1, v4, 15, v4 bitop3:0xc
	v_add_u32_e32 v0, v5, v0
	v_lshl_add_u32 v1, v1, 2, v5
	ds_read_b32 v0, v0
	ds_read_b32 v1, v1 offset:64
	v_not_b32_e32 v2, v3
	v_mul_lo_u32 v4, v7, s36
	s_waitcnt lgkmcnt(0)
	v_lshl_add_u32 v0, v0, 7, v1
	v_mul_f32_e32 v1, v28, v29
	ds_write_b64 v11, v[0:1] offset:24
	v_lshrrev_b32_e32 v0, 2, v2
	v_and_b32_e32 v0, 60, v0
	v_bitop3_b32 v1, v3, 15, v3 bitop3:0xc
	v_add_u32_e32 v0, v5, v0
	v_lshl_add_u32 v1, v1, 2, v5
	ds_read_b32 v0, v0
	ds_read_b32 v1, v1 offset:64
	v_not_b32_e32 v2, v22
	s_waitcnt lgkmcnt(0)
	v_lshl_add_u32 v0, v0, 7, v1
	v_mul_f32_e32 v1, v30, v29
	ds_write_b64 v11, v[0:1] offset:32
	v_lshrrev_b32_e32 v0, 2, v2
	v_and_b32_e32 v0, 60, v0
	v_bitop3_b32 v1, v22, 15, v22 bitop3:0xc
	v_add_u32_e32 v0, v5, v0
	v_lshl_add_u32 v1, v1, 2, v5
	ds_read_b32 v0, v0
	ds_read_b32 v1, v1 offset:64
	v_not_b32_e32 v2, v15
	s_waitcnt lgkmcnt(0)
	v_lshl_add_u32 v0, v0, 7, v1
	v_mul_f32_e32 v1, v31, v29
	ds_write_b64 v11, v[0:1] offset:40
	v_lshrrev_b32_e32 v0, 2, v2
	v_and_b32_e32 v0, 60, v0
	v_bitop3_b32 v1, v15, 15, v15 bitop3:0xc
	v_add_u32_e32 v0, v5, v0
	v_lshl_add_u32 v1, v1, 2, v5
	ds_read_b32 v0, v0
	ds_read_b32 v1, v1 offset:64
	v_not_b32_e32 v2, v23
	s_waitcnt lgkmcnt(0)
	v_lshl_add_u32 v0, v0, 7, v1
	v_mul_f32_e32 v1, v32, v29
	ds_write_b64 v11, v[0:1] offset:48
	v_lshrrev_b32_e32 v0, 2, v2
	v_and_b32_e32 v0, 60, v0
	v_bitop3_b32 v1, v23, 15, v23 bitop3:0xc
	v_add_u32_e32 v0, v5, v0
	v_lshl_add_u32 v1, v1, 2, v5
	ds_read_b32 v0, v0
	ds_read_b32 v1, v1 offset:64
	v_not_b32_e32 v2, v12
	s_waitcnt lgkmcnt(0)
	v_lshl_add_u32 v0, v0, 7, v1
	v_mul_f32_e32 v1, v33, v29
	ds_write_b64 v11, v[0:1] offset:56
	v_lshrrev_b32_e32 v0, 2, v2
	v_and_b32_e32 v0, 60, v0
	v_bitop3_b32 v1, v12, 15, v12 bitop3:0xc
	v_add_u32_e32 v0, v5, v0
	v_lshl_add_u32 v1, v1, 2, v5
	ds_read_b32 v0, v0
	ds_read_b32 v1, v1 offset:64
	v_not_b32_e32 v2, v17
	s_waitcnt lgkmcnt(0)
	v_lshl_add_u32 v0, v0, 7, v1
	v_mul_f32_e32 v1, v34, v29
	ds_write_b64 v11, v[0:1] offset:64
	v_lshrrev_b32_e32 v0, 2, v2
	v_and_b32_e32 v0, 60, v0
	v_bitop3_b32 v1, v17, 15, v17 bitop3:0xc
	v_add_u32_e32 v0, v5, v0
	v_lshl_add_u32 v1, v1, 2, v5
	ds_read_b32 v0, v0
	ds_read_b32 v1, v1 offset:64
	v_not_b32_e32 v2, v14
	s_waitcnt lgkmcnt(0)
	v_lshl_add_u32 v0, v0, 7, v1
	v_mul_f32_e32 v1, v35, v29
	ds_write_b64 v11, v[0:1] offset:72
	v_lshrrev_b32_e32 v0, 2, v2
	v_and_b32_e32 v0, 60, v0
	v_bitop3_b32 v1, v14, 15, v14 bitop3:0xc
	v_add_u32_e32 v0, v5, v0
	v_lshl_add_u32 v1, v1, 2, v5
	ds_read_b32 v0, v0
	ds_read_b32 v1, v1 offset:64
	v_not_b32_e32 v2, v20
	s_waitcnt lgkmcnt(0)
; __device__ __forceinline__ unsigned pk2(float lo, float hi) { const f32x2 v = {lo, hi}; const bf16x2_t b = __builtin_convertvector(v, bf16x2_t); return __builtin_bit_cast(unsigned, b); }
; __device__ __forceinline__ float bflo(unsigned u) { return __uint_as_float(u << 16); }
; __device__ __forceinline__ float bfhi(unsigned u) { return __uint_as_float(u & 0xffff0000u); }
; __device__ __forceinline__ void peer_tile(const Args& A, LAS unsigned char* lds, int tile) {
;     ...
;             for (int k = 0; k < 16; ++k) { const unsigned code = 255u - (Lf[k] & 255u); const unsigned e = idx[code >> 4] * 128u + idx[16 + (code & 15u)];
;                 u32x2 sv; sv.x = e; sv.y = __float_as_uint(fv[k] * rden); SEL[(tl * 8 + h) * 16 + k] = sv; }
;         }
;     }
;     __syncthreads();
;     ...
;     for (int pass = 0; pass < 2; ++pass) {
;         const int tb = 8 * w + 4 * pass;
;         u32x4 xpa[4], xpb[4]; f32x2 oacc[4][8];
; #pragma unroll
;         for (int tk = 0; tk < 4; ++tk) { const size_t m = (size_t)tile * 64 + tb + tk;
;             { const u32x4 ra = *(const u32x4*)(A3 + m * 1024 + 16 * lane), rb = *(const u32x4*)(A3 + m * 1024 + 16 * lane + 8);
;               float xr_; { const f32x4 p0 = *(const f32x4*)(RSq + m * 16), p1 = *(const f32x4*)(RSq + m * 16 + 4), p2 = *(const f32x4*)(RSq + m * 16 + 8), p3 = *(const f32x4*)(RSq + m * 16 + 12);
;                 const f32x4 ps = (p0 + p1) + (p2 + p3); xr_ = rsqrtf(((ps[0] + ps[1]) + (ps[2] + ps[3])) * (1.f / 1024.f) + 1e-6f); }
;               const unsigned rr[8] = {ra.x, ra.y, ra.z, ra.w, rb.x, rb.y, rb.z, rb.w}; unsigned hh[8];
;               const float* sp = MOD + (int)(m >> 11) * 6144 + 3072 + 16 * lane;
; #pragma unroll
;               for (int q = 0; q < 8; ++q) { const f32x2 sh = *(const f32x2*)(sp + 2 * q); hh[q] = pk2(bflo(rr[q]) * xr_ + sh[0], bfhi(rr[q]) * xr_ + sh[1]); }
;               xpa[tk] = (u32x4){hh[0], hh[1], hh[2], hh[3]}; xpb[tk] = (u32x4){hh[4], hh[5], hh[6], hh[7]}; }
	v_lshl_add_u32 v0, v0, 7, v1
	v_mul_f32_e32 v1, v36, v29
	ds_write_b64 v11, v[0:1] offset:80
	v_lshrrev_b32_e32 v0, 2, v2
	v_and_b32_e32 v0, 60, v0
	v_bitop3_b32 v1, v20, 15, v20 bitop3:0xc
	v_add_u32_e32 v0, v5, v0
	v_lshl_add_u32 v1, v1, 2, v5
	ds_read_b32 v0, v0
	ds_read_b32 v1, v1 offset:64
	v_not_b32_e32 v2, v6
	s_waitcnt lgkmcnt(0)
	v_lshl_add_u32 v0, v0, 7, v1
	v_mul_f32_e32 v1, v37, v29
	ds_write_b64 v11, v[0:1] offset:88
	v_lshrrev_b32_e32 v0, 2, v2
	v_and_b32_e32 v0, 60, v0
	v_bitop3_b32 v1, v6, 15, v6 bitop3:0xc
	v_add_u32_e32 v0, v5, v0
	v_lshl_add_u32 v1, v1, 2, v5
	ds_read_b32 v0, v0
	ds_read_b32 v1, v1 offset:64
	v_not_b32_e32 v2, v18
	s_waitcnt lgkmcnt(0)
	v_lshl_add_u32 v0, v0, 7, v1
	v_mul_f32_e32 v1, v38, v29
	ds_write_b64 v11, v[0:1] offset:96
	v_lshrrev_b32_e32 v0, 2, v2
	v_and_b32_e32 v0, 60, v0
	v_bitop3_b32 v1, v18, 15, v18 bitop3:0xc
	v_add_u32_e32 v0, v5, v0
	v_lshl_add_u32 v1, v1, 2, v5
	ds_read_b32 v0, v0
	ds_read_b32 v1, v1 offset:64
	v_not_b32_e32 v2, v8
	s_waitcnt lgkmcnt(0)
	v_lshl_add_u32 v0, v0, 7, v1
	v_mul_f32_e32 v1, v39, v29
	ds_write_b64 v11, v[0:1] offset:104
	v_lshrrev_b32_e32 v0, 2, v2
	v_and_b32_e32 v0, 60, v0
	v_bitop3_b32 v1, v8, 15, v8 bitop3:0xc
	v_add_u32_e32 v0, v5, v0
	v_lshl_add_u32 v1, v1, 2, v5
	ds_read_b32 v0, v0
	ds_read_b32 v1, v1 offset:64
	v_not_b32_e32 v2, v10
	s_waitcnt lgkmcnt(0)
	v_lshl_add_u32 v0, v0, 7, v1
	v_mul_f32_e32 v1, v40, v29
	ds_write_b64 v11, v[0:1] offset:112
	v_lshrrev_b32_e32 v0, 2, v2
	v_and_b32_e32 v0, 60, v0
	v_bitop3_b32 v1, v10, 15, v10 bitop3:0xc
	v_add_u32_e32 v0, v5, v0
	v_lshl_add_u32 v1, v1, 2, v5
	ds_read_b32 v0, v0
	ds_read_b32 v1, v1 offset:64
	v_lshlrev_b32_e32 v5, 13, v7
	v_lshl_or_b32 v6, v9, 3, v5
	s_waitcnt lgkmcnt(0)
	v_lshl_add_u32 v0, v0, 7, v1
	v_mul_f32_e32 v1, v41, v29
	ds_write_b64 v11, v[0:1] offset:120
	s_waitcnt lgkmcnt(0)
	s_barrier
	s_mov_b64 exec, -1
	v_and_b32_e32 v240, 63, v214
	v_lshrrev_b32_e32 v242, 6, v214
	v_lshlrev_b32_e32 v240, 4, v240
	v_readfirstlane_b32 s16, v242
	v_lshlrev_b32_e32 v245, 1, v240
	v_lshlrev_b32_e32 v246, 2, v240
	v_lshrrev_b32_e32 v247, 4, v240
	v_and_b32_e32 v247, 48, v247
	v_mov_b32_e32 v244, 0
	v_mov_b32_e32 v243, 0x358637bd
	v_mov_b32_e32 v242, 0xbf3a00e3
	s_add_u32 s4, s50, 0x1000000
	s_addc_u32 s5, s51, 0
	s_add_u32 s6, s50, 0x2000000
	s_addc_u32 s7, s51, 0
	s_add_u32 s8, s50, 0x3000000
	s_addc_u32 s9, s51, 0
	s_add_u32 s52, s50, 0x3010000
	s_addc_u32 s53, s51, 0
	s_add_u32 s12, s50, 0xb000000
	s_addc_u32 s13, s51, 0
	s_add_u32 s14, s50, 0xd000000
	s_addc_u32 s15, s51, 0
	s_lshr_b32 s0, s2, 5
	s_mul_i32 s0, s0, 0x6000
	s_add_u32 s10, s50, s0
	s_addc_u32 s11, s51, 0
	s_add_u32 s80, s10, 0x4000
	s_addc_u32 s81, s11, 0
	s_add_u32 s82, s10, 0x6000
	s_addc_u32 s83, s11, 0
	s_mul_i32 s22, s16, 9920
	s_cmp_eq_u32 s16, 7
	s_cselect_b32 s22, 0x21000, s22
	s_mov_b32 s85, 0xffffffff
	s_mov_b32 s72, 0x3e6d3388
	s_mov_b32 s56, s4
	s_and_b32 s57, s5, 0xffff
	s_or_b32 s57, s57, 0x04000000
	s_mov_b32 s58, 16384
	s_mov_b32 s59, 0x00027000
	s_mov_b32 s60, s6
	s_and_b32 s61, s7, 0xffff
	s_or_b32 s61, s61, 0x04000000
	s_mov_b32 s62, 16384
	s_mov_b32 s63, 0x00027000
	s_lshl_b32 s76, s16, 3
	s_lshl_b32 s0, s2, 6
	s_add_i32 s77, s0, s76
	global_load_dwordx4 v[192:195], v246, s[80:81] offset:0
	global_load_dwordx4 v[196:199], v246, s[80:81] offset:16
	global_load_dwordx4 v[200:203], v246, s[80:81] offset:32
	global_load_dwordx4 v[204:207], v246, s[80:81] offset:48
	s_add_i32 s0, s77, 0
	s_lshl_b32 s1, s0, 11
	s_add_u32 s78, s12, s1
	s_addc_u32 s79, s13, 0
	global_load_dwordx4 v[128:131], v245, s[78:79]
	global_load_dwordx4 v[132:135], v245, s[78:79] offset:16
	global_load_dwordx4 v[136:139], v245, s[78:79] offset:2048
	global_load_dwordx4 v[140:143], v245, s[78:79] offset:2064
	s_lshl_b32 s1, s0, 6
	s_add_u32 s78, s14, s1
	s_addc_u32 s79, s15, 0
	global_load_dwordx4 v[144:147], v244, s[78:79] offset:0
	global_load_dwordx4 v[148:151], v244, s[78:79] offset:16
	global_load_dwordx4 v[152:155], v244, s[78:79] offset:32
	global_load_dwordx4 v[156:159], v244, s[78:79] offset:48
	global_load_dwordx4 v[160:163], v244, s[78:79] offset:64
	global_load_dwordx4 v[164:167], v244, s[78:79] offset:80
	global_load_dwordx4 v[168:171], v244, s[78:79] offset:96
	global_load_dwordx4 v[172:175], v244, s[78:79] offset:112
	s_add_i32 s0, s77, 2
	s_lshl_b32 s1, s0, 11
	s_add_u32 s78, s12, s1
	s_addc_u32 s79, s13, 0
	global_load_dwordx4 v[176:179], v245, s[78:79]
	global_load_dwordx4 v[180:183], v245, s[78:79] offset:16
	global_load_dwordx4 v[184:187], v245, s[78:79] offset:2048
	global_load_dwordx4 v[188:191], v245, s[78:79] offset:2064
	s_lshl_b32 s1, s0, 6
	s_add_u32 s78, s14, s1
	s_addc_u32 s79, s15, 0
	global_load_dwordx4 v[216:219], v244, s[78:79] offset:0
	global_load_dwordx4 v[220:223], v244, s[78:79] offset:16
	global_load_dwordx4 v[224:227], v244, s[78:79] offset:32
	global_load_dwordx4 v[228:231], v244, s[78:79] offset:48
	global_load_dwordx4 v[232:235], v244, s[78:79] offset:64
	global_load_dwordx4 v[236:239], v244, s[78:79] offset:80
	global_load_dwordx4 v[248:251], v244, s[78:79] offset:96
	global_load_dwordx4 v[252:255], v244, s[78:79] offset:112
	s_waitcnt vmcnt(12)
; __device__ __forceinline__ unsigned pk2(float lo, float hi) { const f32x2 v = {lo, hi}; const bf16x2_t b = __builtin_convertvector(v, bf16x2_t); return __builtin_bit_cast(unsigned, b); }
; __device__ __forceinline__ float bflo(unsigned u) { return __uint_as_float(u << 16); }
; __device__ __forceinline__ float bfhi(unsigned u) { return __uint_as_float(u & 0xffff0000u); }
; __device__ __forceinline__ void peer_tile(const Args& A, LAS unsigned char* lds, int tile) {
;     ...
;         for (int tk = 0; tk < 4; ++tk) { const size_t m = (size_t)tile * 64 + tb + tk;
;             { const u32x4 ra = *(const u32x4*)(A3 + m * 1024 + 16 * lane), rb = *(const u32x4*)(A3 + m * 1024 + 16 * lane + 8);
;               float xr_; { const f32x4 p0 = *(const f32x4*)(RSq + m * 16), p1 = *(const f32x4*)(RSq + m * 16 + 4), p2 = *(const f32x4*)(RSq + m * 16 + 8), p3 = *(const f32x4*)(RSq + m * 16 + 12);
;                 const f32x4 ps = (p0 + p1) + (p2 + p3); xr_ = rsqrtf(((ps[0] + ps[1]) + (ps[2] + ps[3])) * (1.f / 1024.f) + 1e-6f); }
;               const unsigned rr[8] = {ra.x, ra.y, ra.z, ra.w, rb.x, rb.y, rb.z, rb.w}; unsigned hh[8];
;               const float* sp = MOD + (int)(m >> 11) * 6144 + 3072 + 16 * lane;
; #pragma unroll
;               for (int q = 0; q < 8; ++q) { const f32x2 sh = *(const f32x2*)(sp + 2 * q); hh[q] = pk2(bflo(rr[q]) * xr_ + sh[0], bfhi(rr[q]) * xr_ + sh[1]); }
;               xpa[tk] = (u32x4){hh[0], hh[1], hh[2], hh[3]}; xpb[tk] = (u32x4){hh[4], hh[5], hh[6], hh[7]}; }
; #pragma unroll
;             for (int q = 0; q < 8; ++q) oacc[tk][q] = (f32x2){0.f, 0.f}; }
	v_pk_add_f32 v[144:145], v[144:145], v[148:149]
	v_pk_add_f32 v[146:147], v[146:147], v[150:151]
	v_pk_add_f32 v[152:153], v[152:153], v[156:157]
	v_pk_add_f32 v[154:155], v[154:155], v[158:159]
	v_pk_add_f32 v[144:145], v[144:145], v[152:153]
	v_pk_add_f32 v[146:147], v[146:147], v[154:155]
	v_add_f32_e32 v144, v144, v145
	v_add_f32_e32 v146, v146, v147
	v_add_f32_e32 v144, v144, v146
	v_fmamk_f32 v144, v144, 0x3a800000, v243
	v_rsq_f32_e32 v144, v144
	v_pk_add_f32 v[160:161], v[160:161], v[164:165]
	v_pk_add_f32 v[162:163], v[162:163], v[166:167]
	v_pk_add_f32 v[168:169], v[168:169], v[172:173]
	v_pk_add_f32 v[170:171], v[170:171], v[174:175]
	v_pk_add_f32 v[160:161], v[160:161], v[168:169]
	v_pk_add_f32 v[162:163], v[162:163], v[170:171]
	v_add_f32_e32 v160, v160, v161
	v_add_f32_e32 v162, v162, v163
	v_add_f32_e32 v160, v160, v162
	v_fmamk_f32 v160, v160, 0x3a800000, v243
	v_rsq_f32_e32 v160, v160
	v_lshlrev_b32_e32 v208, 16, v128
	v_and_b32_e32 v209, 0xffff0000, v128
	v_fma_f32 v208, v208, v144, v192
	v_fma_f32 v209, v209, v144, v193
	v_cvt_pk_bf16_f32 v210, v208, v209
	v_lshlrev_b32_e32 v0, 16, v210
	v_and_b32_e32 v1, 0xffff0000, v210
	v_lshlrev_b32_e32 v208, 16, v129
	v_and_b32_e32 v209, 0xffff0000, v129
	v_fma_f32 v208, v208, v144, v194
	v_fma_f32 v209, v209, v144, v195
	v_cvt_pk_bf16_f32 v210, v208, v209
	v_lshlrev_b32_e32 v2, 16, v210
	v_and_b32_e32 v3, 0xffff0000, v210
	v_lshlrev_b32_e32 v208, 16, v130
	v_and_b32_e32 v209, 0xffff0000, v130
	v_fma_f32 v208, v208, v144, v196
	v_fma_f32 v209, v209, v144, v197
	v_cvt_pk_bf16_f32 v210, v208, v209
	v_lshlrev_b32_e32 v4, 16, v210
	v_and_b32_e32 v5, 0xffff0000, v210
	v_lshlrev_b32_e32 v208, 16, v131
	v_and_b32_e32 v209, 0xffff0000, v131
	v_fma_f32 v208, v208, v144, v198
	v_fma_f32 v209, v209, v144, v199
	v_cvt_pk_bf16_f32 v210, v208, v209
	v_lshlrev_b32_e32 v6, 16, v210
	v_and_b32_e32 v7, 0xffff0000, v210
	v_lshlrev_b32_e32 v208, 16, v132
	v_and_b32_e32 v209, 0xffff0000, v132
	v_fma_f32 v208, v208, v144, v200
	v_fma_f32 v209, v209, v144, v201
	v_cvt_pk_bf16_f32 v210, v208, v209
	v_lshlrev_b32_e32 v8, 16, v210
	v_and_b32_e32 v9, 0xffff0000, v210
	v_lshlrev_b32_e32 v208, 16, v133
	v_and_b32_e32 v209, 0xffff0000, v133
	v_fma_f32 v208, v208, v144, v202
	v_fma_f32 v209, v209, v144, v203
	v_cvt_pk_bf16_f32 v210, v208, v209
	v_lshlrev_b32_e32 v10, 16, v210
	v_and_b32_e32 v11, 0xffff0000, v210
	v_lshlrev_b32_e32 v208, 16, v134
	v_and_b32_e32 v209, 0xffff0000, v134
	v_fma_f32 v208, v208, v144, v204
	v_fma_f32 v209, v209, v144, v205
	v_cvt_pk_bf16_f32 v210, v208, v209
	v_lshlrev_b32_e32 v12, 16, v210
	v_and_b32_e32 v13, 0xffff0000, v210
	v_lshlrev_b32_e32 v208, 16, v135
	v_and_b32_e32 v209, 0xffff0000, v135
	v_fma_f32 v208, v208, v144, v206
	v_fma_f32 v209, v209, v144, v207
	v_cvt_pk_bf16_f32 v210, v208, v209
	v_lshlrev_b32_e32 v14, 16, v210
	v_and_b32_e32 v15, 0xffff0000, v210
	v_lshlrev_b32_e32 v208, 16, v136
	v_and_b32_e32 v209, 0xffff0000, v136
	v_fma_f32 v208, v208, v160, v192
	v_fma_f32 v209, v209, v160, v193
	v_cvt_pk_bf16_f32 v210, v208, v209
	v_lshlrev_b32_e32 v16, 16, v210
	v_and_b32_e32 v17, 0xffff0000, v210
	v_lshlrev_b32_e32 v208, 16, v137
	v_and_b32_e32 v209, 0xffff0000, v137
	v_fma_f32 v208, v208, v160, v194
	v_fma_f32 v209, v209, v160, v195
	v_cvt_pk_bf16_f32 v210, v208, v209
	v_lshlrev_b32_e32 v18, 16, v210
	v_and_b32_e32 v19, 0xffff0000, v210
	v_lshlrev_b32_e32 v208, 16, v138
	v_and_b32_e32 v209, 0xffff0000, v138
	v_fma_f32 v208, v208, v160, v196
	v_fma_f32 v209, v209, v160, v197
	v_cvt_pk_bf16_f32 v210, v208, v209
	v_lshlrev_b32_e32 v20, 16, v210
	v_and_b32_e32 v21, 0xffff0000, v210
	v_lshlrev_b32_e32 v208, 16, v139
	v_and_b32_e32 v209, 0xffff0000, v139
	v_fma_f32 v208, v208, v160, v198
	v_fma_f32 v209, v209, v160, v199
	v_cvt_pk_bf16_f32 v210, v208, v209
	v_lshlrev_b32_e32 v22, 16, v210
	v_and_b32_e32 v23, 0xffff0000, v210
	v_lshlrev_b32_e32 v208, 16, v140
	v_and_b32_e32 v209, 0xffff0000, v140
	v_fma_f32 v208, v208, v160, v200
	v_fma_f32 v209, v209, v160, v201
	v_cvt_pk_bf16_f32 v210, v208, v209
	v_lshlrev_b32_e32 v24, 16, v210
	v_and_b32_e32 v25, 0xffff0000, v210
	v_lshlrev_b32_e32 v208, 16, v141
	v_and_b32_e32 v209, 0xffff0000, v141
	v_fma_f32 v208, v208, v160, v202
	v_fma_f32 v209, v209, v160, v203
	v_cvt_pk_bf16_f32 v210, v208, v209
	v_lshlrev_b32_e32 v26, 16, v210
	v_and_b32_e32 v27, 0xffff0000, v210
	v_lshlrev_b32_e32 v208, 16, v142
	v_and_b32_e32 v209, 0xffff0000, v142
	v_fma_f32 v208, v208, v160, v204
	v_fma_f32 v209, v209, v160, v205
	v_cvt_pk_bf16_f32 v210, v208, v209
	v_lshlrev_b32_e32 v28, 16, v210
	v_and_b32_e32 v29, 0xffff0000, v210
	v_lshlrev_b32_e32 v208, 16, v143
	v_and_b32_e32 v209, 0xffff0000, v143
	v_fma_f32 v208, v208, v160, v206
	v_fma_f32 v209, v209, v160, v207
	v_cvt_pk_bf16_f32 v210, v208, v209
	v_lshlrev_b32_e32 v30, 16, v210
	v_and_b32_e32 v31, 0xffff0000, v210
	s_nop 0
	s_add_i32 s0, s77, 4
	s_lshl_b32 s1, s0, 11
	s_add_u32 s78, s12, s1
	s_addc_u32 s79, s13, 0
	global_load_dwordx4 v[128:131], v245, s[78:79]
	global_load_dwordx4 v[132:135], v245, s[78:79] offset:16
	global_load_dwordx4 v[136:139], v245, s[78:79] offset:2048
	global_load_dwordx4 v[140:143], v245, s[78:79] offset:2064
	s_lshl_b32 s1, s0, 6
	s_add_u32 s78, s14, s1
	s_addc_u32 s79, s15, 0
	global_load_dwordx4 v[144:147], v244, s[78:79] offset:0
	global_load_dwordx4 v[148:151], v244, s[78:79] offset:16
	global_load_dwordx4 v[152:155], v244, s[78:79] offset:32
	global_load_dwordx4 v[156:159], v244, s[78:79] offset:48
	global_load_dwordx4 v[160:163], v244, s[78:79] offset:64
	global_load_dwordx4 v[164:167], v244, s[78:79] offset:80
	global_load_dwordx4 v[168:171], v244, s[78:79] offset:96
	global_load_dwordx4 v[172:175], v244, s[78:79] offset:112
	s_waitcnt vmcnt(12)
; __device__ __forceinline__ unsigned pk2(float lo, float hi) { const f32x2 v = {lo, hi}; const bf16x2_t b = __builtin_convertvector(v, bf16x2_t); return __builtin_bit_cast(unsigned, b); }
; __device__ __forceinline__ float bflo(unsigned u) { return __uint_as_float(u << 16); }
; __device__ __forceinline__ float bfhi(unsigned u) { return __uint_as_float(u & 0xffff0000u); }
; __device__ __forceinline__ void peer_tile(const Args& A, LAS unsigned char* lds, int tile) {
;     ...
;         for (int tk = 0; tk < 4; ++tk) { const size_t m = (size_t)tile * 64 + tb + tk;
;             { const u32x4 ra = *(const u32x4*)(A3 + m * 1024 + 16 * lane), rb = *(const u32x4*)(A3 + m * 1024 + 16 * lane + 8);
;               float xr_; { const f32x4 p0 = *(const f32x4*)(RSq + m * 16), p1 = *(const f32x4*)(RSq + m * 16 + 4), p2 = *(const f32x4*)(RSq + m * 16 + 8), p3 = *(const f32x4*)(RSq + m * 16 + 12);
;                 const f32x4 ps = (p0 + p1) + (p2 + p3); xr_ = rsqrtf(((ps[0] + ps[1]) + (ps[2] + ps[3])) * (1.f / 1024.f) + 1e-6f); }
;               const unsigned rr[8] = {ra.x, ra.y, ra.z, ra.w, rb.x, rb.y, rb.z, rb.w}; unsigned hh[8];
;               const float* sp = MOD + (int)(m >> 11) * 6144 + 3072 + 16 * lane;
; #pragma unroll
;               for (int q = 0; q < 8; ++q) { const f32x2 sh = *(const f32x2*)(sp + 2 * q); hh[q] = pk2(bflo(rr[q]) * xr_ + sh[0], bfhi(rr[q]) * xr_ + sh[1]); }
;               xpa[tk] = (u32x4){hh[0], hh[1], hh[2], hh[3]}; xpb[tk] = (u32x4){hh[4], hh[5], hh[6], hh[7]}; }
; #pragma unroll
;             for (int q = 0; q < 8; ++q) oacc[tk][q] = (f32x2){0.f, 0.f}; }
	v_pk_add_f32 v[216:217], v[216:217], v[220:221]
	v_pk_add_f32 v[218:219], v[218:219], v[222:223]
	v_pk_add_f32 v[224:225], v[224:225], v[228:229]
	v_pk_add_f32 v[226:227], v[226:227], v[230:231]
	v_pk_add_f32 v[216:217], v[216:217], v[224:225]
	v_pk_add_f32 v[218:219], v[218:219], v[226:227]
	v_add_f32_e32 v216, v216, v217
	v_add_f32_e32 v218, v218, v219
	v_add_f32_e32 v216, v216, v218
	v_fmamk_f32 v216, v216, 0x3a800000, v243
	v_rsq_f32_e32 v216, v216
	v_pk_add_f32 v[232:233], v[232:233], v[236:237]
	v_pk_add_f32 v[234:235], v[234:235], v[238:239]
	v_pk_add_f32 v[248:249], v[248:249], v[252:253]
	v_pk_add_f32 v[250:251], v[250:251], v[254:255]
	v_pk_add_f32 v[232:233], v[232:233], v[248:249]
	v_pk_add_f32 v[234:235], v[234:235], v[250:251]
	v_add_f32_e32 v232, v232, v233
	v_add_f32_e32 v234, v234, v235
	v_add_f32_e32 v232, v232, v234
	v_fmamk_f32 v232, v232, 0x3a800000, v243
	v_rsq_f32_e32 v232, v232
	v_lshlrev_b32_e32 v208, 16, v176
	v_and_b32_e32 v209, 0xffff0000, v176
	v_fma_f32 v208, v208, v216, v192
	v_fma_f32 v209, v209, v216, v193
	v_cvt_pk_bf16_f32 v210, v208, v209
	v_lshlrev_b32_e32 v32, 16, v210
	v_and_b32_e32 v33, 0xffff0000, v210
	v_lshlrev_b32_e32 v208, 16, v177
	v_and_b32_e32 v209, 0xffff0000, v177
	v_fma_f32 v208, v208, v216, v194
	v_fma_f32 v209, v209, v216, v195
	v_cvt_pk_bf16_f32 v210, v208, v209
	v_lshlrev_b32_e32 v34, 16, v210
	v_and_b32_e32 v35, 0xffff0000, v210
	v_lshlrev_b32_e32 v208, 16, v178
	v_and_b32_e32 v209, 0xffff0000, v178
	v_fma_f32 v208, v208, v216, v196
	v_fma_f32 v209, v209, v216, v197
	v_cvt_pk_bf16_f32 v210, v208, v209
	v_lshlrev_b32_e32 v36, 16, v210
	v_and_b32_e32 v37, 0xffff0000, v210
	v_lshlrev_b32_e32 v208, 16, v179
	v_and_b32_e32 v209, 0xffff0000, v179
	v_fma_f32 v208, v208, v216, v198
	v_fma_f32 v209, v209, v216, v199
	v_cvt_pk_bf16_f32 v210, v208, v209
	v_lshlrev_b32_e32 v38, 16, v210
	v_and_b32_e32 v39, 0xffff0000, v210
	v_lshlrev_b32_e32 v208, 16, v180
	v_and_b32_e32 v209, 0xffff0000, v180
	v_fma_f32 v208, v208, v216, v200
	v_fma_f32 v209, v209, v216, v201
	v_cvt_pk_bf16_f32 v210, v208, v209
	v_lshlrev_b32_e32 v40, 16, v210
	v_and_b32_e32 v41, 0xffff0000, v210
	v_lshlrev_b32_e32 v208, 16, v181
	v_and_b32_e32 v209, 0xffff0000, v181
	v_fma_f32 v208, v208, v216, v202
	v_fma_f32 v209, v209, v216, v203
	v_cvt_pk_bf16_f32 v210, v208, v209
	v_lshlrev_b32_e32 v42, 16, v210
	v_and_b32_e32 v43, 0xffff0000, v210
	v_lshlrev_b32_e32 v208, 16, v182
	v_and_b32_e32 v209, 0xffff0000, v182
	v_fma_f32 v208, v208, v216, v204
	v_fma_f32 v209, v209, v216, v205
	v_cvt_pk_bf16_f32 v210, v208, v209
	v_lshlrev_b32_e32 v44, 16, v210
	v_and_b32_e32 v45, 0xffff0000, v210
	v_lshlrev_b32_e32 v208, 16, v183
	v_and_b32_e32 v209, 0xffff0000, v183
	v_fma_f32 v208, v208, v216, v206
	v_fma_f32 v209, v209, v216, v207
	v_cvt_pk_bf16_f32 v210, v208, v209
	v_lshlrev_b32_e32 v46, 16, v210
	v_and_b32_e32 v47, 0xffff0000, v210
	v_lshlrev_b32_e32 v208, 16, v184
	v_and_b32_e32 v209, 0xffff0000, v184
	v_fma_f32 v208, v208, v232, v192
	v_fma_f32 v209, v209, v232, v193
	v_cvt_pk_bf16_f32 v210, v208, v209
	v_lshlrev_b32_e32 v48, 16, v210
	v_and_b32_e32 v49, 0xffff0000, v210
	v_lshlrev_b32_e32 v208, 16, v185
	v_and_b32_e32 v209, 0xffff0000, v185
	v_fma_f32 v208, v208, v232, v194
	v_fma_f32 v209, v209, v232, v195
	v_cvt_pk_bf16_f32 v210, v208, v209
	v_lshlrev_b32_e32 v50, 16, v210
	v_and_b32_e32 v51, 0xffff0000, v210
	v_lshlrev_b32_e32 v208, 16, v186
	v_and_b32_e32 v209, 0xffff0000, v186
	v_fma_f32 v208, v208, v232, v196
	v_fma_f32 v209, v209, v232, v197
	v_cvt_pk_bf16_f32 v210, v208, v209
	v_lshlrev_b32_e32 v52, 16, v210
	v_and_b32_e32 v53, 0xffff0000, v210
	v_lshlrev_b32_e32 v208, 16, v187
	v_and_b32_e32 v209, 0xffff0000, v187
	v_fma_f32 v208, v208, v232, v198
	v_fma_f32 v209, v209, v232, v199
	v_cvt_pk_bf16_f32 v210, v208, v209
	v_lshlrev_b32_e32 v54, 16, v210
	v_and_b32_e32 v55, 0xffff0000, v210
	v_lshlrev_b32_e32 v208, 16, v188
	v_and_b32_e32 v209, 0xffff0000, v188
	v_fma_f32 v208, v208, v232, v200
	v_fma_f32 v209, v209, v232, v201
	v_cvt_pk_bf16_f32 v210, v208, v209
	v_lshlrev_b32_e32 v56, 16, v210
	v_and_b32_e32 v57, 0xffff0000, v210
	v_lshlrev_b32_e32 v208, 16, v189
	v_and_b32_e32 v209, 0xffff0000, v189
	v_fma_f32 v208, v208, v232, v202
	v_fma_f32 v209, v209, v232, v203
	v_cvt_pk_bf16_f32 v210, v208, v209
	v_lshlrev_b32_e32 v58, 16, v210
	v_and_b32_e32 v59, 0xffff0000, v210
	v_lshlrev_b32_e32 v208, 16, v190
	v_and_b32_e32 v209, 0xffff0000, v190
	v_fma_f32 v208, v208, v232, v204
	v_fma_f32 v209, v209, v232, v205
	v_cvt_pk_bf16_f32 v210, v208, v209
	v_lshlrev_b32_e32 v60, 16, v210
	v_and_b32_e32 v61, 0xffff0000, v210
	v_lshlrev_b32_e32 v208, 16, v191
	v_and_b32_e32 v209, 0xffff0000, v191
	v_fma_f32 v208, v208, v232, v206
	v_fma_f32 v209, v209, v232, v207
	v_cvt_pk_bf16_f32 v210, v208, v209
	v_lshlrev_b32_e32 v62, 16, v210
	v_and_b32_e32 v63, 0xffff0000, v210
	s_nop 0
	s_add_i32 s0, s77, 6
	s_lshl_b32 s1, s0, 11
	s_add_u32 s78, s12, s1
	s_addc_u32 s79, s13, 0
	global_load_dwordx4 v[176:179], v245, s[78:79]
	global_load_dwordx4 v[180:183], v245, s[78:79] offset:16
	global_load_dwordx4 v[184:187], v245, s[78:79] offset:2048
	global_load_dwordx4 v[188:191], v245, s[78:79] offset:2064
	s_lshl_b32 s1, s0, 6
	s_add_u32 s78, s14, s1
	s_addc_u32 s79, s15, 0
	global_load_dwordx4 v[216:219], v244, s[78:79] offset:0
	global_load_dwordx4 v[220:223], v244, s[78:79] offset:16
	global_load_dwordx4 v[224:227], v244, s[78:79] offset:32
	global_load_dwordx4 v[228:231], v244, s[78:79] offset:48
	global_load_dwordx4 v[232:235], v244, s[78:79] offset:64
	global_load_dwordx4 v[236:239], v244, s[78:79] offset:80
	global_load_dwordx4 v[248:251], v244, s[78:79] offset:96
	global_load_dwordx4 v[252:255], v244, s[78:79] offset:112
	s_waitcnt vmcnt(12)
; __device__ __forceinline__ unsigned pk2(float lo, float hi) { const f32x2 v = {lo, hi}; const bf16x2_t b = __builtin_convertvector(v, bf16x2_t); return __builtin_bit_cast(unsigned, b); }
; __device__ __forceinline__ float bflo(unsigned u) { return __uint_as_float(u << 16); }
; __device__ __forceinline__ float bfhi(unsigned u) { return __uint_as_float(u & 0xffff0000u); }
; __device__ __forceinline__ void peer_tile(const Args& A, LAS unsigned char* lds, int tile) {
;     ...
;         for (int tk = 0; tk < 4; ++tk) { const size_t m = (size_t)tile * 64 + tb + tk;
;             { const u32x4 ra = *(const u32x4*)(A3 + m * 1024 + 16 * lane), rb = *(const u32x4*)(A3 + m * 1024 + 16 * lane + 8);
;               float xr_; { const f32x4 p0 = *(const f32x4*)(RSq + m * 16), p1 = *(const f32x4*)(RSq + m * 16 + 4), p2 = *(const f32x4*)(RSq + m * 16 + 8), p3 = *(const f32x4*)(RSq + m * 16 + 12);
;                 const f32x4 ps = (p0 + p1) + (p2 + p3); xr_ = rsqrtf(((ps[0] + ps[1]) + (ps[2] + ps[3])) * (1.f / 1024.f) + 1e-6f); }
;               const unsigned rr[8] = {ra.x, ra.y, ra.z, ra.w, rb.x, rb.y, rb.z, rb.w}; unsigned hh[8];
;               const float* sp = MOD + (int)(m >> 11) * 6144 + 3072 + 16 * lane;
; #pragma unroll
;               for (int q = 0; q < 8; ++q) { const f32x2 sh = *(const f32x2*)(sp + 2 * q); hh[q] = pk2(bflo(rr[q]) * xr_ + sh[0], bfhi(rr[q]) * xr_ + sh[1]); }
;               xpa[tk] = (u32x4){hh[0], hh[1], hh[2], hh[3]}; xpb[tk] = (u32x4){hh[4], hh[5], hh[6], hh[7]}; }
; #pragma unroll
;             for (int q = 0; q < 8; ++q) oacc[tk][q] = (f32x2){0.f, 0.f}; }
	v_pk_add_f32 v[144:145], v[144:145], v[148:149]
	v_pk_add_f32 v[146:147], v[146:147], v[150:151]
	v_pk_add_f32 v[152:153], v[152:153], v[156:157]
	v_pk_add_f32 v[154:155], v[154:155], v[158:159]
	v_pk_add_f32 v[144:145], v[144:145], v[152:153]
	v_pk_add_f32 v[146:147], v[146:147], v[154:155]
	v_add_f32_e32 v144, v144, v145
	v_add_f32_e32 v146, v146, v147
	v_add_f32_e32 v144, v144, v146
	v_fmamk_f32 v144, v144, 0x3a800000, v243
	v_rsq_f32_e32 v144, v144
	v_pk_add_f32 v[160:161], v[160:161], v[164:165]
	v_pk_add_f32 v[162:163], v[162:163], v[166:167]
	v_pk_add_f32 v[168:169], v[168:169], v[172:173]
	v_pk_add_f32 v[170:171], v[170:171], v[174:175]
	v_pk_add_f32 v[160:161], v[160:161], v[168:169]
	v_pk_add_f32 v[162:163], v[162:163], v[170:171]
	v_add_f32_e32 v160, v160, v161
	v_add_f32_e32 v162, v162, v163
	v_add_f32_e32 v160, v160, v162
	v_fmamk_f32 v160, v160, 0x3a800000, v243
	v_rsq_f32_e32 v160, v160
	v_lshlrev_b32_e32 v208, 16, v128
	v_and_b32_e32 v209, 0xffff0000, v128
	v_fma_f32 v208, v208, v144, v192
	v_fma_f32 v209, v209, v144, v193
	v_cvt_pk_bf16_f32 v210, v208, v209
	v_lshlrev_b32_e32 v64, 16, v210
	v_and_b32_e32 v65, 0xffff0000, v210
	v_lshlrev_b32_e32 v208, 16, v129
	v_and_b32_e32 v209, 0xffff0000, v129
	v_fma_f32 v208, v208, v144, v194
	v_fma_f32 v209, v209, v144, v195
	v_cvt_pk_bf16_f32 v210, v208, v209
	v_lshlrev_b32_e32 v66, 16, v210
	v_and_b32_e32 v67, 0xffff0000, v210
	v_lshlrev_b32_e32 v208, 16, v130
	v_and_b32_e32 v209, 0xffff0000, v130
	v_fma_f32 v208, v208, v144, v196
	v_fma_f32 v209, v209, v144, v197
	v_cvt_pk_bf16_f32 v210, v208, v209
	v_lshlrev_b32_e32 v68, 16, v210
	v_and_b32_e32 v69, 0xffff0000, v210
	v_lshlrev_b32_e32 v208, 16, v131
	v_and_b32_e32 v209, 0xffff0000, v131
	v_fma_f32 v208, v208, v144, v198
	v_fma_f32 v209, v209, v144, v199
	v_cvt_pk_bf16_f32 v210, v208, v209
	v_lshlrev_b32_e32 v70, 16, v210
	v_and_b32_e32 v71, 0xffff0000, v210
	v_lshlrev_b32_e32 v208, 16, v132
	v_and_b32_e32 v209, 0xffff0000, v132
	v_fma_f32 v208, v208, v144, v200
	v_fma_f32 v209, v209, v144, v201
	v_cvt_pk_bf16_f32 v210, v208, v209
	v_lshlrev_b32_e32 v72, 16, v210
	v_and_b32_e32 v73, 0xffff0000, v210
	v_lshlrev_b32_e32 v208, 16, v133
	v_and_b32_e32 v209, 0xffff0000, v133
	v_fma_f32 v208, v208, v144, v202
	v_fma_f32 v209, v209, v144, v203
	v_cvt_pk_bf16_f32 v210, v208, v209
	v_lshlrev_b32_e32 v74, 16, v210
	v_and_b32_e32 v75, 0xffff0000, v210
	v_lshlrev_b32_e32 v208, 16, v134
	v_and_b32_e32 v209, 0xffff0000, v134
	v_fma_f32 v208, v208, v144, v204
	v_fma_f32 v209, v209, v144, v205
	v_cvt_pk_bf16_f32 v210, v208, v209
	v_lshlrev_b32_e32 v76, 16, v210
	v_and_b32_e32 v77, 0xffff0000, v210
	v_lshlrev_b32_e32 v208, 16, v135
	v_and_b32_e32 v209, 0xffff0000, v135
	v_fma_f32 v208, v208, v144, v206
	v_fma_f32 v209, v209, v144, v207
	v_cvt_pk_bf16_f32 v210, v208, v209
	v_lshlrev_b32_e32 v78, 16, v210
	v_and_b32_e32 v79, 0xffff0000, v210
	v_lshlrev_b32_e32 v208, 16, v136
	v_and_b32_e32 v209, 0xffff0000, v136
	v_fma_f32 v208, v208, v160, v192
	v_fma_f32 v209, v209, v160, v193
	v_cvt_pk_bf16_f32 v210, v208, v209
	v_lshlrev_b32_e32 v80, 16, v210
	v_and_b32_e32 v81, 0xffff0000, v210
	v_lshlrev_b32_e32 v208, 16, v137
	v_and_b32_e32 v209, 0xffff0000, v137
	v_fma_f32 v208, v208, v160, v194
	v_fma_f32 v209, v209, v160, v195
	v_cvt_pk_bf16_f32 v210, v208, v209
	v_lshlrev_b32_e32 v82, 16, v210
	v_and_b32_e32 v83, 0xffff0000, v210
	v_lshlrev_b32_e32 v208, 16, v138
	v_and_b32_e32 v209, 0xffff0000, v138
	v_fma_f32 v208, v208, v160, v196
	v_fma_f32 v209, v209, v160, v197
	v_cvt_pk_bf16_f32 v210, v208, v209
	v_lshlrev_b32_e32 v84, 16, v210
	v_and_b32_e32 v85, 0xffff0000, v210
	v_lshlrev_b32_e32 v208, 16, v139
	v_and_b32_e32 v209, 0xffff0000, v139
	v_fma_f32 v208, v208, v160, v198
	v_fma_f32 v209, v209, v160, v199
	v_cvt_pk_bf16_f32 v210, v208, v209
	v_lshlrev_b32_e32 v86, 16, v210
	v_and_b32_e32 v87, 0xffff0000, v210
	v_lshlrev_b32_e32 v208, 16, v140
	v_and_b32_e32 v209, 0xffff0000, v140
	v_fma_f32 v208, v208, v160, v200
	v_fma_f32 v209, v209, v160, v201
	v_cvt_pk_bf16_f32 v210, v208, v209
	v_lshlrev_b32_e32 v88, 16, v210
	v_and_b32_e32 v89, 0xffff0000, v210
	v_lshlrev_b32_e32 v208, 16, v141
	v_and_b32_e32 v209, 0xffff0000, v141
	v_fma_f32 v208, v208, v160, v202
	v_fma_f32 v209, v209, v160, v203
	v_cvt_pk_bf16_f32 v210, v208, v209
	v_lshlrev_b32_e32 v90, 16, v210
	v_and_b32_e32 v91, 0xffff0000, v210
	v_lshlrev_b32_e32 v208, 16, v142
	v_and_b32_e32 v209, 0xffff0000, v142
	v_fma_f32 v208, v208, v160, v204
	v_fma_f32 v209, v209, v160, v205
	v_cvt_pk_bf16_f32 v210, v208, v209
	v_lshlrev_b32_e32 v92, 16, v210
	v_and_b32_e32 v93, 0xffff0000, v210
	v_lshlrev_b32_e32 v208, 16, v143
	v_and_b32_e32 v209, 0xffff0000, v143
	v_fma_f32 v208, v208, v160, v206
	v_fma_f32 v209, v209, v160, v207
	v_cvt_pk_bf16_f32 v210, v208, v209
	v_lshlrev_b32_e32 v94, 16, v210
	v_and_b32_e32 v95, 0xffff0000, v210
	s_nop 0
	s_waitcnt vmcnt(0)
; #define LAS __attribute__((address_space(3)))
; __device__ __forceinline__ void peer_tile(const Args& A, LAS unsigned char* lds, int tile) {
;     ...
;     const unsigned char* T8 = A.ws + WS_T8; const float* SC = (const float*)(A.ws + WS_SC);
;     LAS u32x2* SORT = (LAS u32x2*)(lds + PE_IDX);
;     LAS int* OFFS = (LAS int*)(lds + PE_SEL + 65536);
;     for (int ti = 0; ti < 8; ++ti) {
;         const int tl = 8 * w + ti;
;         const u32x2 e0 = SEL[tl * 128 + lane], e1 = SEL[tl * 128 + 64 + lane];
;         const int p0 = (int)(e0.x >> 10), p1 = (int)(e1.x >> 10);
;         int off = 0;
;         for (int p = 0; p < 16; ++p) {
;             const unsigned long long m0 = __ballot(p0 == p), m1 = __ballot(p1 == p);
;             const int c0 = __popcll(m0), c1 = __popcll(m1);
;             const int r0 = __builtin_amdgcn_mbcnt_hi((unsigned)(m0 >> 32), __builtin_amdgcn_mbcnt_lo((unsigned)m0, 0u));
;             const int r1 = __builtin_amdgcn_mbcnt_hi((unsigned)(m1 >> 32), __builtin_amdgcn_mbcnt_lo((unsigned)m1, 0u));
;             if (p0 == p) SORT[tl * 128 + off + r0] = e0;
;             if (p1 == p) SORT[tl * 128 + off + c0 + r1] = e1;
;             if (lane == 0) OFFS[tl * 17 + p] = off;
;             off += c0 + c1;
;         }
;         if (lane == 0) OFFS[tl * 17 + 16] = off;
;     }
;     ...
;         for (int tk = 0; tk < 4; ++tk) { const size_t m = (size_t)tile * 64 + tb + tk;
;             { const u32x4 ra = *(const u32x4*)(A3 + m * 1024 + 16 * lane), rb = *(const u32x4*)(A3 + m * 1024 + 16 * lane + 8);
;               float xr_; { const f32x4 p0 = *(const f32x4*)(RSq + m * 16), p1 = *(const f32x4*)(RSq + m * 16 + 4), p2 = *(const f32x4*)(RSq + m * 16 + 8), p3 = *(const f32x4*)(RSq + m * 16 + 12);
;                 const f32x4 ps = (p0 + p1) + (p2 + p3); xr_ = rsqrtf(((ps[0] + ps[1]) + (ps[2] + ps[3])) * (1.f / 1024.f) + 1e-6f); }
;               const unsigned rr[8] = {ra.x, ra.y, ra.z, ra.w, rb.x, rb.y, rb.z, rb.w}; unsigned hh[8];
;               const float* sp = MOD + (int)(m >> 11) * 6144 + 3072 + 16 * lane;
; #pragma unroll
;               for (int q = 0; q < 8; ++q) { const f32x2 sh = *(const f32x2*)(sp + 2 * q); hh[q] = pk2(bflo(rr[q]) * xr_ + sh[0], bfhi(rr[q]) * xr_ + sh[1]); }
;               xpa[tk] = (u32x4){hh[0], hh[1], hh[2], hh[3]}; xpb[tk] = (u32x4){hh[4], hh[5], hh[6], hh[7]}; }
	v_pk_add_f32 v[216:217], v[216:217], v[220:221]
	v_pk_add_f32 v[218:219], v[218:219], v[222:223]
	v_pk_add_f32 v[224:225], v[224:225], v[228:229]
	v_pk_add_f32 v[226:227], v[226:227], v[230:231]
	v_pk_add_f32 v[216:217], v[216:217], v[224:225]
	v_pk_add_f32 v[218:219], v[218:219], v[226:227]
	v_add_f32_e32 v216, v216, v217
	v_add_f32_e32 v218, v218, v219
	v_add_f32_e32 v216, v216, v218
	v_fmamk_f32 v216, v216, 0x3a800000, v243
	v_rsq_f32_e32 v216, v216
	v_pk_add_f32 v[232:233], v[232:233], v[236:237]
	v_pk_add_f32 v[234:235], v[234:235], v[238:239]
	v_pk_add_f32 v[248:249], v[248:249], v[252:253]
	v_pk_add_f32 v[250:251], v[250:251], v[254:255]
	v_pk_add_f32 v[232:233], v[232:233], v[248:249]
	v_pk_add_f32 v[234:235], v[234:235], v[250:251]
	v_add_f32_e32 v232, v232, v233
	v_add_f32_e32 v234, v234, v235
	v_add_f32_e32 v232, v232, v234
	v_fmamk_f32 v232, v232, 0x3a800000, v243
	v_rsq_f32_e32 v232, v232
	v_lshlrev_b32_e32 v208, 16, v176
	v_and_b32_e32 v209, 0xffff0000, v176
	v_fma_f32 v208, v208, v216, v192
	v_fma_f32 v209, v209, v216, v193
	v_cvt_pk_bf16_f32 v210, v208, v209
	v_lshlrev_b32_e32 v96, 16, v210
	v_and_b32_e32 v97, 0xffff0000, v210
	v_lshlrev_b32_e32 v208, 16, v177
	v_and_b32_e32 v209, 0xffff0000, v177
	v_fma_f32 v208, v208, v216, v194
	v_fma_f32 v209, v209, v216, v195
	v_cvt_pk_bf16_f32 v210, v208, v209
	v_lshlrev_b32_e32 v98, 16, v210
	v_and_b32_e32 v99, 0xffff0000, v210
	v_lshlrev_b32_e32 v208, 16, v178
	v_and_b32_e32 v209, 0xffff0000, v178
	v_fma_f32 v208, v208, v216, v196
	v_fma_f32 v209, v209, v216, v197
	v_cvt_pk_bf16_f32 v210, v208, v209
	v_lshlrev_b32_e32 v100, 16, v210
	v_and_b32_e32 v101, 0xffff0000, v210
	v_lshlrev_b32_e32 v208, 16, v179
	v_and_b32_e32 v209, 0xffff0000, v179
	v_fma_f32 v208, v208, v216, v198
	v_fma_f32 v209, v209, v216, v199
	v_cvt_pk_bf16_f32 v210, v208, v209
	v_lshlrev_b32_e32 v102, 16, v210
	v_and_b32_e32 v103, 0xffff0000, v210
	v_lshlrev_b32_e32 v208, 16, v180
	v_and_b32_e32 v209, 0xffff0000, v180
	v_fma_f32 v208, v208, v216, v200
	v_fma_f32 v209, v209, v216, v201
	v_cvt_pk_bf16_f32 v210, v208, v209
	v_lshlrev_b32_e32 v104, 16, v210
	v_and_b32_e32 v105, 0xffff0000, v210
	v_lshlrev_b32_e32 v208, 16, v181
	v_and_b32_e32 v209, 0xffff0000, v181
	v_fma_f32 v208, v208, v216, v202
	v_fma_f32 v209, v209, v216, v203
	v_cvt_pk_bf16_f32 v210, v208, v209
	v_lshlrev_b32_e32 v106, 16, v210
	v_and_b32_e32 v107, 0xffff0000, v210
	v_lshlrev_b32_e32 v208, 16, v182
	v_and_b32_e32 v209, 0xffff0000, v182
	v_fma_f32 v208, v208, v216, v204
	v_fma_f32 v209, v209, v216, v205
	v_cvt_pk_bf16_f32 v210, v208, v209
	v_lshlrev_b32_e32 v108, 16, v210
	v_and_b32_e32 v109, 0xffff0000, v210
	v_lshlrev_b32_e32 v208, 16, v183
	v_and_b32_e32 v209, 0xffff0000, v183
	v_fma_f32 v208, v208, v216, v206
	v_fma_f32 v209, v209, v216, v207
	v_cvt_pk_bf16_f32 v210, v208, v209
	v_lshlrev_b32_e32 v110, 16, v210
	v_and_b32_e32 v111, 0xffff0000, v210
	v_lshlrev_b32_e32 v208, 16, v184
	v_and_b32_e32 v209, 0xffff0000, v184
	v_fma_f32 v208, v208, v232, v192
	v_fma_f32 v209, v209, v232, v193
	v_cvt_pk_bf16_f32 v210, v208, v209
	v_lshlrev_b32_e32 v112, 16, v210
	v_and_b32_e32 v113, 0xffff0000, v210
	v_lshlrev_b32_e32 v208, 16, v185
	v_and_b32_e32 v209, 0xffff0000, v185
	v_fma_f32 v208, v208, v232, v194
	v_fma_f32 v209, v209, v232, v195
	v_cvt_pk_bf16_f32 v210, v208, v209
	v_lshlrev_b32_e32 v114, 16, v210
	v_and_b32_e32 v115, 0xffff0000, v210
	v_lshlrev_b32_e32 v208, 16, v186
	v_and_b32_e32 v209, 0xffff0000, v186
	v_fma_f32 v208, v208, v232, v196
	v_fma_f32 v209, v209, v232, v197
	v_cvt_pk_bf16_f32 v210, v208, v209
	v_lshlrev_b32_e32 v116, 16, v210
	v_and_b32_e32 v117, 0xffff0000, v210
	v_lshlrev_b32_e32 v208, 16, v187
	v_and_b32_e32 v209, 0xffff0000, v187
	v_fma_f32 v208, v208, v232, v198
	v_fma_f32 v209, v209, v232, v199
	v_cvt_pk_bf16_f32 v210, v208, v209
	v_lshlrev_b32_e32 v118, 16, v210
	v_and_b32_e32 v119, 0xffff0000, v210
	v_lshlrev_b32_e32 v208, 16, v188
	v_and_b32_e32 v209, 0xffff0000, v188
	v_fma_f32 v208, v208, v232, v200
	v_fma_f32 v209, v209, v232, v201
	v_cvt_pk_bf16_f32 v210, v208, v209
	v_lshlrev_b32_e32 v120, 16, v210
	v_and_b32_e32 v121, 0xffff0000, v210
	v_lshlrev_b32_e32 v208, 16, v189
	v_and_b32_e32 v209, 0xffff0000, v189
	v_fma_f32 v208, v208, v232, v202
	v_fma_f32 v209, v209, v232, v203
	v_cvt_pk_bf16_f32 v210, v208, v209
	v_lshlrev_b32_e32 v122, 16, v210
	v_and_b32_e32 v123, 0xffff0000, v210
	v_lshlrev_b32_e32 v208, 16, v190
	v_and_b32_e32 v209, 0xffff0000, v190
	v_fma_f32 v208, v208, v232, v204
	v_fma_f32 v209, v209, v232, v205
	v_cvt_pk_bf16_f32 v210, v208, v209
	v_lshlrev_b32_e32 v124, 16, v210
	v_and_b32_e32 v125, 0xffff0000, v210
	v_lshlrev_b32_e32 v208, 16, v191
	v_and_b32_e32 v209, 0xffff0000, v191
	v_fma_f32 v208, v208, v232, v206
	v_fma_f32 v209, v209, v232, v207
	v_cvt_pk_bf16_f32 v210, v208, v209
	v_lshlrev_b32_e32 v126, 16, v210
	v_and_b32_e32 v127, 0xffff0000, v210
	s_nop 0
	s_mov_b32 s24, s8
	s_and_b32 s25, s9, 0xffff
	s_mov_b32 s26, 0x20000
	s_mov_b32 s27, 0x00027000
	s_lshl_b32 s0, s76, 10
	s_add_i32 s0, s0, 0x11000
	s_sub_i32 s85, s0, s22
	v_mov_b32_e32 v224, 0x7fffffff
	v_mov_b32_e32 v225, 0x7fffffff
	v_mov_b32_e32 v226, 0x7fffffff
	v_mov_b32_e32 v227, 0x7fffffff
	v_mov_b32_e32 v228, 0
	v_mov_b32_e32 v229, 0
	v_mov_b32_e32 v230, 0
	v_mov_b32_e32 v231, 0
	v_add_u32_e32 v232, s22, v240
	ds_write_b128 v232, v[224:227] offset:0
	ds_write_b128 v232, v[228:231] offset:4992
	ds_write_b128 v232, v[224:227] offset:1024
	ds_write_b128 v232, v[228:231] offset:6016
	ds_write_b128 v232, v[224:227] offset:2048
	ds_write_b128 v232, v[228:231] offset:7040
	ds_write_b128 v232, v[224:227] offset:3072
	ds_write_b128 v232, v[228:231] offset:8064
	s_mov_b32 exec_hi, 0x00ffffff
	ds_write_b128 v232, v[224:227] offset:4096
	s_mov_b32 exec_hi, 0x000fffff
	ds_write_b128 v232, v[228:231] offset:9088
	s_mov_b64 exec, -1
	v_lshrrev_b32_e32 v221, 2, v240
	v_add_u32_e32 v221, s22, v221
	ds_write_b32 v221, v228 offset:4224
	v_lshrrev_b32_e32 v233, 1, v240
	s_lshl_b32 s0, s76, 10
	s_add_i32 s0, s0, 0x11000
	v_add_u32_e32 v233, s0, v233
	ds_read_b64 v[128:129], v233 offset:0
	ds_read_b64 v[130:131], v233 offset:512
	ds_read_b64 v[132:133], v233 offset:1024
	ds_read_b64 v[134:135], v233 offset:1536
	ds_read_b64 v[136:137], v233 offset:2048
	ds_read_b64 v[138:139], v233 offset:2560
	ds_read_b64 v[140:141], v233 offset:3072
	ds_read_b64 v[142:143], v233 offset:3584
	ds_read_b64 v[144:145], v233 offset:4096
	ds_read_b64 v[146:147], v233 offset:4608
	ds_read_b64 v[148:149], v233 offset:5120
	ds_read_b64 v[150:151], v233 offset:5632
	ds_read_b64 v[152:153], v233 offset:6144
	ds_read_b64 v[154:155], v233 offset:6656
	ds_read_b64 v[156:157], v233 offset:7168
	ds_read_b64 v[158:159], v233 offset:7680
	v_mov_b32_e32 v220, 1
	v_lshrrev_b32_e32 v200, 4, v240
	v_lshrrev_b32_e32 v201, 3, v200
	v_and_b32_e32 v200, 7, v200
	s_add_i32 s3, s22, 4224
	s_and_b32 s1, s32, 7
	s_waitcnt lgkmcnt(0)
; __device__ __forceinline__ void peer_tile(const Args& A, LAS unsigned char* lds, int tile) {
;     ...
;     for (int ti = 0; ti < 8; ++ti) {
;         const int tl = 8 * w + ti;
;         const u32x2 e0 = SEL[tl * 128 + lane], e1 = SEL[tl * 128 + 64 + lane];
;         const int p0 = (int)(e0.x >> 10), p1 = (int)(e1.x >> 10);
;         int off = 0;
;         for (int p = 0; p < 16; ++p) {
;             const unsigned long long m0 = __ballot(p0 == p), m1 = __ballot(p1 == p);
;             const int c0 = __popcll(m0), c1 = __popcll(m1);
;             const int r0 = __builtin_amdgcn_mbcnt_hi((unsigned)(m0 >> 32), __builtin_amdgcn_mbcnt_lo((unsigned)m0, 0u));
;             const int r1 = __builtin_amdgcn_mbcnt_hi((unsigned)(m1 >> 32), __builtin_amdgcn_mbcnt_lo((unsigned)m1, 0u));
;             if (p0 == p) SORT[tl * 128 + off + r0] = e0;
;             if (p1 == p) SORT[tl * 128 + off + c0 + r1] = e1;
;             if (lane == 0) OFFS[tl * 17 + p] = off;
;             off += c0 + c1;
;         }
;         if (lane == 0) OFFS[tl * 17 + 16] = off;
;     }
	v_lshrrev_b32_e32 v160, 11, v128
	v_subrev_u32_e32 v160, s1, v160
	v_and_b32_e32 v160, 7, v160
	v_lshl_add_u32 v176, v160, 2, s3
	v_lshrrev_b32_e32 v161, 11, v130
	v_subrev_u32_e32 v161, s1, v161
	v_and_b32_e32 v161, 7, v161
	v_lshl_add_u32 v177, v161, 2, s3
	v_lshrrev_b32_e32 v162, 11, v132
	v_subrev_u32_e32 v162, s1, v162
	v_and_b32_e32 v162, 7, v162
	v_lshl_add_u32 v178, v162, 2, s3
	v_lshrrev_b32_e32 v163, 11, v134
	v_subrev_u32_e32 v163, s1, v163
	v_and_b32_e32 v163, 7, v163
	v_lshl_add_u32 v179, v163, 2, s3
	v_lshrrev_b32_e32 v164, 11, v136
	v_subrev_u32_e32 v164, s1, v164
	v_and_b32_e32 v164, 7, v164
	v_lshl_add_u32 v180, v164, 2, s3
	v_lshrrev_b32_e32 v165, 11, v138
	v_subrev_u32_e32 v165, s1, v165
	v_and_b32_e32 v165, 7, v165
	v_lshl_add_u32 v181, v165, 2, s3
	v_lshrrev_b32_e32 v166, 11, v140
	v_subrev_u32_e32 v166, s1, v166
	v_and_b32_e32 v166, 7, v166
	v_lshl_add_u32 v182, v166, 2, s3
	v_lshrrev_b32_e32 v167, 11, v142
	v_subrev_u32_e32 v167, s1, v167
	v_and_b32_e32 v167, 7, v167
	v_lshl_add_u32 v183, v167, 2, s3
	v_lshrrev_b32_e32 v168, 11, v144
	v_subrev_u32_e32 v168, s1, v168
	v_and_b32_e32 v168, 7, v168
	v_lshl_add_u32 v184, v168, 2, s3
	v_lshrrev_b32_e32 v169, 11, v146
	v_subrev_u32_e32 v169, s1, v169
	v_and_b32_e32 v169, 7, v169
	v_lshl_add_u32 v185, v169, 2, s3
	v_lshrrev_b32_e32 v170, 11, v148
	v_subrev_u32_e32 v170, s1, v170
	v_and_b32_e32 v170, 7, v170
	v_lshl_add_u32 v186, v170, 2, s3
	v_lshrrev_b32_e32 v171, 11, v150
	v_subrev_u32_e32 v171, s1, v171
	v_and_b32_e32 v171, 7, v171
	v_lshl_add_u32 v187, v171, 2, s3
	v_lshrrev_b32_e32 v172, 11, v152
	v_subrev_u32_e32 v172, s1, v172
	v_and_b32_e32 v172, 7, v172
	v_lshl_add_u32 v188, v172, 2, s3
	v_lshrrev_b32_e32 v173, 11, v154
	v_subrev_u32_e32 v173, s1, v173
	v_and_b32_e32 v173, 7, v173
	v_lshl_add_u32 v189, v173, 2, s3
	v_lshrrev_b32_e32 v174, 11, v156
	v_subrev_u32_e32 v174, s1, v174
	v_and_b32_e32 v174, 7, v174
	v_lshl_add_u32 v190, v174, 2, s3
	v_lshrrev_b32_e32 v175, 11, v158
	v_subrev_u32_e32 v175, s1, v175
	v_and_b32_e32 v175, 7, v175
	v_lshl_add_u32 v191, v175, 2, s3
	v_lshlrev_b32_e32 v206, 3, v128
	buffer_load_dwordx2 v[224:225], v206, s[24:27], 0 offen
	v_lshlrev_b32_e32 v206, 3, v130
	buffer_load_dwordx2 v[226:227], v206, s[24:27], 0 offen
	v_lshlrev_b32_e32 v206, 3, v132
	buffer_load_dwordx2 v[228:229], v206, s[24:27], 0 offen
	v_lshlrev_b32_e32 v206, 3, v134
	buffer_load_dwordx2 v[230:231], v206, s[24:27], 0 offen
	v_lshlrev_b32_e32 v206, 3, v136
	buffer_load_dwordx2 v[232:233], v206, s[24:27], 0 offen
	v_lshlrev_b32_e32 v206, 3, v138
	buffer_load_dwordx2 v[234:235], v206, s[24:27], 0 offen
	v_lshlrev_b32_e32 v206, 3, v140
	buffer_load_dwordx2 v[236:237], v206, s[24:27], 0 offen
	v_lshlrev_b32_e32 v206, 3, v142
	buffer_load_dwordx2 v[238:239], v206, s[24:27], 0 offen
	v_lshlrev_b32_e32 v206, 3, v144
	buffer_load_dwordx2 v[248:249], v206, s[24:27], 0 offen
	v_lshlrev_b32_e32 v206, 3, v146
	buffer_load_dwordx2 v[250:251], v206, s[24:27], 0 offen
	v_lshlrev_b32_e32 v206, 3, v148
	buffer_load_dwordx2 v[252:253], v206, s[24:27], 0 offen
	v_lshlrev_b32_e32 v206, 3, v150
	buffer_load_dwordx2 v[254:255], v206, s[24:27], 0 offen
	ds_add_rtn_u32 v176, v176, v220 offset:0
	ds_add_rtn_u32 v177, v177, v220 offset:0
	ds_add_rtn_u32 v178, v178, v220 offset:32
	ds_add_rtn_u32 v179, v179, v220 offset:32
	ds_add_rtn_u32 v180, v180, v220 offset:64
	ds_add_rtn_u32 v181, v181, v220 offset:64
	ds_add_rtn_u32 v182, v182, v220 offset:96
	ds_add_rtn_u32 v183, v183, v220 offset:96
	ds_add_rtn_u32 v184, v184, v220 offset:128
	ds_add_rtn_u32 v185, v185, v220 offset:128
	ds_add_rtn_u32 v186, v186, v220 offset:160
	ds_add_rtn_u32 v187, v187, v220 offset:160
	ds_add_rtn_u32 v188, v188, v220 offset:192
	ds_add_rtn_u32 v189, v189, v220 offset:192
	ds_add_rtn_u32 v190, v190, v220 offset:224
	ds_add_rtn_u32 v191, v191, v220 offset:224
	v_lshl_add_u32 v207, v201, 5, s3
	ds_read_b32 v203, v221 offset:4224
	ds_read_b128 v[192:195], v207
	ds_read_b128 v[196:199], v207 offset:16
	v_mov_b32_e32 v202, 0
	s_waitcnt lgkmcnt(0)
	v_cmp_lt_u32_e64 s[38:39], 0, v200
	v_cmp_lt_u32_e64 s[40:41], 1, v200
	v_cmp_lt_u32_e64 s[42:43], 2, v200
	v_cmp_lt_u32_e64 s[44:45], 3, v200
	v_cmp_lt_u32_e64 s[64:65], 4, v200
	v_cmp_lt_u32_e64 s[66:67], 5, v200
	v_cmp_lt_u32_e64 s[94:95], 6, v200
	v_cndmask_b32_e64 v206, 0, v192, s[38:39]
	v_add_u32_e32 v202, v202, v206
	v_cndmask_b32_e64 v206, 0, v193, s[40:41]
	v_add_u32_e32 v202, v202, v206
	v_cndmask_b32_e64 v206, 0, v194, s[42:43]
	v_add_u32_e32 v202, v202, v206
	v_cndmask_b32_e64 v206, 0, v195, s[44:45]
	v_add_u32_e32 v202, v202, v206
	v_cndmask_b32_e64 v206, 0, v196, s[64:65]
	v_add_u32_e32 v202, v202, v206
	v_cndmask_b32_e64 v206, 0, v197, s[66:67]
	v_add_u32_e32 v202, v202, v206
	v_cndmask_b32_e64 v206, 0, v198, s[94:95]
	v_add_u32_e32 v202, v202, v206
	v_add_u32_e32 v204, 3, v202
	v_add3_u32 v212, v202, v203, 3
	v_lshrrev_b32_e32 v204, 2, v204
	v_lshrrev_b32_e32 v212, 2, v212
	v_sub_u32_e32 v212, v212, v204
	v_lshl_add_u32 v207, v200, 3, v201
	v_lshl_add_u32 v207, v207, 2, s3
	ds_write_b32 v207, v212 offset:256
	v_lshl_add_u32 v208, v200, 5, s3
	ds_read_b128 v[192:195], v208 offset:256
	ds_read_b128 v[196:199], v208 offset:272
	v_mov_b32_e32 v205, 0
	s_waitcnt lgkmcnt(0)
; __device__ __forceinline__ void peer_tile(const Args& A, LAS unsigned char* lds, int tile) {
;     ...
;     for (int ti = 0; ti < 8; ++ti) {
;         const int tl = 8 * w + ti;
;         const u32x2 e0 = SEL[tl * 128 + lane], e1 = SEL[tl * 128 + 64 + lane];
;         const int p0 = (int)(e0.x >> 10), p1 = (int)(e1.x >> 10);
;         int off = 0;
;         for (int p = 0; p < 16; ++p) {
;             const unsigned long long m0 = __ballot(p0 == p), m1 = __ballot(p1 == p);
;             const int c0 = __popcll(m0), c1 = __popcll(m1);
;             const int r0 = __builtin_amdgcn_mbcnt_hi((unsigned)(m0 >> 32), __builtin_amdgcn_mbcnt_lo((unsigned)m0, 0u));
;             const int r1 = __builtin_amdgcn_mbcnt_hi((unsigned)(m1 >> 32), __builtin_amdgcn_mbcnt_lo((unsigned)m1, 0u));
;             if (p0 == p) SORT[tl * 128 + off + r0] = e0;
;             if (p1 == p) SORT[tl * 128 + off + c0 + r1] = e1;
;             if (lane == 0) OFFS[tl * 17 + p] = off;
;             off += c0 + c1;
;         }
;         if (lane == 0) OFFS[tl * 17 + 16] = off;
;     }
	v_cmp_lt_u32_e64 s[38:39], 0, v201
	v_cmp_lt_u32_e64 s[40:41], 1, v201
	v_cmp_lt_u32_e64 s[42:43], 2, v201
	v_cmp_lt_u32_e64 s[44:45], 3, v201
	v_cmp_lt_u32_e64 s[64:65], 4, v201
	v_cmp_lt_u32_e64 s[66:67], 5, v201
	v_cmp_lt_u32_e64 s[94:95], 6, v201
	v_cndmask_b32_e64 v206, 0, v192, s[38:39]
	v_add_u32_e32 v205, v205, v206
	v_cndmask_b32_e64 v206, 0, v193, s[40:41]
	v_add_u32_e32 v205, v205, v206
	v_cndmask_b32_e64 v206, 0, v194, s[42:43]
	v_add_u32_e32 v205, v205, v206
	v_cndmask_b32_e64 v206, 0, v195, s[44:45]
	v_add_u32_e32 v205, v205, v206
	v_cndmask_b32_e64 v206, 0, v196, s[64:65]
	v_add_u32_e32 v205, v205, v206
	v_cndmask_b32_e64 v206, 0, v197, s[66:67]
	v_add_u32_e32 v205, v205, v206
	v_cndmask_b32_e64 v206, 0, v198, s[94:95]
	v_add_u32_e32 v205, v205, v206
	v_add_u32_e32 v206, v192, v193
	v_add_u32_e32 v206, v206, v194
	v_add_u32_e32 v206, v206, v195
	v_add_u32_e32 v206, v206, v196
	v_add_u32_e32 v206, v206, v197
	v_add_u32_e32 v206, v206, v198
	v_add_u32_e32 v206, v206, v199
	v_lshl_add_u32 v207, v200, 2, s3
	ds_write_b32 v207, v206 offset:512
	v_mov_b32_e32 v207, s3
	ds_read_b128 v[192:195], v207 offset:512
	ds_read_b128 v[196:199], v207 offset:528
	ds_write_b32 v221, v202 offset:4224
	s_waitcnt lgkmcnt(0)
	v_cmp_lt_u32_e64 s[38:39], 0, v200
	v_cmp_lt_u32_e64 s[40:41], 1, v200
	v_cmp_lt_u32_e64 s[42:43], 2, v200
	v_cmp_lt_u32_e64 s[44:45], 3, v200
	v_cmp_lt_u32_e64 s[64:65], 4, v200
	v_cmp_lt_u32_e64 s[66:67], 5, v200
	v_cmp_lt_u32_e64 s[94:95], 6, v200
	v_cndmask_b32_e64 v206, 0, v192, s[38:39]
	v_add_u32_e32 v205, v205, v206
	v_cndmask_b32_e64 v206, 0, v193, s[40:41]
	v_add_u32_e32 v205, v205, v206
	v_cndmask_b32_e64 v206, 0, v194, s[42:43]
	v_add_u32_e32 v205, v205, v206
	v_cndmask_b32_e64 v206, 0, v195, s[44:45]
	v_add_u32_e32 v205, v205, v206
	v_cndmask_b32_e64 v206, 0, v196, s[64:65]
	v_add_u32_e32 v205, v205, v206
	v_cndmask_b32_e64 v206, 0, v197, s[66:67]
	v_add_u32_e32 v205, v205, v206
	v_cndmask_b32_e64 v206, 0, v198, s[94:95]
	v_add_u32_e32 v205, v205, v206
	v_sub_u32_e32 v205, v205, v204
	v_lshrrev_b32_e32 v208, 4, v240
	v_and_b32_e32 v222, 31, v208
	v_lshrrev_b32_e32 v208, 5, v208
	v_add_u32_e32 v207, 0, v208
	v_lshl_add_u32 v206, v207, 5, s3
	ds_read_b128 v[192:195], v206
	ds_read_b128 v[196:199], v206 offset:16
	v_lshlrev_b32_e32 v206, 2, v222
	v_lshlrev_b32_e32 v223, 3, v207
	s_waitcnt lgkmcnt(0)
	v_cmp_le_u32_e64 s[38:39], v193, v206
	v_cmp_le_u32_e64 s[40:41], v194, v206
	v_cmp_le_u32_e64 s[42:43], v195, v206
	v_cmp_le_u32_e64 s[44:45], v196, v206
	v_cmp_le_u32_e64 s[64:65], v197, v206
	v_cmp_le_u32_e64 s[66:67], v198, v206
	v_cmp_le_u32_e64 s[94:95], v199, v206
	v_addc_co_u32_e64 v223, s[92:93], 0, v223, s[38:39]
	v_addc_co_u32_e64 v223, s[92:93], 0, v223, s[40:41]
	v_addc_co_u32_e64 v223, s[92:93], 0, v223, s[42:43]
	v_addc_co_u32_e64 v223, s[92:93], 0, v223, s[44:45]
	v_addc_co_u32_e64 v223, s[92:93], 0, v223, s[64:65]
	v_addc_co_u32_e64 v223, s[92:93], 0, v223, s[66:67]
	v_addc_co_u32_e64 v223, s[92:93], 0, v223, s[94:95]
	v_lshlrev_b32_e32 v223, 2, v223
	ds_bpermute_b32 v216, v223, v205
	v_add_u32_e32 v207, 2, v208
	v_lshl_add_u32 v206, v207, 5, s3
	ds_read_b128 v[192:195], v206
	ds_read_b128 v[196:199], v206 offset:16
	v_lshlrev_b32_e32 v206, 2, v222
	v_lshlrev_b32_e32 v223, 3, v207
	s_waitcnt lgkmcnt(0)
	v_cmp_le_u32_e64 s[38:39], v193, v206
	v_cmp_le_u32_e64 s[40:41], v194, v206
	v_cmp_le_u32_e64 s[42:43], v195, v206
	v_cmp_le_u32_e64 s[44:45], v196, v206
	v_cmp_le_u32_e64 s[64:65], v197, v206
	v_cmp_le_u32_e64 s[66:67], v198, v206
	v_cmp_le_u32_e64 s[94:95], v199, v206
	v_addc_co_u32_e64 v223, s[92:93], 0, v223, s[38:39]
	v_addc_co_u32_e64 v223, s[92:93], 0, v223, s[40:41]
	v_addc_co_u32_e64 v223, s[92:93], 0, v223, s[42:43]
	v_addc_co_u32_e64 v223, s[92:93], 0, v223, s[44:45]
	v_addc_co_u32_e64 v223, s[92:93], 0, v223, s[64:65]
	v_addc_co_u32_e64 v223, s[92:93], 0, v223, s[66:67]
	v_addc_co_u32_e64 v223, s[92:93], 0, v223, s[94:95]
	v_lshlrev_b32_e32 v223, 2, v223
	ds_bpermute_b32 v217, v223, v205
	v_add_u32_e32 v207, 4, v208
	v_lshl_add_u32 v206, v207, 5, s3
	ds_read_b128 v[192:195], v206
	ds_read_b128 v[196:199], v206 offset:16
	v_lshlrev_b32_e32 v206, 2, v222
	v_lshlrev_b32_e32 v223, 3, v207
	s_waitcnt lgkmcnt(0)
	v_cmp_le_u32_e64 s[38:39], v193, v206
	v_cmp_le_u32_e64 s[40:41], v194, v206
	v_cmp_le_u32_e64 s[42:43], v195, v206
	v_cmp_le_u32_e64 s[44:45], v196, v206
	v_cmp_le_u32_e64 s[64:65], v197, v206
	v_cmp_le_u32_e64 s[66:67], v198, v206
	v_cmp_le_u32_e64 s[94:95], v199, v206
	v_addc_co_u32_e64 v223, s[92:93], 0, v223, s[38:39]
	v_addc_co_u32_e64 v223, s[92:93], 0, v223, s[40:41]
	v_addc_co_u32_e64 v223, s[92:93], 0, v223, s[42:43]
	v_addc_co_u32_e64 v223, s[92:93], 0, v223, s[44:45]
	v_addc_co_u32_e64 v223, s[92:93], 0, v223, s[64:65]
	v_addc_co_u32_e64 v223, s[92:93], 0, v223, s[66:67]
	v_addc_co_u32_e64 v223, s[92:93], 0, v223, s[94:95]
	v_lshlrev_b32_e32 v223, 2, v223
	ds_bpermute_b32 v218, v223, v205
	v_add_u32_e32 v207, 6, v208
	v_lshl_add_u32 v206, v207, 5, s3
	ds_read_b128 v[192:195], v206
	ds_read_b128 v[196:199], v206 offset:16
	v_lshlrev_b32_e32 v206, 2, v222
	v_lshlrev_b32_e32 v223, 3, v207
	s_waitcnt lgkmcnt(0)
	v_cmp_le_u32_e64 s[38:39], v193, v206
	v_cmp_le_u32_e64 s[40:41], v194, v206
	v_cmp_le_u32_e64 s[42:43], v195, v206
	v_cmp_le_u32_e64 s[44:45], v196, v206
	v_cmp_le_u32_e64 s[64:65], v197, v206
	v_cmp_le_u32_e64 s[66:67], v198, v206
	v_cmp_le_u32_e64 s[94:95], v199, v206
	v_addc_co_u32_e64 v223, s[92:93], 0, v223, s[38:39]
	v_addc_co_u32_e64 v223, s[92:93], 0, v223, s[40:41]
	v_addc_co_u32_e64 v223, s[92:93], 0, v223, s[42:43]
	v_addc_co_u32_e64 v223, s[92:93], 0, v223, s[44:45]
	v_addc_co_u32_e64 v223, s[92:93], 0, v223, s[64:65]
	v_addc_co_u32_e64 v223, s[92:93], 0, v223, s[66:67]
	v_addc_co_u32_e64 v223, s[92:93], 0, v223, s[94:95]
	v_lshlrev_b32_e32 v223, 2, v223
	ds_bpermute_b32 v219, v223, v205
	s_waitcnt lgkmcnt(0)
; __device__ __forceinline__ void peer_tile(const Args& A, LAS unsigned char* lds, int tile) {
;     ...
;     for (int ti = 0; ti < 8; ++ti) {
;         const int tl = 8 * w + ti;
;         const u32x2 e0 = SEL[tl * 128 + lane], e1 = SEL[tl * 128 + 64 + lane];
;         const int p0 = (int)(e0.x >> 10), p1 = (int)(e1.x >> 10);
;         int off = 0;
;         for (int p = 0; p < 16; ++p) {
;             const unsigned long long m0 = __ballot(p0 == p), m1 = __ballot(p1 == p);
;             const int c0 = __popcll(m0), c1 = __popcll(m1);
;             const int r0 = __builtin_amdgcn_mbcnt_hi((unsigned)(m0 >> 32), __builtin_amdgcn_mbcnt_lo((unsigned)m0, 0u));
;             const int r1 = __builtin_amdgcn_mbcnt_hi((unsigned)(m1 >> 32), __builtin_amdgcn_mbcnt_lo((unsigned)m1, 0u));
;             if (p0 == p) SORT[tl * 128 + off + r0] = e0;
;             if (p1 == p) SORT[tl * 128 + off + c0 + r1] = e1;
;             if (lane == 0) OFFS[tl * 17 + p] = off;
;             off += c0 + c1;
;         }
;         if (lane == 0) OFFS[tl * 17 + 16] = off;
;     }
	v_add_u32_e32 v216, v216, v222
	v_add_u32_e32 v217, v217, v222
	v_add_u32_e32 v218, v218, v222
	v_add_u32_e32 v219, v219, v222
	v_lshlrev_b32_e32 v206, 3, v152
	buffer_load_dwordx2 v[192:193], v206, s[24:27], 0 offen
	v_lshlrev_b32_e32 v206, 3, v154
	buffer_load_dwordx2 v[194:195], v206, s[24:27], 0 offen
	v_lshlrev_b32_e32 v206, 3, v156
	buffer_load_dwordx2 v[196:197], v206, s[24:27], 0 offen
	v_lshlrev_b32_e32 v206, 3, v158
	buffer_load_dwordx2 v[198:199], v206, s[24:27], 0 offen
	v_lshlrev_b32_e32 v160, 2, v160
	ds_bpermute_b32 v160, v160, v202
	v_lshlrev_b32_e32 v161, 2, v161
	ds_bpermute_b32 v161, v161, v202
	v_lshlrev_b32_e32 v162, 2, v162
	v_add_u32_e32 v162, 32, v162
	ds_bpermute_b32 v162, v162, v202
	v_lshlrev_b32_e32 v163, 2, v163
	v_add_u32_e32 v163, 32, v163
	ds_bpermute_b32 v163, v163, v202
	v_lshlrev_b32_e32 v164, 2, v164
	v_add_u32_e32 v164, 64, v164
	ds_bpermute_b32 v164, v164, v202
	v_lshlrev_b32_e32 v165, 2, v165
	v_add_u32_e32 v165, 64, v165
	ds_bpermute_b32 v165, v165, v202
	v_lshlrev_b32_e32 v166, 2, v166
	v_add_u32_e32 v166, 96, v166
	ds_bpermute_b32 v166, v166, v202
	v_lshlrev_b32_e32 v167, 2, v167
	v_add_u32_e32 v167, 96, v167
	ds_bpermute_b32 v167, v167, v202
	v_lshlrev_b32_e32 v168, 2, v168
	v_add_u32_e32 v168, 128, v168
	ds_bpermute_b32 v168, v168, v202
	v_lshlrev_b32_e32 v169, 2, v169
	v_add_u32_e32 v169, 128, v169
	ds_bpermute_b32 v169, v169, v202
	v_lshlrev_b32_e32 v170, 2, v170
	v_add_u32_e32 v170, 160, v170
	ds_bpermute_b32 v170, v170, v202
	v_lshlrev_b32_e32 v171, 2, v171
	v_add_u32_e32 v171, 160, v171
	ds_bpermute_b32 v171, v171, v202
	v_lshlrev_b32_e32 v172, 2, v172
	v_add_u32_e32 v172, 192, v172
	ds_bpermute_b32 v172, v172, v202
	v_lshlrev_b32_e32 v173, 2, v173
	v_add_u32_e32 v173, 192, v173
	ds_bpermute_b32 v173, v173, v202
	v_lshlrev_b32_e32 v174, 2, v174
	v_add_u32_e32 v174, 224, v174
	ds_bpermute_b32 v174, v174, v202
	v_lshlrev_b32_e32 v175, 2, v175
	v_add_u32_e32 v175, 224, v175
	ds_bpermute_b32 v175, v175, v202
	s_waitcnt lgkmcnt(0)
	v_add_u32_e32 v176, v176, v160
	v_lshrrev_b32_e32 v160, 2, v176
	v_and_b32_e32 v176, 3, v176
	v_lshlrev_b32_e32 v160, 2, v160
	ds_bpermute_b32 v160, v160, v216
	v_add_u32_e32 v177, v177, v161
	v_lshrrev_b32_e32 v161, 2, v177
	v_and_b32_e32 v177, 3, v177
	v_lshlrev_b32_e32 v161, 2, v161
	ds_bpermute_b32 v161, v161, v216
	v_add_u32_e32 v178, v178, v162
	v_lshrrev_b32_e32 v162, 2, v178
	v_and_b32_e32 v178, 3, v178
	v_lshlrev_b32_e32 v162, 2, v162
	v_add_u32_e32 v162, 128, v162
	ds_bpermute_b32 v162, v162, v216
	v_add_u32_e32 v179, v179, v163
	v_lshrrev_b32_e32 v163, 2, v179
	v_and_b32_e32 v179, 3, v179
	v_lshlrev_b32_e32 v163, 2, v163
	v_add_u32_e32 v163, 128, v163
	ds_bpermute_b32 v163, v163, v216
	v_add_u32_e32 v180, v180, v164
	v_lshrrev_b32_e32 v164, 2, v180
	v_and_b32_e32 v180, 3, v180
	v_lshlrev_b32_e32 v164, 2, v164
	ds_bpermute_b32 v164, v164, v217
	v_add_u32_e32 v181, v181, v165
	v_lshrrev_b32_e32 v165, 2, v181
	v_and_b32_e32 v181, 3, v181
	v_lshlrev_b32_e32 v165, 2, v165
	ds_bpermute_b32 v165, v165, v217
	v_add_u32_e32 v182, v182, v166
	v_lshrrev_b32_e32 v166, 2, v182
	v_and_b32_e32 v182, 3, v182
	v_lshlrev_b32_e32 v166, 2, v166
	v_add_u32_e32 v166, 128, v166
	ds_bpermute_b32 v166, v166, v217
	v_add_u32_e32 v183, v183, v167
	v_lshrrev_b32_e32 v167, 2, v183
	v_and_b32_e32 v183, 3, v183
	v_lshlrev_b32_e32 v167, 2, v167
	v_add_u32_e32 v167, 128, v167
	ds_bpermute_b32 v167, v167, v217
	v_add_u32_e32 v184, v184, v168
	v_lshrrev_b32_e32 v168, 2, v184
	v_and_b32_e32 v184, 3, v184
	v_lshlrev_b32_e32 v168, 2, v168
	ds_bpermute_b32 v168, v168, v218
	v_add_u32_e32 v185, v185, v169
	v_lshrrev_b32_e32 v169, 2, v185
	v_and_b32_e32 v185, 3, v185
	v_lshlrev_b32_e32 v169, 2, v169
	ds_bpermute_b32 v169, v169, v218
	v_add_u32_e32 v186, v186, v170
	v_lshrrev_b32_e32 v170, 2, v186
	v_and_b32_e32 v186, 3, v186
	v_lshlrev_b32_e32 v170, 2, v170
	v_add_u32_e32 v170, 128, v170
	ds_bpermute_b32 v170, v170, v218
	v_add_u32_e32 v187, v187, v171
	v_lshrrev_b32_e32 v171, 2, v187
	v_and_b32_e32 v187, 3, v187
	v_lshlrev_b32_e32 v171, 2, v171
	v_add_u32_e32 v171, 128, v171
	ds_bpermute_b32 v171, v171, v218
	v_add_u32_e32 v188, v188, v172
	v_lshrrev_b32_e32 v172, 2, v188
	v_and_b32_e32 v188, 3, v188
	v_lshlrev_b32_e32 v172, 2, v172
	ds_bpermute_b32 v172, v172, v219
	v_add_u32_e32 v189, v189, v173
	v_lshrrev_b32_e32 v173, 2, v189
	v_and_b32_e32 v189, 3, v189
	v_lshlrev_b32_e32 v173, 2, v173
	ds_bpermute_b32 v173, v173, v219
	v_add_u32_e32 v190, v190, v174
	v_lshrrev_b32_e32 v174, 2, v190
	v_and_b32_e32 v190, 3, v190
	v_lshlrev_b32_e32 v174, 2, v174
	v_add_u32_e32 v174, 128, v174
	ds_bpermute_b32 v174, v174, v219
	v_add_u32_e32 v191, v191, v175
	v_lshrrev_b32_e32 v175, 2, v191
	v_and_b32_e32 v191, 3, v191
	v_lshlrev_b32_e32 v175, 2, v175
	v_add_u32_e32 v175, 128, v175
	ds_bpermute_b32 v175, v175, v219
	s_waitcnt lgkmcnt(0)
; #define IT_ADVANCE() do { it_j += 4; while (it_j >= it_end) { if (it_done) break; ++it_tk; if (it_tk == 4) { it_tk = 0; ++it_p; if (it_p == 16) { it_done = true; it_p = 15; it_j = 0; it_end = 1; break; } } \
;             it_j = __builtin_amdgcn_readfirstlane(OFFS[(tb + it_tk) * 17 + it_p]); it_end = __builtin_amdgcn_readfirstlane(OFFS[(tb + it_tk) * 17 + it_p + 1]); } } while (0)
; __device__ __forceinline__ void peer_tile(const Args& A, LAS unsigned char* lds, int tile) {
;     ...
;             if (p0 == p) SORT[tl * 128 + off + r0] = e0;
;             if (p1 == p) SORT[tl * 128 + off + c0 + r1] = e1;
;             if (lane == 0) OFFS[tl * 17 + p] = off;
;             off += c0 + c1;
;         }
;         if (lane == 0) OFFS[tl * 17 + 16] = off;
;     }
;     ...
;         int it_p = 0, it_tk = -1, it_j = 0, it_end = 0; bool it_done = false;
;     ...
;         u32x4 uA[4], vA[4], uB[4], vB[4]; float cgA = 0.f, suA = 0.f, svA = 0.f, cgB = 0.f, suB = 0.f, svB = 0.f;
; #pragma unroll
;         for (int k = 0; k < 4; ++k) { uA[k] = (u32x4){0u, 0u, 0u, 0u}; vA[k] = uA[k]; uB[k] = uA[k]; vB[k] = uA[k]; }
;         IT_ADVANCE();
;         LOAD_SET(uA, vA, cgA, suA, svA);
	v_lshl_add_u32 v160, v160, 4, s22
	v_lshl_add_u32 v160, v176, 2, v160
	ds_write_b32 v160, v128
	ds_write_b32 v160, v129 offset:4992
	v_lshl_add_u32 v161, v161, 4, s22
	v_lshl_add_u32 v161, v177, 2, v161
	ds_write_b32 v161, v130
	ds_write_b32 v161, v131 offset:4992
	v_lshl_add_u32 v162, v162, 4, s22
	v_lshl_add_u32 v162, v178, 2, v162
	ds_write_b32 v162, v132
	ds_write_b32 v162, v133 offset:4992
	v_lshl_add_u32 v163, v163, 4, s22
	v_lshl_add_u32 v163, v179, 2, v163
	ds_write_b32 v163, v134
	ds_write_b32 v163, v135 offset:4992
	v_lshl_add_u32 v164, v164, 4, s22
	v_lshl_add_u32 v164, v180, 2, v164
	ds_write_b32 v164, v136
	ds_write_b32 v164, v137 offset:4992
	v_lshl_add_u32 v165, v165, 4, s22
	v_lshl_add_u32 v165, v181, 2, v165
	ds_write_b32 v165, v138
	ds_write_b32 v165, v139 offset:4992
	v_lshl_add_u32 v166, v166, 4, s22
	v_lshl_add_u32 v166, v182, 2, v166
	ds_write_b32 v166, v140
	ds_write_b32 v166, v141 offset:4992
	v_lshl_add_u32 v167, v167, 4, s22
	v_lshl_add_u32 v167, v183, 2, v167
	ds_write_b32 v167, v142
	ds_write_b32 v167, v143 offset:4992
	v_lshl_add_u32 v168, v168, 4, s22
	v_lshl_add_u32 v168, v184, 2, v168
	ds_write_b32 v168, v144
	ds_write_b32 v168, v145 offset:4992
	v_lshl_add_u32 v169, v169, 4, s22
	v_lshl_add_u32 v169, v185, 2, v169
	ds_write_b32 v169, v146
	ds_write_b32 v169, v147 offset:4992
	v_lshl_add_u32 v170, v170, 4, s22
	v_lshl_add_u32 v170, v186, 2, v170
	ds_write_b32 v170, v148
	ds_write_b32 v170, v149 offset:4992
	v_lshl_add_u32 v171, v171, 4, s22
	v_lshl_add_u32 v171, v187, 2, v171
	ds_write_b32 v171, v150
	ds_write_b32 v171, v151 offset:4992
	v_lshl_add_u32 v172, v172, 4, s22
	v_lshl_add_u32 v172, v188, 2, v172
	ds_write_b32 v172, v152
	ds_write_b32 v172, v153 offset:4992
	v_lshl_add_u32 v173, v173, 4, s22
	v_lshl_add_u32 v173, v189, 2, v173
	ds_write_b32 v173, v154
	ds_write_b32 v173, v155 offset:4992
	v_lshl_add_u32 v174, v174, 4, s22
	v_lshl_add_u32 v174, v190, 2, v174
	ds_write_b32 v174, v156
	ds_write_b32 v174, v157 offset:4992
	v_lshl_add_u32 v175, v175, 4, s22
	v_lshl_add_u32 v175, v191, 2, v175
	ds_write_b32 v175, v158
	ds_write_b32 v175, v159 offset:4992
	s_waitcnt vmcnt(0)
	v_add_u32_e32 v160, s85, v160
	ds_write_b32 v160, v224
	ds_write_b32 v160, v225 offset:4096
	v_add_u32_e32 v161, s85, v161
	ds_write_b32 v161, v226
	ds_write_b32 v161, v227 offset:4096
	v_add_u32_e32 v162, s85, v162
	ds_write_b32 v162, v228
	ds_write_b32 v162, v229 offset:4096
	v_add_u32_e32 v163, s85, v163
	ds_write_b32 v163, v230
	ds_write_b32 v163, v231 offset:4096
	v_add_u32_e32 v164, s85, v164
	ds_write_b32 v164, v232
	ds_write_b32 v164, v233 offset:4096
	v_add_u32_e32 v165, s85, v165
	ds_write_b32 v165, v234
	ds_write_b32 v165, v235 offset:4096
	v_add_u32_e32 v166, s85, v166
	ds_write_b32 v166, v236
	ds_write_b32 v166, v237 offset:4096
	v_add_u32_e32 v167, s85, v167
	ds_write_b32 v167, v238
	ds_write_b32 v167, v239 offset:4096
	v_add_u32_e32 v168, s85, v168
	ds_write_b32 v168, v248
	ds_write_b32 v168, v249 offset:4096
	v_add_u32_e32 v169, s85, v169
	ds_write_b32 v169, v250
	ds_write_b32 v169, v251 offset:4096
	v_add_u32_e32 v170, s85, v170
	ds_write_b32 v170, v252
	ds_write_b32 v170, v253 offset:4096
	v_add_u32_e32 v171, s85, v171
	ds_write_b32 v171, v254
	ds_write_b32 v171, v255 offset:4096
	v_add_u32_e32 v172, s85, v172
	ds_write_b32 v172, v192
	ds_write_b32 v172, v193 offset:4096
	v_add_u32_e32 v173, s85, v173
	ds_write_b32 v173, v194
	ds_write_b32 v173, v195 offset:4096
	v_add_u32_e32 v174, s85, v174
	ds_write_b32 v174, v196
	ds_write_b32 v174, v197 offset:4096
	v_add_u32_e32 v175, s85, v175
	ds_write_b32 v175, v198
	ds_write_b32 v175, v199 offset:4096
	v_mov_b32_e32 v206, 0x7fffffff
	ds_write_b32 v221, v206 offset:4224
	ds_write_b32 v221, v206 offset:4480
	ds_write_b32 v221, v206 offset:4736
	s_mov_b32 s91, 256
	s_add_i32 s20, s91, 3
	s_and_b32 s20, s20, -4
	s_mov_b32 s24, s8
	s_and_b32 s25, s9, 0xffff
	s_mov_b32 s26, 0x20000
	s_mov_b32 s27, 0x00027000
	s_mov_b32 s28, s52
	s_and_b32 s29, s53, 0xffff
	s_mov_b32 s30, 0x20000
	s_mov_b32 s31, 0x00027000
	s_waitcnt vmcnt(0) lgkmcnt(0)
	v_mov_b32_e32 v213, s22
	v_mov_b32_e32 v233, v240
	v_mov_b32_e32 v235, v240
	v_mov_b32_e32 v237, v240
	v_mov_b32_e32 v239, v240
	ds_read_b32 v232, v213 offset:0
	ds_read_b32 v234, v213 offset:4
	ds_read_b32 v236, v213 offset:8
	ds_read_b32 v238, v213 offset:12
	s_waitcnt lgkmcnt(0)
	buffer_load_dwordx4 v[128:131], v[232:233], s[56:59], 0 idxen offen
	buffer_load_dwordx4 v[132:135], v[234:235], s[56:59], 0 idxen offen
	buffer_load_dwordx4 v[136:139], v[236:237], s[56:59], 0 idxen offen
	buffer_load_dwordx4 v[140:143], v[238:239], s[56:59], 0 idxen offen
	ds_read_b32 v232, v213 offset:16
	ds_read_b32 v234, v213 offset:20
	ds_read_b32 v236, v213 offset:24
	ds_read_b32 v238, v213 offset:28
	s_waitcnt lgkmcnt(0)
	buffer_load_dwordx4 v[144:147], v[232:233], s[56:59], 0 idxen offen
	buffer_load_dwordx4 v[148:151], v[234:235], s[56:59], 0 idxen offen
	buffer_load_dwordx4 v[152:155], v[236:237], s[56:59], 0 idxen offen
	buffer_load_dwordx4 v[156:159], v[238:239], s[56:59], 0 idxen offen
	ds_read_b32 v232, v213 offset:32
	ds_read_b32 v234, v213 offset:36
	ds_read_b32 v236, v213 offset:40
	ds_read_b32 v238, v213 offset:44
	s_waitcnt lgkmcnt(0)
	buffer_load_dwordx4 v[160:163], v[232:233], s[56:59], 0 idxen offen
	buffer_load_dwordx4 v[164:167], v[234:235], s[56:59], 0 idxen offen
	buffer_load_dwordx4 v[168:171], v[236:237], s[56:59], 0 idxen offen
	buffer_load_dwordx4 v[172:175], v[238:239], s[56:59], 0 idxen offen
	ds_read_b32 v232, v213 offset:48
	ds_read_b32 v234, v213 offset:52
	ds_read_b32 v236, v213 offset:56
	ds_read_b32 v238, v213 offset:60
	s_mov_b32 s21, 0
	s_mov_b32 s89, -1
	s_mov_b32 s86, 0
	v_lshrrev_b32_e32 v208, 6, v240
	v_and_b32_e32 v208, 3, v208
	v_lshrrev_b32_e32 v209, 1, v208
	v_lshlrev_b32_e32 v208, 1, v208
	v_and_b32_e32 v208, 2, v208
	v_or_b32_e32 v208, v208, v209
	v_lshlrev_b32_e32 v208, 2, v208
	v_add3_u32 v211, v208, v247, s22
	v_add_u32_e32 v250, s85, v211
	ds_read_b32 v252, v250
	ds_read_b32 v253, v250 offset:4096
	ds_read_b32 v249, v211 offset:4992
	s_branch .LU_sw0
.LU_t0_s0:
	s_cmp_ge_u32 s21, s20
	s_cbranch_scc1 .LU_done
	s_waitcnt lgkmcnt(0)
	buffer_load_dwordx4 v[176:179], v[232:233], s[56:59], 0 idxen offen
	buffer_load_dwordx4 v[180:183], v[234:235], s[56:59], 0 idxen offen
	buffer_load_dwordx4 v[184:187], v[236:237], s[56:59], 0 idxen offen
	buffer_load_dwordx4 v[188:191], v[238:239], s[56:59], 0 idxen offen
	ds_read_b32 v232, v213 offset:64
	ds_read_b32 v234, v213 offset:68
	ds_read_b32 v236, v213 offset:72
	ds_read_b32 v238, v213 offset:76
	s_waitcnt vmcnt(12)
	v_cvt_pk_f32_fp8_e32 v[224:225], v128
	v_cvt_pk_f32_fp8_e32 v[226:227], v132
	v_cvt_pk_f32_fp8_e32 v[228:229], v136
	v_cvt_pk_f32_fp8_e32 v[230:231], v140
	v_pk_mul_f32 v[216:217], v[224:225], v[0:1]
	v_pk_mul_f32 v[218:219], v[226:227], v[0:1]
	v_pk_mul_f32 v[220:221], v[228:229], v[0:1]
	v_pk_mul_f32 v[222:223], v[230:231], v[0:1]
	v_cvt_pk_f32_fp8_sdwa v[224:225], v128 src0_sel:WORD_1
	v_cvt_pk_f32_fp8_sdwa v[226:227], v132 src0_sel:WORD_1
	v_cvt_pk_f32_fp8_sdwa v[228:229], v136 src0_sel:WORD_1
	v_cvt_pk_f32_fp8_sdwa v[230:231], v140 src0_sel:WORD_1
	v_pk_fma_f32 v[216:217], v[224:225], v[2:3], v[216:217]
	v_pk_fma_f32 v[218:219], v[226:227], v[2:3], v[218:219]
	v_pk_fma_f32 v[220:221], v[228:229], v[2:3], v[220:221]
	v_pk_fma_f32 v[222:223], v[230:231], v[2:3], v[222:223]
	v_cvt_pk_f32_fp8_e32 v[224:225], v129
	v_cvt_pk_f32_fp8_e32 v[226:227], v133
	v_cvt_pk_f32_fp8_e32 v[228:229], v137
	v_cvt_pk_f32_fp8_e32 v[230:231], v141
	v_pk_fma_f32 v[216:217], v[224:225], v[4:5], v[216:217]
	v_pk_fma_f32 v[218:219], v[226:227], v[4:5], v[218:219]
	v_pk_fma_f32 v[220:221], v[228:229], v[4:5], v[220:221]
	v_pk_fma_f32 v[222:223], v[230:231], v[4:5], v[222:223]
	v_cvt_pk_f32_fp8_sdwa v[224:225], v129 src0_sel:WORD_1
	v_cvt_pk_f32_fp8_sdwa v[226:227], v133 src0_sel:WORD_1
	v_cvt_pk_f32_fp8_sdwa v[228:229], v137 src0_sel:WORD_1
	v_cvt_pk_f32_fp8_sdwa v[230:231], v141 src0_sel:WORD_1
	v_pk_fma_f32 v[216:217], v[224:225], v[6:7], v[216:217]
	v_pk_fma_f32 v[218:219], v[226:227], v[6:7], v[218:219]
	v_pk_fma_f32 v[220:221], v[228:229], v[6:7], v[220:221]
	v_pk_fma_f32 v[222:223], v[230:231], v[6:7], v[222:223]
	v_cvt_pk_f32_fp8_e32 v[224:225], v130
	v_cvt_pk_f32_fp8_e32 v[226:227], v134
	v_cvt_pk_f32_fp8_e32 v[228:229], v138
	v_cvt_pk_f32_fp8_e32 v[230:231], v142
	v_pk_fma_f32 v[216:217], v[224:225], v[8:9], v[216:217]
	v_pk_fma_f32 v[218:219], v[226:227], v[8:9], v[218:219]
	v_pk_fma_f32 v[220:221], v[228:229], v[8:9], v[220:221]
	v_pk_fma_f32 v[222:223], v[230:231], v[8:9], v[222:223]
	v_cvt_pk_f32_fp8_sdwa v[224:225], v130 src0_sel:WORD_1
	v_cvt_pk_f32_fp8_sdwa v[226:227], v134 src0_sel:WORD_1
	v_cvt_pk_f32_fp8_sdwa v[228:229], v138 src0_sel:WORD_1
	v_cvt_pk_f32_fp8_sdwa v[230:231], v142 src0_sel:WORD_1
	v_pk_fma_f32 v[216:217], v[224:225], v[10:11], v[216:217]
	v_pk_fma_f32 v[218:219], v[226:227], v[10:11], v[218:219]
	v_pk_fma_f32 v[220:221], v[228:229], v[10:11], v[220:221]
	v_pk_fma_f32 v[222:223], v[230:231], v[10:11], v[222:223]
	v_cvt_pk_f32_fp8_e32 v[224:225], v131
	v_cvt_pk_f32_fp8_e32 v[226:227], v135
	v_cvt_pk_f32_fp8_e32 v[228:229], v139
	v_cvt_pk_f32_fp8_e32 v[230:231], v143
	v_pk_fma_f32 v[216:217], v[224:225], v[12:13], v[216:217]
	v_pk_fma_f32 v[218:219], v[226:227], v[12:13], v[218:219]
	v_pk_fma_f32 v[220:221], v[228:229], v[12:13], v[220:221]
	v_pk_fma_f32 v[222:223], v[230:231], v[12:13], v[222:223]
	v_cvt_pk_f32_fp8_sdwa v[224:225], v131 src0_sel:WORD_1
	v_cvt_pk_f32_fp8_sdwa v[226:227], v135 src0_sel:WORD_1
	v_cvt_pk_f32_fp8_sdwa v[228:229], v139 src0_sel:WORD_1
	v_cvt_pk_f32_fp8_sdwa v[230:231], v143 src0_sel:WORD_1
	v_pk_fma_f32 v[216:217], v[224:225], v[14:15], v[216:217]
	v_pk_fma_f32 v[218:219], v[226:227], v[14:15], v[218:219]
	v_pk_fma_f32 v[220:221], v[228:229], v[14:15], v[220:221]
	v_pk_fma_f32 v[222:223], v[230:231], v[14:15], v[222:223]
	v_add_f32_e32 v192, v216, v217
	v_add_f32_e32 v193, v218, v219
	v_add_f32_e32 v194, v220, v221
	v_add_f32_e32 v195, v222, v223
	s_sub_i32 s90, s90, 1
	s_cmp_eq_u32 s90, 0
	s_cbranch_scc1 .LU_sw1
.LU_t0_s1:
	s_waitcnt lgkmcnt(0)
	buffer_load_dwordx4 v[128:131], v[232:233], s[56:59], 0 idxen offen
	buffer_load_dwordx4 v[132:135], v[234:235], s[56:59], 0 idxen offen
	buffer_load_dwordx4 v[136:139], v[236:237], s[56:59], 0 idxen offen
	buffer_load_dwordx4 v[140:143], v[238:239], s[56:59], 0 idxen offen
	ds_read_b32 v232, v213 offset:80
	ds_read_b32 v234, v213 offset:84
	ds_read_b32 v236, v213 offset:88
	ds_read_b32 v238, v213 offset:92
	s_waitcnt vmcnt(12)
	v_cvt_pk_f32_fp8_e32 v[224:225], v144
	v_cvt_pk_f32_fp8_e32 v[226:227], v148
	v_cvt_pk_f32_fp8_e32 v[228:229], v152
	v_cvt_pk_f32_fp8_e32 v[230:231], v156
	v_pk_mul_f32 v[216:217], v[224:225], v[0:1]
	v_pk_mul_f32 v[218:219], v[226:227], v[0:1]
	v_pk_mul_f32 v[220:221], v[228:229], v[0:1]
	v_pk_mul_f32 v[222:223], v[230:231], v[0:1]
	v_cvt_pk_f32_fp8_sdwa v[224:225], v144 src0_sel:WORD_1
	v_cvt_pk_f32_fp8_sdwa v[226:227], v148 src0_sel:WORD_1
	v_cvt_pk_f32_fp8_sdwa v[228:229], v152 src0_sel:WORD_1
	v_cvt_pk_f32_fp8_sdwa v[230:231], v156 src0_sel:WORD_1
	v_pk_fma_f32 v[216:217], v[224:225], v[2:3], v[216:217]
	v_pk_fma_f32 v[218:219], v[226:227], v[2:3], v[218:219]
	v_pk_fma_f32 v[220:221], v[228:229], v[2:3], v[220:221]
	v_pk_fma_f32 v[222:223], v[230:231], v[2:3], v[222:223]
	v_cvt_pk_f32_fp8_e32 v[224:225], v145
	v_cvt_pk_f32_fp8_e32 v[226:227], v149
	v_cvt_pk_f32_fp8_e32 v[228:229], v153
	v_cvt_pk_f32_fp8_e32 v[230:231], v157
	v_pk_fma_f32 v[216:217], v[224:225], v[4:5], v[216:217]
	v_pk_fma_f32 v[218:219], v[226:227], v[4:5], v[218:219]
	v_pk_fma_f32 v[220:221], v[228:229], v[4:5], v[220:221]
	v_pk_fma_f32 v[222:223], v[230:231], v[4:5], v[222:223]
	v_cvt_pk_f32_fp8_sdwa v[224:225], v145 src0_sel:WORD_1
	v_cvt_pk_f32_fp8_sdwa v[226:227], v149 src0_sel:WORD_1
	v_cvt_pk_f32_fp8_sdwa v[228:229], v153 src0_sel:WORD_1
	v_cvt_pk_f32_fp8_sdwa v[230:231], v157 src0_sel:WORD_1
	v_pk_fma_f32 v[216:217], v[224:225], v[6:7], v[216:217]
	v_pk_fma_f32 v[218:219], v[226:227], v[6:7], v[218:219]
	v_pk_fma_f32 v[220:221], v[228:229], v[6:7], v[220:221]
	v_pk_fma_f32 v[222:223], v[230:231], v[6:7], v[222:223]
	v_cvt_pk_f32_fp8_e32 v[224:225], v146
	v_cvt_pk_f32_fp8_e32 v[226:227], v150
	v_cvt_pk_f32_fp8_e32 v[228:229], v154
	v_cvt_pk_f32_fp8_e32 v[230:231], v158
	v_pk_fma_f32 v[216:217], v[224:225], v[8:9], v[216:217]
	v_pk_fma_f32 v[218:219], v[226:227], v[8:9], v[218:219]
	v_pk_fma_f32 v[220:221], v[228:229], v[8:9], v[220:221]
	v_pk_fma_f32 v[222:223], v[230:231], v[8:9], v[222:223]
	v_cvt_pk_f32_fp8_sdwa v[224:225], v146 src0_sel:WORD_1
	v_cvt_pk_f32_fp8_sdwa v[226:227], v150 src0_sel:WORD_1
	v_cvt_pk_f32_fp8_sdwa v[228:229], v154 src0_sel:WORD_1
	v_cvt_pk_f32_fp8_sdwa v[230:231], v158 src0_sel:WORD_1
	v_pk_fma_f32 v[216:217], v[224:225], v[10:11], v[216:217]
	v_pk_fma_f32 v[218:219], v[226:227], v[10:11], v[218:219]
	v_pk_fma_f32 v[220:221], v[228:229], v[10:11], v[220:221]
	v_pk_fma_f32 v[222:223], v[230:231], v[10:11], v[222:223]
	v_cvt_pk_f32_fp8_e32 v[224:225], v147
	v_cvt_pk_f32_fp8_e32 v[226:227], v151
	v_cvt_pk_f32_fp8_e32 v[228:229], v155
	v_cvt_pk_f32_fp8_e32 v[230:231], v159
	v_pk_fma_f32 v[216:217], v[224:225], v[12:13], v[216:217]
	v_pk_fma_f32 v[218:219], v[226:227], v[12:13], v[218:219]
	v_pk_fma_f32 v[220:221], v[228:229], v[12:13], v[220:221]
	v_pk_fma_f32 v[222:223], v[230:231], v[12:13], v[222:223]
	v_cvt_pk_f32_fp8_sdwa v[224:225], v147 src0_sel:WORD_1
	v_cvt_pk_f32_fp8_sdwa v[226:227], v151 src0_sel:WORD_1
	v_cvt_pk_f32_fp8_sdwa v[228:229], v155 src0_sel:WORD_1
	v_cvt_pk_f32_fp8_sdwa v[230:231], v159 src0_sel:WORD_1
	v_pk_fma_f32 v[216:217], v[224:225], v[14:15], v[216:217]
	v_pk_fma_f32 v[218:219], v[226:227], v[14:15], v[218:219]
	v_pk_fma_f32 v[220:221], v[228:229], v[14:15], v[220:221]
	v_pk_fma_f32 v[222:223], v[230:231], v[14:15], v[222:223]
	v_add_f32_e32 v196, v216, v217
	v_add_f32_e32 v197, v218, v219
	v_add_f32_e32 v198, v220, v221
	v_add_f32_e32 v199, v222, v223
	s_sub_i32 s90, s90, 1
	s_cmp_eq_u32 s90, 0
	s_cbranch_scc1 .LU_sw2
.LU_t0_s2:
	s_waitcnt lgkmcnt(0)
	buffer_load_dwordx4 v[144:147], v[232:233], s[56:59], 0 idxen offen
	buffer_load_dwordx4 v[148:151], v[234:235], s[56:59], 0 idxen offen
	buffer_load_dwordx4 v[152:155], v[236:237], s[56:59], 0 idxen offen
	buffer_load_dwordx4 v[156:159], v[238:239], s[56:59], 0 idxen offen
	ds_read_b32 v232, v213 offset:96
	ds_read_b32 v234, v213 offset:100
	ds_read_b32 v236, v213 offset:104
	ds_read_b32 v238, v213 offset:108
	s_waitcnt vmcnt(12)
	v_cvt_pk_f32_fp8_e32 v[224:225], v160
	v_cvt_pk_f32_fp8_e32 v[226:227], v164
	v_cvt_pk_f32_fp8_e32 v[228:229], v168
	v_cvt_pk_f32_fp8_e32 v[230:231], v172
	v_pk_mul_f32 v[216:217], v[224:225], v[0:1]
	v_pk_mul_f32 v[218:219], v[226:227], v[0:1]
	v_pk_mul_f32 v[220:221], v[228:229], v[0:1]
	v_pk_mul_f32 v[222:223], v[230:231], v[0:1]
	v_cvt_pk_f32_fp8_sdwa v[224:225], v160 src0_sel:WORD_1
	v_cvt_pk_f32_fp8_sdwa v[226:227], v164 src0_sel:WORD_1
	v_cvt_pk_f32_fp8_sdwa v[228:229], v168 src0_sel:WORD_1
	v_cvt_pk_f32_fp8_sdwa v[230:231], v172 src0_sel:WORD_1
	v_pk_fma_f32 v[216:217], v[224:225], v[2:3], v[216:217]
	v_pk_fma_f32 v[218:219], v[226:227], v[2:3], v[218:219]
	v_pk_fma_f32 v[220:221], v[228:229], v[2:3], v[220:221]
	v_pk_fma_f32 v[222:223], v[230:231], v[2:3], v[222:223]
	v_cvt_pk_f32_fp8_e32 v[224:225], v161
	v_cvt_pk_f32_fp8_e32 v[226:227], v165
	v_cvt_pk_f32_fp8_e32 v[228:229], v169
	v_cvt_pk_f32_fp8_e32 v[230:231], v173
	v_pk_fma_f32 v[216:217], v[224:225], v[4:5], v[216:217]
	v_pk_fma_f32 v[218:219], v[226:227], v[4:5], v[218:219]
	v_pk_fma_f32 v[220:221], v[228:229], v[4:5], v[220:221]
	v_pk_fma_f32 v[222:223], v[230:231], v[4:5], v[222:223]
	v_cvt_pk_f32_fp8_sdwa v[224:225], v161 src0_sel:WORD_1
	v_cvt_pk_f32_fp8_sdwa v[226:227], v165 src0_sel:WORD_1
	v_cvt_pk_f32_fp8_sdwa v[228:229], v169 src0_sel:WORD_1
	v_cvt_pk_f32_fp8_sdwa v[230:231], v173 src0_sel:WORD_1
	v_pk_fma_f32 v[216:217], v[224:225], v[6:7], v[216:217]
	v_pk_fma_f32 v[218:219], v[226:227], v[6:7], v[218:219]
	v_pk_fma_f32 v[220:221], v[228:229], v[6:7], v[220:221]
	v_pk_fma_f32 v[222:223], v[230:231], v[6:7], v[222:223]
	v_cvt_pk_f32_fp8_e32 v[224:225], v162
	v_cvt_pk_f32_fp8_e32 v[226:227], v166
	v_cvt_pk_f32_fp8_e32 v[228:229], v170
	v_cvt_pk_f32_fp8_e32 v[230:231], v174
	v_pk_fma_f32 v[216:217], v[224:225], v[8:9], v[216:217]
	v_pk_fma_f32 v[218:219], v[226:227], v[8:9], v[218:219]
	v_pk_fma_f32 v[220:221], v[228:229], v[8:9], v[220:221]
	v_pk_fma_f32 v[222:223], v[230:231], v[8:9], v[222:223]
	v_cvt_pk_f32_fp8_sdwa v[224:225], v162 src0_sel:WORD_1
	v_cvt_pk_f32_fp8_sdwa v[226:227], v166 src0_sel:WORD_1
	v_cvt_pk_f32_fp8_sdwa v[228:229], v170 src0_sel:WORD_1
	v_cvt_pk_f32_fp8_sdwa v[230:231], v174 src0_sel:WORD_1
	v_pk_fma_f32 v[216:217], v[224:225], v[10:11], v[216:217]
	v_pk_fma_f32 v[218:219], v[226:227], v[10:11], v[218:219]
	v_pk_fma_f32 v[220:221], v[228:229], v[10:11], v[220:221]
	v_pk_fma_f32 v[222:223], v[230:231], v[10:11], v[222:223]
	v_cvt_pk_f32_fp8_e32 v[224:225], v163
	v_cvt_pk_f32_fp8_e32 v[226:227], v167
	v_cvt_pk_f32_fp8_e32 v[228:229], v171
	v_cvt_pk_f32_fp8_e32 v[230:231], v175
	v_pk_fma_f32 v[216:217], v[224:225], v[12:13], v[216:217]
	v_pk_fma_f32 v[218:219], v[226:227], v[12:13], v[218:219]
	v_pk_fma_f32 v[220:221], v[228:229], v[12:13], v[220:221]
	v_pk_fma_f32 v[222:223], v[230:231], v[12:13], v[222:223]
	v_cvt_pk_f32_fp8_sdwa v[224:225], v163 src0_sel:WORD_1
	v_cvt_pk_f32_fp8_sdwa v[226:227], v167 src0_sel:WORD_1
	v_cvt_pk_f32_fp8_sdwa v[228:229], v171 src0_sel:WORD_1
	v_cvt_pk_f32_fp8_sdwa v[230:231], v175 src0_sel:WORD_1
	v_pk_fma_f32 v[216:217], v[224:225], v[14:15], v[216:217]
	v_pk_fma_f32 v[218:219], v[226:227], v[14:15], v[218:219]
	v_pk_fma_f32 v[220:221], v[228:229], v[14:15], v[220:221]
	v_pk_fma_f32 v[222:223], v[230:231], v[14:15], v[222:223]
	v_add_f32_e32 v200, v216, v217
	v_add_f32_e32 v201, v218, v219
	v_add_f32_e32 v202, v220, v221
	v_add_f32_e32 v203, v222, v223
	s_sub_i32 s90, s90, 1
	s_cmp_eq_u32 s90, 0
	s_cbranch_scc1 .LU_sw3
.LU_t0_s3:
	s_waitcnt lgkmcnt(0)
	buffer_load_dwordx4 v[160:163], v[232:233], s[56:59], 0 idxen offen
	buffer_load_dwordx4 v[164:167], v[234:235], s[56:59], 0 idxen offen
	buffer_load_dwordx4 v[168:171], v[236:237], s[56:59], 0 idxen offen
	buffer_load_dwordx4 v[172:175], v[238:239], s[56:59], 0 idxen offen
	ds_read_b32 v232, v213 offset:112
	ds_read_b32 v234, v213 offset:116
	ds_read_b32 v236, v213 offset:120
	ds_read_b32 v238, v213 offset:124
	s_waitcnt vmcnt(12)
	v_cvt_pk_f32_fp8_e32 v[224:225], v176
	v_cvt_pk_f32_fp8_e32 v[226:227], v180
	v_cvt_pk_f32_fp8_e32 v[228:229], v184
	v_cvt_pk_f32_fp8_e32 v[230:231], v188
	v_pk_mul_f32 v[216:217], v[224:225], v[0:1]
	v_pk_mul_f32 v[218:219], v[226:227], v[0:1]
	v_pk_mul_f32 v[220:221], v[228:229], v[0:1]
	v_pk_mul_f32 v[222:223], v[230:231], v[0:1]
	v_cvt_pk_f32_fp8_sdwa v[224:225], v176 src0_sel:WORD_1
	v_cvt_pk_f32_fp8_sdwa v[226:227], v180 src0_sel:WORD_1
	v_cvt_pk_f32_fp8_sdwa v[228:229], v184 src0_sel:WORD_1
	v_cvt_pk_f32_fp8_sdwa v[230:231], v188 src0_sel:WORD_1
	v_pk_fma_f32 v[216:217], v[224:225], v[2:3], v[216:217]
	v_pk_fma_f32 v[218:219], v[226:227], v[2:3], v[218:219]
	v_pk_fma_f32 v[220:221], v[228:229], v[2:3], v[220:221]
	v_pk_fma_f32 v[222:223], v[230:231], v[2:3], v[222:223]
	v_cvt_pk_f32_fp8_e32 v[224:225], v177
	v_cvt_pk_f32_fp8_e32 v[226:227], v181
	v_cvt_pk_f32_fp8_e32 v[228:229], v185
	v_cvt_pk_f32_fp8_e32 v[230:231], v189
	v_pk_fma_f32 v[216:217], v[224:225], v[4:5], v[216:217]
	v_pk_fma_f32 v[218:219], v[226:227], v[4:5], v[218:219]
	v_pk_fma_f32 v[220:221], v[228:229], v[4:5], v[220:221]
	v_pk_fma_f32 v[222:223], v[230:231], v[4:5], v[222:223]
	v_cvt_pk_f32_fp8_sdwa v[224:225], v177 src0_sel:WORD_1
	v_cvt_pk_f32_fp8_sdwa v[226:227], v181 src0_sel:WORD_1
	v_cvt_pk_f32_fp8_sdwa v[228:229], v185 src0_sel:WORD_1
	v_cvt_pk_f32_fp8_sdwa v[230:231], v189 src0_sel:WORD_1
	v_pk_fma_f32 v[216:217], v[224:225], v[6:7], v[216:217]
	v_pk_fma_f32 v[218:219], v[226:227], v[6:7], v[218:219]
	v_pk_fma_f32 v[220:221], v[228:229], v[6:7], v[220:221]
	v_pk_fma_f32 v[222:223], v[230:231], v[6:7], v[222:223]
	v_cvt_pk_f32_fp8_e32 v[224:225], v178
	v_cvt_pk_f32_fp8_e32 v[226:227], v182
	v_cvt_pk_f32_fp8_e32 v[228:229], v186
	v_cvt_pk_f32_fp8_e32 v[230:231], v190
	v_pk_fma_f32 v[216:217], v[224:225], v[8:9], v[216:217]
	v_pk_fma_f32 v[218:219], v[226:227], v[8:9], v[218:219]
	v_pk_fma_f32 v[220:221], v[228:229], v[8:9], v[220:221]
	v_pk_fma_f32 v[222:223], v[230:231], v[8:9], v[222:223]
	v_cvt_pk_f32_fp8_sdwa v[224:225], v178 src0_sel:WORD_1
	v_cvt_pk_f32_fp8_sdwa v[226:227], v182 src0_sel:WORD_1
	v_cvt_pk_f32_fp8_sdwa v[228:229], v186 src0_sel:WORD_1
	v_cvt_pk_f32_fp8_sdwa v[230:231], v190 src0_sel:WORD_1
	v_pk_fma_f32 v[216:217], v[224:225], v[10:11], v[216:217]
	v_pk_fma_f32 v[218:219], v[226:227], v[10:11], v[218:219]
	v_pk_fma_f32 v[220:221], v[228:229], v[10:11], v[220:221]
	v_pk_fma_f32 v[222:223], v[230:231], v[10:11], v[222:223]
	v_cvt_pk_f32_fp8_e32 v[224:225], v179
	v_cvt_pk_f32_fp8_e32 v[226:227], v183
	v_cvt_pk_f32_fp8_e32 v[228:229], v187
	v_cvt_pk_f32_fp8_e32 v[230:231], v191
	v_pk_fma_f32 v[216:217], v[224:225], v[12:13], v[216:217]
	v_pk_fma_f32 v[218:219], v[226:227], v[12:13], v[218:219]
	v_pk_fma_f32 v[220:221], v[228:229], v[12:13], v[220:221]
	v_pk_fma_f32 v[222:223], v[230:231], v[12:13], v[222:223]
	v_cvt_pk_f32_fp8_sdwa v[224:225], v179 src0_sel:WORD_1
	v_cvt_pk_f32_fp8_sdwa v[226:227], v183 src0_sel:WORD_1
	v_cvt_pk_f32_fp8_sdwa v[228:229], v187 src0_sel:WORD_1
	v_cvt_pk_f32_fp8_sdwa v[230:231], v191 src0_sel:WORD_1
	v_pk_fma_f32 v[216:217], v[224:225], v[14:15], v[216:217]
	v_pk_fma_f32 v[218:219], v[226:227], v[14:15], v[218:219]
	v_pk_fma_f32 v[220:221], v[228:229], v[14:15], v[220:221]
	v_pk_fma_f32 v[222:223], v[230:231], v[14:15], v[222:223]
; __device__ __forceinline__ float gelu_fast(float v) {
;     const float av = fabsf(v), tt = __builtin_amdgcn_rcpf(av * 0.2316418882f + 1.0f);
;     float q = tt * 0.5307027145f + (-0.7265760135f); q = q * tt + 0.7107068705f; q = q * tt + (-0.142248368f); q = q * tt + 0.127414796f; q = q * tt;
;     const float e = __builtin_amdgcn_exp2f((v * v) * (-0.72134752044f));
;     const float m = v * (q * e);
;     return v < 0.f ? m : v - m;
; }
	v_add_f32_e32 v204, v216, v217
	v_add_f32_e32 v205, v218, v219
	v_add_f32_e32 v206, v220, v221
	v_add_f32_e32 v207, v222, v223
	s_nop 0
	v_permlane32_swap_b32_e32 v192, v200
	v_permlane32_swap_b32_e32 v193, v201
	v_permlane32_swap_b32_e32 v194, v202
	v_permlane32_swap_b32_e32 v195, v203
	v_permlane32_swap_b32_e32 v196, v204
	v_permlane32_swap_b32_e32 v197, v205
	v_permlane32_swap_b32_e32 v198, v206
	v_permlane32_swap_b32_e32 v199, v207
	v_add_f32_e32 v192, v192, v200
	v_add_f32_e32 v193, v193, v201
	v_add_f32_e32 v194, v194, v202
	v_add_f32_e32 v195, v195, v203
	v_add_f32_e32 v196, v196, v204
	v_add_f32_e32 v197, v197, v205
	v_add_f32_e32 v198, v198, v206
	v_add_f32_e32 v199, v199, v207
	v_permlane16_swap_b32_e32 v192, v196
	v_permlane16_swap_b32_e32 v193, v197
	v_permlane16_swap_b32_e32 v194, v198
	v_permlane16_swap_b32_e32 v195, v199
	v_add_f32_e32 v192, v192, v196
	v_add_f32_e32 v193, v193, v197
	v_add_f32_e32 v194, v194, v198
	v_add_f32_e32 v195, v195, v199
	v_add_f32_dpp v216, v192, v192 row_ror:8 row_mask:0xf bank_mask:0xf
	v_add_f32_dpp v218, v194, v194 row_ror:8 row_mask:0xf bank_mask:0xf
	v_add_f32_dpp v216, v193, v193 row_ror:8 row_mask:0xf bank_mask:0xc
	v_add_f32_dpp v218, v195, v195 row_ror:8 row_mask:0xf bank_mask:0xc
	s_nop 1
	v_add_f32_dpp v220, v216, v216 row_half_mirror row_mask:0xf bank_mask:0xf
	v_add_f32_dpp v220, v218, v218 row_half_mirror row_mask:0xf bank_mask:0xa
	s_nop 1
	v_add_f32_dpp v220, v220, v220 quad_perm:[1,0,3,2] row_mask:0xf bank_mask:0xf
	s_nop 1
	v_add_f32_dpp v220, v220, v220 quad_perm:[2,3,0,1] row_mask:0xf bank_mask:0xf
	v_mul_f32_e32 v216, v252, v220
	v_fma_f32 v218, |v216|, s72, 1.0
	v_mul_f32_e32 v222, v216, v216
	v_rcp_f32_e32 v218, v218
	v_mul_f32_e32 v222, 0xbf38aa3b, v222
	v_exp_f32_e32 v222, v222
	v_fmamk_f32 v224, v218, 0x3f07dc22, v242
	v_fmaak_f32 v224, v218, v224, 0x3f35f0e3
	v_fmaak_f32 v224, v218, v224, 0xbe11a98e
	v_fmaak_f32 v224, v218, v224, 0x3e027906
	v_mul_f32_e32 v224, v218, v224
	v_mul_f32_e32 v224, v222, v224
	v_mul_f32_e32 v226, v216, v224
	v_fma_f32 v224, -v216, v224, v216
	v_cmp_gt_f32_e32 vcc, 0, v216
	s_nop 1
	v_cndmask_b32_e32 v224, v224, v226, vcc
	v_mul_f32_e32 v224, v249, v224
	v_mul_f32_e32 v224, v253, v224
	ds_write_b32 v211, v224 offset:4992
	v_add_u32_e32 v211, 64, v211
	v_add_u32_e32 v213, 64, v213
	v_add_u32_e32 v250, 64, v250
	ds_read_b32 v252, v250
	ds_read_b32 v253, v250 offset:4096
	ds_read_b32 v249, v211 offset:4992
	s_add_i32 s21, s21, 4
	s_sub_i32 s90, s90, 1
	s_cmp_eq_u32 s90, 0
	s_cbranch_scc1 .LU_sw0
	s_branch .LU_t0_s0
.LU_t1_s0:
	s_cmp_ge_u32 s21, s20
	s_cbranch_scc1 .LU_done
	s_waitcnt lgkmcnt(0)
	buffer_load_dwordx4 v[176:179], v[232:233], s[56:59], 0 idxen offen
	buffer_load_dwordx4 v[180:183], v[234:235], s[56:59], 0 idxen offen
	buffer_load_dwordx4 v[184:187], v[236:237], s[56:59], 0 idxen offen
	buffer_load_dwordx4 v[188:191], v[238:239], s[56:59], 0 idxen offen
	ds_read_b32 v232, v213 offset:64
	ds_read_b32 v234, v213 offset:68
	ds_read_b32 v236, v213 offset:72
	ds_read_b32 v238, v213 offset:76
	s_waitcnt vmcnt(12)
	v_cvt_pk_f32_fp8_e32 v[224:225], v128
	v_cvt_pk_f32_fp8_e32 v[226:227], v132
	v_cvt_pk_f32_fp8_e32 v[228:229], v136
	v_cvt_pk_f32_fp8_e32 v[230:231], v140
	v_pk_mul_f32 v[216:217], v[224:225], v[16:17]
	v_pk_mul_f32 v[218:219], v[226:227], v[16:17]
	v_pk_mul_f32 v[220:221], v[228:229], v[16:17]
	v_pk_mul_f32 v[222:223], v[230:231], v[16:17]
	v_cvt_pk_f32_fp8_sdwa v[224:225], v128 src0_sel:WORD_1
	v_cvt_pk_f32_fp8_sdwa v[226:227], v132 src0_sel:WORD_1
	v_cvt_pk_f32_fp8_sdwa v[228:229], v136 src0_sel:WORD_1
	v_cvt_pk_f32_fp8_sdwa v[230:231], v140 src0_sel:WORD_1
	v_pk_fma_f32 v[216:217], v[224:225], v[18:19], v[216:217]
	v_pk_fma_f32 v[218:219], v[226:227], v[18:19], v[218:219]
	v_pk_fma_f32 v[220:221], v[228:229], v[18:19], v[220:221]
	v_pk_fma_f32 v[222:223], v[230:231], v[18:19], v[222:223]
	v_cvt_pk_f32_fp8_e32 v[224:225], v129
	v_cvt_pk_f32_fp8_e32 v[226:227], v133
	v_cvt_pk_f32_fp8_e32 v[228:229], v137
	v_cvt_pk_f32_fp8_e32 v[230:231], v141
	v_pk_fma_f32 v[216:217], v[224:225], v[20:21], v[216:217]
	v_pk_fma_f32 v[218:219], v[226:227], v[20:21], v[218:219]
	v_pk_fma_f32 v[220:221], v[228:229], v[20:21], v[220:221]
	v_pk_fma_f32 v[222:223], v[230:231], v[20:21], v[222:223]
	v_cvt_pk_f32_fp8_sdwa v[224:225], v129 src0_sel:WORD_1
	v_cvt_pk_f32_fp8_sdwa v[226:227], v133 src0_sel:WORD_1
	v_cvt_pk_f32_fp8_sdwa v[228:229], v137 src0_sel:WORD_1
	v_cvt_pk_f32_fp8_sdwa v[230:231], v141 src0_sel:WORD_1
	v_pk_fma_f32 v[216:217], v[224:225], v[22:23], v[216:217]
	v_pk_fma_f32 v[218:219], v[226:227], v[22:23], v[218:219]
	v_pk_fma_f32 v[220:221], v[228:229], v[22:23], v[220:221]
	v_pk_fma_f32 v[222:223], v[230:231], v[22:23], v[222:223]
	v_cvt_pk_f32_fp8_e32 v[224:225], v130
	v_cvt_pk_f32_fp8_e32 v[226:227], v134
	v_cvt_pk_f32_fp8_e32 v[228:229], v138
	v_cvt_pk_f32_fp8_e32 v[230:231], v142
	v_pk_fma_f32 v[216:217], v[224:225], v[24:25], v[216:217]
	v_pk_fma_f32 v[218:219], v[226:227], v[24:25], v[218:219]
	v_pk_fma_f32 v[220:221], v[228:229], v[24:25], v[220:221]
	v_pk_fma_f32 v[222:223], v[230:231], v[24:25], v[222:223]
	v_cvt_pk_f32_fp8_sdwa v[224:225], v130 src0_sel:WORD_1
	v_cvt_pk_f32_fp8_sdwa v[226:227], v134 src0_sel:WORD_1
	v_cvt_pk_f32_fp8_sdwa v[228:229], v138 src0_sel:WORD_1
	v_cvt_pk_f32_fp8_sdwa v[230:231], v142 src0_sel:WORD_1
	v_pk_fma_f32 v[216:217], v[224:225], v[26:27], v[216:217]
	v_pk_fma_f32 v[218:219], v[226:227], v[26:27], v[218:219]
	v_pk_fma_f32 v[220:221], v[228:229], v[26:27], v[220:221]
	v_pk_fma_f32 v[222:223], v[230:231], v[26:27], v[222:223]
	v_cvt_pk_f32_fp8_e32 v[224:225], v131
	v_cvt_pk_f32_fp8_e32 v[226:227], v135
	v_cvt_pk_f32_fp8_e32 v[228:229], v139
	v_cvt_pk_f32_fp8_e32 v[230:231], v143
	v_pk_fma_f32 v[216:217], v[224:225], v[28:29], v[216:217]
	v_pk_fma_f32 v[218:219], v[226:227], v[28:29], v[218:219]
	v_pk_fma_f32 v[220:221], v[228:229], v[28:29], v[220:221]
	v_pk_fma_f32 v[222:223], v[230:231], v[28:29], v[222:223]
	v_cvt_pk_f32_fp8_sdwa v[224:225], v131 src0_sel:WORD_1
	v_cvt_pk_f32_fp8_sdwa v[226:227], v135 src0_sel:WORD_1
	v_cvt_pk_f32_fp8_sdwa v[228:229], v139 src0_sel:WORD_1
	v_cvt_pk_f32_fp8_sdwa v[230:231], v143 src0_sel:WORD_1
	v_pk_fma_f32 v[216:217], v[224:225], v[30:31], v[216:217]
	v_pk_fma_f32 v[218:219], v[226:227], v[30:31], v[218:219]
	v_pk_fma_f32 v[220:221], v[228:229], v[30:31], v[220:221]
	v_pk_fma_f32 v[222:223], v[230:231], v[30:31], v[222:223]
	v_add_f32_e32 v192, v216, v217
	v_add_f32_e32 v193, v218, v219
	v_add_f32_e32 v194, v220, v221
	v_add_f32_e32 v195, v222, v223
	s_sub_i32 s90, s90, 1
	s_cmp_eq_u32 s90, 0
	s_cbranch_scc1 .LU_sw1
.LU_t1_s1:
	s_waitcnt lgkmcnt(0)
	buffer_load_dwordx4 v[128:131], v[232:233], s[56:59], 0 idxen offen
	buffer_load_dwordx4 v[132:135], v[234:235], s[56:59], 0 idxen offen
	buffer_load_dwordx4 v[136:139], v[236:237], s[56:59], 0 idxen offen
	buffer_load_dwordx4 v[140:143], v[238:239], s[56:59], 0 idxen offen
	ds_read_b32 v232, v213 offset:80
	ds_read_b32 v234, v213 offset:84
	ds_read_b32 v236, v213 offset:88
	ds_read_b32 v238, v213 offset:92
	s_waitcnt vmcnt(12)
	v_cvt_pk_f32_fp8_e32 v[224:225], v144
	v_cvt_pk_f32_fp8_e32 v[226:227], v148
	v_cvt_pk_f32_fp8_e32 v[228:229], v152
	v_cvt_pk_f32_fp8_e32 v[230:231], v156
	v_pk_mul_f32 v[216:217], v[224:225], v[16:17]
	v_pk_mul_f32 v[218:219], v[226:227], v[16:17]
	v_pk_mul_f32 v[220:221], v[228:229], v[16:17]
	v_pk_mul_f32 v[222:223], v[230:231], v[16:17]
	v_cvt_pk_f32_fp8_sdwa v[224:225], v144 src0_sel:WORD_1
	v_cvt_pk_f32_fp8_sdwa v[226:227], v148 src0_sel:WORD_1
	v_cvt_pk_f32_fp8_sdwa v[228:229], v152 src0_sel:WORD_1
	v_cvt_pk_f32_fp8_sdwa v[230:231], v156 src0_sel:WORD_1
	v_pk_fma_f32 v[216:217], v[224:225], v[18:19], v[216:217]
	v_pk_fma_f32 v[218:219], v[226:227], v[18:19], v[218:219]
	v_pk_fma_f32 v[220:221], v[228:229], v[18:19], v[220:221]
	v_pk_fma_f32 v[222:223], v[230:231], v[18:19], v[222:223]
	v_cvt_pk_f32_fp8_e32 v[224:225], v145
	v_cvt_pk_f32_fp8_e32 v[226:227], v149
	v_cvt_pk_f32_fp8_e32 v[228:229], v153
	v_cvt_pk_f32_fp8_e32 v[230:231], v157
	v_pk_fma_f32 v[216:217], v[224:225], v[20:21], v[216:217]
	v_pk_fma_f32 v[218:219], v[226:227], v[20:21], v[218:219]
	v_pk_fma_f32 v[220:221], v[228:229], v[20:21], v[220:221]
	v_pk_fma_f32 v[222:223], v[230:231], v[20:21], v[222:223]
	v_cvt_pk_f32_fp8_sdwa v[224:225], v145 src0_sel:WORD_1
	v_cvt_pk_f32_fp8_sdwa v[226:227], v149 src0_sel:WORD_1
	v_cvt_pk_f32_fp8_sdwa v[228:229], v153 src0_sel:WORD_1
	v_cvt_pk_f32_fp8_sdwa v[230:231], v157 src0_sel:WORD_1
	v_pk_fma_f32 v[216:217], v[224:225], v[22:23], v[216:217]
	v_pk_fma_f32 v[218:219], v[226:227], v[22:23], v[218:219]
	v_pk_fma_f32 v[220:221], v[228:229], v[22:23], v[220:221]
	v_pk_fma_f32 v[222:223], v[230:231], v[22:23], v[222:223]
	v_cvt_pk_f32_fp8_e32 v[224:225], v146
	v_cvt_pk_f32_fp8_e32 v[226:227], v150
	v_cvt_pk_f32_fp8_e32 v[228:229], v154
	v_cvt_pk_f32_fp8_e32 v[230:231], v158
	v_pk_fma_f32 v[216:217], v[224:225], v[24:25], v[216:217]
	v_pk_fma_f32 v[218:219], v[226:227], v[24:25], v[218:219]
	v_pk_fma_f32 v[220:221], v[228:229], v[24:25], v[220:221]
	v_pk_fma_f32 v[222:223], v[230:231], v[24:25], v[222:223]
	v_cvt_pk_f32_fp8_sdwa v[224:225], v146 src0_sel:WORD_1
	v_cvt_pk_f32_fp8_sdwa v[226:227], v150 src0_sel:WORD_1
	v_cvt_pk_f32_fp8_sdwa v[228:229], v154 src0_sel:WORD_1
	v_cvt_pk_f32_fp8_sdwa v[230:231], v158 src0_sel:WORD_1
	v_pk_fma_f32 v[216:217], v[224:225], v[26:27], v[216:217]
	v_pk_fma_f32 v[218:219], v[226:227], v[26:27], v[218:219]
	v_pk_fma_f32 v[220:221], v[228:229], v[26:27], v[220:221]
	v_pk_fma_f32 v[222:223], v[230:231], v[26:27], v[222:223]
	v_cvt_pk_f32_fp8_e32 v[224:225], v147
	v_cvt_pk_f32_fp8_e32 v[226:227], v151
	v_cvt_pk_f32_fp8_e32 v[228:229], v155
	v_cvt_pk_f32_fp8_e32 v[230:231], v159
	v_pk_fma_f32 v[216:217], v[224:225], v[28:29], v[216:217]
	v_pk_fma_f32 v[218:219], v[226:227], v[28:29], v[218:219]
	v_pk_fma_f32 v[220:221], v[228:229], v[28:29], v[220:221]
	v_pk_fma_f32 v[222:223], v[230:231], v[28:29], v[222:223]
	v_cvt_pk_f32_fp8_sdwa v[224:225], v147 src0_sel:WORD_1
	v_cvt_pk_f32_fp8_sdwa v[226:227], v151 src0_sel:WORD_1
	v_cvt_pk_f32_fp8_sdwa v[228:229], v155 src0_sel:WORD_1
	v_cvt_pk_f32_fp8_sdwa v[230:231], v159 src0_sel:WORD_1
	v_pk_fma_f32 v[216:217], v[224:225], v[30:31], v[216:217]
	v_pk_fma_f32 v[218:219], v[226:227], v[30:31], v[218:219]
	v_pk_fma_f32 v[220:221], v[228:229], v[30:31], v[220:221]
	v_pk_fma_f32 v[222:223], v[230:231], v[30:31], v[222:223]
	v_add_f32_e32 v196, v216, v217
	v_add_f32_e32 v197, v218, v219
	v_add_f32_e32 v198, v220, v221
	v_add_f32_e32 v199, v222, v223
	s_sub_i32 s90, s90, 1
	s_cmp_eq_u32 s90, 0
	s_cbranch_scc1 .LU_sw2
.LU_t1_s2:
	s_waitcnt lgkmcnt(0)
	buffer_load_dwordx4 v[144:147], v[232:233], s[56:59], 0 idxen offen
	buffer_load_dwordx4 v[148:151], v[234:235], s[56:59], 0 idxen offen
	buffer_load_dwordx4 v[152:155], v[236:237], s[56:59], 0 idxen offen
	buffer_load_dwordx4 v[156:159], v[238:239], s[56:59], 0 idxen offen
	ds_read_b32 v232, v213 offset:96
	ds_read_b32 v234, v213 offset:100
	ds_read_b32 v236, v213 offset:104
	ds_read_b32 v238, v213 offset:108
	s_waitcnt vmcnt(12)
	v_cvt_pk_f32_fp8_e32 v[224:225], v160
	v_cvt_pk_f32_fp8_e32 v[226:227], v164
	v_cvt_pk_f32_fp8_e32 v[228:229], v168
	v_cvt_pk_f32_fp8_e32 v[230:231], v172
	v_pk_mul_f32 v[216:217], v[224:225], v[16:17]
	v_pk_mul_f32 v[218:219], v[226:227], v[16:17]
	v_pk_mul_f32 v[220:221], v[228:229], v[16:17]
	v_pk_mul_f32 v[222:223], v[230:231], v[16:17]
	v_cvt_pk_f32_fp8_sdwa v[224:225], v160 src0_sel:WORD_1
	v_cvt_pk_f32_fp8_sdwa v[226:227], v164 src0_sel:WORD_1
	v_cvt_pk_f32_fp8_sdwa v[228:229], v168 src0_sel:WORD_1
	v_cvt_pk_f32_fp8_sdwa v[230:231], v172 src0_sel:WORD_1
	v_pk_fma_f32 v[216:217], v[224:225], v[18:19], v[216:217]
	v_pk_fma_f32 v[218:219], v[226:227], v[18:19], v[218:219]
	v_pk_fma_f32 v[220:221], v[228:229], v[18:19], v[220:221]
	v_pk_fma_f32 v[222:223], v[230:231], v[18:19], v[222:223]
	v_cvt_pk_f32_fp8_e32 v[224:225], v161
	v_cvt_pk_f32_fp8_e32 v[226:227], v165
	v_cvt_pk_f32_fp8_e32 v[228:229], v169
	v_cvt_pk_f32_fp8_e32 v[230:231], v173
	v_pk_fma_f32 v[216:217], v[224:225], v[20:21], v[216:217]
	v_pk_fma_f32 v[218:219], v[226:227], v[20:21], v[218:219]
	v_pk_fma_f32 v[220:221], v[228:229], v[20:21], v[220:221]
	v_pk_fma_f32 v[222:223], v[230:231], v[20:21], v[222:223]
	v_cvt_pk_f32_fp8_sdwa v[224:225], v161 src0_sel:WORD_1
	v_cvt_pk_f32_fp8_sdwa v[226:227], v165 src0_sel:WORD_1
	v_cvt_pk_f32_fp8_sdwa v[228:229], v169 src0_sel:WORD_1
	v_cvt_pk_f32_fp8_sdwa v[230:231], v173 src0_sel:WORD_1
	v_pk_fma_f32 v[216:217], v[224:225], v[22:23], v[216:217]
	v_pk_fma_f32 v[218:219], v[226:227], v[22:23], v[218:219]
	v_pk_fma_f32 v[220:221], v[228:229], v[22:23], v[220:221]
	v_pk_fma_f32 v[222:223], v[230:231], v[22:23], v[222:223]
	v_cvt_pk_f32_fp8_e32 v[224:225], v162
	v_cvt_pk_f32_fp8_e32 v[226:227], v166
	v_cvt_pk_f32_fp8_e32 v[228:229], v170
	v_cvt_pk_f32_fp8_e32 v[230:231], v174
	v_pk_fma_f32 v[216:217], v[224:225], v[24:25], v[216:217]
	v_pk_fma_f32 v[218:219], v[226:227], v[24:25], v[218:219]
	v_pk_fma_f32 v[220:221], v[228:229], v[24:25], v[220:221]
	v_pk_fma_f32 v[222:223], v[230:231], v[24:25], v[222:223]
	v_cvt_pk_f32_fp8_sdwa v[224:225], v162 src0_sel:WORD_1
	v_cvt_pk_f32_fp8_sdwa v[226:227], v166 src0_sel:WORD_1
	v_cvt_pk_f32_fp8_sdwa v[228:229], v170 src0_sel:WORD_1
	v_cvt_pk_f32_fp8_sdwa v[230:231], v174 src0_sel:WORD_1
	v_pk_fma_f32 v[216:217], v[224:225], v[26:27], v[216:217]
	v_pk_fma_f32 v[218:219], v[226:227], v[26:27], v[218:219]
	v_pk_fma_f32 v[220:221], v[228:229], v[26:27], v[220:221]
	v_pk_fma_f32 v[222:223], v[230:231], v[26:27], v[222:223]
	v_cvt_pk_f32_fp8_e32 v[224:225], v163
	v_cvt_pk_f32_fp8_e32 v[226:227], v167
	v_cvt_pk_f32_fp8_e32 v[228:229], v171
	v_cvt_pk_f32_fp8_e32 v[230:231], v175
	v_pk_fma_f32 v[216:217], v[224:225], v[28:29], v[216:217]
	v_pk_fma_f32 v[218:219], v[226:227], v[28:29], v[218:219]
	v_pk_fma_f32 v[220:221], v[228:229], v[28:29], v[220:221]
	v_pk_fma_f32 v[222:223], v[230:231], v[28:29], v[222:223]
	v_cvt_pk_f32_fp8_sdwa v[224:225], v163 src0_sel:WORD_1
	v_cvt_pk_f32_fp8_sdwa v[226:227], v167 src0_sel:WORD_1
	v_cvt_pk_f32_fp8_sdwa v[228:229], v171 src0_sel:WORD_1
	v_cvt_pk_f32_fp8_sdwa v[230:231], v175 src0_sel:WORD_1
	v_pk_fma_f32 v[216:217], v[224:225], v[30:31], v[216:217]
	v_pk_fma_f32 v[218:219], v[226:227], v[30:31], v[218:219]
	v_pk_fma_f32 v[220:221], v[228:229], v[30:31], v[220:221]
	v_pk_fma_f32 v[222:223], v[230:231], v[30:31], v[222:223]
	v_add_f32_e32 v200, v216, v217
	v_add_f32_e32 v201, v218, v219
	v_add_f32_e32 v202, v220, v221
	v_add_f32_e32 v203, v222, v223
	s_sub_i32 s90, s90, 1
	s_cmp_eq_u32 s90, 0
	s_cbranch_scc1 .LU_sw3
.LU_t1_s3:
	s_waitcnt lgkmcnt(0)
	buffer_load_dwordx4 v[160:163], v[232:233], s[56:59], 0 idxen offen
	buffer_load_dwordx4 v[164:167], v[234:235], s[56:59], 0 idxen offen
	buffer_load_dwordx4 v[168:171], v[236:237], s[56:59], 0 idxen offen
	buffer_load_dwordx4 v[172:175], v[238:239], s[56:59], 0 idxen offen
	ds_read_b32 v232, v213 offset:112
	ds_read_b32 v234, v213 offset:116
	ds_read_b32 v236, v213 offset:120
	ds_read_b32 v238, v213 offset:124
	s_waitcnt vmcnt(12)
	v_cvt_pk_f32_fp8_e32 v[224:225], v176
	v_cvt_pk_f32_fp8_e32 v[226:227], v180
	v_cvt_pk_f32_fp8_e32 v[228:229], v184
	v_cvt_pk_f32_fp8_e32 v[230:231], v188
	v_pk_mul_f32 v[216:217], v[224:225], v[16:17]
	v_pk_mul_f32 v[218:219], v[226:227], v[16:17]
	v_pk_mul_f32 v[220:221], v[228:229], v[16:17]
	v_pk_mul_f32 v[222:223], v[230:231], v[16:17]
	v_cvt_pk_f32_fp8_sdwa v[224:225], v176 src0_sel:WORD_1
	v_cvt_pk_f32_fp8_sdwa v[226:227], v180 src0_sel:WORD_1
	v_cvt_pk_f32_fp8_sdwa v[228:229], v184 src0_sel:WORD_1
	v_cvt_pk_f32_fp8_sdwa v[230:231], v188 src0_sel:WORD_1
	v_pk_fma_f32 v[216:217], v[224:225], v[18:19], v[216:217]
	v_pk_fma_f32 v[218:219], v[226:227], v[18:19], v[218:219]
	v_pk_fma_f32 v[220:221], v[228:229], v[18:19], v[220:221]
	v_pk_fma_f32 v[222:223], v[230:231], v[18:19], v[222:223]
	v_cvt_pk_f32_fp8_e32 v[224:225], v177
	v_cvt_pk_f32_fp8_e32 v[226:227], v181
	v_cvt_pk_f32_fp8_e32 v[228:229], v185
	v_cvt_pk_f32_fp8_e32 v[230:231], v189
	v_pk_fma_f32 v[216:217], v[224:225], v[20:21], v[216:217]
	v_pk_fma_f32 v[218:219], v[226:227], v[20:21], v[218:219]
	v_pk_fma_f32 v[220:221], v[228:229], v[20:21], v[220:221]
	v_pk_fma_f32 v[222:223], v[230:231], v[20:21], v[222:223]
	v_cvt_pk_f32_fp8_sdwa v[224:225], v177 src0_sel:WORD_1
	v_cvt_pk_f32_fp8_sdwa v[226:227], v181 src0_sel:WORD_1
	v_cvt_pk_f32_fp8_sdwa v[228:229], v185 src0_sel:WORD_1
	v_cvt_pk_f32_fp8_sdwa v[230:231], v189 src0_sel:WORD_1
	v_pk_fma_f32 v[216:217], v[224:225], v[22:23], v[216:217]
	v_pk_fma_f32 v[218:219], v[226:227], v[22:23], v[218:219]
	v_pk_fma_f32 v[220:221], v[228:229], v[22:23], v[220:221]
; __device__ __forceinline__ float gelu_fast(float v) {
;     const float av = fabsf(v), tt = __builtin_amdgcn_rcpf(av * 0.2316418882f + 1.0f);
;     float q = tt * 0.5307027145f + (-0.7265760135f); q = q * tt + 0.7107068705f; q = q * tt + (-0.142248368f); q = q * tt + 0.127414796f; q = q * tt;
;     const float e = __builtin_amdgcn_exp2f((v * v) * (-0.72134752044f));
;     const float m = v * (q * e);
;     return v < 0.f ? m : v - m;
; }
	v_pk_fma_f32 v[222:223], v[230:231], v[22:23], v[222:223]
	v_cvt_pk_f32_fp8_e32 v[224:225], v178
	v_cvt_pk_f32_fp8_e32 v[226:227], v182
	v_cvt_pk_f32_fp8_e32 v[228:229], v186
	v_cvt_pk_f32_fp8_e32 v[230:231], v190
	v_pk_fma_f32 v[216:217], v[224:225], v[24:25], v[216:217]
	v_pk_fma_f32 v[218:219], v[226:227], v[24:25], v[218:219]
	v_pk_fma_f32 v[220:221], v[228:229], v[24:25], v[220:221]
	v_pk_fma_f32 v[222:223], v[230:231], v[24:25], v[222:223]
	v_cvt_pk_f32_fp8_sdwa v[224:225], v178 src0_sel:WORD_1
	v_cvt_pk_f32_fp8_sdwa v[226:227], v182 src0_sel:WORD_1
	v_cvt_pk_f32_fp8_sdwa v[228:229], v186 src0_sel:WORD_1
	v_cvt_pk_f32_fp8_sdwa v[230:231], v190 src0_sel:WORD_1
	v_pk_fma_f32 v[216:217], v[224:225], v[26:27], v[216:217]
	v_pk_fma_f32 v[218:219], v[226:227], v[26:27], v[218:219]
	v_pk_fma_f32 v[220:221], v[228:229], v[26:27], v[220:221]
	v_pk_fma_f32 v[222:223], v[230:231], v[26:27], v[222:223]
	v_cvt_pk_f32_fp8_e32 v[224:225], v179
	v_cvt_pk_f32_fp8_e32 v[226:227], v183
	v_cvt_pk_f32_fp8_e32 v[228:229], v187
	v_cvt_pk_f32_fp8_e32 v[230:231], v191
	v_pk_fma_f32 v[216:217], v[224:225], v[28:29], v[216:217]
	v_pk_fma_f32 v[218:219], v[226:227], v[28:29], v[218:219]
	v_pk_fma_f32 v[220:221], v[228:229], v[28:29], v[220:221]
	v_pk_fma_f32 v[222:223], v[230:231], v[28:29], v[222:223]
	v_cvt_pk_f32_fp8_sdwa v[224:225], v179 src0_sel:WORD_1
	v_cvt_pk_f32_fp8_sdwa v[226:227], v183 src0_sel:WORD_1
	v_cvt_pk_f32_fp8_sdwa v[228:229], v187 src0_sel:WORD_1
	v_cvt_pk_f32_fp8_sdwa v[230:231], v191 src0_sel:WORD_1
	v_pk_fma_f32 v[216:217], v[224:225], v[30:31], v[216:217]
	v_pk_fma_f32 v[218:219], v[226:227], v[30:31], v[218:219]
	v_pk_fma_f32 v[220:221], v[228:229], v[30:31], v[220:221]
	v_pk_fma_f32 v[222:223], v[230:231], v[30:31], v[222:223]
	v_add_f32_e32 v204, v216, v217
	v_add_f32_e32 v205, v218, v219
	v_add_f32_e32 v206, v220, v221
	v_add_f32_e32 v207, v222, v223
	s_nop 0
	v_permlane32_swap_b32_e32 v192, v200
	v_permlane32_swap_b32_e32 v193, v201
	v_permlane32_swap_b32_e32 v194, v202
	v_permlane32_swap_b32_e32 v195, v203
	v_permlane32_swap_b32_e32 v196, v204
	v_permlane32_swap_b32_e32 v197, v205
	v_permlane32_swap_b32_e32 v198, v206
	v_permlane32_swap_b32_e32 v199, v207
	v_add_f32_e32 v192, v192, v200
	v_add_f32_e32 v193, v193, v201
	v_add_f32_e32 v194, v194, v202
	v_add_f32_e32 v195, v195, v203
	v_add_f32_e32 v196, v196, v204
	v_add_f32_e32 v197, v197, v205
	v_add_f32_e32 v198, v198, v206
	v_add_f32_e32 v199, v199, v207
	v_permlane16_swap_b32_e32 v192, v196
	v_permlane16_swap_b32_e32 v193, v197
	v_permlane16_swap_b32_e32 v194, v198
	v_permlane16_swap_b32_e32 v195, v199
	v_add_f32_e32 v192, v192, v196
	v_add_f32_e32 v193, v193, v197
	v_add_f32_e32 v194, v194, v198
	v_add_f32_e32 v195, v195, v199
	v_add_f32_dpp v216, v192, v192 row_ror:8 row_mask:0xf bank_mask:0xf
	v_add_f32_dpp v218, v194, v194 row_ror:8 row_mask:0xf bank_mask:0xf
	v_add_f32_dpp v216, v193, v193 row_ror:8 row_mask:0xf bank_mask:0xc
	v_add_f32_dpp v218, v195, v195 row_ror:8 row_mask:0xf bank_mask:0xc
	s_nop 1
	v_add_f32_dpp v220, v216, v216 row_half_mirror row_mask:0xf bank_mask:0xf
	v_add_f32_dpp v220, v218, v218 row_half_mirror row_mask:0xf bank_mask:0xa
	s_nop 1
	v_add_f32_dpp v220, v220, v220 quad_perm:[1,0,3,2] row_mask:0xf bank_mask:0xf
	s_nop 1
	v_add_f32_dpp v220, v220, v220 quad_perm:[2,3,0,1] row_mask:0xf bank_mask:0xf
	v_mul_f32_e32 v216, v252, v220
	v_fma_f32 v218, |v216|, s72, 1.0
	v_mul_f32_e32 v222, v216, v216
	v_rcp_f32_e32 v218, v218
	v_mul_f32_e32 v222, 0xbf38aa3b, v222
	v_exp_f32_e32 v222, v222
	v_fmamk_f32 v224, v218, 0x3f07dc22, v242
	v_fmaak_f32 v224, v218, v224, 0x3f35f0e3
	v_fmaak_f32 v224, v218, v224, 0xbe11a98e
	v_fmaak_f32 v224, v218, v224, 0x3e027906
	v_mul_f32_e32 v224, v218, v224
	v_mul_f32_e32 v224, v222, v224
	v_mul_f32_e32 v226, v216, v224
	v_fma_f32 v224, -v216, v224, v216
	v_cmp_gt_f32_e32 vcc, 0, v216
	s_nop 1
	v_cndmask_b32_e32 v224, v224, v226, vcc
	v_mul_f32_e32 v224, v249, v224
	v_mul_f32_e32 v224, v253, v224
	ds_write_b32 v211, v224 offset:4992
	v_add_u32_e32 v211, 64, v211
	v_add_u32_e32 v213, 64, v213
	v_add_u32_e32 v250, 64, v250
	ds_read_b32 v252, v250
	ds_read_b32 v253, v250 offset:4096
	ds_read_b32 v249, v211 offset:4992
	s_add_i32 s21, s21, 4
	s_sub_i32 s90, s90, 1
	s_cmp_eq_u32 s90, 0
	s_cbranch_scc1 .LU_sw0
	s_branch .LU_t1_s0
.LU_t2_s0:
	s_cmp_ge_u32 s21, s20
	s_cbranch_scc1 .LU_done
	s_waitcnt lgkmcnt(0)
	buffer_load_dwordx4 v[176:179], v[232:233], s[56:59], 0 idxen offen
	buffer_load_dwordx4 v[180:183], v[234:235], s[56:59], 0 idxen offen
	buffer_load_dwordx4 v[184:187], v[236:237], s[56:59], 0 idxen offen
	buffer_load_dwordx4 v[188:191], v[238:239], s[56:59], 0 idxen offen
	ds_read_b32 v232, v213 offset:64
	ds_read_b32 v234, v213 offset:68
	ds_read_b32 v236, v213 offset:72
	ds_read_b32 v238, v213 offset:76
	s_waitcnt vmcnt(12)
	v_cvt_pk_f32_fp8_e32 v[224:225], v128
	v_cvt_pk_f32_fp8_e32 v[226:227], v132
	v_cvt_pk_f32_fp8_e32 v[228:229], v136
	v_cvt_pk_f32_fp8_e32 v[230:231], v140
	v_pk_mul_f32 v[216:217], v[224:225], v[32:33]
	v_pk_mul_f32 v[218:219], v[226:227], v[32:33]
	v_pk_mul_f32 v[220:221], v[228:229], v[32:33]
	v_pk_mul_f32 v[222:223], v[230:231], v[32:33]
	v_cvt_pk_f32_fp8_sdwa v[224:225], v128 src0_sel:WORD_1
	v_cvt_pk_f32_fp8_sdwa v[226:227], v132 src0_sel:WORD_1
	v_cvt_pk_f32_fp8_sdwa v[228:229], v136 src0_sel:WORD_1
	v_cvt_pk_f32_fp8_sdwa v[230:231], v140 src0_sel:WORD_1
	v_pk_fma_f32 v[216:217], v[224:225], v[34:35], v[216:217]
	v_pk_fma_f32 v[218:219], v[226:227], v[34:35], v[218:219]
	v_pk_fma_f32 v[220:221], v[228:229], v[34:35], v[220:221]
	v_pk_fma_f32 v[222:223], v[230:231], v[34:35], v[222:223]
	v_cvt_pk_f32_fp8_e32 v[224:225], v129
	v_cvt_pk_f32_fp8_e32 v[226:227], v133
	v_cvt_pk_f32_fp8_e32 v[228:229], v137
	v_cvt_pk_f32_fp8_e32 v[230:231], v141
	v_pk_fma_f32 v[216:217], v[224:225], v[36:37], v[216:217]
	v_pk_fma_f32 v[218:219], v[226:227], v[36:37], v[218:219]
	v_pk_fma_f32 v[220:221], v[228:229], v[36:37], v[220:221]
	v_pk_fma_f32 v[222:223], v[230:231], v[36:37], v[222:223]
	v_cvt_pk_f32_fp8_sdwa v[224:225], v129 src0_sel:WORD_1
	v_cvt_pk_f32_fp8_sdwa v[226:227], v133 src0_sel:WORD_1
	v_cvt_pk_f32_fp8_sdwa v[228:229], v137 src0_sel:WORD_1
	v_cvt_pk_f32_fp8_sdwa v[230:231], v141 src0_sel:WORD_1
	v_pk_fma_f32 v[216:217], v[224:225], v[38:39], v[216:217]
	v_pk_fma_f32 v[218:219], v[226:227], v[38:39], v[218:219]
	v_pk_fma_f32 v[220:221], v[228:229], v[38:39], v[220:221]
	v_pk_fma_f32 v[222:223], v[230:231], v[38:39], v[222:223]
	v_cvt_pk_f32_fp8_e32 v[224:225], v130
	v_cvt_pk_f32_fp8_e32 v[226:227], v134
	v_cvt_pk_f32_fp8_e32 v[228:229], v138
	v_cvt_pk_f32_fp8_e32 v[230:231], v142
	v_pk_fma_f32 v[216:217], v[224:225], v[40:41], v[216:217]
	v_pk_fma_f32 v[218:219], v[226:227], v[40:41], v[218:219]
	v_pk_fma_f32 v[220:221], v[228:229], v[40:41], v[220:221]
	v_pk_fma_f32 v[222:223], v[230:231], v[40:41], v[222:223]
	v_cvt_pk_f32_fp8_sdwa v[224:225], v130 src0_sel:WORD_1
	v_cvt_pk_f32_fp8_sdwa v[226:227], v134 src0_sel:WORD_1
	v_cvt_pk_f32_fp8_sdwa v[228:229], v138 src0_sel:WORD_1
	v_cvt_pk_f32_fp8_sdwa v[230:231], v142 src0_sel:WORD_1
	v_pk_fma_f32 v[216:217], v[224:225], v[42:43], v[216:217]
	v_pk_fma_f32 v[218:219], v[226:227], v[42:43], v[218:219]
	v_pk_fma_f32 v[220:221], v[228:229], v[42:43], v[220:221]
	v_pk_fma_f32 v[222:223], v[230:231], v[42:43], v[222:223]
	v_cvt_pk_f32_fp8_e32 v[224:225], v131
	v_cvt_pk_f32_fp8_e32 v[226:227], v135
	v_cvt_pk_f32_fp8_e32 v[228:229], v139
	v_cvt_pk_f32_fp8_e32 v[230:231], v143
	v_pk_fma_f32 v[216:217], v[224:225], v[44:45], v[216:217]
	v_pk_fma_f32 v[218:219], v[226:227], v[44:45], v[218:219]
	v_pk_fma_f32 v[220:221], v[228:229], v[44:45], v[220:221]
	v_pk_fma_f32 v[222:223], v[230:231], v[44:45], v[222:223]
	v_cvt_pk_f32_fp8_sdwa v[224:225], v131 src0_sel:WORD_1
	v_cvt_pk_f32_fp8_sdwa v[226:227], v135 src0_sel:WORD_1
	v_cvt_pk_f32_fp8_sdwa v[228:229], v139 src0_sel:WORD_1
	v_cvt_pk_f32_fp8_sdwa v[230:231], v143 src0_sel:WORD_1
	v_pk_fma_f32 v[216:217], v[224:225], v[46:47], v[216:217]
	v_pk_fma_f32 v[218:219], v[226:227], v[46:47], v[218:219]
	v_pk_fma_f32 v[220:221], v[228:229], v[46:47], v[220:221]
	v_pk_fma_f32 v[222:223], v[230:231], v[46:47], v[222:223]
	v_add_f32_e32 v192, v216, v217
	v_add_f32_e32 v193, v218, v219
	v_add_f32_e32 v194, v220, v221
	v_add_f32_e32 v195, v222, v223
	s_sub_i32 s90, s90, 1
	s_cmp_eq_u32 s90, 0
	s_cbranch_scc1 .LU_sw1
.LU_t2_s1:
	s_waitcnt lgkmcnt(0)
	buffer_load_dwordx4 v[128:131], v[232:233], s[56:59], 0 idxen offen
	buffer_load_dwordx4 v[132:135], v[234:235], s[56:59], 0 idxen offen
	buffer_load_dwordx4 v[136:139], v[236:237], s[56:59], 0 idxen offen
	buffer_load_dwordx4 v[140:143], v[238:239], s[56:59], 0 idxen offen
	ds_read_b32 v232, v213 offset:80
	ds_read_b32 v234, v213 offset:84
	ds_read_b32 v236, v213 offset:88
	ds_read_b32 v238, v213 offset:92
	s_waitcnt vmcnt(12)
	v_cvt_pk_f32_fp8_e32 v[224:225], v144
	v_cvt_pk_f32_fp8_e32 v[226:227], v148
	v_cvt_pk_f32_fp8_e32 v[228:229], v152
	v_cvt_pk_f32_fp8_e32 v[230:231], v156
	v_pk_mul_f32 v[216:217], v[224:225], v[32:33]
	v_pk_mul_f32 v[218:219], v[226:227], v[32:33]
	v_pk_mul_f32 v[220:221], v[228:229], v[32:33]
	v_pk_mul_f32 v[222:223], v[230:231], v[32:33]
	v_cvt_pk_f32_fp8_sdwa v[224:225], v144 src0_sel:WORD_1
	v_cvt_pk_f32_fp8_sdwa v[226:227], v148 src0_sel:WORD_1
	v_cvt_pk_f32_fp8_sdwa v[228:229], v152 src0_sel:WORD_1
	v_cvt_pk_f32_fp8_sdwa v[230:231], v156 src0_sel:WORD_1
	v_pk_fma_f32 v[216:217], v[224:225], v[34:35], v[216:217]
	v_pk_fma_f32 v[218:219], v[226:227], v[34:35], v[218:219]
	v_pk_fma_f32 v[220:221], v[228:229], v[34:35], v[220:221]
	v_pk_fma_f32 v[222:223], v[230:231], v[34:35], v[222:223]
	v_cvt_pk_f32_fp8_e32 v[224:225], v145
	v_cvt_pk_f32_fp8_e32 v[226:227], v149
	v_cvt_pk_f32_fp8_e32 v[228:229], v153
	v_cvt_pk_f32_fp8_e32 v[230:231], v157
	v_pk_fma_f32 v[216:217], v[224:225], v[36:37], v[216:217]
	v_pk_fma_f32 v[218:219], v[226:227], v[36:37], v[218:219]
	v_pk_fma_f32 v[220:221], v[228:229], v[36:37], v[220:221]
	v_pk_fma_f32 v[222:223], v[230:231], v[36:37], v[222:223]
	v_cvt_pk_f32_fp8_sdwa v[224:225], v145 src0_sel:WORD_1
	v_cvt_pk_f32_fp8_sdwa v[226:227], v149 src0_sel:WORD_1
	v_cvt_pk_f32_fp8_sdwa v[228:229], v153 src0_sel:WORD_1
	v_cvt_pk_f32_fp8_sdwa v[230:231], v157 src0_sel:WORD_1
	v_pk_fma_f32 v[216:217], v[224:225], v[38:39], v[216:217]
	v_pk_fma_f32 v[218:219], v[226:227], v[38:39], v[218:219]
	v_pk_fma_f32 v[220:221], v[228:229], v[38:39], v[220:221]
	v_pk_fma_f32 v[222:223], v[230:231], v[38:39], v[222:223]
	v_cvt_pk_f32_fp8_e32 v[224:225], v146
	v_cvt_pk_f32_fp8_e32 v[226:227], v150
	v_cvt_pk_f32_fp8_e32 v[228:229], v154
	v_cvt_pk_f32_fp8_e32 v[230:231], v158
	v_pk_fma_f32 v[216:217], v[224:225], v[40:41], v[216:217]
	v_pk_fma_f32 v[218:219], v[226:227], v[40:41], v[218:219]
	v_pk_fma_f32 v[220:221], v[228:229], v[40:41], v[220:221]
	v_pk_fma_f32 v[222:223], v[230:231], v[40:41], v[222:223]
	v_cvt_pk_f32_fp8_sdwa v[224:225], v146 src0_sel:WORD_1
	v_cvt_pk_f32_fp8_sdwa v[226:227], v150 src0_sel:WORD_1
	v_cvt_pk_f32_fp8_sdwa v[228:229], v154 src0_sel:WORD_1
	v_cvt_pk_f32_fp8_sdwa v[230:231], v158 src0_sel:WORD_1
	v_pk_fma_f32 v[216:217], v[224:225], v[42:43], v[216:217]
	v_pk_fma_f32 v[218:219], v[226:227], v[42:43], v[218:219]
	v_pk_fma_f32 v[220:221], v[228:229], v[42:43], v[220:221]
	v_pk_fma_f32 v[222:223], v[230:231], v[42:43], v[222:223]
	v_cvt_pk_f32_fp8_e32 v[224:225], v147
	v_cvt_pk_f32_fp8_e32 v[226:227], v151
	v_cvt_pk_f32_fp8_e32 v[228:229], v155
	v_cvt_pk_f32_fp8_e32 v[230:231], v159
	v_pk_fma_f32 v[216:217], v[224:225], v[44:45], v[216:217]
	v_pk_fma_f32 v[218:219], v[226:227], v[44:45], v[218:219]
	v_pk_fma_f32 v[220:221], v[228:229], v[44:45], v[220:221]
	v_pk_fma_f32 v[222:223], v[230:231], v[44:45], v[222:223]
	v_cvt_pk_f32_fp8_sdwa v[224:225], v147 src0_sel:WORD_1
	v_cvt_pk_f32_fp8_sdwa v[226:227], v151 src0_sel:WORD_1
	v_cvt_pk_f32_fp8_sdwa v[228:229], v155 src0_sel:WORD_1
	v_cvt_pk_f32_fp8_sdwa v[230:231], v159 src0_sel:WORD_1
	v_pk_fma_f32 v[216:217], v[224:225], v[46:47], v[216:217]
	v_pk_fma_f32 v[218:219], v[226:227], v[46:47], v[218:219]
	v_pk_fma_f32 v[220:221], v[228:229], v[46:47], v[220:221]
	v_pk_fma_f32 v[222:223], v[230:231], v[46:47], v[222:223]
	v_add_f32_e32 v196, v216, v217
	v_add_f32_e32 v197, v218, v219
	v_add_f32_e32 v198, v220, v221
	v_add_f32_e32 v199, v222, v223
	s_sub_i32 s90, s90, 1
	s_cmp_eq_u32 s90, 0
	s_cbranch_scc1 .LU_sw2
.LU_t2_s2:
	s_waitcnt lgkmcnt(0)
	buffer_load_dwordx4 v[144:147], v[232:233], s[56:59], 0 idxen offen
	buffer_load_dwordx4 v[148:151], v[234:235], s[56:59], 0 idxen offen
	buffer_load_dwordx4 v[152:155], v[236:237], s[56:59], 0 idxen offen
	buffer_load_dwordx4 v[156:159], v[238:239], s[56:59], 0 idxen offen
	ds_read_b32 v232, v213 offset:96
	ds_read_b32 v234, v213 offset:100
	ds_read_b32 v236, v213 offset:104
	ds_read_b32 v238, v213 offset:108
	s_waitcnt vmcnt(12)
	v_cvt_pk_f32_fp8_e32 v[224:225], v160
	v_cvt_pk_f32_fp8_e32 v[226:227], v164
	v_cvt_pk_f32_fp8_e32 v[228:229], v168
	v_cvt_pk_f32_fp8_e32 v[230:231], v172
	v_pk_mul_f32 v[216:217], v[224:225], v[32:33]
	v_pk_mul_f32 v[218:219], v[226:227], v[32:33]
	v_pk_mul_f32 v[220:221], v[228:229], v[32:33]
	v_pk_mul_f32 v[222:223], v[230:231], v[32:33]
	v_cvt_pk_f32_fp8_sdwa v[224:225], v160 src0_sel:WORD_1
	v_cvt_pk_f32_fp8_sdwa v[226:227], v164 src0_sel:WORD_1
	v_cvt_pk_f32_fp8_sdwa v[228:229], v168 src0_sel:WORD_1
	v_cvt_pk_f32_fp8_sdwa v[230:231], v172 src0_sel:WORD_1
	v_pk_fma_f32 v[216:217], v[224:225], v[34:35], v[216:217]
	v_pk_fma_f32 v[218:219], v[226:227], v[34:35], v[218:219]
	v_pk_fma_f32 v[220:221], v[228:229], v[34:35], v[220:221]
	v_pk_fma_f32 v[222:223], v[230:231], v[34:35], v[222:223]
	v_cvt_pk_f32_fp8_e32 v[224:225], v161
	v_cvt_pk_f32_fp8_e32 v[226:227], v165
	v_cvt_pk_f32_fp8_e32 v[228:229], v169
	v_cvt_pk_f32_fp8_e32 v[230:231], v173
	v_pk_fma_f32 v[216:217], v[224:225], v[36:37], v[216:217]
	v_pk_fma_f32 v[218:219], v[226:227], v[36:37], v[218:219]
	v_pk_fma_f32 v[220:221], v[228:229], v[36:37], v[220:221]
	v_pk_fma_f32 v[222:223], v[230:231], v[36:37], v[222:223]
	v_cvt_pk_f32_fp8_sdwa v[224:225], v161 src0_sel:WORD_1
	v_cvt_pk_f32_fp8_sdwa v[226:227], v165 src0_sel:WORD_1
	v_cvt_pk_f32_fp8_sdwa v[228:229], v169 src0_sel:WORD_1
	v_cvt_pk_f32_fp8_sdwa v[230:231], v173 src0_sel:WORD_1
	v_pk_fma_f32 v[216:217], v[224:225], v[38:39], v[216:217]
	v_pk_fma_f32 v[218:219], v[226:227], v[38:39], v[218:219]
	v_pk_fma_f32 v[220:221], v[228:229], v[38:39], v[220:221]
	v_pk_fma_f32 v[222:223], v[230:231], v[38:39], v[222:223]
	v_cvt_pk_f32_fp8_e32 v[224:225], v162
	v_cvt_pk_f32_fp8_e32 v[226:227], v166
	v_cvt_pk_f32_fp8_e32 v[228:229], v170
	v_cvt_pk_f32_fp8_e32 v[230:231], v174
	v_pk_fma_f32 v[216:217], v[224:225], v[40:41], v[216:217]
	v_pk_fma_f32 v[218:219], v[226:227], v[40:41], v[218:219]
	v_pk_fma_f32 v[220:221], v[228:229], v[40:41], v[220:221]
	v_pk_fma_f32 v[222:223], v[230:231], v[40:41], v[222:223]
	v_cvt_pk_f32_fp8_sdwa v[224:225], v162 src0_sel:WORD_1
	v_cvt_pk_f32_fp8_sdwa v[226:227], v166 src0_sel:WORD_1
	v_cvt_pk_f32_fp8_sdwa v[228:229], v170 src0_sel:WORD_1
	v_cvt_pk_f32_fp8_sdwa v[230:231], v174 src0_sel:WORD_1
	v_pk_fma_f32 v[216:217], v[224:225], v[42:43], v[216:217]
	v_pk_fma_f32 v[218:219], v[226:227], v[42:43], v[218:219]
	v_pk_fma_f32 v[220:221], v[228:229], v[42:43], v[220:221]
	v_pk_fma_f32 v[222:223], v[230:231], v[42:43], v[222:223]
	v_cvt_pk_f32_fp8_e32 v[224:225], v163
	v_cvt_pk_f32_fp8_e32 v[226:227], v167
	v_cvt_pk_f32_fp8_e32 v[228:229], v171
	v_cvt_pk_f32_fp8_e32 v[230:231], v175
	v_pk_fma_f32 v[216:217], v[224:225], v[44:45], v[216:217]
	v_pk_fma_f32 v[218:219], v[226:227], v[44:45], v[218:219]
	v_pk_fma_f32 v[220:221], v[228:229], v[44:45], v[220:221]
	v_pk_fma_f32 v[222:223], v[230:231], v[44:45], v[222:223]
	v_cvt_pk_f32_fp8_sdwa v[224:225], v163 src0_sel:WORD_1
	v_cvt_pk_f32_fp8_sdwa v[226:227], v167 src0_sel:WORD_1
	v_cvt_pk_f32_fp8_sdwa v[228:229], v171 src0_sel:WORD_1
	v_cvt_pk_f32_fp8_sdwa v[230:231], v175 src0_sel:WORD_1
	v_pk_fma_f32 v[216:217], v[224:225], v[46:47], v[216:217]
	v_pk_fma_f32 v[218:219], v[226:227], v[46:47], v[218:219]
	v_pk_fma_f32 v[220:221], v[228:229], v[46:47], v[220:221]
	v_pk_fma_f32 v[222:223], v[230:231], v[46:47], v[222:223]
	v_add_f32_e32 v200, v216, v217
	v_add_f32_e32 v201, v218, v219
	v_add_f32_e32 v202, v220, v221
	v_add_f32_e32 v203, v222, v223
	s_sub_i32 s90, s90, 1
	s_cmp_eq_u32 s90, 0
	s_cbranch_scc1 .LU_sw3
.LU_t2_s3:
	s_waitcnt lgkmcnt(0)
	buffer_load_dwordx4 v[160:163], v[232:233], s[56:59], 0 idxen offen
	buffer_load_dwordx4 v[164:167], v[234:235], s[56:59], 0 idxen offen
	buffer_load_dwordx4 v[168:171], v[236:237], s[56:59], 0 idxen offen
	buffer_load_dwordx4 v[172:175], v[238:239], s[56:59], 0 idxen offen
	ds_read_b32 v232, v213 offset:112
	ds_read_b32 v234, v213 offset:116
	ds_read_b32 v236, v213 offset:120
	ds_read_b32 v238, v213 offset:124
	s_waitcnt vmcnt(12)
	v_cvt_pk_f32_fp8_e32 v[224:225], v176
	v_cvt_pk_f32_fp8_e32 v[226:227], v180
	v_cvt_pk_f32_fp8_e32 v[228:229], v184
	v_cvt_pk_f32_fp8_e32 v[230:231], v188
	v_pk_mul_f32 v[216:217], v[224:225], v[32:33]
	v_pk_mul_f32 v[218:219], v[226:227], v[32:33]
	v_pk_mul_f32 v[220:221], v[228:229], v[32:33]
	v_pk_mul_f32 v[222:223], v[230:231], v[32:33]
	v_cvt_pk_f32_fp8_sdwa v[224:225], v176 src0_sel:WORD_1
	v_cvt_pk_f32_fp8_sdwa v[226:227], v180 src0_sel:WORD_1
	v_cvt_pk_f32_fp8_sdwa v[228:229], v184 src0_sel:WORD_1
	v_cvt_pk_f32_fp8_sdwa v[230:231], v188 src0_sel:WORD_1
	v_pk_fma_f32 v[216:217], v[224:225], v[34:35], v[216:217]
	v_pk_fma_f32 v[218:219], v[226:227], v[34:35], v[218:219]
	v_pk_fma_f32 v[220:221], v[228:229], v[34:35], v[220:221]
	v_pk_fma_f32 v[222:223], v[230:231], v[34:35], v[222:223]
	v_cvt_pk_f32_fp8_e32 v[224:225], v177
	v_cvt_pk_f32_fp8_e32 v[226:227], v181
	v_cvt_pk_f32_fp8_e32 v[228:229], v185
	v_cvt_pk_f32_fp8_e32 v[230:231], v189
	v_pk_fma_f32 v[216:217], v[224:225], v[36:37], v[216:217]
	v_pk_fma_f32 v[218:219], v[226:227], v[36:37], v[218:219]
	v_pk_fma_f32 v[220:221], v[228:229], v[36:37], v[220:221]
	v_pk_fma_f32 v[222:223], v[230:231], v[36:37], v[222:223]
	v_cvt_pk_f32_fp8_sdwa v[224:225], v177 src0_sel:WORD_1
	v_cvt_pk_f32_fp8_sdwa v[226:227], v181 src0_sel:WORD_1
	v_cvt_pk_f32_fp8_sdwa v[228:229], v185 src0_sel:WORD_1
	v_cvt_pk_f32_fp8_sdwa v[230:231], v189 src0_sel:WORD_1
	v_pk_fma_f32 v[216:217], v[224:225], v[38:39], v[216:217]
	v_pk_fma_f32 v[218:219], v[226:227], v[38:39], v[218:219]
	v_pk_fma_f32 v[220:221], v[228:229], v[38:39], v[220:221]
	v_pk_fma_f32 v[222:223], v[230:231], v[38:39], v[222:223]
	v_cvt_pk_f32_fp8_e32 v[224:225], v178
	v_cvt_pk_f32_fp8_e32 v[226:227], v182
	v_cvt_pk_f32_fp8_e32 v[228:229], v186
	v_cvt_pk_f32_fp8_e32 v[230:231], v190
	v_pk_fma_f32 v[216:217], v[224:225], v[40:41], v[216:217]
	v_pk_fma_f32 v[218:219], v[226:227], v[40:41], v[218:219]
	v_pk_fma_f32 v[220:221], v[228:229], v[40:41], v[220:221]
	v_pk_fma_f32 v[222:223], v[230:231], v[40:41], v[222:223]
	v_cvt_pk_f32_fp8_sdwa v[224:225], v178 src0_sel:WORD_1
	v_cvt_pk_f32_fp8_sdwa v[226:227], v182 src0_sel:WORD_1
	v_cvt_pk_f32_fp8_sdwa v[228:229], v186 src0_sel:WORD_1
	v_cvt_pk_f32_fp8_sdwa v[230:231], v190 src0_sel:WORD_1
	v_pk_fma_f32 v[216:217], v[224:225], v[42:43], v[216:217]
	v_pk_fma_f32 v[218:219], v[226:227], v[42:43], v[218:219]
	v_pk_fma_f32 v[220:221], v[228:229], v[42:43], v[220:221]
	v_pk_fma_f32 v[222:223], v[230:231], v[42:43], v[222:223]
	v_cvt_pk_f32_fp8_e32 v[224:225], v179
	v_cvt_pk_f32_fp8_e32 v[226:227], v183
	v_cvt_pk_f32_fp8_e32 v[228:229], v187
	v_cvt_pk_f32_fp8_e32 v[230:231], v191
	v_pk_fma_f32 v[216:217], v[224:225], v[44:45], v[216:217]
	v_pk_fma_f32 v[218:219], v[226:227], v[44:45], v[218:219]
	v_pk_fma_f32 v[220:221], v[228:229], v[44:45], v[220:221]
	v_pk_fma_f32 v[222:223], v[230:231], v[44:45], v[222:223]
	v_cvt_pk_f32_fp8_sdwa v[224:225], v179 src0_sel:WORD_1
	v_cvt_pk_f32_fp8_sdwa v[226:227], v183 src0_sel:WORD_1
	v_cvt_pk_f32_fp8_sdwa v[228:229], v187 src0_sel:WORD_1
	v_cvt_pk_f32_fp8_sdwa v[230:231], v191 src0_sel:WORD_1
	v_pk_fma_f32 v[216:217], v[224:225], v[46:47], v[216:217]
; __device__ __forceinline__ float gelu_fast(float v) {
;     const float av = fabsf(v), tt = __builtin_amdgcn_rcpf(av * 0.2316418882f + 1.0f);
;     float q = tt * 0.5307027145f + (-0.7265760135f); q = q * tt + 0.7107068705f; q = q * tt + (-0.142248368f); q = q * tt + 0.127414796f; q = q * tt;
;     const float e = __builtin_amdgcn_exp2f((v * v) * (-0.72134752044f));
;     const float m = v * (q * e);
;     return v < 0.f ? m : v - m;
; }
	v_pk_fma_f32 v[218:219], v[226:227], v[46:47], v[218:219]
	v_pk_fma_f32 v[220:221], v[228:229], v[46:47], v[220:221]
	v_pk_fma_f32 v[222:223], v[230:231], v[46:47], v[222:223]
	v_add_f32_e32 v204, v216, v217
	v_add_f32_e32 v205, v218, v219
	v_add_f32_e32 v206, v220, v221
	v_add_f32_e32 v207, v222, v223
	s_nop 0
	v_permlane32_swap_b32_e32 v192, v200
	v_permlane32_swap_b32_e32 v193, v201
	v_permlane32_swap_b32_e32 v194, v202
	v_permlane32_swap_b32_e32 v195, v203
	v_permlane32_swap_b32_e32 v196, v204
	v_permlane32_swap_b32_e32 v197, v205
	v_permlane32_swap_b32_e32 v198, v206
	v_permlane32_swap_b32_e32 v199, v207
	v_add_f32_e32 v192, v192, v200
	v_add_f32_e32 v193, v193, v201
	v_add_f32_e32 v194, v194, v202
	v_add_f32_e32 v195, v195, v203
	v_add_f32_e32 v196, v196, v204
	v_add_f32_e32 v197, v197, v205
	v_add_f32_e32 v198, v198, v206
	v_add_f32_e32 v199, v199, v207
	v_permlane16_swap_b32_e32 v192, v196
	v_permlane16_swap_b32_e32 v193, v197
	v_permlane16_swap_b32_e32 v194, v198
	v_permlane16_swap_b32_e32 v195, v199
	v_add_f32_e32 v192, v192, v196
	v_add_f32_e32 v193, v193, v197
	v_add_f32_e32 v194, v194, v198
	v_add_f32_e32 v195, v195, v199
	v_add_f32_dpp v216, v192, v192 row_ror:8 row_mask:0xf bank_mask:0xf
	v_add_f32_dpp v218, v194, v194 row_ror:8 row_mask:0xf bank_mask:0xf
	v_add_f32_dpp v216, v193, v193 row_ror:8 row_mask:0xf bank_mask:0xc
	v_add_f32_dpp v218, v195, v195 row_ror:8 row_mask:0xf bank_mask:0xc
	s_nop 1
	v_add_f32_dpp v220, v216, v216 row_half_mirror row_mask:0xf bank_mask:0xf
	v_add_f32_dpp v220, v218, v218 row_half_mirror row_mask:0xf bank_mask:0xa
	s_nop 1
	v_add_f32_dpp v220, v220, v220 quad_perm:[1,0,3,2] row_mask:0xf bank_mask:0xf
	s_nop 1
	v_add_f32_dpp v220, v220, v220 quad_perm:[2,3,0,1] row_mask:0xf bank_mask:0xf
	v_mul_f32_e32 v216, v252, v220
	v_fma_f32 v218, |v216|, s72, 1.0
	v_mul_f32_e32 v222, v216, v216
	v_rcp_f32_e32 v218, v218
	v_mul_f32_e32 v222, 0xbf38aa3b, v222
	v_exp_f32_e32 v222, v222
	v_fmamk_f32 v224, v218, 0x3f07dc22, v242
	v_fmaak_f32 v224, v218, v224, 0x3f35f0e3
	v_fmaak_f32 v224, v218, v224, 0xbe11a98e
	v_fmaak_f32 v224, v218, v224, 0x3e027906
	v_mul_f32_e32 v224, v218, v224
	v_mul_f32_e32 v224, v222, v224
	v_mul_f32_e32 v226, v216, v224
	v_fma_f32 v224, -v216, v224, v216
	v_cmp_gt_f32_e32 vcc, 0, v216
	s_nop 1
	v_cndmask_b32_e32 v224, v224, v226, vcc
	v_mul_f32_e32 v224, v249, v224
	v_mul_f32_e32 v224, v253, v224
	ds_write_b32 v211, v224 offset:4992
	v_add_u32_e32 v211, 64, v211
	v_add_u32_e32 v213, 64, v213
	v_add_u32_e32 v250, 64, v250
	ds_read_b32 v252, v250
	ds_read_b32 v253, v250 offset:4096
	ds_read_b32 v249, v211 offset:4992
	s_add_i32 s21, s21, 4
	s_sub_i32 s90, s90, 1
	s_cmp_eq_u32 s90, 0
	s_cbranch_scc1 .LU_sw0
	s_branch .LU_t2_s0
.LU_t3_s0:
	s_cmp_ge_u32 s21, s20
	s_cbranch_scc1 .LU_done
	s_waitcnt lgkmcnt(0)
	buffer_load_dwordx4 v[176:179], v[232:233], s[56:59], 0 idxen offen
	buffer_load_dwordx4 v[180:183], v[234:235], s[56:59], 0 idxen offen
	buffer_load_dwordx4 v[184:187], v[236:237], s[56:59], 0 idxen offen
	buffer_load_dwordx4 v[188:191], v[238:239], s[56:59], 0 idxen offen
	ds_read_b32 v232, v213 offset:64
	ds_read_b32 v234, v213 offset:68
	ds_read_b32 v236, v213 offset:72
	ds_read_b32 v238, v213 offset:76
	s_waitcnt vmcnt(12)
	v_cvt_pk_f32_fp8_e32 v[224:225], v128
	v_cvt_pk_f32_fp8_e32 v[226:227], v132
	v_cvt_pk_f32_fp8_e32 v[228:229], v136
	v_cvt_pk_f32_fp8_e32 v[230:231], v140
	v_pk_mul_f32 v[216:217], v[224:225], v[48:49]
	v_pk_mul_f32 v[218:219], v[226:227], v[48:49]
	v_pk_mul_f32 v[220:221], v[228:229], v[48:49]
	v_pk_mul_f32 v[222:223], v[230:231], v[48:49]
	v_cvt_pk_f32_fp8_sdwa v[224:225], v128 src0_sel:WORD_1
	v_cvt_pk_f32_fp8_sdwa v[226:227], v132 src0_sel:WORD_1
	v_cvt_pk_f32_fp8_sdwa v[228:229], v136 src0_sel:WORD_1
	v_cvt_pk_f32_fp8_sdwa v[230:231], v140 src0_sel:WORD_1
	v_pk_fma_f32 v[216:217], v[224:225], v[50:51], v[216:217]
	v_pk_fma_f32 v[218:219], v[226:227], v[50:51], v[218:219]
	v_pk_fma_f32 v[220:221], v[228:229], v[50:51], v[220:221]
	v_pk_fma_f32 v[222:223], v[230:231], v[50:51], v[222:223]
	v_cvt_pk_f32_fp8_e32 v[224:225], v129
	v_cvt_pk_f32_fp8_e32 v[226:227], v133
	v_cvt_pk_f32_fp8_e32 v[228:229], v137
	v_cvt_pk_f32_fp8_e32 v[230:231], v141
	v_pk_fma_f32 v[216:217], v[224:225], v[52:53], v[216:217]
	v_pk_fma_f32 v[218:219], v[226:227], v[52:53], v[218:219]
	v_pk_fma_f32 v[220:221], v[228:229], v[52:53], v[220:221]
	v_pk_fma_f32 v[222:223], v[230:231], v[52:53], v[222:223]
	v_cvt_pk_f32_fp8_sdwa v[224:225], v129 src0_sel:WORD_1
	v_cvt_pk_f32_fp8_sdwa v[226:227], v133 src0_sel:WORD_1
	v_cvt_pk_f32_fp8_sdwa v[228:229], v137 src0_sel:WORD_1
	v_cvt_pk_f32_fp8_sdwa v[230:231], v141 src0_sel:WORD_1
	v_pk_fma_f32 v[216:217], v[224:225], v[54:55], v[216:217]
	v_pk_fma_f32 v[218:219], v[226:227], v[54:55], v[218:219]
	v_pk_fma_f32 v[220:221], v[228:229], v[54:55], v[220:221]
	v_pk_fma_f32 v[222:223], v[230:231], v[54:55], v[222:223]
	v_cvt_pk_f32_fp8_e32 v[224:225], v130
	v_cvt_pk_f32_fp8_e32 v[226:227], v134
	v_cvt_pk_f32_fp8_e32 v[228:229], v138
	v_cvt_pk_f32_fp8_e32 v[230:231], v142
	v_pk_fma_f32 v[216:217], v[224:225], v[56:57], v[216:217]
	v_pk_fma_f32 v[218:219], v[226:227], v[56:57], v[218:219]
	v_pk_fma_f32 v[220:221], v[228:229], v[56:57], v[220:221]
	v_pk_fma_f32 v[222:223], v[230:231], v[56:57], v[222:223]
	v_cvt_pk_f32_fp8_sdwa v[224:225], v130 src0_sel:WORD_1
	v_cvt_pk_f32_fp8_sdwa v[226:227], v134 src0_sel:WORD_1
	v_cvt_pk_f32_fp8_sdwa v[228:229], v138 src0_sel:WORD_1
	v_cvt_pk_f32_fp8_sdwa v[230:231], v142 src0_sel:WORD_1
	v_pk_fma_f32 v[216:217], v[224:225], v[58:59], v[216:217]
	v_pk_fma_f32 v[218:219], v[226:227], v[58:59], v[218:219]
	v_pk_fma_f32 v[220:221], v[228:229], v[58:59], v[220:221]
	v_pk_fma_f32 v[222:223], v[230:231], v[58:59], v[222:223]
	v_cvt_pk_f32_fp8_e32 v[224:225], v131
	v_cvt_pk_f32_fp8_e32 v[226:227], v135
	v_cvt_pk_f32_fp8_e32 v[228:229], v139
	v_cvt_pk_f32_fp8_e32 v[230:231], v143
	v_pk_fma_f32 v[216:217], v[224:225], v[60:61], v[216:217]
	v_pk_fma_f32 v[218:219], v[226:227], v[60:61], v[218:219]
	v_pk_fma_f32 v[220:221], v[228:229], v[60:61], v[220:221]
	v_pk_fma_f32 v[222:223], v[230:231], v[60:61], v[222:223]
	v_cvt_pk_f32_fp8_sdwa v[224:225], v131 src0_sel:WORD_1
	v_cvt_pk_f32_fp8_sdwa v[226:227], v135 src0_sel:WORD_1
	v_cvt_pk_f32_fp8_sdwa v[228:229], v139 src0_sel:WORD_1
	v_cvt_pk_f32_fp8_sdwa v[230:231], v143 src0_sel:WORD_1
	v_pk_fma_f32 v[216:217], v[224:225], v[62:63], v[216:217]
	v_pk_fma_f32 v[218:219], v[226:227], v[62:63], v[218:219]
	v_pk_fma_f32 v[220:221], v[228:229], v[62:63], v[220:221]
	v_pk_fma_f32 v[222:223], v[230:231], v[62:63], v[222:223]
	v_add_f32_e32 v192, v216, v217
	v_add_f32_e32 v193, v218, v219
	v_add_f32_e32 v194, v220, v221
	v_add_f32_e32 v195, v222, v223
	s_sub_i32 s90, s90, 1
	s_cmp_eq_u32 s90, 0
	s_cbranch_scc1 .LU_sw1
.LU_t3_s1:
	s_waitcnt lgkmcnt(0)
	buffer_load_dwordx4 v[128:131], v[232:233], s[56:59], 0 idxen offen
	buffer_load_dwordx4 v[132:135], v[234:235], s[56:59], 0 idxen offen
	buffer_load_dwordx4 v[136:139], v[236:237], s[56:59], 0 idxen offen
	buffer_load_dwordx4 v[140:143], v[238:239], s[56:59], 0 idxen offen
	ds_read_b32 v232, v213 offset:80
	ds_read_b32 v234, v213 offset:84
	ds_read_b32 v236, v213 offset:88
	ds_read_b32 v238, v213 offset:92
	s_waitcnt vmcnt(12)
	v_cvt_pk_f32_fp8_e32 v[224:225], v144
	v_cvt_pk_f32_fp8_e32 v[226:227], v148
	v_cvt_pk_f32_fp8_e32 v[228:229], v152
	v_cvt_pk_f32_fp8_e32 v[230:231], v156
	v_pk_mul_f32 v[216:217], v[224:225], v[48:49]
	v_pk_mul_f32 v[218:219], v[226:227], v[48:49]
	v_pk_mul_f32 v[220:221], v[228:229], v[48:49]
	v_pk_mul_f32 v[222:223], v[230:231], v[48:49]
	v_cvt_pk_f32_fp8_sdwa v[224:225], v144 src0_sel:WORD_1
	v_cvt_pk_f32_fp8_sdwa v[226:227], v148 src0_sel:WORD_1
	v_cvt_pk_f32_fp8_sdwa v[228:229], v152 src0_sel:WORD_1
	v_cvt_pk_f32_fp8_sdwa v[230:231], v156 src0_sel:WORD_1
	v_pk_fma_f32 v[216:217], v[224:225], v[50:51], v[216:217]
	v_pk_fma_f32 v[218:219], v[226:227], v[50:51], v[218:219]
	v_pk_fma_f32 v[220:221], v[228:229], v[50:51], v[220:221]
	v_pk_fma_f32 v[222:223], v[230:231], v[50:51], v[222:223]
	v_cvt_pk_f32_fp8_e32 v[224:225], v145
	v_cvt_pk_f32_fp8_e32 v[226:227], v149
	v_cvt_pk_f32_fp8_e32 v[228:229], v153
	v_cvt_pk_f32_fp8_e32 v[230:231], v157
	v_pk_fma_f32 v[216:217], v[224:225], v[52:53], v[216:217]
	v_pk_fma_f32 v[218:219], v[226:227], v[52:53], v[218:219]
	v_pk_fma_f32 v[220:221], v[228:229], v[52:53], v[220:221]
	v_pk_fma_f32 v[222:223], v[230:231], v[52:53], v[222:223]
	v_cvt_pk_f32_fp8_sdwa v[224:225], v145 src0_sel:WORD_1
	v_cvt_pk_f32_fp8_sdwa v[226:227], v149 src0_sel:WORD_1
	v_cvt_pk_f32_fp8_sdwa v[228:229], v153 src0_sel:WORD_1
	v_cvt_pk_f32_fp8_sdwa v[230:231], v157 src0_sel:WORD_1
	v_pk_fma_f32 v[216:217], v[224:225], v[54:55], v[216:217]
	v_pk_fma_f32 v[218:219], v[226:227], v[54:55], v[218:219]
	v_pk_fma_f32 v[220:221], v[228:229], v[54:55], v[220:221]
	v_pk_fma_f32 v[222:223], v[230:231], v[54:55], v[222:223]
	v_cvt_pk_f32_fp8_e32 v[224:225], v146
	v_cvt_pk_f32_fp8_e32 v[226:227], v150
	v_cvt_pk_f32_fp8_e32 v[228:229], v154
	v_cvt_pk_f32_fp8_e32 v[230:231], v158
	v_pk_fma_f32 v[216:217], v[224:225], v[56:57], v[216:217]
	v_pk_fma_f32 v[218:219], v[226:227], v[56:57], v[218:219]
	v_pk_fma_f32 v[220:221], v[228:229], v[56:57], v[220:221]
	v_pk_fma_f32 v[222:223], v[230:231], v[56:57], v[222:223]
	v_cvt_pk_f32_fp8_sdwa v[224:225], v146 src0_sel:WORD_1
	v_cvt_pk_f32_fp8_sdwa v[226:227], v150 src0_sel:WORD_1
	v_cvt_pk_f32_fp8_sdwa v[228:229], v154 src0_sel:WORD_1
	v_cvt_pk_f32_fp8_sdwa v[230:231], v158 src0_sel:WORD_1
	v_pk_fma_f32 v[216:217], v[224:225], v[58:59], v[216:217]
	v_pk_fma_f32 v[218:219], v[226:227], v[58:59], v[218:219]
	v_pk_fma_f32 v[220:221], v[228:229], v[58:59], v[220:221]
	v_pk_fma_f32 v[222:223], v[230:231], v[58:59], v[222:223]
	v_cvt_pk_f32_fp8_e32 v[224:225], v147
	v_cvt_pk_f32_fp8_e32 v[226:227], v151
	v_cvt_pk_f32_fp8_e32 v[228:229], v155
	v_cvt_pk_f32_fp8_e32 v[230:231], v159
	v_pk_fma_f32 v[216:217], v[224:225], v[60:61], v[216:217]
	v_pk_fma_f32 v[218:219], v[226:227], v[60:61], v[218:219]
	v_pk_fma_f32 v[220:221], v[228:229], v[60:61], v[220:221]
	v_pk_fma_f32 v[222:223], v[230:231], v[60:61], v[222:223]
	v_cvt_pk_f32_fp8_sdwa v[224:225], v147 src0_sel:WORD_1
	v_cvt_pk_f32_fp8_sdwa v[226:227], v151 src0_sel:WORD_1
	v_cvt_pk_f32_fp8_sdwa v[228:229], v155 src0_sel:WORD_1
	v_cvt_pk_f32_fp8_sdwa v[230:231], v159 src0_sel:WORD_1
	v_pk_fma_f32 v[216:217], v[224:225], v[62:63], v[216:217]
	v_pk_fma_f32 v[218:219], v[226:227], v[62:63], v[218:219]
	v_pk_fma_f32 v[220:221], v[228:229], v[62:63], v[220:221]
	v_pk_fma_f32 v[222:223], v[230:231], v[62:63], v[222:223]
	v_add_f32_e32 v196, v216, v217
	v_add_f32_e32 v197, v218, v219
	v_add_f32_e32 v198, v220, v221
	v_add_f32_e32 v199, v222, v223
	s_sub_i32 s90, s90, 1
	s_cmp_eq_u32 s90, 0
	s_cbranch_scc1 .LU_sw2
.LU_t3_s2:
	s_waitcnt lgkmcnt(0)
	buffer_load_dwordx4 v[144:147], v[232:233], s[56:59], 0 idxen offen
	buffer_load_dwordx4 v[148:151], v[234:235], s[56:59], 0 idxen offen
	buffer_load_dwordx4 v[152:155], v[236:237], s[56:59], 0 idxen offen
	buffer_load_dwordx4 v[156:159], v[238:239], s[56:59], 0 idxen offen
	ds_read_b32 v232, v213 offset:96
	ds_read_b32 v234, v213 offset:100
	ds_read_b32 v236, v213 offset:104
	ds_read_b32 v238, v213 offset:108
	s_waitcnt vmcnt(12)
	v_cvt_pk_f32_fp8_e32 v[224:225], v160
	v_cvt_pk_f32_fp8_e32 v[226:227], v164
	v_cvt_pk_f32_fp8_e32 v[228:229], v168
	v_cvt_pk_f32_fp8_e32 v[230:231], v172
	v_pk_mul_f32 v[216:217], v[224:225], v[48:49]
	v_pk_mul_f32 v[218:219], v[226:227], v[48:49]
	v_pk_mul_f32 v[220:221], v[228:229], v[48:49]
	v_pk_mul_f32 v[222:223], v[230:231], v[48:49]
	v_cvt_pk_f32_fp8_sdwa v[224:225], v160 src0_sel:WORD_1
	v_cvt_pk_f32_fp8_sdwa v[226:227], v164 src0_sel:WORD_1
	v_cvt_pk_f32_fp8_sdwa v[228:229], v168 src0_sel:WORD_1
	v_cvt_pk_f32_fp8_sdwa v[230:231], v172 src0_sel:WORD_1
	v_pk_fma_f32 v[216:217], v[224:225], v[50:51], v[216:217]
	v_pk_fma_f32 v[218:219], v[226:227], v[50:51], v[218:219]
	v_pk_fma_f32 v[220:221], v[228:229], v[50:51], v[220:221]
	v_pk_fma_f32 v[222:223], v[230:231], v[50:51], v[222:223]
	v_cvt_pk_f32_fp8_e32 v[224:225], v161
	v_cvt_pk_f32_fp8_e32 v[226:227], v165
	v_cvt_pk_f32_fp8_e32 v[228:229], v169
	v_cvt_pk_f32_fp8_e32 v[230:231], v173
	v_pk_fma_f32 v[216:217], v[224:225], v[52:53], v[216:217]
	v_pk_fma_f32 v[218:219], v[226:227], v[52:53], v[218:219]
	v_pk_fma_f32 v[220:221], v[228:229], v[52:53], v[220:221]
	v_pk_fma_f32 v[222:223], v[230:231], v[52:53], v[222:223]
	v_cvt_pk_f32_fp8_sdwa v[224:225], v161 src0_sel:WORD_1
	v_cvt_pk_f32_fp8_sdwa v[226:227], v165 src0_sel:WORD_1
	v_cvt_pk_f32_fp8_sdwa v[228:229], v169 src0_sel:WORD_1
	v_cvt_pk_f32_fp8_sdwa v[230:231], v173 src0_sel:WORD_1
	v_pk_fma_f32 v[216:217], v[224:225], v[54:55], v[216:217]
	v_pk_fma_f32 v[218:219], v[226:227], v[54:55], v[218:219]
	v_pk_fma_f32 v[220:221], v[228:229], v[54:55], v[220:221]
	v_pk_fma_f32 v[222:223], v[230:231], v[54:55], v[222:223]
	v_cvt_pk_f32_fp8_e32 v[224:225], v162
	v_cvt_pk_f32_fp8_e32 v[226:227], v166
	v_cvt_pk_f32_fp8_e32 v[228:229], v170
	v_cvt_pk_f32_fp8_e32 v[230:231], v174
	v_pk_fma_f32 v[216:217], v[224:225], v[56:57], v[216:217]
	v_pk_fma_f32 v[218:219], v[226:227], v[56:57], v[218:219]
	v_pk_fma_f32 v[220:221], v[228:229], v[56:57], v[220:221]
	v_pk_fma_f32 v[222:223], v[230:231], v[56:57], v[222:223]
	v_cvt_pk_f32_fp8_sdwa v[224:225], v162 src0_sel:WORD_1
	v_cvt_pk_f32_fp8_sdwa v[226:227], v166 src0_sel:WORD_1
	v_cvt_pk_f32_fp8_sdwa v[228:229], v170 src0_sel:WORD_1
	v_cvt_pk_f32_fp8_sdwa v[230:231], v174 src0_sel:WORD_1
	v_pk_fma_f32 v[216:217], v[224:225], v[58:59], v[216:217]
	v_pk_fma_f32 v[218:219], v[226:227], v[58:59], v[218:219]
	v_pk_fma_f32 v[220:221], v[228:229], v[58:59], v[220:221]
	v_pk_fma_f32 v[222:223], v[230:231], v[58:59], v[222:223]
	v_cvt_pk_f32_fp8_e32 v[224:225], v163
	v_cvt_pk_f32_fp8_e32 v[226:227], v167
	v_cvt_pk_f32_fp8_e32 v[228:229], v171
	v_cvt_pk_f32_fp8_e32 v[230:231], v175
	v_pk_fma_f32 v[216:217], v[224:225], v[60:61], v[216:217]
	v_pk_fma_f32 v[218:219], v[226:227], v[60:61], v[218:219]
	v_pk_fma_f32 v[220:221], v[228:229], v[60:61], v[220:221]
	v_pk_fma_f32 v[222:223], v[230:231], v[60:61], v[222:223]
	v_cvt_pk_f32_fp8_sdwa v[224:225], v163 src0_sel:WORD_1
	v_cvt_pk_f32_fp8_sdwa v[226:227], v167 src0_sel:WORD_1
	v_cvt_pk_f32_fp8_sdwa v[228:229], v171 src0_sel:WORD_1
	v_cvt_pk_f32_fp8_sdwa v[230:231], v175 src0_sel:WORD_1
	v_pk_fma_f32 v[216:217], v[224:225], v[62:63], v[216:217]
	v_pk_fma_f32 v[218:219], v[226:227], v[62:63], v[218:219]
	v_pk_fma_f32 v[220:221], v[228:229], v[62:63], v[220:221]
	v_pk_fma_f32 v[222:223], v[230:231], v[62:63], v[222:223]
	v_add_f32_e32 v200, v216, v217
	v_add_f32_e32 v201, v218, v219
	v_add_f32_e32 v202, v220, v221
	v_add_f32_e32 v203, v222, v223
	s_sub_i32 s90, s90, 1
	s_cmp_eq_u32 s90, 0
	s_cbranch_scc1 .LU_sw3
.LU_t3_s3:
	s_waitcnt lgkmcnt(0)
	buffer_load_dwordx4 v[160:163], v[232:233], s[56:59], 0 idxen offen
	buffer_load_dwordx4 v[164:167], v[234:235], s[56:59], 0 idxen offen
	buffer_load_dwordx4 v[168:171], v[236:237], s[56:59], 0 idxen offen
	buffer_load_dwordx4 v[172:175], v[238:239], s[56:59], 0 idxen offen
	ds_read_b32 v232, v213 offset:112
	ds_read_b32 v234, v213 offset:116
	ds_read_b32 v236, v213 offset:120
	ds_read_b32 v238, v213 offset:124
	s_waitcnt vmcnt(12)
	v_cvt_pk_f32_fp8_e32 v[224:225], v176
	v_cvt_pk_f32_fp8_e32 v[226:227], v180
	v_cvt_pk_f32_fp8_e32 v[228:229], v184
	v_cvt_pk_f32_fp8_e32 v[230:231], v188
	v_pk_mul_f32 v[216:217], v[224:225], v[48:49]
	v_pk_mul_f32 v[218:219], v[226:227], v[48:49]
	v_pk_mul_f32 v[220:221], v[228:229], v[48:49]
	v_pk_mul_f32 v[222:223], v[230:231], v[48:49]
	v_cvt_pk_f32_fp8_sdwa v[224:225], v176 src0_sel:WORD_1
	v_cvt_pk_f32_fp8_sdwa v[226:227], v180 src0_sel:WORD_1
	v_cvt_pk_f32_fp8_sdwa v[228:229], v184 src0_sel:WORD_1
	v_cvt_pk_f32_fp8_sdwa v[230:231], v188 src0_sel:WORD_1
	v_pk_fma_f32 v[216:217], v[224:225], v[50:51], v[216:217]
	v_pk_fma_f32 v[218:219], v[226:227], v[50:51], v[218:219]
	v_pk_fma_f32 v[220:221], v[228:229], v[50:51], v[220:221]
	v_pk_fma_f32 v[222:223], v[230:231], v[50:51], v[222:223]
	v_cvt_pk_f32_fp8_e32 v[224:225], v177
	v_cvt_pk_f32_fp8_e32 v[226:227], v181
	v_cvt_pk_f32_fp8_e32 v[228:229], v185
	v_cvt_pk_f32_fp8_e32 v[230:231], v189
	v_pk_fma_f32 v[216:217], v[224:225], v[52:53], v[216:217]
	v_pk_fma_f32 v[218:219], v[226:227], v[52:53], v[218:219]
	v_pk_fma_f32 v[220:221], v[228:229], v[52:53], v[220:221]
	v_pk_fma_f32 v[222:223], v[230:231], v[52:53], v[222:223]
	v_cvt_pk_f32_fp8_sdwa v[224:225], v177 src0_sel:WORD_1
	v_cvt_pk_f32_fp8_sdwa v[226:227], v181 src0_sel:WORD_1
	v_cvt_pk_f32_fp8_sdwa v[228:229], v185 src0_sel:WORD_1
	v_cvt_pk_f32_fp8_sdwa v[230:231], v189 src0_sel:WORD_1
	v_pk_fma_f32 v[216:217], v[224:225], v[54:55], v[216:217]
	v_pk_fma_f32 v[218:219], v[226:227], v[54:55], v[218:219]
	v_pk_fma_f32 v[220:221], v[228:229], v[54:55], v[220:221]
; __device__ __forceinline__ float gelu_fast(float v) {
;     const float av = fabsf(v), tt = __builtin_amdgcn_rcpf(av * 0.2316418882f + 1.0f);
;     float q = tt * 0.5307027145f + (-0.7265760135f); q = q * tt + 0.7107068705f; q = q * tt + (-0.142248368f); q = q * tt + 0.127414796f; q = q * tt;
;     const float e = __builtin_amdgcn_exp2f((v * v) * (-0.72134752044f));
;     const float m = v * (q * e);
;     return v < 0.f ? m : v - m;
; }
	v_pk_fma_f32 v[222:223], v[230:231], v[54:55], v[222:223]
	v_cvt_pk_f32_fp8_e32 v[224:225], v178
	v_cvt_pk_f32_fp8_e32 v[226:227], v182
	v_cvt_pk_f32_fp8_e32 v[228:229], v186
	v_cvt_pk_f32_fp8_e32 v[230:231], v190
	v_pk_fma_f32 v[216:217], v[224:225], v[56:57], v[216:217]
	v_pk_fma_f32 v[218:219], v[226:227], v[56:57], v[218:219]
	v_pk_fma_f32 v[220:221], v[228:229], v[56:57], v[220:221]
	v_pk_fma_f32 v[222:223], v[230:231], v[56:57], v[222:223]
	v_cvt_pk_f32_fp8_sdwa v[224:225], v178 src0_sel:WORD_1
	v_cvt_pk_f32_fp8_sdwa v[226:227], v182 src0_sel:WORD_1
	v_cvt_pk_f32_fp8_sdwa v[228:229], v186 src0_sel:WORD_1
	v_cvt_pk_f32_fp8_sdwa v[230:231], v190 src0_sel:WORD_1
	v_pk_fma_f32 v[216:217], v[224:225], v[58:59], v[216:217]
	v_pk_fma_f32 v[218:219], v[226:227], v[58:59], v[218:219]
	v_pk_fma_f32 v[220:221], v[228:229], v[58:59], v[220:221]
	v_pk_fma_f32 v[222:223], v[230:231], v[58:59], v[222:223]
	v_cvt_pk_f32_fp8_e32 v[224:225], v179
	v_cvt_pk_f32_fp8_e32 v[226:227], v183
	v_cvt_pk_f32_fp8_e32 v[228:229], v187
	v_cvt_pk_f32_fp8_e32 v[230:231], v191
	v_pk_fma_f32 v[216:217], v[224:225], v[60:61], v[216:217]
	v_pk_fma_f32 v[218:219], v[226:227], v[60:61], v[218:219]
	v_pk_fma_f32 v[220:221], v[228:229], v[60:61], v[220:221]
	v_pk_fma_f32 v[222:223], v[230:231], v[60:61], v[222:223]
	v_cvt_pk_f32_fp8_sdwa v[224:225], v179 src0_sel:WORD_1
	v_cvt_pk_f32_fp8_sdwa v[226:227], v183 src0_sel:WORD_1
	v_cvt_pk_f32_fp8_sdwa v[228:229], v187 src0_sel:WORD_1
	v_cvt_pk_f32_fp8_sdwa v[230:231], v191 src0_sel:WORD_1
	v_pk_fma_f32 v[216:217], v[224:225], v[62:63], v[216:217]
	v_pk_fma_f32 v[218:219], v[226:227], v[62:63], v[218:219]
	v_pk_fma_f32 v[220:221], v[228:229], v[62:63], v[220:221]
	v_pk_fma_f32 v[222:223], v[230:231], v[62:63], v[222:223]
	v_add_f32_e32 v204, v216, v217
	v_add_f32_e32 v205, v218, v219
	v_add_f32_e32 v206, v220, v221
	v_add_f32_e32 v207, v222, v223
	s_nop 0
	v_permlane32_swap_b32_e32 v192, v200
	v_permlane32_swap_b32_e32 v193, v201
	v_permlane32_swap_b32_e32 v194, v202
	v_permlane32_swap_b32_e32 v195, v203
	v_permlane32_swap_b32_e32 v196, v204
	v_permlane32_swap_b32_e32 v197, v205
	v_permlane32_swap_b32_e32 v198, v206
	v_permlane32_swap_b32_e32 v199, v207
	v_add_f32_e32 v192, v192, v200
	v_add_f32_e32 v193, v193, v201
	v_add_f32_e32 v194, v194, v202
	v_add_f32_e32 v195, v195, v203
	v_add_f32_e32 v196, v196, v204
	v_add_f32_e32 v197, v197, v205
	v_add_f32_e32 v198, v198, v206
	v_add_f32_e32 v199, v199, v207
	v_permlane16_swap_b32_e32 v192, v196
	v_permlane16_swap_b32_e32 v193, v197
	v_permlane16_swap_b32_e32 v194, v198
	v_permlane16_swap_b32_e32 v195, v199
	v_add_f32_e32 v192, v192, v196
	v_add_f32_e32 v193, v193, v197
	v_add_f32_e32 v194, v194, v198
	v_add_f32_e32 v195, v195, v199
	v_add_f32_dpp v216, v192, v192 row_ror:8 row_mask:0xf bank_mask:0xf
	v_add_f32_dpp v218, v194, v194 row_ror:8 row_mask:0xf bank_mask:0xf
	v_add_f32_dpp v216, v193, v193 row_ror:8 row_mask:0xf bank_mask:0xc
	v_add_f32_dpp v218, v195, v195 row_ror:8 row_mask:0xf bank_mask:0xc
	s_nop 1
	v_add_f32_dpp v220, v216, v216 row_half_mirror row_mask:0xf bank_mask:0xf
	v_add_f32_dpp v220, v218, v218 row_half_mirror row_mask:0xf bank_mask:0xa
	s_nop 1
	v_add_f32_dpp v220, v220, v220 quad_perm:[1,0,3,2] row_mask:0xf bank_mask:0xf
	s_nop 1
	v_add_f32_dpp v220, v220, v220 quad_perm:[2,3,0,1] row_mask:0xf bank_mask:0xf
	v_mul_f32_e32 v216, v252, v220
	v_fma_f32 v218, |v216|, s72, 1.0
	v_mul_f32_e32 v222, v216, v216
	v_rcp_f32_e32 v218, v218
	v_mul_f32_e32 v222, 0xbf38aa3b, v222
	v_exp_f32_e32 v222, v222
	v_fmamk_f32 v224, v218, 0x3f07dc22, v242
	v_fmaak_f32 v224, v218, v224, 0x3f35f0e3
	v_fmaak_f32 v224, v218, v224, 0xbe11a98e
	v_fmaak_f32 v224, v218, v224, 0x3e027906
	v_mul_f32_e32 v224, v218, v224
	v_mul_f32_e32 v224, v222, v224
	v_mul_f32_e32 v226, v216, v224
	v_fma_f32 v224, -v216, v224, v216
	v_cmp_gt_f32_e32 vcc, 0, v216
	s_nop 1
	v_cndmask_b32_e32 v224, v224, v226, vcc
	v_mul_f32_e32 v224, v249, v224
	v_mul_f32_e32 v224, v253, v224
	ds_write_b32 v211, v224 offset:4992
	v_add_u32_e32 v211, 64, v211
	v_add_u32_e32 v213, 64, v213
	v_add_u32_e32 v250, 64, v250
	ds_read_b32 v252, v250
	ds_read_b32 v253, v250 offset:4096
	ds_read_b32 v249, v211 offset:4992
	s_add_i32 s21, s21, 4
	s_sub_i32 s90, s90, 1
	s_cmp_eq_u32 s90, 0
	s_cbranch_scc1 .LU_sw0
	s_branch .LU_t3_s0
.LU_t4_s0:
	s_cmp_ge_u32 s21, s20
	s_cbranch_scc1 .LU_done
	s_waitcnt lgkmcnt(0)
	buffer_load_dwordx4 v[176:179], v[232:233], s[56:59], 0 idxen offen
	buffer_load_dwordx4 v[180:183], v[234:235], s[56:59], 0 idxen offen
	buffer_load_dwordx4 v[184:187], v[236:237], s[56:59], 0 idxen offen
	buffer_load_dwordx4 v[188:191], v[238:239], s[56:59], 0 idxen offen
	ds_read_b32 v232, v213 offset:64
	ds_read_b32 v234, v213 offset:68
	ds_read_b32 v236, v213 offset:72
	ds_read_b32 v238, v213 offset:76
	s_waitcnt vmcnt(12)
	v_cvt_pk_f32_fp8_e32 v[224:225], v128
	v_cvt_pk_f32_fp8_e32 v[226:227], v132
	v_cvt_pk_f32_fp8_e32 v[228:229], v136
	v_cvt_pk_f32_fp8_e32 v[230:231], v140
	v_pk_mul_f32 v[216:217], v[224:225], v[64:65]
	v_pk_mul_f32 v[218:219], v[226:227], v[64:65]
	v_pk_mul_f32 v[220:221], v[228:229], v[64:65]
	v_pk_mul_f32 v[222:223], v[230:231], v[64:65]
	v_cvt_pk_f32_fp8_sdwa v[224:225], v128 src0_sel:WORD_1
	v_cvt_pk_f32_fp8_sdwa v[226:227], v132 src0_sel:WORD_1
	v_cvt_pk_f32_fp8_sdwa v[228:229], v136 src0_sel:WORD_1
	v_cvt_pk_f32_fp8_sdwa v[230:231], v140 src0_sel:WORD_1
	v_pk_fma_f32 v[216:217], v[224:225], v[66:67], v[216:217]
	v_pk_fma_f32 v[218:219], v[226:227], v[66:67], v[218:219]
	v_pk_fma_f32 v[220:221], v[228:229], v[66:67], v[220:221]
	v_pk_fma_f32 v[222:223], v[230:231], v[66:67], v[222:223]
	v_cvt_pk_f32_fp8_e32 v[224:225], v129
	v_cvt_pk_f32_fp8_e32 v[226:227], v133
	v_cvt_pk_f32_fp8_e32 v[228:229], v137
	v_cvt_pk_f32_fp8_e32 v[230:231], v141
	v_pk_fma_f32 v[216:217], v[224:225], v[68:69], v[216:217]
	v_pk_fma_f32 v[218:219], v[226:227], v[68:69], v[218:219]
	v_pk_fma_f32 v[220:221], v[228:229], v[68:69], v[220:221]
	v_pk_fma_f32 v[222:223], v[230:231], v[68:69], v[222:223]
	v_cvt_pk_f32_fp8_sdwa v[224:225], v129 src0_sel:WORD_1
	v_cvt_pk_f32_fp8_sdwa v[226:227], v133 src0_sel:WORD_1
	v_cvt_pk_f32_fp8_sdwa v[228:229], v137 src0_sel:WORD_1
	v_cvt_pk_f32_fp8_sdwa v[230:231], v141 src0_sel:WORD_1
	v_pk_fma_f32 v[216:217], v[224:225], v[70:71], v[216:217]
	v_pk_fma_f32 v[218:219], v[226:227], v[70:71], v[218:219]
	v_pk_fma_f32 v[220:221], v[228:229], v[70:71], v[220:221]
	v_pk_fma_f32 v[222:223], v[230:231], v[70:71], v[222:223]
	v_cvt_pk_f32_fp8_e32 v[224:225], v130
	v_cvt_pk_f32_fp8_e32 v[226:227], v134
	v_cvt_pk_f32_fp8_e32 v[228:229], v138
	v_cvt_pk_f32_fp8_e32 v[230:231], v142
	v_pk_fma_f32 v[216:217], v[224:225], v[72:73], v[216:217]
	v_pk_fma_f32 v[218:219], v[226:227], v[72:73], v[218:219]
	v_pk_fma_f32 v[220:221], v[228:229], v[72:73], v[220:221]
	v_pk_fma_f32 v[222:223], v[230:231], v[72:73], v[222:223]
	v_cvt_pk_f32_fp8_sdwa v[224:225], v130 src0_sel:WORD_1
	v_cvt_pk_f32_fp8_sdwa v[226:227], v134 src0_sel:WORD_1
	v_cvt_pk_f32_fp8_sdwa v[228:229], v138 src0_sel:WORD_1
	v_cvt_pk_f32_fp8_sdwa v[230:231], v142 src0_sel:WORD_1
	v_pk_fma_f32 v[216:217], v[224:225], v[74:75], v[216:217]
	v_pk_fma_f32 v[218:219], v[226:227], v[74:75], v[218:219]
	v_pk_fma_f32 v[220:221], v[228:229], v[74:75], v[220:221]
	v_pk_fma_f32 v[222:223], v[230:231], v[74:75], v[222:223]
	v_cvt_pk_f32_fp8_e32 v[224:225], v131
	v_cvt_pk_f32_fp8_e32 v[226:227], v135
	v_cvt_pk_f32_fp8_e32 v[228:229], v139
	v_cvt_pk_f32_fp8_e32 v[230:231], v143
	v_pk_fma_f32 v[216:217], v[224:225], v[76:77], v[216:217]
	v_pk_fma_f32 v[218:219], v[226:227], v[76:77], v[218:219]
	v_pk_fma_f32 v[220:221], v[228:229], v[76:77], v[220:221]
	v_pk_fma_f32 v[222:223], v[230:231], v[76:77], v[222:223]
	v_cvt_pk_f32_fp8_sdwa v[224:225], v131 src0_sel:WORD_1
	v_cvt_pk_f32_fp8_sdwa v[226:227], v135 src0_sel:WORD_1
	v_cvt_pk_f32_fp8_sdwa v[228:229], v139 src0_sel:WORD_1
	v_cvt_pk_f32_fp8_sdwa v[230:231], v143 src0_sel:WORD_1
	v_pk_fma_f32 v[216:217], v[224:225], v[78:79], v[216:217]
	v_pk_fma_f32 v[218:219], v[226:227], v[78:79], v[218:219]
	v_pk_fma_f32 v[220:221], v[228:229], v[78:79], v[220:221]
	v_pk_fma_f32 v[222:223], v[230:231], v[78:79], v[222:223]
	v_add_f32_e32 v192, v216, v217
	v_add_f32_e32 v193, v218, v219
	v_add_f32_e32 v194, v220, v221
	v_add_f32_e32 v195, v222, v223
	s_sub_i32 s90, s90, 1
	s_cmp_eq_u32 s90, 0
	s_cbranch_scc1 .LU_sw1
.LU_t4_s1:
	s_waitcnt lgkmcnt(0)
	buffer_load_dwordx4 v[128:131], v[232:233], s[56:59], 0 idxen offen
	buffer_load_dwordx4 v[132:135], v[234:235], s[56:59], 0 idxen offen
	buffer_load_dwordx4 v[136:139], v[236:237], s[56:59], 0 idxen offen
	buffer_load_dwordx4 v[140:143], v[238:239], s[56:59], 0 idxen offen
	ds_read_b32 v232, v213 offset:80
	ds_read_b32 v234, v213 offset:84
	ds_read_b32 v236, v213 offset:88
	ds_read_b32 v238, v213 offset:92
	s_waitcnt vmcnt(12)
	v_cvt_pk_f32_fp8_e32 v[224:225], v144
	v_cvt_pk_f32_fp8_e32 v[226:227], v148
	v_cvt_pk_f32_fp8_e32 v[228:229], v152
	v_cvt_pk_f32_fp8_e32 v[230:231], v156
	v_pk_mul_f32 v[216:217], v[224:225], v[64:65]
	v_pk_mul_f32 v[218:219], v[226:227], v[64:65]
	v_pk_mul_f32 v[220:221], v[228:229], v[64:65]
	v_pk_mul_f32 v[222:223], v[230:231], v[64:65]
	v_cvt_pk_f32_fp8_sdwa v[224:225], v144 src0_sel:WORD_1
	v_cvt_pk_f32_fp8_sdwa v[226:227], v148 src0_sel:WORD_1
	v_cvt_pk_f32_fp8_sdwa v[228:229], v152 src0_sel:WORD_1
	v_cvt_pk_f32_fp8_sdwa v[230:231], v156 src0_sel:WORD_1
	v_pk_fma_f32 v[216:217], v[224:225], v[66:67], v[216:217]
	v_pk_fma_f32 v[218:219], v[226:227], v[66:67], v[218:219]
	v_pk_fma_f32 v[220:221], v[228:229], v[66:67], v[220:221]
	v_pk_fma_f32 v[222:223], v[230:231], v[66:67], v[222:223]
	v_cvt_pk_f32_fp8_e32 v[224:225], v145
	v_cvt_pk_f32_fp8_e32 v[226:227], v149
	v_cvt_pk_f32_fp8_e32 v[228:229], v153
	v_cvt_pk_f32_fp8_e32 v[230:231], v157
	v_pk_fma_f32 v[216:217], v[224:225], v[68:69], v[216:217]
	v_pk_fma_f32 v[218:219], v[226:227], v[68:69], v[218:219]
	v_pk_fma_f32 v[220:221], v[228:229], v[68:69], v[220:221]
	v_pk_fma_f32 v[222:223], v[230:231], v[68:69], v[222:223]
	v_cvt_pk_f32_fp8_sdwa v[224:225], v145 src0_sel:WORD_1
	v_cvt_pk_f32_fp8_sdwa v[226:227], v149 src0_sel:WORD_1
	v_cvt_pk_f32_fp8_sdwa v[228:229], v153 src0_sel:WORD_1
	v_cvt_pk_f32_fp8_sdwa v[230:231], v157 src0_sel:WORD_1
	v_pk_fma_f32 v[216:217], v[224:225], v[70:71], v[216:217]
	v_pk_fma_f32 v[218:219], v[226:227], v[70:71], v[218:219]
	v_pk_fma_f32 v[220:221], v[228:229], v[70:71], v[220:221]
	v_pk_fma_f32 v[222:223], v[230:231], v[70:71], v[222:223]
	v_cvt_pk_f32_fp8_e32 v[224:225], v146
	v_cvt_pk_f32_fp8_e32 v[226:227], v150
	v_cvt_pk_f32_fp8_e32 v[228:229], v154
	v_cvt_pk_f32_fp8_e32 v[230:231], v158
	v_pk_fma_f32 v[216:217], v[224:225], v[72:73], v[216:217]
	v_pk_fma_f32 v[218:219], v[226:227], v[72:73], v[218:219]
	v_pk_fma_f32 v[220:221], v[228:229], v[72:73], v[220:221]
	v_pk_fma_f32 v[222:223], v[230:231], v[72:73], v[222:223]
	v_cvt_pk_f32_fp8_sdwa v[224:225], v146 src0_sel:WORD_1
	v_cvt_pk_f32_fp8_sdwa v[226:227], v150 src0_sel:WORD_1
	v_cvt_pk_f32_fp8_sdwa v[228:229], v154 src0_sel:WORD_1
	v_cvt_pk_f32_fp8_sdwa v[230:231], v158 src0_sel:WORD_1
	v_pk_fma_f32 v[216:217], v[224:225], v[74:75], v[216:217]
	v_pk_fma_f32 v[218:219], v[226:227], v[74:75], v[218:219]
	v_pk_fma_f32 v[220:221], v[228:229], v[74:75], v[220:221]
	v_pk_fma_f32 v[222:223], v[230:231], v[74:75], v[222:223]
	v_cvt_pk_f32_fp8_e32 v[224:225], v147
	v_cvt_pk_f32_fp8_e32 v[226:227], v151
	v_cvt_pk_f32_fp8_e32 v[228:229], v155
	v_cvt_pk_f32_fp8_e32 v[230:231], v159
	v_pk_fma_f32 v[216:217], v[224:225], v[76:77], v[216:217]
	v_pk_fma_f32 v[218:219], v[226:227], v[76:77], v[218:219]
	v_pk_fma_f32 v[220:221], v[228:229], v[76:77], v[220:221]
	v_pk_fma_f32 v[222:223], v[230:231], v[76:77], v[222:223]
	v_cvt_pk_f32_fp8_sdwa v[224:225], v147 src0_sel:WORD_1
	v_cvt_pk_f32_fp8_sdwa v[226:227], v151 src0_sel:WORD_1
	v_cvt_pk_f32_fp8_sdwa v[228:229], v155 src0_sel:WORD_1
	v_cvt_pk_f32_fp8_sdwa v[230:231], v159 src0_sel:WORD_1
	v_pk_fma_f32 v[216:217], v[224:225], v[78:79], v[216:217]
	v_pk_fma_f32 v[218:219], v[226:227], v[78:79], v[218:219]
	v_pk_fma_f32 v[220:221], v[228:229], v[78:79], v[220:221]
	v_pk_fma_f32 v[222:223], v[230:231], v[78:79], v[222:223]
	v_add_f32_e32 v196, v216, v217
	v_add_f32_e32 v197, v218, v219
	v_add_f32_e32 v198, v220, v221
	v_add_f32_e32 v199, v222, v223
	s_sub_i32 s90, s90, 1
	s_cmp_eq_u32 s90, 0
	s_cbranch_scc1 .LU_sw2
.LU_t4_s2:
	s_waitcnt lgkmcnt(0)
	buffer_load_dwordx4 v[144:147], v[232:233], s[56:59], 0 idxen offen
	buffer_load_dwordx4 v[148:151], v[234:235], s[56:59], 0 idxen offen
	buffer_load_dwordx4 v[152:155], v[236:237], s[56:59], 0 idxen offen
	buffer_load_dwordx4 v[156:159], v[238:239], s[56:59], 0 idxen offen
	ds_read_b32 v232, v213 offset:96
	ds_read_b32 v234, v213 offset:100
	ds_read_b32 v236, v213 offset:104
	ds_read_b32 v238, v213 offset:108
	s_waitcnt vmcnt(12)
	v_cvt_pk_f32_fp8_e32 v[224:225], v160
	v_cvt_pk_f32_fp8_e32 v[226:227], v164
	v_cvt_pk_f32_fp8_e32 v[228:229], v168
	v_cvt_pk_f32_fp8_e32 v[230:231], v172
	v_pk_mul_f32 v[216:217], v[224:225], v[64:65]
	v_pk_mul_f32 v[218:219], v[226:227], v[64:65]
	v_pk_mul_f32 v[220:221], v[228:229], v[64:65]
	v_pk_mul_f32 v[222:223], v[230:231], v[64:65]
	v_cvt_pk_f32_fp8_sdwa v[224:225], v160 src0_sel:WORD_1
	v_cvt_pk_f32_fp8_sdwa v[226:227], v164 src0_sel:WORD_1
	v_cvt_pk_f32_fp8_sdwa v[228:229], v168 src0_sel:WORD_1
	v_cvt_pk_f32_fp8_sdwa v[230:231], v172 src0_sel:WORD_1
	v_pk_fma_f32 v[216:217], v[224:225], v[66:67], v[216:217]
	v_pk_fma_f32 v[218:219], v[226:227], v[66:67], v[218:219]
	v_pk_fma_f32 v[220:221], v[228:229], v[66:67], v[220:221]
	v_pk_fma_f32 v[222:223], v[230:231], v[66:67], v[222:223]
	v_cvt_pk_f32_fp8_e32 v[224:225], v161
	v_cvt_pk_f32_fp8_e32 v[226:227], v165
	v_cvt_pk_f32_fp8_e32 v[228:229], v169
	v_cvt_pk_f32_fp8_e32 v[230:231], v173
	v_pk_fma_f32 v[216:217], v[224:225], v[68:69], v[216:217]
	v_pk_fma_f32 v[218:219], v[226:227], v[68:69], v[218:219]
	v_pk_fma_f32 v[220:221], v[228:229], v[68:69], v[220:221]
	v_pk_fma_f32 v[222:223], v[230:231], v[68:69], v[222:223]
	v_cvt_pk_f32_fp8_sdwa v[224:225], v161 src0_sel:WORD_1
	v_cvt_pk_f32_fp8_sdwa v[226:227], v165 src0_sel:WORD_1
	v_cvt_pk_f32_fp8_sdwa v[228:229], v169 src0_sel:WORD_1
	v_cvt_pk_f32_fp8_sdwa v[230:231], v173 src0_sel:WORD_1
	v_pk_fma_f32 v[216:217], v[224:225], v[70:71], v[216:217]
	v_pk_fma_f32 v[218:219], v[226:227], v[70:71], v[218:219]
	v_pk_fma_f32 v[220:221], v[228:229], v[70:71], v[220:221]
	v_pk_fma_f32 v[222:223], v[230:231], v[70:71], v[222:223]
	v_cvt_pk_f32_fp8_e32 v[224:225], v162
	v_cvt_pk_f32_fp8_e32 v[226:227], v166
	v_cvt_pk_f32_fp8_e32 v[228:229], v170
	v_cvt_pk_f32_fp8_e32 v[230:231], v174
	v_pk_fma_f32 v[216:217], v[224:225], v[72:73], v[216:217]
	v_pk_fma_f32 v[218:219], v[226:227], v[72:73], v[218:219]
	v_pk_fma_f32 v[220:221], v[228:229], v[72:73], v[220:221]
	v_pk_fma_f32 v[222:223], v[230:231], v[72:73], v[222:223]
	v_cvt_pk_f32_fp8_sdwa v[224:225], v162 src0_sel:WORD_1
	v_cvt_pk_f32_fp8_sdwa v[226:227], v166 src0_sel:WORD_1
	v_cvt_pk_f32_fp8_sdwa v[228:229], v170 src0_sel:WORD_1
	v_cvt_pk_f32_fp8_sdwa v[230:231], v174 src0_sel:WORD_1
	v_pk_fma_f32 v[216:217], v[224:225], v[74:75], v[216:217]
	v_pk_fma_f32 v[218:219], v[226:227], v[74:75], v[218:219]
	v_pk_fma_f32 v[220:221], v[228:229], v[74:75], v[220:221]
	v_pk_fma_f32 v[222:223], v[230:231], v[74:75], v[222:223]
	v_cvt_pk_f32_fp8_e32 v[224:225], v163
	v_cvt_pk_f32_fp8_e32 v[226:227], v167
	v_cvt_pk_f32_fp8_e32 v[228:229], v171
	v_cvt_pk_f32_fp8_e32 v[230:231], v175
	v_pk_fma_f32 v[216:217], v[224:225], v[76:77], v[216:217]
	v_pk_fma_f32 v[218:219], v[226:227], v[76:77], v[218:219]
	v_pk_fma_f32 v[220:221], v[228:229], v[76:77], v[220:221]
	v_pk_fma_f32 v[222:223], v[230:231], v[76:77], v[222:223]
	v_cvt_pk_f32_fp8_sdwa v[224:225], v163 src0_sel:WORD_1
	v_cvt_pk_f32_fp8_sdwa v[226:227], v167 src0_sel:WORD_1
	v_cvt_pk_f32_fp8_sdwa v[228:229], v171 src0_sel:WORD_1
	v_cvt_pk_f32_fp8_sdwa v[230:231], v175 src0_sel:WORD_1
	v_pk_fma_f32 v[216:217], v[224:225], v[78:79], v[216:217]
	v_pk_fma_f32 v[218:219], v[226:227], v[78:79], v[218:219]
	v_pk_fma_f32 v[220:221], v[228:229], v[78:79], v[220:221]
	v_pk_fma_f32 v[222:223], v[230:231], v[78:79], v[222:223]
	v_add_f32_e32 v200, v216, v217
	v_add_f32_e32 v201, v218, v219
	v_add_f32_e32 v202, v220, v221
	v_add_f32_e32 v203, v222, v223
	s_sub_i32 s90, s90, 1
	s_cmp_eq_u32 s90, 0
	s_cbranch_scc1 .LU_sw3
.LU_t4_s3:
	s_waitcnt lgkmcnt(0)
	buffer_load_dwordx4 v[160:163], v[232:233], s[56:59], 0 idxen offen
	buffer_load_dwordx4 v[164:167], v[234:235], s[56:59], 0 idxen offen
	buffer_load_dwordx4 v[168:171], v[236:237], s[56:59], 0 idxen offen
	buffer_load_dwordx4 v[172:175], v[238:239], s[56:59], 0 idxen offen
	ds_read_b32 v232, v213 offset:112
	ds_read_b32 v234, v213 offset:116
	ds_read_b32 v236, v213 offset:120
	ds_read_b32 v238, v213 offset:124
	s_waitcnt vmcnt(12)
	v_cvt_pk_f32_fp8_e32 v[224:225], v176
	v_cvt_pk_f32_fp8_e32 v[226:227], v180
	v_cvt_pk_f32_fp8_e32 v[228:229], v184
	v_cvt_pk_f32_fp8_e32 v[230:231], v188
	v_pk_mul_f32 v[216:217], v[224:225], v[64:65]
	v_pk_mul_f32 v[218:219], v[226:227], v[64:65]
	v_pk_mul_f32 v[220:221], v[228:229], v[64:65]
	v_pk_mul_f32 v[222:223], v[230:231], v[64:65]
	v_cvt_pk_f32_fp8_sdwa v[224:225], v176 src0_sel:WORD_1
	v_cvt_pk_f32_fp8_sdwa v[226:227], v180 src0_sel:WORD_1
	v_cvt_pk_f32_fp8_sdwa v[228:229], v184 src0_sel:WORD_1
	v_cvt_pk_f32_fp8_sdwa v[230:231], v188 src0_sel:WORD_1
	v_pk_fma_f32 v[216:217], v[224:225], v[66:67], v[216:217]
	v_pk_fma_f32 v[218:219], v[226:227], v[66:67], v[218:219]
	v_pk_fma_f32 v[220:221], v[228:229], v[66:67], v[220:221]
	v_pk_fma_f32 v[222:223], v[230:231], v[66:67], v[222:223]
	v_cvt_pk_f32_fp8_e32 v[224:225], v177
	v_cvt_pk_f32_fp8_e32 v[226:227], v181
	v_cvt_pk_f32_fp8_e32 v[228:229], v185
	v_cvt_pk_f32_fp8_e32 v[230:231], v189
	v_pk_fma_f32 v[216:217], v[224:225], v[68:69], v[216:217]
	v_pk_fma_f32 v[218:219], v[226:227], v[68:69], v[218:219]
	v_pk_fma_f32 v[220:221], v[228:229], v[68:69], v[220:221]
	v_pk_fma_f32 v[222:223], v[230:231], v[68:69], v[222:223]
	v_cvt_pk_f32_fp8_sdwa v[224:225], v177 src0_sel:WORD_1
	v_cvt_pk_f32_fp8_sdwa v[226:227], v181 src0_sel:WORD_1
	v_cvt_pk_f32_fp8_sdwa v[228:229], v185 src0_sel:WORD_1
	v_cvt_pk_f32_fp8_sdwa v[230:231], v189 src0_sel:WORD_1
	v_pk_fma_f32 v[216:217], v[224:225], v[70:71], v[216:217]
	v_pk_fma_f32 v[218:219], v[226:227], v[70:71], v[218:219]
	v_pk_fma_f32 v[220:221], v[228:229], v[70:71], v[220:221]
	v_pk_fma_f32 v[222:223], v[230:231], v[70:71], v[222:223]
	v_cvt_pk_f32_fp8_e32 v[224:225], v178
	v_cvt_pk_f32_fp8_e32 v[226:227], v182
	v_cvt_pk_f32_fp8_e32 v[228:229], v186
	v_cvt_pk_f32_fp8_e32 v[230:231], v190
	v_pk_fma_f32 v[216:217], v[224:225], v[72:73], v[216:217]
	v_pk_fma_f32 v[218:219], v[226:227], v[72:73], v[218:219]
	v_pk_fma_f32 v[220:221], v[228:229], v[72:73], v[220:221]
	v_pk_fma_f32 v[222:223], v[230:231], v[72:73], v[222:223]
	v_cvt_pk_f32_fp8_sdwa v[224:225], v178 src0_sel:WORD_1
	v_cvt_pk_f32_fp8_sdwa v[226:227], v182 src0_sel:WORD_1
	v_cvt_pk_f32_fp8_sdwa v[228:229], v186 src0_sel:WORD_1
	v_cvt_pk_f32_fp8_sdwa v[230:231], v190 src0_sel:WORD_1
	v_pk_fma_f32 v[216:217], v[224:225], v[74:75], v[216:217]
	v_pk_fma_f32 v[218:219], v[226:227], v[74:75], v[218:219]
	v_pk_fma_f32 v[220:221], v[228:229], v[74:75], v[220:221]
	v_pk_fma_f32 v[222:223], v[230:231], v[74:75], v[222:223]
	v_cvt_pk_f32_fp8_e32 v[224:225], v179
	v_cvt_pk_f32_fp8_e32 v[226:227], v183
	v_cvt_pk_f32_fp8_e32 v[228:229], v187
	v_cvt_pk_f32_fp8_e32 v[230:231], v191
	v_pk_fma_f32 v[216:217], v[224:225], v[76:77], v[216:217]
	v_pk_fma_f32 v[218:219], v[226:227], v[76:77], v[218:219]
	v_pk_fma_f32 v[220:221], v[228:229], v[76:77], v[220:221]
	v_pk_fma_f32 v[222:223], v[230:231], v[76:77], v[222:223]
	v_cvt_pk_f32_fp8_sdwa v[224:225], v179 src0_sel:WORD_1
	v_cvt_pk_f32_fp8_sdwa v[226:227], v183 src0_sel:WORD_1
	v_cvt_pk_f32_fp8_sdwa v[228:229], v187 src0_sel:WORD_1
	v_cvt_pk_f32_fp8_sdwa v[230:231], v191 src0_sel:WORD_1
	v_pk_fma_f32 v[216:217], v[224:225], v[78:79], v[216:217]
; __device__ __forceinline__ float gelu_fast(float v) {
;     const float av = fabsf(v), tt = __builtin_amdgcn_rcpf(av * 0.2316418882f + 1.0f);
;     float q = tt * 0.5307027145f + (-0.7265760135f); q = q * tt + 0.7107068705f; q = q * tt + (-0.142248368f); q = q * tt + 0.127414796f; q = q * tt;
;     const float e = __builtin_amdgcn_exp2f((v * v) * (-0.72134752044f));
;     const float m = v * (q * e);
;     return v < 0.f ? m : v - m;
; }
	v_pk_fma_f32 v[218:219], v[226:227], v[78:79], v[218:219]
	v_pk_fma_f32 v[220:221], v[228:229], v[78:79], v[220:221]
	v_pk_fma_f32 v[222:223], v[230:231], v[78:79], v[222:223]
	v_add_f32_e32 v204, v216, v217
	v_add_f32_e32 v205, v218, v219
	v_add_f32_e32 v206, v220, v221
	v_add_f32_e32 v207, v222, v223
	s_nop 0
	v_permlane32_swap_b32_e32 v192, v200
	v_permlane32_swap_b32_e32 v193, v201
	v_permlane32_swap_b32_e32 v194, v202
	v_permlane32_swap_b32_e32 v195, v203
	v_permlane32_swap_b32_e32 v196, v204
	v_permlane32_swap_b32_e32 v197, v205
	v_permlane32_swap_b32_e32 v198, v206
	v_permlane32_swap_b32_e32 v199, v207
	v_add_f32_e32 v192, v192, v200
	v_add_f32_e32 v193, v193, v201
	v_add_f32_e32 v194, v194, v202
	v_add_f32_e32 v195, v195, v203
	v_add_f32_e32 v196, v196, v204
	v_add_f32_e32 v197, v197, v205
	v_add_f32_e32 v198, v198, v206
	v_add_f32_e32 v199, v199, v207
	v_permlane16_swap_b32_e32 v192, v196
	v_permlane16_swap_b32_e32 v193, v197
	v_permlane16_swap_b32_e32 v194, v198
	v_permlane16_swap_b32_e32 v195, v199
	v_add_f32_e32 v192, v192, v196
	v_add_f32_e32 v193, v193, v197
	v_add_f32_e32 v194, v194, v198
	v_add_f32_e32 v195, v195, v199
	v_add_f32_dpp v216, v192, v192 row_ror:8 row_mask:0xf bank_mask:0xf
	v_add_f32_dpp v218, v194, v194 row_ror:8 row_mask:0xf bank_mask:0xf
	v_add_f32_dpp v216, v193, v193 row_ror:8 row_mask:0xf bank_mask:0xc
	v_add_f32_dpp v218, v195, v195 row_ror:8 row_mask:0xf bank_mask:0xc
	s_nop 1
	v_add_f32_dpp v220, v216, v216 row_half_mirror row_mask:0xf bank_mask:0xf
	v_add_f32_dpp v220, v218, v218 row_half_mirror row_mask:0xf bank_mask:0xa
	s_nop 1
	v_add_f32_dpp v220, v220, v220 quad_perm:[1,0,3,2] row_mask:0xf bank_mask:0xf
	s_nop 1
	v_add_f32_dpp v220, v220, v220 quad_perm:[2,3,0,1] row_mask:0xf bank_mask:0xf
	v_mul_f32_e32 v216, v252, v220
	v_fma_f32 v218, |v216|, s72, 1.0
	v_mul_f32_e32 v222, v216, v216
	v_rcp_f32_e32 v218, v218
	v_mul_f32_e32 v222, 0xbf38aa3b, v222
	v_exp_f32_e32 v222, v222
	v_fmamk_f32 v224, v218, 0x3f07dc22, v242
	v_fmaak_f32 v224, v218, v224, 0x3f35f0e3
	v_fmaak_f32 v224, v218, v224, 0xbe11a98e
	v_fmaak_f32 v224, v218, v224, 0x3e027906
	v_mul_f32_e32 v224, v218, v224
	v_mul_f32_e32 v224, v222, v224
	v_mul_f32_e32 v226, v216, v224
	v_fma_f32 v224, -v216, v224, v216
	v_cmp_gt_f32_e32 vcc, 0, v216
	s_nop 1
	v_cndmask_b32_e32 v224, v224, v226, vcc
	v_mul_f32_e32 v224, v249, v224
	v_mul_f32_e32 v224, v253, v224
	ds_write_b32 v211, v224 offset:4992
	v_add_u32_e32 v211, 64, v211
	v_add_u32_e32 v213, 64, v213
	v_add_u32_e32 v250, 64, v250
	ds_read_b32 v252, v250
	ds_read_b32 v253, v250 offset:4096
	ds_read_b32 v249, v211 offset:4992
	s_add_i32 s21, s21, 4
	s_sub_i32 s90, s90, 1
	s_cmp_eq_u32 s90, 0
	s_cbranch_scc1 .LU_sw0
	s_branch .LU_t4_s0
.LU_t5_s0:
	s_cmp_ge_u32 s21, s20
	s_cbranch_scc1 .LU_done
	s_waitcnt lgkmcnt(0)
	buffer_load_dwordx4 v[176:179], v[232:233], s[56:59], 0 idxen offen
	buffer_load_dwordx4 v[180:183], v[234:235], s[56:59], 0 idxen offen
	buffer_load_dwordx4 v[184:187], v[236:237], s[56:59], 0 idxen offen
	buffer_load_dwordx4 v[188:191], v[238:239], s[56:59], 0 idxen offen
	ds_read_b32 v232, v213 offset:64
	ds_read_b32 v234, v213 offset:68
	ds_read_b32 v236, v213 offset:72
	ds_read_b32 v238, v213 offset:76
	s_waitcnt vmcnt(12)
	v_cvt_pk_f32_fp8_e32 v[224:225], v128
	v_cvt_pk_f32_fp8_e32 v[226:227], v132
	v_cvt_pk_f32_fp8_e32 v[228:229], v136
	v_cvt_pk_f32_fp8_e32 v[230:231], v140
	v_pk_mul_f32 v[216:217], v[224:225], v[80:81]
	v_pk_mul_f32 v[218:219], v[226:227], v[80:81]
	v_pk_mul_f32 v[220:221], v[228:229], v[80:81]
	v_pk_mul_f32 v[222:223], v[230:231], v[80:81]
	v_cvt_pk_f32_fp8_sdwa v[224:225], v128 src0_sel:WORD_1
	v_cvt_pk_f32_fp8_sdwa v[226:227], v132 src0_sel:WORD_1
	v_cvt_pk_f32_fp8_sdwa v[228:229], v136 src0_sel:WORD_1
	v_cvt_pk_f32_fp8_sdwa v[230:231], v140 src0_sel:WORD_1
	v_pk_fma_f32 v[216:217], v[224:225], v[82:83], v[216:217]
	v_pk_fma_f32 v[218:219], v[226:227], v[82:83], v[218:219]
	v_pk_fma_f32 v[220:221], v[228:229], v[82:83], v[220:221]
	v_pk_fma_f32 v[222:223], v[230:231], v[82:83], v[222:223]
	v_cvt_pk_f32_fp8_e32 v[224:225], v129
	v_cvt_pk_f32_fp8_e32 v[226:227], v133
	v_cvt_pk_f32_fp8_e32 v[228:229], v137
	v_cvt_pk_f32_fp8_e32 v[230:231], v141
	v_pk_fma_f32 v[216:217], v[224:225], v[84:85], v[216:217]
	v_pk_fma_f32 v[218:219], v[226:227], v[84:85], v[218:219]
	v_pk_fma_f32 v[220:221], v[228:229], v[84:85], v[220:221]
	v_pk_fma_f32 v[222:223], v[230:231], v[84:85], v[222:223]
	v_cvt_pk_f32_fp8_sdwa v[224:225], v129 src0_sel:WORD_1
	v_cvt_pk_f32_fp8_sdwa v[226:227], v133 src0_sel:WORD_1
	v_cvt_pk_f32_fp8_sdwa v[228:229], v137 src0_sel:WORD_1
	v_cvt_pk_f32_fp8_sdwa v[230:231], v141 src0_sel:WORD_1
	v_pk_fma_f32 v[216:217], v[224:225], v[86:87], v[216:217]
	v_pk_fma_f32 v[218:219], v[226:227], v[86:87], v[218:219]
	v_pk_fma_f32 v[220:221], v[228:229], v[86:87], v[220:221]
	v_pk_fma_f32 v[222:223], v[230:231], v[86:87], v[222:223]
	v_cvt_pk_f32_fp8_e32 v[224:225], v130
	v_cvt_pk_f32_fp8_e32 v[226:227], v134
	v_cvt_pk_f32_fp8_e32 v[228:229], v138
	v_cvt_pk_f32_fp8_e32 v[230:231], v142
	v_pk_fma_f32 v[216:217], v[224:225], v[88:89], v[216:217]
	v_pk_fma_f32 v[218:219], v[226:227], v[88:89], v[218:219]
	v_pk_fma_f32 v[220:221], v[228:229], v[88:89], v[220:221]
	v_pk_fma_f32 v[222:223], v[230:231], v[88:89], v[222:223]
	v_cvt_pk_f32_fp8_sdwa v[224:225], v130 src0_sel:WORD_1
	v_cvt_pk_f32_fp8_sdwa v[226:227], v134 src0_sel:WORD_1
	v_cvt_pk_f32_fp8_sdwa v[228:229], v138 src0_sel:WORD_1
	v_cvt_pk_f32_fp8_sdwa v[230:231], v142 src0_sel:WORD_1
	v_pk_fma_f32 v[216:217], v[224:225], v[90:91], v[216:217]
	v_pk_fma_f32 v[218:219], v[226:227], v[90:91], v[218:219]
	v_pk_fma_f32 v[220:221], v[228:229], v[90:91], v[220:221]
	v_pk_fma_f32 v[222:223], v[230:231], v[90:91], v[222:223]
	v_cvt_pk_f32_fp8_e32 v[224:225], v131
	v_cvt_pk_f32_fp8_e32 v[226:227], v135
	v_cvt_pk_f32_fp8_e32 v[228:229], v139
	v_cvt_pk_f32_fp8_e32 v[230:231], v143
	v_pk_fma_f32 v[216:217], v[224:225], v[92:93], v[216:217]
	v_pk_fma_f32 v[218:219], v[226:227], v[92:93], v[218:219]
	v_pk_fma_f32 v[220:221], v[228:229], v[92:93], v[220:221]
	v_pk_fma_f32 v[222:223], v[230:231], v[92:93], v[222:223]
	v_cvt_pk_f32_fp8_sdwa v[224:225], v131 src0_sel:WORD_1
	v_cvt_pk_f32_fp8_sdwa v[226:227], v135 src0_sel:WORD_1
	v_cvt_pk_f32_fp8_sdwa v[228:229], v139 src0_sel:WORD_1
	v_cvt_pk_f32_fp8_sdwa v[230:231], v143 src0_sel:WORD_1
	v_pk_fma_f32 v[216:217], v[224:225], v[94:95], v[216:217]
	v_pk_fma_f32 v[218:219], v[226:227], v[94:95], v[218:219]
	v_pk_fma_f32 v[220:221], v[228:229], v[94:95], v[220:221]
	v_pk_fma_f32 v[222:223], v[230:231], v[94:95], v[222:223]
	v_add_f32_e32 v192, v216, v217
	v_add_f32_e32 v193, v218, v219
	v_add_f32_e32 v194, v220, v221
	v_add_f32_e32 v195, v222, v223
	s_sub_i32 s90, s90, 1
	s_cmp_eq_u32 s90, 0
	s_cbranch_scc1 .LU_sw1
.LU_t5_s1:
	s_waitcnt lgkmcnt(0)
	buffer_load_dwordx4 v[128:131], v[232:233], s[56:59], 0 idxen offen
	buffer_load_dwordx4 v[132:135], v[234:235], s[56:59], 0 idxen offen
	buffer_load_dwordx4 v[136:139], v[236:237], s[56:59], 0 idxen offen
	buffer_load_dwordx4 v[140:143], v[238:239], s[56:59], 0 idxen offen
	ds_read_b32 v232, v213 offset:80
	ds_read_b32 v234, v213 offset:84
	ds_read_b32 v236, v213 offset:88
	ds_read_b32 v238, v213 offset:92
	s_waitcnt vmcnt(12)
	v_cvt_pk_f32_fp8_e32 v[224:225], v144
	v_cvt_pk_f32_fp8_e32 v[226:227], v148
	v_cvt_pk_f32_fp8_e32 v[228:229], v152
	v_cvt_pk_f32_fp8_e32 v[230:231], v156
	v_pk_mul_f32 v[216:217], v[224:225], v[80:81]
	v_pk_mul_f32 v[218:219], v[226:227], v[80:81]
	v_pk_mul_f32 v[220:221], v[228:229], v[80:81]
	v_pk_mul_f32 v[222:223], v[230:231], v[80:81]
	v_cvt_pk_f32_fp8_sdwa v[224:225], v144 src0_sel:WORD_1
	v_cvt_pk_f32_fp8_sdwa v[226:227], v148 src0_sel:WORD_1
	v_cvt_pk_f32_fp8_sdwa v[228:229], v152 src0_sel:WORD_1
	v_cvt_pk_f32_fp8_sdwa v[230:231], v156 src0_sel:WORD_1
	v_pk_fma_f32 v[216:217], v[224:225], v[82:83], v[216:217]
	v_pk_fma_f32 v[218:219], v[226:227], v[82:83], v[218:219]
	v_pk_fma_f32 v[220:221], v[228:229], v[82:83], v[220:221]
	v_pk_fma_f32 v[222:223], v[230:231], v[82:83], v[222:223]
	v_cvt_pk_f32_fp8_e32 v[224:225], v145
	v_cvt_pk_f32_fp8_e32 v[226:227], v149
	v_cvt_pk_f32_fp8_e32 v[228:229], v153
	v_cvt_pk_f32_fp8_e32 v[230:231], v157
	v_pk_fma_f32 v[216:217], v[224:225], v[84:85], v[216:217]
	v_pk_fma_f32 v[218:219], v[226:227], v[84:85], v[218:219]
	v_pk_fma_f32 v[220:221], v[228:229], v[84:85], v[220:221]
	v_pk_fma_f32 v[222:223], v[230:231], v[84:85], v[222:223]
	v_cvt_pk_f32_fp8_sdwa v[224:225], v145 src0_sel:WORD_1
	v_cvt_pk_f32_fp8_sdwa v[226:227], v149 src0_sel:WORD_1
	v_cvt_pk_f32_fp8_sdwa v[228:229], v153 src0_sel:WORD_1
	v_cvt_pk_f32_fp8_sdwa v[230:231], v157 src0_sel:WORD_1
	v_pk_fma_f32 v[216:217], v[224:225], v[86:87], v[216:217]
	v_pk_fma_f32 v[218:219], v[226:227], v[86:87], v[218:219]
	v_pk_fma_f32 v[220:221], v[228:229], v[86:87], v[220:221]
	v_pk_fma_f32 v[222:223], v[230:231], v[86:87], v[222:223]
	v_cvt_pk_f32_fp8_e32 v[224:225], v146
	v_cvt_pk_f32_fp8_e32 v[226:227], v150
	v_cvt_pk_f32_fp8_e32 v[228:229], v154
	v_cvt_pk_f32_fp8_e32 v[230:231], v158
	v_pk_fma_f32 v[216:217], v[224:225], v[88:89], v[216:217]
	v_pk_fma_f32 v[218:219], v[226:227], v[88:89], v[218:219]
	v_pk_fma_f32 v[220:221], v[228:229], v[88:89], v[220:221]
	v_pk_fma_f32 v[222:223], v[230:231], v[88:89], v[222:223]
	v_cvt_pk_f32_fp8_sdwa v[224:225], v146 src0_sel:WORD_1
	v_cvt_pk_f32_fp8_sdwa v[226:227], v150 src0_sel:WORD_1
	v_cvt_pk_f32_fp8_sdwa v[228:229], v154 src0_sel:WORD_1
	v_cvt_pk_f32_fp8_sdwa v[230:231], v158 src0_sel:WORD_1
	v_pk_fma_f32 v[216:217], v[224:225], v[90:91], v[216:217]
	v_pk_fma_f32 v[218:219], v[226:227], v[90:91], v[218:219]
	v_pk_fma_f32 v[220:221], v[228:229], v[90:91], v[220:221]
	v_pk_fma_f32 v[222:223], v[230:231], v[90:91], v[222:223]
	v_cvt_pk_f32_fp8_e32 v[224:225], v147
	v_cvt_pk_f32_fp8_e32 v[226:227], v151
	v_cvt_pk_f32_fp8_e32 v[228:229], v155
	v_cvt_pk_f32_fp8_e32 v[230:231], v159
	v_pk_fma_f32 v[216:217], v[224:225], v[92:93], v[216:217]
	v_pk_fma_f32 v[218:219], v[226:227], v[92:93], v[218:219]
	v_pk_fma_f32 v[220:221], v[228:229], v[92:93], v[220:221]
	v_pk_fma_f32 v[222:223], v[230:231], v[92:93], v[222:223]
	v_cvt_pk_f32_fp8_sdwa v[224:225], v147 src0_sel:WORD_1
	v_cvt_pk_f32_fp8_sdwa v[226:227], v151 src0_sel:WORD_1
	v_cvt_pk_f32_fp8_sdwa v[228:229], v155 src0_sel:WORD_1
	v_cvt_pk_f32_fp8_sdwa v[230:231], v159 src0_sel:WORD_1
	v_pk_fma_f32 v[216:217], v[224:225], v[94:95], v[216:217]
	v_pk_fma_f32 v[218:219], v[226:227], v[94:95], v[218:219]
	v_pk_fma_f32 v[220:221], v[228:229], v[94:95], v[220:221]
	v_pk_fma_f32 v[222:223], v[230:231], v[94:95], v[222:223]
	v_add_f32_e32 v196, v216, v217
	v_add_f32_e32 v197, v218, v219
	v_add_f32_e32 v198, v220, v221
	v_add_f32_e32 v199, v222, v223
	s_sub_i32 s90, s90, 1
	s_cmp_eq_u32 s90, 0
	s_cbranch_scc1 .LU_sw2
.LU_t5_s2:
	s_waitcnt lgkmcnt(0)
	buffer_load_dwordx4 v[144:147], v[232:233], s[56:59], 0 idxen offen
	buffer_load_dwordx4 v[148:151], v[234:235], s[56:59], 0 idxen offen
	buffer_load_dwordx4 v[152:155], v[236:237], s[56:59], 0 idxen offen
	buffer_load_dwordx4 v[156:159], v[238:239], s[56:59], 0 idxen offen
	ds_read_b32 v232, v213 offset:96
	ds_read_b32 v234, v213 offset:100
	ds_read_b32 v236, v213 offset:104
	ds_read_b32 v238, v213 offset:108
	s_waitcnt vmcnt(12)
	v_cvt_pk_f32_fp8_e32 v[224:225], v160
	v_cvt_pk_f32_fp8_e32 v[226:227], v164
	v_cvt_pk_f32_fp8_e32 v[228:229], v168
	v_cvt_pk_f32_fp8_e32 v[230:231], v172
	v_pk_mul_f32 v[216:217], v[224:225], v[80:81]
	v_pk_mul_f32 v[218:219], v[226:227], v[80:81]
	v_pk_mul_f32 v[220:221], v[228:229], v[80:81]
	v_pk_mul_f32 v[222:223], v[230:231], v[80:81]
	v_cvt_pk_f32_fp8_sdwa v[224:225], v160 src0_sel:WORD_1
	v_cvt_pk_f32_fp8_sdwa v[226:227], v164 src0_sel:WORD_1
	v_cvt_pk_f32_fp8_sdwa v[228:229], v168 src0_sel:WORD_1
	v_cvt_pk_f32_fp8_sdwa v[230:231], v172 src0_sel:WORD_1
	v_pk_fma_f32 v[216:217], v[224:225], v[82:83], v[216:217]
	v_pk_fma_f32 v[218:219], v[226:227], v[82:83], v[218:219]
	v_pk_fma_f32 v[220:221], v[228:229], v[82:83], v[220:221]
	v_pk_fma_f32 v[222:223], v[230:231], v[82:83], v[222:223]
	v_cvt_pk_f32_fp8_e32 v[224:225], v161
	v_cvt_pk_f32_fp8_e32 v[226:227], v165
	v_cvt_pk_f32_fp8_e32 v[228:229], v169
	v_cvt_pk_f32_fp8_e32 v[230:231], v173
	v_pk_fma_f32 v[216:217], v[224:225], v[84:85], v[216:217]
	v_pk_fma_f32 v[218:219], v[226:227], v[84:85], v[218:219]
	v_pk_fma_f32 v[220:221], v[228:229], v[84:85], v[220:221]
	v_pk_fma_f32 v[222:223], v[230:231], v[84:85], v[222:223]
	v_cvt_pk_f32_fp8_sdwa v[224:225], v161 src0_sel:WORD_1
	v_cvt_pk_f32_fp8_sdwa v[226:227], v165 src0_sel:WORD_1
	v_cvt_pk_f32_fp8_sdwa v[228:229], v169 src0_sel:WORD_1
	v_cvt_pk_f32_fp8_sdwa v[230:231], v173 src0_sel:WORD_1
	v_pk_fma_f32 v[216:217], v[224:225], v[86:87], v[216:217]
	v_pk_fma_f32 v[218:219], v[226:227], v[86:87], v[218:219]
	v_pk_fma_f32 v[220:221], v[228:229], v[86:87], v[220:221]
	v_pk_fma_f32 v[222:223], v[230:231], v[86:87], v[222:223]
	v_cvt_pk_f32_fp8_e32 v[224:225], v162
	v_cvt_pk_f32_fp8_e32 v[226:227], v166
	v_cvt_pk_f32_fp8_e32 v[228:229], v170
	v_cvt_pk_f32_fp8_e32 v[230:231], v174
	v_pk_fma_f32 v[216:217], v[224:225], v[88:89], v[216:217]
	v_pk_fma_f32 v[218:219], v[226:227], v[88:89], v[218:219]
	v_pk_fma_f32 v[220:221], v[228:229], v[88:89], v[220:221]
	v_pk_fma_f32 v[222:223], v[230:231], v[88:89], v[222:223]
	v_cvt_pk_f32_fp8_sdwa v[224:225], v162 src0_sel:WORD_1
	v_cvt_pk_f32_fp8_sdwa v[226:227], v166 src0_sel:WORD_1
	v_cvt_pk_f32_fp8_sdwa v[228:229], v170 src0_sel:WORD_1
	v_cvt_pk_f32_fp8_sdwa v[230:231], v174 src0_sel:WORD_1
	v_pk_fma_f32 v[216:217], v[224:225], v[90:91], v[216:217]
	v_pk_fma_f32 v[218:219], v[226:227], v[90:91], v[218:219]
	v_pk_fma_f32 v[220:221], v[228:229], v[90:91], v[220:221]
	v_pk_fma_f32 v[222:223], v[230:231], v[90:91], v[222:223]
	v_cvt_pk_f32_fp8_e32 v[224:225], v163
	v_cvt_pk_f32_fp8_e32 v[226:227], v167
	v_cvt_pk_f32_fp8_e32 v[228:229], v171
	v_cvt_pk_f32_fp8_e32 v[230:231], v175
	v_pk_fma_f32 v[216:217], v[224:225], v[92:93], v[216:217]
	v_pk_fma_f32 v[218:219], v[226:227], v[92:93], v[218:219]
	v_pk_fma_f32 v[220:221], v[228:229], v[92:93], v[220:221]
	v_pk_fma_f32 v[222:223], v[230:231], v[92:93], v[222:223]
	v_cvt_pk_f32_fp8_sdwa v[224:225], v163 src0_sel:WORD_1
	v_cvt_pk_f32_fp8_sdwa v[226:227], v167 src0_sel:WORD_1
	v_cvt_pk_f32_fp8_sdwa v[228:229], v171 src0_sel:WORD_1
	v_cvt_pk_f32_fp8_sdwa v[230:231], v175 src0_sel:WORD_1
	v_pk_fma_f32 v[216:217], v[224:225], v[94:95], v[216:217]
	v_pk_fma_f32 v[218:219], v[226:227], v[94:95], v[218:219]
	v_pk_fma_f32 v[220:221], v[228:229], v[94:95], v[220:221]
	v_pk_fma_f32 v[222:223], v[230:231], v[94:95], v[222:223]
	v_add_f32_e32 v200, v216, v217
	v_add_f32_e32 v201, v218, v219
	v_add_f32_e32 v202, v220, v221
	v_add_f32_e32 v203, v222, v223
	s_sub_i32 s90, s90, 1
	s_cmp_eq_u32 s90, 0
	s_cbranch_scc1 .LU_sw3
.LU_t5_s3:
	s_waitcnt lgkmcnt(0)
	buffer_load_dwordx4 v[160:163], v[232:233], s[56:59], 0 idxen offen
	buffer_load_dwordx4 v[164:167], v[234:235], s[56:59], 0 idxen offen
	buffer_load_dwordx4 v[168:171], v[236:237], s[56:59], 0 idxen offen
	buffer_load_dwordx4 v[172:175], v[238:239], s[56:59], 0 idxen offen
	ds_read_b32 v232, v213 offset:112
	ds_read_b32 v234, v213 offset:116
	ds_read_b32 v236, v213 offset:120
	ds_read_b32 v238, v213 offset:124
	s_waitcnt vmcnt(12)
	v_cvt_pk_f32_fp8_e32 v[224:225], v176
	v_cvt_pk_f32_fp8_e32 v[226:227], v180
	v_cvt_pk_f32_fp8_e32 v[228:229], v184
	v_cvt_pk_f32_fp8_e32 v[230:231], v188
	v_pk_mul_f32 v[216:217], v[224:225], v[80:81]
	v_pk_mul_f32 v[218:219], v[226:227], v[80:81]
	v_pk_mul_f32 v[220:221], v[228:229], v[80:81]
	v_pk_mul_f32 v[222:223], v[230:231], v[80:81]
	v_cvt_pk_f32_fp8_sdwa v[224:225], v176 src0_sel:WORD_1
	v_cvt_pk_f32_fp8_sdwa v[226:227], v180 src0_sel:WORD_1
	v_cvt_pk_f32_fp8_sdwa v[228:229], v184 src0_sel:WORD_1
	v_cvt_pk_f32_fp8_sdwa v[230:231], v188 src0_sel:WORD_1
	v_pk_fma_f32 v[216:217], v[224:225], v[82:83], v[216:217]
	v_pk_fma_f32 v[218:219], v[226:227], v[82:83], v[218:219]
	v_pk_fma_f32 v[220:221], v[228:229], v[82:83], v[220:221]
	v_pk_fma_f32 v[222:223], v[230:231], v[82:83], v[222:223]
	v_cvt_pk_f32_fp8_e32 v[224:225], v177
	v_cvt_pk_f32_fp8_e32 v[226:227], v181
	v_cvt_pk_f32_fp8_e32 v[228:229], v185
	v_cvt_pk_f32_fp8_e32 v[230:231], v189
	v_pk_fma_f32 v[216:217], v[224:225], v[84:85], v[216:217]
	v_pk_fma_f32 v[218:219], v[226:227], v[84:85], v[218:219]
	v_pk_fma_f32 v[220:221], v[228:229], v[84:85], v[220:221]
	v_pk_fma_f32 v[222:223], v[230:231], v[84:85], v[222:223]
	v_cvt_pk_f32_fp8_sdwa v[224:225], v177 src0_sel:WORD_1
	v_cvt_pk_f32_fp8_sdwa v[226:227], v181 src0_sel:WORD_1
	v_cvt_pk_f32_fp8_sdwa v[228:229], v185 src0_sel:WORD_1
	v_cvt_pk_f32_fp8_sdwa v[230:231], v189 src0_sel:WORD_1
	v_pk_fma_f32 v[216:217], v[224:225], v[86:87], v[216:217]
	v_pk_fma_f32 v[218:219], v[226:227], v[86:87], v[218:219]
	v_pk_fma_f32 v[220:221], v[228:229], v[86:87], v[220:221]
; __device__ __forceinline__ float gelu_fast(float v) {
;     const float av = fabsf(v), tt = __builtin_amdgcn_rcpf(av * 0.2316418882f + 1.0f);
;     float q = tt * 0.5307027145f + (-0.7265760135f); q = q * tt + 0.7107068705f; q = q * tt + (-0.142248368f); q = q * tt + 0.127414796f; q = q * tt;
;     const float e = __builtin_amdgcn_exp2f((v * v) * (-0.72134752044f));
;     const float m = v * (q * e);
;     return v < 0.f ? m : v - m;
; }
	v_pk_fma_f32 v[222:223], v[230:231], v[86:87], v[222:223]
	v_cvt_pk_f32_fp8_e32 v[224:225], v178
	v_cvt_pk_f32_fp8_e32 v[226:227], v182
	v_cvt_pk_f32_fp8_e32 v[228:229], v186
	v_cvt_pk_f32_fp8_e32 v[230:231], v190
	v_pk_fma_f32 v[216:217], v[224:225], v[88:89], v[216:217]
	v_pk_fma_f32 v[218:219], v[226:227], v[88:89], v[218:219]
	v_pk_fma_f32 v[220:221], v[228:229], v[88:89], v[220:221]
	v_pk_fma_f32 v[222:223], v[230:231], v[88:89], v[222:223]
	v_cvt_pk_f32_fp8_sdwa v[224:225], v178 src0_sel:WORD_1
	v_cvt_pk_f32_fp8_sdwa v[226:227], v182 src0_sel:WORD_1
	v_cvt_pk_f32_fp8_sdwa v[228:229], v186 src0_sel:WORD_1
	v_cvt_pk_f32_fp8_sdwa v[230:231], v190 src0_sel:WORD_1
	v_pk_fma_f32 v[216:217], v[224:225], v[90:91], v[216:217]
	v_pk_fma_f32 v[218:219], v[226:227], v[90:91], v[218:219]
	v_pk_fma_f32 v[220:221], v[228:229], v[90:91], v[220:221]
	v_pk_fma_f32 v[222:223], v[230:231], v[90:91], v[222:223]
	v_cvt_pk_f32_fp8_e32 v[224:225], v179
	v_cvt_pk_f32_fp8_e32 v[226:227], v183
	v_cvt_pk_f32_fp8_e32 v[228:229], v187
	v_cvt_pk_f32_fp8_e32 v[230:231], v191
	v_pk_fma_f32 v[216:217], v[224:225], v[92:93], v[216:217]
	v_pk_fma_f32 v[218:219], v[226:227], v[92:93], v[218:219]
	v_pk_fma_f32 v[220:221], v[228:229], v[92:93], v[220:221]
	v_pk_fma_f32 v[222:223], v[230:231], v[92:93], v[222:223]
	v_cvt_pk_f32_fp8_sdwa v[224:225], v179 src0_sel:WORD_1
	v_cvt_pk_f32_fp8_sdwa v[226:227], v183 src0_sel:WORD_1
	v_cvt_pk_f32_fp8_sdwa v[228:229], v187 src0_sel:WORD_1
	v_cvt_pk_f32_fp8_sdwa v[230:231], v191 src0_sel:WORD_1
	v_pk_fma_f32 v[216:217], v[224:225], v[94:95], v[216:217]
	v_pk_fma_f32 v[218:219], v[226:227], v[94:95], v[218:219]
	v_pk_fma_f32 v[220:221], v[228:229], v[94:95], v[220:221]
	v_pk_fma_f32 v[222:223], v[230:231], v[94:95], v[222:223]
	v_add_f32_e32 v204, v216, v217
	v_add_f32_e32 v205, v218, v219
	v_add_f32_e32 v206, v220, v221
	v_add_f32_e32 v207, v222, v223
	s_nop 0
	v_permlane32_swap_b32_e32 v192, v200
	v_permlane32_swap_b32_e32 v193, v201
	v_permlane32_swap_b32_e32 v194, v202
	v_permlane32_swap_b32_e32 v195, v203
	v_permlane32_swap_b32_e32 v196, v204
	v_permlane32_swap_b32_e32 v197, v205
	v_permlane32_swap_b32_e32 v198, v206
	v_permlane32_swap_b32_e32 v199, v207
	v_add_f32_e32 v192, v192, v200
	v_add_f32_e32 v193, v193, v201
	v_add_f32_e32 v194, v194, v202
	v_add_f32_e32 v195, v195, v203
	v_add_f32_e32 v196, v196, v204
	v_add_f32_e32 v197, v197, v205
	v_add_f32_e32 v198, v198, v206
	v_add_f32_e32 v199, v199, v207
	v_permlane16_swap_b32_e32 v192, v196
	v_permlane16_swap_b32_e32 v193, v197
	v_permlane16_swap_b32_e32 v194, v198
	v_permlane16_swap_b32_e32 v195, v199
	v_add_f32_e32 v192, v192, v196
	v_add_f32_e32 v193, v193, v197
	v_add_f32_e32 v194, v194, v198
	v_add_f32_e32 v195, v195, v199
	v_add_f32_dpp v216, v192, v192 row_ror:8 row_mask:0xf bank_mask:0xf
	v_add_f32_dpp v218, v194, v194 row_ror:8 row_mask:0xf bank_mask:0xf
	v_add_f32_dpp v216, v193, v193 row_ror:8 row_mask:0xf bank_mask:0xc
	v_add_f32_dpp v218, v195, v195 row_ror:8 row_mask:0xf bank_mask:0xc
	s_nop 1
	v_add_f32_dpp v220, v216, v216 row_half_mirror row_mask:0xf bank_mask:0xf
	v_add_f32_dpp v220, v218, v218 row_half_mirror row_mask:0xf bank_mask:0xa
	s_nop 1
	v_add_f32_dpp v220, v220, v220 quad_perm:[1,0,3,2] row_mask:0xf bank_mask:0xf
	s_nop 1
	v_add_f32_dpp v220, v220, v220 quad_perm:[2,3,0,1] row_mask:0xf bank_mask:0xf
	v_mul_f32_e32 v216, v252, v220
	v_fma_f32 v218, |v216|, s72, 1.0
	v_mul_f32_e32 v222, v216, v216
	v_rcp_f32_e32 v218, v218
	v_mul_f32_e32 v222, 0xbf38aa3b, v222
	v_exp_f32_e32 v222, v222
	v_fmamk_f32 v224, v218, 0x3f07dc22, v242
	v_fmaak_f32 v224, v218, v224, 0x3f35f0e3
	v_fmaak_f32 v224, v218, v224, 0xbe11a98e
	v_fmaak_f32 v224, v218, v224, 0x3e027906
	v_mul_f32_e32 v224, v218, v224
	v_mul_f32_e32 v224, v222, v224
	v_mul_f32_e32 v226, v216, v224
	v_fma_f32 v224, -v216, v224, v216
	v_cmp_gt_f32_e32 vcc, 0, v216
	s_nop 1
	v_cndmask_b32_e32 v224, v224, v226, vcc
	v_mul_f32_e32 v224, v249, v224
	v_mul_f32_e32 v224, v253, v224
	ds_write_b32 v211, v224 offset:4992
	v_add_u32_e32 v211, 64, v211
	v_add_u32_e32 v213, 64, v213
	v_add_u32_e32 v250, 64, v250
	ds_read_b32 v252, v250
	ds_read_b32 v253, v250 offset:4096
	ds_read_b32 v249, v211 offset:4992
	s_add_i32 s21, s21, 4
	s_sub_i32 s90, s90, 1
	s_cmp_eq_u32 s90, 0
	s_cbranch_scc1 .LU_sw0
	s_branch .LU_t5_s0
.LU_t6_s0:
	s_cmp_ge_u32 s21, s20
	s_cbranch_scc1 .LU_done
	s_waitcnt lgkmcnt(0)
	buffer_load_dwordx4 v[176:179], v[232:233], s[56:59], 0 idxen offen
	buffer_load_dwordx4 v[180:183], v[234:235], s[56:59], 0 idxen offen
	buffer_load_dwordx4 v[184:187], v[236:237], s[56:59], 0 idxen offen
	buffer_load_dwordx4 v[188:191], v[238:239], s[56:59], 0 idxen offen
	ds_read_b32 v232, v213 offset:64
	ds_read_b32 v234, v213 offset:68
	ds_read_b32 v236, v213 offset:72
	ds_read_b32 v238, v213 offset:76
	s_waitcnt vmcnt(12)
	v_cvt_pk_f32_fp8_e32 v[224:225], v128
	v_cvt_pk_f32_fp8_e32 v[226:227], v132
	v_cvt_pk_f32_fp8_e32 v[228:229], v136
	v_cvt_pk_f32_fp8_e32 v[230:231], v140
	v_pk_mul_f32 v[216:217], v[224:225], v[96:97]
	v_pk_mul_f32 v[218:219], v[226:227], v[96:97]
	v_pk_mul_f32 v[220:221], v[228:229], v[96:97]
	v_pk_mul_f32 v[222:223], v[230:231], v[96:97]
	v_cvt_pk_f32_fp8_sdwa v[224:225], v128 src0_sel:WORD_1
	v_cvt_pk_f32_fp8_sdwa v[226:227], v132 src0_sel:WORD_1
	v_cvt_pk_f32_fp8_sdwa v[228:229], v136 src0_sel:WORD_1
	v_cvt_pk_f32_fp8_sdwa v[230:231], v140 src0_sel:WORD_1
	v_pk_fma_f32 v[216:217], v[224:225], v[98:99], v[216:217]
	v_pk_fma_f32 v[218:219], v[226:227], v[98:99], v[218:219]
	v_pk_fma_f32 v[220:221], v[228:229], v[98:99], v[220:221]
	v_pk_fma_f32 v[222:223], v[230:231], v[98:99], v[222:223]
	v_cvt_pk_f32_fp8_e32 v[224:225], v129
	v_cvt_pk_f32_fp8_e32 v[226:227], v133
	v_cvt_pk_f32_fp8_e32 v[228:229], v137
	v_cvt_pk_f32_fp8_e32 v[230:231], v141
	v_pk_fma_f32 v[216:217], v[224:225], v[100:101], v[216:217]
	v_pk_fma_f32 v[218:219], v[226:227], v[100:101], v[218:219]
	v_pk_fma_f32 v[220:221], v[228:229], v[100:101], v[220:221]
	v_pk_fma_f32 v[222:223], v[230:231], v[100:101], v[222:223]
	v_cvt_pk_f32_fp8_sdwa v[224:225], v129 src0_sel:WORD_1
	v_cvt_pk_f32_fp8_sdwa v[226:227], v133 src0_sel:WORD_1
	v_cvt_pk_f32_fp8_sdwa v[228:229], v137 src0_sel:WORD_1
	v_cvt_pk_f32_fp8_sdwa v[230:231], v141 src0_sel:WORD_1
	v_pk_fma_f32 v[216:217], v[224:225], v[102:103], v[216:217]
	v_pk_fma_f32 v[218:219], v[226:227], v[102:103], v[218:219]
	v_pk_fma_f32 v[220:221], v[228:229], v[102:103], v[220:221]
	v_pk_fma_f32 v[222:223], v[230:231], v[102:103], v[222:223]
	v_cvt_pk_f32_fp8_e32 v[224:225], v130
	v_cvt_pk_f32_fp8_e32 v[226:227], v134
	v_cvt_pk_f32_fp8_e32 v[228:229], v138
	v_cvt_pk_f32_fp8_e32 v[230:231], v142
	v_pk_fma_f32 v[216:217], v[224:225], v[104:105], v[216:217]
	v_pk_fma_f32 v[218:219], v[226:227], v[104:105], v[218:219]
	v_pk_fma_f32 v[220:221], v[228:229], v[104:105], v[220:221]
	v_pk_fma_f32 v[222:223], v[230:231], v[104:105], v[222:223]
	v_cvt_pk_f32_fp8_sdwa v[224:225], v130 src0_sel:WORD_1
	v_cvt_pk_f32_fp8_sdwa v[226:227], v134 src0_sel:WORD_1
	v_cvt_pk_f32_fp8_sdwa v[228:229], v138 src0_sel:WORD_1
	v_cvt_pk_f32_fp8_sdwa v[230:231], v142 src0_sel:WORD_1
	v_pk_fma_f32 v[216:217], v[224:225], v[106:107], v[216:217]
	v_pk_fma_f32 v[218:219], v[226:227], v[106:107], v[218:219]
	v_pk_fma_f32 v[220:221], v[228:229], v[106:107], v[220:221]
	v_pk_fma_f32 v[222:223], v[230:231], v[106:107], v[222:223]
	v_cvt_pk_f32_fp8_e32 v[224:225], v131
	v_cvt_pk_f32_fp8_e32 v[226:227], v135
	v_cvt_pk_f32_fp8_e32 v[228:229], v139
	v_cvt_pk_f32_fp8_e32 v[230:231], v143
	v_pk_fma_f32 v[216:217], v[224:225], v[108:109], v[216:217]
	v_pk_fma_f32 v[218:219], v[226:227], v[108:109], v[218:219]
	v_pk_fma_f32 v[220:221], v[228:229], v[108:109], v[220:221]
	v_pk_fma_f32 v[222:223], v[230:231], v[108:109], v[222:223]
	v_cvt_pk_f32_fp8_sdwa v[224:225], v131 src0_sel:WORD_1
	v_cvt_pk_f32_fp8_sdwa v[226:227], v135 src0_sel:WORD_1
	v_cvt_pk_f32_fp8_sdwa v[228:229], v139 src0_sel:WORD_1
	v_cvt_pk_f32_fp8_sdwa v[230:231], v143 src0_sel:WORD_1
	v_pk_fma_f32 v[216:217], v[224:225], v[110:111], v[216:217]
	v_pk_fma_f32 v[218:219], v[226:227], v[110:111], v[218:219]
	v_pk_fma_f32 v[220:221], v[228:229], v[110:111], v[220:221]
	v_pk_fma_f32 v[222:223], v[230:231], v[110:111], v[222:223]
	v_add_f32_e32 v192, v216, v217
	v_add_f32_e32 v193, v218, v219
	v_add_f32_e32 v194, v220, v221
	v_add_f32_e32 v195, v222, v223
	s_sub_i32 s90, s90, 1
	s_cmp_eq_u32 s90, 0
	s_cbranch_scc1 .LU_sw1
.LU_t6_s1:
	s_waitcnt lgkmcnt(0)
	buffer_load_dwordx4 v[128:131], v[232:233], s[56:59], 0 idxen offen
	buffer_load_dwordx4 v[132:135], v[234:235], s[56:59], 0 idxen offen
	buffer_load_dwordx4 v[136:139], v[236:237], s[56:59], 0 idxen offen
	buffer_load_dwordx4 v[140:143], v[238:239], s[56:59], 0 idxen offen
	ds_read_b32 v232, v213 offset:80
	ds_read_b32 v234, v213 offset:84
	ds_read_b32 v236, v213 offset:88
	ds_read_b32 v238, v213 offset:92
	s_waitcnt vmcnt(12)
	v_cvt_pk_f32_fp8_e32 v[224:225], v144
	v_cvt_pk_f32_fp8_e32 v[226:227], v148
	v_cvt_pk_f32_fp8_e32 v[228:229], v152
	v_cvt_pk_f32_fp8_e32 v[230:231], v156
	v_pk_mul_f32 v[216:217], v[224:225], v[96:97]
	v_pk_mul_f32 v[218:219], v[226:227], v[96:97]
	v_pk_mul_f32 v[220:221], v[228:229], v[96:97]
	v_pk_mul_f32 v[222:223], v[230:231], v[96:97]
	v_cvt_pk_f32_fp8_sdwa v[224:225], v144 src0_sel:WORD_1
	v_cvt_pk_f32_fp8_sdwa v[226:227], v148 src0_sel:WORD_1
	v_cvt_pk_f32_fp8_sdwa v[228:229], v152 src0_sel:WORD_1
	v_cvt_pk_f32_fp8_sdwa v[230:231], v156 src0_sel:WORD_1
	v_pk_fma_f32 v[216:217], v[224:225], v[98:99], v[216:217]
	v_pk_fma_f32 v[218:219], v[226:227], v[98:99], v[218:219]
	v_pk_fma_f32 v[220:221], v[228:229], v[98:99], v[220:221]
	v_pk_fma_f32 v[222:223], v[230:231], v[98:99], v[222:223]
	v_cvt_pk_f32_fp8_e32 v[224:225], v145
	v_cvt_pk_f32_fp8_e32 v[226:227], v149
	v_cvt_pk_f32_fp8_e32 v[228:229], v153
	v_cvt_pk_f32_fp8_e32 v[230:231], v157
	v_pk_fma_f32 v[216:217], v[224:225], v[100:101], v[216:217]
	v_pk_fma_f32 v[218:219], v[226:227], v[100:101], v[218:219]
	v_pk_fma_f32 v[220:221], v[228:229], v[100:101], v[220:221]
	v_pk_fma_f32 v[222:223], v[230:231], v[100:101], v[222:223]
	v_cvt_pk_f32_fp8_sdwa v[224:225], v145 src0_sel:WORD_1
	v_cvt_pk_f32_fp8_sdwa v[226:227], v149 src0_sel:WORD_1
	v_cvt_pk_f32_fp8_sdwa v[228:229], v153 src0_sel:WORD_1
	v_cvt_pk_f32_fp8_sdwa v[230:231], v157 src0_sel:WORD_1
	v_pk_fma_f32 v[216:217], v[224:225], v[102:103], v[216:217]
	v_pk_fma_f32 v[218:219], v[226:227], v[102:103], v[218:219]
	v_pk_fma_f32 v[220:221], v[228:229], v[102:103], v[220:221]
	v_pk_fma_f32 v[222:223], v[230:231], v[102:103], v[222:223]
	v_cvt_pk_f32_fp8_e32 v[224:225], v146
	v_cvt_pk_f32_fp8_e32 v[226:227], v150
	v_cvt_pk_f32_fp8_e32 v[228:229], v154
	v_cvt_pk_f32_fp8_e32 v[230:231], v158
	v_pk_fma_f32 v[216:217], v[224:225], v[104:105], v[216:217]
	v_pk_fma_f32 v[218:219], v[226:227], v[104:105], v[218:219]
	v_pk_fma_f32 v[220:221], v[228:229], v[104:105], v[220:221]
	v_pk_fma_f32 v[222:223], v[230:231], v[104:105], v[222:223]
	v_cvt_pk_f32_fp8_sdwa v[224:225], v146 src0_sel:WORD_1
	v_cvt_pk_f32_fp8_sdwa v[226:227], v150 src0_sel:WORD_1
	v_cvt_pk_f32_fp8_sdwa v[228:229], v154 src0_sel:WORD_1
	v_cvt_pk_f32_fp8_sdwa v[230:231], v158 src0_sel:WORD_1
	v_pk_fma_f32 v[216:217], v[224:225], v[106:107], v[216:217]
	v_pk_fma_f32 v[218:219], v[226:227], v[106:107], v[218:219]
	v_pk_fma_f32 v[220:221], v[228:229], v[106:107], v[220:221]
	v_pk_fma_f32 v[222:223], v[230:231], v[106:107], v[222:223]
	v_cvt_pk_f32_fp8_e32 v[224:225], v147
	v_cvt_pk_f32_fp8_e32 v[226:227], v151
	v_cvt_pk_f32_fp8_e32 v[228:229], v155
	v_cvt_pk_f32_fp8_e32 v[230:231], v159
	v_pk_fma_f32 v[216:217], v[224:225], v[108:109], v[216:217]
	v_pk_fma_f32 v[218:219], v[226:227], v[108:109], v[218:219]
	v_pk_fma_f32 v[220:221], v[228:229], v[108:109], v[220:221]
	v_pk_fma_f32 v[222:223], v[230:231], v[108:109], v[222:223]
	v_cvt_pk_f32_fp8_sdwa v[224:225], v147 src0_sel:WORD_1
	v_cvt_pk_f32_fp8_sdwa v[226:227], v151 src0_sel:WORD_1
	v_cvt_pk_f32_fp8_sdwa v[228:229], v155 src0_sel:WORD_1
	v_cvt_pk_f32_fp8_sdwa v[230:231], v159 src0_sel:WORD_1
	v_pk_fma_f32 v[216:217], v[224:225], v[110:111], v[216:217]
	v_pk_fma_f32 v[218:219], v[226:227], v[110:111], v[218:219]
	v_pk_fma_f32 v[220:221], v[228:229], v[110:111], v[220:221]
	v_pk_fma_f32 v[222:223], v[230:231], v[110:111], v[222:223]
	v_add_f32_e32 v196, v216, v217
	v_add_f32_e32 v197, v218, v219
	v_add_f32_e32 v198, v220, v221
	v_add_f32_e32 v199, v222, v223
	s_sub_i32 s90, s90, 1
	s_cmp_eq_u32 s90, 0
	s_cbranch_scc1 .LU_sw2
.LU_t6_s2:
	s_waitcnt lgkmcnt(0)
	buffer_load_dwordx4 v[144:147], v[232:233], s[56:59], 0 idxen offen
	buffer_load_dwordx4 v[148:151], v[234:235], s[56:59], 0 idxen offen
	buffer_load_dwordx4 v[152:155], v[236:237], s[56:59], 0 idxen offen
	buffer_load_dwordx4 v[156:159], v[238:239], s[56:59], 0 idxen offen
	ds_read_b32 v232, v213 offset:96
	ds_read_b32 v234, v213 offset:100
	ds_read_b32 v236, v213 offset:104
	ds_read_b32 v238, v213 offset:108
	s_waitcnt vmcnt(12)
	v_cvt_pk_f32_fp8_e32 v[224:225], v160
	v_cvt_pk_f32_fp8_e32 v[226:227], v164
	v_cvt_pk_f32_fp8_e32 v[228:229], v168
	v_cvt_pk_f32_fp8_e32 v[230:231], v172
	v_pk_mul_f32 v[216:217], v[224:225], v[96:97]
	v_pk_mul_f32 v[218:219], v[226:227], v[96:97]
	v_pk_mul_f32 v[220:221], v[228:229], v[96:97]
	v_pk_mul_f32 v[222:223], v[230:231], v[96:97]
	v_cvt_pk_f32_fp8_sdwa v[224:225], v160 src0_sel:WORD_1
	v_cvt_pk_f32_fp8_sdwa v[226:227], v164 src0_sel:WORD_1
	v_cvt_pk_f32_fp8_sdwa v[228:229], v168 src0_sel:WORD_1
	v_cvt_pk_f32_fp8_sdwa v[230:231], v172 src0_sel:WORD_1
	v_pk_fma_f32 v[216:217], v[224:225], v[98:99], v[216:217]
	v_pk_fma_f32 v[218:219], v[226:227], v[98:99], v[218:219]
	v_pk_fma_f32 v[220:221], v[228:229], v[98:99], v[220:221]
	v_pk_fma_f32 v[222:223], v[230:231], v[98:99], v[222:223]
	v_cvt_pk_f32_fp8_e32 v[224:225], v161
	v_cvt_pk_f32_fp8_e32 v[226:227], v165
	v_cvt_pk_f32_fp8_e32 v[228:229], v169
	v_cvt_pk_f32_fp8_e32 v[230:231], v173
	v_pk_fma_f32 v[216:217], v[224:225], v[100:101], v[216:217]
	v_pk_fma_f32 v[218:219], v[226:227], v[100:101], v[218:219]
	v_pk_fma_f32 v[220:221], v[228:229], v[100:101], v[220:221]
	v_pk_fma_f32 v[222:223], v[230:231], v[100:101], v[222:223]
	v_cvt_pk_f32_fp8_sdwa v[224:225], v161 src0_sel:WORD_1
	v_cvt_pk_f32_fp8_sdwa v[226:227], v165 src0_sel:WORD_1
	v_cvt_pk_f32_fp8_sdwa v[228:229], v169 src0_sel:WORD_1
	v_cvt_pk_f32_fp8_sdwa v[230:231], v173 src0_sel:WORD_1
	v_pk_fma_f32 v[216:217], v[224:225], v[102:103], v[216:217]
	v_pk_fma_f32 v[218:219], v[226:227], v[102:103], v[218:219]
	v_pk_fma_f32 v[220:221], v[228:229], v[102:103], v[220:221]
	v_pk_fma_f32 v[222:223], v[230:231], v[102:103], v[222:223]
	v_cvt_pk_f32_fp8_e32 v[224:225], v162
	v_cvt_pk_f32_fp8_e32 v[226:227], v166
	v_cvt_pk_f32_fp8_e32 v[228:229], v170
	v_cvt_pk_f32_fp8_e32 v[230:231], v174
	v_pk_fma_f32 v[216:217], v[224:225], v[104:105], v[216:217]
	v_pk_fma_f32 v[218:219], v[226:227], v[104:105], v[218:219]
	v_pk_fma_f32 v[220:221], v[228:229], v[104:105], v[220:221]
	v_pk_fma_f32 v[222:223], v[230:231], v[104:105], v[222:223]
	v_cvt_pk_f32_fp8_sdwa v[224:225], v162 src0_sel:WORD_1
	v_cvt_pk_f32_fp8_sdwa v[226:227], v166 src0_sel:WORD_1
	v_cvt_pk_f32_fp8_sdwa v[228:229], v170 src0_sel:WORD_1
	v_cvt_pk_f32_fp8_sdwa v[230:231], v174 src0_sel:WORD_1
	v_pk_fma_f32 v[216:217], v[224:225], v[106:107], v[216:217]
	v_pk_fma_f32 v[218:219], v[226:227], v[106:107], v[218:219]
	v_pk_fma_f32 v[220:221], v[228:229], v[106:107], v[220:221]
	v_pk_fma_f32 v[222:223], v[230:231], v[106:107], v[222:223]
	v_cvt_pk_f32_fp8_e32 v[224:225], v163
	v_cvt_pk_f32_fp8_e32 v[226:227], v167
	v_cvt_pk_f32_fp8_e32 v[228:229], v171
	v_cvt_pk_f32_fp8_e32 v[230:231], v175
	v_pk_fma_f32 v[216:217], v[224:225], v[108:109], v[216:217]
	v_pk_fma_f32 v[218:219], v[226:227], v[108:109], v[218:219]
	v_pk_fma_f32 v[220:221], v[228:229], v[108:109], v[220:221]
	v_pk_fma_f32 v[222:223], v[230:231], v[108:109], v[222:223]
	v_cvt_pk_f32_fp8_sdwa v[224:225], v163 src0_sel:WORD_1
	v_cvt_pk_f32_fp8_sdwa v[226:227], v167 src0_sel:WORD_1
	v_cvt_pk_f32_fp8_sdwa v[228:229], v171 src0_sel:WORD_1
	v_cvt_pk_f32_fp8_sdwa v[230:231], v175 src0_sel:WORD_1
	v_pk_fma_f32 v[216:217], v[224:225], v[110:111], v[216:217]
	v_pk_fma_f32 v[218:219], v[226:227], v[110:111], v[218:219]
	v_pk_fma_f32 v[220:221], v[228:229], v[110:111], v[220:221]
	v_pk_fma_f32 v[222:223], v[230:231], v[110:111], v[222:223]
	v_add_f32_e32 v200, v216, v217
	v_add_f32_e32 v201, v218, v219
	v_add_f32_e32 v202, v220, v221
	v_add_f32_e32 v203, v222, v223
	s_sub_i32 s90, s90, 1
	s_cmp_eq_u32 s90, 0
	s_cbranch_scc1 .LU_sw3
.LU_t6_s3:
	s_waitcnt lgkmcnt(0)
	buffer_load_dwordx4 v[160:163], v[232:233], s[56:59], 0 idxen offen
	buffer_load_dwordx4 v[164:167], v[234:235], s[56:59], 0 idxen offen
	buffer_load_dwordx4 v[168:171], v[236:237], s[56:59], 0 idxen offen
	buffer_load_dwordx4 v[172:175], v[238:239], s[56:59], 0 idxen offen
	ds_read_b32 v232, v213 offset:112
	ds_read_b32 v234, v213 offset:116
	ds_read_b32 v236, v213 offset:120
	ds_read_b32 v238, v213 offset:124
	s_waitcnt vmcnt(12)
	v_cvt_pk_f32_fp8_e32 v[224:225], v176
	v_cvt_pk_f32_fp8_e32 v[226:227], v180
	v_cvt_pk_f32_fp8_e32 v[228:229], v184
	v_cvt_pk_f32_fp8_e32 v[230:231], v188
	v_pk_mul_f32 v[216:217], v[224:225], v[96:97]
	v_pk_mul_f32 v[218:219], v[226:227], v[96:97]
	v_pk_mul_f32 v[220:221], v[228:229], v[96:97]
	v_pk_mul_f32 v[222:223], v[230:231], v[96:97]
	v_cvt_pk_f32_fp8_sdwa v[224:225], v176 src0_sel:WORD_1
	v_cvt_pk_f32_fp8_sdwa v[226:227], v180 src0_sel:WORD_1
	v_cvt_pk_f32_fp8_sdwa v[228:229], v184 src0_sel:WORD_1
	v_cvt_pk_f32_fp8_sdwa v[230:231], v188 src0_sel:WORD_1
	v_pk_fma_f32 v[216:217], v[224:225], v[98:99], v[216:217]
	v_pk_fma_f32 v[218:219], v[226:227], v[98:99], v[218:219]
	v_pk_fma_f32 v[220:221], v[228:229], v[98:99], v[220:221]
	v_pk_fma_f32 v[222:223], v[230:231], v[98:99], v[222:223]
	v_cvt_pk_f32_fp8_e32 v[224:225], v177
	v_cvt_pk_f32_fp8_e32 v[226:227], v181
	v_cvt_pk_f32_fp8_e32 v[228:229], v185
	v_cvt_pk_f32_fp8_e32 v[230:231], v189
	v_pk_fma_f32 v[216:217], v[224:225], v[100:101], v[216:217]
	v_pk_fma_f32 v[218:219], v[226:227], v[100:101], v[218:219]
	v_pk_fma_f32 v[220:221], v[228:229], v[100:101], v[220:221]
	v_pk_fma_f32 v[222:223], v[230:231], v[100:101], v[222:223]
	v_cvt_pk_f32_fp8_sdwa v[224:225], v177 src0_sel:WORD_1
	v_cvt_pk_f32_fp8_sdwa v[226:227], v181 src0_sel:WORD_1
	v_cvt_pk_f32_fp8_sdwa v[228:229], v185 src0_sel:WORD_1
	v_cvt_pk_f32_fp8_sdwa v[230:231], v189 src0_sel:WORD_1
	v_pk_fma_f32 v[216:217], v[224:225], v[102:103], v[216:217]
	v_pk_fma_f32 v[218:219], v[226:227], v[102:103], v[218:219]
	v_pk_fma_f32 v[220:221], v[228:229], v[102:103], v[220:221]
	v_pk_fma_f32 v[222:223], v[230:231], v[102:103], v[222:223]
	v_cvt_pk_f32_fp8_e32 v[224:225], v178
	v_cvt_pk_f32_fp8_e32 v[226:227], v182
	v_cvt_pk_f32_fp8_e32 v[228:229], v186
	v_cvt_pk_f32_fp8_e32 v[230:231], v190
	v_pk_fma_f32 v[216:217], v[224:225], v[104:105], v[216:217]
	v_pk_fma_f32 v[218:219], v[226:227], v[104:105], v[218:219]
	v_pk_fma_f32 v[220:221], v[228:229], v[104:105], v[220:221]
	v_pk_fma_f32 v[222:223], v[230:231], v[104:105], v[222:223]
	v_cvt_pk_f32_fp8_sdwa v[224:225], v178 src0_sel:WORD_1
	v_cvt_pk_f32_fp8_sdwa v[226:227], v182 src0_sel:WORD_1
	v_cvt_pk_f32_fp8_sdwa v[228:229], v186 src0_sel:WORD_1
	v_cvt_pk_f32_fp8_sdwa v[230:231], v190 src0_sel:WORD_1
	v_pk_fma_f32 v[216:217], v[224:225], v[106:107], v[216:217]
	v_pk_fma_f32 v[218:219], v[226:227], v[106:107], v[218:219]
	v_pk_fma_f32 v[220:221], v[228:229], v[106:107], v[220:221]
	v_pk_fma_f32 v[222:223], v[230:231], v[106:107], v[222:223]
	v_cvt_pk_f32_fp8_e32 v[224:225], v179
	v_cvt_pk_f32_fp8_e32 v[226:227], v183
	v_cvt_pk_f32_fp8_e32 v[228:229], v187
	v_cvt_pk_f32_fp8_e32 v[230:231], v191
	v_pk_fma_f32 v[216:217], v[224:225], v[108:109], v[216:217]
	v_pk_fma_f32 v[218:219], v[226:227], v[108:109], v[218:219]
	v_pk_fma_f32 v[220:221], v[228:229], v[108:109], v[220:221]
	v_pk_fma_f32 v[222:223], v[230:231], v[108:109], v[222:223]
	v_cvt_pk_f32_fp8_sdwa v[224:225], v179 src0_sel:WORD_1
	v_cvt_pk_f32_fp8_sdwa v[226:227], v183 src0_sel:WORD_1
	v_cvt_pk_f32_fp8_sdwa v[228:229], v187 src0_sel:WORD_1
; __device__ __forceinline__ float gelu_fast(float v) {
;     const float av = fabsf(v), tt = __builtin_amdgcn_rcpf(av * 0.2316418882f + 1.0f);
;     float q = tt * 0.5307027145f + (-0.7265760135f); q = q * tt + 0.7107068705f; q = q * tt + (-0.142248368f); q = q * tt + 0.127414796f; q = q * tt;
;     const float e = __builtin_amdgcn_exp2f((v * v) * (-0.72134752044f));
;     const float m = v * (q * e);
;     return v < 0.f ? m : v - m;
; }
	v_cvt_pk_f32_fp8_sdwa v[230:231], v191 src0_sel:WORD_1
	v_pk_fma_f32 v[216:217], v[224:225], v[110:111], v[216:217]
	v_pk_fma_f32 v[218:219], v[226:227], v[110:111], v[218:219]
	v_pk_fma_f32 v[220:221], v[228:229], v[110:111], v[220:221]
	v_pk_fma_f32 v[222:223], v[230:231], v[110:111], v[222:223]
	v_add_f32_e32 v204, v216, v217
	v_add_f32_e32 v205, v218, v219
	v_add_f32_e32 v206, v220, v221
	v_add_f32_e32 v207, v222, v223
	s_nop 0
	v_permlane32_swap_b32_e32 v192, v200
	v_permlane32_swap_b32_e32 v193, v201
	v_permlane32_swap_b32_e32 v194, v202
	v_permlane32_swap_b32_e32 v195, v203
	v_permlane32_swap_b32_e32 v196, v204
	v_permlane32_swap_b32_e32 v197, v205
	v_permlane32_swap_b32_e32 v198, v206
	v_permlane32_swap_b32_e32 v199, v207
	v_add_f32_e32 v192, v192, v200
	v_add_f32_e32 v193, v193, v201
	v_add_f32_e32 v194, v194, v202
	v_add_f32_e32 v195, v195, v203
	v_add_f32_e32 v196, v196, v204
	v_add_f32_e32 v197, v197, v205
	v_add_f32_e32 v198, v198, v206
	v_add_f32_e32 v199, v199, v207
	v_permlane16_swap_b32_e32 v192, v196
	v_permlane16_swap_b32_e32 v193, v197
	v_permlane16_swap_b32_e32 v194, v198
	v_permlane16_swap_b32_e32 v195, v199
	v_add_f32_e32 v192, v192, v196
	v_add_f32_e32 v193, v193, v197
	v_add_f32_e32 v194, v194, v198
	v_add_f32_e32 v195, v195, v199
	v_add_f32_dpp v216, v192, v192 row_ror:8 row_mask:0xf bank_mask:0xf
	v_add_f32_dpp v218, v194, v194 row_ror:8 row_mask:0xf bank_mask:0xf
	v_add_f32_dpp v216, v193, v193 row_ror:8 row_mask:0xf bank_mask:0xc
	v_add_f32_dpp v218, v195, v195 row_ror:8 row_mask:0xf bank_mask:0xc
	s_nop 1
	v_add_f32_dpp v220, v216, v216 row_half_mirror row_mask:0xf bank_mask:0xf
	v_add_f32_dpp v220, v218, v218 row_half_mirror row_mask:0xf bank_mask:0xa
	s_nop 1
	v_add_f32_dpp v220, v220, v220 quad_perm:[1,0,3,2] row_mask:0xf bank_mask:0xf
	s_nop 1
	v_add_f32_dpp v220, v220, v220 quad_perm:[2,3,0,1] row_mask:0xf bank_mask:0xf
	v_mul_f32_e32 v216, v252, v220
	v_fma_f32 v218, |v216|, s72, 1.0
	v_mul_f32_e32 v222, v216, v216
	v_rcp_f32_e32 v218, v218
	v_mul_f32_e32 v222, 0xbf38aa3b, v222
	v_exp_f32_e32 v222, v222
	v_fmamk_f32 v224, v218, 0x3f07dc22, v242
	v_fmaak_f32 v224, v218, v224, 0x3f35f0e3
	v_fmaak_f32 v224, v218, v224, 0xbe11a98e
	v_fmaak_f32 v224, v218, v224, 0x3e027906
	v_mul_f32_e32 v224, v218, v224
	v_mul_f32_e32 v224, v222, v224
	v_mul_f32_e32 v226, v216, v224
	v_fma_f32 v224, -v216, v224, v216
	v_cmp_gt_f32_e32 vcc, 0, v216
	s_nop 1
	v_cndmask_b32_e32 v224, v224, v226, vcc
	v_mul_f32_e32 v224, v249, v224
	v_mul_f32_e32 v224, v253, v224
	ds_write_b32 v211, v224 offset:4992
	v_add_u32_e32 v211, 64, v211
	v_add_u32_e32 v213, 64, v213
	v_add_u32_e32 v250, 64, v250
	ds_read_b32 v252, v250
	ds_read_b32 v253, v250 offset:4096
	ds_read_b32 v249, v211 offset:4992
	s_add_i32 s21, s21, 4
	s_sub_i32 s90, s90, 1
	s_cmp_eq_u32 s90, 0
	s_cbranch_scc1 .LU_sw0
	s_branch .LU_t6_s0
.LU_t7_s0:
	s_cmp_ge_u32 s21, s20
	s_cbranch_scc1 .LU_done
	s_waitcnt lgkmcnt(0)
	buffer_load_dwordx4 v[176:179], v[232:233], s[56:59], 0 idxen offen
	buffer_load_dwordx4 v[180:183], v[234:235], s[56:59], 0 idxen offen
	buffer_load_dwordx4 v[184:187], v[236:237], s[56:59], 0 idxen offen
	buffer_load_dwordx4 v[188:191], v[238:239], s[56:59], 0 idxen offen
	ds_read_b32 v232, v213 offset:64
	ds_read_b32 v234, v213 offset:68
	ds_read_b32 v236, v213 offset:72
	ds_read_b32 v238, v213 offset:76
	s_waitcnt vmcnt(12)
	v_cvt_pk_f32_fp8_e32 v[224:225], v128
	v_cvt_pk_f32_fp8_e32 v[226:227], v132
	v_cvt_pk_f32_fp8_e32 v[228:229], v136
	v_cvt_pk_f32_fp8_e32 v[230:231], v140
	v_pk_mul_f32 v[216:217], v[224:225], v[112:113]
	v_pk_mul_f32 v[218:219], v[226:227], v[112:113]
	v_pk_mul_f32 v[220:221], v[228:229], v[112:113]
	v_pk_mul_f32 v[222:223], v[230:231], v[112:113]
	v_cvt_pk_f32_fp8_sdwa v[224:225], v128 src0_sel:WORD_1
	v_cvt_pk_f32_fp8_sdwa v[226:227], v132 src0_sel:WORD_1
	v_cvt_pk_f32_fp8_sdwa v[228:229], v136 src0_sel:WORD_1
	v_cvt_pk_f32_fp8_sdwa v[230:231], v140 src0_sel:WORD_1
	v_pk_fma_f32 v[216:217], v[224:225], v[114:115], v[216:217]
	v_pk_fma_f32 v[218:219], v[226:227], v[114:115], v[218:219]
	v_pk_fma_f32 v[220:221], v[228:229], v[114:115], v[220:221]
	v_pk_fma_f32 v[222:223], v[230:231], v[114:115], v[222:223]
	v_cvt_pk_f32_fp8_e32 v[224:225], v129
	v_cvt_pk_f32_fp8_e32 v[226:227], v133
	v_cvt_pk_f32_fp8_e32 v[228:229], v137
	v_cvt_pk_f32_fp8_e32 v[230:231], v141
	v_pk_fma_f32 v[216:217], v[224:225], v[116:117], v[216:217]
	v_pk_fma_f32 v[218:219], v[226:227], v[116:117], v[218:219]
	v_pk_fma_f32 v[220:221], v[228:229], v[116:117], v[220:221]
	v_pk_fma_f32 v[222:223], v[230:231], v[116:117], v[222:223]
	v_cvt_pk_f32_fp8_sdwa v[224:225], v129 src0_sel:WORD_1
	v_cvt_pk_f32_fp8_sdwa v[226:227], v133 src0_sel:WORD_1
	v_cvt_pk_f32_fp8_sdwa v[228:229], v137 src0_sel:WORD_1
	v_cvt_pk_f32_fp8_sdwa v[230:231], v141 src0_sel:WORD_1
	v_pk_fma_f32 v[216:217], v[224:225], v[118:119], v[216:217]
	v_pk_fma_f32 v[218:219], v[226:227], v[118:119], v[218:219]
	v_pk_fma_f32 v[220:221], v[228:229], v[118:119], v[220:221]
	v_pk_fma_f32 v[222:223], v[230:231], v[118:119], v[222:223]
	v_cvt_pk_f32_fp8_e32 v[224:225], v130
	v_cvt_pk_f32_fp8_e32 v[226:227], v134
	v_cvt_pk_f32_fp8_e32 v[228:229], v138
	v_cvt_pk_f32_fp8_e32 v[230:231], v142
	v_pk_fma_f32 v[216:217], v[224:225], v[120:121], v[216:217]
	v_pk_fma_f32 v[218:219], v[226:227], v[120:121], v[218:219]
	v_pk_fma_f32 v[220:221], v[228:229], v[120:121], v[220:221]
	v_pk_fma_f32 v[222:223], v[230:231], v[120:121], v[222:223]
	v_cvt_pk_f32_fp8_sdwa v[224:225], v130 src0_sel:WORD_1
	v_cvt_pk_f32_fp8_sdwa v[226:227], v134 src0_sel:WORD_1
	v_cvt_pk_f32_fp8_sdwa v[228:229], v138 src0_sel:WORD_1
	v_cvt_pk_f32_fp8_sdwa v[230:231], v142 src0_sel:WORD_1
	v_pk_fma_f32 v[216:217], v[224:225], v[122:123], v[216:217]
	v_pk_fma_f32 v[218:219], v[226:227], v[122:123], v[218:219]
	v_pk_fma_f32 v[220:221], v[228:229], v[122:123], v[220:221]
	v_pk_fma_f32 v[222:223], v[230:231], v[122:123], v[222:223]
	v_cvt_pk_f32_fp8_e32 v[224:225], v131
	v_cvt_pk_f32_fp8_e32 v[226:227], v135
	v_cvt_pk_f32_fp8_e32 v[228:229], v139
	v_cvt_pk_f32_fp8_e32 v[230:231], v143
	v_pk_fma_f32 v[216:217], v[224:225], v[124:125], v[216:217]
	v_pk_fma_f32 v[218:219], v[226:227], v[124:125], v[218:219]
	v_pk_fma_f32 v[220:221], v[228:229], v[124:125], v[220:221]
	v_pk_fma_f32 v[222:223], v[230:231], v[124:125], v[222:223]
	v_cvt_pk_f32_fp8_sdwa v[224:225], v131 src0_sel:WORD_1
	v_cvt_pk_f32_fp8_sdwa v[226:227], v135 src0_sel:WORD_1
	v_cvt_pk_f32_fp8_sdwa v[228:229], v139 src0_sel:WORD_1
	v_cvt_pk_f32_fp8_sdwa v[230:231], v143 src0_sel:WORD_1
	v_pk_fma_f32 v[216:217], v[224:225], v[126:127], v[216:217]
	v_pk_fma_f32 v[218:219], v[226:227], v[126:127], v[218:219]
	v_pk_fma_f32 v[220:221], v[228:229], v[126:127], v[220:221]
	v_pk_fma_f32 v[222:223], v[230:231], v[126:127], v[222:223]
	v_add_f32_e32 v192, v216, v217
	v_add_f32_e32 v193, v218, v219
	v_add_f32_e32 v194, v220, v221
	v_add_f32_e32 v195, v222, v223
	s_sub_i32 s90, s90, 1
	s_cmp_eq_u32 s90, 0
	s_cbranch_scc1 .LU_sw1
.LU_t7_s1:
	s_waitcnt lgkmcnt(0)
	buffer_load_dwordx4 v[128:131], v[232:233], s[56:59], 0 idxen offen
	buffer_load_dwordx4 v[132:135], v[234:235], s[56:59], 0 idxen offen
	buffer_load_dwordx4 v[136:139], v[236:237], s[56:59], 0 idxen offen
	buffer_load_dwordx4 v[140:143], v[238:239], s[56:59], 0 idxen offen
	ds_read_b32 v232, v213 offset:80
	ds_read_b32 v234, v213 offset:84
	ds_read_b32 v236, v213 offset:88
	ds_read_b32 v238, v213 offset:92
	s_waitcnt vmcnt(12)
	v_cvt_pk_f32_fp8_e32 v[224:225], v144
	v_cvt_pk_f32_fp8_e32 v[226:227], v148
	v_cvt_pk_f32_fp8_e32 v[228:229], v152
	v_cvt_pk_f32_fp8_e32 v[230:231], v156
	v_pk_mul_f32 v[216:217], v[224:225], v[112:113]
	v_pk_mul_f32 v[218:219], v[226:227], v[112:113]
	v_pk_mul_f32 v[220:221], v[228:229], v[112:113]
	v_pk_mul_f32 v[222:223], v[230:231], v[112:113]
	v_cvt_pk_f32_fp8_sdwa v[224:225], v144 src0_sel:WORD_1
	v_cvt_pk_f32_fp8_sdwa v[226:227], v148 src0_sel:WORD_1
	v_cvt_pk_f32_fp8_sdwa v[228:229], v152 src0_sel:WORD_1
	v_cvt_pk_f32_fp8_sdwa v[230:231], v156 src0_sel:WORD_1
	v_pk_fma_f32 v[216:217], v[224:225], v[114:115], v[216:217]
	v_pk_fma_f32 v[218:219], v[226:227], v[114:115], v[218:219]
	v_pk_fma_f32 v[220:221], v[228:229], v[114:115], v[220:221]
	v_pk_fma_f32 v[222:223], v[230:231], v[114:115], v[222:223]
	v_cvt_pk_f32_fp8_e32 v[224:225], v145
	v_cvt_pk_f32_fp8_e32 v[226:227], v149
	v_cvt_pk_f32_fp8_e32 v[228:229], v153
	v_cvt_pk_f32_fp8_e32 v[230:231], v157
	v_pk_fma_f32 v[216:217], v[224:225], v[116:117], v[216:217]
	v_pk_fma_f32 v[218:219], v[226:227], v[116:117], v[218:219]
	v_pk_fma_f32 v[220:221], v[228:229], v[116:117], v[220:221]
	v_pk_fma_f32 v[222:223], v[230:231], v[116:117], v[222:223]
	v_cvt_pk_f32_fp8_sdwa v[224:225], v145 src0_sel:WORD_1
	v_cvt_pk_f32_fp8_sdwa v[226:227], v149 src0_sel:WORD_1
	v_cvt_pk_f32_fp8_sdwa v[228:229], v153 src0_sel:WORD_1
	v_cvt_pk_f32_fp8_sdwa v[230:231], v157 src0_sel:WORD_1
	v_pk_fma_f32 v[216:217], v[224:225], v[118:119], v[216:217]
	v_pk_fma_f32 v[218:219], v[226:227], v[118:119], v[218:219]
	v_pk_fma_f32 v[220:221], v[228:229], v[118:119], v[220:221]
	v_pk_fma_f32 v[222:223], v[230:231], v[118:119], v[222:223]
	v_cvt_pk_f32_fp8_e32 v[224:225], v146
	v_cvt_pk_f32_fp8_e32 v[226:227], v150
	v_cvt_pk_f32_fp8_e32 v[228:229], v154
	v_cvt_pk_f32_fp8_e32 v[230:231], v158
	v_pk_fma_f32 v[216:217], v[224:225], v[120:121], v[216:217]
	v_pk_fma_f32 v[218:219], v[226:227], v[120:121], v[218:219]
	v_pk_fma_f32 v[220:221], v[228:229], v[120:121], v[220:221]
	v_pk_fma_f32 v[222:223], v[230:231], v[120:121], v[222:223]
	v_cvt_pk_f32_fp8_sdwa v[224:225], v146 src0_sel:WORD_1
	v_cvt_pk_f32_fp8_sdwa v[226:227], v150 src0_sel:WORD_1
	v_cvt_pk_f32_fp8_sdwa v[228:229], v154 src0_sel:WORD_1
	v_cvt_pk_f32_fp8_sdwa v[230:231], v158 src0_sel:WORD_1
	v_pk_fma_f32 v[216:217], v[224:225], v[122:123], v[216:217]
	v_pk_fma_f32 v[218:219], v[226:227], v[122:123], v[218:219]
	v_pk_fma_f32 v[220:221], v[228:229], v[122:123], v[220:221]
	v_pk_fma_f32 v[222:223], v[230:231], v[122:123], v[222:223]
	v_cvt_pk_f32_fp8_e32 v[224:225], v147
	v_cvt_pk_f32_fp8_e32 v[226:227], v151
	v_cvt_pk_f32_fp8_e32 v[228:229], v155
	v_cvt_pk_f32_fp8_e32 v[230:231], v159
	v_pk_fma_f32 v[216:217], v[224:225], v[124:125], v[216:217]
	v_pk_fma_f32 v[218:219], v[226:227], v[124:125], v[218:219]
	v_pk_fma_f32 v[220:221], v[228:229], v[124:125], v[220:221]
	v_pk_fma_f32 v[222:223], v[230:231], v[124:125], v[222:223]
	v_cvt_pk_f32_fp8_sdwa v[224:225], v147 src0_sel:WORD_1
	v_cvt_pk_f32_fp8_sdwa v[226:227], v151 src0_sel:WORD_1
	v_cvt_pk_f32_fp8_sdwa v[228:229], v155 src0_sel:WORD_1
	v_cvt_pk_f32_fp8_sdwa v[230:231], v159 src0_sel:WORD_1
	v_pk_fma_f32 v[216:217], v[224:225], v[126:127], v[216:217]
	v_pk_fma_f32 v[218:219], v[226:227], v[126:127], v[218:219]
	v_pk_fma_f32 v[220:221], v[228:229], v[126:127], v[220:221]
	v_pk_fma_f32 v[222:223], v[230:231], v[126:127], v[222:223]
	v_add_f32_e32 v196, v216, v217
	v_add_f32_e32 v197, v218, v219
	v_add_f32_e32 v198, v220, v221
	v_add_f32_e32 v199, v222, v223
	s_sub_i32 s90, s90, 1
	s_cmp_eq_u32 s90, 0
	s_cbranch_scc1 .LU_sw2
.LU_t7_s2:
	s_waitcnt lgkmcnt(0)
	buffer_load_dwordx4 v[144:147], v[232:233], s[56:59], 0 idxen offen
	buffer_load_dwordx4 v[148:151], v[234:235], s[56:59], 0 idxen offen
	buffer_load_dwordx4 v[152:155], v[236:237], s[56:59], 0 idxen offen
	buffer_load_dwordx4 v[156:159], v[238:239], s[56:59], 0 idxen offen
	ds_read_b32 v232, v213 offset:96
	ds_read_b32 v234, v213 offset:100
	ds_read_b32 v236, v213 offset:104
	ds_read_b32 v238, v213 offset:108
	s_waitcnt vmcnt(12)
	v_cvt_pk_f32_fp8_e32 v[224:225], v160
	v_cvt_pk_f32_fp8_e32 v[226:227], v164
	v_cvt_pk_f32_fp8_e32 v[228:229], v168
	v_cvt_pk_f32_fp8_e32 v[230:231], v172
	v_pk_mul_f32 v[216:217], v[224:225], v[112:113]
	v_pk_mul_f32 v[218:219], v[226:227], v[112:113]
	v_pk_mul_f32 v[220:221], v[228:229], v[112:113]
	v_pk_mul_f32 v[222:223], v[230:231], v[112:113]
	v_cvt_pk_f32_fp8_sdwa v[224:225], v160 src0_sel:WORD_1
	v_cvt_pk_f32_fp8_sdwa v[226:227], v164 src0_sel:WORD_1
	v_cvt_pk_f32_fp8_sdwa v[228:229], v168 src0_sel:WORD_1
	v_cvt_pk_f32_fp8_sdwa v[230:231], v172 src0_sel:WORD_1
	v_pk_fma_f32 v[216:217], v[224:225], v[114:115], v[216:217]
	v_pk_fma_f32 v[218:219], v[226:227], v[114:115], v[218:219]
	v_pk_fma_f32 v[220:221], v[228:229], v[114:115], v[220:221]
	v_pk_fma_f32 v[222:223], v[230:231], v[114:115], v[222:223]
	v_cvt_pk_f32_fp8_e32 v[224:225], v161
	v_cvt_pk_f32_fp8_e32 v[226:227], v165
	v_cvt_pk_f32_fp8_e32 v[228:229], v169
	v_cvt_pk_f32_fp8_e32 v[230:231], v173
	v_pk_fma_f32 v[216:217], v[224:225], v[116:117], v[216:217]
	v_pk_fma_f32 v[218:219], v[226:227], v[116:117], v[218:219]
	v_pk_fma_f32 v[220:221], v[228:229], v[116:117], v[220:221]
	v_pk_fma_f32 v[222:223], v[230:231], v[116:117], v[222:223]
	v_cvt_pk_f32_fp8_sdwa v[224:225], v161 src0_sel:WORD_1
	v_cvt_pk_f32_fp8_sdwa v[226:227], v165 src0_sel:WORD_1
	v_cvt_pk_f32_fp8_sdwa v[228:229], v169 src0_sel:WORD_1
	v_cvt_pk_f32_fp8_sdwa v[230:231], v173 src0_sel:WORD_1
	v_pk_fma_f32 v[216:217], v[224:225], v[118:119], v[216:217]
	v_pk_fma_f32 v[218:219], v[226:227], v[118:119], v[218:219]
	v_pk_fma_f32 v[220:221], v[228:229], v[118:119], v[220:221]
	v_pk_fma_f32 v[222:223], v[230:231], v[118:119], v[222:223]
	v_cvt_pk_f32_fp8_e32 v[224:225], v162
	v_cvt_pk_f32_fp8_e32 v[226:227], v166
	v_cvt_pk_f32_fp8_e32 v[228:229], v170
	v_cvt_pk_f32_fp8_e32 v[230:231], v174
	v_pk_fma_f32 v[216:217], v[224:225], v[120:121], v[216:217]
	v_pk_fma_f32 v[218:219], v[226:227], v[120:121], v[218:219]
	v_pk_fma_f32 v[220:221], v[228:229], v[120:121], v[220:221]
	v_pk_fma_f32 v[222:223], v[230:231], v[120:121], v[222:223]
	v_cvt_pk_f32_fp8_sdwa v[224:225], v162 src0_sel:WORD_1
	v_cvt_pk_f32_fp8_sdwa v[226:227], v166 src0_sel:WORD_1
	v_cvt_pk_f32_fp8_sdwa v[228:229], v170 src0_sel:WORD_1
	v_cvt_pk_f32_fp8_sdwa v[230:231], v174 src0_sel:WORD_1
	v_pk_fma_f32 v[216:217], v[224:225], v[122:123], v[216:217]
	v_pk_fma_f32 v[218:219], v[226:227], v[122:123], v[218:219]
	v_pk_fma_f32 v[220:221], v[228:229], v[122:123], v[220:221]
	v_pk_fma_f32 v[222:223], v[230:231], v[122:123], v[222:223]
	v_cvt_pk_f32_fp8_e32 v[224:225], v163
	v_cvt_pk_f32_fp8_e32 v[226:227], v167
	v_cvt_pk_f32_fp8_e32 v[228:229], v171
	v_cvt_pk_f32_fp8_e32 v[230:231], v175
	v_pk_fma_f32 v[216:217], v[224:225], v[124:125], v[216:217]
	v_pk_fma_f32 v[218:219], v[226:227], v[124:125], v[218:219]
	v_pk_fma_f32 v[220:221], v[228:229], v[124:125], v[220:221]
	v_pk_fma_f32 v[222:223], v[230:231], v[124:125], v[222:223]
	v_cvt_pk_f32_fp8_sdwa v[224:225], v163 src0_sel:WORD_1
	v_cvt_pk_f32_fp8_sdwa v[226:227], v167 src0_sel:WORD_1
	v_cvt_pk_f32_fp8_sdwa v[228:229], v171 src0_sel:WORD_1
	v_cvt_pk_f32_fp8_sdwa v[230:231], v175 src0_sel:WORD_1
	v_pk_fma_f32 v[216:217], v[224:225], v[126:127], v[216:217]
	v_pk_fma_f32 v[218:219], v[226:227], v[126:127], v[218:219]
	v_pk_fma_f32 v[220:221], v[228:229], v[126:127], v[220:221]
	v_pk_fma_f32 v[222:223], v[230:231], v[126:127], v[222:223]
	v_add_f32_e32 v200, v216, v217
	v_add_f32_e32 v201, v218, v219
	v_add_f32_e32 v202, v220, v221
	v_add_f32_e32 v203, v222, v223
	s_sub_i32 s90, s90, 1
	s_cmp_eq_u32 s90, 0
	s_cbranch_scc1 .LU_sw3
; __device__ __forceinline__ float gelu_fast(float v) {
;     const float av = fabsf(v), tt = __builtin_amdgcn_rcpf(av * 0.2316418882f + 1.0f);
;     float q = tt * 0.5307027145f + (-0.7265760135f); q = q * tt + 0.7107068705f; q = q * tt + (-0.142248368f); q = q * tt + 0.127414796f; q = q * tt;
;     const float e = __builtin_amdgcn_exp2f((v * v) * (-0.72134752044f));
;     const float m = v * (q * e);
;     return v < 0.f ? m : v - m;
; }
.LU_t7_s3:
	s_waitcnt lgkmcnt(0)
	buffer_load_dwordx4 v[160:163], v[232:233], s[56:59], 0 idxen offen
	buffer_load_dwordx4 v[164:167], v[234:235], s[56:59], 0 idxen offen
	buffer_load_dwordx4 v[168:171], v[236:237], s[56:59], 0 idxen offen
	buffer_load_dwordx4 v[172:175], v[238:239], s[56:59], 0 idxen offen
	ds_read_b32 v232, v213 offset:112
	ds_read_b32 v234, v213 offset:116
	ds_read_b32 v236, v213 offset:120
	ds_read_b32 v238, v213 offset:124
	s_waitcnt vmcnt(12)
	v_cvt_pk_f32_fp8_e32 v[224:225], v176
	v_cvt_pk_f32_fp8_e32 v[226:227], v180
	v_cvt_pk_f32_fp8_e32 v[228:229], v184
	v_cvt_pk_f32_fp8_e32 v[230:231], v188
	v_pk_mul_f32 v[216:217], v[224:225], v[112:113]
	v_pk_mul_f32 v[218:219], v[226:227], v[112:113]
	v_pk_mul_f32 v[220:221], v[228:229], v[112:113]
	v_pk_mul_f32 v[222:223], v[230:231], v[112:113]
	v_cvt_pk_f32_fp8_sdwa v[224:225], v176 src0_sel:WORD_1
	v_cvt_pk_f32_fp8_sdwa v[226:227], v180 src0_sel:WORD_1
	v_cvt_pk_f32_fp8_sdwa v[228:229], v184 src0_sel:WORD_1
	v_cvt_pk_f32_fp8_sdwa v[230:231], v188 src0_sel:WORD_1
	v_pk_fma_f32 v[216:217], v[224:225], v[114:115], v[216:217]
	v_pk_fma_f32 v[218:219], v[226:227], v[114:115], v[218:219]
	v_pk_fma_f32 v[220:221], v[228:229], v[114:115], v[220:221]
	v_pk_fma_f32 v[222:223], v[230:231], v[114:115], v[222:223]
	v_cvt_pk_f32_fp8_e32 v[224:225], v177
	v_cvt_pk_f32_fp8_e32 v[226:227], v181
	v_cvt_pk_f32_fp8_e32 v[228:229], v185
	v_cvt_pk_f32_fp8_e32 v[230:231], v189
	v_pk_fma_f32 v[216:217], v[224:225], v[116:117], v[216:217]
	v_pk_fma_f32 v[218:219], v[226:227], v[116:117], v[218:219]
	v_pk_fma_f32 v[220:221], v[228:229], v[116:117], v[220:221]
	v_pk_fma_f32 v[222:223], v[230:231], v[116:117], v[222:223]
	v_cvt_pk_f32_fp8_sdwa v[224:225], v177 src0_sel:WORD_1
	v_cvt_pk_f32_fp8_sdwa v[226:227], v181 src0_sel:WORD_1
	v_cvt_pk_f32_fp8_sdwa v[228:229], v185 src0_sel:WORD_1
	v_cvt_pk_f32_fp8_sdwa v[230:231], v189 src0_sel:WORD_1
	v_pk_fma_f32 v[216:217], v[224:225], v[118:119], v[216:217]
	v_pk_fma_f32 v[218:219], v[226:227], v[118:119], v[218:219]
	v_pk_fma_f32 v[220:221], v[228:229], v[118:119], v[220:221]
	v_pk_fma_f32 v[222:223], v[230:231], v[118:119], v[222:223]
	v_cvt_pk_f32_fp8_e32 v[224:225], v178
	v_cvt_pk_f32_fp8_e32 v[226:227], v182
	v_cvt_pk_f32_fp8_e32 v[228:229], v186
	v_cvt_pk_f32_fp8_e32 v[230:231], v190
	v_pk_fma_f32 v[216:217], v[224:225], v[120:121], v[216:217]
	v_pk_fma_f32 v[218:219], v[226:227], v[120:121], v[218:219]
	v_pk_fma_f32 v[220:221], v[228:229], v[120:121], v[220:221]
	v_pk_fma_f32 v[222:223], v[230:231], v[120:121], v[222:223]
	v_cvt_pk_f32_fp8_sdwa v[224:225], v178 src0_sel:WORD_1
	v_cvt_pk_f32_fp8_sdwa v[226:227], v182 src0_sel:WORD_1
	v_cvt_pk_f32_fp8_sdwa v[228:229], v186 src0_sel:WORD_1
	v_cvt_pk_f32_fp8_sdwa v[230:231], v190 src0_sel:WORD_1
	v_pk_fma_f32 v[216:217], v[224:225], v[122:123], v[216:217]
	v_pk_fma_f32 v[218:219], v[226:227], v[122:123], v[218:219]
	v_pk_fma_f32 v[220:221], v[228:229], v[122:123], v[220:221]
	v_pk_fma_f32 v[222:223], v[230:231], v[122:123], v[222:223]
	v_cvt_pk_f32_fp8_e32 v[224:225], v179
	v_cvt_pk_f32_fp8_e32 v[226:227], v183
	v_cvt_pk_f32_fp8_e32 v[228:229], v187
	v_cvt_pk_f32_fp8_e32 v[230:231], v191
	v_pk_fma_f32 v[216:217], v[224:225], v[124:125], v[216:217]
	v_pk_fma_f32 v[218:219], v[226:227], v[124:125], v[218:219]
	v_pk_fma_f32 v[220:221], v[228:229], v[124:125], v[220:221]
	v_pk_fma_f32 v[222:223], v[230:231], v[124:125], v[222:223]
	v_cvt_pk_f32_fp8_sdwa v[224:225], v179 src0_sel:WORD_1
	v_cvt_pk_f32_fp8_sdwa v[226:227], v183 src0_sel:WORD_1
	v_cvt_pk_f32_fp8_sdwa v[228:229], v187 src0_sel:WORD_1
	v_cvt_pk_f32_fp8_sdwa v[230:231], v191 src0_sel:WORD_1
	v_pk_fma_f32 v[216:217], v[224:225], v[126:127], v[216:217]
	v_pk_fma_f32 v[218:219], v[226:227], v[126:127], v[218:219]
	v_pk_fma_f32 v[220:221], v[228:229], v[126:127], v[220:221]
	v_pk_fma_f32 v[222:223], v[230:231], v[126:127], v[222:223]
	v_add_f32_e32 v204, v216, v217
	v_add_f32_e32 v205, v218, v219
	v_add_f32_e32 v206, v220, v221
	v_add_f32_e32 v207, v222, v223
	s_nop 0
	v_permlane32_swap_b32_e32 v192, v200
	v_permlane32_swap_b32_e32 v193, v201
	v_permlane32_swap_b32_e32 v194, v202
	v_permlane32_swap_b32_e32 v195, v203
	v_permlane32_swap_b32_e32 v196, v204
	v_permlane32_swap_b32_e32 v197, v205
	v_permlane32_swap_b32_e32 v198, v206
	v_permlane32_swap_b32_e32 v199, v207
	v_add_f32_e32 v192, v192, v200
	v_add_f32_e32 v193, v193, v201
	v_add_f32_e32 v194, v194, v202
	v_add_f32_e32 v195, v195, v203
	v_add_f32_e32 v196, v196, v204
	v_add_f32_e32 v197, v197, v205
	v_add_f32_e32 v198, v198, v206
	v_add_f32_e32 v199, v199, v207
	v_permlane16_swap_b32_e32 v192, v196
	v_permlane16_swap_b32_e32 v193, v197
	v_permlane16_swap_b32_e32 v194, v198
	v_permlane16_swap_b32_e32 v195, v199
	v_add_f32_e32 v192, v192, v196
	v_add_f32_e32 v193, v193, v197
	v_add_f32_e32 v194, v194, v198
	v_add_f32_e32 v195, v195, v199
	v_add_f32_dpp v216, v192, v192 row_ror:8 row_mask:0xf bank_mask:0xf
	v_add_f32_dpp v218, v194, v194 row_ror:8 row_mask:0xf bank_mask:0xf
	v_add_f32_dpp v216, v193, v193 row_ror:8 row_mask:0xf bank_mask:0xc
	v_add_f32_dpp v218, v195, v195 row_ror:8 row_mask:0xf bank_mask:0xc
	s_nop 1
	v_add_f32_dpp v220, v216, v216 row_half_mirror row_mask:0xf bank_mask:0xf
	v_add_f32_dpp v220, v218, v218 row_half_mirror row_mask:0xf bank_mask:0xa
	s_nop 1
	v_add_f32_dpp v220, v220, v220 quad_perm:[1,0,3,2] row_mask:0xf bank_mask:0xf
	s_nop 1
	v_add_f32_dpp v220, v220, v220 quad_perm:[2,3,0,1] row_mask:0xf bank_mask:0xf
	v_mul_f32_e32 v216, v252, v220
	v_fma_f32 v218, |v216|, s72, 1.0
	v_mul_f32_e32 v222, v216, v216
	v_rcp_f32_e32 v218, v218
	v_mul_f32_e32 v222, 0xbf38aa3b, v222
	v_exp_f32_e32 v222, v222
	v_fmamk_f32 v224, v218, 0x3f07dc22, v242
	v_fmaak_f32 v224, v218, v224, 0x3f35f0e3
	v_fmaak_f32 v224, v218, v224, 0xbe11a98e
	v_fmaak_f32 v224, v218, v224, 0x3e027906
	v_mul_f32_e32 v224, v218, v224
	v_mul_f32_e32 v224, v222, v224
	v_mul_f32_e32 v226, v216, v224
	v_fma_f32 v224, -v216, v224, v216
	v_cmp_gt_f32_e32 vcc, 0, v216
	s_nop 1
	v_cndmask_b32_e32 v224, v224, v226, vcc
	v_mul_f32_e32 v224, v249, v224
	v_mul_f32_e32 v224, v253, v224
	ds_write_b32 v211, v224 offset:4992
	v_add_u32_e32 v211, 64, v211
	v_add_u32_e32 v213, 64, v213
	v_add_u32_e32 v250, 64, v250
	ds_read_b32 v252, v250
	ds_read_b32 v253, v250 offset:4096
	ds_read_b32 v249, v211 offset:4992
	s_add_i32 s21, s21, 4
	s_sub_i32 s90, s90, 1
	s_cmp_eq_u32 s90, 0
	s_cbranch_scc1 .LU_sw0
	s_branch .LU_t7_s0
